# pipelined dil loop: global-load wait split (K loads only before the K write/readback, V loads before the V write)
# baseline (speedup 1.0000x reference)
; #define LAS __attribute__((address_space(3)))
; #define GAS __attribute__((address_space(1)))
; __device__ __forceinline__ void dil_unit(LAS unsigned char* lds, bf16_t* proj, int seq, int hd, int T0, int rho) {
;     ...
;     const int tid = tid_, lane = tid & 63, r32 = lane & 31, hi = lane >> 5, wid = __builtin_amdgcn_readfirstlane(tid >> 6);
;     bf16_t* base = proj + (size_t)seq * SEQ * NIN;
;     LAS unsigned char* wbuf = lds + wid * 4096;
;     const LAS unsigned char* vp = wbuf + ((lane >> 4) & 1) * 32 + (lane & 3) * 8 + (4 * hi + ((lane & 15) >> 2)) * 64;
;     const int P0 = T0 + rho;
;     bf16x8 qr[4];
; #pragma unroll
;     for (int ks = 0; ks < 4; ++ks) qr[ks] = *(const GAS bf16x8*)(base + (size_t)(P0 + 16 * r32) * NIN + PC_LQ + hd * 64 + 16 * ks + 8 * hi);
;     f32x16 o0 = {}, o1 = {}; float l = 0.f;
;     const bool bound = (T0 < 1024) || (T0 >= 15360);
; __device__ __forceinline__ void attn_phase(unsigned char* ws, int l, LAS unsigned char* lds, int G) {
;     ...
;         const int sh = bu >> 6, rem = bu & 63, T0 = (rem >> 1) * 512, rho = (rem & 1) * 8 + wid;
;         dil_unit(lds, proj, sh / 6, sh % 6, T0, rho);
.LBB0_554:
	s_lshr_b32 s82, s33, 8
	s_mul_i32 s82, s82, 13
	s_add_i32 s82, s82, s33
	s_ashr_i32 s2, s33, 6
	s_mul_hi_i32 s7, s2, 0x2aaaaaab
	s_lshl_b32 s3, s82, 8
	s_lshr_b32 s8, s7, 31
	s_and_b32 s6, s3, 0x3e00
	s_lshl_b32 s3, s82, 3
	s_add_i32 s7, s7, s8
	s_and_b32 s3, s3, 8
	s_mul_i32 s8, s7, 6
	s_add_i32 s3, s3, s64
	s_sub_i32 s8, s2, s8
	s_mul_hi_i32 s2, s7, 0x6000000
	s_mul_i32 s7, s7, 0x6000000
	v_mov_b32_e32 v2, v154
	s_add_u32 s56, s48, s7
	s_addc_u32 s57, s49, s2
	v_and_b32_e32 v105, 31, v2
	s_add_i32 s76, s3, s6
	v_lshl_add_u32 v3, v105, 4, s76
	v_mov_b64_e32 v[0:1], s[56:57]
	s_lshl_b32 s58, s8, 6
	v_bfe_u32 v106, v2, 5, 1
	v_mad_u64_u32 v[0:1], s[2:3], v3, s65, v[0:1]
	s_ashr_i32 s59, s58, 31
	v_lshl_add_u64 v[0:1], s[58:59], 1, v[0:1]
	v_lshlrev_b32_e32 v80, 4, v106
	v_lshl_add_u64 v[0:1], v[0:1], 0, v[80:81]
	global_load_dwordx4 v[48:51], v[0:1], off offset:1280
	global_load_dwordx4 v[52:55], v[0:1], off offset:1312
	global_load_dwordx4 v[56:59], v[0:1], off offset:1344
	global_load_dwordx4 v[60:63], v[0:1], off offset:1376
	v_readfirstlane_b32 s2, v2
	s_lshl_b32 s2, s2, 6
	s_and_b32 s2, s2, 0xfffff000
	v_lshlrev_b32_e32 v0, 1, v2
	v_lshlrev_b32_e32 v104, 3, v2
	v_lshlrev_b32_e32 v107, 2, v106
	v_lshrrev_b32_e32 v1, 2, v2
	v_and_b32_e32 v103, 63, v2
	v_and_b32_e32 v0, 32, v0
	v_and_b32_e32 v98, 24, v104
	v_and_or_b32 v1, v1, 3, v107
	s_add_i32 s77, s2, 0
	v_lshlrev_b32_e32 v108, 6, v1
	v_lshlrev_b32_e32 v1, 3, v106
	v_add3_u32 v109, s77, v0, v98
	s_addk_i32 s6, 0xc400
	v_lshrrev_b32_e32 v110, 2, v103
	v_lshlrev_b32_e32 v0, 4, v103
	s_mov_b64 s[2:3], -1
	s_cmp_gt_u32 s6, 0xffffc7ff
	v_lshlrev_b32_e32 v100, 1, v98
	s_mul_i32 s6, s8, 0x1c00
	v_lshlrev_b32_e32 v82, 1, v1
	v_or_b32_e32 v111, 16, v110
	v_add_u32_e32 v112, s77, v0
	s_cbranch_scc0 .LBB0_558
	s_movk_i32 s100, 0x1800
	s_add_i32 s101, s6, 0x15c00
	s_lshl_b32 s90, s58, 1
	s_add_u32 s82, s56, s90
	s_addc_u32 s83, s57, 0
	s_add_u32 s82, s82, 0x1200
	s_addc_u32 s83, s83, 0
	s_sub_i32 s90, s76, 64
	s_mul_i32 s90, s90, 0x1800
	s_add_u32 s84, s82, s90
	s_addc_u32 s85, s83, 0
	s_sub_i32 s90, s76, 256
	s_mul_i32 s90, s90, 0x1800
	s_add_u32 s86, s82, s90
	s_addc_u32 s87, s83, 0
	s_sub_i32 s90, s76, 1024
	s_mul_i32 s90, s90, 0x1800
	s_add_u32 s88, s82, s90
	s_addc_u32 s89, s83, 0
	v_lshlrev_b32_e32 v153, 1, v98
	v_mad_u32_u24 v80, v105, s100, v82
	v_mad_u32_u24 v100, v110, s100, v153
	v_add_u32_e32 v149, 0x18000, v100
	v_lshlrev_b32_e32 v83, 2, v105
	v_mad_u32_u24 v83, v83, s100, v82
	v_lshlrev_b32_e32 v101, 2, v110
	v_mad_u32_u24 v101, v101, s100, v153
	v_add_u32_e32 v150, 0x60000, v101
	v_lshlrev_b32_e32 v99, 4, v105
	v_mad_u32_u24 v99, v99, s100, v82
	v_lshlrev_b32_e32 v148, 4, v110
	v_mad_u32_u24 v148, v148, s100, v153
	v_add_u32_e32 v151, 0x180000, v148
	v_lshrrev_b32_e32 v249, 3, v103
	v_and_b32_e32 v250, 7, v103
	v_lshlrev_b32_e32 v250, 4, v250
	v_add_u32_e32 v235, 0, v249
	v_mad_u32_u24 v235, v235, s100, v250
	v_add_u32_e32 v236, 8, v249
	v_mad_u32_u24 v236, v236, s100, v250
	v_add_u32_e32 v237, 16, v249
	v_mad_u32_u24 v237, v237, s100, v250
	v_add_u32_e32 v238, 24, v249
	v_mad_u32_u24 v238, v238, s100, v250
	v_add_u32_e32 v239, 0, v249
	v_lshlrev_b32_e32 v239, 2, v239
	v_mad_u32_u24 v239, v239, s100, v250
	v_add_u32_e32 v240, 8, v249
	v_lshlrev_b32_e32 v240, 2, v240
	v_mad_u32_u24 v240, v240, s100, v250
	v_add_u32_e32 v241, 16, v249
	v_lshlrev_b32_e32 v241, 2, v241
	v_mad_u32_u24 v241, v241, s100, v250
	v_add_u32_e32 v242, 24, v249
	v_lshlrev_b32_e32 v242, 2, v242
	v_mad_u32_u24 v242, v242, s100, v250
	v_add_u32_e32 v243, 0, v249
	v_lshlrev_b32_e32 v243, 4, v243
	v_mad_u32_u24 v243, v243, s100, v250
	v_add_u32_e32 v244, 8, v249
	v_lshlrev_b32_e32 v244, 4, v244
	v_mad_u32_u24 v244, v244, s100, v250
	v_add_u32_e32 v245, 16, v249
	v_lshlrev_b32_e32 v245, 4, v245
	v_mad_u32_u24 v245, v245, s100, v250
	v_add_u32_e32 v246, 24, v249
	v_lshlrev_b32_e32 v246, 4, v246
	v_mad_u32_u24 v246, v246, s100, v250
	v_and_b32_e32 v247, 7, v249
	v_lshlrev_b32_e32 v247, 4, v247
	v_xor_b32_e32 v247, v247, v112
	v_and_b32_e32 v153, 7, v105
	v_or_b32_e32 v248, 0, v106
	v_xor_b32_e32 v248, v248, v153
	v_lshlrev_b32_e32 v248, 4, v248
	v_lshl_add_u32 v248, v105, 7, v248
	v_add_u32_e32 v248, s77, v248
	v_or_b32_e32 v249, 2, v106
	v_xor_b32_e32 v249, v249, v153
	v_lshlrev_b32_e32 v249, 4, v249
	v_lshl_add_u32 v249, v105, 7, v249
	v_add_u32_e32 v249, s77, v249
	v_or_b32_e32 v250, 4, v106
	v_xor_b32_e32 v250, v250, v153
	v_lshlrev_b32_e32 v250, 4, v250
	v_lshl_add_u32 v250, v105, 7, v250
	v_add_u32_e32 v250, s77, v250
	v_or_b32_e32 v251, 6, v106
	v_xor_b32_e32 v251, v251, v153
	v_lshlrev_b32_e32 v251, 4, v251
	v_lshl_add_u32 v251, v105, 7, v251
	v_add_u32_e32 v251, s77, v251
	v_lshlrev_b32_e32 v153, 1, v98
	v_mul_u32_u24_e32 v228, 17, v105
	v_sub_u32_e32 v228, v107, v228
	s_mul_i32 s90, s58, 153
	s_lshr_b32 s90, s90, 1
	s_add_i32 s90, s90, 34876
	v_lshl_add_u32 v228, v228, 2, s90
	v_lshlrev_b32_e32 v229, 2, v105
	v_sub_u32_e32 v229, v107, v229
	s_add_i32 s90, s101, 5104
	v_lshl_add_u32 v229, v229, 2, s90
	v_sub_u32_e32 v230, v107, v105
	s_add_i32 s90, s101, 6364
	v_lshl_add_u32 v230, v230, 2, s90
	v_add_u32_e32 v231, v109, v108
	v_mov_b64_e32 v[232:233], 0
	v_mov_b64_e32 v[0:1], 0
	v_mov_b64_e32 v[2:3], 0
	v_mov_b64_e32 v[4:5], 0
	v_mov_b64_e32 v[6:7], 0
	v_mov_b64_e32 v[8:9], 0
	v_mov_b64_e32 v[10:11], 0
	v_mov_b64_e32 v[12:13], 0
	v_mov_b64_e32 v[14:15], 0
	v_mov_b64_e32 v[16:17], 0
	v_mov_b64_e32 v[18:19], 0
	v_mov_b64_e32 v[20:21], 0
	v_mov_b64_e32 v[22:23], 0
	v_mov_b64_e32 v[24:25], 0
	v_mov_b64_e32 v[26:27], 0
	v_mov_b64_e32 v[28:29], 0
	v_mov_b64_e32 v[30:31], 0
	global_load_dwordx4 v[116:119], v235, s[84:85]
	global_load_dwordx4 v[120:123], v236, s[84:85]
	global_load_dwordx4 v[124:127], v237, s[84:85]
	global_load_dwordx4 v[128:131], v238, s[84:85]
	global_load_dwordx4 v[132:135], v100, s[84:85] offset:768
	global_load_dwordx4 v[136:139], v149, s[84:85] offset:768
	global_load_dwordx4 v[140:143], v100, s[84:85] offset:832
	global_load_dwordx4 v[144:147], v149, s[84:85] offset:832
	s_add_u32 s84, s84, 0x30000
	s_addc_u32 s85, s85, 0
	global_load_dwordx4 v[156:159], v235, s[84:85]
	global_load_dwordx4 v[160:163], v236, s[84:85]
	global_load_dwordx4 v[164:167], v237, s[84:85]
	global_load_dwordx4 v[168:171], v238, s[84:85]
	global_load_dwordx4 v[172:175], v100, s[84:85] offset:768
	global_load_dwordx4 v[176:179], v149, s[84:85] offset:768
	global_load_dwordx4 v[180:183], v100, s[84:85] offset:832
	global_load_dwordx4 v[184:187], v149, s[84:85] offset:832
	s_add_u32 s84, s84, 0x30000
	s_addc_u32 s85, s85, 0
	v_mov_b32_e32 v115, v228
	ds_read2_b32 v[32:33], v115 offset0:0 offset1:1
	ds_read2_b32 v[34:35], v115 offset0:2 offset1:3
	ds_read2_b32 v[36:37], v115 offset0:8 offset1:9
	ds_read2_b32 v[38:39], v115 offset0:10 offset1:11
	ds_read2_b32 v[40:41], v115 offset0:17 offset1:18
	ds_read2_b32 v[42:43], v115 offset0:19 offset1:20
	ds_read2_b32 v[44:45], v115 offset0:25 offset1:26
	ds_read2_b32 v[46:47], v115 offset0:27 offset1:28
	s_waitcnt vmcnt(8)
	ds_write_b128 v247, v[116:119]
	ds_write_b128 v247, v[120:123] offset:1024
	ds_write_b128 v247, v[124:127] offset:2048
	ds_write_b128 v247, v[128:131] offset:3072
	ds_read_b128 v[116:119], v248
	ds_read_b128 v[120:123], v249
	ds_read_b128 v[124:127], v250
	ds_read_b128 v[128:131], v251
	ds_write_b128 v112, v[132:135]
	ds_write_b128 v112, v[136:139] offset:1024
	ds_write_b128 v112, v[140:143] offset:2048
	ds_write_b128 v112, v[144:147] offset:3072
	s_waitcnt lgkmcnt(4)
	v_mfma_f32_32x32x16_bf16 v[32:47], v[116:119], v[48:51], v[32:47]
	v_mfma_f32_32x32x16_bf16 v[32:47], v[120:123], v[52:55], v[32:47]
	v_mfma_f32_32x32x16_bf16 v[32:47], v[124:127], v[56:59], v[32:47]
	v_mfma_f32_32x32x16_bf16 v[32:47], v[128:131], v[60:63], v[32:47]
	ds_read2_b32 v[188:189], v115 offset0:34 offset1:35
	ds_read2_b32 v[190:191], v115 offset0:36 offset1:37
	ds_read2_b32 v[192:193], v115 offset0:42 offset1:43
	ds_read2_b32 v[194:195], v115 offset0:44 offset1:45
	ds_read2_b32 v[196:197], v115 offset0:51 offset1:52
	ds_read2_b32 v[198:199], v115 offset0:53 offset1:54
	ds_read2_b32 v[200:201], v115 offset0:59 offset1:60
	ds_read2_b32 v[202:203], v115 offset0:61 offset1:62
	global_load_dwordx4 v[116:119], v235, s[84:85]
	global_load_dwordx4 v[120:123], v236, s[84:85]
	global_load_dwordx4 v[124:127], v237, s[84:85]
	global_load_dwordx4 v[128:131], v238, s[84:85]
	global_load_dwordx4 v[132:135], v100, s[84:85] offset:768
	global_load_dwordx4 v[136:139], v149, s[84:85] offset:768
	global_load_dwordx4 v[140:143], v100, s[84:85] offset:832
	global_load_dwordx4 v[144:147], v149, s[84:85] offset:832
	s_add_u32 s84, s84, 0x30000
	s_addc_u32 s85, s85, 0
	ds_read_b64_tr_b16 v[72:73], v231
	ds_read_b64_tr_b16 v[74:75], v231 offset:512
	ds_read_b64_tr_b16 v[76:77], v231 offset:2048
	ds_read_b64_tr_b16 v[78:79], v231 offset:2560
	ds_read_b64_tr_b16 v[220:221], v231 offset:1024
	ds_read_b64_tr_b16 v[222:223], v231 offset:1536
	ds_read_b64_tr_b16 v[224:225], v231 offset:3072
	ds_read_b64_tr_b16 v[226:227], v231 offset:3584
	v_exp_f32_e32 v32, v32
	v_exp_f32_e32 v33, v33
	v_exp_f32_e32 v34, v34
	v_exp_f32_e32 v35, v35
	s_waitcnt vmcnt(12)
	ds_write_b128 v247, v[156:159]
	ds_write_b128 v247, v[160:163] offset:1024
	ds_write_b128 v247, v[164:167] offset:2048
	ds_write_b128 v247, v[168:171] offset:3072
	ds_read_b128 v[156:159], v248
	ds_read_b128 v[160:163], v249
	ds_read_b128 v[164:167], v250
	ds_read_b128 v[168:171], v251
	s_waitcnt vmcnt(8)
	ds_write_b128 v112, v[172:175]
	ds_write_b128 v112, v[176:179] offset:1024
	ds_write_b128 v112, v[180:183] offset:2048
	ds_write_b128 v112, v[184:187] offset:3072
	v_exp_f32_e32 v36, v36
	v_exp_f32_e32 v37, v37
	v_exp_f32_e32 v38, v38
	v_exp_f32_e32 v39, v39
	s_waitcnt lgkmcnt(4)
	v_mfma_f32_32x32x16_bf16 v[188:203], v[156:159], v[48:51], v[188:203]
	v_exp_f32_e32 v40, v40
	v_exp_f32_e32 v41, v41
	v_mfma_f32_32x32x16_bf16 v[188:203], v[160:163], v[52:55], v[188:203]
	v_exp_f32_e32 v42, v42
	v_exp_f32_e32 v43, v43
	v_mfma_f32_32x32x16_bf16 v[188:203], v[164:167], v[56:59], v[188:203]
	v_exp_f32_e32 v44, v44
	v_exp_f32_e32 v45, v45
	v_mfma_f32_32x32x16_bf16 v[188:203], v[168:171], v[60:63], v[188:203]
	v_exp_f32_e32 v46, v46
	v_exp_f32_e32 v47, v47
	v_cvt_pk_bf16_f32 v64, v32, v33
	v_cvt_pk_bf16_f32 v65, v34, v35
	v_cvt_pk_bf16_f32 v66, v36, v37
	v_cvt_pk_bf16_f32 v67, v38, v39
	v_cvt_pk_bf16_f32 v68, v40, v41
	v_cvt_pk_bf16_f32 v69, v42, v43
	v_cvt_pk_bf16_f32 v70, v44, v45
	v_cvt_pk_bf16_f32 v71, v46, v47
	v_pk_add_f32 v[232:233], v[232:233], v[32:33]
	v_pk_add_f32 v[232:233], v[232:233], v[34:35]
	v_pk_add_f32 v[232:233], v[232:233], v[36:37]
	v_pk_add_f32 v[232:233], v[232:233], v[38:39]
	v_pk_add_f32 v[232:233], v[232:233], v[40:41]
	v_pk_add_f32 v[232:233], v[232:233], v[42:43]
	v_pk_add_f32 v[232:233], v[232:233], v[44:45]
	v_pk_add_f32 v[232:233], v[232:233], v[46:47]
	ds_read2_b32 v[32:33], v115 offset0:68 offset1:69
	ds_read2_b32 v[34:35], v115 offset0:70 offset1:71
	ds_read2_b32 v[36:37], v115 offset0:76 offset1:77
	ds_read2_b32 v[38:39], v115 offset0:78 offset1:79
	ds_read2_b32 v[40:41], v115 offset0:85 offset1:86
	ds_read2_b32 v[42:43], v115 offset0:87 offset1:88
	ds_read2_b32 v[44:45], v115 offset0:93 offset1:94
	ds_read2_b32 v[46:47], v115 offset0:95 offset1:96
	v_mfma_f32_32x32x16_bf16 v[0:15], v[64:67], v[72:75], v[0:15]
	v_mfma_f32_32x32x16_bf16 v[16:31], v[64:67], v[76:79], v[16:31]
	v_mfma_f32_32x32x16_bf16 v[0:15], v[68:71], v[220:223], v[0:15]
	v_mfma_f32_32x32x16_bf16 v[16:31], v[68:71], v[224:227], v[16:31]
	global_load_dwordx4 v[156:159], v235, s[84:85]
	global_load_dwordx4 v[160:163], v236, s[84:85]
	global_load_dwordx4 v[164:167], v237, s[84:85]
	global_load_dwordx4 v[168:171], v238, s[84:85]
	global_load_dwordx4 v[172:175], v100, s[84:85] offset:768
	global_load_dwordx4 v[176:179], v149, s[84:85] offset:768
	global_load_dwordx4 v[180:183], v100, s[84:85] offset:832
	global_load_dwordx4 v[184:187], v149, s[84:85] offset:832
	s_add_u32 s84, s84, 0x30000
	s_addc_u32 s85, s85, 0
	ds_read_b64_tr_b16 v[72:73], v231
	ds_read_b64_tr_b16 v[74:75], v231 offset:512
	ds_read_b64_tr_b16 v[76:77], v231 offset:2048
	ds_read_b64_tr_b16 v[78:79], v231 offset:2560
	ds_read_b64_tr_b16 v[220:221], v231 offset:1024
	ds_read_b64_tr_b16 v[222:223], v231 offset:1536
	ds_read_b64_tr_b16 v[224:225], v231 offset:3072
	ds_read_b64_tr_b16 v[226:227], v231 offset:3584
	v_exp_f32_e32 v188, v188
	v_exp_f32_e32 v189, v189
	v_exp_f32_e32 v190, v190
	v_exp_f32_e32 v191, v191
	s_waitcnt vmcnt(12)
	ds_write_b128 v247, v[116:119]
	ds_write_b128 v247, v[120:123] offset:1024
	ds_write_b128 v247, v[124:127] offset:2048
	ds_write_b128 v247, v[128:131] offset:3072
	ds_read_b128 v[116:119], v248
	ds_read_b128 v[120:123], v249
	ds_read_b128 v[124:127], v250
	ds_read_b128 v[128:131], v251
	s_waitcnt vmcnt(8)
	ds_write_b128 v112, v[132:135]
	ds_write_b128 v112, v[136:139] offset:1024
	ds_write_b128 v112, v[140:143] offset:2048
	ds_write_b128 v112, v[144:147] offset:3072
	v_exp_f32_e32 v192, v192
	v_exp_f32_e32 v193, v193
	v_exp_f32_e32 v194, v194
	v_exp_f32_e32 v195, v195
	s_waitcnt lgkmcnt(4)
	v_mfma_f32_32x32x16_bf16 v[32:47], v[116:119], v[48:51], v[32:47]
	v_exp_f32_e32 v196, v196
	v_exp_f32_e32 v197, v197
	v_mfma_f32_32x32x16_bf16 v[32:47], v[120:123], v[52:55], v[32:47]
	v_exp_f32_e32 v198, v198
	v_exp_f32_e32 v199, v199
	v_mfma_f32_32x32x16_bf16 v[32:47], v[124:127], v[56:59], v[32:47]
	v_exp_f32_e32 v200, v200
	v_exp_f32_e32 v201, v201
	v_mfma_f32_32x32x16_bf16 v[32:47], v[128:131], v[60:63], v[32:47]
	v_exp_f32_e32 v202, v202
	v_exp_f32_e32 v203, v203
	v_cvt_pk_bf16_f32 v64, v188, v189
	v_cvt_pk_bf16_f32 v65, v190, v191
	v_cvt_pk_bf16_f32 v66, v192, v193
	v_cvt_pk_bf16_f32 v67, v194, v195
	v_cvt_pk_bf16_f32 v68, v196, v197
	v_cvt_pk_bf16_f32 v69, v198, v199
	v_cvt_pk_bf16_f32 v70, v200, v201
	v_cvt_pk_bf16_f32 v71, v202, v203
	v_pk_add_f32 v[232:233], v[232:233], v[188:189]
	v_pk_add_f32 v[232:233], v[232:233], v[190:191]
	v_pk_add_f32 v[232:233], v[232:233], v[192:193]
	v_pk_add_f32 v[232:233], v[232:233], v[194:195]
	v_pk_add_f32 v[232:233], v[232:233], v[196:197]
	v_pk_add_f32 v[232:233], v[232:233], v[198:199]
	v_pk_add_f32 v[232:233], v[232:233], v[200:201]
	v_pk_add_f32 v[232:233], v[232:233], v[202:203]
	ds_read2_b32 v[188:189], v115 offset0:102 offset1:103
	ds_read2_b32 v[190:191], v115 offset0:104 offset1:105
	ds_read2_b32 v[192:193], v115 offset0:110 offset1:111
	ds_read2_b32 v[194:195], v115 offset0:112 offset1:113
	ds_read2_b32 v[196:197], v115 offset0:119 offset1:120
	ds_read2_b32 v[198:199], v115 offset0:121 offset1:122
	ds_read2_b32 v[200:201], v115 offset0:127 offset1:128
	ds_read2_b32 v[202:203], v115 offset0:129 offset1:130
	v_mfma_f32_32x32x16_bf16 v[0:15], v[64:67], v[72:75], v[0:15]
	v_mfma_f32_32x32x16_bf16 v[16:31], v[64:67], v[76:79], v[16:31]
	v_mfma_f32_32x32x16_bf16 v[0:15], v[68:71], v[220:223], v[0:15]
	v_mfma_f32_32x32x16_bf16 v[16:31], v[68:71], v[224:227], v[16:31]
	global_load_dwordx4 v[116:119], v235, s[84:85]
	global_load_dwordx4 v[120:123], v236, s[84:85]
	global_load_dwordx4 v[124:127], v237, s[84:85]
	global_load_dwordx4 v[128:131], v238, s[84:85]
	global_load_dwordx4 v[132:135], v100, s[84:85] offset:768
	global_load_dwordx4 v[136:139], v149, s[84:85] offset:768
	global_load_dwordx4 v[140:143], v100, s[84:85] offset:832
	global_load_dwordx4 v[144:147], v149, s[84:85] offset:832
	s_add_u32 s84, s84, 0x30000
	s_addc_u32 s85, s85, 0
	ds_read_b64_tr_b16 v[72:73], v231
	ds_read_b64_tr_b16 v[74:75], v231 offset:512
	ds_read_b64_tr_b16 v[76:77], v231 offset:2048
	ds_read_b64_tr_b16 v[78:79], v231 offset:2560
	ds_read_b64_tr_b16 v[220:221], v231 offset:1024
	ds_read_b64_tr_b16 v[222:223], v231 offset:1536
	ds_read_b64_tr_b16 v[224:225], v231 offset:3072
	ds_read_b64_tr_b16 v[226:227], v231 offset:3584
	v_exp_f32_e32 v32, v32
	v_exp_f32_e32 v33, v33
	v_exp_f32_e32 v34, v34
	v_exp_f32_e32 v35, v35
	s_waitcnt vmcnt(12)
	ds_write_b128 v247, v[156:159]
	ds_write_b128 v247, v[160:163] offset:1024
	ds_write_b128 v247, v[164:167] offset:2048
	ds_write_b128 v247, v[168:171] offset:3072
	ds_read_b128 v[156:159], v248
	ds_read_b128 v[160:163], v249
	ds_read_b128 v[164:167], v250
	ds_read_b128 v[168:171], v251
	s_waitcnt vmcnt(8)
	ds_write_b128 v112, v[172:175]
	ds_write_b128 v112, v[176:179] offset:1024
	ds_write_b128 v112, v[180:183] offset:2048
	ds_write_b128 v112, v[184:187] offset:3072
	v_exp_f32_e32 v36, v36
	v_exp_f32_e32 v37, v37
	v_exp_f32_e32 v38, v38
	v_exp_f32_e32 v39, v39
	s_waitcnt lgkmcnt(4)
	v_mfma_f32_32x32x16_bf16 v[188:203], v[156:159], v[48:51], v[188:203]
	v_exp_f32_e32 v40, v40
	v_exp_f32_e32 v41, v41
	v_mfma_f32_32x32x16_bf16 v[188:203], v[160:163], v[52:55], v[188:203]
	v_exp_f32_e32 v42, v42
	v_exp_f32_e32 v43, v43
	v_mfma_f32_32x32x16_bf16 v[188:203], v[164:167], v[56:59], v[188:203]
	v_exp_f32_e32 v44, v44
	v_exp_f32_e32 v45, v45
	v_mfma_f32_32x32x16_bf16 v[188:203], v[168:171], v[60:63], v[188:203]
	v_exp_f32_e32 v46, v46
	v_exp_f32_e32 v47, v47
	v_cvt_pk_bf16_f32 v64, v32, v33
	v_cvt_pk_bf16_f32 v65, v34, v35
	v_cvt_pk_bf16_f32 v66, v36, v37
	v_cvt_pk_bf16_f32 v67, v38, v39
	v_cvt_pk_bf16_f32 v68, v40, v41
	v_cvt_pk_bf16_f32 v69, v42, v43
	v_cvt_pk_bf16_f32 v70, v44, v45
	v_cvt_pk_bf16_f32 v71, v46, v47
	v_pk_add_f32 v[232:233], v[232:233], v[32:33]
	v_pk_add_f32 v[232:233], v[232:233], v[34:35]
	v_pk_add_f32 v[232:233], v[232:233], v[36:37]
	v_pk_add_f32 v[232:233], v[232:233], v[38:39]
	v_pk_add_f32 v[232:233], v[232:233], v[40:41]
	v_pk_add_f32 v[232:233], v[232:233], v[42:43]
	v_pk_add_f32 v[232:233], v[232:233], v[44:45]
	v_pk_add_f32 v[232:233], v[232:233], v[46:47]
	ds_read2_b32 v[32:33], v115 offset0:136 offset1:137
	ds_read2_b32 v[34:35], v115 offset0:138 offset1:139
	ds_read2_b32 v[36:37], v115 offset0:144 offset1:145
	ds_read2_b32 v[38:39], v115 offset0:146 offset1:147
	ds_read2_b32 v[40:41], v115 offset0:153 offset1:154
	ds_read2_b32 v[42:43], v115 offset0:155 offset1:156
	ds_read2_b32 v[44:45], v115 offset0:161 offset1:162
	ds_read2_b32 v[46:47], v115 offset0:163 offset1:164
	v_mfma_f32_32x32x16_bf16 v[0:15], v[64:67], v[72:75], v[0:15]
	v_mfma_f32_32x32x16_bf16 v[16:31], v[64:67], v[76:79], v[16:31]
	v_mfma_f32_32x32x16_bf16 v[0:15], v[68:71], v[220:223], v[0:15]
	v_mfma_f32_32x32x16_bf16 v[16:31], v[68:71], v[224:227], v[16:31]
	global_load_dwordx4 v[156:159], v235, s[84:85]
	global_load_dwordx4 v[160:163], v236, s[84:85]
	global_load_dwordx4 v[164:167], v237, s[84:85]
	global_load_dwordx4 v[168:171], v238, s[84:85]
	global_load_dwordx4 v[172:175], v100, s[84:85] offset:768
	global_load_dwordx4 v[176:179], v149, s[84:85] offset:768
	global_load_dwordx4 v[180:183], v100, s[84:85] offset:832
	global_load_dwordx4 v[184:187], v149, s[84:85] offset:832
	s_add_u32 s84, s84, 0x30000
	s_addc_u32 s85, s85, 0
	ds_read_b64_tr_b16 v[72:73], v231
	ds_read_b64_tr_b16 v[74:75], v231 offset:512
	ds_read_b64_tr_b16 v[76:77], v231 offset:2048
	ds_read_b64_tr_b16 v[78:79], v231 offset:2560
	ds_read_b64_tr_b16 v[220:221], v231 offset:1024
	ds_read_b64_tr_b16 v[222:223], v231 offset:1536
	ds_read_b64_tr_b16 v[224:225], v231 offset:3072
	ds_read_b64_tr_b16 v[226:227], v231 offset:3584
	v_exp_f32_e32 v188, v188
	v_exp_f32_e32 v189, v189
	v_exp_f32_e32 v190, v190
	v_exp_f32_e32 v191, v191
	s_waitcnt vmcnt(12)
	ds_write_b128 v247, v[116:119]
	ds_write_b128 v247, v[120:123] offset:1024
	ds_write_b128 v247, v[124:127] offset:2048
	ds_write_b128 v247, v[128:131] offset:3072
	ds_read_b128 v[116:119], v248
	ds_read_b128 v[120:123], v249
	ds_read_b128 v[124:127], v250
	ds_read_b128 v[128:131], v251
	s_waitcnt vmcnt(8)
	ds_write_b128 v112, v[132:135]
	ds_write_b128 v112, v[136:139] offset:1024
	ds_write_b128 v112, v[140:143] offset:2048
	ds_write_b128 v112, v[144:147] offset:3072
	v_exp_f32_e32 v192, v192
	v_exp_f32_e32 v193, v193
	v_exp_f32_e32 v194, v194
	v_exp_f32_e32 v195, v195
	s_waitcnt lgkmcnt(4)
	v_mfma_f32_32x32x16_bf16 v[32:47], v[116:119], v[48:51], v[32:47]
	v_exp_f32_e32 v196, v196
	v_exp_f32_e32 v197, v197
	v_mfma_f32_32x32x16_bf16 v[32:47], v[120:123], v[52:55], v[32:47]
	v_exp_f32_e32 v198, v198
	v_exp_f32_e32 v199, v199
	v_mfma_f32_32x32x16_bf16 v[32:47], v[124:127], v[56:59], v[32:47]
	v_exp_f32_e32 v200, v200
	v_exp_f32_e32 v201, v201
	v_mfma_f32_32x32x16_bf16 v[32:47], v[128:131], v[60:63], v[32:47]
	v_exp_f32_e32 v202, v202
	v_exp_f32_e32 v203, v203
	v_cvt_pk_bf16_f32 v64, v188, v189
	v_cvt_pk_bf16_f32 v65, v190, v191
	v_cvt_pk_bf16_f32 v66, v192, v193
	v_cvt_pk_bf16_f32 v67, v194, v195
	v_cvt_pk_bf16_f32 v68, v196, v197
	v_cvt_pk_bf16_f32 v69, v198, v199
	v_cvt_pk_bf16_f32 v70, v200, v201
	v_cvt_pk_bf16_f32 v71, v202, v203
	v_pk_add_f32 v[232:233], v[232:233], v[188:189]
	v_pk_add_f32 v[232:233], v[232:233], v[190:191]
	v_pk_add_f32 v[232:233], v[232:233], v[192:193]
	v_pk_add_f32 v[232:233], v[232:233], v[194:195]
	v_pk_add_f32 v[232:233], v[232:233], v[196:197]
	v_pk_add_f32 v[232:233], v[232:233], v[198:199]
	v_pk_add_f32 v[232:233], v[232:233], v[200:201]
	v_pk_add_f32 v[232:233], v[232:233], v[202:203]
	ds_read2_b32 v[188:189], v115 offset0:170 offset1:171
	ds_read2_b32 v[190:191], v115 offset0:172 offset1:173
	ds_read2_b32 v[192:193], v115 offset0:178 offset1:179
	ds_read2_b32 v[194:195], v115 offset0:180 offset1:181
	ds_read2_b32 v[196:197], v115 offset0:187 offset1:188
	ds_read2_b32 v[198:199], v115 offset0:189 offset1:190
	ds_read2_b32 v[200:201], v115 offset0:195 offset1:196
	ds_read2_b32 v[202:203], v115 offset0:197 offset1:198
	v_mfma_f32_32x32x16_bf16 v[0:15], v[64:67], v[72:75], v[0:15]
	v_mfma_f32_32x32x16_bf16 v[16:31], v[64:67], v[76:79], v[16:31]
	v_mfma_f32_32x32x16_bf16 v[0:15], v[68:71], v[220:223], v[0:15]
	v_mfma_f32_32x32x16_bf16 v[16:31], v[68:71], v[224:227], v[16:31]
	global_load_dwordx4 v[116:119], v235, s[84:85]
	global_load_dwordx4 v[120:123], v236, s[84:85]
	global_load_dwordx4 v[124:127], v237, s[84:85]
	global_load_dwordx4 v[128:131], v238, s[84:85]
	global_load_dwordx4 v[132:135], v100, s[84:85] offset:768
	global_load_dwordx4 v[136:139], v149, s[84:85] offset:768
	global_load_dwordx4 v[140:143], v100, s[84:85] offset:832
	global_load_dwordx4 v[144:147], v149, s[84:85] offset:832
	s_add_u32 s84, s84, 0x30000
	s_addc_u32 s85, s85, 0
	ds_read_b64_tr_b16 v[72:73], v231
	ds_read_b64_tr_b16 v[74:75], v231 offset:512
	ds_read_b64_tr_b16 v[76:77], v231 offset:2048
	ds_read_b64_tr_b16 v[78:79], v231 offset:2560
	ds_read_b64_tr_b16 v[220:221], v231 offset:1024
	ds_read_b64_tr_b16 v[222:223], v231 offset:1536
	ds_read_b64_tr_b16 v[224:225], v231 offset:3072
	ds_read_b64_tr_b16 v[226:227], v231 offset:3584
	v_exp_f32_e32 v32, v32
	v_exp_f32_e32 v33, v33
	v_exp_f32_e32 v34, v34
	v_exp_f32_e32 v35, v35
	s_waitcnt vmcnt(12)
	ds_write_b128 v247, v[156:159]
	ds_write_b128 v247, v[160:163] offset:1024
	ds_write_b128 v247, v[164:167] offset:2048
	ds_write_b128 v247, v[168:171] offset:3072
	ds_read_b128 v[156:159], v248
	ds_read_b128 v[160:163], v249
	ds_read_b128 v[164:167], v250
	ds_read_b128 v[168:171], v251
	s_waitcnt vmcnt(8)
	ds_write_b128 v112, v[172:175]
	ds_write_b128 v112, v[176:179] offset:1024
	ds_write_b128 v112, v[180:183] offset:2048
	ds_write_b128 v112, v[184:187] offset:3072
	v_exp_f32_e32 v36, v36
	v_exp_f32_e32 v37, v37
	v_exp_f32_e32 v38, v38
	v_exp_f32_e32 v39, v39
	s_waitcnt lgkmcnt(4)
	v_mfma_f32_32x32x16_bf16 v[188:203], v[156:159], v[48:51], v[188:203]
	v_exp_f32_e32 v40, v40
	v_exp_f32_e32 v41, v41
	v_mfma_f32_32x32x16_bf16 v[188:203], v[160:163], v[52:55], v[188:203]
	v_exp_f32_e32 v42, v42
	v_exp_f32_e32 v43, v43
	v_mfma_f32_32x32x16_bf16 v[188:203], v[164:167], v[56:59], v[188:203]
	v_exp_f32_e32 v44, v44
	v_exp_f32_e32 v45, v45
	v_mfma_f32_32x32x16_bf16 v[188:203], v[168:171], v[60:63], v[188:203]
	v_exp_f32_e32 v46, v46
	v_exp_f32_e32 v47, v47
	v_cvt_pk_bf16_f32 v64, v32, v33
	v_cvt_pk_bf16_f32 v65, v34, v35
	v_cvt_pk_bf16_f32 v66, v36, v37
	v_cvt_pk_bf16_f32 v67, v38, v39
	v_cvt_pk_bf16_f32 v68, v40, v41
	v_cvt_pk_bf16_f32 v69, v42, v43
	v_cvt_pk_bf16_f32 v70, v44, v45
	v_cvt_pk_bf16_f32 v71, v46, v47
	v_pk_add_f32 v[232:233], v[232:233], v[32:33]
	v_pk_add_f32 v[232:233], v[232:233], v[34:35]
	v_pk_add_f32 v[232:233], v[232:233], v[36:37]
	v_pk_add_f32 v[232:233], v[232:233], v[38:39]
	v_pk_add_f32 v[232:233], v[232:233], v[40:41]
	v_pk_add_f32 v[232:233], v[232:233], v[42:43]
	v_pk_add_f32 v[232:233], v[232:233], v[44:45]
	v_pk_add_f32 v[232:233], v[232:233], v[46:47]
	ds_read2_b32 v[32:33], v115 offset0:204 offset1:205
	ds_read2_b32 v[34:35], v115 offset0:206 offset1:207
	ds_read2_b32 v[36:37], v115 offset0:212 offset1:213
	ds_read2_b32 v[38:39], v115 offset0:214 offset1:215
	ds_read2_b32 v[40:41], v115 offset0:221 offset1:222
	ds_read2_b32 v[42:43], v115 offset0:223 offset1:224
	ds_read2_b32 v[44:45], v115 offset0:229 offset1:230
	ds_read2_b32 v[46:47], v115 offset0:231 offset1:232
	v_mfma_f32_32x32x16_bf16 v[0:15], v[64:67], v[72:75], v[0:15]
	v_mfma_f32_32x32x16_bf16 v[16:31], v[64:67], v[76:79], v[16:31]
	v_mfma_f32_32x32x16_bf16 v[0:15], v[68:71], v[220:223], v[0:15]
	v_mfma_f32_32x32x16_bf16 v[16:31], v[68:71], v[224:227], v[16:31]
	global_load_dwordx4 v[156:159], v235, s[84:85]
	global_load_dwordx4 v[160:163], v236, s[84:85]
	global_load_dwordx4 v[164:167], v237, s[84:85]
	global_load_dwordx4 v[168:171], v238, s[84:85]
	global_load_dwordx4 v[172:175], v100, s[84:85] offset:768
	global_load_dwordx4 v[176:179], v149, s[84:85] offset:768
	global_load_dwordx4 v[180:183], v100, s[84:85] offset:832
	global_load_dwordx4 v[184:187], v149, s[84:85] offset:832
	s_add_u32 s84, s84, 0x30000
	s_addc_u32 s85, s85, 0
	ds_read_b64_tr_b16 v[72:73], v231
	ds_read_b64_tr_b16 v[74:75], v231 offset:512
	ds_read_b64_tr_b16 v[76:77], v231 offset:2048
	ds_read_b64_tr_b16 v[78:79], v231 offset:2560
	ds_read_b64_tr_b16 v[220:221], v231 offset:1024
	ds_read_b64_tr_b16 v[222:223], v231 offset:1536
	ds_read_b64_tr_b16 v[224:225], v231 offset:3072
	ds_read_b64_tr_b16 v[226:227], v231 offset:3584
	v_exp_f32_e32 v188, v188
	v_exp_f32_e32 v189, v189
	v_exp_f32_e32 v190, v190
	v_exp_f32_e32 v191, v191
	s_waitcnt vmcnt(12)
	ds_write_b128 v247, v[116:119]
	ds_write_b128 v247, v[120:123] offset:1024
	ds_write_b128 v247, v[124:127] offset:2048
	ds_write_b128 v247, v[128:131] offset:3072
	ds_read_b128 v[116:119], v248
	ds_read_b128 v[120:123], v249
	ds_read_b128 v[124:127], v250
	ds_read_b128 v[128:131], v251
	s_waitcnt vmcnt(8)
	ds_write_b128 v112, v[132:135]
	ds_write_b128 v112, v[136:139] offset:1024
	ds_write_b128 v112, v[140:143] offset:2048
	ds_write_b128 v112, v[144:147] offset:3072
	v_exp_f32_e32 v192, v192
	v_exp_f32_e32 v193, v193
	v_exp_f32_e32 v194, v194
	v_exp_f32_e32 v195, v195
	s_waitcnt lgkmcnt(4)
	v_mfma_f32_32x32x16_bf16 v[32:47], v[116:119], v[48:51], v[32:47]
	v_exp_f32_e32 v196, v196
	v_exp_f32_e32 v197, v197
	v_mfma_f32_32x32x16_bf16 v[32:47], v[120:123], v[52:55], v[32:47]
	v_exp_f32_e32 v198, v198
	v_exp_f32_e32 v199, v199
	v_mfma_f32_32x32x16_bf16 v[32:47], v[124:127], v[56:59], v[32:47]
	v_exp_f32_e32 v200, v200
	v_exp_f32_e32 v201, v201
	v_mfma_f32_32x32x16_bf16 v[32:47], v[128:131], v[60:63], v[32:47]
	v_exp_f32_e32 v202, v202
	v_exp_f32_e32 v203, v203
	v_cvt_pk_bf16_f32 v64, v188, v189
	v_cvt_pk_bf16_f32 v65, v190, v191
	v_cvt_pk_bf16_f32 v66, v192, v193
	v_cvt_pk_bf16_f32 v67, v194, v195
	v_cvt_pk_bf16_f32 v68, v196, v197
	v_cvt_pk_bf16_f32 v69, v198, v199
	v_cvt_pk_bf16_f32 v70, v200, v201
	v_cvt_pk_bf16_f32 v71, v202, v203
	v_pk_add_f32 v[232:233], v[232:233], v[188:189]
	v_pk_add_f32 v[232:233], v[232:233], v[190:191]
	v_pk_add_f32 v[232:233], v[232:233], v[192:193]
	v_pk_add_f32 v[232:233], v[232:233], v[194:195]
	v_pk_add_f32 v[232:233], v[232:233], v[196:197]
	v_pk_add_f32 v[232:233], v[232:233], v[198:199]
	v_pk_add_f32 v[232:233], v[232:233], v[200:201]
	v_pk_add_f32 v[232:233], v[232:233], v[202:203]
	v_add_u32_e32 v115, 952, v115
	ds_read2_b32 v[188:189], v115 offset0:0 offset1:1
	ds_read2_b32 v[190:191], v115 offset0:2 offset1:3
	ds_read2_b32 v[192:193], v115 offset0:8 offset1:9
	ds_read2_b32 v[194:195], v115 offset0:10 offset1:11
	ds_read2_b32 v[196:197], v115 offset0:17 offset1:18
	ds_read2_b32 v[198:199], v115 offset0:19 offset1:20
	ds_read2_b32 v[200:201], v115 offset0:25 offset1:26
	ds_read2_b32 v[202:203], v115 offset0:27 offset1:28
	v_mfma_f32_32x32x16_bf16 v[0:15], v[64:67], v[72:75], v[0:15]
	v_mfma_f32_32x32x16_bf16 v[16:31], v[64:67], v[76:79], v[16:31]
	v_mfma_f32_32x32x16_bf16 v[0:15], v[68:71], v[220:223], v[0:15]
	v_mfma_f32_32x32x16_bf16 v[16:31], v[68:71], v[224:227], v[16:31]
	global_load_dwordx4 v[116:119], v235, s[84:85]
	global_load_dwordx4 v[120:123], v236, s[84:85]
	global_load_dwordx4 v[124:127], v237, s[84:85]
	global_load_dwordx4 v[128:131], v238, s[84:85]
	global_load_dwordx4 v[132:135], v100, s[84:85] offset:768
	global_load_dwordx4 v[136:139], v149, s[84:85] offset:768
	global_load_dwordx4 v[140:143], v100, s[84:85] offset:832
	global_load_dwordx4 v[144:147], v149, s[84:85] offset:832
	s_add_u32 s84, s84, 0x30000
	s_addc_u32 s85, s85, 0
	ds_read_b64_tr_b16 v[72:73], v231
	ds_read_b64_tr_b16 v[74:75], v231 offset:512
	ds_read_b64_tr_b16 v[76:77], v231 offset:2048
	ds_read_b64_tr_b16 v[78:79], v231 offset:2560
	ds_read_b64_tr_b16 v[220:221], v231 offset:1024
	ds_read_b64_tr_b16 v[222:223], v231 offset:1536
	ds_read_b64_tr_b16 v[224:225], v231 offset:3072
	ds_read_b64_tr_b16 v[226:227], v231 offset:3584
	v_exp_f32_e32 v32, v32
	v_exp_f32_e32 v33, v33
	v_exp_f32_e32 v34, v34
	v_exp_f32_e32 v35, v35
	s_waitcnt vmcnt(12)
	ds_write_b128 v247, v[156:159]
	ds_write_b128 v247, v[160:163] offset:1024
	ds_write_b128 v247, v[164:167] offset:2048
	ds_write_b128 v247, v[168:171] offset:3072
	ds_read_b128 v[156:159], v248
	ds_read_b128 v[160:163], v249
	ds_read_b128 v[164:167], v250
	ds_read_b128 v[168:171], v251
	s_waitcnt vmcnt(8)
	ds_write_b128 v112, v[172:175]
	ds_write_b128 v112, v[176:179] offset:1024
	ds_write_b128 v112, v[180:183] offset:2048
	ds_write_b128 v112, v[184:187] offset:3072
	v_exp_f32_e32 v36, v36
	v_exp_f32_e32 v37, v37
	v_exp_f32_e32 v38, v38
	v_exp_f32_e32 v39, v39
	s_waitcnt lgkmcnt(4)
	v_mfma_f32_32x32x16_bf16 v[188:203], v[156:159], v[48:51], v[188:203]
	v_exp_f32_e32 v40, v40
	v_exp_f32_e32 v41, v41
	v_mfma_f32_32x32x16_bf16 v[188:203], v[160:163], v[52:55], v[188:203]
	v_exp_f32_e32 v42, v42
	v_exp_f32_e32 v43, v43
	v_mfma_f32_32x32x16_bf16 v[188:203], v[164:167], v[56:59], v[188:203]
	v_exp_f32_e32 v44, v44
	v_exp_f32_e32 v45, v45
	v_mfma_f32_32x32x16_bf16 v[188:203], v[168:171], v[60:63], v[188:203]
	v_exp_f32_e32 v46, v46
	v_exp_f32_e32 v47, v47
	v_cvt_pk_bf16_f32 v64, v32, v33
	v_cvt_pk_bf16_f32 v65, v34, v35
	v_cvt_pk_bf16_f32 v66, v36, v37
	v_cvt_pk_bf16_f32 v67, v38, v39
	v_cvt_pk_bf16_f32 v68, v40, v41
	v_cvt_pk_bf16_f32 v69, v42, v43
	v_cvt_pk_bf16_f32 v70, v44, v45
	v_cvt_pk_bf16_f32 v71, v46, v47
	v_pk_add_f32 v[232:233], v[232:233], v[32:33]
	v_pk_add_f32 v[232:233], v[232:233], v[34:35]
	v_pk_add_f32 v[232:233], v[232:233], v[36:37]
	v_pk_add_f32 v[232:233], v[232:233], v[38:39]
	v_pk_add_f32 v[232:233], v[232:233], v[40:41]
	v_pk_add_f32 v[232:233], v[232:233], v[42:43]
	v_pk_add_f32 v[232:233], v[232:233], v[44:45]
	v_pk_add_f32 v[232:233], v[232:233], v[46:47]
	ds_read2_b32 v[32:33], v115 offset0:34 offset1:35
	ds_read2_b32 v[34:35], v115 offset0:36 offset1:37
	ds_read2_b32 v[36:37], v115 offset0:42 offset1:43
	ds_read2_b32 v[38:39], v115 offset0:44 offset1:45
	ds_read2_b32 v[40:41], v115 offset0:51 offset1:52
	ds_read2_b32 v[42:43], v115 offset0:53 offset1:54
	ds_read2_b32 v[44:45], v115 offset0:59 offset1:60
	ds_read2_b32 v[46:47], v115 offset0:61 offset1:62
	v_mfma_f32_32x32x16_bf16 v[0:15], v[64:67], v[72:75], v[0:15]
	v_mfma_f32_32x32x16_bf16 v[16:31], v[64:67], v[76:79], v[16:31]
	v_mfma_f32_32x32x16_bf16 v[0:15], v[68:71], v[220:223], v[0:15]
	v_mfma_f32_32x32x16_bf16 v[16:31], v[68:71], v[224:227], v[16:31]
	global_load_dwordx4 v[156:159], v235, s[84:85]
	global_load_dwordx4 v[160:163], v236, s[84:85]
	global_load_dwordx4 v[164:167], v237, s[84:85]
	global_load_dwordx4 v[168:171], v238, s[84:85]
	global_load_dwordx4 v[172:175], v100, s[84:85] offset:768
	global_load_dwordx4 v[176:179], v149, s[84:85] offset:768
	global_load_dwordx4 v[180:183], v100, s[84:85] offset:832
	global_load_dwordx4 v[184:187], v149, s[84:85] offset:832
	s_add_u32 s84, s84, 0x30000
	s_addc_u32 s85, s85, 0
	ds_read_b64_tr_b16 v[72:73], v231
	ds_read_b64_tr_b16 v[74:75], v231 offset:512
	ds_read_b64_tr_b16 v[76:77], v231 offset:2048
	ds_read_b64_tr_b16 v[78:79], v231 offset:2560
	ds_read_b64_tr_b16 v[220:221], v231 offset:1024
	ds_read_b64_tr_b16 v[222:223], v231 offset:1536
	ds_read_b64_tr_b16 v[224:225], v231 offset:3072
	ds_read_b64_tr_b16 v[226:227], v231 offset:3584
	v_exp_f32_e32 v188, v188
	v_exp_f32_e32 v189, v189
	v_exp_f32_e32 v190, v190
	v_exp_f32_e32 v191, v191
	s_waitcnt vmcnt(12)
	ds_write_b128 v247, v[116:119]
	ds_write_b128 v247, v[120:123] offset:1024
	ds_write_b128 v247, v[124:127] offset:2048
	ds_write_b128 v247, v[128:131] offset:3072
	ds_read_b128 v[116:119], v248
	ds_read_b128 v[120:123], v249
	ds_read_b128 v[124:127], v250
	ds_read_b128 v[128:131], v251
	s_waitcnt vmcnt(8)
	ds_write_b128 v112, v[132:135]
	ds_write_b128 v112, v[136:139] offset:1024
	ds_write_b128 v112, v[140:143] offset:2048
	ds_write_b128 v112, v[144:147] offset:3072
	v_exp_f32_e32 v192, v192
	v_exp_f32_e32 v193, v193
	v_exp_f32_e32 v194, v194
	v_exp_f32_e32 v195, v195
	s_waitcnt lgkmcnt(4)
	v_mfma_f32_32x32x16_bf16 v[32:47], v[116:119], v[48:51], v[32:47]
	v_exp_f32_e32 v196, v196
	v_exp_f32_e32 v197, v197
	v_mfma_f32_32x32x16_bf16 v[32:47], v[120:123], v[52:55], v[32:47]
	v_exp_f32_e32 v198, v198
	v_exp_f32_e32 v199, v199
	v_mfma_f32_32x32x16_bf16 v[32:47], v[124:127], v[56:59], v[32:47]
	v_exp_f32_e32 v200, v200
	v_exp_f32_e32 v201, v201
	v_mfma_f32_32x32x16_bf16 v[32:47], v[128:131], v[60:63], v[32:47]
	v_exp_f32_e32 v202, v202
	v_exp_f32_e32 v203, v203
	v_cvt_pk_bf16_f32 v64, v188, v189
	v_cvt_pk_bf16_f32 v65, v190, v191
	v_cvt_pk_bf16_f32 v66, v192, v193
	v_cvt_pk_bf16_f32 v67, v194, v195
	v_cvt_pk_bf16_f32 v68, v196, v197
	v_cvt_pk_bf16_f32 v69, v198, v199
	v_cvt_pk_bf16_f32 v70, v200, v201
	v_cvt_pk_bf16_f32 v71, v202, v203
	v_pk_add_f32 v[232:233], v[232:233], v[188:189]
	v_pk_add_f32 v[232:233], v[232:233], v[190:191]
	v_pk_add_f32 v[232:233], v[232:233], v[192:193]
	v_pk_add_f32 v[232:233], v[232:233], v[194:195]
	v_pk_add_f32 v[232:233], v[232:233], v[196:197]
	v_pk_add_f32 v[232:233], v[232:233], v[198:199]
	v_pk_add_f32 v[232:233], v[232:233], v[200:201]
	v_pk_add_f32 v[232:233], v[232:233], v[202:203]
	ds_read2_b32 v[188:189], v115 offset0:68 offset1:69
	ds_read2_b32 v[190:191], v115 offset0:70 offset1:71
	ds_read2_b32 v[192:193], v115 offset0:76 offset1:77
	ds_read2_b32 v[194:195], v115 offset0:78 offset1:79
	ds_read2_b32 v[196:197], v115 offset0:85 offset1:86
	ds_read2_b32 v[198:199], v115 offset0:87 offset1:88
	ds_read2_b32 v[200:201], v115 offset0:93 offset1:94
	ds_read2_b32 v[202:203], v115 offset0:95 offset1:96
	v_mfma_f32_32x32x16_bf16 v[0:15], v[64:67], v[72:75], v[0:15]
	v_mfma_f32_32x32x16_bf16 v[16:31], v[64:67], v[76:79], v[16:31]
	v_mfma_f32_32x32x16_bf16 v[0:15], v[68:71], v[220:223], v[0:15]
	v_mfma_f32_32x32x16_bf16 v[16:31], v[68:71], v[224:227], v[16:31]
	global_load_dwordx4 v[116:119], v235, s[84:85]
	global_load_dwordx4 v[120:123], v236, s[84:85]
	global_load_dwordx4 v[124:127], v237, s[84:85]
	global_load_dwordx4 v[128:131], v238, s[84:85]
	global_load_dwordx4 v[132:135], v100, s[84:85] offset:768
	global_load_dwordx4 v[136:139], v149, s[84:85] offset:768
	global_load_dwordx4 v[140:143], v100, s[84:85] offset:832
	global_load_dwordx4 v[144:147], v149, s[84:85] offset:832
	s_add_u32 s84, s84, 0x30000
	s_addc_u32 s85, s85, 0
	ds_read_b64_tr_b16 v[72:73], v231
	ds_read_b64_tr_b16 v[74:75], v231 offset:512
	ds_read_b64_tr_b16 v[76:77], v231 offset:2048
	ds_read_b64_tr_b16 v[78:79], v231 offset:2560
	ds_read_b64_tr_b16 v[220:221], v231 offset:1024
	ds_read_b64_tr_b16 v[222:223], v231 offset:1536
	ds_read_b64_tr_b16 v[224:225], v231 offset:3072
	ds_read_b64_tr_b16 v[226:227], v231 offset:3584
	v_exp_f32_e32 v32, v32
	v_exp_f32_e32 v33, v33
	v_exp_f32_e32 v34, v34
	v_exp_f32_e32 v35, v35
	s_waitcnt vmcnt(12)
	ds_write_b128 v247, v[156:159]
	ds_write_b128 v247, v[160:163] offset:1024
	ds_write_b128 v247, v[164:167] offset:2048
	ds_write_b128 v247, v[168:171] offset:3072
	ds_read_b128 v[156:159], v248
	ds_read_b128 v[160:163], v249
	ds_read_b128 v[164:167], v250
	ds_read_b128 v[168:171], v251
	s_waitcnt vmcnt(8)
	ds_write_b128 v112, v[172:175]
	ds_write_b128 v112, v[176:179] offset:1024
	ds_write_b128 v112, v[180:183] offset:2048
	ds_write_b128 v112, v[184:187] offset:3072
	v_exp_f32_e32 v36, v36
	v_exp_f32_e32 v37, v37
	v_exp_f32_e32 v38, v38
	v_exp_f32_e32 v39, v39
	s_waitcnt lgkmcnt(4)
	v_mfma_f32_32x32x16_bf16 v[188:203], v[156:159], v[48:51], v[188:203]
	v_exp_f32_e32 v40, v40
	v_exp_f32_e32 v41, v41
	v_mfma_f32_32x32x16_bf16 v[188:203], v[160:163], v[52:55], v[188:203]
	v_exp_f32_e32 v42, v42
	v_exp_f32_e32 v43, v43
	v_mfma_f32_32x32x16_bf16 v[188:203], v[164:167], v[56:59], v[188:203]
	v_exp_f32_e32 v44, v44
	v_exp_f32_e32 v45, v45
	v_mfma_f32_32x32x16_bf16 v[188:203], v[168:171], v[60:63], v[188:203]
	v_exp_f32_e32 v46, v46
	v_exp_f32_e32 v47, v47
	v_cvt_pk_bf16_f32 v64, v32, v33
	v_cvt_pk_bf16_f32 v65, v34, v35
	v_cvt_pk_bf16_f32 v66, v36, v37
	v_cvt_pk_bf16_f32 v67, v38, v39
	v_cvt_pk_bf16_f32 v68, v40, v41
	v_cvt_pk_bf16_f32 v69, v42, v43
	v_cvt_pk_bf16_f32 v70, v44, v45
	v_cvt_pk_bf16_f32 v71, v46, v47
	v_pk_add_f32 v[232:233], v[232:233], v[32:33]
	v_pk_add_f32 v[232:233], v[232:233], v[34:35]
	v_pk_add_f32 v[232:233], v[232:233], v[36:37]
	v_pk_add_f32 v[232:233], v[232:233], v[38:39]
	v_pk_add_f32 v[232:233], v[232:233], v[40:41]
	v_pk_add_f32 v[232:233], v[232:233], v[42:43]
	v_pk_add_f32 v[232:233], v[232:233], v[44:45]
	v_pk_add_f32 v[232:233], v[232:233], v[46:47]
	ds_read2_b32 v[32:33], v115 offset0:102 offset1:103
	ds_read2_b32 v[34:35], v115 offset0:104 offset1:105
	ds_read2_b32 v[36:37], v115 offset0:110 offset1:111
	ds_read2_b32 v[38:39], v115 offset0:112 offset1:113
	ds_read2_b32 v[40:41], v115 offset0:119 offset1:120
	ds_read2_b32 v[42:43], v115 offset0:121 offset1:122
	ds_read2_b32 v[44:45], v115 offset0:127 offset1:128
	ds_read2_b32 v[46:47], v115 offset0:129 offset1:130
	v_mfma_f32_32x32x16_bf16 v[0:15], v[64:67], v[72:75], v[0:15]
	v_mfma_f32_32x32x16_bf16 v[16:31], v[64:67], v[76:79], v[16:31]
	v_mfma_f32_32x32x16_bf16 v[0:15], v[68:71], v[220:223], v[0:15]
	v_mfma_f32_32x32x16_bf16 v[16:31], v[68:71], v[224:227], v[16:31]
	global_load_dwordx4 v[156:159], v235, s[84:85]
	global_load_dwordx4 v[160:163], v236, s[84:85]
	global_load_dwordx4 v[164:167], v237, s[84:85]
	global_load_dwordx4 v[168:171], v238, s[84:85]
	global_load_dwordx4 v[172:175], v100, s[84:85] offset:768
	global_load_dwordx4 v[176:179], v149, s[84:85] offset:768
	global_load_dwordx4 v[180:183], v100, s[84:85] offset:832
	global_load_dwordx4 v[184:187], v149, s[84:85] offset:832
	s_add_u32 s84, s84, 0x30000
	s_addc_u32 s85, s85, 0
	ds_read_b64_tr_b16 v[72:73], v231
	ds_read_b64_tr_b16 v[74:75], v231 offset:512
	ds_read_b64_tr_b16 v[76:77], v231 offset:2048
	ds_read_b64_tr_b16 v[78:79], v231 offset:2560
	ds_read_b64_tr_b16 v[220:221], v231 offset:1024
	ds_read_b64_tr_b16 v[222:223], v231 offset:1536
	ds_read_b64_tr_b16 v[224:225], v231 offset:3072
	ds_read_b64_tr_b16 v[226:227], v231 offset:3584
	v_exp_f32_e32 v188, v188
	v_exp_f32_e32 v189, v189
	v_exp_f32_e32 v190, v190
	v_exp_f32_e32 v191, v191
	s_waitcnt vmcnt(12)
	ds_write_b128 v247, v[116:119]
	ds_write_b128 v247, v[120:123] offset:1024
	ds_write_b128 v247, v[124:127] offset:2048
	ds_write_b128 v247, v[128:131] offset:3072
	ds_read_b128 v[116:119], v248
	ds_read_b128 v[120:123], v249
	ds_read_b128 v[124:127], v250
	ds_read_b128 v[128:131], v251
	s_waitcnt vmcnt(8)
	ds_write_b128 v112, v[132:135]
	ds_write_b128 v112, v[136:139] offset:1024
	ds_write_b128 v112, v[140:143] offset:2048
	ds_write_b128 v112, v[144:147] offset:3072
	v_exp_f32_e32 v192, v192
	v_exp_f32_e32 v193, v193
	v_exp_f32_e32 v194, v194
	v_exp_f32_e32 v195, v195
	s_waitcnt lgkmcnt(4)
	v_mfma_f32_32x32x16_bf16 v[32:47], v[116:119], v[48:51], v[32:47]
	v_exp_f32_e32 v196, v196
	v_exp_f32_e32 v197, v197
	v_mfma_f32_32x32x16_bf16 v[32:47], v[120:123], v[52:55], v[32:47]
	v_exp_f32_e32 v198, v198
	v_exp_f32_e32 v199, v199
	v_mfma_f32_32x32x16_bf16 v[32:47], v[124:127], v[56:59], v[32:47]
	v_exp_f32_e32 v200, v200
	v_exp_f32_e32 v201, v201
	v_mfma_f32_32x32x16_bf16 v[32:47], v[128:131], v[60:63], v[32:47]
	v_exp_f32_e32 v202, v202
	v_exp_f32_e32 v203, v203
	v_cvt_pk_bf16_f32 v64, v188, v189
	v_cvt_pk_bf16_f32 v65, v190, v191
	v_cvt_pk_bf16_f32 v66, v192, v193
	v_cvt_pk_bf16_f32 v67, v194, v195
	v_cvt_pk_bf16_f32 v68, v196, v197
	v_cvt_pk_bf16_f32 v69, v198, v199
	v_cvt_pk_bf16_f32 v70, v200, v201
	v_cvt_pk_bf16_f32 v71, v202, v203
	v_pk_add_f32 v[232:233], v[232:233], v[188:189]
	v_pk_add_f32 v[232:233], v[232:233], v[190:191]
	v_pk_add_f32 v[232:233], v[232:233], v[192:193]
	v_pk_add_f32 v[232:233], v[232:233], v[194:195]
	v_pk_add_f32 v[232:233], v[232:233], v[196:197]
	v_pk_add_f32 v[232:233], v[232:233], v[198:199]
	v_pk_add_f32 v[232:233], v[232:233], v[200:201]
	v_pk_add_f32 v[232:233], v[232:233], v[202:203]
	ds_read2_b32 v[188:189], v115 offset0:136 offset1:137
	ds_read2_b32 v[190:191], v115 offset0:138 offset1:139
	ds_read2_b32 v[192:193], v115 offset0:144 offset1:145
	ds_read2_b32 v[194:195], v115 offset0:146 offset1:147
	ds_read2_b32 v[196:197], v115 offset0:153 offset1:154
	ds_read2_b32 v[198:199], v115 offset0:155 offset1:156
	ds_read2_b32 v[200:201], v115 offset0:161 offset1:162
	ds_read2_b32 v[202:203], v115 offset0:163 offset1:164
	v_mfma_f32_32x32x16_bf16 v[0:15], v[64:67], v[72:75], v[0:15]
	v_mfma_f32_32x32x16_bf16 v[16:31], v[64:67], v[76:79], v[16:31]
	v_mfma_f32_32x32x16_bf16 v[0:15], v[68:71], v[220:223], v[0:15]
	v_mfma_f32_32x32x16_bf16 v[16:31], v[68:71], v[224:227], v[16:31]
	global_load_dwordx4 v[116:119], v235, s[84:85]
	global_load_dwordx4 v[120:123], v236, s[84:85]
	global_load_dwordx4 v[124:127], v237, s[84:85]
	global_load_dwordx4 v[128:131], v238, s[84:85]
	global_load_dwordx4 v[132:135], v100, s[84:85] offset:768
	global_load_dwordx4 v[136:139], v149, s[84:85] offset:768
	global_load_dwordx4 v[140:143], v100, s[84:85] offset:832
	global_load_dwordx4 v[144:147], v149, s[84:85] offset:832
	s_add_u32 s84, s84, 0x30000
	s_addc_u32 s85, s85, 0
	ds_read_b64_tr_b16 v[72:73], v231
	ds_read_b64_tr_b16 v[74:75], v231 offset:512
	ds_read_b64_tr_b16 v[76:77], v231 offset:2048
	ds_read_b64_tr_b16 v[78:79], v231 offset:2560
	ds_read_b64_tr_b16 v[220:221], v231 offset:1024
	ds_read_b64_tr_b16 v[222:223], v231 offset:1536
	ds_read_b64_tr_b16 v[224:225], v231 offset:3072
	ds_read_b64_tr_b16 v[226:227], v231 offset:3584
	v_exp_f32_e32 v32, v32
	v_exp_f32_e32 v33, v33
	v_exp_f32_e32 v34, v34
	v_exp_f32_e32 v35, v35
	s_waitcnt vmcnt(12)
	ds_write_b128 v247, v[156:159]
	ds_write_b128 v247, v[160:163] offset:1024
	ds_write_b128 v247, v[164:167] offset:2048
	ds_write_b128 v247, v[168:171] offset:3072
	ds_read_b128 v[156:159], v248
	ds_read_b128 v[160:163], v249
	ds_read_b128 v[164:167], v250
	ds_read_b128 v[168:171], v251
	s_waitcnt vmcnt(8)
	ds_write_b128 v112, v[172:175]
	ds_write_b128 v112, v[176:179] offset:1024
	ds_write_b128 v112, v[180:183] offset:2048
	ds_write_b128 v112, v[184:187] offset:3072
	v_exp_f32_e32 v36, v36
	v_exp_f32_e32 v37, v37
	v_exp_f32_e32 v38, v38
	v_exp_f32_e32 v39, v39
	s_waitcnt lgkmcnt(4)
	v_mfma_f32_32x32x16_bf16 v[188:203], v[156:159], v[48:51], v[188:203]
	v_exp_f32_e32 v40, v40
	v_exp_f32_e32 v41, v41
	v_mfma_f32_32x32x16_bf16 v[188:203], v[160:163], v[52:55], v[188:203]
	v_exp_f32_e32 v42, v42
	v_exp_f32_e32 v43, v43
	v_mfma_f32_32x32x16_bf16 v[188:203], v[164:167], v[56:59], v[188:203]
	v_exp_f32_e32 v44, v44
	v_exp_f32_e32 v45, v45
	v_mfma_f32_32x32x16_bf16 v[188:203], v[168:171], v[60:63], v[188:203]
	v_exp_f32_e32 v46, v46
	v_exp_f32_e32 v47, v47
	v_cvt_pk_bf16_f32 v64, v32, v33
	v_cvt_pk_bf16_f32 v65, v34, v35
	v_cvt_pk_bf16_f32 v66, v36, v37
	v_cvt_pk_bf16_f32 v67, v38, v39
	v_cvt_pk_bf16_f32 v68, v40, v41
	v_cvt_pk_bf16_f32 v69, v42, v43
	v_cvt_pk_bf16_f32 v70, v44, v45
	v_cvt_pk_bf16_f32 v71, v46, v47
	v_pk_add_f32 v[232:233], v[232:233], v[32:33]
	v_pk_add_f32 v[232:233], v[232:233], v[34:35]
	v_pk_add_f32 v[232:233], v[232:233], v[36:37]
	v_pk_add_f32 v[232:233], v[232:233], v[38:39]
	v_pk_add_f32 v[232:233], v[232:233], v[40:41]
	v_pk_add_f32 v[232:233], v[232:233], v[42:43]
	v_pk_add_f32 v[232:233], v[232:233], v[44:45]
	v_pk_add_f32 v[232:233], v[232:233], v[46:47]
	ds_read2_b32 v[32:33], v115 offset0:170 offset1:171
	ds_read2_b32 v[34:35], v115 offset0:172 offset1:173
	ds_read2_b32 v[36:37], v115 offset0:178 offset1:179
	ds_read2_b32 v[38:39], v115 offset0:180 offset1:181
	ds_read2_b32 v[40:41], v115 offset0:187 offset1:188
	ds_read2_b32 v[42:43], v115 offset0:189 offset1:190
	ds_read2_b32 v[44:45], v115 offset0:195 offset1:196
	ds_read2_b32 v[46:47], v115 offset0:197 offset1:198
	v_mfma_f32_32x32x16_bf16 v[0:15], v[64:67], v[72:75], v[0:15]
	v_mfma_f32_32x32x16_bf16 v[16:31], v[64:67], v[76:79], v[16:31]
	v_mfma_f32_32x32x16_bf16 v[0:15], v[68:71], v[220:223], v[0:15]
	v_mfma_f32_32x32x16_bf16 v[16:31], v[68:71], v[224:227], v[16:31]
	global_load_dwordx4 v[156:159], v235, s[84:85]
	global_load_dwordx4 v[160:163], v236, s[84:85]
	global_load_dwordx4 v[164:167], v237, s[84:85]
	global_load_dwordx4 v[168:171], v238, s[84:85]
	global_load_dwordx4 v[172:175], v100, s[84:85] offset:768
	global_load_dwordx4 v[176:179], v149, s[84:85] offset:768
	global_load_dwordx4 v[180:183], v100, s[84:85] offset:832
	global_load_dwordx4 v[184:187], v149, s[84:85] offset:832
	s_add_u32 s84, s84, 0x30000
	s_addc_u32 s85, s85, 0
	ds_read_b64_tr_b16 v[72:73], v231
	ds_read_b64_tr_b16 v[74:75], v231 offset:512
	ds_read_b64_tr_b16 v[76:77], v231 offset:2048
	ds_read_b64_tr_b16 v[78:79], v231 offset:2560
	ds_read_b64_tr_b16 v[220:221], v231 offset:1024
	ds_read_b64_tr_b16 v[222:223], v231 offset:1536
	ds_read_b64_tr_b16 v[224:225], v231 offset:3072
	ds_read_b64_tr_b16 v[226:227], v231 offset:3584
	v_exp_f32_e32 v188, v188
	v_exp_f32_e32 v189, v189
	v_exp_f32_e32 v190, v190
	v_exp_f32_e32 v191, v191
	s_waitcnt vmcnt(12)
	ds_write_b128 v247, v[116:119]
	ds_write_b128 v247, v[120:123] offset:1024
	ds_write_b128 v247, v[124:127] offset:2048
	ds_write_b128 v247, v[128:131] offset:3072
	ds_read_b128 v[116:119], v248
	ds_read_b128 v[120:123], v249
	ds_read_b128 v[124:127], v250
	ds_read_b128 v[128:131], v251
	s_waitcnt vmcnt(8)
	ds_write_b128 v112, v[132:135]
	ds_write_b128 v112, v[136:139] offset:1024
	ds_write_b128 v112, v[140:143] offset:2048
	ds_write_b128 v112, v[144:147] offset:3072
	v_exp_f32_e32 v192, v192
	v_exp_f32_e32 v193, v193
	v_exp_f32_e32 v194, v194
	v_exp_f32_e32 v195, v195
	s_waitcnt lgkmcnt(4)
	v_mfma_f32_32x32x16_bf16 v[32:47], v[116:119], v[48:51], v[32:47]
	v_exp_f32_e32 v196, v196
	v_exp_f32_e32 v197, v197
	v_mfma_f32_32x32x16_bf16 v[32:47], v[120:123], v[52:55], v[32:47]
	v_exp_f32_e32 v198, v198
	v_exp_f32_e32 v199, v199
	v_mfma_f32_32x32x16_bf16 v[32:47], v[124:127], v[56:59], v[32:47]
	v_exp_f32_e32 v200, v200
	v_exp_f32_e32 v201, v201
	v_mfma_f32_32x32x16_bf16 v[32:47], v[128:131], v[60:63], v[32:47]
	v_exp_f32_e32 v202, v202
	v_exp_f32_e32 v203, v203
	v_cvt_pk_bf16_f32 v64, v188, v189
	v_cvt_pk_bf16_f32 v65, v190, v191
	v_cvt_pk_bf16_f32 v66, v192, v193
	v_cvt_pk_bf16_f32 v67, v194, v195
	v_cvt_pk_bf16_f32 v68, v196, v197
	v_cvt_pk_bf16_f32 v69, v198, v199
	v_cvt_pk_bf16_f32 v70, v200, v201
	v_cvt_pk_bf16_f32 v71, v202, v203
	v_pk_add_f32 v[232:233], v[232:233], v[188:189]
	v_pk_add_f32 v[232:233], v[232:233], v[190:191]
	v_pk_add_f32 v[232:233], v[232:233], v[192:193]
	v_pk_add_f32 v[232:233], v[232:233], v[194:195]
	v_pk_add_f32 v[232:233], v[232:233], v[196:197]
	v_pk_add_f32 v[232:233], v[232:233], v[198:199]
	v_pk_add_f32 v[232:233], v[232:233], v[200:201]
	v_pk_add_f32 v[232:233], v[232:233], v[202:203]
	ds_read2_b32 v[188:189], v115 offset0:204 offset1:205
	ds_read2_b32 v[190:191], v115 offset0:206 offset1:207
	ds_read2_b32 v[192:193], v115 offset0:212 offset1:213
	ds_read2_b32 v[194:195], v115 offset0:214 offset1:215
	ds_read2_b32 v[196:197], v115 offset0:221 offset1:222
	ds_read2_b32 v[198:199], v115 offset0:223 offset1:224
	ds_read2_b32 v[200:201], v115 offset0:229 offset1:230
	ds_read2_b32 v[202:203], v115 offset0:231 offset1:232
	v_mfma_f32_32x32x16_bf16 v[0:15], v[64:67], v[72:75], v[0:15]
	v_mfma_f32_32x32x16_bf16 v[16:31], v[64:67], v[76:79], v[16:31]
	v_mfma_f32_32x32x16_bf16 v[0:15], v[68:71], v[220:223], v[0:15]
	v_mfma_f32_32x32x16_bf16 v[16:31], v[68:71], v[224:227], v[16:31]
	global_load_dwordx4 v[116:119], v235, s[84:85]
	global_load_dwordx4 v[120:123], v236, s[84:85]
	global_load_dwordx4 v[124:127], v237, s[84:85]
	global_load_dwordx4 v[128:131], v238, s[84:85]
	global_load_dwordx4 v[132:135], v100, s[84:85] offset:768
	global_load_dwordx4 v[136:139], v149, s[84:85] offset:768
	global_load_dwordx4 v[140:143], v100, s[84:85] offset:832
	global_load_dwordx4 v[144:147], v149, s[84:85] offset:832
	s_add_u32 s84, s84, 0x30000
	s_addc_u32 s85, s85, 0
	ds_read_b64_tr_b16 v[72:73], v231
	ds_read_b64_tr_b16 v[74:75], v231 offset:512
	ds_read_b64_tr_b16 v[76:77], v231 offset:2048
	ds_read_b64_tr_b16 v[78:79], v231 offset:2560
	ds_read_b64_tr_b16 v[220:221], v231 offset:1024
	ds_read_b64_tr_b16 v[222:223], v231 offset:1536
	ds_read_b64_tr_b16 v[224:225], v231 offset:3072
	ds_read_b64_tr_b16 v[226:227], v231 offset:3584
	v_exp_f32_e32 v32, v32
	v_exp_f32_e32 v33, v33
	v_exp_f32_e32 v34, v34
	v_exp_f32_e32 v35, v35
	s_waitcnt vmcnt(12)
	ds_write_b128 v247, v[156:159]
	ds_write_b128 v247, v[160:163] offset:1024
	ds_write_b128 v247, v[164:167] offset:2048
	ds_write_b128 v247, v[168:171] offset:3072
	ds_read_b128 v[156:159], v248
	ds_read_b128 v[160:163], v249
	ds_read_b128 v[164:167], v250
	ds_read_b128 v[168:171], v251
	s_waitcnt vmcnt(8)
	ds_write_b128 v112, v[172:175]
	ds_write_b128 v112, v[176:179] offset:1024
	ds_write_b128 v112, v[180:183] offset:2048
	ds_write_b128 v112, v[184:187] offset:3072
	v_exp_f32_e32 v36, v36
	v_exp_f32_e32 v37, v37
	v_exp_f32_e32 v38, v38
	v_exp_f32_e32 v39, v39
	s_waitcnt lgkmcnt(4)
	v_mfma_f32_32x32x16_bf16 v[188:203], v[156:159], v[48:51], v[188:203]
	v_exp_f32_e32 v40, v40
	v_exp_f32_e32 v41, v41
	v_mfma_f32_32x32x16_bf16 v[188:203], v[160:163], v[52:55], v[188:203]
	v_exp_f32_e32 v42, v42
	v_exp_f32_e32 v43, v43
	v_mfma_f32_32x32x16_bf16 v[188:203], v[164:167], v[56:59], v[188:203]
	v_exp_f32_e32 v44, v44
	v_exp_f32_e32 v45, v45
	v_mfma_f32_32x32x16_bf16 v[188:203], v[168:171], v[60:63], v[188:203]
	v_exp_f32_e32 v46, v46
	v_exp_f32_e32 v47, v47
	v_cvt_pk_bf16_f32 v64, v32, v33
	v_cvt_pk_bf16_f32 v65, v34, v35
	v_cvt_pk_bf16_f32 v66, v36, v37
	v_cvt_pk_bf16_f32 v67, v38, v39
	v_cvt_pk_bf16_f32 v68, v40, v41
	v_cvt_pk_bf16_f32 v69, v42, v43
	v_cvt_pk_bf16_f32 v70, v44, v45
	v_cvt_pk_bf16_f32 v71, v46, v47
	v_pk_add_f32 v[232:233], v[232:233], v[32:33]
	v_pk_add_f32 v[232:233], v[232:233], v[34:35]
	v_pk_add_f32 v[232:233], v[232:233], v[36:37]
	v_pk_add_f32 v[232:233], v[232:233], v[38:39]
	v_pk_add_f32 v[232:233], v[232:233], v[40:41]
	v_pk_add_f32 v[232:233], v[232:233], v[42:43]
	v_pk_add_f32 v[232:233], v[232:233], v[44:45]
	v_pk_add_f32 v[232:233], v[232:233], v[46:47]
	v_add_u32_e32 v115, 952, v115
	ds_read2_b32 v[32:33], v115 offset0:0 offset1:1
	ds_read2_b32 v[34:35], v115 offset0:2 offset1:3
	ds_read2_b32 v[36:37], v115 offset0:8 offset1:9
	ds_read2_b32 v[38:39], v115 offset0:10 offset1:11
	ds_read2_b32 v[40:41], v115 offset0:17 offset1:18
	ds_read2_b32 v[42:43], v115 offset0:19 offset1:20
	ds_read2_b32 v[44:45], v115 offset0:25 offset1:26
	ds_read2_b32 v[46:47], v115 offset0:27 offset1:28
	v_mfma_f32_32x32x16_bf16 v[0:15], v[64:67], v[72:75], v[0:15]
	v_mfma_f32_32x32x16_bf16 v[16:31], v[64:67], v[76:79], v[16:31]
	v_mfma_f32_32x32x16_bf16 v[0:15], v[68:71], v[220:223], v[0:15]
	v_mfma_f32_32x32x16_bf16 v[16:31], v[68:71], v[224:227], v[16:31]
	global_load_dwordx4 v[156:159], v235, s[84:85]
	global_load_dwordx4 v[160:163], v236, s[84:85]
	global_load_dwordx4 v[164:167], v237, s[84:85]
	global_load_dwordx4 v[168:171], v238, s[84:85]
	global_load_dwordx4 v[172:175], v100, s[84:85] offset:768
	global_load_dwordx4 v[176:179], v149, s[84:85] offset:768
	global_load_dwordx4 v[180:183], v100, s[84:85] offset:832
	global_load_dwordx4 v[184:187], v149, s[84:85] offset:832
	s_add_u32 s84, s84, 0x30000
	s_addc_u32 s85, s85, 0
	ds_read_b64_tr_b16 v[72:73], v231
	ds_read_b64_tr_b16 v[74:75], v231 offset:512
	ds_read_b64_tr_b16 v[76:77], v231 offset:2048
	ds_read_b64_tr_b16 v[78:79], v231 offset:2560
	ds_read_b64_tr_b16 v[220:221], v231 offset:1024
	ds_read_b64_tr_b16 v[222:223], v231 offset:1536
	ds_read_b64_tr_b16 v[224:225], v231 offset:3072
	ds_read_b64_tr_b16 v[226:227], v231 offset:3584
	v_exp_f32_e32 v188, v188
	v_exp_f32_e32 v189, v189
	v_exp_f32_e32 v190, v190
	v_exp_f32_e32 v191, v191
	s_waitcnt vmcnt(12)
	ds_write_b128 v247, v[116:119]
	ds_write_b128 v247, v[120:123] offset:1024
	ds_write_b128 v247, v[124:127] offset:2048
	ds_write_b128 v247, v[128:131] offset:3072
	ds_read_b128 v[116:119], v248
	ds_read_b128 v[120:123], v249
	ds_read_b128 v[124:127], v250
	ds_read_b128 v[128:131], v251
	s_waitcnt vmcnt(8)
	ds_write_b128 v112, v[132:135]
	ds_write_b128 v112, v[136:139] offset:1024
	ds_write_b128 v112, v[140:143] offset:2048
	ds_write_b128 v112, v[144:147] offset:3072
	v_exp_f32_e32 v192, v192
	v_exp_f32_e32 v193, v193
	v_exp_f32_e32 v194, v194
	v_exp_f32_e32 v195, v195
	s_waitcnt lgkmcnt(4)
	v_mfma_f32_32x32x16_bf16 v[32:47], v[116:119], v[48:51], v[32:47]
	v_exp_f32_e32 v196, v196
	v_exp_f32_e32 v197, v197
	v_mfma_f32_32x32x16_bf16 v[32:47], v[120:123], v[52:55], v[32:47]
	v_exp_f32_e32 v198, v198
	v_exp_f32_e32 v199, v199
	v_mfma_f32_32x32x16_bf16 v[32:47], v[124:127], v[56:59], v[32:47]
	v_exp_f32_e32 v200, v200
	v_exp_f32_e32 v201, v201
	v_mfma_f32_32x32x16_bf16 v[32:47], v[128:131], v[60:63], v[32:47]
	v_exp_f32_e32 v202, v202
	v_exp_f32_e32 v203, v203
	v_cvt_pk_bf16_f32 v64, v188, v189
	v_cvt_pk_bf16_f32 v65, v190, v191
	v_cvt_pk_bf16_f32 v66, v192, v193
	v_cvt_pk_bf16_f32 v67, v194, v195
	v_cvt_pk_bf16_f32 v68, v196, v197
	v_cvt_pk_bf16_f32 v69, v198, v199
	v_cvt_pk_bf16_f32 v70, v200, v201
	v_cvt_pk_bf16_f32 v71, v202, v203
	v_pk_add_f32 v[232:233], v[232:233], v[188:189]
	v_pk_add_f32 v[232:233], v[232:233], v[190:191]
	v_pk_add_f32 v[232:233], v[232:233], v[192:193]
	v_pk_add_f32 v[232:233], v[232:233], v[194:195]
	v_pk_add_f32 v[232:233], v[232:233], v[196:197]
	v_pk_add_f32 v[232:233], v[232:233], v[198:199]
	v_pk_add_f32 v[232:233], v[232:233], v[200:201]
	v_pk_add_f32 v[232:233], v[232:233], v[202:203]
	ds_read2_b32 v[188:189], v115 offset0:34 offset1:35
	ds_read2_b32 v[190:191], v115 offset0:36 offset1:37
	ds_read2_b32 v[192:193], v115 offset0:42 offset1:43
	ds_read2_b32 v[194:195], v115 offset0:44 offset1:45
	ds_read2_b32 v[196:197], v115 offset0:51 offset1:52
	ds_read2_b32 v[198:199], v115 offset0:53 offset1:54
	ds_read2_b32 v[200:201], v115 offset0:59 offset1:60
	ds_read2_b32 v[202:203], v115 offset0:61 offset1:62
	v_mfma_f32_32x32x16_bf16 v[0:15], v[64:67], v[72:75], v[0:15]
	v_mfma_f32_32x32x16_bf16 v[16:31], v[64:67], v[76:79], v[16:31]
	v_mfma_f32_32x32x16_bf16 v[0:15], v[68:71], v[220:223], v[0:15]
	v_mfma_f32_32x32x16_bf16 v[16:31], v[68:71], v[224:227], v[16:31]
	global_load_dwordx4 v[116:119], v235, s[84:85]
	global_load_dwordx4 v[120:123], v236, s[84:85]
	global_load_dwordx4 v[124:127], v237, s[84:85]
	global_load_dwordx4 v[128:131], v238, s[84:85]
	global_load_dwordx4 v[132:135], v100, s[84:85] offset:768
	global_load_dwordx4 v[136:139], v149, s[84:85] offset:768
	global_load_dwordx4 v[140:143], v100, s[84:85] offset:832
	global_load_dwordx4 v[144:147], v149, s[84:85] offset:832
	s_add_u32 s84, s84, 0x30000
	s_addc_u32 s85, s85, 0
	ds_read_b64_tr_b16 v[72:73], v231
	ds_read_b64_tr_b16 v[74:75], v231 offset:512
	ds_read_b64_tr_b16 v[76:77], v231 offset:2048
	ds_read_b64_tr_b16 v[78:79], v231 offset:2560
	ds_read_b64_tr_b16 v[220:221], v231 offset:1024
	ds_read_b64_tr_b16 v[222:223], v231 offset:1536
	ds_read_b64_tr_b16 v[224:225], v231 offset:3072
	ds_read_b64_tr_b16 v[226:227], v231 offset:3584
	v_exp_f32_e32 v32, v32
	v_exp_f32_e32 v33, v33
	v_exp_f32_e32 v34, v34
	v_exp_f32_e32 v35, v35
	s_waitcnt vmcnt(12)
	ds_write_b128 v247, v[156:159]
	ds_write_b128 v247, v[160:163] offset:1024
	ds_write_b128 v247, v[164:167] offset:2048
	ds_write_b128 v247, v[168:171] offset:3072
	ds_read_b128 v[156:159], v248
	ds_read_b128 v[160:163], v249
	ds_read_b128 v[164:167], v250
	ds_read_b128 v[168:171], v251
	s_waitcnt vmcnt(8)
	ds_write_b128 v112, v[172:175]
	ds_write_b128 v112, v[176:179] offset:1024
	ds_write_b128 v112, v[180:183] offset:2048
	ds_write_b128 v112, v[184:187] offset:3072
	v_exp_f32_e32 v36, v36
	v_exp_f32_e32 v37, v37
	v_exp_f32_e32 v38, v38
	v_exp_f32_e32 v39, v39
	s_waitcnt lgkmcnt(4)
	v_mfma_f32_32x32x16_bf16 v[188:203], v[156:159], v[48:51], v[188:203]
	v_exp_f32_e32 v40, v40
	v_exp_f32_e32 v41, v41
	v_mfma_f32_32x32x16_bf16 v[188:203], v[160:163], v[52:55], v[188:203]
	v_exp_f32_e32 v42, v42
	v_exp_f32_e32 v43, v43
	v_mfma_f32_32x32x16_bf16 v[188:203], v[164:167], v[56:59], v[188:203]
	v_exp_f32_e32 v44, v44
	v_exp_f32_e32 v45, v45
	v_mfma_f32_32x32x16_bf16 v[188:203], v[168:171], v[60:63], v[188:203]
	v_exp_f32_e32 v46, v46
	v_exp_f32_e32 v47, v47
	v_cvt_pk_bf16_f32 v64, v32, v33
	v_cvt_pk_bf16_f32 v65, v34, v35
	v_cvt_pk_bf16_f32 v66, v36, v37
	v_cvt_pk_bf16_f32 v67, v38, v39
	v_cvt_pk_bf16_f32 v68, v40, v41
	v_cvt_pk_bf16_f32 v69, v42, v43
	v_cvt_pk_bf16_f32 v70, v44, v45
	v_cvt_pk_bf16_f32 v71, v46, v47
	v_pk_add_f32 v[232:233], v[232:233], v[32:33]
	v_pk_add_f32 v[232:233], v[232:233], v[34:35]
	v_pk_add_f32 v[232:233], v[232:233], v[36:37]
	v_pk_add_f32 v[232:233], v[232:233], v[38:39]
	v_pk_add_f32 v[232:233], v[232:233], v[40:41]
	v_pk_add_f32 v[232:233], v[232:233], v[42:43]
	v_pk_add_f32 v[232:233], v[232:233], v[44:45]
	v_pk_add_f32 v[232:233], v[232:233], v[46:47]
	ds_read2_b32 v[32:33], v115 offset0:68 offset1:69
	ds_read2_b32 v[34:35], v115 offset0:70 offset1:71
	ds_read2_b32 v[36:37], v115 offset0:76 offset1:77
	ds_read2_b32 v[38:39], v115 offset0:78 offset1:79
	ds_read2_b32 v[40:41], v115 offset0:85 offset1:86
	ds_read2_b32 v[42:43], v115 offset0:87 offset1:88
	ds_read2_b32 v[44:45], v115 offset0:93 offset1:94
	ds_read2_b32 v[46:47], v115 offset0:95 offset1:96
	v_mfma_f32_32x32x16_bf16 v[0:15], v[64:67], v[72:75], v[0:15]
	v_mfma_f32_32x32x16_bf16 v[16:31], v[64:67], v[76:79], v[16:31]
	v_mfma_f32_32x32x16_bf16 v[0:15], v[68:71], v[220:223], v[0:15]
	v_mfma_f32_32x32x16_bf16 v[16:31], v[68:71], v[224:227], v[16:31]
	global_load_dwordx4 v[156:159], v235, s[84:85]
	global_load_dwordx4 v[160:163], v236, s[84:85]
	global_load_dwordx4 v[164:167], v237, s[84:85]
	global_load_dwordx4 v[168:171], v238, s[84:85]
	global_load_dwordx4 v[172:175], v100, s[84:85] offset:768
	global_load_dwordx4 v[176:179], v149, s[84:85] offset:768
	global_load_dwordx4 v[180:183], v100, s[84:85] offset:832
	global_load_dwordx4 v[184:187], v149, s[84:85] offset:832
	s_add_u32 s84, s84, 0x30000
	s_addc_u32 s85, s85, 0
	ds_read_b64_tr_b16 v[72:73], v231
	ds_read_b64_tr_b16 v[74:75], v231 offset:512
	ds_read_b64_tr_b16 v[76:77], v231 offset:2048
	ds_read_b64_tr_b16 v[78:79], v231 offset:2560
	ds_read_b64_tr_b16 v[220:221], v231 offset:1024
	ds_read_b64_tr_b16 v[222:223], v231 offset:1536
	ds_read_b64_tr_b16 v[224:225], v231 offset:3072
	ds_read_b64_tr_b16 v[226:227], v231 offset:3584
	v_exp_f32_e32 v188, v188
	v_exp_f32_e32 v189, v189
	v_exp_f32_e32 v190, v190
	v_exp_f32_e32 v191, v191
	s_waitcnt vmcnt(12)
	ds_write_b128 v247, v[116:119]
	ds_write_b128 v247, v[120:123] offset:1024
	ds_write_b128 v247, v[124:127] offset:2048
	ds_write_b128 v247, v[128:131] offset:3072
	ds_read_b128 v[116:119], v248
	ds_read_b128 v[120:123], v249
	ds_read_b128 v[124:127], v250
	ds_read_b128 v[128:131], v251
	s_waitcnt vmcnt(8)
	ds_write_b128 v112, v[132:135]
	ds_write_b128 v112, v[136:139] offset:1024
	ds_write_b128 v112, v[140:143] offset:2048
	ds_write_b128 v112, v[144:147] offset:3072
	v_exp_f32_e32 v192, v192
	v_exp_f32_e32 v193, v193
	v_exp_f32_e32 v194, v194
	v_exp_f32_e32 v195, v195
	s_waitcnt lgkmcnt(4)
	v_mfma_f32_32x32x16_bf16 v[32:47], v[116:119], v[48:51], v[32:47]
	v_exp_f32_e32 v196, v196
	v_exp_f32_e32 v197, v197
	v_mfma_f32_32x32x16_bf16 v[32:47], v[120:123], v[52:55], v[32:47]
	v_exp_f32_e32 v198, v198
	v_exp_f32_e32 v199, v199
	v_mfma_f32_32x32x16_bf16 v[32:47], v[124:127], v[56:59], v[32:47]
	v_exp_f32_e32 v200, v200
	v_exp_f32_e32 v201, v201
	v_mfma_f32_32x32x16_bf16 v[32:47], v[128:131], v[60:63], v[32:47]
	v_exp_f32_e32 v202, v202
	v_exp_f32_e32 v203, v203
	v_cvt_pk_bf16_f32 v64, v188, v189
	v_cvt_pk_bf16_f32 v65, v190, v191
	v_cvt_pk_bf16_f32 v66, v192, v193
	v_cvt_pk_bf16_f32 v67, v194, v195
	v_cvt_pk_bf16_f32 v68, v196, v197
	v_cvt_pk_bf16_f32 v69, v198, v199
	v_cvt_pk_bf16_f32 v70, v200, v201
	v_cvt_pk_bf16_f32 v71, v202, v203
	v_pk_add_f32 v[232:233], v[232:233], v[188:189]
	v_pk_add_f32 v[232:233], v[232:233], v[190:191]
	v_pk_add_f32 v[232:233], v[232:233], v[192:193]
	v_pk_add_f32 v[232:233], v[232:233], v[194:195]
	v_pk_add_f32 v[232:233], v[232:233], v[196:197]
	v_pk_add_f32 v[232:233], v[232:233], v[198:199]
	v_pk_add_f32 v[232:233], v[232:233], v[200:201]
	v_pk_add_f32 v[232:233], v[232:233], v[202:203]
	ds_read2_b32 v[188:189], v115 offset0:102 offset1:103
	ds_read2_b32 v[190:191], v115 offset0:104 offset1:105
	ds_read2_b32 v[192:193], v115 offset0:110 offset1:111
	ds_read2_b32 v[194:195], v115 offset0:112 offset1:113
	ds_read2_b32 v[196:197], v115 offset0:119 offset1:120
	ds_read2_b32 v[198:199], v115 offset0:121 offset1:122
	ds_read2_b32 v[200:201], v115 offset0:127 offset1:128
	ds_read2_b32 v[202:203], v115 offset0:129 offset1:130
	v_mfma_f32_32x32x16_bf16 v[0:15], v[64:67], v[72:75], v[0:15]
	v_mfma_f32_32x32x16_bf16 v[16:31], v[64:67], v[76:79], v[16:31]
	v_mfma_f32_32x32x16_bf16 v[0:15], v[68:71], v[220:223], v[0:15]
	v_mfma_f32_32x32x16_bf16 v[16:31], v[68:71], v[224:227], v[16:31]
	global_load_dwordx4 v[116:119], v235, s[84:85]
	global_load_dwordx4 v[120:123], v236, s[84:85]
	global_load_dwordx4 v[124:127], v237, s[84:85]
	global_load_dwordx4 v[128:131], v238, s[84:85]
	global_load_dwordx4 v[132:135], v100, s[84:85] offset:768
	global_load_dwordx4 v[136:139], v149, s[84:85] offset:768
	global_load_dwordx4 v[140:143], v100, s[84:85] offset:832
	global_load_dwordx4 v[144:147], v149, s[84:85] offset:832
	s_add_u32 s84, s84, 0x30000
	s_addc_u32 s85, s85, 0
	ds_read_b64_tr_b16 v[72:73], v231
	ds_read_b64_tr_b16 v[74:75], v231 offset:512
	ds_read_b64_tr_b16 v[76:77], v231 offset:2048
	ds_read_b64_tr_b16 v[78:79], v231 offset:2560
	ds_read_b64_tr_b16 v[220:221], v231 offset:1024
	ds_read_b64_tr_b16 v[222:223], v231 offset:1536
	ds_read_b64_tr_b16 v[224:225], v231 offset:3072
	ds_read_b64_tr_b16 v[226:227], v231 offset:3584
	v_exp_f32_e32 v32, v32
	v_exp_f32_e32 v33, v33
	v_exp_f32_e32 v34, v34
	v_exp_f32_e32 v35, v35
	s_waitcnt vmcnt(12)
	ds_write_b128 v247, v[156:159]
	ds_write_b128 v247, v[160:163] offset:1024
	ds_write_b128 v247, v[164:167] offset:2048
	ds_write_b128 v247, v[168:171] offset:3072
	ds_read_b128 v[156:159], v248
	ds_read_b128 v[160:163], v249
	ds_read_b128 v[164:167], v250
	ds_read_b128 v[168:171], v251
	s_waitcnt vmcnt(8)
	ds_write_b128 v112, v[172:175]
	ds_write_b128 v112, v[176:179] offset:1024
	ds_write_b128 v112, v[180:183] offset:2048
	ds_write_b128 v112, v[184:187] offset:3072
	v_exp_f32_e32 v36, v36
	v_exp_f32_e32 v37, v37
	v_exp_f32_e32 v38, v38
	v_exp_f32_e32 v39, v39
	s_waitcnt lgkmcnt(4)
	v_mfma_f32_32x32x16_bf16 v[188:203], v[156:159], v[48:51], v[188:203]
	v_exp_f32_e32 v40, v40
	v_exp_f32_e32 v41, v41
	v_mfma_f32_32x32x16_bf16 v[188:203], v[160:163], v[52:55], v[188:203]
	v_exp_f32_e32 v42, v42
	v_exp_f32_e32 v43, v43
	v_mfma_f32_32x32x16_bf16 v[188:203], v[164:167], v[56:59], v[188:203]
	v_exp_f32_e32 v44, v44
	v_exp_f32_e32 v45, v45
	v_mfma_f32_32x32x16_bf16 v[188:203], v[168:171], v[60:63], v[188:203]
	v_exp_f32_e32 v46, v46
	v_exp_f32_e32 v47, v47
	v_cvt_pk_bf16_f32 v64, v32, v33
	v_cvt_pk_bf16_f32 v65, v34, v35
	v_cvt_pk_bf16_f32 v66, v36, v37
	v_cvt_pk_bf16_f32 v67, v38, v39
	v_cvt_pk_bf16_f32 v68, v40, v41
	v_cvt_pk_bf16_f32 v69, v42, v43
	v_cvt_pk_bf16_f32 v70, v44, v45
	v_cvt_pk_bf16_f32 v71, v46, v47
	v_pk_add_f32 v[232:233], v[232:233], v[32:33]
	v_pk_add_f32 v[232:233], v[232:233], v[34:35]
	v_pk_add_f32 v[232:233], v[232:233], v[36:37]
	v_pk_add_f32 v[232:233], v[232:233], v[38:39]
	v_pk_add_f32 v[232:233], v[232:233], v[40:41]
	v_pk_add_f32 v[232:233], v[232:233], v[42:43]
	v_pk_add_f32 v[232:233], v[232:233], v[44:45]
	v_pk_add_f32 v[232:233], v[232:233], v[46:47]
	ds_read2_b32 v[32:33], v115 offset0:136 offset1:137
	ds_read2_b32 v[34:35], v115 offset0:138 offset1:139
	ds_read2_b32 v[36:37], v115 offset0:144 offset1:145
	ds_read2_b32 v[38:39], v115 offset0:146 offset1:147
	ds_read2_b32 v[40:41], v115 offset0:153 offset1:154
	ds_read2_b32 v[42:43], v115 offset0:155 offset1:156
	ds_read2_b32 v[44:45], v115 offset0:161 offset1:162
	ds_read2_b32 v[46:47], v115 offset0:163 offset1:164
	v_mfma_f32_32x32x16_bf16 v[0:15], v[64:67], v[72:75], v[0:15]
	v_mfma_f32_32x32x16_bf16 v[16:31], v[64:67], v[76:79], v[16:31]
	v_mfma_f32_32x32x16_bf16 v[0:15], v[68:71], v[220:223], v[0:15]
	v_mfma_f32_32x32x16_bf16 v[16:31], v[68:71], v[224:227], v[16:31]
	global_load_dwordx4 v[156:159], v235, s[84:85]
	global_load_dwordx4 v[160:163], v236, s[84:85]
	global_load_dwordx4 v[164:167], v237, s[84:85]
	global_load_dwordx4 v[168:171], v238, s[84:85]
	global_load_dwordx4 v[172:175], v100, s[84:85] offset:768
	global_load_dwordx4 v[176:179], v149, s[84:85] offset:768
	global_load_dwordx4 v[180:183], v100, s[84:85] offset:832
	global_load_dwordx4 v[184:187], v149, s[84:85] offset:832
	ds_read_b64_tr_b16 v[72:73], v231
	ds_read_b64_tr_b16 v[74:75], v231 offset:512
	ds_read_b64_tr_b16 v[76:77], v231 offset:2048
	ds_read_b64_tr_b16 v[78:79], v231 offset:2560
	ds_read_b64_tr_b16 v[220:221], v231 offset:1024
	ds_read_b64_tr_b16 v[222:223], v231 offset:1536
	ds_read_b64_tr_b16 v[224:225], v231 offset:3072
	ds_read_b64_tr_b16 v[226:227], v231 offset:3584
	v_exp_f32_e32 v188, v188
	v_exp_f32_e32 v189, v189
	v_exp_f32_e32 v190, v190
	v_exp_f32_e32 v191, v191
	s_waitcnt vmcnt(12)
	ds_write_b128 v247, v[116:119]
	ds_write_b128 v247, v[120:123] offset:1024
	ds_write_b128 v247, v[124:127] offset:2048
	ds_write_b128 v247, v[128:131] offset:3072
	ds_read_b128 v[116:119], v248
	ds_read_b128 v[120:123], v249
	ds_read_b128 v[124:127], v250
	ds_read_b128 v[128:131], v251
	s_waitcnt vmcnt(8)
	ds_write_b128 v112, v[132:135]
	ds_write_b128 v112, v[136:139] offset:1024
	ds_write_b128 v112, v[140:143] offset:2048
	ds_write_b128 v112, v[144:147] offset:3072
	v_exp_f32_e32 v192, v192
	v_exp_f32_e32 v193, v193
	v_exp_f32_e32 v194, v194
	v_exp_f32_e32 v195, v195
	s_waitcnt lgkmcnt(4)
	v_mfma_f32_32x32x16_bf16 v[32:47], v[116:119], v[48:51], v[32:47]
	v_exp_f32_e32 v196, v196
	v_exp_f32_e32 v197, v197
	v_mfma_f32_32x32x16_bf16 v[32:47], v[120:123], v[52:55], v[32:47]
	v_exp_f32_e32 v198, v198
	v_exp_f32_e32 v199, v199
	v_mfma_f32_32x32x16_bf16 v[32:47], v[124:127], v[56:59], v[32:47]
	v_exp_f32_e32 v200, v200
	v_exp_f32_e32 v201, v201
	v_mfma_f32_32x32x16_bf16 v[32:47], v[128:131], v[60:63], v[32:47]
	v_exp_f32_e32 v202, v202
	v_exp_f32_e32 v203, v203
	v_cvt_pk_bf16_f32 v64, v188, v189
	v_cvt_pk_bf16_f32 v65, v190, v191
	v_cvt_pk_bf16_f32 v66, v192, v193
	v_cvt_pk_bf16_f32 v67, v194, v195
	v_cvt_pk_bf16_f32 v68, v196, v197
	v_cvt_pk_bf16_f32 v69, v198, v199
	v_cvt_pk_bf16_f32 v70, v200, v201
	v_cvt_pk_bf16_f32 v71, v202, v203
	v_pk_add_f32 v[232:233], v[232:233], v[188:189]
	v_pk_add_f32 v[232:233], v[232:233], v[190:191]
	v_pk_add_f32 v[232:233], v[232:233], v[192:193]
	v_pk_add_f32 v[232:233], v[232:233], v[194:195]
	v_pk_add_f32 v[232:233], v[232:233], v[196:197]
	v_pk_add_f32 v[232:233], v[232:233], v[198:199]
	v_pk_add_f32 v[232:233], v[232:233], v[200:201]
	v_pk_add_f32 v[232:233], v[232:233], v[202:203]
	ds_read2_b32 v[188:189], v115 offset0:170 offset1:171
	ds_read2_b32 v[190:191], v115 offset0:172 offset1:173
	ds_read2_b32 v[192:193], v115 offset0:178 offset1:179
	ds_read2_b32 v[194:195], v115 offset0:180 offset1:181
	ds_read2_b32 v[196:197], v115 offset0:187 offset1:188
	ds_read2_b32 v[198:199], v115 offset0:189 offset1:190
	ds_read2_b32 v[200:201], v115 offset0:195 offset1:196
	ds_read2_b32 v[202:203], v115 offset0:197 offset1:198
	v_mfma_f32_32x32x16_bf16 v[0:15], v[64:67], v[72:75], v[0:15]
	v_mfma_f32_32x32x16_bf16 v[16:31], v[64:67], v[76:79], v[16:31]
	v_mfma_f32_32x32x16_bf16 v[0:15], v[68:71], v[220:223], v[0:15]
	v_mfma_f32_32x32x16_bf16 v[16:31], v[68:71], v[224:227], v[16:31]
	global_load_dwordx4 v[116:119], v239, s[86:87]
	global_load_dwordx4 v[120:123], v240, s[86:87]
	global_load_dwordx4 v[124:127], v241, s[86:87]
	global_load_dwordx4 v[128:131], v242, s[86:87]
	global_load_dwordx4 v[132:135], v101, s[86:87] offset:768
	global_load_dwordx4 v[136:139], v150, s[86:87] offset:768
	global_load_dwordx4 v[140:143], v101, s[86:87] offset:832
	global_load_dwordx4 v[144:147], v150, s[86:87] offset:832
	s_add_u32 s86, s86, 0xc0000
	s_addc_u32 s87, s87, 0
	ds_read_b64_tr_b16 v[72:73], v231
	ds_read_b64_tr_b16 v[74:75], v231 offset:512
	ds_read_b64_tr_b16 v[76:77], v231 offset:2048
	ds_read_b64_tr_b16 v[78:79], v231 offset:2560
	ds_read_b64_tr_b16 v[220:221], v231 offset:1024
	ds_read_b64_tr_b16 v[222:223], v231 offset:1536
	ds_read_b64_tr_b16 v[224:225], v231 offset:3072
	ds_read_b64_tr_b16 v[226:227], v231 offset:3584
	v_exp_f32_e32 v32, v32
	v_exp_f32_e32 v33, v33
	v_exp_f32_e32 v34, v34
	v_exp_f32_e32 v35, v35
	s_waitcnt vmcnt(12)
	ds_write_b128 v247, v[156:159]
	ds_write_b128 v247, v[160:163] offset:1024
	ds_write_b128 v247, v[164:167] offset:2048
	ds_write_b128 v247, v[168:171] offset:3072
	ds_read_b128 v[156:159], v248
	ds_read_b128 v[160:163], v249
	ds_read_b128 v[164:167], v250
	ds_read_b128 v[168:171], v251
	s_waitcnt vmcnt(8)
	ds_write_b128 v112, v[172:175]
	ds_write_b128 v112, v[176:179] offset:1024
	ds_write_b128 v112, v[180:183] offset:2048
	ds_write_b128 v112, v[184:187] offset:3072
	v_exp_f32_e32 v36, v36
	v_exp_f32_e32 v37, v37
	v_exp_f32_e32 v38, v38
	v_exp_f32_e32 v39, v39
	s_waitcnt lgkmcnt(4)
	v_mfma_f32_32x32x16_bf16 v[188:203], v[156:159], v[48:51], v[188:203]
	v_exp_f32_e32 v40, v40
	v_exp_f32_e32 v41, v41
	v_mfma_f32_32x32x16_bf16 v[188:203], v[160:163], v[52:55], v[188:203]
	v_exp_f32_e32 v42, v42
	v_exp_f32_e32 v43, v43
	v_mfma_f32_32x32x16_bf16 v[188:203], v[164:167], v[56:59], v[188:203]
	v_exp_f32_e32 v44, v44
	v_exp_f32_e32 v45, v45
	v_mfma_f32_32x32x16_bf16 v[188:203], v[168:171], v[60:63], v[188:203]
	v_exp_f32_e32 v46, v46
	v_exp_f32_e32 v47, v47
	v_cvt_pk_bf16_f32 v64, v32, v33
	v_cvt_pk_bf16_f32 v65, v34, v35
	v_cvt_pk_bf16_f32 v66, v36, v37
	v_cvt_pk_bf16_f32 v67, v38, v39
	v_cvt_pk_bf16_f32 v68, v40, v41
	v_cvt_pk_bf16_f32 v69, v42, v43
	v_cvt_pk_bf16_f32 v70, v44, v45
	v_cvt_pk_bf16_f32 v71, v46, v47
	v_pk_add_f32 v[232:233], v[232:233], v[32:33]
	v_pk_add_f32 v[232:233], v[232:233], v[34:35]
	v_pk_add_f32 v[232:233], v[232:233], v[36:37]
	v_pk_add_f32 v[232:233], v[232:233], v[38:39]
	v_pk_add_f32 v[232:233], v[232:233], v[40:41]
	v_pk_add_f32 v[232:233], v[232:233], v[42:43]
	v_pk_add_f32 v[232:233], v[232:233], v[44:45]
	v_pk_add_f32 v[232:233], v[232:233], v[46:47]
	v_mov_b32_e32 v115, v229
	ds_read2_b32 v[32:33], v115 offset0:0 offset1:1
	ds_read2_b32 v[34:35], v115 offset0:2 offset1:3
	ds_read2_b32 v[36:37], v115 offset0:8 offset1:9
	ds_read2_b32 v[38:39], v115 offset0:10 offset1:11
	ds_read2_b32 v[40:41], v115 offset0:16 offset1:17
	ds_read2_b32 v[42:43], v115 offset0:18 offset1:19
	ds_read2_b32 v[44:45], v115 offset0:24 offset1:25
	ds_read2_b32 v[46:47], v115 offset0:26 offset1:27
	v_mfma_f32_32x32x16_bf16 v[0:15], v[64:67], v[72:75], v[0:15]
	v_mfma_f32_32x32x16_bf16 v[16:31], v[64:67], v[76:79], v[16:31]
	v_mfma_f32_32x32x16_bf16 v[0:15], v[68:71], v[220:223], v[0:15]
	v_mfma_f32_32x32x16_bf16 v[16:31], v[68:71], v[224:227], v[16:31]
	global_load_dwordx4 v[156:159], v239, s[86:87]
	global_load_dwordx4 v[160:163], v240, s[86:87]
	global_load_dwordx4 v[164:167], v241, s[86:87]
	global_load_dwordx4 v[168:171], v242, s[86:87]
	global_load_dwordx4 v[172:175], v101, s[86:87] offset:768
	global_load_dwordx4 v[176:179], v150, s[86:87] offset:768
	global_load_dwordx4 v[180:183], v101, s[86:87] offset:832
	global_load_dwordx4 v[184:187], v150, s[86:87] offset:832
	s_add_u32 s86, s86, 0xc0000
	s_addc_u32 s87, s87, 0
	ds_read_b64_tr_b16 v[72:73], v231
	ds_read_b64_tr_b16 v[74:75], v231 offset:512
	ds_read_b64_tr_b16 v[76:77], v231 offset:2048
	ds_read_b64_tr_b16 v[78:79], v231 offset:2560
	ds_read_b64_tr_b16 v[220:221], v231 offset:1024
	ds_read_b64_tr_b16 v[222:223], v231 offset:1536
	ds_read_b64_tr_b16 v[224:225], v231 offset:3072
	ds_read_b64_tr_b16 v[226:227], v231 offset:3584
	v_exp_f32_e32 v188, v188
	v_exp_f32_e32 v189, v189
	v_exp_f32_e32 v190, v190
	v_exp_f32_e32 v191, v191
	s_waitcnt vmcnt(12)
	ds_write_b128 v247, v[116:119]
	ds_write_b128 v247, v[120:123] offset:1024
	ds_write_b128 v247, v[124:127] offset:2048
	ds_write_b128 v247, v[128:131] offset:3072
	ds_read_b128 v[116:119], v248
	ds_read_b128 v[120:123], v249
	ds_read_b128 v[124:127], v250
	ds_read_b128 v[128:131], v251
	s_waitcnt vmcnt(8)
	ds_write_b128 v112, v[132:135]
	ds_write_b128 v112, v[136:139] offset:1024
	ds_write_b128 v112, v[140:143] offset:2048
	ds_write_b128 v112, v[144:147] offset:3072
	v_exp_f32_e32 v192, v192
	v_exp_f32_e32 v193, v193
	v_exp_f32_e32 v194, v194
	v_exp_f32_e32 v195, v195
	s_waitcnt lgkmcnt(4)
	v_mfma_f32_32x32x16_bf16 v[32:47], v[116:119], v[48:51], v[32:47]
	v_exp_f32_e32 v196, v196
	v_exp_f32_e32 v197, v197
	v_mfma_f32_32x32x16_bf16 v[32:47], v[120:123], v[52:55], v[32:47]
	v_exp_f32_e32 v198, v198
	v_exp_f32_e32 v199, v199
	v_mfma_f32_32x32x16_bf16 v[32:47], v[124:127], v[56:59], v[32:47]
	v_exp_f32_e32 v200, v200
	v_exp_f32_e32 v201, v201
	v_mfma_f32_32x32x16_bf16 v[32:47], v[128:131], v[60:63], v[32:47]
	v_exp_f32_e32 v202, v202
	v_exp_f32_e32 v203, v203
	v_cvt_pk_bf16_f32 v64, v188, v189
	v_cvt_pk_bf16_f32 v65, v190, v191
	v_cvt_pk_bf16_f32 v66, v192, v193
	v_cvt_pk_bf16_f32 v67, v194, v195
	v_cvt_pk_bf16_f32 v68, v196, v197
	v_cvt_pk_bf16_f32 v69, v198, v199
	v_cvt_pk_bf16_f32 v70, v200, v201
	v_cvt_pk_bf16_f32 v71, v202, v203
	v_pk_add_f32 v[232:233], v[232:233], v[188:189]
	v_pk_add_f32 v[232:233], v[232:233], v[190:191]
	v_pk_add_f32 v[232:233], v[232:233], v[192:193]
	v_pk_add_f32 v[232:233], v[232:233], v[194:195]
	v_pk_add_f32 v[232:233], v[232:233], v[196:197]
	v_pk_add_f32 v[232:233], v[232:233], v[198:199]
	v_pk_add_f32 v[232:233], v[232:233], v[200:201]
	v_pk_add_f32 v[232:233], v[232:233], v[202:203]
	ds_read2_b32 v[188:189], v115 offset0:32 offset1:33
	ds_read2_b32 v[190:191], v115 offset0:34 offset1:35
	ds_read2_b32 v[192:193], v115 offset0:40 offset1:41
	ds_read2_b32 v[194:195], v115 offset0:42 offset1:43
	ds_read2_b32 v[196:197], v115 offset0:48 offset1:49
	ds_read2_b32 v[198:199], v115 offset0:50 offset1:51
	ds_read2_b32 v[200:201], v115 offset0:56 offset1:57
	ds_read2_b32 v[202:203], v115 offset0:58 offset1:59
	v_mfma_f32_32x32x16_bf16 v[0:15], v[64:67], v[72:75], v[0:15]
	v_mfma_f32_32x32x16_bf16 v[16:31], v[64:67], v[76:79], v[16:31]
	v_mfma_f32_32x32x16_bf16 v[0:15], v[68:71], v[220:223], v[0:15]
	v_mfma_f32_32x32x16_bf16 v[16:31], v[68:71], v[224:227], v[16:31]
	global_load_dwordx4 v[116:119], v239, s[86:87]
	global_load_dwordx4 v[120:123], v240, s[86:87]
	global_load_dwordx4 v[124:127], v241, s[86:87]
	global_load_dwordx4 v[128:131], v242, s[86:87]
	global_load_dwordx4 v[132:135], v101, s[86:87] offset:768
	global_load_dwordx4 v[136:139], v150, s[86:87] offset:768
	global_load_dwordx4 v[140:143], v101, s[86:87] offset:832
	global_load_dwordx4 v[144:147], v150, s[86:87] offset:832
	s_add_u32 s86, s86, 0xc0000
	s_addc_u32 s87, s87, 0
	ds_read_b64_tr_b16 v[72:73], v231
	ds_read_b64_tr_b16 v[74:75], v231 offset:512
	ds_read_b64_tr_b16 v[76:77], v231 offset:2048
	ds_read_b64_tr_b16 v[78:79], v231 offset:2560
	ds_read_b64_tr_b16 v[220:221], v231 offset:1024
	ds_read_b64_tr_b16 v[222:223], v231 offset:1536
	ds_read_b64_tr_b16 v[224:225], v231 offset:3072
	ds_read_b64_tr_b16 v[226:227], v231 offset:3584
	v_exp_f32_e32 v32, v32
	v_exp_f32_e32 v33, v33
	v_exp_f32_e32 v34, v34
	v_exp_f32_e32 v35, v35
	s_waitcnt vmcnt(12)
	ds_write_b128 v247, v[156:159]
	ds_write_b128 v247, v[160:163] offset:1024
	ds_write_b128 v247, v[164:167] offset:2048
	ds_write_b128 v247, v[168:171] offset:3072
	ds_read_b128 v[156:159], v248
	ds_read_b128 v[160:163], v249
	ds_read_b128 v[164:167], v250
	ds_read_b128 v[168:171], v251
	s_waitcnt vmcnt(8)
	ds_write_b128 v112, v[172:175]
	ds_write_b128 v112, v[176:179] offset:1024
	ds_write_b128 v112, v[180:183] offset:2048
	ds_write_b128 v112, v[184:187] offset:3072
	v_exp_f32_e32 v36, v36
	v_exp_f32_e32 v37, v37
	v_exp_f32_e32 v38, v38
	v_exp_f32_e32 v39, v39
	s_waitcnt lgkmcnt(4)
	v_mfma_f32_32x32x16_bf16 v[188:203], v[156:159], v[48:51], v[188:203]
	v_exp_f32_e32 v40, v40
	v_exp_f32_e32 v41, v41
	v_mfma_f32_32x32x16_bf16 v[188:203], v[160:163], v[52:55], v[188:203]
	v_exp_f32_e32 v42, v42
	v_exp_f32_e32 v43, v43
	v_mfma_f32_32x32x16_bf16 v[188:203], v[164:167], v[56:59], v[188:203]
	v_exp_f32_e32 v44, v44
	v_exp_f32_e32 v45, v45
	v_mfma_f32_32x32x16_bf16 v[188:203], v[168:171], v[60:63], v[188:203]
	v_exp_f32_e32 v46, v46
	v_exp_f32_e32 v47, v47
	v_cvt_pk_bf16_f32 v64, v32, v33
	v_cvt_pk_bf16_f32 v65, v34, v35
	v_cvt_pk_bf16_f32 v66, v36, v37
	v_cvt_pk_bf16_f32 v67, v38, v39
	v_cvt_pk_bf16_f32 v68, v40, v41
	v_cvt_pk_bf16_f32 v69, v42, v43
	v_cvt_pk_bf16_f32 v70, v44, v45
	v_cvt_pk_bf16_f32 v71, v46, v47
	v_pk_add_f32 v[232:233], v[232:233], v[32:33]
	v_pk_add_f32 v[232:233], v[232:233], v[34:35]
	v_pk_add_f32 v[232:233], v[232:233], v[36:37]
	v_pk_add_f32 v[232:233], v[232:233], v[38:39]
	v_pk_add_f32 v[232:233], v[232:233], v[40:41]
	v_pk_add_f32 v[232:233], v[232:233], v[42:43]
	v_pk_add_f32 v[232:233], v[232:233], v[44:45]
	v_pk_add_f32 v[232:233], v[232:233], v[46:47]
	ds_read2_b32 v[32:33], v115 offset0:64 offset1:65
	ds_read2_b32 v[34:35], v115 offset0:66 offset1:67
	ds_read2_b32 v[36:37], v115 offset0:72 offset1:73
	ds_read2_b32 v[38:39], v115 offset0:74 offset1:75
	ds_read2_b32 v[40:41], v115 offset0:80 offset1:81
	ds_read2_b32 v[42:43], v115 offset0:82 offset1:83
	ds_read2_b32 v[44:45], v115 offset0:88 offset1:89
	ds_read2_b32 v[46:47], v115 offset0:90 offset1:91
	v_mfma_f32_32x32x16_bf16 v[0:15], v[64:67], v[72:75], v[0:15]
	v_mfma_f32_32x32x16_bf16 v[16:31], v[64:67], v[76:79], v[16:31]
	v_mfma_f32_32x32x16_bf16 v[0:15], v[68:71], v[220:223], v[0:15]
	v_mfma_f32_32x32x16_bf16 v[16:31], v[68:71], v[224:227], v[16:31]
	global_load_dwordx4 v[156:159], v239, s[86:87]
	global_load_dwordx4 v[160:163], v240, s[86:87]
	global_load_dwordx4 v[164:167], v241, s[86:87]
	global_load_dwordx4 v[168:171], v242, s[86:87]
	global_load_dwordx4 v[172:175], v101, s[86:87] offset:768
	global_load_dwordx4 v[176:179], v150, s[86:87] offset:768
	global_load_dwordx4 v[180:183], v101, s[86:87] offset:832
	global_load_dwordx4 v[184:187], v150, s[86:87] offset:832
	s_add_u32 s86, s86, 0xc0000
	s_addc_u32 s87, s87, 0
	ds_read_b64_tr_b16 v[72:73], v231
	ds_read_b64_tr_b16 v[74:75], v231 offset:512
	ds_read_b64_tr_b16 v[76:77], v231 offset:2048
	ds_read_b64_tr_b16 v[78:79], v231 offset:2560
	ds_read_b64_tr_b16 v[220:221], v231 offset:1024
	ds_read_b64_tr_b16 v[222:223], v231 offset:1536
	ds_read_b64_tr_b16 v[224:225], v231 offset:3072
	ds_read_b64_tr_b16 v[226:227], v231 offset:3584
	v_exp_f32_e32 v188, v188
	v_exp_f32_e32 v189, v189
	v_exp_f32_e32 v190, v190
	v_exp_f32_e32 v191, v191
	s_waitcnt vmcnt(12)
	ds_write_b128 v247, v[116:119]
	ds_write_b128 v247, v[120:123] offset:1024
	ds_write_b128 v247, v[124:127] offset:2048
	ds_write_b128 v247, v[128:131] offset:3072
	ds_read_b128 v[116:119], v248
	ds_read_b128 v[120:123], v249
	ds_read_b128 v[124:127], v250
	ds_read_b128 v[128:131], v251
	s_waitcnt vmcnt(8)
	ds_write_b128 v112, v[132:135]
	ds_write_b128 v112, v[136:139] offset:1024
	ds_write_b128 v112, v[140:143] offset:2048
	ds_write_b128 v112, v[144:147] offset:3072
	v_exp_f32_e32 v192, v192
	v_exp_f32_e32 v193, v193
	v_exp_f32_e32 v194, v194
	v_exp_f32_e32 v195, v195
	s_waitcnt lgkmcnt(4)
	v_mfma_f32_32x32x16_bf16 v[32:47], v[116:119], v[48:51], v[32:47]
	v_exp_f32_e32 v196, v196
	v_exp_f32_e32 v197, v197
	v_mfma_f32_32x32x16_bf16 v[32:47], v[120:123], v[52:55], v[32:47]
	v_exp_f32_e32 v198, v198
	v_exp_f32_e32 v199, v199
	v_mfma_f32_32x32x16_bf16 v[32:47], v[124:127], v[56:59], v[32:47]
	v_exp_f32_e32 v200, v200
	v_exp_f32_e32 v201, v201
	v_mfma_f32_32x32x16_bf16 v[32:47], v[128:131], v[60:63], v[32:47]
	v_exp_f32_e32 v202, v202
	v_exp_f32_e32 v203, v203
	v_cvt_pk_bf16_f32 v64, v188, v189
	v_cvt_pk_bf16_f32 v65, v190, v191
	v_cvt_pk_bf16_f32 v66, v192, v193
	v_cvt_pk_bf16_f32 v67, v194, v195
	v_cvt_pk_bf16_f32 v68, v196, v197
	v_cvt_pk_bf16_f32 v69, v198, v199
	v_cvt_pk_bf16_f32 v70, v200, v201
	v_cvt_pk_bf16_f32 v71, v202, v203
	v_pk_add_f32 v[232:233], v[232:233], v[188:189]
	v_pk_add_f32 v[232:233], v[232:233], v[190:191]
	v_pk_add_f32 v[232:233], v[232:233], v[192:193]
	v_pk_add_f32 v[232:233], v[232:233], v[194:195]
	v_pk_add_f32 v[232:233], v[232:233], v[196:197]
	v_pk_add_f32 v[232:233], v[232:233], v[198:199]
	v_pk_add_f32 v[232:233], v[232:233], v[200:201]
	v_pk_add_f32 v[232:233], v[232:233], v[202:203]
	ds_read2_b32 v[188:189], v115 offset0:96 offset1:97
	ds_read2_b32 v[190:191], v115 offset0:98 offset1:99
	ds_read2_b32 v[192:193], v115 offset0:104 offset1:105
	ds_read2_b32 v[194:195], v115 offset0:106 offset1:107
	ds_read2_b32 v[196:197], v115 offset0:112 offset1:113
	ds_read2_b32 v[198:199], v115 offset0:114 offset1:115
	ds_read2_b32 v[200:201], v115 offset0:120 offset1:121
	ds_read2_b32 v[202:203], v115 offset0:122 offset1:123
	v_mfma_f32_32x32x16_bf16 v[0:15], v[64:67], v[72:75], v[0:15]
	v_mfma_f32_32x32x16_bf16 v[16:31], v[64:67], v[76:79], v[16:31]
	v_mfma_f32_32x32x16_bf16 v[0:15], v[68:71], v[220:223], v[0:15]
	v_mfma_f32_32x32x16_bf16 v[16:31], v[68:71], v[224:227], v[16:31]
	global_load_dwordx4 v[116:119], v239, s[86:87]
	global_load_dwordx4 v[120:123], v240, s[86:87]
	global_load_dwordx4 v[124:127], v241, s[86:87]
	global_load_dwordx4 v[128:131], v242, s[86:87]
	global_load_dwordx4 v[132:135], v101, s[86:87] offset:768
	global_load_dwordx4 v[136:139], v150, s[86:87] offset:768
	global_load_dwordx4 v[140:143], v101, s[86:87] offset:832
	global_load_dwordx4 v[144:147], v150, s[86:87] offset:832
	s_add_u32 s86, s86, 0xc0000
	s_addc_u32 s87, s87, 0
	ds_read_b64_tr_b16 v[72:73], v231
	ds_read_b64_tr_b16 v[74:75], v231 offset:512
	ds_read_b64_tr_b16 v[76:77], v231 offset:2048
	ds_read_b64_tr_b16 v[78:79], v231 offset:2560
	ds_read_b64_tr_b16 v[220:221], v231 offset:1024
	ds_read_b64_tr_b16 v[222:223], v231 offset:1536
	ds_read_b64_tr_b16 v[224:225], v231 offset:3072
	ds_read_b64_tr_b16 v[226:227], v231 offset:3584
	v_exp_f32_e32 v32, v32
	v_exp_f32_e32 v33, v33
	v_exp_f32_e32 v34, v34
	v_exp_f32_e32 v35, v35
	s_waitcnt vmcnt(12)
	ds_write_b128 v247, v[156:159]
	ds_write_b128 v247, v[160:163] offset:1024
	ds_write_b128 v247, v[164:167] offset:2048
	ds_write_b128 v247, v[168:171] offset:3072
	ds_read_b128 v[156:159], v248
	ds_read_b128 v[160:163], v249
	ds_read_b128 v[164:167], v250
	ds_read_b128 v[168:171], v251
	s_waitcnt vmcnt(8)
	ds_write_b128 v112, v[172:175]
	ds_write_b128 v112, v[176:179] offset:1024
	ds_write_b128 v112, v[180:183] offset:2048
	ds_write_b128 v112, v[184:187] offset:3072
	v_exp_f32_e32 v36, v36
	v_exp_f32_e32 v37, v37
	v_exp_f32_e32 v38, v38
	v_exp_f32_e32 v39, v39
	s_waitcnt lgkmcnt(4)
	v_mfma_f32_32x32x16_bf16 v[188:203], v[156:159], v[48:51], v[188:203]
	v_exp_f32_e32 v40, v40
	v_exp_f32_e32 v41, v41
	v_mfma_f32_32x32x16_bf16 v[188:203], v[160:163], v[52:55], v[188:203]
	v_exp_f32_e32 v42, v42
	v_exp_f32_e32 v43, v43
	v_mfma_f32_32x32x16_bf16 v[188:203], v[164:167], v[56:59], v[188:203]
	v_exp_f32_e32 v44, v44
	v_exp_f32_e32 v45, v45
	v_mfma_f32_32x32x16_bf16 v[188:203], v[168:171], v[60:63], v[188:203]
	v_exp_f32_e32 v46, v46
	v_exp_f32_e32 v47, v47
	v_cvt_pk_bf16_f32 v64, v32, v33
	v_cvt_pk_bf16_f32 v65, v34, v35
	v_cvt_pk_bf16_f32 v66, v36, v37
	v_cvt_pk_bf16_f32 v67, v38, v39
	v_cvt_pk_bf16_f32 v68, v40, v41
	v_cvt_pk_bf16_f32 v69, v42, v43
	v_cvt_pk_bf16_f32 v70, v44, v45
	v_cvt_pk_bf16_f32 v71, v46, v47
	v_pk_add_f32 v[232:233], v[232:233], v[32:33]
	v_pk_add_f32 v[232:233], v[232:233], v[34:35]
	v_pk_add_f32 v[232:233], v[232:233], v[36:37]
	v_pk_add_f32 v[232:233], v[232:233], v[38:39]
	v_pk_add_f32 v[232:233], v[232:233], v[40:41]
	v_pk_add_f32 v[232:233], v[232:233], v[42:43]
	v_pk_add_f32 v[232:233], v[232:233], v[44:45]
	v_pk_add_f32 v[232:233], v[232:233], v[46:47]
	ds_read2_b32 v[32:33], v115 offset0:128 offset1:129
	ds_read2_b32 v[34:35], v115 offset0:130 offset1:131
	ds_read2_b32 v[36:37], v115 offset0:136 offset1:137
	ds_read2_b32 v[38:39], v115 offset0:138 offset1:139
	ds_read2_b32 v[40:41], v115 offset0:144 offset1:145
	ds_read2_b32 v[42:43], v115 offset0:146 offset1:147
	ds_read2_b32 v[44:45], v115 offset0:152 offset1:153
	ds_read2_b32 v[46:47], v115 offset0:154 offset1:155
	v_mfma_f32_32x32x16_bf16 v[0:15], v[64:67], v[72:75], v[0:15]
	v_mfma_f32_32x32x16_bf16 v[16:31], v[64:67], v[76:79], v[16:31]
	v_mfma_f32_32x32x16_bf16 v[0:15], v[68:71], v[220:223], v[0:15]
	v_mfma_f32_32x32x16_bf16 v[16:31], v[68:71], v[224:227], v[16:31]
	global_load_dwordx4 v[156:159], v239, s[86:87]
	global_load_dwordx4 v[160:163], v240, s[86:87]
	global_load_dwordx4 v[164:167], v241, s[86:87]
	global_load_dwordx4 v[168:171], v242, s[86:87]
	global_load_dwordx4 v[172:175], v101, s[86:87] offset:768
	global_load_dwordx4 v[176:179], v150, s[86:87] offset:768
	global_load_dwordx4 v[180:183], v101, s[86:87] offset:832
	global_load_dwordx4 v[184:187], v150, s[86:87] offset:832
	s_add_u32 s86, s86, 0xc0000
	s_addc_u32 s87, s87, 0
	ds_read_b64_tr_b16 v[72:73], v231
	ds_read_b64_tr_b16 v[74:75], v231 offset:512
	ds_read_b64_tr_b16 v[76:77], v231 offset:2048
	ds_read_b64_tr_b16 v[78:79], v231 offset:2560
	ds_read_b64_tr_b16 v[220:221], v231 offset:1024
	ds_read_b64_tr_b16 v[222:223], v231 offset:1536
	ds_read_b64_tr_b16 v[224:225], v231 offset:3072
	ds_read_b64_tr_b16 v[226:227], v231 offset:3584
	v_exp_f32_e32 v188, v188
	v_exp_f32_e32 v189, v189
	v_exp_f32_e32 v190, v190
	v_exp_f32_e32 v191, v191
	s_waitcnt vmcnt(12)
	ds_write_b128 v247, v[116:119]
	ds_write_b128 v247, v[120:123] offset:1024
	ds_write_b128 v247, v[124:127] offset:2048
	ds_write_b128 v247, v[128:131] offset:3072
	ds_read_b128 v[116:119], v248
	ds_read_b128 v[120:123], v249
	ds_read_b128 v[124:127], v250
	ds_read_b128 v[128:131], v251
	s_waitcnt vmcnt(8)
	ds_write_b128 v112, v[132:135]
	ds_write_b128 v112, v[136:139] offset:1024
	ds_write_b128 v112, v[140:143] offset:2048
	ds_write_b128 v112, v[144:147] offset:3072
	v_exp_f32_e32 v192, v192
	v_exp_f32_e32 v193, v193
	v_exp_f32_e32 v194, v194
	v_exp_f32_e32 v195, v195
	s_waitcnt lgkmcnt(4)
	v_mfma_f32_32x32x16_bf16 v[32:47], v[116:119], v[48:51], v[32:47]
	v_exp_f32_e32 v196, v196
	v_exp_f32_e32 v197, v197
	v_mfma_f32_32x32x16_bf16 v[32:47], v[120:123], v[52:55], v[32:47]
	v_exp_f32_e32 v198, v198
	v_exp_f32_e32 v199, v199
	v_mfma_f32_32x32x16_bf16 v[32:47], v[124:127], v[56:59], v[32:47]
	v_exp_f32_e32 v200, v200
	v_exp_f32_e32 v201, v201
	v_mfma_f32_32x32x16_bf16 v[32:47], v[128:131], v[60:63], v[32:47]
	v_exp_f32_e32 v202, v202
	v_exp_f32_e32 v203, v203
	v_cvt_pk_bf16_f32 v64, v188, v189
	v_cvt_pk_bf16_f32 v65, v190, v191
	v_cvt_pk_bf16_f32 v66, v192, v193
	v_cvt_pk_bf16_f32 v67, v194, v195
	v_cvt_pk_bf16_f32 v68, v196, v197
	v_cvt_pk_bf16_f32 v69, v198, v199
	v_cvt_pk_bf16_f32 v70, v200, v201
	v_cvt_pk_bf16_f32 v71, v202, v203
	v_pk_add_f32 v[232:233], v[232:233], v[188:189]
	v_pk_add_f32 v[232:233], v[232:233], v[190:191]
	v_pk_add_f32 v[232:233], v[232:233], v[192:193]
	v_pk_add_f32 v[232:233], v[232:233], v[194:195]
	v_pk_add_f32 v[232:233], v[232:233], v[196:197]
	v_pk_add_f32 v[232:233], v[232:233], v[198:199]
	v_pk_add_f32 v[232:233], v[232:233], v[200:201]
	v_pk_add_f32 v[232:233], v[232:233], v[202:203]
	ds_read2_b32 v[188:189], v115 offset0:160 offset1:161
	ds_read2_b32 v[190:191], v115 offset0:162 offset1:163
	ds_read2_b32 v[192:193], v115 offset0:168 offset1:169
	ds_read2_b32 v[194:195], v115 offset0:170 offset1:171
	ds_read2_b32 v[196:197], v115 offset0:176 offset1:177
	ds_read2_b32 v[198:199], v115 offset0:178 offset1:179
	ds_read2_b32 v[200:201], v115 offset0:184 offset1:185
	ds_read2_b32 v[202:203], v115 offset0:186 offset1:187
	v_mfma_f32_32x32x16_bf16 v[0:15], v[64:67], v[72:75], v[0:15]
	v_mfma_f32_32x32x16_bf16 v[16:31], v[64:67], v[76:79], v[16:31]
	v_mfma_f32_32x32x16_bf16 v[0:15], v[68:71], v[220:223], v[0:15]
	v_mfma_f32_32x32x16_bf16 v[16:31], v[68:71], v[224:227], v[16:31]
	global_load_dwordx4 v[116:119], v239, s[86:87]
	global_load_dwordx4 v[120:123], v240, s[86:87]
	global_load_dwordx4 v[124:127], v241, s[86:87]
	global_load_dwordx4 v[128:131], v242, s[86:87]
	global_load_dwordx4 v[132:135], v101, s[86:87] offset:768
	global_load_dwordx4 v[136:139], v150, s[86:87] offset:768
	global_load_dwordx4 v[140:143], v101, s[86:87] offset:832
	global_load_dwordx4 v[144:147], v150, s[86:87] offset:832
	s_add_u32 s86, s86, 0xc0000
	s_addc_u32 s87, s87, 0
	ds_read_b64_tr_b16 v[72:73], v231
	ds_read_b64_tr_b16 v[74:75], v231 offset:512
	ds_read_b64_tr_b16 v[76:77], v231 offset:2048
	ds_read_b64_tr_b16 v[78:79], v231 offset:2560
	ds_read_b64_tr_b16 v[220:221], v231 offset:1024
	ds_read_b64_tr_b16 v[222:223], v231 offset:1536
	ds_read_b64_tr_b16 v[224:225], v231 offset:3072
	ds_read_b64_tr_b16 v[226:227], v231 offset:3584
	v_exp_f32_e32 v32, v32
	v_exp_f32_e32 v33, v33
	v_exp_f32_e32 v34, v34
	v_exp_f32_e32 v35, v35
	s_waitcnt vmcnt(12)
	ds_write_b128 v247, v[156:159]
	ds_write_b128 v247, v[160:163] offset:1024
	ds_write_b128 v247, v[164:167] offset:2048
	ds_write_b128 v247, v[168:171] offset:3072
	ds_read_b128 v[156:159], v248
	ds_read_b128 v[160:163], v249
	ds_read_b128 v[164:167], v250
	ds_read_b128 v[168:171], v251
	s_waitcnt vmcnt(8)
	ds_write_b128 v112, v[172:175]
	ds_write_b128 v112, v[176:179] offset:1024
	ds_write_b128 v112, v[180:183] offset:2048
	ds_write_b128 v112, v[184:187] offset:3072
	v_exp_f32_e32 v36, v36
	v_exp_f32_e32 v37, v37
	v_exp_f32_e32 v38, v38
	v_exp_f32_e32 v39, v39
	s_waitcnt lgkmcnt(4)
	v_mfma_f32_32x32x16_bf16 v[188:203], v[156:159], v[48:51], v[188:203]
	v_exp_f32_e32 v40, v40
	v_exp_f32_e32 v41, v41
	v_mfma_f32_32x32x16_bf16 v[188:203], v[160:163], v[52:55], v[188:203]
	v_exp_f32_e32 v42, v42
	v_exp_f32_e32 v43, v43
	v_mfma_f32_32x32x16_bf16 v[188:203], v[164:167], v[56:59], v[188:203]
	v_exp_f32_e32 v44, v44
	v_exp_f32_e32 v45, v45
	v_mfma_f32_32x32x16_bf16 v[188:203], v[168:171], v[60:63], v[188:203]
	v_exp_f32_e32 v46, v46
	v_exp_f32_e32 v47, v47
	v_cvt_pk_bf16_f32 v64, v32, v33
	v_cvt_pk_bf16_f32 v65, v34, v35
	v_cvt_pk_bf16_f32 v66, v36, v37
	v_cvt_pk_bf16_f32 v67, v38, v39
	v_cvt_pk_bf16_f32 v68, v40, v41
	v_cvt_pk_bf16_f32 v69, v42, v43
	v_cvt_pk_bf16_f32 v70, v44, v45
	v_cvt_pk_bf16_f32 v71, v46, v47
	v_pk_add_f32 v[232:233], v[232:233], v[32:33]
	v_pk_add_f32 v[232:233], v[232:233], v[34:35]
	v_pk_add_f32 v[232:233], v[232:233], v[36:37]
	v_pk_add_f32 v[232:233], v[232:233], v[38:39]
	v_pk_add_f32 v[232:233], v[232:233], v[40:41]
	v_pk_add_f32 v[232:233], v[232:233], v[42:43]
	v_pk_add_f32 v[232:233], v[232:233], v[44:45]
	v_pk_add_f32 v[232:233], v[232:233], v[46:47]
	ds_read2_b32 v[32:33], v115 offset0:192 offset1:193
	ds_read2_b32 v[34:35], v115 offset0:194 offset1:195
	ds_read2_b32 v[36:37], v115 offset0:200 offset1:201
	ds_read2_b32 v[38:39], v115 offset0:202 offset1:203
	ds_read2_b32 v[40:41], v115 offset0:208 offset1:209
	ds_read2_b32 v[42:43], v115 offset0:210 offset1:211
	ds_read2_b32 v[44:45], v115 offset0:216 offset1:217
	ds_read2_b32 v[46:47], v115 offset0:218 offset1:219
	v_mfma_f32_32x32x16_bf16 v[0:15], v[64:67], v[72:75], v[0:15]
	v_mfma_f32_32x32x16_bf16 v[16:31], v[64:67], v[76:79], v[16:31]
	v_mfma_f32_32x32x16_bf16 v[0:15], v[68:71], v[220:223], v[0:15]
	v_mfma_f32_32x32x16_bf16 v[16:31], v[68:71], v[224:227], v[16:31]
	global_load_dwordx4 v[156:159], v239, s[86:87]
	global_load_dwordx4 v[160:163], v240, s[86:87]
	global_load_dwordx4 v[164:167], v241, s[86:87]
	global_load_dwordx4 v[168:171], v242, s[86:87]
	global_load_dwordx4 v[172:175], v101, s[86:87] offset:768
	global_load_dwordx4 v[176:179], v150, s[86:87] offset:768
	global_load_dwordx4 v[180:183], v101, s[86:87] offset:832
	global_load_dwordx4 v[184:187], v150, s[86:87] offset:832
	ds_read_b64_tr_b16 v[72:73], v231
	ds_read_b64_tr_b16 v[74:75], v231 offset:512
	ds_read_b64_tr_b16 v[76:77], v231 offset:2048
	ds_read_b64_tr_b16 v[78:79], v231 offset:2560
	ds_read_b64_tr_b16 v[220:221], v231 offset:1024
	ds_read_b64_tr_b16 v[222:223], v231 offset:1536
	ds_read_b64_tr_b16 v[224:225], v231 offset:3072
	ds_read_b64_tr_b16 v[226:227], v231 offset:3584
	v_exp_f32_e32 v188, v188
	v_exp_f32_e32 v189, v189
	v_exp_f32_e32 v190, v190
	v_exp_f32_e32 v191, v191
	s_waitcnt vmcnt(12)
	ds_write_b128 v247, v[116:119]
	ds_write_b128 v247, v[120:123] offset:1024
	ds_write_b128 v247, v[124:127] offset:2048
	ds_write_b128 v247, v[128:131] offset:3072
	ds_read_b128 v[116:119], v248
	ds_read_b128 v[120:123], v249
	ds_read_b128 v[124:127], v250
	ds_read_b128 v[128:131], v251
	s_waitcnt vmcnt(8)
	ds_write_b128 v112, v[132:135]
	ds_write_b128 v112, v[136:139] offset:1024
	ds_write_b128 v112, v[140:143] offset:2048
	ds_write_b128 v112, v[144:147] offset:3072
	v_exp_f32_e32 v192, v192
	v_exp_f32_e32 v193, v193
	v_exp_f32_e32 v194, v194
	v_exp_f32_e32 v195, v195
	s_waitcnt lgkmcnt(4)
	v_mfma_f32_32x32x16_bf16 v[32:47], v[116:119], v[48:51], v[32:47]
	v_exp_f32_e32 v196, v196
	v_exp_f32_e32 v197, v197
	v_mfma_f32_32x32x16_bf16 v[32:47], v[120:123], v[52:55], v[32:47]
	v_exp_f32_e32 v198, v198
	v_exp_f32_e32 v199, v199
	v_mfma_f32_32x32x16_bf16 v[32:47], v[124:127], v[56:59], v[32:47]
	v_exp_f32_e32 v200, v200
	v_exp_f32_e32 v201, v201
	v_mfma_f32_32x32x16_bf16 v[32:47], v[128:131], v[60:63], v[32:47]
	v_exp_f32_e32 v202, v202
	v_exp_f32_e32 v203, v203
	v_cvt_pk_bf16_f32 v64, v188, v189
	v_cvt_pk_bf16_f32 v65, v190, v191
	v_cvt_pk_bf16_f32 v66, v192, v193
	v_cvt_pk_bf16_f32 v67, v194, v195
	v_cvt_pk_bf16_f32 v68, v196, v197
	v_cvt_pk_bf16_f32 v69, v198, v199
	v_cvt_pk_bf16_f32 v70, v200, v201
	v_cvt_pk_bf16_f32 v71, v202, v203
	v_pk_add_f32 v[232:233], v[232:233], v[188:189]
	v_pk_add_f32 v[232:233], v[232:233], v[190:191]
	v_pk_add_f32 v[232:233], v[232:233], v[192:193]
	v_pk_add_f32 v[232:233], v[232:233], v[194:195]
	v_pk_add_f32 v[232:233], v[232:233], v[196:197]
	v_pk_add_f32 v[232:233], v[232:233], v[198:199]
	v_pk_add_f32 v[232:233], v[232:233], v[200:201]
	v_pk_add_f32 v[232:233], v[232:233], v[202:203]
	ds_read2_b32 v[188:189], v115 offset0:224 offset1:225
	ds_read2_b32 v[190:191], v115 offset0:226 offset1:227
	ds_read2_b32 v[192:193], v115 offset0:232 offset1:233
	ds_read2_b32 v[194:195], v115 offset0:234 offset1:235
	ds_read2_b32 v[196:197], v115 offset0:240 offset1:241
	ds_read2_b32 v[198:199], v115 offset0:242 offset1:243
	ds_read2_b32 v[200:201], v115 offset0:248 offset1:249
	ds_read2_b32 v[202:203], v115 offset0:250 offset1:251
	v_mfma_f32_32x32x16_bf16 v[0:15], v[64:67], v[72:75], v[0:15]
	v_mfma_f32_32x32x16_bf16 v[16:31], v[64:67], v[76:79], v[16:31]
	v_mfma_f32_32x32x16_bf16 v[0:15], v[68:71], v[220:223], v[0:15]
	v_mfma_f32_32x32x16_bf16 v[16:31], v[68:71], v[224:227], v[16:31]
	global_load_dwordx4 v[116:119], v243, s[88:89]
	global_load_dwordx4 v[120:123], v244, s[88:89]
	global_load_dwordx4 v[124:127], v245, s[88:89]
	global_load_dwordx4 v[128:131], v246, s[88:89]
	global_load_dwordx4 v[132:135], v148, s[88:89] offset:768
	global_load_dwordx4 v[136:139], v151, s[88:89] offset:768
	global_load_dwordx4 v[140:143], v148, s[88:89] offset:832
	global_load_dwordx4 v[144:147], v151, s[88:89] offset:832
	s_add_u32 s88, s88, 0x300000
	s_addc_u32 s89, s89, 0
	ds_read_b64_tr_b16 v[72:73], v231
	ds_read_b64_tr_b16 v[74:75], v231 offset:512
	ds_read_b64_tr_b16 v[76:77], v231 offset:2048
	ds_read_b64_tr_b16 v[78:79], v231 offset:2560
	ds_read_b64_tr_b16 v[220:221], v231 offset:1024
	ds_read_b64_tr_b16 v[222:223], v231 offset:1536
	ds_read_b64_tr_b16 v[224:225], v231 offset:3072
	ds_read_b64_tr_b16 v[226:227], v231 offset:3584
	v_exp_f32_e32 v32, v32
	v_exp_f32_e32 v33, v33
	v_exp_f32_e32 v34, v34
	v_exp_f32_e32 v35, v35
	s_waitcnt vmcnt(12)
	ds_write_b128 v247, v[156:159]
	ds_write_b128 v247, v[160:163] offset:1024
	ds_write_b128 v247, v[164:167] offset:2048
	ds_write_b128 v247, v[168:171] offset:3072
	ds_read_b128 v[156:159], v248
	ds_read_b128 v[160:163], v249
	ds_read_b128 v[164:167], v250
	ds_read_b128 v[168:171], v251
	s_waitcnt vmcnt(8)
	ds_write_b128 v112, v[172:175]
	ds_write_b128 v112, v[176:179] offset:1024
	ds_write_b128 v112, v[180:183] offset:2048
	ds_write_b128 v112, v[184:187] offset:3072
	v_exp_f32_e32 v36, v36
	v_exp_f32_e32 v37, v37
	v_exp_f32_e32 v38, v38
	v_exp_f32_e32 v39, v39
	s_waitcnt lgkmcnt(4)
	v_mfma_f32_32x32x16_bf16 v[188:203], v[156:159], v[48:51], v[188:203]
	v_exp_f32_e32 v40, v40
	v_exp_f32_e32 v41, v41
	v_mfma_f32_32x32x16_bf16 v[188:203], v[160:163], v[52:55], v[188:203]
	v_exp_f32_e32 v42, v42
	v_exp_f32_e32 v43, v43
	v_mfma_f32_32x32x16_bf16 v[188:203], v[164:167], v[56:59], v[188:203]
	v_exp_f32_e32 v44, v44
	v_exp_f32_e32 v45, v45
	v_mfma_f32_32x32x16_bf16 v[188:203], v[168:171], v[60:63], v[188:203]
	v_exp_f32_e32 v46, v46
	v_exp_f32_e32 v47, v47
	v_cvt_pk_bf16_f32 v64, v32, v33
	v_cvt_pk_bf16_f32 v65, v34, v35
	v_cvt_pk_bf16_f32 v66, v36, v37
	v_cvt_pk_bf16_f32 v67, v38, v39
	v_cvt_pk_bf16_f32 v68, v40, v41
	v_cvt_pk_bf16_f32 v69, v42, v43
	v_cvt_pk_bf16_f32 v70, v44, v45
	v_cvt_pk_bf16_f32 v71, v46, v47
	v_pk_add_f32 v[232:233], v[232:233], v[32:33]
	v_pk_add_f32 v[232:233], v[232:233], v[34:35]
	v_pk_add_f32 v[232:233], v[232:233], v[36:37]
	v_pk_add_f32 v[232:233], v[232:233], v[38:39]
	v_pk_add_f32 v[232:233], v[232:233], v[40:41]
	v_pk_add_f32 v[232:233], v[232:233], v[42:43]
	v_pk_add_f32 v[232:233], v[232:233], v[44:45]
	v_pk_add_f32 v[232:233], v[232:233], v[46:47]
	v_mov_b32_e32 v115, v230
	ds_read2_b32 v[32:33], v115 offset0:0 offset1:1
	ds_read2_b32 v[34:35], v115 offset0:2 offset1:3
	ds_read2_b32 v[36:37], v115 offset0:8 offset1:9
	ds_read2_b32 v[38:39], v115 offset0:10 offset1:11
	ds_read2_b32 v[40:41], v115 offset0:16 offset1:17
	ds_read2_b32 v[42:43], v115 offset0:18 offset1:19
	ds_read2_b32 v[44:45], v115 offset0:24 offset1:25
	ds_read2_b32 v[46:47], v115 offset0:26 offset1:27
	v_mfma_f32_32x32x16_bf16 v[0:15], v[64:67], v[72:75], v[0:15]
	v_mfma_f32_32x32x16_bf16 v[16:31], v[64:67], v[76:79], v[16:31]
	v_mfma_f32_32x32x16_bf16 v[0:15], v[68:71], v[220:223], v[0:15]
	v_mfma_f32_32x32x16_bf16 v[16:31], v[68:71], v[224:227], v[16:31]
	global_load_dwordx4 v[156:159], v243, s[88:89]
	global_load_dwordx4 v[160:163], v244, s[88:89]
	global_load_dwordx4 v[164:167], v245, s[88:89]
	global_load_dwordx4 v[168:171], v246, s[88:89]
	global_load_dwordx4 v[172:175], v148, s[88:89] offset:768
	global_load_dwordx4 v[176:179], v151, s[88:89] offset:768
	global_load_dwordx4 v[180:183], v148, s[88:89] offset:832
	global_load_dwordx4 v[184:187], v151, s[88:89] offset:832
	s_add_u32 s88, s88, 0x300000
	s_addc_u32 s89, s89, 0
	ds_read_b64_tr_b16 v[72:73], v231
	ds_read_b64_tr_b16 v[74:75], v231 offset:512
	ds_read_b64_tr_b16 v[76:77], v231 offset:2048
	ds_read_b64_tr_b16 v[78:79], v231 offset:2560
	ds_read_b64_tr_b16 v[220:221], v231 offset:1024
	ds_read_b64_tr_b16 v[222:223], v231 offset:1536
	ds_read_b64_tr_b16 v[224:225], v231 offset:3072
	ds_read_b64_tr_b16 v[226:227], v231 offset:3584
	v_exp_f32_e32 v188, v188
	v_exp_f32_e32 v189, v189
	v_exp_f32_e32 v190, v190
	v_exp_f32_e32 v191, v191
	s_waitcnt vmcnt(12)
	ds_write_b128 v247, v[116:119]
	ds_write_b128 v247, v[120:123] offset:1024
	ds_write_b128 v247, v[124:127] offset:2048
	ds_write_b128 v247, v[128:131] offset:3072
	ds_read_b128 v[116:119], v248
	ds_read_b128 v[120:123], v249
	ds_read_b128 v[124:127], v250
	ds_read_b128 v[128:131], v251
	s_waitcnt vmcnt(8)
	ds_write_b128 v112, v[132:135]
	ds_write_b128 v112, v[136:139] offset:1024
	ds_write_b128 v112, v[140:143] offset:2048
	ds_write_b128 v112, v[144:147] offset:3072
	v_exp_f32_e32 v192, v192
	v_exp_f32_e32 v193, v193
	v_exp_f32_e32 v194, v194
	v_exp_f32_e32 v195, v195
	s_waitcnt lgkmcnt(4)
	v_mfma_f32_32x32x16_bf16 v[32:47], v[116:119], v[48:51], v[32:47]
	v_exp_f32_e32 v196, v196
	v_exp_f32_e32 v197, v197
	v_mfma_f32_32x32x16_bf16 v[32:47], v[120:123], v[52:55], v[32:47]
	v_exp_f32_e32 v198, v198
	v_exp_f32_e32 v199, v199
	v_mfma_f32_32x32x16_bf16 v[32:47], v[124:127], v[56:59], v[32:47]
	v_exp_f32_e32 v200, v200
	v_exp_f32_e32 v201, v201
	v_mfma_f32_32x32x16_bf16 v[32:47], v[128:131], v[60:63], v[32:47]
	v_exp_f32_e32 v202, v202
	v_exp_f32_e32 v203, v203
	v_cvt_pk_bf16_f32 v64, v188, v189
	v_cvt_pk_bf16_f32 v65, v190, v191
	v_cvt_pk_bf16_f32 v66, v192, v193
	v_cvt_pk_bf16_f32 v67, v194, v195
	v_cvt_pk_bf16_f32 v68, v196, v197
	v_cvt_pk_bf16_f32 v69, v198, v199
	v_cvt_pk_bf16_f32 v70, v200, v201
	v_cvt_pk_bf16_f32 v71, v202, v203
	v_pk_add_f32 v[232:233], v[232:233], v[188:189]
	v_pk_add_f32 v[232:233], v[232:233], v[190:191]
	v_pk_add_f32 v[232:233], v[232:233], v[192:193]
	v_pk_add_f32 v[232:233], v[232:233], v[194:195]
	v_pk_add_f32 v[232:233], v[232:233], v[196:197]
	v_pk_add_f32 v[232:233], v[232:233], v[198:199]
	v_pk_add_f32 v[232:233], v[232:233], v[200:201]
	v_pk_add_f32 v[232:233], v[232:233], v[202:203]
	ds_read2_b32 v[188:189], v115 offset0:32 offset1:33
	ds_read2_b32 v[190:191], v115 offset0:34 offset1:35
	ds_read2_b32 v[192:193], v115 offset0:40 offset1:41
	ds_read2_b32 v[194:195], v115 offset0:42 offset1:43
	ds_read2_b32 v[196:197], v115 offset0:48 offset1:49
	ds_read2_b32 v[198:199], v115 offset0:50 offset1:51
	ds_read2_b32 v[200:201], v115 offset0:56 offset1:57
	ds_read2_b32 v[202:203], v115 offset0:58 offset1:59
	v_mfma_f32_32x32x16_bf16 v[0:15], v[64:67], v[72:75], v[0:15]
	v_mfma_f32_32x32x16_bf16 v[16:31], v[64:67], v[76:79], v[16:31]
	v_mfma_f32_32x32x16_bf16 v[0:15], v[68:71], v[220:223], v[0:15]
	v_mfma_f32_32x32x16_bf16 v[16:31], v[68:71], v[224:227], v[16:31]
	global_load_dwordx4 v[116:119], v243, s[88:89]
	global_load_dwordx4 v[120:123], v244, s[88:89]
	global_load_dwordx4 v[124:127], v245, s[88:89]
	global_load_dwordx4 v[128:131], v246, s[88:89]
	global_load_dwordx4 v[132:135], v148, s[88:89] offset:768
	global_load_dwordx4 v[136:139], v151, s[88:89] offset:768
	global_load_dwordx4 v[140:143], v148, s[88:89] offset:832
	global_load_dwordx4 v[144:147], v151, s[88:89] offset:832
	s_add_u32 s88, s88, 0x300000
	s_addc_u32 s89, s89, 0
	ds_read_b64_tr_b16 v[72:73], v231
	ds_read_b64_tr_b16 v[74:75], v231 offset:512
	ds_read_b64_tr_b16 v[76:77], v231 offset:2048
	ds_read_b64_tr_b16 v[78:79], v231 offset:2560
	ds_read_b64_tr_b16 v[220:221], v231 offset:1024
	ds_read_b64_tr_b16 v[222:223], v231 offset:1536
	ds_read_b64_tr_b16 v[224:225], v231 offset:3072
	ds_read_b64_tr_b16 v[226:227], v231 offset:3584
	v_exp_f32_e32 v32, v32
	v_exp_f32_e32 v33, v33
	v_exp_f32_e32 v34, v34
	v_exp_f32_e32 v35, v35
	s_waitcnt vmcnt(12)
	ds_write_b128 v247, v[156:159]
	ds_write_b128 v247, v[160:163] offset:1024
	ds_write_b128 v247, v[164:167] offset:2048
	ds_write_b128 v247, v[168:171] offset:3072
	ds_read_b128 v[156:159], v248
	ds_read_b128 v[160:163], v249
	ds_read_b128 v[164:167], v250
	ds_read_b128 v[168:171], v251
	s_waitcnt vmcnt(8)
	ds_write_b128 v112, v[172:175]
	ds_write_b128 v112, v[176:179] offset:1024
	ds_write_b128 v112, v[180:183] offset:2048
	ds_write_b128 v112, v[184:187] offset:3072
	v_exp_f32_e32 v36, v36
	v_exp_f32_e32 v37, v37
	v_exp_f32_e32 v38, v38
	v_exp_f32_e32 v39, v39
	s_waitcnt lgkmcnt(4)
	v_mfma_f32_32x32x16_bf16 v[188:203], v[156:159], v[48:51], v[188:203]
	v_exp_f32_e32 v40, v40
	v_exp_f32_e32 v41, v41
	v_mfma_f32_32x32x16_bf16 v[188:203], v[160:163], v[52:55], v[188:203]
	v_exp_f32_e32 v42, v42
	v_exp_f32_e32 v43, v43
	v_mfma_f32_32x32x16_bf16 v[188:203], v[164:167], v[56:59], v[188:203]
	v_exp_f32_e32 v44, v44
	v_exp_f32_e32 v45, v45
	v_mfma_f32_32x32x16_bf16 v[188:203], v[168:171], v[60:63], v[188:203]
	v_exp_f32_e32 v46, v46
	v_exp_f32_e32 v47, v47
	v_cvt_pk_bf16_f32 v64, v32, v33
	v_cvt_pk_bf16_f32 v65, v34, v35
	v_cvt_pk_bf16_f32 v66, v36, v37
	v_cvt_pk_bf16_f32 v67, v38, v39
	v_cvt_pk_bf16_f32 v68, v40, v41
	v_cvt_pk_bf16_f32 v69, v42, v43
	v_cvt_pk_bf16_f32 v70, v44, v45
	v_cvt_pk_bf16_f32 v71, v46, v47
	v_pk_add_f32 v[232:233], v[232:233], v[32:33]
	v_pk_add_f32 v[232:233], v[232:233], v[34:35]
	v_pk_add_f32 v[232:233], v[232:233], v[36:37]
	v_pk_add_f32 v[232:233], v[232:233], v[38:39]
	v_pk_add_f32 v[232:233], v[232:233], v[40:41]
	v_pk_add_f32 v[232:233], v[232:233], v[42:43]
	v_pk_add_f32 v[232:233], v[232:233], v[44:45]
	v_pk_add_f32 v[232:233], v[232:233], v[46:47]
	ds_read2_b32 v[32:33], v115 offset0:64 offset1:65
	ds_read2_b32 v[34:35], v115 offset0:66 offset1:67
	ds_read2_b32 v[36:37], v115 offset0:72 offset1:73
	ds_read2_b32 v[38:39], v115 offset0:74 offset1:75
	ds_read2_b32 v[40:41], v115 offset0:80 offset1:81
	ds_read2_b32 v[42:43], v115 offset0:82 offset1:83
	ds_read2_b32 v[44:45], v115 offset0:88 offset1:89
	ds_read2_b32 v[46:47], v115 offset0:90 offset1:91
	v_mfma_f32_32x32x16_bf16 v[0:15], v[64:67], v[72:75], v[0:15]
	v_mfma_f32_32x32x16_bf16 v[16:31], v[64:67], v[76:79], v[16:31]
	v_mfma_f32_32x32x16_bf16 v[0:15], v[68:71], v[220:223], v[0:15]
	v_mfma_f32_32x32x16_bf16 v[16:31], v[68:71], v[224:227], v[16:31]
	global_load_dwordx4 v[156:159], v243, s[88:89]
	global_load_dwordx4 v[160:163], v244, s[88:89]
	global_load_dwordx4 v[164:167], v245, s[88:89]
	global_load_dwordx4 v[168:171], v246, s[88:89]
	global_load_dwordx4 v[172:175], v148, s[88:89] offset:768
	global_load_dwordx4 v[176:179], v151, s[88:89] offset:768
	global_load_dwordx4 v[180:183], v148, s[88:89] offset:832
	global_load_dwordx4 v[184:187], v151, s[88:89] offset:832
	s_add_u32 s88, s88, 0x300000
	s_addc_u32 s89, s89, 0
	ds_read_b64_tr_b16 v[72:73], v231
	ds_read_b64_tr_b16 v[74:75], v231 offset:512
	ds_read_b64_tr_b16 v[76:77], v231 offset:2048
	ds_read_b64_tr_b16 v[78:79], v231 offset:2560
	ds_read_b64_tr_b16 v[220:221], v231 offset:1024
	ds_read_b64_tr_b16 v[222:223], v231 offset:1536
	ds_read_b64_tr_b16 v[224:225], v231 offset:3072
	ds_read_b64_tr_b16 v[226:227], v231 offset:3584
	v_exp_f32_e32 v188, v188
	v_exp_f32_e32 v189, v189
	v_exp_f32_e32 v190, v190
	v_exp_f32_e32 v191, v191
	s_waitcnt vmcnt(12)
	ds_write_b128 v247, v[116:119]
	ds_write_b128 v247, v[120:123] offset:1024
	ds_write_b128 v247, v[124:127] offset:2048
	ds_write_b128 v247, v[128:131] offset:3072
	ds_read_b128 v[116:119], v248
	ds_read_b128 v[120:123], v249
	ds_read_b128 v[124:127], v250
	ds_read_b128 v[128:131], v251
	s_waitcnt vmcnt(8)
	ds_write_b128 v112, v[132:135]
	ds_write_b128 v112, v[136:139] offset:1024
	ds_write_b128 v112, v[140:143] offset:2048
	ds_write_b128 v112, v[144:147] offset:3072
	v_exp_f32_e32 v192, v192
	v_exp_f32_e32 v193, v193
	v_exp_f32_e32 v194, v194
	v_exp_f32_e32 v195, v195
	s_waitcnt lgkmcnt(4)
	v_mfma_f32_32x32x16_bf16 v[32:47], v[116:119], v[48:51], v[32:47]
	v_exp_f32_e32 v196, v196
	v_exp_f32_e32 v197, v197
	v_mfma_f32_32x32x16_bf16 v[32:47], v[120:123], v[52:55], v[32:47]
	v_exp_f32_e32 v198, v198
	v_exp_f32_e32 v199, v199
	v_mfma_f32_32x32x16_bf16 v[32:47], v[124:127], v[56:59], v[32:47]
	v_exp_f32_e32 v200, v200
	v_exp_f32_e32 v201, v201
	v_mfma_f32_32x32x16_bf16 v[32:47], v[128:131], v[60:63], v[32:47]
	v_exp_f32_e32 v202, v202
	v_exp_f32_e32 v203, v203
	v_cvt_pk_bf16_f32 v64, v188, v189
	v_cvt_pk_bf16_f32 v65, v190, v191
	v_cvt_pk_bf16_f32 v66, v192, v193
	v_cvt_pk_bf16_f32 v67, v194, v195
	v_cvt_pk_bf16_f32 v68, v196, v197
	v_cvt_pk_bf16_f32 v69, v198, v199
	v_cvt_pk_bf16_f32 v70, v200, v201
	v_cvt_pk_bf16_f32 v71, v202, v203
	v_pk_add_f32 v[232:233], v[232:233], v[188:189]
	v_pk_add_f32 v[232:233], v[232:233], v[190:191]
	v_pk_add_f32 v[232:233], v[232:233], v[192:193]
	v_pk_add_f32 v[232:233], v[232:233], v[194:195]
	v_pk_add_f32 v[232:233], v[232:233], v[196:197]
	v_pk_add_f32 v[232:233], v[232:233], v[198:199]
	v_pk_add_f32 v[232:233], v[232:233], v[200:201]
	v_pk_add_f32 v[232:233], v[232:233], v[202:203]
	ds_read2_b32 v[188:189], v115 offset0:96 offset1:97
	ds_read2_b32 v[190:191], v115 offset0:98 offset1:99
	ds_read2_b32 v[192:193], v115 offset0:104 offset1:105
	ds_read2_b32 v[194:195], v115 offset0:106 offset1:107
	ds_read2_b32 v[196:197], v115 offset0:112 offset1:113
	ds_read2_b32 v[198:199], v115 offset0:114 offset1:115
	ds_read2_b32 v[200:201], v115 offset0:120 offset1:121
	ds_read2_b32 v[202:203], v115 offset0:122 offset1:123
	v_mfma_f32_32x32x16_bf16 v[0:15], v[64:67], v[72:75], v[0:15]
	v_mfma_f32_32x32x16_bf16 v[16:31], v[64:67], v[76:79], v[16:31]
	v_mfma_f32_32x32x16_bf16 v[0:15], v[68:71], v[220:223], v[0:15]
	v_mfma_f32_32x32x16_bf16 v[16:31], v[68:71], v[224:227], v[16:31]
	global_load_dwordx4 v[116:119], v243, s[88:89]
	global_load_dwordx4 v[120:123], v244, s[88:89]
	global_load_dwordx4 v[124:127], v245, s[88:89]
	global_load_dwordx4 v[128:131], v246, s[88:89]
	global_load_dwordx4 v[132:135], v148, s[88:89] offset:768
	global_load_dwordx4 v[136:139], v151, s[88:89] offset:768
	global_load_dwordx4 v[140:143], v148, s[88:89] offset:832
	global_load_dwordx4 v[144:147], v151, s[88:89] offset:832
	ds_read_b64_tr_b16 v[72:73], v231
	ds_read_b64_tr_b16 v[74:75], v231 offset:512
	ds_read_b64_tr_b16 v[76:77], v231 offset:2048
	ds_read_b64_tr_b16 v[78:79], v231 offset:2560
	ds_read_b64_tr_b16 v[220:221], v231 offset:1024
	ds_read_b64_tr_b16 v[222:223], v231 offset:1536
	ds_read_b64_tr_b16 v[224:225], v231 offset:3072
	ds_read_b64_tr_b16 v[226:227], v231 offset:3584
	v_exp_f32_e32 v32, v32
	v_exp_f32_e32 v33, v33
	v_exp_f32_e32 v34, v34
	v_exp_f32_e32 v35, v35
	s_waitcnt vmcnt(12)
	ds_write_b128 v247, v[156:159]
	ds_write_b128 v247, v[160:163] offset:1024
	ds_write_b128 v247, v[164:167] offset:2048
	ds_write_b128 v247, v[168:171] offset:3072
	ds_read_b128 v[156:159], v248
	ds_read_b128 v[160:163], v249
	ds_read_b128 v[164:167], v250
	ds_read_b128 v[168:171], v251
	s_waitcnt vmcnt(8)
	ds_write_b128 v112, v[172:175]
	ds_write_b128 v112, v[176:179] offset:1024
	ds_write_b128 v112, v[180:183] offset:2048
	ds_write_b128 v112, v[184:187] offset:3072
	v_exp_f32_e32 v36, v36
	v_exp_f32_e32 v37, v37
	v_exp_f32_e32 v38, v38
	v_exp_f32_e32 v39, v39
	s_waitcnt lgkmcnt(4)
	v_mfma_f32_32x32x16_bf16 v[188:203], v[156:159], v[48:51], v[188:203]
	v_exp_f32_e32 v40, v40
	v_exp_f32_e32 v41, v41
	v_mfma_f32_32x32x16_bf16 v[188:203], v[160:163], v[52:55], v[188:203]
	v_exp_f32_e32 v42, v42
	v_exp_f32_e32 v43, v43
	v_mfma_f32_32x32x16_bf16 v[188:203], v[164:167], v[56:59], v[188:203]
	v_exp_f32_e32 v44, v44
	v_exp_f32_e32 v45, v45
	v_mfma_f32_32x32x16_bf16 v[188:203], v[168:171], v[60:63], v[188:203]
	v_exp_f32_e32 v46, v46
	v_exp_f32_e32 v47, v47
	v_cvt_pk_bf16_f32 v64, v32, v33
	v_cvt_pk_bf16_f32 v65, v34, v35
	v_cvt_pk_bf16_f32 v66, v36, v37
	v_cvt_pk_bf16_f32 v67, v38, v39
	v_cvt_pk_bf16_f32 v68, v40, v41
	v_cvt_pk_bf16_f32 v69, v42, v43
	v_cvt_pk_bf16_f32 v70, v44, v45
	v_cvt_pk_bf16_f32 v71, v46, v47
	v_pk_add_f32 v[232:233], v[232:233], v[32:33]
	v_pk_add_f32 v[232:233], v[232:233], v[34:35]
	v_pk_add_f32 v[232:233], v[232:233], v[36:37]
	v_pk_add_f32 v[232:233], v[232:233], v[38:39]
	v_pk_add_f32 v[232:233], v[232:233], v[40:41]
	v_pk_add_f32 v[232:233], v[232:233], v[42:43]
	v_pk_add_f32 v[232:233], v[232:233], v[44:45]
	v_pk_add_f32 v[232:233], v[232:233], v[46:47]
	ds_read2_b32 v[32:33], v115 offset0:128 offset1:129
	ds_read2_b32 v[34:35], v115 offset0:130 offset1:131
	ds_read2_b32 v[36:37], v115 offset0:136 offset1:137
	ds_read2_b32 v[38:39], v115 offset0:138 offset1:139
	ds_read2_b32 v[40:41], v115 offset0:144 offset1:145
	ds_read2_b32 v[42:43], v115 offset0:146 offset1:147
	ds_read2_b32 v[44:45], v115 offset0:152 offset1:153
	ds_read2_b32 v[46:47], v115 offset0:154 offset1:155
	v_mfma_f32_32x32x16_bf16 v[0:15], v[64:67], v[72:75], v[0:15]
	v_mfma_f32_32x32x16_bf16 v[16:31], v[64:67], v[76:79], v[16:31]
	v_mfma_f32_32x32x16_bf16 v[0:15], v[68:71], v[220:223], v[0:15]
	v_mfma_f32_32x32x16_bf16 v[16:31], v[68:71], v[224:227], v[16:31]
	ds_read_b64_tr_b16 v[72:73], v231
	ds_read_b64_tr_b16 v[74:75], v231 offset:512
	ds_read_b64_tr_b16 v[76:77], v231 offset:2048
	ds_read_b64_tr_b16 v[78:79], v231 offset:2560
	ds_read_b64_tr_b16 v[220:221], v231 offset:1024
	ds_read_b64_tr_b16 v[222:223], v231 offset:1536
	ds_read_b64_tr_b16 v[224:225], v231 offset:3072
	ds_read_b64_tr_b16 v[226:227], v231 offset:3584
	v_exp_f32_e32 v188, v188
	v_exp_f32_e32 v189, v189
	v_exp_f32_e32 v190, v190
	v_exp_f32_e32 v191, v191
	s_waitcnt vmcnt(4)
	ds_write_b128 v247, v[116:119]
	ds_write_b128 v247, v[120:123] offset:1024
	ds_write_b128 v247, v[124:127] offset:2048
	ds_write_b128 v247, v[128:131] offset:3072
	ds_read_b128 v[116:119], v248
	ds_read_b128 v[120:123], v249
	ds_read_b128 v[124:127], v250
	ds_read_b128 v[128:131], v251
	s_waitcnt vmcnt(0)
	ds_write_b128 v112, v[132:135]
	ds_write_b128 v112, v[136:139] offset:1024
	ds_write_b128 v112, v[140:143] offset:2048
	ds_write_b128 v112, v[144:147] offset:3072
	v_exp_f32_e32 v192, v192
	v_exp_f32_e32 v193, v193
	v_exp_f32_e32 v194, v194
	v_exp_f32_e32 v195, v195
	s_waitcnt lgkmcnt(4)
	v_mfma_f32_32x32x16_bf16 v[32:47], v[116:119], v[48:51], v[32:47]
	v_exp_f32_e32 v196, v196
	v_exp_f32_e32 v197, v197
	v_mfma_f32_32x32x16_bf16 v[32:47], v[120:123], v[52:55], v[32:47]
	v_exp_f32_e32 v198, v198
	v_exp_f32_e32 v199, v199
	v_mfma_f32_32x32x16_bf16 v[32:47], v[124:127], v[56:59], v[32:47]
	v_exp_f32_e32 v200, v200
	v_exp_f32_e32 v201, v201
	v_mfma_f32_32x32x16_bf16 v[32:47], v[128:131], v[60:63], v[32:47]
	v_exp_f32_e32 v202, v202
	v_exp_f32_e32 v203, v203
	v_cvt_pk_bf16_f32 v64, v188, v189
	v_cvt_pk_bf16_f32 v65, v190, v191
	v_cvt_pk_bf16_f32 v66, v192, v193
	v_cvt_pk_bf16_f32 v67, v194, v195
	v_cvt_pk_bf16_f32 v68, v196, v197
	v_cvt_pk_bf16_f32 v69, v198, v199
	v_cvt_pk_bf16_f32 v70, v200, v201
	v_cvt_pk_bf16_f32 v71, v202, v203
	v_pk_add_f32 v[232:233], v[232:233], v[188:189]
	v_pk_add_f32 v[232:233], v[232:233], v[190:191]
	v_pk_add_f32 v[232:233], v[232:233], v[192:193]
	v_pk_add_f32 v[232:233], v[232:233], v[194:195]
	v_pk_add_f32 v[232:233], v[232:233], v[196:197]
	v_pk_add_f32 v[232:233], v[232:233], v[198:199]
	v_pk_add_f32 v[232:233], v[232:233], v[200:201]
	v_pk_add_f32 v[232:233], v[232:233], v[202:203]
	v_mfma_f32_32x32x16_bf16 v[0:15], v[64:67], v[72:75], v[0:15]
	v_mfma_f32_32x32x16_bf16 v[16:31], v[64:67], v[76:79], v[16:31]
	v_mfma_f32_32x32x16_bf16 v[0:15], v[68:71], v[220:223], v[0:15]
	v_mfma_f32_32x32x16_bf16 v[16:31], v[68:71], v[224:227], v[16:31]
	ds_read_b64_tr_b16 v[72:73], v231
	ds_read_b64_tr_b16 v[74:75], v231 offset:512
	ds_read_b64_tr_b16 v[76:77], v231 offset:2048
	ds_read_b64_tr_b16 v[78:79], v231 offset:2560
	ds_read_b64_tr_b16 v[220:221], v231 offset:1024
	ds_read_b64_tr_b16 v[222:223], v231 offset:1536
	ds_read_b64_tr_b16 v[224:225], v231 offset:3072
	ds_read_b64_tr_b16 v[226:227], v231 offset:3584
	s_waitcnt lgkmcnt(0)
	v_exp_f32_e32 v32, v32
	v_exp_f32_e32 v33, v33
	v_exp_f32_e32 v34, v34
	v_exp_f32_e32 v35, v35
	v_exp_f32_e32 v36, v36
	v_exp_f32_e32 v37, v37
	v_exp_f32_e32 v38, v38
	v_exp_f32_e32 v39, v39
	v_exp_f32_e32 v40, v40
	v_exp_f32_e32 v41, v41
	v_exp_f32_e32 v42, v42
	v_exp_f32_e32 v43, v43
	v_exp_f32_e32 v44, v44
	v_exp_f32_e32 v45, v45
	v_exp_f32_e32 v46, v46
	v_exp_f32_e32 v47, v47
	v_cvt_pk_bf16_f32 v64, v32, v33
	v_cvt_pk_bf16_f32 v65, v34, v35
	v_cvt_pk_bf16_f32 v66, v36, v37
	v_cvt_pk_bf16_f32 v67, v38, v39
	v_cvt_pk_bf16_f32 v68, v40, v41
	v_cvt_pk_bf16_f32 v69, v42, v43
	v_cvt_pk_bf16_f32 v70, v44, v45
	v_cvt_pk_bf16_f32 v71, v46, v47
	v_pk_add_f32 v[232:233], v[232:233], v[32:33]
	v_pk_add_f32 v[232:233], v[232:233], v[34:35]
	v_pk_add_f32 v[232:233], v[232:233], v[36:37]
	v_pk_add_f32 v[232:233], v[232:233], v[38:39]
	v_pk_add_f32 v[232:233], v[232:233], v[40:41]
	v_pk_add_f32 v[232:233], v[232:233], v[42:43]
	v_pk_add_f32 v[232:233], v[232:233], v[44:45]
	v_pk_add_f32 v[232:233], v[232:233], v[46:47]
	v_mfma_f32_32x32x16_bf16 v[0:15], v[64:67], v[72:75], v[0:15]
	v_mfma_f32_32x32x16_bf16 v[16:31], v[64:67], v[76:79], v[16:31]
	v_mfma_f32_32x32x16_bf16 v[0:15], v[68:71], v[220:223], v[0:15]
	v_mfma_f32_32x32x16_bf16 v[16:31], v[68:71], v[224:227], v[16:31]
	v_add_f32_e32 v113, v232, v233
	v_or_b32_e32 v114, 1, v107
	v_or_b32_e32 v97, 2, v107
	v_or_b32_e32 v96, 3, v107
	v_or_b32_e32 v95, 8, v107
	v_or_b32_e32 v94, 9, v107
	v_or_b32_e32 v93, 10, v107
	v_or_b32_e32 v92, 11, v107
	v_or_b32_e32 v91, 16, v107
	v_or_b32_e32 v90, 17, v107
	v_or_b32_e32 v89, 18, v107
	v_or_b32_e32 v88, 19, v107
	v_or_b32_e32 v87, 24, v107
	v_or_b32_e32 v86, 25, v107
	v_or_b32_e32 v85, 26, v107
	v_or_b32_e32 v84, 27, v107
	s_nop 11
	s_branch .LBB0_553
.LBB0_558:
	s_movk_i32 s100, 0x1800
	s_add_i32 s101, s6, 0x15c00
	s_lshl_b32 s90, s58, 1
	s_add_u32 s82, s56, s90
	s_addc_u32 s83, s57, 0
	s_add_u32 s82, s82, 0x1200
	s_addc_u32 s83, s83, 0
	s_sub_i32 s90, s76, 64
	s_mul_i32 s90, s90, 0x1800
	s_add_u32 s84, s82, s90
	s_addc_u32 s85, s83, 0
	s_sub_i32 s90, s76, 256
	s_mul_i32 s90, s90, 0x1800
	s_add_u32 s86, s82, s90
	s_addc_u32 s87, s83, 0
	s_sub_i32 s90, s76, 1024
	s_mul_i32 s90, s90, 0x1800
	s_add_u32 s88, s82, s90
	s_addc_u32 s89, s83, 0
	v_lshlrev_b32_e32 v153, 1, v98
	v_mad_u32_u24 v80, v105, s100, v82
	v_mad_u32_u24 v100, v110, s100, v153
	v_add_u32_e32 v149, 0x18000, v100
	v_lshlrev_b32_e32 v83, 2, v105
	v_mad_u32_u24 v83, v83, s100, v82
	v_lshlrev_b32_e32 v101, 2, v110
	v_mad_u32_u24 v101, v101, s100, v153
	v_add_u32_e32 v150, 0x60000, v101
	v_lshlrev_b32_e32 v99, 4, v105
	v_mad_u32_u24 v99, v99, s100, v82
	v_lshlrev_b32_e32 v148, 4, v110
	v_mad_u32_u24 v148, v148, s100, v153
	v_add_u32_e32 v151, 0x180000, v148
	v_lshrrev_b32_e32 v249, 3, v103
	v_and_b32_e32 v250, 7, v103
	v_lshlrev_b32_e32 v250, 4, v250
	v_add_u32_e32 v235, 0, v249
	v_add_u32_e32 v236, 8, v249
	v_add_u32_e32 v237, 16, v249
	v_add_u32_e32 v238, 24, v249
	v_add_u32_e32 v239, 0, v249
	v_lshlrev_b32_e32 v239, 2, v239
	v_add_u32_e32 v240, 8, v249
	v_lshlrev_b32_e32 v240, 2, v240
	v_add_u32_e32 v241, 16, v249
	v_lshlrev_b32_e32 v241, 2, v241
	v_add_u32_e32 v242, 24, v249
	v_lshlrev_b32_e32 v242, 2, v242
	v_add_u32_e32 v243, 0, v249
; #define LAS __attribute__((address_space(3)))
; #define GAS __attribute__((address_space(1)))
; __device__ __forceinline__ void dil_unit(LAS unsigned char* lds, bf16_t* proj, int seq, int hd, int T0, int rho) {
;     ...
;     const int tid = tid_, lane = tid & 63, r32 = lane & 31, hi = lane >> 5, wid = __builtin_amdgcn_readfirstlane(tid >> 6);
;     bf16_t* base = proj + (size_t)seq * SEQ * NIN;
;     LAS unsigned char* wbuf = lds + wid * 4096;
;     const LAS unsigned char* vp = wbuf + ((lane >> 4) & 1) * 32 + (lane & 3) * 8 + (4 * hi + ((lane & 15) >> 2)) * 64;
;     const int P0 = T0 + rho;
;     bf16x8 qr[4];
; #pragma unroll
;     for (int ks = 0; ks < 4; ++ks) qr[ks] = *(const GAS bf16x8*)(base + (size_t)(P0 + 16 * r32) * NIN + PC_LQ + hd * 64 + 16 * ks + 8 * hi);
;     f32x16 o0 = {}, o1 = {}; float l = 0.f;
;     const bool bound = (T0 < 1024) || (T0 >= 15360);
	v_lshlrev_b32_e32 v243, 4, v243
	v_add_u32_e32 v244, 8, v249
	v_lshlrev_b32_e32 v244, 4, v244
	v_add_u32_e32 v245, 16, v249
	v_lshlrev_b32_e32 v245, 4, v245
	v_add_u32_e32 v246, 24, v249
	v_lshlrev_b32_e32 v246, 4, v246
	v_mov_b32_e32 v252, v250
	v_mov_b32_e32 v100, v110
	v_add_u32_e32 v149, 16, v100
	v_lshlrev_b32_e32 v101, 2, v110
	v_add_u32_e32 v150, 64, v101
	v_lshlrev_b32_e32 v148, 4, v110
	v_add_u32_e32 v151, 256, v148
	s_mov_b32 s98, 0x4000
	s_mov_b32 s99, 0x3fff
	v_and_b32_e32 v247, 7, v249
	v_lshlrev_b32_e32 v247, 4, v247
	v_xor_b32_e32 v247, v247, v112
	v_and_b32_e32 v153, 7, v105
	v_or_b32_e32 v248, 0, v106
	v_xor_b32_e32 v248, v248, v153
	v_lshlrev_b32_e32 v248, 4, v248
	v_lshl_add_u32 v248, v105, 7, v248
	v_add_u32_e32 v248, s77, v248
	v_or_b32_e32 v249, 2, v106
	v_xor_b32_e32 v249, v249, v153
	v_lshlrev_b32_e32 v249, 4, v249
	v_lshl_add_u32 v249, v105, 7, v249
	v_add_u32_e32 v249, s77, v249
	v_or_b32_e32 v250, 4, v106
	v_xor_b32_e32 v250, v250, v153
	v_lshlrev_b32_e32 v250, 4, v250
	v_lshl_add_u32 v250, v105, 7, v250
	v_add_u32_e32 v250, s77, v250
	v_or_b32_e32 v251, 6, v106
	v_xor_b32_e32 v251, v251, v153
	v_lshlrev_b32_e32 v251, 4, v251
	v_lshl_add_u32 v251, v105, 7, v251
	v_add_u32_e32 v251, s77, v251
	v_lshlrev_b32_e32 v153, 1, v98
	v_mul_u32_u24_e32 v228, 17, v105
	v_sub_u32_e32 v228, v107, v228
	s_mul_i32 s90, s58, 153
	s_lshr_b32 s90, s90, 1
	s_add_i32 s90, s90, 34876
	v_lshl_add_u32 v228, v228, 2, s90
	v_lshlrev_b32_e32 v229, 2, v105
	v_sub_u32_e32 v229, v107, v229
	s_add_i32 s90, s101, 5104
	v_lshl_add_u32 v229, v229, 2, s90
	v_sub_u32_e32 v230, v107, v105
	s_add_i32 s90, s101, 6364
	v_lshl_add_u32 v230, v230, 2, s90
	v_add_u32_e32 v231, v109, v108
	v_mov_b64_e32 v[232:233], 0
	v_mov_b64_e32 v[0:1], 0
	v_mov_b64_e32 v[2:3], 0
	v_mov_b64_e32 v[4:5], 0
	v_mov_b64_e32 v[6:7], 0
	v_mov_b64_e32 v[8:9], 0
	v_mov_b64_e32 v[10:11], 0
	v_mov_b64_e32 v[12:13], 0
	v_mov_b64_e32 v[14:15], 0
	v_mov_b64_e32 v[16:17], 0
	v_mov_b64_e32 v[18:19], 0
	v_mov_b64_e32 v[20:21], 0
	v_mov_b64_e32 v[22:23], 0
	v_mov_b64_e32 v[24:25], 0
	v_mov_b64_e32 v[26:27], 0
	v_mov_b64_e32 v[28:29], 0
	v_mov_b64_e32 v[30:31], 0
	s_add_i32 s90, s76, -64
	v_add_u32_e32 v80, s90, v235
	v_add_u32_e32 v83, s90, v236
	v_add_u32_e32 v99, s90, v237
	v_add_u32_e32 v253, s90, v238
	v_add_u32_e32 v254, s90, v100
	v_add_u32_e32 v255, s90, v149
	v_med3_i32 v80, v80, 0, s99
	v_med3_i32 v83, v83, 0, s99
	v_med3_i32 v99, v99, 0, s99
	v_med3_i32 v253, v253, 0, s99
	v_med3_i32 v254, v254, 0, s99
	v_med3_i32 v255, v255, 0, s99
	v_mad_u32_u24 v80, v80, s100, v252
	v_mad_u32_u24 v83, v83, s100, v252
	v_mad_u32_u24 v99, v99, s100, v252
	v_mad_u32_u24 v253, v253, s100, v252
	v_mad_u32_u24 v254, v254, s100, v153
	v_mad_u32_u24 v255, v255, s100, v153
	global_load_dwordx4 v[116:119], v80, s[82:83]
	global_load_dwordx4 v[120:123], v83, s[82:83]
	global_load_dwordx4 v[124:127], v99, s[82:83]
	global_load_dwordx4 v[128:131], v253, s[82:83]
	global_load_dwordx4 v[132:135], v254, s[82:83] offset:768
	global_load_dwordx4 v[136:139], v255, s[82:83] offset:768
	global_load_dwordx4 v[140:143], v254, s[82:83] offset:832
	global_load_dwordx4 v[144:147], v255, s[82:83] offset:832
	s_add_i32 s90, s76, -32
	v_add_u32_e32 v80, s90, v235
	v_add_u32_e32 v83, s90, v236
	v_add_u32_e32 v99, s90, v237
	v_add_u32_e32 v253, s90, v238
	v_add_u32_e32 v254, s90, v100
	v_add_u32_e32 v255, s90, v149
	v_med3_i32 v80, v80, 0, s99
	v_med3_i32 v83, v83, 0, s99
	v_med3_i32 v99, v99, 0, s99
	v_med3_i32 v253, v253, 0, s99
	v_med3_i32 v254, v254, 0, s99
	v_med3_i32 v255, v255, 0, s99
	v_mad_u32_u24 v80, v80, s100, v252
	v_mad_u32_u24 v83, v83, s100, v252
	v_mad_u32_u24 v99, v99, s100, v252
	v_mad_u32_u24 v253, v253, s100, v252
	v_mad_u32_u24 v254, v254, s100, v153
	v_mad_u32_u24 v255, v255, s100, v153
	global_load_dwordx4 v[156:159], v80, s[82:83]
	global_load_dwordx4 v[160:163], v83, s[82:83]
	global_load_dwordx4 v[164:167], v99, s[82:83]
	global_load_dwordx4 v[168:171], v253, s[82:83]
	global_load_dwordx4 v[172:175], v254, s[82:83] offset:768
	global_load_dwordx4 v[176:179], v255, s[82:83] offset:768
	global_load_dwordx4 v[180:183], v254, s[82:83] offset:832
	global_load_dwordx4 v[184:187], v255, s[82:83] offset:832
	v_mov_b32_e32 v115, v228
	ds_read2_b32 v[32:33], v115 offset0:0 offset1:1
	ds_read2_b32 v[34:35], v115 offset0:2 offset1:3
	ds_read2_b32 v[36:37], v115 offset0:8 offset1:9
	ds_read2_b32 v[38:39], v115 offset0:10 offset1:11
	ds_read2_b32 v[40:41], v115 offset0:17 offset1:18
	ds_read2_b32 v[42:43], v115 offset0:19 offset1:20
	ds_read2_b32 v[44:45], v115 offset0:25 offset1:26
	ds_read2_b32 v[46:47], v115 offset0:27 offset1:28
	s_waitcnt vmcnt(8)
	ds_write_b128 v247, v[116:119]
	ds_write_b128 v247, v[120:123] offset:1024
	ds_write_b128 v247, v[124:127] offset:2048
	ds_write_b128 v247, v[128:131] offset:3072
	ds_read_b128 v[116:119], v248
	ds_read_b128 v[120:123], v249
	ds_read_b128 v[124:127], v250
	ds_read_b128 v[128:131], v251
	ds_write_b128 v112, v[132:135]
	ds_write_b128 v112, v[136:139] offset:1024
	ds_write_b128 v112, v[140:143] offset:2048
	ds_write_b128 v112, v[144:147] offset:3072
	s_waitcnt lgkmcnt(4)
	v_mfma_f32_32x32x16_bf16 v[32:47], v[116:119], v[48:51], v[32:47]
	v_mfma_f32_32x32x16_bf16 v[32:47], v[120:123], v[52:55], v[32:47]
	v_mfma_f32_32x32x16_bf16 v[32:47], v[124:127], v[56:59], v[32:47]
	v_mfma_f32_32x32x16_bf16 v[32:47], v[128:131], v[60:63], v[32:47]
	ds_read2_b32 v[188:189], v115 offset0:34 offset1:35
	ds_read2_b32 v[190:191], v115 offset0:36 offset1:37
	ds_read2_b32 v[192:193], v115 offset0:42 offset1:43
	ds_read2_b32 v[194:195], v115 offset0:44 offset1:45
	ds_read2_b32 v[196:197], v115 offset0:51 offset1:52
	ds_read2_b32 v[198:199], v115 offset0:53 offset1:54
	ds_read2_b32 v[200:201], v115 offset0:59 offset1:60
	ds_read2_b32 v[202:203], v115 offset0:61 offset1:62
	s_add_i32 s90, s76, 0
	v_add_u32_e32 v80, s90, v235
	v_add_u32_e32 v83, s90, v236
	v_add_u32_e32 v99, s90, v237
	v_add_u32_e32 v253, s90, v238
	v_add_u32_e32 v254, s90, v100
	v_add_u32_e32 v255, s90, v149
	v_med3_i32 v80, v80, 0, s99
	v_med3_i32 v83, v83, 0, s99
	v_med3_i32 v99, v99, 0, s99
	v_med3_i32 v253, v253, 0, s99
	v_med3_i32 v254, v254, 0, s99
	v_med3_i32 v255, v255, 0, s99
	v_mad_u32_u24 v80, v80, s100, v252
	v_mad_u32_u24 v83, v83, s100, v252
	v_mad_u32_u24 v99, v99, s100, v252
	v_mad_u32_u24 v253, v253, s100, v252
	v_mad_u32_u24 v254, v254, s100, v153
	v_mad_u32_u24 v255, v255, s100, v153
	global_load_dwordx4 v[116:119], v80, s[82:83]
	global_load_dwordx4 v[120:123], v83, s[82:83]
	global_load_dwordx4 v[124:127], v99, s[82:83]
	global_load_dwordx4 v[128:131], v253, s[82:83]
	global_load_dwordx4 v[132:135], v254, s[82:83] offset:768
	global_load_dwordx4 v[136:139], v255, s[82:83] offset:768
	global_load_dwordx4 v[140:143], v254, s[82:83] offset:832
	global_load_dwordx4 v[144:147], v255, s[82:83] offset:832
	ds_read_b64_tr_b16 v[72:73], v231
	ds_read_b64_tr_b16 v[74:75], v231 offset:512
	ds_read_b64_tr_b16 v[76:77], v231 offset:2048
	ds_read_b64_tr_b16 v[78:79], v231 offset:2560
	ds_read_b64_tr_b16 v[220:221], v231 offset:1024
	ds_read_b64_tr_b16 v[222:223], v231 offset:1536
	ds_read_b64_tr_b16 v[224:225], v231 offset:3072
	ds_read_b64_tr_b16 v[226:227], v231 offset:3584
	v_exp_f32_e32 v32, v32
	v_exp_f32_e32 v33, v33
	v_exp_f32_e32 v34, v34
	v_exp_f32_e32 v35, v35
	s_waitcnt vmcnt(12)
	ds_write_b128 v247, v[156:159]
	ds_write_b128 v247, v[160:163] offset:1024
	ds_write_b128 v247, v[164:167] offset:2048
	ds_write_b128 v247, v[168:171] offset:3072
	ds_read_b128 v[156:159], v248
	ds_read_b128 v[160:163], v249
	ds_read_b128 v[164:167], v250
	ds_read_b128 v[168:171], v251
	s_waitcnt vmcnt(8)
	ds_write_b128 v112, v[172:175]
	ds_write_b128 v112, v[176:179] offset:1024
	ds_write_b128 v112, v[180:183] offset:2048
	ds_write_b128 v112, v[184:187] offset:3072
	v_exp_f32_e32 v36, v36
	v_exp_f32_e32 v37, v37
	v_exp_f32_e32 v38, v38
	v_exp_f32_e32 v39, v39
	s_waitcnt lgkmcnt(4)
	v_mfma_f32_32x32x16_bf16 v[188:203], v[156:159], v[48:51], v[188:203]
	v_exp_f32_e32 v40, v40
	v_exp_f32_e32 v41, v41
	v_mfma_f32_32x32x16_bf16 v[188:203], v[160:163], v[52:55], v[188:203]
	v_exp_f32_e32 v42, v42
	v_exp_f32_e32 v43, v43
	v_mfma_f32_32x32x16_bf16 v[188:203], v[164:167], v[56:59], v[188:203]
	v_exp_f32_e32 v44, v44
	v_exp_f32_e32 v45, v45
	v_mfma_f32_32x32x16_bf16 v[188:203], v[168:171], v[60:63], v[188:203]
	v_exp_f32_e32 v46, v46
	v_exp_f32_e32 v47, v47
	s_add_i32 s90, s76, -64
	v_add_u32_e32 v84, s90, v107
	v_add_u32_e32 v85, 0, v84
	v_add_u32_e32 v86, 1, v84
	v_add_u32_e32 v87, 2, v84
	v_add_u32_e32 v88, 3, v84
	v_cmp_gt_u32_e64 s[30:31], s98, v85
	v_cmp_gt_u32_e64 s[36:37], s98, v86
	v_cmp_gt_u32_e64 s[78:79], s98, v87
	v_cmp_gt_u32_e64 s[50:51], s98, v88
	v_cndmask_b32_e64 v32, 0, v32, s[30:31]
	v_add_u32_e32 v85, 8, v84
	v_cmp_gt_u32_e64 s[30:31], s98, v85
	v_cndmask_b32_e64 v33, 0, v33, s[36:37]
	v_add_u32_e32 v86, 9, v84
	v_cmp_gt_u32_e64 s[36:37], s98, v86
	v_cndmask_b32_e64 v34, 0, v34, s[78:79]
	v_add_u32_e32 v87, 10, v84
	v_cmp_gt_u32_e64 s[78:79], s98, v87
	v_cndmask_b32_e64 v35, 0, v35, s[50:51]
	v_add_u32_e32 v88, 11, v84
	v_cmp_gt_u32_e64 s[50:51], s98, v88
	v_cndmask_b32_e64 v36, 0, v36, s[30:31]
	v_add_u32_e32 v85, 16, v84
	v_cmp_gt_u32_e64 s[30:31], s98, v85
	v_cndmask_b32_e64 v37, 0, v37, s[36:37]
	v_add_u32_e32 v86, 17, v84
	v_cmp_gt_u32_e64 s[36:37], s98, v86
	v_cndmask_b32_e64 v38, 0, v38, s[78:79]
	v_add_u32_e32 v87, 18, v84
	v_cmp_gt_u32_e64 s[78:79], s98, v87
	v_cndmask_b32_e64 v39, 0, v39, s[50:51]
	v_add_u32_e32 v88, 19, v84
	v_cmp_gt_u32_e64 s[50:51], s98, v88
	v_cndmask_b32_e64 v40, 0, v40, s[30:31]
	v_add_u32_e32 v85, 24, v84
	v_cmp_gt_u32_e64 s[30:31], s98, v85
	v_cndmask_b32_e64 v41, 0, v41, s[36:37]
	v_add_u32_e32 v86, 25, v84
	v_cmp_gt_u32_e64 s[36:37], s98, v86
	v_cndmask_b32_e64 v42, 0, v42, s[78:79]
	v_add_u32_e32 v87, 26, v84
	v_cmp_gt_u32_e64 s[78:79], s98, v87
	v_cndmask_b32_e64 v43, 0, v43, s[50:51]
	v_add_u32_e32 v88, 27, v84
	v_cmp_gt_u32_e64 s[50:51], s98, v88
	v_nop
	v_cndmask_b32_e64 v44, 0, v44, s[30:31]
	v_cndmask_b32_e64 v45, 0, v45, s[36:37]
	v_cndmask_b32_e64 v46, 0, v46, s[78:79]
	v_cndmask_b32_e64 v47, 0, v47, s[50:51]
	v_cvt_pk_bf16_f32 v64, v32, v33
	v_cvt_pk_bf16_f32 v65, v34, v35
	v_cvt_pk_bf16_f32 v66, v36, v37
	v_cvt_pk_bf16_f32 v67, v38, v39
	v_cvt_pk_bf16_f32 v68, v40, v41
	v_cvt_pk_bf16_f32 v69, v42, v43
	v_cvt_pk_bf16_f32 v70, v44, v45
	v_cvt_pk_bf16_f32 v71, v46, v47
	v_pk_add_f32 v[232:233], v[232:233], v[32:33]
	v_pk_add_f32 v[232:233], v[232:233], v[34:35]
	v_pk_add_f32 v[232:233], v[232:233], v[36:37]
	v_pk_add_f32 v[232:233], v[232:233], v[38:39]
	v_pk_add_f32 v[232:233], v[232:233], v[40:41]
	v_pk_add_f32 v[232:233], v[232:233], v[42:43]
	v_pk_add_f32 v[232:233], v[232:233], v[44:45]
	v_pk_add_f32 v[232:233], v[232:233], v[46:47]
	ds_read2_b32 v[32:33], v115 offset0:68 offset1:69
	ds_read2_b32 v[34:35], v115 offset0:70 offset1:71
	ds_read2_b32 v[36:37], v115 offset0:76 offset1:77
	ds_read2_b32 v[38:39], v115 offset0:78 offset1:79
	ds_read2_b32 v[40:41], v115 offset0:85 offset1:86
	ds_read2_b32 v[42:43], v115 offset0:87 offset1:88
	ds_read2_b32 v[44:45], v115 offset0:93 offset1:94
	ds_read2_b32 v[46:47], v115 offset0:95 offset1:96
	v_mfma_f32_32x32x16_bf16 v[0:15], v[64:67], v[72:75], v[0:15]
	v_mfma_f32_32x32x16_bf16 v[16:31], v[64:67], v[76:79], v[16:31]
	v_mfma_f32_32x32x16_bf16 v[0:15], v[68:71], v[220:223], v[0:15]
	v_mfma_f32_32x32x16_bf16 v[16:31], v[68:71], v[224:227], v[16:31]
	s_add_i32 s90, s76, 32
	v_add_u32_e32 v80, s90, v235
	v_add_u32_e32 v83, s90, v236
	v_add_u32_e32 v99, s90, v237
	v_add_u32_e32 v253, s90, v238
	v_add_u32_e32 v254, s90, v100
	v_add_u32_e32 v255, s90, v149
	v_med3_i32 v80, v80, 0, s99
	v_med3_i32 v83, v83, 0, s99
	v_med3_i32 v99, v99, 0, s99
	v_med3_i32 v253, v253, 0, s99
	v_med3_i32 v254, v254, 0, s99
	v_med3_i32 v255, v255, 0, s99
	v_mad_u32_u24 v80, v80, s100, v252
	v_mad_u32_u24 v83, v83, s100, v252
	v_mad_u32_u24 v99, v99, s100, v252
	v_mad_u32_u24 v253, v253, s100, v252
	v_mad_u32_u24 v254, v254, s100, v153
	v_mad_u32_u24 v255, v255, s100, v153
	global_load_dwordx4 v[156:159], v80, s[82:83]
	global_load_dwordx4 v[160:163], v83, s[82:83]
	global_load_dwordx4 v[164:167], v99, s[82:83]
	global_load_dwordx4 v[168:171], v253, s[82:83]
	global_load_dwordx4 v[172:175], v254, s[82:83] offset:768
	global_load_dwordx4 v[176:179], v255, s[82:83] offset:768
	global_load_dwordx4 v[180:183], v254, s[82:83] offset:832
	global_load_dwordx4 v[184:187], v255, s[82:83] offset:832
	ds_read_b64_tr_b16 v[72:73], v231
	ds_read_b64_tr_b16 v[74:75], v231 offset:512
	ds_read_b64_tr_b16 v[76:77], v231 offset:2048
	ds_read_b64_tr_b16 v[78:79], v231 offset:2560
	ds_read_b64_tr_b16 v[220:221], v231 offset:1024
	ds_read_b64_tr_b16 v[222:223], v231 offset:1536
	ds_read_b64_tr_b16 v[224:225], v231 offset:3072
	ds_read_b64_tr_b16 v[226:227], v231 offset:3584
	v_exp_f32_e32 v188, v188
	v_exp_f32_e32 v189, v189
	v_exp_f32_e32 v190, v190
	v_exp_f32_e32 v191, v191
	s_waitcnt vmcnt(12)
	ds_write_b128 v247, v[116:119]
	ds_write_b128 v247, v[120:123] offset:1024
	ds_write_b128 v247, v[124:127] offset:2048
	ds_write_b128 v247, v[128:131] offset:3072
	ds_read_b128 v[116:119], v248
	ds_read_b128 v[120:123], v249
	ds_read_b128 v[124:127], v250
	ds_read_b128 v[128:131], v251
	s_waitcnt vmcnt(8)
	ds_write_b128 v112, v[132:135]
	ds_write_b128 v112, v[136:139] offset:1024
	ds_write_b128 v112, v[140:143] offset:2048
	ds_write_b128 v112, v[144:147] offset:3072
	v_exp_f32_e32 v192, v192
	v_exp_f32_e32 v193, v193
	v_exp_f32_e32 v194, v194
	v_exp_f32_e32 v195, v195
	s_waitcnt lgkmcnt(4)
	v_mfma_f32_32x32x16_bf16 v[32:47], v[116:119], v[48:51], v[32:47]
	v_exp_f32_e32 v196, v196
	v_exp_f32_e32 v197, v197
	v_mfma_f32_32x32x16_bf16 v[32:47], v[120:123], v[52:55], v[32:47]
	v_exp_f32_e32 v198, v198
	v_exp_f32_e32 v199, v199
	v_mfma_f32_32x32x16_bf16 v[32:47], v[124:127], v[56:59], v[32:47]
	v_exp_f32_e32 v200, v200
	v_exp_f32_e32 v201, v201
	v_mfma_f32_32x32x16_bf16 v[32:47], v[128:131], v[60:63], v[32:47]
	v_exp_f32_e32 v202, v202
	v_exp_f32_e32 v203, v203
	s_add_i32 s90, s76, -32
	v_add_u32_e32 v84, s90, v107
	v_add_u32_e32 v85, 0, v84
	v_add_u32_e32 v86, 1, v84
	v_add_u32_e32 v87, 2, v84
	v_add_u32_e32 v88, 3, v84
	v_cmp_gt_u32_e64 s[30:31], s98, v85
	v_cmp_gt_u32_e64 s[36:37], s98, v86
	v_cmp_gt_u32_e64 s[78:79], s98, v87
	v_cmp_gt_u32_e64 s[50:51], s98, v88
	v_cndmask_b32_e64 v188, 0, v188, s[30:31]
	v_add_u32_e32 v85, 8, v84
	v_cmp_gt_u32_e64 s[30:31], s98, v85
	v_cndmask_b32_e64 v189, 0, v189, s[36:37]
	v_add_u32_e32 v86, 9, v84
	v_cmp_gt_u32_e64 s[36:37], s98, v86
	v_cndmask_b32_e64 v190, 0, v190, s[78:79]
	v_add_u32_e32 v87, 10, v84
	v_cmp_gt_u32_e64 s[78:79], s98, v87
	v_cndmask_b32_e64 v191, 0, v191, s[50:51]
	v_add_u32_e32 v88, 11, v84
	v_cmp_gt_u32_e64 s[50:51], s98, v88
	v_cndmask_b32_e64 v192, 0, v192, s[30:31]
	v_add_u32_e32 v85, 16, v84
	v_cmp_gt_u32_e64 s[30:31], s98, v85
	v_cndmask_b32_e64 v193, 0, v193, s[36:37]
	v_add_u32_e32 v86, 17, v84
	v_cmp_gt_u32_e64 s[36:37], s98, v86
	v_cndmask_b32_e64 v194, 0, v194, s[78:79]
	v_add_u32_e32 v87, 18, v84
	v_cmp_gt_u32_e64 s[78:79], s98, v87
	v_cndmask_b32_e64 v195, 0, v195, s[50:51]
	v_add_u32_e32 v88, 19, v84
	v_cmp_gt_u32_e64 s[50:51], s98, v88
	v_cndmask_b32_e64 v196, 0, v196, s[30:31]
	v_add_u32_e32 v85, 24, v84
	v_cmp_gt_u32_e64 s[30:31], s98, v85
	v_cndmask_b32_e64 v197, 0, v197, s[36:37]
	v_add_u32_e32 v86, 25, v84
	v_cmp_gt_u32_e64 s[36:37], s98, v86
	v_cndmask_b32_e64 v198, 0, v198, s[78:79]
	v_add_u32_e32 v87, 26, v84
	v_cmp_gt_u32_e64 s[78:79], s98, v87
	v_cndmask_b32_e64 v199, 0, v199, s[50:51]
	v_add_u32_e32 v88, 27, v84
	v_cmp_gt_u32_e64 s[50:51], s98, v88
	v_nop
	v_cndmask_b32_e64 v200, 0, v200, s[30:31]
	v_cndmask_b32_e64 v201, 0, v201, s[36:37]
	v_cndmask_b32_e64 v202, 0, v202, s[78:79]
	v_cndmask_b32_e64 v203, 0, v203, s[50:51]
	v_cvt_pk_bf16_f32 v64, v188, v189
	v_cvt_pk_bf16_f32 v65, v190, v191
	v_cvt_pk_bf16_f32 v66, v192, v193
	v_cvt_pk_bf16_f32 v67, v194, v195
	v_cvt_pk_bf16_f32 v68, v196, v197
	v_cvt_pk_bf16_f32 v69, v198, v199
	v_cvt_pk_bf16_f32 v70, v200, v201
	v_cvt_pk_bf16_f32 v71, v202, v203
	v_pk_add_f32 v[232:233], v[232:233], v[188:189]
	v_pk_add_f32 v[232:233], v[232:233], v[190:191]
	v_pk_add_f32 v[232:233], v[232:233], v[192:193]
	v_pk_add_f32 v[232:233], v[232:233], v[194:195]
	v_pk_add_f32 v[232:233], v[232:233], v[196:197]
	v_pk_add_f32 v[232:233], v[232:233], v[198:199]
	v_pk_add_f32 v[232:233], v[232:233], v[200:201]
	v_pk_add_f32 v[232:233], v[232:233], v[202:203]
	ds_read2_b32 v[188:189], v115 offset0:102 offset1:103
	ds_read2_b32 v[190:191], v115 offset0:104 offset1:105
	ds_read2_b32 v[192:193], v115 offset0:110 offset1:111
	ds_read2_b32 v[194:195], v115 offset0:112 offset1:113
	ds_read2_b32 v[196:197], v115 offset0:119 offset1:120
	ds_read2_b32 v[198:199], v115 offset0:121 offset1:122
	ds_read2_b32 v[200:201], v115 offset0:127 offset1:128
	ds_read2_b32 v[202:203], v115 offset0:129 offset1:130
	v_mfma_f32_32x32x16_bf16 v[0:15], v[64:67], v[72:75], v[0:15]
	v_mfma_f32_32x32x16_bf16 v[16:31], v[64:67], v[76:79], v[16:31]
	v_mfma_f32_32x32x16_bf16 v[0:15], v[68:71], v[220:223], v[0:15]
	v_mfma_f32_32x32x16_bf16 v[16:31], v[68:71], v[224:227], v[16:31]
	s_add_i32 s90, s76, 64
	v_add_u32_e32 v80, s90, v235
	v_add_u32_e32 v83, s90, v236
	v_add_u32_e32 v99, s90, v237
	v_add_u32_e32 v253, s90, v238
	v_add_u32_e32 v254, s90, v100
	v_add_u32_e32 v255, s90, v149
	v_med3_i32 v80, v80, 0, s99
	v_med3_i32 v83, v83, 0, s99
	v_med3_i32 v99, v99, 0, s99
	v_med3_i32 v253, v253, 0, s99
	v_med3_i32 v254, v254, 0, s99
	v_med3_i32 v255, v255, 0, s99
	v_mad_u32_u24 v80, v80, s100, v252
	v_mad_u32_u24 v83, v83, s100, v252
	v_mad_u32_u24 v99, v99, s100, v252
	v_mad_u32_u24 v253, v253, s100, v252
	v_mad_u32_u24 v254, v254, s100, v153
	v_mad_u32_u24 v255, v255, s100, v153
	global_load_dwordx4 v[116:119], v80, s[82:83]
	global_load_dwordx4 v[120:123], v83, s[82:83]
	global_load_dwordx4 v[124:127], v99, s[82:83]
	global_load_dwordx4 v[128:131], v253, s[82:83]
	global_load_dwordx4 v[132:135], v254, s[82:83] offset:768
	global_load_dwordx4 v[136:139], v255, s[82:83] offset:768
	global_load_dwordx4 v[140:143], v254, s[82:83] offset:832
	global_load_dwordx4 v[144:147], v255, s[82:83] offset:832
	ds_read_b64_tr_b16 v[72:73], v231
	ds_read_b64_tr_b16 v[74:75], v231 offset:512
	ds_read_b64_tr_b16 v[76:77], v231 offset:2048
	ds_read_b64_tr_b16 v[78:79], v231 offset:2560
	ds_read_b64_tr_b16 v[220:221], v231 offset:1024
	ds_read_b64_tr_b16 v[222:223], v231 offset:1536
	ds_read_b64_tr_b16 v[224:225], v231 offset:3072
	ds_read_b64_tr_b16 v[226:227], v231 offset:3584
	v_exp_f32_e32 v32, v32
	v_exp_f32_e32 v33, v33
	v_exp_f32_e32 v34, v34
	v_exp_f32_e32 v35, v35
	s_waitcnt vmcnt(12)
	ds_write_b128 v247, v[156:159]
	ds_write_b128 v247, v[160:163] offset:1024
	ds_write_b128 v247, v[164:167] offset:2048
	ds_write_b128 v247, v[168:171] offset:3072
	ds_read_b128 v[156:159], v248
	ds_read_b128 v[160:163], v249
	ds_read_b128 v[164:167], v250
	ds_read_b128 v[168:171], v251
	s_waitcnt vmcnt(8)
	ds_write_b128 v112, v[172:175]
	ds_write_b128 v112, v[176:179] offset:1024
	ds_write_b128 v112, v[180:183] offset:2048
	ds_write_b128 v112, v[184:187] offset:3072
	v_exp_f32_e32 v36, v36
	v_exp_f32_e32 v37, v37
	v_exp_f32_e32 v38, v38
	v_exp_f32_e32 v39, v39
	s_waitcnt lgkmcnt(4)
	v_mfma_f32_32x32x16_bf16 v[188:203], v[156:159], v[48:51], v[188:203]
	v_exp_f32_e32 v40, v40
	v_exp_f32_e32 v41, v41
	v_mfma_f32_32x32x16_bf16 v[188:203], v[160:163], v[52:55], v[188:203]
	v_exp_f32_e32 v42, v42
	v_exp_f32_e32 v43, v43
	v_mfma_f32_32x32x16_bf16 v[188:203], v[164:167], v[56:59], v[188:203]
	v_exp_f32_e32 v44, v44
	v_exp_f32_e32 v45, v45
	v_mfma_f32_32x32x16_bf16 v[188:203], v[168:171], v[60:63], v[188:203]
	v_exp_f32_e32 v46, v46
	v_exp_f32_e32 v47, v47
	s_add_i32 s90, s76, 0
	v_add_u32_e32 v84, s90, v107
	v_add_u32_e32 v85, 0, v84
	v_add_u32_e32 v86, 1, v84
	v_add_u32_e32 v87, 2, v84
	v_add_u32_e32 v88, 3, v84
	v_cmp_gt_u32_e64 s[30:31], s98, v85
	v_cmp_gt_u32_e64 s[36:37], s98, v86
	v_cmp_gt_u32_e64 s[78:79], s98, v87
	v_cmp_gt_u32_e64 s[50:51], s98, v88
	v_cndmask_b32_e64 v32, 0, v32, s[30:31]
	v_add_u32_e32 v85, 8, v84
	v_cmp_gt_u32_e64 s[30:31], s98, v85
	v_cndmask_b32_e64 v33, 0, v33, s[36:37]
	v_add_u32_e32 v86, 9, v84
	v_cmp_gt_u32_e64 s[36:37], s98, v86
	v_cndmask_b32_e64 v34, 0, v34, s[78:79]
	v_add_u32_e32 v87, 10, v84
	v_cmp_gt_u32_e64 s[78:79], s98, v87
	v_cndmask_b32_e64 v35, 0, v35, s[50:51]
	v_add_u32_e32 v88, 11, v84
	v_cmp_gt_u32_e64 s[50:51], s98, v88
	v_cndmask_b32_e64 v36, 0, v36, s[30:31]
	v_add_u32_e32 v85, 16, v84
	v_cmp_gt_u32_e64 s[30:31], s98, v85
	v_cndmask_b32_e64 v37, 0, v37, s[36:37]
	v_add_u32_e32 v86, 17, v84
	v_cmp_gt_u32_e64 s[36:37], s98, v86
	v_cndmask_b32_e64 v38, 0, v38, s[78:79]
	v_add_u32_e32 v87, 18, v84
	v_cmp_gt_u32_e64 s[78:79], s98, v87
	v_cndmask_b32_e64 v39, 0, v39, s[50:51]
	v_add_u32_e32 v88, 19, v84
	v_cmp_gt_u32_e64 s[50:51], s98, v88
	v_cndmask_b32_e64 v40, 0, v40, s[30:31]
	v_add_u32_e32 v85, 24, v84
	v_cmp_gt_u32_e64 s[30:31], s98, v85
	v_cndmask_b32_e64 v41, 0, v41, s[36:37]
	v_add_u32_e32 v86, 25, v84
	v_cmp_gt_u32_e64 s[36:37], s98, v86
	v_cndmask_b32_e64 v42, 0, v42, s[78:79]
	v_add_u32_e32 v87, 26, v84
	v_cmp_gt_u32_e64 s[78:79], s98, v87
	v_cndmask_b32_e64 v43, 0, v43, s[50:51]
	v_add_u32_e32 v88, 27, v84
	v_cmp_gt_u32_e64 s[50:51], s98, v88
	v_nop
	v_cndmask_b32_e64 v44, 0, v44, s[30:31]
	v_cndmask_b32_e64 v45, 0, v45, s[36:37]
	v_cndmask_b32_e64 v46, 0, v46, s[78:79]
	v_cndmask_b32_e64 v47, 0, v47, s[50:51]
	v_cvt_pk_bf16_f32 v64, v32, v33
	v_cvt_pk_bf16_f32 v65, v34, v35
	v_cvt_pk_bf16_f32 v66, v36, v37
	v_cvt_pk_bf16_f32 v67, v38, v39
	v_cvt_pk_bf16_f32 v68, v40, v41
	v_cvt_pk_bf16_f32 v69, v42, v43
	v_cvt_pk_bf16_f32 v70, v44, v45
	v_cvt_pk_bf16_f32 v71, v46, v47
	v_pk_add_f32 v[232:233], v[232:233], v[32:33]
	v_pk_add_f32 v[232:233], v[232:233], v[34:35]
	v_pk_add_f32 v[232:233], v[232:233], v[36:37]
	v_pk_add_f32 v[232:233], v[232:233], v[38:39]
	v_pk_add_f32 v[232:233], v[232:233], v[40:41]
	v_pk_add_f32 v[232:233], v[232:233], v[42:43]
	v_pk_add_f32 v[232:233], v[232:233], v[44:45]
	v_pk_add_f32 v[232:233], v[232:233], v[46:47]
	ds_read2_b32 v[32:33], v115 offset0:136 offset1:137
	ds_read2_b32 v[34:35], v115 offset0:138 offset1:139
	ds_read2_b32 v[36:37], v115 offset0:144 offset1:145
	ds_read2_b32 v[38:39], v115 offset0:146 offset1:147
	ds_read2_b32 v[40:41], v115 offset0:153 offset1:154
	ds_read2_b32 v[42:43], v115 offset0:155 offset1:156
	ds_read2_b32 v[44:45], v115 offset0:161 offset1:162
	ds_read2_b32 v[46:47], v115 offset0:163 offset1:164
	v_mfma_f32_32x32x16_bf16 v[0:15], v[64:67], v[72:75], v[0:15]
	v_mfma_f32_32x32x16_bf16 v[16:31], v[64:67], v[76:79], v[16:31]
	v_mfma_f32_32x32x16_bf16 v[0:15], v[68:71], v[220:223], v[0:15]
	v_mfma_f32_32x32x16_bf16 v[16:31], v[68:71], v[224:227], v[16:31]
	s_add_i32 s90, s76, 96
	v_add_u32_e32 v80, s90, v235
	v_add_u32_e32 v83, s90, v236
	v_add_u32_e32 v99, s90, v237
	v_add_u32_e32 v253, s90, v238
	v_add_u32_e32 v254, s90, v100
	v_add_u32_e32 v255, s90, v149
	v_med3_i32 v80, v80, 0, s99
	v_med3_i32 v83, v83, 0, s99
	v_med3_i32 v99, v99, 0, s99
	v_med3_i32 v253, v253, 0, s99
	v_med3_i32 v254, v254, 0, s99
	v_med3_i32 v255, v255, 0, s99
	v_mad_u32_u24 v80, v80, s100, v252
	v_mad_u32_u24 v83, v83, s100, v252
	v_mad_u32_u24 v99, v99, s100, v252
	v_mad_u32_u24 v253, v253, s100, v252
	v_mad_u32_u24 v254, v254, s100, v153
	v_mad_u32_u24 v255, v255, s100, v153
	global_load_dwordx4 v[156:159], v80, s[82:83]
	global_load_dwordx4 v[160:163], v83, s[82:83]
	global_load_dwordx4 v[164:167], v99, s[82:83]
	global_load_dwordx4 v[168:171], v253, s[82:83]
	global_load_dwordx4 v[172:175], v254, s[82:83] offset:768
	global_load_dwordx4 v[176:179], v255, s[82:83] offset:768
	global_load_dwordx4 v[180:183], v254, s[82:83] offset:832
	global_load_dwordx4 v[184:187], v255, s[82:83] offset:832
	ds_read_b64_tr_b16 v[72:73], v231
	ds_read_b64_tr_b16 v[74:75], v231 offset:512
	ds_read_b64_tr_b16 v[76:77], v231 offset:2048
	ds_read_b64_tr_b16 v[78:79], v231 offset:2560
	ds_read_b64_tr_b16 v[220:221], v231 offset:1024
	ds_read_b64_tr_b16 v[222:223], v231 offset:1536
	ds_read_b64_tr_b16 v[224:225], v231 offset:3072
	ds_read_b64_tr_b16 v[226:227], v231 offset:3584
	v_exp_f32_e32 v188, v188
	v_exp_f32_e32 v189, v189
	v_exp_f32_e32 v190, v190
	v_exp_f32_e32 v191, v191
	s_waitcnt vmcnt(12)
	ds_write_b128 v247, v[116:119]
	ds_write_b128 v247, v[120:123] offset:1024
	ds_write_b128 v247, v[124:127] offset:2048
	ds_write_b128 v247, v[128:131] offset:3072
	ds_read_b128 v[116:119], v248
	ds_read_b128 v[120:123], v249
	ds_read_b128 v[124:127], v250
	ds_read_b128 v[128:131], v251
	s_waitcnt vmcnt(8)
	ds_write_b128 v112, v[132:135]
	ds_write_b128 v112, v[136:139] offset:1024
	ds_write_b128 v112, v[140:143] offset:2048
	ds_write_b128 v112, v[144:147] offset:3072
	v_exp_f32_e32 v192, v192
	v_exp_f32_e32 v193, v193
	v_exp_f32_e32 v194, v194
	v_exp_f32_e32 v195, v195
	s_waitcnt lgkmcnt(4)
	v_mfma_f32_32x32x16_bf16 v[32:47], v[116:119], v[48:51], v[32:47]
	v_exp_f32_e32 v196, v196
	v_exp_f32_e32 v197, v197
	v_mfma_f32_32x32x16_bf16 v[32:47], v[120:123], v[52:55], v[32:47]
	v_exp_f32_e32 v198, v198
	v_exp_f32_e32 v199, v199
	v_mfma_f32_32x32x16_bf16 v[32:47], v[124:127], v[56:59], v[32:47]
	v_exp_f32_e32 v200, v200
	v_exp_f32_e32 v201, v201
	v_mfma_f32_32x32x16_bf16 v[32:47], v[128:131], v[60:63], v[32:47]
	v_exp_f32_e32 v202, v202
	v_exp_f32_e32 v203, v203
	s_add_i32 s90, s76, 32
	v_add_u32_e32 v84, s90, v107
	v_add_u32_e32 v85, 0, v84
	v_add_u32_e32 v86, 1, v84
	v_add_u32_e32 v87, 2, v84
	v_add_u32_e32 v88, 3, v84
	v_cmp_gt_u32_e64 s[30:31], s98, v85
	v_cmp_gt_u32_e64 s[36:37], s98, v86
	v_cmp_gt_u32_e64 s[78:79], s98, v87
	v_cmp_gt_u32_e64 s[50:51], s98, v88
	v_cndmask_b32_e64 v188, 0, v188, s[30:31]
	v_add_u32_e32 v85, 8, v84
	v_cmp_gt_u32_e64 s[30:31], s98, v85
	v_cndmask_b32_e64 v189, 0, v189, s[36:37]
	v_add_u32_e32 v86, 9, v84
	v_cmp_gt_u32_e64 s[36:37], s98, v86
	v_cndmask_b32_e64 v190, 0, v190, s[78:79]
	v_add_u32_e32 v87, 10, v84
	v_cmp_gt_u32_e64 s[78:79], s98, v87
	v_cndmask_b32_e64 v191, 0, v191, s[50:51]
	v_add_u32_e32 v88, 11, v84
	v_cmp_gt_u32_e64 s[50:51], s98, v88
	v_cndmask_b32_e64 v192, 0, v192, s[30:31]
	v_add_u32_e32 v85, 16, v84
	v_cmp_gt_u32_e64 s[30:31], s98, v85
	v_cndmask_b32_e64 v193, 0, v193, s[36:37]
	v_add_u32_e32 v86, 17, v84
	v_cmp_gt_u32_e64 s[36:37], s98, v86
	v_cndmask_b32_e64 v194, 0, v194, s[78:79]
	v_add_u32_e32 v87, 18, v84
	v_cmp_gt_u32_e64 s[78:79], s98, v87
	v_cndmask_b32_e64 v195, 0, v195, s[50:51]
	v_add_u32_e32 v88, 19, v84
	v_cmp_gt_u32_e64 s[50:51], s98, v88
	v_cndmask_b32_e64 v196, 0, v196, s[30:31]
	v_add_u32_e32 v85, 24, v84
	v_cmp_gt_u32_e64 s[30:31], s98, v85
	v_cndmask_b32_e64 v197, 0, v197, s[36:37]
	v_add_u32_e32 v86, 25, v84
	v_cmp_gt_u32_e64 s[36:37], s98, v86
	v_cndmask_b32_e64 v198, 0, v198, s[78:79]
	v_add_u32_e32 v87, 26, v84
	v_cmp_gt_u32_e64 s[78:79], s98, v87
	v_cndmask_b32_e64 v199, 0, v199, s[50:51]
	v_add_u32_e32 v88, 27, v84
	v_cmp_gt_u32_e64 s[50:51], s98, v88
	v_nop
	v_cndmask_b32_e64 v200, 0, v200, s[30:31]
	v_cndmask_b32_e64 v201, 0, v201, s[36:37]
	v_cndmask_b32_e64 v202, 0, v202, s[78:79]
	v_cndmask_b32_e64 v203, 0, v203, s[50:51]
	v_cvt_pk_bf16_f32 v64, v188, v189
	v_cvt_pk_bf16_f32 v65, v190, v191
	v_cvt_pk_bf16_f32 v66, v192, v193
	v_cvt_pk_bf16_f32 v67, v194, v195
	v_cvt_pk_bf16_f32 v68, v196, v197
	v_cvt_pk_bf16_f32 v69, v198, v199
	v_cvt_pk_bf16_f32 v70, v200, v201
	v_cvt_pk_bf16_f32 v71, v202, v203
	v_pk_add_f32 v[232:233], v[232:233], v[188:189]
	v_pk_add_f32 v[232:233], v[232:233], v[190:191]
	v_pk_add_f32 v[232:233], v[232:233], v[192:193]
	v_pk_add_f32 v[232:233], v[232:233], v[194:195]
	v_pk_add_f32 v[232:233], v[232:233], v[196:197]
	v_pk_add_f32 v[232:233], v[232:233], v[198:199]
	v_pk_add_f32 v[232:233], v[232:233], v[200:201]
	v_pk_add_f32 v[232:233], v[232:233], v[202:203]
	ds_read2_b32 v[188:189], v115 offset0:170 offset1:171
	ds_read2_b32 v[190:191], v115 offset0:172 offset1:173
	ds_read2_b32 v[192:193], v115 offset0:178 offset1:179
	ds_read2_b32 v[194:195], v115 offset0:180 offset1:181
	ds_read2_b32 v[196:197], v115 offset0:187 offset1:188
	ds_read2_b32 v[198:199], v115 offset0:189 offset1:190
	ds_read2_b32 v[200:201], v115 offset0:195 offset1:196
	ds_read2_b32 v[202:203], v115 offset0:197 offset1:198
	v_mfma_f32_32x32x16_bf16 v[0:15], v[64:67], v[72:75], v[0:15]
	v_mfma_f32_32x32x16_bf16 v[16:31], v[64:67], v[76:79], v[16:31]
	v_mfma_f32_32x32x16_bf16 v[0:15], v[68:71], v[220:223], v[0:15]
	v_mfma_f32_32x32x16_bf16 v[16:31], v[68:71], v[224:227], v[16:31]
	s_add_i32 s90, s76, 128
	v_add_u32_e32 v80, s90, v235
	v_add_u32_e32 v83, s90, v236
	v_add_u32_e32 v99, s90, v237
	v_add_u32_e32 v253, s90, v238
	v_add_u32_e32 v254, s90, v100
	v_add_u32_e32 v255, s90, v149
	v_med3_i32 v80, v80, 0, s99
	v_med3_i32 v83, v83, 0, s99
	v_med3_i32 v99, v99, 0, s99
	v_med3_i32 v253, v253, 0, s99
	v_med3_i32 v254, v254, 0, s99
	v_med3_i32 v255, v255, 0, s99
	v_mad_u32_u24 v80, v80, s100, v252
	v_mad_u32_u24 v83, v83, s100, v252
	v_mad_u32_u24 v99, v99, s100, v252
	v_mad_u32_u24 v253, v253, s100, v252
	v_mad_u32_u24 v254, v254, s100, v153
	v_mad_u32_u24 v255, v255, s100, v153
	global_load_dwordx4 v[116:119], v80, s[82:83]
	global_load_dwordx4 v[120:123], v83, s[82:83]
	global_load_dwordx4 v[124:127], v99, s[82:83]
	global_load_dwordx4 v[128:131], v253, s[82:83]
	global_load_dwordx4 v[132:135], v254, s[82:83] offset:768
	global_load_dwordx4 v[136:139], v255, s[82:83] offset:768
	global_load_dwordx4 v[140:143], v254, s[82:83] offset:832
	global_load_dwordx4 v[144:147], v255, s[82:83] offset:832
	ds_read_b64_tr_b16 v[72:73], v231
	ds_read_b64_tr_b16 v[74:75], v231 offset:512
	ds_read_b64_tr_b16 v[76:77], v231 offset:2048
	ds_read_b64_tr_b16 v[78:79], v231 offset:2560
	ds_read_b64_tr_b16 v[220:221], v231 offset:1024
	ds_read_b64_tr_b16 v[222:223], v231 offset:1536
	ds_read_b64_tr_b16 v[224:225], v231 offset:3072
	ds_read_b64_tr_b16 v[226:227], v231 offset:3584
	v_exp_f32_e32 v32, v32
	v_exp_f32_e32 v33, v33
	v_exp_f32_e32 v34, v34
	v_exp_f32_e32 v35, v35
	s_waitcnt vmcnt(12)
	ds_write_b128 v247, v[156:159]
	ds_write_b128 v247, v[160:163] offset:1024
	ds_write_b128 v247, v[164:167] offset:2048
	ds_write_b128 v247, v[168:171] offset:3072
	ds_read_b128 v[156:159], v248
	ds_read_b128 v[160:163], v249
	ds_read_b128 v[164:167], v250
	ds_read_b128 v[168:171], v251
	s_waitcnt vmcnt(8)
	ds_write_b128 v112, v[172:175]
	ds_write_b128 v112, v[176:179] offset:1024
	ds_write_b128 v112, v[180:183] offset:2048
	ds_write_b128 v112, v[184:187] offset:3072
	v_exp_f32_e32 v36, v36
	v_exp_f32_e32 v37, v37
	v_exp_f32_e32 v38, v38
	v_exp_f32_e32 v39, v39
	s_waitcnt lgkmcnt(4)
	v_mfma_f32_32x32x16_bf16 v[188:203], v[156:159], v[48:51], v[188:203]
	v_exp_f32_e32 v40, v40
	v_exp_f32_e32 v41, v41
	v_mfma_f32_32x32x16_bf16 v[188:203], v[160:163], v[52:55], v[188:203]
	v_exp_f32_e32 v42, v42
	v_exp_f32_e32 v43, v43
	v_mfma_f32_32x32x16_bf16 v[188:203], v[164:167], v[56:59], v[188:203]
	v_exp_f32_e32 v44, v44
	v_exp_f32_e32 v45, v45
	v_mfma_f32_32x32x16_bf16 v[188:203], v[168:171], v[60:63], v[188:203]
	v_exp_f32_e32 v46, v46
	v_exp_f32_e32 v47, v47
	s_add_i32 s90, s76, 64
	v_add_u32_e32 v84, s90, v107
	v_add_u32_e32 v85, 0, v84
	v_add_u32_e32 v86, 1, v84
	v_add_u32_e32 v87, 2, v84
	v_add_u32_e32 v88, 3, v84
	v_cmp_gt_u32_e64 s[30:31], s98, v85
	v_cmp_gt_u32_e64 s[36:37], s98, v86
	v_cmp_gt_u32_e64 s[78:79], s98, v87
	v_cmp_gt_u32_e64 s[50:51], s98, v88
	v_cndmask_b32_e64 v32, 0, v32, s[30:31]
	v_add_u32_e32 v85, 8, v84
	v_cmp_gt_u32_e64 s[30:31], s98, v85
	v_cndmask_b32_e64 v33, 0, v33, s[36:37]
	v_add_u32_e32 v86, 9, v84
	v_cmp_gt_u32_e64 s[36:37], s98, v86
	v_cndmask_b32_e64 v34, 0, v34, s[78:79]
	v_add_u32_e32 v87, 10, v84
	v_cmp_gt_u32_e64 s[78:79], s98, v87
	v_cndmask_b32_e64 v35, 0, v35, s[50:51]
	v_add_u32_e32 v88, 11, v84
	v_cmp_gt_u32_e64 s[50:51], s98, v88
	v_cndmask_b32_e64 v36, 0, v36, s[30:31]
	v_add_u32_e32 v85, 16, v84
	v_cmp_gt_u32_e64 s[30:31], s98, v85
	v_cndmask_b32_e64 v37, 0, v37, s[36:37]
	v_add_u32_e32 v86, 17, v84
	v_cmp_gt_u32_e64 s[36:37], s98, v86
	v_cndmask_b32_e64 v38, 0, v38, s[78:79]
	v_add_u32_e32 v87, 18, v84
	v_cmp_gt_u32_e64 s[78:79], s98, v87
	v_cndmask_b32_e64 v39, 0, v39, s[50:51]
	v_add_u32_e32 v88, 19, v84
	v_cmp_gt_u32_e64 s[50:51], s98, v88
	v_cndmask_b32_e64 v40, 0, v40, s[30:31]
	v_add_u32_e32 v85, 24, v84
	v_cmp_gt_u32_e64 s[30:31], s98, v85
	v_cndmask_b32_e64 v41, 0, v41, s[36:37]
	v_add_u32_e32 v86, 25, v84
	v_cmp_gt_u32_e64 s[36:37], s98, v86
	v_cndmask_b32_e64 v42, 0, v42, s[78:79]
	v_add_u32_e32 v87, 26, v84
	v_cmp_gt_u32_e64 s[78:79], s98, v87
	v_cndmask_b32_e64 v43, 0, v43, s[50:51]
	v_add_u32_e32 v88, 27, v84
	v_cmp_gt_u32_e64 s[50:51], s98, v88
	v_nop
	v_cndmask_b32_e64 v44, 0, v44, s[30:31]
	v_cndmask_b32_e64 v45, 0, v45, s[36:37]
	v_cndmask_b32_e64 v46, 0, v46, s[78:79]
	v_cndmask_b32_e64 v47, 0, v47, s[50:51]
	v_cvt_pk_bf16_f32 v64, v32, v33
	v_cvt_pk_bf16_f32 v65, v34, v35
	v_cvt_pk_bf16_f32 v66, v36, v37
	v_cvt_pk_bf16_f32 v67, v38, v39
	v_cvt_pk_bf16_f32 v68, v40, v41
	v_cvt_pk_bf16_f32 v69, v42, v43
	v_cvt_pk_bf16_f32 v70, v44, v45
	v_cvt_pk_bf16_f32 v71, v46, v47
	v_pk_add_f32 v[232:233], v[232:233], v[32:33]
	v_pk_add_f32 v[232:233], v[232:233], v[34:35]
	v_pk_add_f32 v[232:233], v[232:233], v[36:37]
	v_pk_add_f32 v[232:233], v[232:233], v[38:39]
	v_pk_add_f32 v[232:233], v[232:233], v[40:41]
	v_pk_add_f32 v[232:233], v[232:233], v[42:43]
	v_pk_add_f32 v[232:233], v[232:233], v[44:45]
	v_pk_add_f32 v[232:233], v[232:233], v[46:47]
	ds_read2_b32 v[32:33], v115 offset0:204 offset1:205
	ds_read2_b32 v[34:35], v115 offset0:206 offset1:207
	ds_read2_b32 v[36:37], v115 offset0:212 offset1:213
	ds_read2_b32 v[38:39], v115 offset0:214 offset1:215
	ds_read2_b32 v[40:41], v115 offset0:221 offset1:222
	ds_read2_b32 v[42:43], v115 offset0:223 offset1:224
	ds_read2_b32 v[44:45], v115 offset0:229 offset1:230
	ds_read2_b32 v[46:47], v115 offset0:231 offset1:232
	v_mfma_f32_32x32x16_bf16 v[0:15], v[64:67], v[72:75], v[0:15]
	v_mfma_f32_32x32x16_bf16 v[16:31], v[64:67], v[76:79], v[16:31]
	v_mfma_f32_32x32x16_bf16 v[0:15], v[68:71], v[220:223], v[0:15]
	v_mfma_f32_32x32x16_bf16 v[16:31], v[68:71], v[224:227], v[16:31]
	s_add_i32 s90, s76, 160
	v_add_u32_e32 v80, s90, v235
	v_add_u32_e32 v83, s90, v236
	v_add_u32_e32 v99, s90, v237
	v_add_u32_e32 v253, s90, v238
	v_add_u32_e32 v254, s90, v100
	v_add_u32_e32 v255, s90, v149
	v_med3_i32 v80, v80, 0, s99
	v_med3_i32 v83, v83, 0, s99
	v_med3_i32 v99, v99, 0, s99
	v_med3_i32 v253, v253, 0, s99
	v_med3_i32 v254, v254, 0, s99
	v_med3_i32 v255, v255, 0, s99
	v_mad_u32_u24 v80, v80, s100, v252
	v_mad_u32_u24 v83, v83, s100, v252
	v_mad_u32_u24 v99, v99, s100, v252
	v_mad_u32_u24 v253, v253, s100, v252
	v_mad_u32_u24 v254, v254, s100, v153
	v_mad_u32_u24 v255, v255, s100, v153
	global_load_dwordx4 v[156:159], v80, s[82:83]
	global_load_dwordx4 v[160:163], v83, s[82:83]
	global_load_dwordx4 v[164:167], v99, s[82:83]
	global_load_dwordx4 v[168:171], v253, s[82:83]
	global_load_dwordx4 v[172:175], v254, s[82:83] offset:768
	global_load_dwordx4 v[176:179], v255, s[82:83] offset:768
	global_load_dwordx4 v[180:183], v254, s[82:83] offset:832
	global_load_dwordx4 v[184:187], v255, s[82:83] offset:832
	ds_read_b64_tr_b16 v[72:73], v231
	ds_read_b64_tr_b16 v[74:75], v231 offset:512
	ds_read_b64_tr_b16 v[76:77], v231 offset:2048
	ds_read_b64_tr_b16 v[78:79], v231 offset:2560
	ds_read_b64_tr_b16 v[220:221], v231 offset:1024
	ds_read_b64_tr_b16 v[222:223], v231 offset:1536
	ds_read_b64_tr_b16 v[224:225], v231 offset:3072
	ds_read_b64_tr_b16 v[226:227], v231 offset:3584
	v_exp_f32_e32 v188, v188
	v_exp_f32_e32 v189, v189
	v_exp_f32_e32 v190, v190
	v_exp_f32_e32 v191, v191
	s_waitcnt vmcnt(12)
	ds_write_b128 v247, v[116:119]
	ds_write_b128 v247, v[120:123] offset:1024
	ds_write_b128 v247, v[124:127] offset:2048
	ds_write_b128 v247, v[128:131] offset:3072
	ds_read_b128 v[116:119], v248
	ds_read_b128 v[120:123], v249
	ds_read_b128 v[124:127], v250
	ds_read_b128 v[128:131], v251
	s_waitcnt vmcnt(8)
	ds_write_b128 v112, v[132:135]
	ds_write_b128 v112, v[136:139] offset:1024
	ds_write_b128 v112, v[140:143] offset:2048
	ds_write_b128 v112, v[144:147] offset:3072
	v_exp_f32_e32 v192, v192
	v_exp_f32_e32 v193, v193
	v_exp_f32_e32 v194, v194
	v_exp_f32_e32 v195, v195
	s_waitcnt lgkmcnt(4)
	v_mfma_f32_32x32x16_bf16 v[32:47], v[116:119], v[48:51], v[32:47]
	v_exp_f32_e32 v196, v196
	v_exp_f32_e32 v197, v197
	v_mfma_f32_32x32x16_bf16 v[32:47], v[120:123], v[52:55], v[32:47]
	v_exp_f32_e32 v198, v198
	v_exp_f32_e32 v199, v199
	v_mfma_f32_32x32x16_bf16 v[32:47], v[124:127], v[56:59], v[32:47]
	v_exp_f32_e32 v200, v200
	v_exp_f32_e32 v201, v201
	v_mfma_f32_32x32x16_bf16 v[32:47], v[128:131], v[60:63], v[32:47]
	v_exp_f32_e32 v202, v202
	v_exp_f32_e32 v203, v203
	s_add_i32 s90, s76, 96
	v_add_u32_e32 v84, s90, v107
	v_add_u32_e32 v85, 0, v84
	v_add_u32_e32 v86, 1, v84
	v_add_u32_e32 v87, 2, v84
	v_add_u32_e32 v88, 3, v84
	v_cmp_gt_u32_e64 s[30:31], s98, v85
	v_cmp_gt_u32_e64 s[36:37], s98, v86
	v_cmp_gt_u32_e64 s[78:79], s98, v87
	v_cmp_gt_u32_e64 s[50:51], s98, v88
	v_cndmask_b32_e64 v188, 0, v188, s[30:31]
	v_add_u32_e32 v85, 8, v84
	v_cmp_gt_u32_e64 s[30:31], s98, v85
	v_cndmask_b32_e64 v189, 0, v189, s[36:37]
	v_add_u32_e32 v86, 9, v84
	v_cmp_gt_u32_e64 s[36:37], s98, v86
	v_cndmask_b32_e64 v190, 0, v190, s[78:79]
	v_add_u32_e32 v87, 10, v84
	v_cmp_gt_u32_e64 s[78:79], s98, v87
	v_cndmask_b32_e64 v191, 0, v191, s[50:51]
	v_add_u32_e32 v88, 11, v84
	v_cmp_gt_u32_e64 s[50:51], s98, v88
	v_cndmask_b32_e64 v192, 0, v192, s[30:31]
	v_add_u32_e32 v85, 16, v84
	v_cmp_gt_u32_e64 s[30:31], s98, v85
	v_cndmask_b32_e64 v193, 0, v193, s[36:37]
	v_add_u32_e32 v86, 17, v84
	v_cmp_gt_u32_e64 s[36:37], s98, v86
	v_cndmask_b32_e64 v194, 0, v194, s[78:79]
	v_add_u32_e32 v87, 18, v84
	v_cmp_gt_u32_e64 s[78:79], s98, v87
	v_cndmask_b32_e64 v195, 0, v195, s[50:51]
	v_add_u32_e32 v88, 19, v84
	v_cmp_gt_u32_e64 s[50:51], s98, v88
	v_cndmask_b32_e64 v196, 0, v196, s[30:31]
	v_add_u32_e32 v85, 24, v84
	v_cmp_gt_u32_e64 s[30:31], s98, v85
	v_cndmask_b32_e64 v197, 0, v197, s[36:37]
	v_add_u32_e32 v86, 25, v84
	v_cmp_gt_u32_e64 s[36:37], s98, v86
	v_cndmask_b32_e64 v198, 0, v198, s[78:79]
	v_add_u32_e32 v87, 26, v84
	v_cmp_gt_u32_e64 s[78:79], s98, v87
	v_cndmask_b32_e64 v199, 0, v199, s[50:51]
	v_add_u32_e32 v88, 27, v84
	v_cmp_gt_u32_e64 s[50:51], s98, v88
	v_nop
	v_cndmask_b32_e64 v200, 0, v200, s[30:31]
	v_cndmask_b32_e64 v201, 0, v201, s[36:37]
	v_cndmask_b32_e64 v202, 0, v202, s[78:79]
	v_cndmask_b32_e64 v203, 0, v203, s[50:51]
	v_cvt_pk_bf16_f32 v64, v188, v189
	v_cvt_pk_bf16_f32 v65, v190, v191
	v_cvt_pk_bf16_f32 v66, v192, v193
	v_cvt_pk_bf16_f32 v67, v194, v195
	v_cvt_pk_bf16_f32 v68, v196, v197
	v_cvt_pk_bf16_f32 v69, v198, v199
	v_cvt_pk_bf16_f32 v70, v200, v201
	v_cvt_pk_bf16_f32 v71, v202, v203
	v_pk_add_f32 v[232:233], v[232:233], v[188:189]
	v_pk_add_f32 v[232:233], v[232:233], v[190:191]
	v_pk_add_f32 v[232:233], v[232:233], v[192:193]
	v_pk_add_f32 v[232:233], v[232:233], v[194:195]
	v_pk_add_f32 v[232:233], v[232:233], v[196:197]
	v_pk_add_f32 v[232:233], v[232:233], v[198:199]
	v_pk_add_f32 v[232:233], v[232:233], v[200:201]
	v_pk_add_f32 v[232:233], v[232:233], v[202:203]
	v_add_u32_e32 v115, 952, v115
	ds_read2_b32 v[188:189], v115 offset0:0 offset1:1
	ds_read2_b32 v[190:191], v115 offset0:2 offset1:3
	ds_read2_b32 v[192:193], v115 offset0:8 offset1:9
	ds_read2_b32 v[194:195], v115 offset0:10 offset1:11
	ds_read2_b32 v[196:197], v115 offset0:17 offset1:18
	ds_read2_b32 v[198:199], v115 offset0:19 offset1:20
	ds_read2_b32 v[200:201], v115 offset0:25 offset1:26
	ds_read2_b32 v[202:203], v115 offset0:27 offset1:28
	v_mfma_f32_32x32x16_bf16 v[0:15], v[64:67], v[72:75], v[0:15]
	v_mfma_f32_32x32x16_bf16 v[16:31], v[64:67], v[76:79], v[16:31]
	v_mfma_f32_32x32x16_bf16 v[0:15], v[68:71], v[220:223], v[0:15]
	v_mfma_f32_32x32x16_bf16 v[16:31], v[68:71], v[224:227], v[16:31]
	s_add_i32 s90, s76, 192
	v_add_u32_e32 v80, s90, v235
	v_add_u32_e32 v83, s90, v236
	v_add_u32_e32 v99, s90, v237
	v_add_u32_e32 v253, s90, v238
	v_add_u32_e32 v254, s90, v100
	v_add_u32_e32 v255, s90, v149
	v_med3_i32 v80, v80, 0, s99
	v_med3_i32 v83, v83, 0, s99
	v_med3_i32 v99, v99, 0, s99
	v_med3_i32 v253, v253, 0, s99
	v_med3_i32 v254, v254, 0, s99
	v_med3_i32 v255, v255, 0, s99
	v_mad_u32_u24 v80, v80, s100, v252
	v_mad_u32_u24 v83, v83, s100, v252
	v_mad_u32_u24 v99, v99, s100, v252
	v_mad_u32_u24 v253, v253, s100, v252
	v_mad_u32_u24 v254, v254, s100, v153
	v_mad_u32_u24 v255, v255, s100, v153
	global_load_dwordx4 v[116:119], v80, s[82:83]
	global_load_dwordx4 v[120:123], v83, s[82:83]
	global_load_dwordx4 v[124:127], v99, s[82:83]
	global_load_dwordx4 v[128:131], v253, s[82:83]
	global_load_dwordx4 v[132:135], v254, s[82:83] offset:768
	global_load_dwordx4 v[136:139], v255, s[82:83] offset:768
	global_load_dwordx4 v[140:143], v254, s[82:83] offset:832
	global_load_dwordx4 v[144:147], v255, s[82:83] offset:832
	ds_read_b64_tr_b16 v[72:73], v231
	ds_read_b64_tr_b16 v[74:75], v231 offset:512
	ds_read_b64_tr_b16 v[76:77], v231 offset:2048
	ds_read_b64_tr_b16 v[78:79], v231 offset:2560
	ds_read_b64_tr_b16 v[220:221], v231 offset:1024
	ds_read_b64_tr_b16 v[222:223], v231 offset:1536
	ds_read_b64_tr_b16 v[224:225], v231 offset:3072
	ds_read_b64_tr_b16 v[226:227], v231 offset:3584
	v_exp_f32_e32 v32, v32
	v_exp_f32_e32 v33, v33
	v_exp_f32_e32 v34, v34
	v_exp_f32_e32 v35, v35
	s_waitcnt vmcnt(12)
	ds_write_b128 v247, v[156:159]
	ds_write_b128 v247, v[160:163] offset:1024
	ds_write_b128 v247, v[164:167] offset:2048
	ds_write_b128 v247, v[168:171] offset:3072
	ds_read_b128 v[156:159], v248
	ds_read_b128 v[160:163], v249
	ds_read_b128 v[164:167], v250
	ds_read_b128 v[168:171], v251
	s_waitcnt vmcnt(8)
	ds_write_b128 v112, v[172:175]
	ds_write_b128 v112, v[176:179] offset:1024
	ds_write_b128 v112, v[180:183] offset:2048
	ds_write_b128 v112, v[184:187] offset:3072
	v_exp_f32_e32 v36, v36
	v_exp_f32_e32 v37, v37
	v_exp_f32_e32 v38, v38
	v_exp_f32_e32 v39, v39
	s_waitcnt lgkmcnt(4)
	v_mfma_f32_32x32x16_bf16 v[188:203], v[156:159], v[48:51], v[188:203]
	v_exp_f32_e32 v40, v40
	v_exp_f32_e32 v41, v41
	v_mfma_f32_32x32x16_bf16 v[188:203], v[160:163], v[52:55], v[188:203]
	v_exp_f32_e32 v42, v42
	v_exp_f32_e32 v43, v43
	v_mfma_f32_32x32x16_bf16 v[188:203], v[164:167], v[56:59], v[188:203]
	v_exp_f32_e32 v44, v44
	v_exp_f32_e32 v45, v45
	v_mfma_f32_32x32x16_bf16 v[188:203], v[168:171], v[60:63], v[188:203]
	v_exp_f32_e32 v46, v46
	v_exp_f32_e32 v47, v47
	s_add_i32 s90, s76, 128
	v_add_u32_e32 v84, s90, v107
	v_add_u32_e32 v85, 0, v84
	v_add_u32_e32 v86, 1, v84
	v_add_u32_e32 v87, 2, v84
	v_add_u32_e32 v88, 3, v84
	v_cmp_gt_u32_e64 s[30:31], s98, v85
	v_cmp_gt_u32_e64 s[36:37], s98, v86
	v_cmp_gt_u32_e64 s[78:79], s98, v87
	v_cmp_gt_u32_e64 s[50:51], s98, v88
	v_cndmask_b32_e64 v32, 0, v32, s[30:31]
	v_add_u32_e32 v85, 8, v84
	v_cmp_gt_u32_e64 s[30:31], s98, v85
	v_cndmask_b32_e64 v33, 0, v33, s[36:37]
	v_add_u32_e32 v86, 9, v84
	v_cmp_gt_u32_e64 s[36:37], s98, v86
	v_cndmask_b32_e64 v34, 0, v34, s[78:79]
	v_add_u32_e32 v87, 10, v84
	v_cmp_gt_u32_e64 s[78:79], s98, v87
	v_cndmask_b32_e64 v35, 0, v35, s[50:51]
	v_add_u32_e32 v88, 11, v84
	v_cmp_gt_u32_e64 s[50:51], s98, v88
	v_cndmask_b32_e64 v36, 0, v36, s[30:31]
	v_add_u32_e32 v85, 16, v84
	v_cmp_gt_u32_e64 s[30:31], s98, v85
	v_cndmask_b32_e64 v37, 0, v37, s[36:37]
	v_add_u32_e32 v86, 17, v84
	v_cmp_gt_u32_e64 s[36:37], s98, v86
	v_cndmask_b32_e64 v38, 0, v38, s[78:79]
	v_add_u32_e32 v87, 18, v84
	v_cmp_gt_u32_e64 s[78:79], s98, v87
	v_cndmask_b32_e64 v39, 0, v39, s[50:51]
	v_add_u32_e32 v88, 19, v84
	v_cmp_gt_u32_e64 s[50:51], s98, v88
	v_cndmask_b32_e64 v40, 0, v40, s[30:31]
	v_add_u32_e32 v85, 24, v84
	v_cmp_gt_u32_e64 s[30:31], s98, v85
	v_cndmask_b32_e64 v41, 0, v41, s[36:37]
	v_add_u32_e32 v86, 25, v84
	v_cmp_gt_u32_e64 s[36:37], s98, v86
	v_cndmask_b32_e64 v42, 0, v42, s[78:79]
	v_add_u32_e32 v87, 26, v84
	v_cmp_gt_u32_e64 s[78:79], s98, v87
	v_cndmask_b32_e64 v43, 0, v43, s[50:51]
	v_add_u32_e32 v88, 27, v84
	v_cmp_gt_u32_e64 s[50:51], s98, v88
	v_nop
	v_cndmask_b32_e64 v44, 0, v44, s[30:31]
	v_cndmask_b32_e64 v45, 0, v45, s[36:37]
	v_cndmask_b32_e64 v46, 0, v46, s[78:79]
	v_cndmask_b32_e64 v47, 0, v47, s[50:51]
	v_cvt_pk_bf16_f32 v64, v32, v33
	v_cvt_pk_bf16_f32 v65, v34, v35
	v_cvt_pk_bf16_f32 v66, v36, v37
	v_cvt_pk_bf16_f32 v67, v38, v39
	v_cvt_pk_bf16_f32 v68, v40, v41
	v_cvt_pk_bf16_f32 v69, v42, v43
	v_cvt_pk_bf16_f32 v70, v44, v45
	v_cvt_pk_bf16_f32 v71, v46, v47
	v_pk_add_f32 v[232:233], v[232:233], v[32:33]
	v_pk_add_f32 v[232:233], v[232:233], v[34:35]
	v_pk_add_f32 v[232:233], v[232:233], v[36:37]
	v_pk_add_f32 v[232:233], v[232:233], v[38:39]
	v_pk_add_f32 v[232:233], v[232:233], v[40:41]
	v_pk_add_f32 v[232:233], v[232:233], v[42:43]
	v_pk_add_f32 v[232:233], v[232:233], v[44:45]
	v_pk_add_f32 v[232:233], v[232:233], v[46:47]
	ds_read2_b32 v[32:33], v115 offset0:34 offset1:35
	ds_read2_b32 v[34:35], v115 offset0:36 offset1:37
	ds_read2_b32 v[36:37], v115 offset0:42 offset1:43
	ds_read2_b32 v[38:39], v115 offset0:44 offset1:45
	ds_read2_b32 v[40:41], v115 offset0:51 offset1:52
	ds_read2_b32 v[42:43], v115 offset0:53 offset1:54
	ds_read2_b32 v[44:45], v115 offset0:59 offset1:60
	ds_read2_b32 v[46:47], v115 offset0:61 offset1:62
	v_mfma_f32_32x32x16_bf16 v[0:15], v[64:67], v[72:75], v[0:15]
	v_mfma_f32_32x32x16_bf16 v[16:31], v[64:67], v[76:79], v[16:31]
	v_mfma_f32_32x32x16_bf16 v[0:15], v[68:71], v[220:223], v[0:15]
	v_mfma_f32_32x32x16_bf16 v[16:31], v[68:71], v[224:227], v[16:31]
	s_add_i32 s90, s76, 224
	v_add_u32_e32 v80, s90, v235
	v_add_u32_e32 v83, s90, v236
	v_add_u32_e32 v99, s90, v237
	v_add_u32_e32 v253, s90, v238
	v_add_u32_e32 v254, s90, v100
	v_add_u32_e32 v255, s90, v149
	v_med3_i32 v80, v80, 0, s99
	v_med3_i32 v83, v83, 0, s99
	v_med3_i32 v99, v99, 0, s99
	v_med3_i32 v253, v253, 0, s99
	v_med3_i32 v254, v254, 0, s99
	v_med3_i32 v255, v255, 0, s99
	v_mad_u32_u24 v80, v80, s100, v252
	v_mad_u32_u24 v83, v83, s100, v252
	v_mad_u32_u24 v99, v99, s100, v252
	v_mad_u32_u24 v253, v253, s100, v252
	v_mad_u32_u24 v254, v254, s100, v153
	v_mad_u32_u24 v255, v255, s100, v153
	global_load_dwordx4 v[156:159], v80, s[82:83]
	global_load_dwordx4 v[160:163], v83, s[82:83]
	global_load_dwordx4 v[164:167], v99, s[82:83]
	global_load_dwordx4 v[168:171], v253, s[82:83]
	global_load_dwordx4 v[172:175], v254, s[82:83] offset:768
	global_load_dwordx4 v[176:179], v255, s[82:83] offset:768
	global_load_dwordx4 v[180:183], v254, s[82:83] offset:832
	global_load_dwordx4 v[184:187], v255, s[82:83] offset:832
	ds_read_b64_tr_b16 v[72:73], v231
	ds_read_b64_tr_b16 v[74:75], v231 offset:512
	ds_read_b64_tr_b16 v[76:77], v231 offset:2048
	ds_read_b64_tr_b16 v[78:79], v231 offset:2560
	ds_read_b64_tr_b16 v[220:221], v231 offset:1024
	ds_read_b64_tr_b16 v[222:223], v231 offset:1536
	ds_read_b64_tr_b16 v[224:225], v231 offset:3072
	ds_read_b64_tr_b16 v[226:227], v231 offset:3584
	v_exp_f32_e32 v188, v188
	v_exp_f32_e32 v189, v189
	v_exp_f32_e32 v190, v190
	v_exp_f32_e32 v191, v191
	s_waitcnt vmcnt(12)
	ds_write_b128 v247, v[116:119]
	ds_write_b128 v247, v[120:123] offset:1024
	ds_write_b128 v247, v[124:127] offset:2048
	ds_write_b128 v247, v[128:131] offset:3072
	ds_read_b128 v[116:119], v248
	ds_read_b128 v[120:123], v249
	ds_read_b128 v[124:127], v250
	ds_read_b128 v[128:131], v251
	s_waitcnt vmcnt(8)
	ds_write_b128 v112, v[132:135]
	ds_write_b128 v112, v[136:139] offset:1024
	ds_write_b128 v112, v[140:143] offset:2048
	ds_write_b128 v112, v[144:147] offset:3072
	v_exp_f32_e32 v192, v192
	v_exp_f32_e32 v193, v193
	v_exp_f32_e32 v194, v194
	v_exp_f32_e32 v195, v195
	s_waitcnt lgkmcnt(4)
	v_mfma_f32_32x32x16_bf16 v[32:47], v[116:119], v[48:51], v[32:47]
	v_exp_f32_e32 v196, v196
	v_exp_f32_e32 v197, v197
	v_mfma_f32_32x32x16_bf16 v[32:47], v[120:123], v[52:55], v[32:47]
	v_exp_f32_e32 v198, v198
	v_exp_f32_e32 v199, v199
	v_mfma_f32_32x32x16_bf16 v[32:47], v[124:127], v[56:59], v[32:47]
	v_exp_f32_e32 v200, v200
	v_exp_f32_e32 v201, v201
	v_mfma_f32_32x32x16_bf16 v[32:47], v[128:131], v[60:63], v[32:47]
	v_exp_f32_e32 v202, v202
	v_exp_f32_e32 v203, v203
	s_add_i32 s90, s76, 160
	v_add_u32_e32 v84, s90, v107
	v_add_u32_e32 v85, 0, v84
	v_add_u32_e32 v86, 1, v84
	v_add_u32_e32 v87, 2, v84
	v_add_u32_e32 v88, 3, v84
	v_cmp_gt_u32_e64 s[30:31], s98, v85
	v_cmp_gt_u32_e64 s[36:37], s98, v86
	v_cmp_gt_u32_e64 s[78:79], s98, v87
	v_cmp_gt_u32_e64 s[50:51], s98, v88
	v_cndmask_b32_e64 v188, 0, v188, s[30:31]
	v_add_u32_e32 v85, 8, v84
	v_cmp_gt_u32_e64 s[30:31], s98, v85
	v_cndmask_b32_e64 v189, 0, v189, s[36:37]
	v_add_u32_e32 v86, 9, v84
	v_cmp_gt_u32_e64 s[36:37], s98, v86
	v_cndmask_b32_e64 v190, 0, v190, s[78:79]
	v_add_u32_e32 v87, 10, v84
	v_cmp_gt_u32_e64 s[78:79], s98, v87
	v_cndmask_b32_e64 v191, 0, v191, s[50:51]
	v_add_u32_e32 v88, 11, v84
	v_cmp_gt_u32_e64 s[50:51], s98, v88
	v_cndmask_b32_e64 v192, 0, v192, s[30:31]
	v_add_u32_e32 v85, 16, v84
	v_cmp_gt_u32_e64 s[30:31], s98, v85
	v_cndmask_b32_e64 v193, 0, v193, s[36:37]
	v_add_u32_e32 v86, 17, v84
	v_cmp_gt_u32_e64 s[36:37], s98, v86
	v_cndmask_b32_e64 v194, 0, v194, s[78:79]
	v_add_u32_e32 v87, 18, v84
	v_cmp_gt_u32_e64 s[78:79], s98, v87
	v_cndmask_b32_e64 v195, 0, v195, s[50:51]
	v_add_u32_e32 v88, 19, v84
	v_cmp_gt_u32_e64 s[50:51], s98, v88
	v_cndmask_b32_e64 v196, 0, v196, s[30:31]
	v_add_u32_e32 v85, 24, v84
	v_cmp_gt_u32_e64 s[30:31], s98, v85
	v_cndmask_b32_e64 v197, 0, v197, s[36:37]
	v_add_u32_e32 v86, 25, v84
	v_cmp_gt_u32_e64 s[36:37], s98, v86
	v_cndmask_b32_e64 v198, 0, v198, s[78:79]
	v_add_u32_e32 v87, 26, v84
	v_cmp_gt_u32_e64 s[78:79], s98, v87
	v_cndmask_b32_e64 v199, 0, v199, s[50:51]
	v_add_u32_e32 v88, 27, v84
	v_cmp_gt_u32_e64 s[50:51], s98, v88
	v_nop
	v_cndmask_b32_e64 v200, 0, v200, s[30:31]
	v_cndmask_b32_e64 v201, 0, v201, s[36:37]
	v_cndmask_b32_e64 v202, 0, v202, s[78:79]
	v_cndmask_b32_e64 v203, 0, v203, s[50:51]
	v_cvt_pk_bf16_f32 v64, v188, v189
	v_cvt_pk_bf16_f32 v65, v190, v191
	v_cvt_pk_bf16_f32 v66, v192, v193
	v_cvt_pk_bf16_f32 v67, v194, v195
	v_cvt_pk_bf16_f32 v68, v196, v197
	v_cvt_pk_bf16_f32 v69, v198, v199
	v_cvt_pk_bf16_f32 v70, v200, v201
	v_cvt_pk_bf16_f32 v71, v202, v203
	v_pk_add_f32 v[232:233], v[232:233], v[188:189]
	v_pk_add_f32 v[232:233], v[232:233], v[190:191]
	v_pk_add_f32 v[232:233], v[232:233], v[192:193]
	v_pk_add_f32 v[232:233], v[232:233], v[194:195]
	v_pk_add_f32 v[232:233], v[232:233], v[196:197]
	v_pk_add_f32 v[232:233], v[232:233], v[198:199]
	v_pk_add_f32 v[232:233], v[232:233], v[200:201]
	v_pk_add_f32 v[232:233], v[232:233], v[202:203]
	ds_read2_b32 v[188:189], v115 offset0:68 offset1:69
	ds_read2_b32 v[190:191], v115 offset0:70 offset1:71
	ds_read2_b32 v[192:193], v115 offset0:76 offset1:77
	ds_read2_b32 v[194:195], v115 offset0:78 offset1:79
	ds_read2_b32 v[196:197], v115 offset0:85 offset1:86
	ds_read2_b32 v[198:199], v115 offset0:87 offset1:88
	ds_read2_b32 v[200:201], v115 offset0:93 offset1:94
	ds_read2_b32 v[202:203], v115 offset0:95 offset1:96
	v_mfma_f32_32x32x16_bf16 v[0:15], v[64:67], v[72:75], v[0:15]
	v_mfma_f32_32x32x16_bf16 v[16:31], v[64:67], v[76:79], v[16:31]
	v_mfma_f32_32x32x16_bf16 v[0:15], v[68:71], v[220:223], v[0:15]
	v_mfma_f32_32x32x16_bf16 v[16:31], v[68:71], v[224:227], v[16:31]
	s_add_i32 s90, s76, 256
	v_add_u32_e32 v80, s90, v235
	v_add_u32_e32 v83, s90, v236
	v_add_u32_e32 v99, s90, v237
	v_add_u32_e32 v253, s90, v238
	v_add_u32_e32 v254, s90, v100
	v_add_u32_e32 v255, s90, v149
	v_med3_i32 v80, v80, 0, s99
	v_med3_i32 v83, v83, 0, s99
	v_med3_i32 v99, v99, 0, s99
	v_med3_i32 v253, v253, 0, s99
	v_med3_i32 v254, v254, 0, s99
	v_med3_i32 v255, v255, 0, s99
	v_mad_u32_u24 v80, v80, s100, v252
	v_mad_u32_u24 v83, v83, s100, v252
	v_mad_u32_u24 v99, v99, s100, v252
	v_mad_u32_u24 v253, v253, s100, v252
	v_mad_u32_u24 v254, v254, s100, v153
	v_mad_u32_u24 v255, v255, s100, v153
	global_load_dwordx4 v[116:119], v80, s[82:83]
	global_load_dwordx4 v[120:123], v83, s[82:83]
	global_load_dwordx4 v[124:127], v99, s[82:83]
	global_load_dwordx4 v[128:131], v253, s[82:83]
	global_load_dwordx4 v[132:135], v254, s[82:83] offset:768
	global_load_dwordx4 v[136:139], v255, s[82:83] offset:768
	global_load_dwordx4 v[140:143], v254, s[82:83] offset:832
	global_load_dwordx4 v[144:147], v255, s[82:83] offset:832
	ds_read_b64_tr_b16 v[72:73], v231
	ds_read_b64_tr_b16 v[74:75], v231 offset:512
	ds_read_b64_tr_b16 v[76:77], v231 offset:2048
	ds_read_b64_tr_b16 v[78:79], v231 offset:2560
	ds_read_b64_tr_b16 v[220:221], v231 offset:1024
	ds_read_b64_tr_b16 v[222:223], v231 offset:1536
	ds_read_b64_tr_b16 v[224:225], v231 offset:3072
	ds_read_b64_tr_b16 v[226:227], v231 offset:3584
	v_exp_f32_e32 v32, v32
	v_exp_f32_e32 v33, v33
	v_exp_f32_e32 v34, v34
	v_exp_f32_e32 v35, v35
	s_waitcnt vmcnt(12)
	ds_write_b128 v247, v[156:159]
	ds_write_b128 v247, v[160:163] offset:1024
	ds_write_b128 v247, v[164:167] offset:2048
	ds_write_b128 v247, v[168:171] offset:3072
	ds_read_b128 v[156:159], v248
	ds_read_b128 v[160:163], v249
	ds_read_b128 v[164:167], v250
	ds_read_b128 v[168:171], v251
	s_waitcnt vmcnt(8)
	ds_write_b128 v112, v[172:175]
	ds_write_b128 v112, v[176:179] offset:1024
	ds_write_b128 v112, v[180:183] offset:2048
	ds_write_b128 v112, v[184:187] offset:3072
	v_exp_f32_e32 v36, v36
	v_exp_f32_e32 v37, v37
	v_exp_f32_e32 v38, v38
	v_exp_f32_e32 v39, v39
	s_waitcnt lgkmcnt(4)
	v_mfma_f32_32x32x16_bf16 v[188:203], v[156:159], v[48:51], v[188:203]
	v_exp_f32_e32 v40, v40
	v_exp_f32_e32 v41, v41
	v_mfma_f32_32x32x16_bf16 v[188:203], v[160:163], v[52:55], v[188:203]
	v_exp_f32_e32 v42, v42
	v_exp_f32_e32 v43, v43
	v_mfma_f32_32x32x16_bf16 v[188:203], v[164:167], v[56:59], v[188:203]
	v_exp_f32_e32 v44, v44
	v_exp_f32_e32 v45, v45
	v_mfma_f32_32x32x16_bf16 v[188:203], v[168:171], v[60:63], v[188:203]
	v_exp_f32_e32 v46, v46
	v_exp_f32_e32 v47, v47
	s_add_i32 s90, s76, 192
	v_add_u32_e32 v84, s90, v107
	v_add_u32_e32 v85, 0, v84
	v_add_u32_e32 v86, 1, v84
	v_add_u32_e32 v87, 2, v84
	v_add_u32_e32 v88, 3, v84
	v_cmp_gt_u32_e64 s[30:31], s98, v85
	v_cmp_gt_u32_e64 s[36:37], s98, v86
	v_cmp_gt_u32_e64 s[78:79], s98, v87
	v_cmp_gt_u32_e64 s[50:51], s98, v88
	v_cndmask_b32_e64 v32, 0, v32, s[30:31]
	v_add_u32_e32 v85, 8, v84
	v_cmp_gt_u32_e64 s[30:31], s98, v85
	v_cndmask_b32_e64 v33, 0, v33, s[36:37]
	v_add_u32_e32 v86, 9, v84
	v_cmp_gt_u32_e64 s[36:37], s98, v86
	v_cndmask_b32_e64 v34, 0, v34, s[78:79]
	v_add_u32_e32 v87, 10, v84
	v_cmp_gt_u32_e64 s[78:79], s98, v87
	v_cndmask_b32_e64 v35, 0, v35, s[50:51]
	v_add_u32_e32 v88, 11, v84
	v_cmp_gt_u32_e64 s[50:51], s98, v88
	v_cndmask_b32_e64 v36, 0, v36, s[30:31]
	v_add_u32_e32 v85, 16, v84
	v_cmp_gt_u32_e64 s[30:31], s98, v85
	v_cndmask_b32_e64 v37, 0, v37, s[36:37]
	v_add_u32_e32 v86, 17, v84
	v_cmp_gt_u32_e64 s[36:37], s98, v86
	v_cndmask_b32_e64 v38, 0, v38, s[78:79]
	v_add_u32_e32 v87, 18, v84
	v_cmp_gt_u32_e64 s[78:79], s98, v87
	v_cndmask_b32_e64 v39, 0, v39, s[50:51]
	v_add_u32_e32 v88, 19, v84
	v_cmp_gt_u32_e64 s[50:51], s98, v88
	v_cndmask_b32_e64 v40, 0, v40, s[30:31]
	v_add_u32_e32 v85, 24, v84
	v_cmp_gt_u32_e64 s[30:31], s98, v85
	v_cndmask_b32_e64 v41, 0, v41, s[36:37]
	v_add_u32_e32 v86, 25, v84
	v_cmp_gt_u32_e64 s[36:37], s98, v86
	v_cndmask_b32_e64 v42, 0, v42, s[78:79]
	v_add_u32_e32 v87, 26, v84
	v_cmp_gt_u32_e64 s[78:79], s98, v87
	v_cndmask_b32_e64 v43, 0, v43, s[50:51]
	v_add_u32_e32 v88, 27, v84
	v_cmp_gt_u32_e64 s[50:51], s98, v88
	v_nop
	v_cndmask_b32_e64 v44, 0, v44, s[30:31]
	v_cndmask_b32_e64 v45, 0, v45, s[36:37]
	v_cndmask_b32_e64 v46, 0, v46, s[78:79]
	v_cndmask_b32_e64 v47, 0, v47, s[50:51]
	v_cvt_pk_bf16_f32 v64, v32, v33
	v_cvt_pk_bf16_f32 v65, v34, v35
	v_cvt_pk_bf16_f32 v66, v36, v37
	v_cvt_pk_bf16_f32 v67, v38, v39
	v_cvt_pk_bf16_f32 v68, v40, v41
	v_cvt_pk_bf16_f32 v69, v42, v43
	v_cvt_pk_bf16_f32 v70, v44, v45
	v_cvt_pk_bf16_f32 v71, v46, v47
	v_pk_add_f32 v[232:233], v[232:233], v[32:33]
	v_pk_add_f32 v[232:233], v[232:233], v[34:35]
	v_pk_add_f32 v[232:233], v[232:233], v[36:37]
	v_pk_add_f32 v[232:233], v[232:233], v[38:39]
	v_pk_add_f32 v[232:233], v[232:233], v[40:41]
	v_pk_add_f32 v[232:233], v[232:233], v[42:43]
	v_pk_add_f32 v[232:233], v[232:233], v[44:45]
	v_pk_add_f32 v[232:233], v[232:233], v[46:47]
	ds_read2_b32 v[32:33], v115 offset0:102 offset1:103
	ds_read2_b32 v[34:35], v115 offset0:104 offset1:105
	ds_read2_b32 v[36:37], v115 offset0:110 offset1:111
	ds_read2_b32 v[38:39], v115 offset0:112 offset1:113
	ds_read2_b32 v[40:41], v115 offset0:119 offset1:120
	ds_read2_b32 v[42:43], v115 offset0:121 offset1:122
	ds_read2_b32 v[44:45], v115 offset0:127 offset1:128
	ds_read2_b32 v[46:47], v115 offset0:129 offset1:130
	v_mfma_f32_32x32x16_bf16 v[0:15], v[64:67], v[72:75], v[0:15]
	v_mfma_f32_32x32x16_bf16 v[16:31], v[64:67], v[76:79], v[16:31]
	v_mfma_f32_32x32x16_bf16 v[0:15], v[68:71], v[220:223], v[0:15]
	v_mfma_f32_32x32x16_bf16 v[16:31], v[68:71], v[224:227], v[16:31]
	s_add_i32 s90, s76, 288
	v_add_u32_e32 v80, s90, v235
	v_add_u32_e32 v83, s90, v236
	v_add_u32_e32 v99, s90, v237
	v_add_u32_e32 v253, s90, v238
	v_add_u32_e32 v254, s90, v100
	v_add_u32_e32 v255, s90, v149
	v_med3_i32 v80, v80, 0, s99
	v_med3_i32 v83, v83, 0, s99
	v_med3_i32 v99, v99, 0, s99
	v_med3_i32 v253, v253, 0, s99
	v_med3_i32 v254, v254, 0, s99
	v_med3_i32 v255, v255, 0, s99
	v_mad_u32_u24 v80, v80, s100, v252
	v_mad_u32_u24 v83, v83, s100, v252
	v_mad_u32_u24 v99, v99, s100, v252
	v_mad_u32_u24 v253, v253, s100, v252
	v_mad_u32_u24 v254, v254, s100, v153
	v_mad_u32_u24 v255, v255, s100, v153
	global_load_dwordx4 v[156:159], v80, s[82:83]
	global_load_dwordx4 v[160:163], v83, s[82:83]
	global_load_dwordx4 v[164:167], v99, s[82:83]
	global_load_dwordx4 v[168:171], v253, s[82:83]
	global_load_dwordx4 v[172:175], v254, s[82:83] offset:768
	global_load_dwordx4 v[176:179], v255, s[82:83] offset:768
	global_load_dwordx4 v[180:183], v254, s[82:83] offset:832
	global_load_dwordx4 v[184:187], v255, s[82:83] offset:832
	ds_read_b64_tr_b16 v[72:73], v231
	ds_read_b64_tr_b16 v[74:75], v231 offset:512
	ds_read_b64_tr_b16 v[76:77], v231 offset:2048
	ds_read_b64_tr_b16 v[78:79], v231 offset:2560
	ds_read_b64_tr_b16 v[220:221], v231 offset:1024
	ds_read_b64_tr_b16 v[222:223], v231 offset:1536
	ds_read_b64_tr_b16 v[224:225], v231 offset:3072
	ds_read_b64_tr_b16 v[226:227], v231 offset:3584
	v_exp_f32_e32 v188, v188
	v_exp_f32_e32 v189, v189
	v_exp_f32_e32 v190, v190
	v_exp_f32_e32 v191, v191
	s_waitcnt vmcnt(12)
	ds_write_b128 v247, v[116:119]
	ds_write_b128 v247, v[120:123] offset:1024
	ds_write_b128 v247, v[124:127] offset:2048
	ds_write_b128 v247, v[128:131] offset:3072
	ds_read_b128 v[116:119], v248
	ds_read_b128 v[120:123], v249
	ds_read_b128 v[124:127], v250
	ds_read_b128 v[128:131], v251
	s_waitcnt vmcnt(8)
	ds_write_b128 v112, v[132:135]
	ds_write_b128 v112, v[136:139] offset:1024
	ds_write_b128 v112, v[140:143] offset:2048
	ds_write_b128 v112, v[144:147] offset:3072
	v_exp_f32_e32 v192, v192
	v_exp_f32_e32 v193, v193
	v_exp_f32_e32 v194, v194
	v_exp_f32_e32 v195, v195
	s_waitcnt lgkmcnt(4)
	v_mfma_f32_32x32x16_bf16 v[32:47], v[116:119], v[48:51], v[32:47]
	v_exp_f32_e32 v196, v196
	v_exp_f32_e32 v197, v197
	v_mfma_f32_32x32x16_bf16 v[32:47], v[120:123], v[52:55], v[32:47]
	v_exp_f32_e32 v198, v198
	v_exp_f32_e32 v199, v199
	v_mfma_f32_32x32x16_bf16 v[32:47], v[124:127], v[56:59], v[32:47]
	v_exp_f32_e32 v200, v200
	v_exp_f32_e32 v201, v201
	v_mfma_f32_32x32x16_bf16 v[32:47], v[128:131], v[60:63], v[32:47]
	v_exp_f32_e32 v202, v202
	v_exp_f32_e32 v203, v203
	s_add_i32 s90, s76, 224
	v_add_u32_e32 v84, s90, v107
	v_add_u32_e32 v85, 0, v84
	v_add_u32_e32 v86, 1, v84
	v_add_u32_e32 v87, 2, v84
	v_add_u32_e32 v88, 3, v84
	v_cmp_gt_u32_e64 s[30:31], s98, v85
	v_cmp_gt_u32_e64 s[36:37], s98, v86
	v_cmp_gt_u32_e64 s[78:79], s98, v87
	v_cmp_gt_u32_e64 s[50:51], s98, v88
	v_cndmask_b32_e64 v188, 0, v188, s[30:31]
	v_add_u32_e32 v85, 8, v84
	v_cmp_gt_u32_e64 s[30:31], s98, v85
	v_cndmask_b32_e64 v189, 0, v189, s[36:37]
	v_add_u32_e32 v86, 9, v84
	v_cmp_gt_u32_e64 s[36:37], s98, v86
	v_cndmask_b32_e64 v190, 0, v190, s[78:79]
	v_add_u32_e32 v87, 10, v84
	v_cmp_gt_u32_e64 s[78:79], s98, v87
	v_cndmask_b32_e64 v191, 0, v191, s[50:51]
	v_add_u32_e32 v88, 11, v84
	v_cmp_gt_u32_e64 s[50:51], s98, v88
	v_cndmask_b32_e64 v192, 0, v192, s[30:31]
	v_add_u32_e32 v85, 16, v84
	v_cmp_gt_u32_e64 s[30:31], s98, v85
	v_cndmask_b32_e64 v193, 0, v193, s[36:37]
	v_add_u32_e32 v86, 17, v84
	v_cmp_gt_u32_e64 s[36:37], s98, v86
	v_cndmask_b32_e64 v194, 0, v194, s[78:79]
	v_add_u32_e32 v87, 18, v84
	v_cmp_gt_u32_e64 s[78:79], s98, v87
	v_cndmask_b32_e64 v195, 0, v195, s[50:51]
	v_add_u32_e32 v88, 19, v84
	v_cmp_gt_u32_e64 s[50:51], s98, v88
	v_cndmask_b32_e64 v196, 0, v196, s[30:31]
	v_add_u32_e32 v85, 24, v84
	v_cmp_gt_u32_e64 s[30:31], s98, v85
	v_cndmask_b32_e64 v197, 0, v197, s[36:37]
	v_add_u32_e32 v86, 25, v84
	v_cmp_gt_u32_e64 s[36:37], s98, v86
	v_cndmask_b32_e64 v198, 0, v198, s[78:79]
	v_add_u32_e32 v87, 26, v84
	v_cmp_gt_u32_e64 s[78:79], s98, v87
	v_cndmask_b32_e64 v199, 0, v199, s[50:51]
	v_add_u32_e32 v88, 27, v84
	v_cmp_gt_u32_e64 s[50:51], s98, v88
	v_nop
	v_cndmask_b32_e64 v200, 0, v200, s[30:31]
	v_cndmask_b32_e64 v201, 0, v201, s[36:37]
	v_cndmask_b32_e64 v202, 0, v202, s[78:79]
	v_cndmask_b32_e64 v203, 0, v203, s[50:51]
	v_cvt_pk_bf16_f32 v64, v188, v189
	v_cvt_pk_bf16_f32 v65, v190, v191
	v_cvt_pk_bf16_f32 v66, v192, v193
	v_cvt_pk_bf16_f32 v67, v194, v195
	v_cvt_pk_bf16_f32 v68, v196, v197
	v_cvt_pk_bf16_f32 v69, v198, v199
	v_cvt_pk_bf16_f32 v70, v200, v201
	v_cvt_pk_bf16_f32 v71, v202, v203
	v_pk_add_f32 v[232:233], v[232:233], v[188:189]
	v_pk_add_f32 v[232:233], v[232:233], v[190:191]
	v_pk_add_f32 v[232:233], v[232:233], v[192:193]
	v_pk_add_f32 v[232:233], v[232:233], v[194:195]
	v_pk_add_f32 v[232:233], v[232:233], v[196:197]
	v_pk_add_f32 v[232:233], v[232:233], v[198:199]
	v_pk_add_f32 v[232:233], v[232:233], v[200:201]
	v_pk_add_f32 v[232:233], v[232:233], v[202:203]
	ds_read2_b32 v[188:189], v115 offset0:136 offset1:137
	ds_read2_b32 v[190:191], v115 offset0:138 offset1:139
	ds_read2_b32 v[192:193], v115 offset0:144 offset1:145
	ds_read2_b32 v[194:195], v115 offset0:146 offset1:147
	ds_read2_b32 v[196:197], v115 offset0:153 offset1:154
	ds_read2_b32 v[198:199], v115 offset0:155 offset1:156
	ds_read2_b32 v[200:201], v115 offset0:161 offset1:162
	ds_read2_b32 v[202:203], v115 offset0:163 offset1:164
	v_mfma_f32_32x32x16_bf16 v[0:15], v[64:67], v[72:75], v[0:15]
	v_mfma_f32_32x32x16_bf16 v[16:31], v[64:67], v[76:79], v[16:31]
	v_mfma_f32_32x32x16_bf16 v[0:15], v[68:71], v[220:223], v[0:15]
	v_mfma_f32_32x32x16_bf16 v[16:31], v[68:71], v[224:227], v[16:31]
	s_add_i32 s90, s76, 320
	v_add_u32_e32 v80, s90, v235
	v_add_u32_e32 v83, s90, v236
	v_add_u32_e32 v99, s90, v237
	v_add_u32_e32 v253, s90, v238
	v_add_u32_e32 v254, s90, v100
	v_add_u32_e32 v255, s90, v149
	v_med3_i32 v80, v80, 0, s99
	v_med3_i32 v83, v83, 0, s99
	v_med3_i32 v99, v99, 0, s99
	v_med3_i32 v253, v253, 0, s99
	v_med3_i32 v254, v254, 0, s99
	v_med3_i32 v255, v255, 0, s99
	v_mad_u32_u24 v80, v80, s100, v252
	v_mad_u32_u24 v83, v83, s100, v252
	v_mad_u32_u24 v99, v99, s100, v252
	v_mad_u32_u24 v253, v253, s100, v252
	v_mad_u32_u24 v254, v254, s100, v153
	v_mad_u32_u24 v255, v255, s100, v153
	global_load_dwordx4 v[116:119], v80, s[82:83]
	global_load_dwordx4 v[120:123], v83, s[82:83]
	global_load_dwordx4 v[124:127], v99, s[82:83]
	global_load_dwordx4 v[128:131], v253, s[82:83]
	global_load_dwordx4 v[132:135], v254, s[82:83] offset:768
	global_load_dwordx4 v[136:139], v255, s[82:83] offset:768
	global_load_dwordx4 v[140:143], v254, s[82:83] offset:832
	global_load_dwordx4 v[144:147], v255, s[82:83] offset:832
	ds_read_b64_tr_b16 v[72:73], v231
	ds_read_b64_tr_b16 v[74:75], v231 offset:512
	ds_read_b64_tr_b16 v[76:77], v231 offset:2048
	ds_read_b64_tr_b16 v[78:79], v231 offset:2560
	ds_read_b64_tr_b16 v[220:221], v231 offset:1024
	ds_read_b64_tr_b16 v[222:223], v231 offset:1536
	ds_read_b64_tr_b16 v[224:225], v231 offset:3072
	ds_read_b64_tr_b16 v[226:227], v231 offset:3584
	v_exp_f32_e32 v32, v32
	v_exp_f32_e32 v33, v33
	v_exp_f32_e32 v34, v34
	v_exp_f32_e32 v35, v35
	s_waitcnt vmcnt(12)
	ds_write_b128 v247, v[156:159]
	ds_write_b128 v247, v[160:163] offset:1024
	ds_write_b128 v247, v[164:167] offset:2048
	ds_write_b128 v247, v[168:171] offset:3072
	ds_read_b128 v[156:159], v248
	ds_read_b128 v[160:163], v249
	ds_read_b128 v[164:167], v250
	ds_read_b128 v[168:171], v251
	s_waitcnt vmcnt(8)
	ds_write_b128 v112, v[172:175]
	ds_write_b128 v112, v[176:179] offset:1024
	ds_write_b128 v112, v[180:183] offset:2048
	ds_write_b128 v112, v[184:187] offset:3072
	v_exp_f32_e32 v36, v36
	v_exp_f32_e32 v37, v37
	v_exp_f32_e32 v38, v38
	v_exp_f32_e32 v39, v39
	s_waitcnt lgkmcnt(4)
	v_mfma_f32_32x32x16_bf16 v[188:203], v[156:159], v[48:51], v[188:203]
	v_exp_f32_e32 v40, v40
	v_exp_f32_e32 v41, v41
	v_mfma_f32_32x32x16_bf16 v[188:203], v[160:163], v[52:55], v[188:203]
	v_exp_f32_e32 v42, v42
	v_exp_f32_e32 v43, v43
	v_mfma_f32_32x32x16_bf16 v[188:203], v[164:167], v[56:59], v[188:203]
	v_exp_f32_e32 v44, v44
	v_exp_f32_e32 v45, v45
	v_mfma_f32_32x32x16_bf16 v[188:203], v[168:171], v[60:63], v[188:203]
	v_exp_f32_e32 v46, v46
	v_exp_f32_e32 v47, v47
	s_add_i32 s90, s76, 256
	v_add_u32_e32 v84, s90, v107
	v_add_u32_e32 v85, 0, v84
	v_add_u32_e32 v86, 1, v84
	v_add_u32_e32 v87, 2, v84
	v_add_u32_e32 v88, 3, v84
	v_cmp_gt_u32_e64 s[30:31], s98, v85
	v_cmp_gt_u32_e64 s[36:37], s98, v86
	v_cmp_gt_u32_e64 s[78:79], s98, v87
	v_cmp_gt_u32_e64 s[50:51], s98, v88
	v_cndmask_b32_e64 v32, 0, v32, s[30:31]
	v_add_u32_e32 v85, 8, v84
	v_cmp_gt_u32_e64 s[30:31], s98, v85
	v_cndmask_b32_e64 v33, 0, v33, s[36:37]
	v_add_u32_e32 v86, 9, v84
	v_cmp_gt_u32_e64 s[36:37], s98, v86
	v_cndmask_b32_e64 v34, 0, v34, s[78:79]
	v_add_u32_e32 v87, 10, v84
	v_cmp_gt_u32_e64 s[78:79], s98, v87
	v_cndmask_b32_e64 v35, 0, v35, s[50:51]
	v_add_u32_e32 v88, 11, v84
	v_cmp_gt_u32_e64 s[50:51], s98, v88
	v_cndmask_b32_e64 v36, 0, v36, s[30:31]
	v_add_u32_e32 v85, 16, v84
	v_cmp_gt_u32_e64 s[30:31], s98, v85
	v_cndmask_b32_e64 v37, 0, v37, s[36:37]
	v_add_u32_e32 v86, 17, v84
	v_cmp_gt_u32_e64 s[36:37], s98, v86
	v_cndmask_b32_e64 v38, 0, v38, s[78:79]
	v_add_u32_e32 v87, 18, v84
	v_cmp_gt_u32_e64 s[78:79], s98, v87
	v_cndmask_b32_e64 v39, 0, v39, s[50:51]
	v_add_u32_e32 v88, 19, v84
	v_cmp_gt_u32_e64 s[50:51], s98, v88
	v_cndmask_b32_e64 v40, 0, v40, s[30:31]
	v_add_u32_e32 v85, 24, v84
	v_cmp_gt_u32_e64 s[30:31], s98, v85
	v_cndmask_b32_e64 v41, 0, v41, s[36:37]
	v_add_u32_e32 v86, 25, v84
	v_cmp_gt_u32_e64 s[36:37], s98, v86
	v_cndmask_b32_e64 v42, 0, v42, s[78:79]
	v_add_u32_e32 v87, 26, v84
	v_cmp_gt_u32_e64 s[78:79], s98, v87
	v_cndmask_b32_e64 v43, 0, v43, s[50:51]
	v_add_u32_e32 v88, 27, v84
	v_cmp_gt_u32_e64 s[50:51], s98, v88
	v_nop
	v_cndmask_b32_e64 v44, 0, v44, s[30:31]
	v_cndmask_b32_e64 v45, 0, v45, s[36:37]
	v_cndmask_b32_e64 v46, 0, v46, s[78:79]
	v_cndmask_b32_e64 v47, 0, v47, s[50:51]
	v_cvt_pk_bf16_f32 v64, v32, v33
	v_cvt_pk_bf16_f32 v65, v34, v35
	v_cvt_pk_bf16_f32 v66, v36, v37
	v_cvt_pk_bf16_f32 v67, v38, v39
	v_cvt_pk_bf16_f32 v68, v40, v41
	v_cvt_pk_bf16_f32 v69, v42, v43
	v_cvt_pk_bf16_f32 v70, v44, v45
	v_cvt_pk_bf16_f32 v71, v46, v47
	v_pk_add_f32 v[232:233], v[232:233], v[32:33]
	v_pk_add_f32 v[232:233], v[232:233], v[34:35]
	v_pk_add_f32 v[232:233], v[232:233], v[36:37]
	v_pk_add_f32 v[232:233], v[232:233], v[38:39]
	v_pk_add_f32 v[232:233], v[232:233], v[40:41]
	v_pk_add_f32 v[232:233], v[232:233], v[42:43]
	v_pk_add_f32 v[232:233], v[232:233], v[44:45]
	v_pk_add_f32 v[232:233], v[232:233], v[46:47]
	ds_read2_b32 v[32:33], v115 offset0:170 offset1:171
	ds_read2_b32 v[34:35], v115 offset0:172 offset1:173
	ds_read2_b32 v[36:37], v115 offset0:178 offset1:179
	ds_read2_b32 v[38:39], v115 offset0:180 offset1:181
	ds_read2_b32 v[40:41], v115 offset0:187 offset1:188
	ds_read2_b32 v[42:43], v115 offset0:189 offset1:190
	ds_read2_b32 v[44:45], v115 offset0:195 offset1:196
	ds_read2_b32 v[46:47], v115 offset0:197 offset1:198
	v_mfma_f32_32x32x16_bf16 v[0:15], v[64:67], v[72:75], v[0:15]
	v_mfma_f32_32x32x16_bf16 v[16:31], v[64:67], v[76:79], v[16:31]
	v_mfma_f32_32x32x16_bf16 v[0:15], v[68:71], v[220:223], v[0:15]
	v_mfma_f32_32x32x16_bf16 v[16:31], v[68:71], v[224:227], v[16:31]
	s_add_i32 s90, s76, 352
	v_add_u32_e32 v80, s90, v235
	v_add_u32_e32 v83, s90, v236
	v_add_u32_e32 v99, s90, v237
	v_add_u32_e32 v253, s90, v238
	v_add_u32_e32 v254, s90, v100
	v_add_u32_e32 v255, s90, v149
	v_med3_i32 v80, v80, 0, s99
	v_med3_i32 v83, v83, 0, s99
	v_med3_i32 v99, v99, 0, s99
	v_med3_i32 v253, v253, 0, s99
	v_med3_i32 v254, v254, 0, s99
	v_med3_i32 v255, v255, 0, s99
	v_mad_u32_u24 v80, v80, s100, v252
	v_mad_u32_u24 v83, v83, s100, v252
	v_mad_u32_u24 v99, v99, s100, v252
	v_mad_u32_u24 v253, v253, s100, v252
	v_mad_u32_u24 v254, v254, s100, v153
	v_mad_u32_u24 v255, v255, s100, v153
	global_load_dwordx4 v[156:159], v80, s[82:83]
	global_load_dwordx4 v[160:163], v83, s[82:83]
	global_load_dwordx4 v[164:167], v99, s[82:83]
	global_load_dwordx4 v[168:171], v253, s[82:83]
	global_load_dwordx4 v[172:175], v254, s[82:83] offset:768
	global_load_dwordx4 v[176:179], v255, s[82:83] offset:768
	global_load_dwordx4 v[180:183], v254, s[82:83] offset:832
	global_load_dwordx4 v[184:187], v255, s[82:83] offset:832
	ds_read_b64_tr_b16 v[72:73], v231
	ds_read_b64_tr_b16 v[74:75], v231 offset:512
	ds_read_b64_tr_b16 v[76:77], v231 offset:2048
	ds_read_b64_tr_b16 v[78:79], v231 offset:2560
	ds_read_b64_tr_b16 v[220:221], v231 offset:1024
	ds_read_b64_tr_b16 v[222:223], v231 offset:1536
	ds_read_b64_tr_b16 v[224:225], v231 offset:3072
	ds_read_b64_tr_b16 v[226:227], v231 offset:3584
	v_exp_f32_e32 v188, v188
	v_exp_f32_e32 v189, v189
	v_exp_f32_e32 v190, v190
	v_exp_f32_e32 v191, v191
	s_waitcnt vmcnt(12)
	ds_write_b128 v247, v[116:119]
	ds_write_b128 v247, v[120:123] offset:1024
	ds_write_b128 v247, v[124:127] offset:2048
	ds_write_b128 v247, v[128:131] offset:3072
	ds_read_b128 v[116:119], v248
	ds_read_b128 v[120:123], v249
	ds_read_b128 v[124:127], v250
	ds_read_b128 v[128:131], v251
	s_waitcnt vmcnt(8)
	ds_write_b128 v112, v[132:135]
	ds_write_b128 v112, v[136:139] offset:1024
	ds_write_b128 v112, v[140:143] offset:2048
	ds_write_b128 v112, v[144:147] offset:3072
	v_exp_f32_e32 v192, v192
	v_exp_f32_e32 v193, v193
	v_exp_f32_e32 v194, v194
	v_exp_f32_e32 v195, v195
	s_waitcnt lgkmcnt(4)
	v_mfma_f32_32x32x16_bf16 v[32:47], v[116:119], v[48:51], v[32:47]
	v_exp_f32_e32 v196, v196
	v_exp_f32_e32 v197, v197
	v_mfma_f32_32x32x16_bf16 v[32:47], v[120:123], v[52:55], v[32:47]
	v_exp_f32_e32 v198, v198
	v_exp_f32_e32 v199, v199
	v_mfma_f32_32x32x16_bf16 v[32:47], v[124:127], v[56:59], v[32:47]
	v_exp_f32_e32 v200, v200
	v_exp_f32_e32 v201, v201
	v_mfma_f32_32x32x16_bf16 v[32:47], v[128:131], v[60:63], v[32:47]
	v_exp_f32_e32 v202, v202
	v_exp_f32_e32 v203, v203
	s_add_i32 s90, s76, 288
	v_add_u32_e32 v84, s90, v107
	v_add_u32_e32 v85, 0, v84
	v_add_u32_e32 v86, 1, v84
	v_add_u32_e32 v87, 2, v84
	v_add_u32_e32 v88, 3, v84
	v_cmp_gt_u32_e64 s[30:31], s98, v85
	v_cmp_gt_u32_e64 s[36:37], s98, v86
	v_cmp_gt_u32_e64 s[78:79], s98, v87
	v_cmp_gt_u32_e64 s[50:51], s98, v88
	v_cndmask_b32_e64 v188, 0, v188, s[30:31]
	v_add_u32_e32 v85, 8, v84
	v_cmp_gt_u32_e64 s[30:31], s98, v85
	v_cndmask_b32_e64 v189, 0, v189, s[36:37]
	v_add_u32_e32 v86, 9, v84
	v_cmp_gt_u32_e64 s[36:37], s98, v86
	v_cndmask_b32_e64 v190, 0, v190, s[78:79]
	v_add_u32_e32 v87, 10, v84
	v_cmp_gt_u32_e64 s[78:79], s98, v87
	v_cndmask_b32_e64 v191, 0, v191, s[50:51]
	v_add_u32_e32 v88, 11, v84
	v_cmp_gt_u32_e64 s[50:51], s98, v88
	v_cndmask_b32_e64 v192, 0, v192, s[30:31]
	v_add_u32_e32 v85, 16, v84
	v_cmp_gt_u32_e64 s[30:31], s98, v85
	v_cndmask_b32_e64 v193, 0, v193, s[36:37]
	v_add_u32_e32 v86, 17, v84
	v_cmp_gt_u32_e64 s[36:37], s98, v86
	v_cndmask_b32_e64 v194, 0, v194, s[78:79]
	v_add_u32_e32 v87, 18, v84
	v_cmp_gt_u32_e64 s[78:79], s98, v87
	v_cndmask_b32_e64 v195, 0, v195, s[50:51]
	v_add_u32_e32 v88, 19, v84
	v_cmp_gt_u32_e64 s[50:51], s98, v88
	v_cndmask_b32_e64 v196, 0, v196, s[30:31]
	v_add_u32_e32 v85, 24, v84
	v_cmp_gt_u32_e64 s[30:31], s98, v85
	v_cndmask_b32_e64 v197, 0, v197, s[36:37]
	v_add_u32_e32 v86, 25, v84
	v_cmp_gt_u32_e64 s[36:37], s98, v86
	v_cndmask_b32_e64 v198, 0, v198, s[78:79]
	v_add_u32_e32 v87, 26, v84
	v_cmp_gt_u32_e64 s[78:79], s98, v87
	v_cndmask_b32_e64 v199, 0, v199, s[50:51]
	v_add_u32_e32 v88, 27, v84
	v_cmp_gt_u32_e64 s[50:51], s98, v88
	v_nop
	v_cndmask_b32_e64 v200, 0, v200, s[30:31]
	v_cndmask_b32_e64 v201, 0, v201, s[36:37]
	v_cndmask_b32_e64 v202, 0, v202, s[78:79]
	v_cndmask_b32_e64 v203, 0, v203, s[50:51]
	v_cvt_pk_bf16_f32 v64, v188, v189
	v_cvt_pk_bf16_f32 v65, v190, v191
	v_cvt_pk_bf16_f32 v66, v192, v193
	v_cvt_pk_bf16_f32 v67, v194, v195
	v_cvt_pk_bf16_f32 v68, v196, v197
	v_cvt_pk_bf16_f32 v69, v198, v199
	v_cvt_pk_bf16_f32 v70, v200, v201
	v_cvt_pk_bf16_f32 v71, v202, v203
	v_pk_add_f32 v[232:233], v[232:233], v[188:189]
	v_pk_add_f32 v[232:233], v[232:233], v[190:191]
	v_pk_add_f32 v[232:233], v[232:233], v[192:193]
	v_pk_add_f32 v[232:233], v[232:233], v[194:195]
	v_pk_add_f32 v[232:233], v[232:233], v[196:197]
	v_pk_add_f32 v[232:233], v[232:233], v[198:199]
	v_pk_add_f32 v[232:233], v[232:233], v[200:201]
	v_pk_add_f32 v[232:233], v[232:233], v[202:203]
	ds_read2_b32 v[188:189], v115 offset0:204 offset1:205
	ds_read2_b32 v[190:191], v115 offset0:206 offset1:207
	ds_read2_b32 v[192:193], v115 offset0:212 offset1:213
	ds_read2_b32 v[194:195], v115 offset0:214 offset1:215
	ds_read2_b32 v[196:197], v115 offset0:221 offset1:222
	ds_read2_b32 v[198:199], v115 offset0:223 offset1:224
	ds_read2_b32 v[200:201], v115 offset0:229 offset1:230
	ds_read2_b32 v[202:203], v115 offset0:231 offset1:232
	v_mfma_f32_32x32x16_bf16 v[0:15], v[64:67], v[72:75], v[0:15]
	v_mfma_f32_32x32x16_bf16 v[16:31], v[64:67], v[76:79], v[16:31]
	v_mfma_f32_32x32x16_bf16 v[0:15], v[68:71], v[220:223], v[0:15]
	v_mfma_f32_32x32x16_bf16 v[16:31], v[68:71], v[224:227], v[16:31]
	s_add_i32 s90, s76, 384
	v_add_u32_e32 v80, s90, v235
	v_add_u32_e32 v83, s90, v236
	v_add_u32_e32 v99, s90, v237
	v_add_u32_e32 v253, s90, v238
	v_add_u32_e32 v254, s90, v100
	v_add_u32_e32 v255, s90, v149
	v_med3_i32 v80, v80, 0, s99
	v_med3_i32 v83, v83, 0, s99
	v_med3_i32 v99, v99, 0, s99
	v_med3_i32 v253, v253, 0, s99
	v_med3_i32 v254, v254, 0, s99
	v_med3_i32 v255, v255, 0, s99
	v_mad_u32_u24 v80, v80, s100, v252
	v_mad_u32_u24 v83, v83, s100, v252
	v_mad_u32_u24 v99, v99, s100, v252
	v_mad_u32_u24 v253, v253, s100, v252
	v_mad_u32_u24 v254, v254, s100, v153
	v_mad_u32_u24 v255, v255, s100, v153
	global_load_dwordx4 v[116:119], v80, s[82:83]
	global_load_dwordx4 v[120:123], v83, s[82:83]
	global_load_dwordx4 v[124:127], v99, s[82:83]
	global_load_dwordx4 v[128:131], v253, s[82:83]
	global_load_dwordx4 v[132:135], v254, s[82:83] offset:768
	global_load_dwordx4 v[136:139], v255, s[82:83] offset:768
	global_load_dwordx4 v[140:143], v254, s[82:83] offset:832
	global_load_dwordx4 v[144:147], v255, s[82:83] offset:832
	ds_read_b64_tr_b16 v[72:73], v231
	ds_read_b64_tr_b16 v[74:75], v231 offset:512
	ds_read_b64_tr_b16 v[76:77], v231 offset:2048
	ds_read_b64_tr_b16 v[78:79], v231 offset:2560
	ds_read_b64_tr_b16 v[220:221], v231 offset:1024
	ds_read_b64_tr_b16 v[222:223], v231 offset:1536
	ds_read_b64_tr_b16 v[224:225], v231 offset:3072
	ds_read_b64_tr_b16 v[226:227], v231 offset:3584
	v_exp_f32_e32 v32, v32
	v_exp_f32_e32 v33, v33
	v_exp_f32_e32 v34, v34
	v_exp_f32_e32 v35, v35
	s_waitcnt vmcnt(12)
	ds_write_b128 v247, v[156:159]
	ds_write_b128 v247, v[160:163] offset:1024
	ds_write_b128 v247, v[164:167] offset:2048
	ds_write_b128 v247, v[168:171] offset:3072
	ds_read_b128 v[156:159], v248
	ds_read_b128 v[160:163], v249
	ds_read_b128 v[164:167], v250
	ds_read_b128 v[168:171], v251
	s_waitcnt vmcnt(8)
	ds_write_b128 v112, v[172:175]
	ds_write_b128 v112, v[176:179] offset:1024
	ds_write_b128 v112, v[180:183] offset:2048
	ds_write_b128 v112, v[184:187] offset:3072
	v_exp_f32_e32 v36, v36
	v_exp_f32_e32 v37, v37
	v_exp_f32_e32 v38, v38
	v_exp_f32_e32 v39, v39
	s_waitcnt lgkmcnt(4)
	v_mfma_f32_32x32x16_bf16 v[188:203], v[156:159], v[48:51], v[188:203]
	v_exp_f32_e32 v40, v40
	v_exp_f32_e32 v41, v41
	v_mfma_f32_32x32x16_bf16 v[188:203], v[160:163], v[52:55], v[188:203]
	v_exp_f32_e32 v42, v42
	v_exp_f32_e32 v43, v43
	v_mfma_f32_32x32x16_bf16 v[188:203], v[164:167], v[56:59], v[188:203]
	v_exp_f32_e32 v44, v44
	v_exp_f32_e32 v45, v45
	v_mfma_f32_32x32x16_bf16 v[188:203], v[168:171], v[60:63], v[188:203]
	v_exp_f32_e32 v46, v46
	v_exp_f32_e32 v47, v47
	s_add_i32 s90, s76, 320
	v_add_u32_e32 v84, s90, v107
	v_add_u32_e32 v85, 0, v84
	v_add_u32_e32 v86, 1, v84
	v_add_u32_e32 v87, 2, v84
	v_add_u32_e32 v88, 3, v84
	v_cmp_gt_u32_e64 s[30:31], s98, v85
	v_cmp_gt_u32_e64 s[36:37], s98, v86
	v_cmp_gt_u32_e64 s[78:79], s98, v87
	v_cmp_gt_u32_e64 s[50:51], s98, v88
	v_cndmask_b32_e64 v32, 0, v32, s[30:31]
	v_add_u32_e32 v85, 8, v84
	v_cmp_gt_u32_e64 s[30:31], s98, v85
	v_cndmask_b32_e64 v33, 0, v33, s[36:37]
	v_add_u32_e32 v86, 9, v84
	v_cmp_gt_u32_e64 s[36:37], s98, v86
	v_cndmask_b32_e64 v34, 0, v34, s[78:79]
	v_add_u32_e32 v87, 10, v84
	v_cmp_gt_u32_e64 s[78:79], s98, v87
	v_cndmask_b32_e64 v35, 0, v35, s[50:51]
	v_add_u32_e32 v88, 11, v84
	v_cmp_gt_u32_e64 s[50:51], s98, v88
	v_cndmask_b32_e64 v36, 0, v36, s[30:31]
	v_add_u32_e32 v85, 16, v84
	v_cmp_gt_u32_e64 s[30:31], s98, v85
	v_cndmask_b32_e64 v37, 0, v37, s[36:37]
	v_add_u32_e32 v86, 17, v84
	v_cmp_gt_u32_e64 s[36:37], s98, v86
	v_cndmask_b32_e64 v38, 0, v38, s[78:79]
	v_add_u32_e32 v87, 18, v84
	v_cmp_gt_u32_e64 s[78:79], s98, v87
	v_cndmask_b32_e64 v39, 0, v39, s[50:51]
	v_add_u32_e32 v88, 19, v84
	v_cmp_gt_u32_e64 s[50:51], s98, v88
	v_cndmask_b32_e64 v40, 0, v40, s[30:31]
	v_add_u32_e32 v85, 24, v84
	v_cmp_gt_u32_e64 s[30:31], s98, v85
	v_cndmask_b32_e64 v41, 0, v41, s[36:37]
	v_add_u32_e32 v86, 25, v84
	v_cmp_gt_u32_e64 s[36:37], s98, v86
	v_cndmask_b32_e64 v42, 0, v42, s[78:79]
	v_add_u32_e32 v87, 26, v84
	v_cmp_gt_u32_e64 s[78:79], s98, v87
	v_cndmask_b32_e64 v43, 0, v43, s[50:51]
	v_add_u32_e32 v88, 27, v84
	v_cmp_gt_u32_e64 s[50:51], s98, v88
	v_nop
	v_cndmask_b32_e64 v44, 0, v44, s[30:31]
	v_cndmask_b32_e64 v45, 0, v45, s[36:37]
	v_cndmask_b32_e64 v46, 0, v46, s[78:79]
	v_cndmask_b32_e64 v47, 0, v47, s[50:51]
	v_cvt_pk_bf16_f32 v64, v32, v33
	v_cvt_pk_bf16_f32 v65, v34, v35
	v_cvt_pk_bf16_f32 v66, v36, v37
	v_cvt_pk_bf16_f32 v67, v38, v39
	v_cvt_pk_bf16_f32 v68, v40, v41
	v_cvt_pk_bf16_f32 v69, v42, v43
	v_cvt_pk_bf16_f32 v70, v44, v45
	v_cvt_pk_bf16_f32 v71, v46, v47
	v_pk_add_f32 v[232:233], v[232:233], v[32:33]
	v_pk_add_f32 v[232:233], v[232:233], v[34:35]
	v_pk_add_f32 v[232:233], v[232:233], v[36:37]
	v_pk_add_f32 v[232:233], v[232:233], v[38:39]
	v_pk_add_f32 v[232:233], v[232:233], v[40:41]
	v_pk_add_f32 v[232:233], v[232:233], v[42:43]
	v_pk_add_f32 v[232:233], v[232:233], v[44:45]
	v_pk_add_f32 v[232:233], v[232:233], v[46:47]
	v_add_u32_e32 v115, 952, v115
	ds_read2_b32 v[32:33], v115 offset0:0 offset1:1
	ds_read2_b32 v[34:35], v115 offset0:2 offset1:3
	ds_read2_b32 v[36:37], v115 offset0:8 offset1:9
	ds_read2_b32 v[38:39], v115 offset0:10 offset1:11
	ds_read2_b32 v[40:41], v115 offset0:17 offset1:18
	ds_read2_b32 v[42:43], v115 offset0:19 offset1:20
	ds_read2_b32 v[44:45], v115 offset0:25 offset1:26
	ds_read2_b32 v[46:47], v115 offset0:27 offset1:28
	v_mfma_f32_32x32x16_bf16 v[0:15], v[64:67], v[72:75], v[0:15]
	v_mfma_f32_32x32x16_bf16 v[16:31], v[64:67], v[76:79], v[16:31]
	v_mfma_f32_32x32x16_bf16 v[0:15], v[68:71], v[220:223], v[0:15]
	v_mfma_f32_32x32x16_bf16 v[16:31], v[68:71], v[224:227], v[16:31]
	s_add_i32 s90, s76, 416
	v_add_u32_e32 v80, s90, v235
	v_add_u32_e32 v83, s90, v236
	v_add_u32_e32 v99, s90, v237
	v_add_u32_e32 v253, s90, v238
	v_add_u32_e32 v254, s90, v100
	v_add_u32_e32 v255, s90, v149
	v_med3_i32 v80, v80, 0, s99
	v_med3_i32 v83, v83, 0, s99
	v_med3_i32 v99, v99, 0, s99
	v_med3_i32 v253, v253, 0, s99
	v_med3_i32 v254, v254, 0, s99
	v_med3_i32 v255, v255, 0, s99
	v_mad_u32_u24 v80, v80, s100, v252
	v_mad_u32_u24 v83, v83, s100, v252
	v_mad_u32_u24 v99, v99, s100, v252
	v_mad_u32_u24 v253, v253, s100, v252
	v_mad_u32_u24 v254, v254, s100, v153
	v_mad_u32_u24 v255, v255, s100, v153
	global_load_dwordx4 v[156:159], v80, s[82:83]
	global_load_dwordx4 v[160:163], v83, s[82:83]
	global_load_dwordx4 v[164:167], v99, s[82:83]
	global_load_dwordx4 v[168:171], v253, s[82:83]
	global_load_dwordx4 v[172:175], v254, s[82:83] offset:768
	global_load_dwordx4 v[176:179], v255, s[82:83] offset:768
	global_load_dwordx4 v[180:183], v254, s[82:83] offset:832
	global_load_dwordx4 v[184:187], v255, s[82:83] offset:832
	ds_read_b64_tr_b16 v[72:73], v231
	ds_read_b64_tr_b16 v[74:75], v231 offset:512
	ds_read_b64_tr_b16 v[76:77], v231 offset:2048
	ds_read_b64_tr_b16 v[78:79], v231 offset:2560
	ds_read_b64_tr_b16 v[220:221], v231 offset:1024
	ds_read_b64_tr_b16 v[222:223], v231 offset:1536
	ds_read_b64_tr_b16 v[224:225], v231 offset:3072
	ds_read_b64_tr_b16 v[226:227], v231 offset:3584
	v_exp_f32_e32 v188, v188
	v_exp_f32_e32 v189, v189
	v_exp_f32_e32 v190, v190
	v_exp_f32_e32 v191, v191
	s_waitcnt vmcnt(12)
	ds_write_b128 v247, v[116:119]
	ds_write_b128 v247, v[120:123] offset:1024
	ds_write_b128 v247, v[124:127] offset:2048
	ds_write_b128 v247, v[128:131] offset:3072
	ds_read_b128 v[116:119], v248
	ds_read_b128 v[120:123], v249
	ds_read_b128 v[124:127], v250
	ds_read_b128 v[128:131], v251
	s_waitcnt vmcnt(8)
	ds_write_b128 v112, v[132:135]
	ds_write_b128 v112, v[136:139] offset:1024
	ds_write_b128 v112, v[140:143] offset:2048
	ds_write_b128 v112, v[144:147] offset:3072
	v_exp_f32_e32 v192, v192
	v_exp_f32_e32 v193, v193
	v_exp_f32_e32 v194, v194
	v_exp_f32_e32 v195, v195
	s_waitcnt lgkmcnt(4)
	v_mfma_f32_32x32x16_bf16 v[32:47], v[116:119], v[48:51], v[32:47]
	v_exp_f32_e32 v196, v196
	v_exp_f32_e32 v197, v197
	v_mfma_f32_32x32x16_bf16 v[32:47], v[120:123], v[52:55], v[32:47]
	v_exp_f32_e32 v198, v198
	v_exp_f32_e32 v199, v199
	v_mfma_f32_32x32x16_bf16 v[32:47], v[124:127], v[56:59], v[32:47]
	v_exp_f32_e32 v200, v200
	v_exp_f32_e32 v201, v201
	v_mfma_f32_32x32x16_bf16 v[32:47], v[128:131], v[60:63], v[32:47]
	v_exp_f32_e32 v202, v202
	v_exp_f32_e32 v203, v203
	s_add_i32 s90, s76, 352
	v_add_u32_e32 v84, s90, v107
	v_add_u32_e32 v85, 0, v84
	v_add_u32_e32 v86, 1, v84
	v_add_u32_e32 v87, 2, v84
	v_add_u32_e32 v88, 3, v84
	v_cmp_gt_u32_e64 s[30:31], s98, v85
	v_cmp_gt_u32_e64 s[36:37], s98, v86
	v_cmp_gt_u32_e64 s[78:79], s98, v87
	v_cmp_gt_u32_e64 s[50:51], s98, v88
	v_cndmask_b32_e64 v188, 0, v188, s[30:31]
	v_add_u32_e32 v85, 8, v84
	v_cmp_gt_u32_e64 s[30:31], s98, v85
	v_cndmask_b32_e64 v189, 0, v189, s[36:37]
	v_add_u32_e32 v86, 9, v84
	v_cmp_gt_u32_e64 s[36:37], s98, v86
	v_cndmask_b32_e64 v190, 0, v190, s[78:79]
	v_add_u32_e32 v87, 10, v84
	v_cmp_gt_u32_e64 s[78:79], s98, v87
	v_cndmask_b32_e64 v191, 0, v191, s[50:51]
	v_add_u32_e32 v88, 11, v84
	v_cmp_gt_u32_e64 s[50:51], s98, v88
	v_cndmask_b32_e64 v192, 0, v192, s[30:31]
	v_add_u32_e32 v85, 16, v84
	v_cmp_gt_u32_e64 s[30:31], s98, v85
	v_cndmask_b32_e64 v193, 0, v193, s[36:37]
	v_add_u32_e32 v86, 17, v84
	v_cmp_gt_u32_e64 s[36:37], s98, v86
	v_cndmask_b32_e64 v194, 0, v194, s[78:79]
	v_add_u32_e32 v87, 18, v84
	v_cmp_gt_u32_e64 s[78:79], s98, v87
	v_cndmask_b32_e64 v195, 0, v195, s[50:51]
	v_add_u32_e32 v88, 19, v84
	v_cmp_gt_u32_e64 s[50:51], s98, v88
	v_cndmask_b32_e64 v196, 0, v196, s[30:31]
	v_add_u32_e32 v85, 24, v84
	v_cmp_gt_u32_e64 s[30:31], s98, v85
	v_cndmask_b32_e64 v197, 0, v197, s[36:37]
	v_add_u32_e32 v86, 25, v84
	v_cmp_gt_u32_e64 s[36:37], s98, v86
	v_cndmask_b32_e64 v198, 0, v198, s[78:79]
	v_add_u32_e32 v87, 26, v84
	v_cmp_gt_u32_e64 s[78:79], s98, v87
	v_cndmask_b32_e64 v199, 0, v199, s[50:51]
	v_add_u32_e32 v88, 27, v84
	v_cmp_gt_u32_e64 s[50:51], s98, v88
	v_nop
	v_cndmask_b32_e64 v200, 0, v200, s[30:31]
	v_cndmask_b32_e64 v201, 0, v201, s[36:37]
	v_cndmask_b32_e64 v202, 0, v202, s[78:79]
	v_cndmask_b32_e64 v203, 0, v203, s[50:51]
	v_cvt_pk_bf16_f32 v64, v188, v189
	v_cvt_pk_bf16_f32 v65, v190, v191
	v_cvt_pk_bf16_f32 v66, v192, v193
	v_cvt_pk_bf16_f32 v67, v194, v195
	v_cvt_pk_bf16_f32 v68, v196, v197
	v_cvt_pk_bf16_f32 v69, v198, v199
	v_cvt_pk_bf16_f32 v70, v200, v201
	v_cvt_pk_bf16_f32 v71, v202, v203
	v_pk_add_f32 v[232:233], v[232:233], v[188:189]
	v_pk_add_f32 v[232:233], v[232:233], v[190:191]
	v_pk_add_f32 v[232:233], v[232:233], v[192:193]
	v_pk_add_f32 v[232:233], v[232:233], v[194:195]
	v_pk_add_f32 v[232:233], v[232:233], v[196:197]
	v_pk_add_f32 v[232:233], v[232:233], v[198:199]
	v_pk_add_f32 v[232:233], v[232:233], v[200:201]
	v_pk_add_f32 v[232:233], v[232:233], v[202:203]
	ds_read2_b32 v[188:189], v115 offset0:34 offset1:35
	ds_read2_b32 v[190:191], v115 offset0:36 offset1:37
	ds_read2_b32 v[192:193], v115 offset0:42 offset1:43
	ds_read2_b32 v[194:195], v115 offset0:44 offset1:45
	ds_read2_b32 v[196:197], v115 offset0:51 offset1:52
	ds_read2_b32 v[198:199], v115 offset0:53 offset1:54
	ds_read2_b32 v[200:201], v115 offset0:59 offset1:60
	ds_read2_b32 v[202:203], v115 offset0:61 offset1:62
	v_mfma_f32_32x32x16_bf16 v[0:15], v[64:67], v[72:75], v[0:15]
	v_mfma_f32_32x32x16_bf16 v[16:31], v[64:67], v[76:79], v[16:31]
	v_mfma_f32_32x32x16_bf16 v[0:15], v[68:71], v[220:223], v[0:15]
	v_mfma_f32_32x32x16_bf16 v[16:31], v[68:71], v[224:227], v[16:31]
	s_add_i32 s90, s76, 448
	v_add_u32_e32 v80, s90, v235
	v_add_u32_e32 v83, s90, v236
	v_add_u32_e32 v99, s90, v237
	v_add_u32_e32 v253, s90, v238
	v_add_u32_e32 v254, s90, v100
	v_add_u32_e32 v255, s90, v149
	v_med3_i32 v80, v80, 0, s99
	v_med3_i32 v83, v83, 0, s99
	v_med3_i32 v99, v99, 0, s99
	v_med3_i32 v253, v253, 0, s99
	v_med3_i32 v254, v254, 0, s99
	v_med3_i32 v255, v255, 0, s99
	v_mad_u32_u24 v80, v80, s100, v252
	v_mad_u32_u24 v83, v83, s100, v252
	v_mad_u32_u24 v99, v99, s100, v252
	v_mad_u32_u24 v253, v253, s100, v252
	v_mad_u32_u24 v254, v254, s100, v153
	v_mad_u32_u24 v255, v255, s100, v153
	global_load_dwordx4 v[116:119], v80, s[82:83]
	global_load_dwordx4 v[120:123], v83, s[82:83]
	global_load_dwordx4 v[124:127], v99, s[82:83]
	global_load_dwordx4 v[128:131], v253, s[82:83]
	global_load_dwordx4 v[132:135], v254, s[82:83] offset:768
	global_load_dwordx4 v[136:139], v255, s[82:83] offset:768
	global_load_dwordx4 v[140:143], v254, s[82:83] offset:832
	global_load_dwordx4 v[144:147], v255, s[82:83] offset:832
	ds_read_b64_tr_b16 v[72:73], v231
	ds_read_b64_tr_b16 v[74:75], v231 offset:512
	ds_read_b64_tr_b16 v[76:77], v231 offset:2048
	ds_read_b64_tr_b16 v[78:79], v231 offset:2560
	ds_read_b64_tr_b16 v[220:221], v231 offset:1024
	ds_read_b64_tr_b16 v[222:223], v231 offset:1536
	ds_read_b64_tr_b16 v[224:225], v231 offset:3072
	ds_read_b64_tr_b16 v[226:227], v231 offset:3584
	v_exp_f32_e32 v32, v32
	v_exp_f32_e32 v33, v33
	v_exp_f32_e32 v34, v34
	v_exp_f32_e32 v35, v35
	s_waitcnt vmcnt(12)
	ds_write_b128 v247, v[156:159]
	ds_write_b128 v247, v[160:163] offset:1024
	ds_write_b128 v247, v[164:167] offset:2048
	ds_write_b128 v247, v[168:171] offset:3072
	ds_read_b128 v[156:159], v248
	ds_read_b128 v[160:163], v249
	ds_read_b128 v[164:167], v250
	ds_read_b128 v[168:171], v251
	s_waitcnt vmcnt(8)
	ds_write_b128 v112, v[172:175]
	ds_write_b128 v112, v[176:179] offset:1024
	ds_write_b128 v112, v[180:183] offset:2048
	ds_write_b128 v112, v[184:187] offset:3072
	v_exp_f32_e32 v36, v36
	v_exp_f32_e32 v37, v37
	v_exp_f32_e32 v38, v38
	v_exp_f32_e32 v39, v39
	s_waitcnt lgkmcnt(4)
	v_mfma_f32_32x32x16_bf16 v[188:203], v[156:159], v[48:51], v[188:203]
	v_exp_f32_e32 v40, v40
	v_exp_f32_e32 v41, v41
	v_mfma_f32_32x32x16_bf16 v[188:203], v[160:163], v[52:55], v[188:203]
	v_exp_f32_e32 v42, v42
	v_exp_f32_e32 v43, v43
	v_mfma_f32_32x32x16_bf16 v[188:203], v[164:167], v[56:59], v[188:203]
	v_exp_f32_e32 v44, v44
	v_exp_f32_e32 v45, v45
	v_mfma_f32_32x32x16_bf16 v[188:203], v[168:171], v[60:63], v[188:203]
	v_exp_f32_e32 v46, v46
	v_exp_f32_e32 v47, v47
	s_add_i32 s90, s76, 384
	v_add_u32_e32 v84, s90, v107
	v_add_u32_e32 v85, 0, v84
	v_add_u32_e32 v86, 1, v84
	v_add_u32_e32 v87, 2, v84
	v_add_u32_e32 v88, 3, v84
	v_cmp_gt_u32_e64 s[30:31], s98, v85
	v_cmp_gt_u32_e64 s[36:37], s98, v86
	v_cmp_gt_u32_e64 s[78:79], s98, v87
	v_cmp_gt_u32_e64 s[50:51], s98, v88
	v_cndmask_b32_e64 v32, 0, v32, s[30:31]
	v_add_u32_e32 v85, 8, v84
	v_cmp_gt_u32_e64 s[30:31], s98, v85
	v_cndmask_b32_e64 v33, 0, v33, s[36:37]
	v_add_u32_e32 v86, 9, v84
	v_cmp_gt_u32_e64 s[36:37], s98, v86
	v_cndmask_b32_e64 v34, 0, v34, s[78:79]
	v_add_u32_e32 v87, 10, v84
	v_cmp_gt_u32_e64 s[78:79], s98, v87
	v_cndmask_b32_e64 v35, 0, v35, s[50:51]
	v_add_u32_e32 v88, 11, v84
	v_cmp_gt_u32_e64 s[50:51], s98, v88
	v_cndmask_b32_e64 v36, 0, v36, s[30:31]
	v_add_u32_e32 v85, 16, v84
	v_cmp_gt_u32_e64 s[30:31], s98, v85
	v_cndmask_b32_e64 v37, 0, v37, s[36:37]
	v_add_u32_e32 v86, 17, v84
	v_cmp_gt_u32_e64 s[36:37], s98, v86
	v_cndmask_b32_e64 v38, 0, v38, s[78:79]
	v_add_u32_e32 v87, 18, v84
	v_cmp_gt_u32_e64 s[78:79], s98, v87
	v_cndmask_b32_e64 v39, 0, v39, s[50:51]
	v_add_u32_e32 v88, 19, v84
	v_cmp_gt_u32_e64 s[50:51], s98, v88
	v_cndmask_b32_e64 v40, 0, v40, s[30:31]
	v_add_u32_e32 v85, 24, v84
	v_cmp_gt_u32_e64 s[30:31], s98, v85
	v_cndmask_b32_e64 v41, 0, v41, s[36:37]
	v_add_u32_e32 v86, 25, v84
	v_cmp_gt_u32_e64 s[36:37], s98, v86
	v_cndmask_b32_e64 v42, 0, v42, s[78:79]
	v_add_u32_e32 v87, 26, v84
	v_cmp_gt_u32_e64 s[78:79], s98, v87
	v_cndmask_b32_e64 v43, 0, v43, s[50:51]
	v_add_u32_e32 v88, 27, v84
	v_cmp_gt_u32_e64 s[50:51], s98, v88
	v_nop
	v_cndmask_b32_e64 v44, 0, v44, s[30:31]
	v_cndmask_b32_e64 v45, 0, v45, s[36:37]
	v_cndmask_b32_e64 v46, 0, v46, s[78:79]
	v_cndmask_b32_e64 v47, 0, v47, s[50:51]
	v_cvt_pk_bf16_f32 v64, v32, v33
	v_cvt_pk_bf16_f32 v65, v34, v35
	v_cvt_pk_bf16_f32 v66, v36, v37
	v_cvt_pk_bf16_f32 v67, v38, v39
	v_cvt_pk_bf16_f32 v68, v40, v41
	v_cvt_pk_bf16_f32 v69, v42, v43
	v_cvt_pk_bf16_f32 v70, v44, v45
	v_cvt_pk_bf16_f32 v71, v46, v47
	v_pk_add_f32 v[232:233], v[232:233], v[32:33]
	v_pk_add_f32 v[232:233], v[232:233], v[34:35]
	v_pk_add_f32 v[232:233], v[232:233], v[36:37]
	v_pk_add_f32 v[232:233], v[232:233], v[38:39]
	v_pk_add_f32 v[232:233], v[232:233], v[40:41]
	v_pk_add_f32 v[232:233], v[232:233], v[42:43]
	v_pk_add_f32 v[232:233], v[232:233], v[44:45]
	v_pk_add_f32 v[232:233], v[232:233], v[46:47]
	ds_read2_b32 v[32:33], v115 offset0:68 offset1:69
	ds_read2_b32 v[34:35], v115 offset0:70 offset1:71
	ds_read2_b32 v[36:37], v115 offset0:76 offset1:77
	ds_read2_b32 v[38:39], v115 offset0:78 offset1:79
	ds_read2_b32 v[40:41], v115 offset0:85 offset1:86
	ds_read2_b32 v[42:43], v115 offset0:87 offset1:88
	ds_read2_b32 v[44:45], v115 offset0:93 offset1:94
	ds_read2_b32 v[46:47], v115 offset0:95 offset1:96
	v_mfma_f32_32x32x16_bf16 v[0:15], v[64:67], v[72:75], v[0:15]
	v_mfma_f32_32x32x16_bf16 v[16:31], v[64:67], v[76:79], v[16:31]
	v_mfma_f32_32x32x16_bf16 v[0:15], v[68:71], v[220:223], v[0:15]
	v_mfma_f32_32x32x16_bf16 v[16:31], v[68:71], v[224:227], v[16:31]
	s_add_i32 s90, s76, 480
	v_add_u32_e32 v80, s90, v235
	v_add_u32_e32 v83, s90, v236
	v_add_u32_e32 v99, s90, v237
	v_add_u32_e32 v253, s90, v238
	v_add_u32_e32 v254, s90, v100
	v_add_u32_e32 v255, s90, v149
	v_med3_i32 v80, v80, 0, s99
	v_med3_i32 v83, v83, 0, s99
	v_med3_i32 v99, v99, 0, s99
	v_med3_i32 v253, v253, 0, s99
	v_med3_i32 v254, v254, 0, s99
	v_med3_i32 v255, v255, 0, s99
	v_mad_u32_u24 v80, v80, s100, v252
	v_mad_u32_u24 v83, v83, s100, v252
	v_mad_u32_u24 v99, v99, s100, v252
	v_mad_u32_u24 v253, v253, s100, v252
	v_mad_u32_u24 v254, v254, s100, v153
	v_mad_u32_u24 v255, v255, s100, v153
	global_load_dwordx4 v[156:159], v80, s[82:83]
	global_load_dwordx4 v[160:163], v83, s[82:83]
	global_load_dwordx4 v[164:167], v99, s[82:83]
	global_load_dwordx4 v[168:171], v253, s[82:83]
	global_load_dwordx4 v[172:175], v254, s[82:83] offset:768
	global_load_dwordx4 v[176:179], v255, s[82:83] offset:768
	global_load_dwordx4 v[180:183], v254, s[82:83] offset:832
	global_load_dwordx4 v[184:187], v255, s[82:83] offset:832
	ds_read_b64_tr_b16 v[72:73], v231
	ds_read_b64_tr_b16 v[74:75], v231 offset:512
	ds_read_b64_tr_b16 v[76:77], v231 offset:2048
	ds_read_b64_tr_b16 v[78:79], v231 offset:2560
	ds_read_b64_tr_b16 v[220:221], v231 offset:1024
	ds_read_b64_tr_b16 v[222:223], v231 offset:1536
	ds_read_b64_tr_b16 v[224:225], v231 offset:3072
	ds_read_b64_tr_b16 v[226:227], v231 offset:3584
	v_exp_f32_e32 v188, v188
	v_exp_f32_e32 v189, v189
	v_exp_f32_e32 v190, v190
	v_exp_f32_e32 v191, v191
	s_waitcnt vmcnt(12)
	ds_write_b128 v247, v[116:119]
	ds_write_b128 v247, v[120:123] offset:1024
	ds_write_b128 v247, v[124:127] offset:2048
	ds_write_b128 v247, v[128:131] offset:3072
	ds_read_b128 v[116:119], v248
	ds_read_b128 v[120:123], v249
	ds_read_b128 v[124:127], v250
	ds_read_b128 v[128:131], v251
	s_waitcnt vmcnt(8)
	ds_write_b128 v112, v[132:135]
	ds_write_b128 v112, v[136:139] offset:1024
	ds_write_b128 v112, v[140:143] offset:2048
	ds_write_b128 v112, v[144:147] offset:3072
	v_exp_f32_e32 v192, v192
	v_exp_f32_e32 v193, v193
	v_exp_f32_e32 v194, v194
	v_exp_f32_e32 v195, v195
	s_waitcnt lgkmcnt(4)
	v_mfma_f32_32x32x16_bf16 v[32:47], v[116:119], v[48:51], v[32:47]
	v_exp_f32_e32 v196, v196
	v_exp_f32_e32 v197, v197
	v_mfma_f32_32x32x16_bf16 v[32:47], v[120:123], v[52:55], v[32:47]
	v_exp_f32_e32 v198, v198
	v_exp_f32_e32 v199, v199
	v_mfma_f32_32x32x16_bf16 v[32:47], v[124:127], v[56:59], v[32:47]
	v_exp_f32_e32 v200, v200
	v_exp_f32_e32 v201, v201
	v_mfma_f32_32x32x16_bf16 v[32:47], v[128:131], v[60:63], v[32:47]
	v_exp_f32_e32 v202, v202
	v_exp_f32_e32 v203, v203
	s_add_i32 s90, s76, 416
	v_add_u32_e32 v84, s90, v107
	v_add_u32_e32 v85, 0, v84
	v_add_u32_e32 v86, 1, v84
	v_add_u32_e32 v87, 2, v84
	v_add_u32_e32 v88, 3, v84
	v_cmp_gt_u32_e64 s[30:31], s98, v85
	v_cmp_gt_u32_e64 s[36:37], s98, v86
	v_cmp_gt_u32_e64 s[78:79], s98, v87
	v_cmp_gt_u32_e64 s[50:51], s98, v88
	v_cndmask_b32_e64 v188, 0, v188, s[30:31]
	v_add_u32_e32 v85, 8, v84
	v_cmp_gt_u32_e64 s[30:31], s98, v85
	v_cndmask_b32_e64 v189, 0, v189, s[36:37]
	v_add_u32_e32 v86, 9, v84
	v_cmp_gt_u32_e64 s[36:37], s98, v86
	v_cndmask_b32_e64 v190, 0, v190, s[78:79]
	v_add_u32_e32 v87, 10, v84
	v_cmp_gt_u32_e64 s[78:79], s98, v87
	v_cndmask_b32_e64 v191, 0, v191, s[50:51]
	v_add_u32_e32 v88, 11, v84
	v_cmp_gt_u32_e64 s[50:51], s98, v88
	v_cndmask_b32_e64 v192, 0, v192, s[30:31]
	v_add_u32_e32 v85, 16, v84
	v_cmp_gt_u32_e64 s[30:31], s98, v85
	v_cndmask_b32_e64 v193, 0, v193, s[36:37]
	v_add_u32_e32 v86, 17, v84
	v_cmp_gt_u32_e64 s[36:37], s98, v86
	v_cndmask_b32_e64 v194, 0, v194, s[78:79]
	v_add_u32_e32 v87, 18, v84
	v_cmp_gt_u32_e64 s[78:79], s98, v87
	v_cndmask_b32_e64 v195, 0, v195, s[50:51]
	v_add_u32_e32 v88, 19, v84
	v_cmp_gt_u32_e64 s[50:51], s98, v88
	v_cndmask_b32_e64 v196, 0, v196, s[30:31]
	v_add_u32_e32 v85, 24, v84
	v_cmp_gt_u32_e64 s[30:31], s98, v85
	v_cndmask_b32_e64 v197, 0, v197, s[36:37]
	v_add_u32_e32 v86, 25, v84
	v_cmp_gt_u32_e64 s[36:37], s98, v86
	v_cndmask_b32_e64 v198, 0, v198, s[78:79]
	v_add_u32_e32 v87, 26, v84
	v_cmp_gt_u32_e64 s[78:79], s98, v87
	v_cndmask_b32_e64 v199, 0, v199, s[50:51]
	v_add_u32_e32 v88, 27, v84
	v_cmp_gt_u32_e64 s[50:51], s98, v88
	v_nop
	v_cndmask_b32_e64 v200, 0, v200, s[30:31]
	v_cndmask_b32_e64 v201, 0, v201, s[36:37]
	v_cndmask_b32_e64 v202, 0, v202, s[78:79]
	v_cndmask_b32_e64 v203, 0, v203, s[50:51]
	v_cvt_pk_bf16_f32 v64, v188, v189
	v_cvt_pk_bf16_f32 v65, v190, v191
	v_cvt_pk_bf16_f32 v66, v192, v193
	v_cvt_pk_bf16_f32 v67, v194, v195
	v_cvt_pk_bf16_f32 v68, v196, v197
	v_cvt_pk_bf16_f32 v69, v198, v199
	v_cvt_pk_bf16_f32 v70, v200, v201
	v_cvt_pk_bf16_f32 v71, v202, v203
	v_pk_add_f32 v[232:233], v[232:233], v[188:189]
	v_pk_add_f32 v[232:233], v[232:233], v[190:191]
	v_pk_add_f32 v[232:233], v[232:233], v[192:193]
	v_pk_add_f32 v[232:233], v[232:233], v[194:195]
	v_pk_add_f32 v[232:233], v[232:233], v[196:197]
	v_pk_add_f32 v[232:233], v[232:233], v[198:199]
	v_pk_add_f32 v[232:233], v[232:233], v[200:201]
	v_pk_add_f32 v[232:233], v[232:233], v[202:203]
	ds_read2_b32 v[188:189], v115 offset0:102 offset1:103
	ds_read2_b32 v[190:191], v115 offset0:104 offset1:105
	ds_read2_b32 v[192:193], v115 offset0:110 offset1:111
	ds_read2_b32 v[194:195], v115 offset0:112 offset1:113
	ds_read2_b32 v[196:197], v115 offset0:119 offset1:120
	ds_read2_b32 v[198:199], v115 offset0:121 offset1:122
	ds_read2_b32 v[200:201], v115 offset0:127 offset1:128
	ds_read2_b32 v[202:203], v115 offset0:129 offset1:130
	v_mfma_f32_32x32x16_bf16 v[0:15], v[64:67], v[72:75], v[0:15]
	v_mfma_f32_32x32x16_bf16 v[16:31], v[64:67], v[76:79], v[16:31]
	v_mfma_f32_32x32x16_bf16 v[0:15], v[68:71], v[220:223], v[0:15]
	v_mfma_f32_32x32x16_bf16 v[16:31], v[68:71], v[224:227], v[16:31]
	s_add_i32 s90, s76, 512
	v_add_u32_e32 v80, s90, v235
	v_add_u32_e32 v83, s90, v236
	v_add_u32_e32 v99, s90, v237
	v_add_u32_e32 v253, s90, v238
	v_add_u32_e32 v254, s90, v100
	v_add_u32_e32 v255, s90, v149
	v_med3_i32 v80, v80, 0, s99
	v_med3_i32 v83, v83, 0, s99
	v_med3_i32 v99, v99, 0, s99
	v_med3_i32 v253, v253, 0, s99
	v_med3_i32 v254, v254, 0, s99
	v_med3_i32 v255, v255, 0, s99
	v_mad_u32_u24 v80, v80, s100, v252
	v_mad_u32_u24 v83, v83, s100, v252
	v_mad_u32_u24 v99, v99, s100, v252
	v_mad_u32_u24 v253, v253, s100, v252
	v_mad_u32_u24 v254, v254, s100, v153
	v_mad_u32_u24 v255, v255, s100, v153
	global_load_dwordx4 v[116:119], v80, s[82:83]
	global_load_dwordx4 v[120:123], v83, s[82:83]
	global_load_dwordx4 v[124:127], v99, s[82:83]
	global_load_dwordx4 v[128:131], v253, s[82:83]
	global_load_dwordx4 v[132:135], v254, s[82:83] offset:768
	global_load_dwordx4 v[136:139], v255, s[82:83] offset:768
	global_load_dwordx4 v[140:143], v254, s[82:83] offset:832
	global_load_dwordx4 v[144:147], v255, s[82:83] offset:832
	ds_read_b64_tr_b16 v[72:73], v231
	ds_read_b64_tr_b16 v[74:75], v231 offset:512
	ds_read_b64_tr_b16 v[76:77], v231 offset:2048
	ds_read_b64_tr_b16 v[78:79], v231 offset:2560
	ds_read_b64_tr_b16 v[220:221], v231 offset:1024
	ds_read_b64_tr_b16 v[222:223], v231 offset:1536
	ds_read_b64_tr_b16 v[224:225], v231 offset:3072
	ds_read_b64_tr_b16 v[226:227], v231 offset:3584
	v_exp_f32_e32 v32, v32
	v_exp_f32_e32 v33, v33
	v_exp_f32_e32 v34, v34
	v_exp_f32_e32 v35, v35
	s_waitcnt vmcnt(12)
	ds_write_b128 v247, v[156:159]
	ds_write_b128 v247, v[160:163] offset:1024
	ds_write_b128 v247, v[164:167] offset:2048
	ds_write_b128 v247, v[168:171] offset:3072
	ds_read_b128 v[156:159], v248
	ds_read_b128 v[160:163], v249
	ds_read_b128 v[164:167], v250
	ds_read_b128 v[168:171], v251
	s_waitcnt vmcnt(8)
	ds_write_b128 v112, v[172:175]
	ds_write_b128 v112, v[176:179] offset:1024
	ds_write_b128 v112, v[180:183] offset:2048
	ds_write_b128 v112, v[184:187] offset:3072
	v_exp_f32_e32 v36, v36
	v_exp_f32_e32 v37, v37
	v_exp_f32_e32 v38, v38
	v_exp_f32_e32 v39, v39
	s_waitcnt lgkmcnt(4)
	v_mfma_f32_32x32x16_bf16 v[188:203], v[156:159], v[48:51], v[188:203]
	v_exp_f32_e32 v40, v40
	v_exp_f32_e32 v41, v41
	v_mfma_f32_32x32x16_bf16 v[188:203], v[160:163], v[52:55], v[188:203]
	v_exp_f32_e32 v42, v42
	v_exp_f32_e32 v43, v43
	v_mfma_f32_32x32x16_bf16 v[188:203], v[164:167], v[56:59], v[188:203]
	v_exp_f32_e32 v44, v44
	v_exp_f32_e32 v45, v45
	v_mfma_f32_32x32x16_bf16 v[188:203], v[168:171], v[60:63], v[188:203]
	v_exp_f32_e32 v46, v46
	v_exp_f32_e32 v47, v47
	s_add_i32 s90, s76, 448
	v_add_u32_e32 v84, s90, v107
	v_add_u32_e32 v85, 0, v84
	v_add_u32_e32 v86, 1, v84
	v_add_u32_e32 v87, 2, v84
	v_add_u32_e32 v88, 3, v84
	v_cmp_gt_u32_e64 s[30:31], s98, v85
	v_cmp_gt_u32_e64 s[36:37], s98, v86
	v_cmp_gt_u32_e64 s[78:79], s98, v87
	v_cmp_gt_u32_e64 s[50:51], s98, v88
	v_cndmask_b32_e64 v32, 0, v32, s[30:31]
	v_add_u32_e32 v85, 8, v84
	v_cmp_gt_u32_e64 s[30:31], s98, v85
	v_cndmask_b32_e64 v33, 0, v33, s[36:37]
	v_add_u32_e32 v86, 9, v84
	v_cmp_gt_u32_e64 s[36:37], s98, v86
	v_cndmask_b32_e64 v34, 0, v34, s[78:79]
	v_add_u32_e32 v87, 10, v84
	v_cmp_gt_u32_e64 s[78:79], s98, v87
	v_cndmask_b32_e64 v35, 0, v35, s[50:51]
	v_add_u32_e32 v88, 11, v84
	v_cmp_gt_u32_e64 s[50:51], s98, v88
	v_cndmask_b32_e64 v36, 0, v36, s[30:31]
	v_add_u32_e32 v85, 16, v84
	v_cmp_gt_u32_e64 s[30:31], s98, v85
	v_cndmask_b32_e64 v37, 0, v37, s[36:37]
	v_add_u32_e32 v86, 17, v84
	v_cmp_gt_u32_e64 s[36:37], s98, v86
	v_cndmask_b32_e64 v38, 0, v38, s[78:79]
	v_add_u32_e32 v87, 18, v84
	v_cmp_gt_u32_e64 s[78:79], s98, v87
	v_cndmask_b32_e64 v39, 0, v39, s[50:51]
	v_add_u32_e32 v88, 19, v84
	v_cmp_gt_u32_e64 s[50:51], s98, v88
	v_cndmask_b32_e64 v40, 0, v40, s[30:31]
	v_add_u32_e32 v85, 24, v84
	v_cmp_gt_u32_e64 s[30:31], s98, v85
	v_cndmask_b32_e64 v41, 0, v41, s[36:37]
	v_add_u32_e32 v86, 25, v84
	v_cmp_gt_u32_e64 s[36:37], s98, v86
	v_cndmask_b32_e64 v42, 0, v42, s[78:79]
	v_add_u32_e32 v87, 26, v84
	v_cmp_gt_u32_e64 s[78:79], s98, v87
	v_cndmask_b32_e64 v43, 0, v43, s[50:51]
	v_add_u32_e32 v88, 27, v84
	v_cmp_gt_u32_e64 s[50:51], s98, v88
	v_nop
	v_cndmask_b32_e64 v44, 0, v44, s[30:31]
	v_cndmask_b32_e64 v45, 0, v45, s[36:37]
	v_cndmask_b32_e64 v46, 0, v46, s[78:79]
	v_cndmask_b32_e64 v47, 0, v47, s[50:51]
	v_cvt_pk_bf16_f32 v64, v32, v33
	v_cvt_pk_bf16_f32 v65, v34, v35
	v_cvt_pk_bf16_f32 v66, v36, v37
	v_cvt_pk_bf16_f32 v67, v38, v39
	v_cvt_pk_bf16_f32 v68, v40, v41
	v_cvt_pk_bf16_f32 v69, v42, v43
	v_cvt_pk_bf16_f32 v70, v44, v45
	v_cvt_pk_bf16_f32 v71, v46, v47
	v_pk_add_f32 v[232:233], v[232:233], v[32:33]
	v_pk_add_f32 v[232:233], v[232:233], v[34:35]
	v_pk_add_f32 v[232:233], v[232:233], v[36:37]
	v_pk_add_f32 v[232:233], v[232:233], v[38:39]
	v_pk_add_f32 v[232:233], v[232:233], v[40:41]
	v_pk_add_f32 v[232:233], v[232:233], v[42:43]
	v_pk_add_f32 v[232:233], v[232:233], v[44:45]
	v_pk_add_f32 v[232:233], v[232:233], v[46:47]
	ds_read2_b32 v[32:33], v115 offset0:136 offset1:137
	ds_read2_b32 v[34:35], v115 offset0:138 offset1:139
	ds_read2_b32 v[36:37], v115 offset0:144 offset1:145
	ds_read2_b32 v[38:39], v115 offset0:146 offset1:147
	ds_read2_b32 v[40:41], v115 offset0:153 offset1:154
	ds_read2_b32 v[42:43], v115 offset0:155 offset1:156
	ds_read2_b32 v[44:45], v115 offset0:161 offset1:162
	ds_read2_b32 v[46:47], v115 offset0:163 offset1:164
	v_mfma_f32_32x32x16_bf16 v[0:15], v[64:67], v[72:75], v[0:15]
	v_mfma_f32_32x32x16_bf16 v[16:31], v[64:67], v[76:79], v[16:31]
	v_mfma_f32_32x32x16_bf16 v[0:15], v[68:71], v[220:223], v[0:15]
	v_mfma_f32_32x32x16_bf16 v[16:31], v[68:71], v[224:227], v[16:31]
	s_add_i32 s90, s76, 544
	v_add_u32_e32 v80, s90, v235
	v_add_u32_e32 v83, s90, v236
	v_add_u32_e32 v99, s90, v237
	v_add_u32_e32 v253, s90, v238
	v_add_u32_e32 v254, s90, v100
	v_add_u32_e32 v255, s90, v149
	v_med3_i32 v80, v80, 0, s99
	v_med3_i32 v83, v83, 0, s99
	v_med3_i32 v99, v99, 0, s99
	v_med3_i32 v253, v253, 0, s99
	v_med3_i32 v254, v254, 0, s99
	v_med3_i32 v255, v255, 0, s99
	v_mad_u32_u24 v80, v80, s100, v252
	v_mad_u32_u24 v83, v83, s100, v252
	v_mad_u32_u24 v99, v99, s100, v252
	v_mad_u32_u24 v253, v253, s100, v252
	v_mad_u32_u24 v254, v254, s100, v153
	v_mad_u32_u24 v255, v255, s100, v153
	global_load_dwordx4 v[156:159], v80, s[82:83]
	global_load_dwordx4 v[160:163], v83, s[82:83]
	global_load_dwordx4 v[164:167], v99, s[82:83]
	global_load_dwordx4 v[168:171], v253, s[82:83]
	global_load_dwordx4 v[172:175], v254, s[82:83] offset:768
	global_load_dwordx4 v[176:179], v255, s[82:83] offset:768
	global_load_dwordx4 v[180:183], v254, s[82:83] offset:832
	global_load_dwordx4 v[184:187], v255, s[82:83] offset:832
	ds_read_b64_tr_b16 v[72:73], v231
	ds_read_b64_tr_b16 v[74:75], v231 offset:512
	ds_read_b64_tr_b16 v[76:77], v231 offset:2048
	ds_read_b64_tr_b16 v[78:79], v231 offset:2560
	ds_read_b64_tr_b16 v[220:221], v231 offset:1024
	ds_read_b64_tr_b16 v[222:223], v231 offset:1536
	ds_read_b64_tr_b16 v[224:225], v231 offset:3072
	ds_read_b64_tr_b16 v[226:227], v231 offset:3584
	v_exp_f32_e32 v188, v188
	v_exp_f32_e32 v189, v189
	v_exp_f32_e32 v190, v190
	v_exp_f32_e32 v191, v191
	s_waitcnt vmcnt(12)
	ds_write_b128 v247, v[116:119]
	ds_write_b128 v247, v[120:123] offset:1024
	ds_write_b128 v247, v[124:127] offset:2048
	ds_write_b128 v247, v[128:131] offset:3072
	ds_read_b128 v[116:119], v248
	ds_read_b128 v[120:123], v249
	ds_read_b128 v[124:127], v250
	ds_read_b128 v[128:131], v251
	s_waitcnt vmcnt(8)
	ds_write_b128 v112, v[132:135]
	ds_write_b128 v112, v[136:139] offset:1024
	ds_write_b128 v112, v[140:143] offset:2048
	ds_write_b128 v112, v[144:147] offset:3072
	v_exp_f32_e32 v192, v192
	v_exp_f32_e32 v193, v193
	v_exp_f32_e32 v194, v194
	v_exp_f32_e32 v195, v195
	s_waitcnt lgkmcnt(4)
	v_mfma_f32_32x32x16_bf16 v[32:47], v[116:119], v[48:51], v[32:47]
	v_exp_f32_e32 v196, v196
	v_exp_f32_e32 v197, v197
	v_mfma_f32_32x32x16_bf16 v[32:47], v[120:123], v[52:55], v[32:47]
	v_exp_f32_e32 v198, v198
	v_exp_f32_e32 v199, v199
	v_mfma_f32_32x32x16_bf16 v[32:47], v[124:127], v[56:59], v[32:47]
	v_exp_f32_e32 v200, v200
	v_exp_f32_e32 v201, v201
	v_mfma_f32_32x32x16_bf16 v[32:47], v[128:131], v[60:63], v[32:47]
	v_exp_f32_e32 v202, v202
	v_exp_f32_e32 v203, v203
	s_add_i32 s90, s76, 480
	v_add_u32_e32 v84, s90, v107
	v_add_u32_e32 v85, 0, v84
	v_add_u32_e32 v86, 1, v84
	v_add_u32_e32 v87, 2, v84
	v_add_u32_e32 v88, 3, v84
	v_cmp_gt_u32_e64 s[30:31], s98, v85
	v_cmp_gt_u32_e64 s[36:37], s98, v86
	v_cmp_gt_u32_e64 s[78:79], s98, v87
	v_cmp_gt_u32_e64 s[50:51], s98, v88
	v_cndmask_b32_e64 v188, 0, v188, s[30:31]
	v_add_u32_e32 v85, 8, v84
	v_cmp_gt_u32_e64 s[30:31], s98, v85
	v_cndmask_b32_e64 v189, 0, v189, s[36:37]
	v_add_u32_e32 v86, 9, v84
	v_cmp_gt_u32_e64 s[36:37], s98, v86
	v_cndmask_b32_e64 v190, 0, v190, s[78:79]
	v_add_u32_e32 v87, 10, v84
	v_cmp_gt_u32_e64 s[78:79], s98, v87
	v_cndmask_b32_e64 v191, 0, v191, s[50:51]
	v_add_u32_e32 v88, 11, v84
	v_cmp_gt_u32_e64 s[50:51], s98, v88
	v_cndmask_b32_e64 v192, 0, v192, s[30:31]
	v_add_u32_e32 v85, 16, v84
	v_cmp_gt_u32_e64 s[30:31], s98, v85
	v_cndmask_b32_e64 v193, 0, v193, s[36:37]
	v_add_u32_e32 v86, 17, v84
	v_cmp_gt_u32_e64 s[36:37], s98, v86
	v_cndmask_b32_e64 v194, 0, v194, s[78:79]
	v_add_u32_e32 v87, 18, v84
	v_cmp_gt_u32_e64 s[78:79], s98, v87
	v_cndmask_b32_e64 v195, 0, v195, s[50:51]
	v_add_u32_e32 v88, 19, v84
	v_cmp_gt_u32_e64 s[50:51], s98, v88
	v_cndmask_b32_e64 v196, 0, v196, s[30:31]
	v_add_u32_e32 v85, 24, v84
	v_cmp_gt_u32_e64 s[30:31], s98, v85
	v_cndmask_b32_e64 v197, 0, v197, s[36:37]
	v_add_u32_e32 v86, 25, v84
	v_cmp_gt_u32_e64 s[36:37], s98, v86
	v_cndmask_b32_e64 v198, 0, v198, s[78:79]
	v_add_u32_e32 v87, 26, v84
	v_cmp_gt_u32_e64 s[78:79], s98, v87
	v_cndmask_b32_e64 v199, 0, v199, s[50:51]
	v_add_u32_e32 v88, 27, v84
	v_cmp_gt_u32_e64 s[50:51], s98, v88
	v_nop
	v_cndmask_b32_e64 v200, 0, v200, s[30:31]
	v_cndmask_b32_e64 v201, 0, v201, s[36:37]
	v_cndmask_b32_e64 v202, 0, v202, s[78:79]
	v_cndmask_b32_e64 v203, 0, v203, s[50:51]
	v_cvt_pk_bf16_f32 v64, v188, v189
	v_cvt_pk_bf16_f32 v65, v190, v191
	v_cvt_pk_bf16_f32 v66, v192, v193
	v_cvt_pk_bf16_f32 v67, v194, v195
	v_cvt_pk_bf16_f32 v68, v196, v197
	v_cvt_pk_bf16_f32 v69, v198, v199
	v_cvt_pk_bf16_f32 v70, v200, v201
	v_cvt_pk_bf16_f32 v71, v202, v203
	v_pk_add_f32 v[232:233], v[232:233], v[188:189]
	v_pk_add_f32 v[232:233], v[232:233], v[190:191]
	v_pk_add_f32 v[232:233], v[232:233], v[192:193]
	v_pk_add_f32 v[232:233], v[232:233], v[194:195]
	v_pk_add_f32 v[232:233], v[232:233], v[196:197]
	v_pk_add_f32 v[232:233], v[232:233], v[198:199]
	v_pk_add_f32 v[232:233], v[232:233], v[200:201]
	v_pk_add_f32 v[232:233], v[232:233], v[202:203]
	ds_read2_b32 v[188:189], v115 offset0:170 offset1:171
	ds_read2_b32 v[190:191], v115 offset0:172 offset1:173
	ds_read2_b32 v[192:193], v115 offset0:178 offset1:179
	ds_read2_b32 v[194:195], v115 offset0:180 offset1:181
	ds_read2_b32 v[196:197], v115 offset0:187 offset1:188
	ds_read2_b32 v[198:199], v115 offset0:189 offset1:190
	ds_read2_b32 v[200:201], v115 offset0:195 offset1:196
	ds_read2_b32 v[202:203], v115 offset0:197 offset1:198
	v_mfma_f32_32x32x16_bf16 v[0:15], v[64:67], v[72:75], v[0:15]
	v_mfma_f32_32x32x16_bf16 v[16:31], v[64:67], v[76:79], v[16:31]
	v_mfma_f32_32x32x16_bf16 v[0:15], v[68:71], v[220:223], v[0:15]
	v_mfma_f32_32x32x16_bf16 v[16:31], v[68:71], v[224:227], v[16:31]
	s_add_i32 s90, s76, -256
	v_add_u32_e32 v80, s90, v239
	v_add_u32_e32 v83, s90, v240
	v_add_u32_e32 v99, s90, v241
	v_add_u32_e32 v253, s90, v242
	v_add_u32_e32 v254, s90, v101
	v_add_u32_e32 v255, s90, v150
	v_med3_i32 v80, v80, 0, s99
	v_med3_i32 v83, v83, 0, s99
	v_med3_i32 v99, v99, 0, s99
	v_med3_i32 v253, v253, 0, s99
	v_med3_i32 v254, v254, 0, s99
	v_med3_i32 v255, v255, 0, s99
	v_mad_u32_u24 v80, v80, s100, v252
	v_mad_u32_u24 v83, v83, s100, v252
	v_mad_u32_u24 v99, v99, s100, v252
	v_mad_u32_u24 v253, v253, s100, v252
	v_mad_u32_u24 v254, v254, s100, v153
	v_mad_u32_u24 v255, v255, s100, v153
	global_load_dwordx4 v[116:119], v80, s[82:83]
	global_load_dwordx4 v[120:123], v83, s[82:83]
	global_load_dwordx4 v[124:127], v99, s[82:83]
	global_load_dwordx4 v[128:131], v253, s[82:83]
	global_load_dwordx4 v[132:135], v254, s[82:83] offset:768
	global_load_dwordx4 v[136:139], v255, s[82:83] offset:768
	global_load_dwordx4 v[140:143], v254, s[82:83] offset:832
	global_load_dwordx4 v[144:147], v255, s[82:83] offset:832
	ds_read_b64_tr_b16 v[72:73], v231
	ds_read_b64_tr_b16 v[74:75], v231 offset:512
	ds_read_b64_tr_b16 v[76:77], v231 offset:2048
	ds_read_b64_tr_b16 v[78:79], v231 offset:2560
	ds_read_b64_tr_b16 v[220:221], v231 offset:1024
	ds_read_b64_tr_b16 v[222:223], v231 offset:1536
	ds_read_b64_tr_b16 v[224:225], v231 offset:3072
	ds_read_b64_tr_b16 v[226:227], v231 offset:3584
	v_exp_f32_e32 v32, v32
	v_exp_f32_e32 v33, v33
	v_exp_f32_e32 v34, v34
	v_exp_f32_e32 v35, v35
	s_waitcnt vmcnt(12)
	ds_write_b128 v247, v[156:159]
	ds_write_b128 v247, v[160:163] offset:1024
	ds_write_b128 v247, v[164:167] offset:2048
	ds_write_b128 v247, v[168:171] offset:3072
	ds_read_b128 v[156:159], v248
	ds_read_b128 v[160:163], v249
	ds_read_b128 v[164:167], v250
	ds_read_b128 v[168:171], v251
	s_waitcnt vmcnt(8)
	ds_write_b128 v112, v[172:175]
	ds_write_b128 v112, v[176:179] offset:1024
	ds_write_b128 v112, v[180:183] offset:2048
	ds_write_b128 v112, v[184:187] offset:3072
	v_exp_f32_e32 v36, v36
	v_exp_f32_e32 v37, v37
	v_exp_f32_e32 v38, v38
	v_exp_f32_e32 v39, v39
	s_waitcnt lgkmcnt(4)
	v_mfma_f32_32x32x16_bf16 v[188:203], v[156:159], v[48:51], v[188:203]
	v_exp_f32_e32 v40, v40
	v_exp_f32_e32 v41, v41
	v_mfma_f32_32x32x16_bf16 v[188:203], v[160:163], v[52:55], v[188:203]
	v_exp_f32_e32 v42, v42
	v_exp_f32_e32 v43, v43
	v_mfma_f32_32x32x16_bf16 v[188:203], v[164:167], v[56:59], v[188:203]
	v_exp_f32_e32 v44, v44
	v_exp_f32_e32 v45, v45
	v_mfma_f32_32x32x16_bf16 v[188:203], v[168:171], v[60:63], v[188:203]
	v_exp_f32_e32 v46, v46
	v_exp_f32_e32 v47, v47
	s_add_i32 s90, s76, 512
	v_add_u32_e32 v84, s90, v107
	v_add_u32_e32 v85, 0, v84
	v_add_u32_e32 v86, 1, v84
	v_add_u32_e32 v87, 2, v84
	v_add_u32_e32 v88, 3, v84
	v_cmp_gt_u32_e64 s[30:31], s98, v85
	v_cmp_gt_u32_e64 s[36:37], s98, v86
	v_cmp_gt_u32_e64 s[78:79], s98, v87
	v_cmp_gt_u32_e64 s[50:51], s98, v88
	v_cndmask_b32_e64 v32, 0, v32, s[30:31]
	v_add_u32_e32 v85, 8, v84
	v_cmp_gt_u32_e64 s[30:31], s98, v85
	v_cndmask_b32_e64 v33, 0, v33, s[36:37]
	v_add_u32_e32 v86, 9, v84
	v_cmp_gt_u32_e64 s[36:37], s98, v86
	v_cndmask_b32_e64 v34, 0, v34, s[78:79]
	v_add_u32_e32 v87, 10, v84
	v_cmp_gt_u32_e64 s[78:79], s98, v87
	v_cndmask_b32_e64 v35, 0, v35, s[50:51]
	v_add_u32_e32 v88, 11, v84
	v_cmp_gt_u32_e64 s[50:51], s98, v88
	v_cndmask_b32_e64 v36, 0, v36, s[30:31]
	v_add_u32_e32 v85, 16, v84
	v_cmp_gt_u32_e64 s[30:31], s98, v85
	v_cndmask_b32_e64 v37, 0, v37, s[36:37]
	v_add_u32_e32 v86, 17, v84
	v_cmp_gt_u32_e64 s[36:37], s98, v86
	v_cndmask_b32_e64 v38, 0, v38, s[78:79]
	v_add_u32_e32 v87, 18, v84
	v_cmp_gt_u32_e64 s[78:79], s98, v87
	v_cndmask_b32_e64 v39, 0, v39, s[50:51]
	v_add_u32_e32 v88, 19, v84
	v_cmp_gt_u32_e64 s[50:51], s98, v88
	v_cndmask_b32_e64 v40, 0, v40, s[30:31]
	v_add_u32_e32 v85, 24, v84
	v_cmp_gt_u32_e64 s[30:31], s98, v85
	v_cndmask_b32_e64 v41, 0, v41, s[36:37]
	v_add_u32_e32 v86, 25, v84
	v_cmp_gt_u32_e64 s[36:37], s98, v86
	v_cndmask_b32_e64 v42, 0, v42, s[78:79]
	v_add_u32_e32 v87, 26, v84
	v_cmp_gt_u32_e64 s[78:79], s98, v87
	v_cndmask_b32_e64 v43, 0, v43, s[50:51]
	v_add_u32_e32 v88, 27, v84
	v_cmp_gt_u32_e64 s[50:51], s98, v88
	v_nop
	v_cndmask_b32_e64 v44, 0, v44, s[30:31]
	v_cndmask_b32_e64 v45, 0, v45, s[36:37]
	v_cndmask_b32_e64 v46, 0, v46, s[78:79]
	v_cndmask_b32_e64 v47, 0, v47, s[50:51]
	v_cvt_pk_bf16_f32 v64, v32, v33
	v_cvt_pk_bf16_f32 v65, v34, v35
	v_cvt_pk_bf16_f32 v66, v36, v37
	v_cvt_pk_bf16_f32 v67, v38, v39
	v_cvt_pk_bf16_f32 v68, v40, v41
	v_cvt_pk_bf16_f32 v69, v42, v43
	v_cvt_pk_bf16_f32 v70, v44, v45
	v_cvt_pk_bf16_f32 v71, v46, v47
	v_pk_add_f32 v[232:233], v[232:233], v[32:33]
	v_pk_add_f32 v[232:233], v[232:233], v[34:35]
	v_pk_add_f32 v[232:233], v[232:233], v[36:37]
	v_pk_add_f32 v[232:233], v[232:233], v[38:39]
	v_pk_add_f32 v[232:233], v[232:233], v[40:41]
	v_pk_add_f32 v[232:233], v[232:233], v[42:43]
	v_pk_add_f32 v[232:233], v[232:233], v[44:45]
	v_pk_add_f32 v[232:233], v[232:233], v[46:47]
	v_mov_b32_e32 v115, v229
	ds_read2_b32 v[32:33], v115 offset0:0 offset1:1
	ds_read2_b32 v[34:35], v115 offset0:2 offset1:3
	ds_read2_b32 v[36:37], v115 offset0:8 offset1:9
	ds_read2_b32 v[38:39], v115 offset0:10 offset1:11
	ds_read2_b32 v[40:41], v115 offset0:16 offset1:17
	ds_read2_b32 v[42:43], v115 offset0:18 offset1:19
	ds_read2_b32 v[44:45], v115 offset0:24 offset1:25
	ds_read2_b32 v[46:47], v115 offset0:26 offset1:27
	v_mfma_f32_32x32x16_bf16 v[0:15], v[64:67], v[72:75], v[0:15]
	v_mfma_f32_32x32x16_bf16 v[16:31], v[64:67], v[76:79], v[16:31]
	v_mfma_f32_32x32x16_bf16 v[0:15], v[68:71], v[220:223], v[0:15]
	v_mfma_f32_32x32x16_bf16 v[16:31], v[68:71], v[224:227], v[16:31]
	s_add_i32 s90, s76, -128
	v_add_u32_e32 v80, s90, v239
	v_add_u32_e32 v83, s90, v240
	v_add_u32_e32 v99, s90, v241
	v_add_u32_e32 v253, s90, v242
	v_add_u32_e32 v254, s90, v101
	v_add_u32_e32 v255, s90, v150
	v_med3_i32 v80, v80, 0, s99
	v_med3_i32 v83, v83, 0, s99
	v_med3_i32 v99, v99, 0, s99
	v_med3_i32 v253, v253, 0, s99
	v_med3_i32 v254, v254, 0, s99
	v_med3_i32 v255, v255, 0, s99
	v_mad_u32_u24 v80, v80, s100, v252
	v_mad_u32_u24 v83, v83, s100, v252
	v_mad_u32_u24 v99, v99, s100, v252
	v_mad_u32_u24 v253, v253, s100, v252
	v_mad_u32_u24 v254, v254, s100, v153
	v_mad_u32_u24 v255, v255, s100, v153
	global_load_dwordx4 v[156:159], v80, s[82:83]
	global_load_dwordx4 v[160:163], v83, s[82:83]
	global_load_dwordx4 v[164:167], v99, s[82:83]
	global_load_dwordx4 v[168:171], v253, s[82:83]
	global_load_dwordx4 v[172:175], v254, s[82:83] offset:768
	global_load_dwordx4 v[176:179], v255, s[82:83] offset:768
	global_load_dwordx4 v[180:183], v254, s[82:83] offset:832
	global_load_dwordx4 v[184:187], v255, s[82:83] offset:832
	ds_read_b64_tr_b16 v[72:73], v231
	ds_read_b64_tr_b16 v[74:75], v231 offset:512
	ds_read_b64_tr_b16 v[76:77], v231 offset:2048
	ds_read_b64_tr_b16 v[78:79], v231 offset:2560
	ds_read_b64_tr_b16 v[220:221], v231 offset:1024
	ds_read_b64_tr_b16 v[222:223], v231 offset:1536
	ds_read_b64_tr_b16 v[224:225], v231 offset:3072
	ds_read_b64_tr_b16 v[226:227], v231 offset:3584
	v_exp_f32_e32 v188, v188
	v_exp_f32_e32 v189, v189
	v_exp_f32_e32 v190, v190
	v_exp_f32_e32 v191, v191
	s_waitcnt vmcnt(12)
	ds_write_b128 v247, v[116:119]
	ds_write_b128 v247, v[120:123] offset:1024
	ds_write_b128 v247, v[124:127] offset:2048
	ds_write_b128 v247, v[128:131] offset:3072
	ds_read_b128 v[116:119], v248
	ds_read_b128 v[120:123], v249
	ds_read_b128 v[124:127], v250
	ds_read_b128 v[128:131], v251
	s_waitcnt vmcnt(8)
	ds_write_b128 v112, v[132:135]
	ds_write_b128 v112, v[136:139] offset:1024
	ds_write_b128 v112, v[140:143] offset:2048
	ds_write_b128 v112, v[144:147] offset:3072
	v_exp_f32_e32 v192, v192
	v_exp_f32_e32 v193, v193
	v_exp_f32_e32 v194, v194
	v_exp_f32_e32 v195, v195
	s_waitcnt lgkmcnt(4)
	v_mfma_f32_32x32x16_bf16 v[32:47], v[116:119], v[48:51], v[32:47]
	v_exp_f32_e32 v196, v196
	v_exp_f32_e32 v197, v197
	v_mfma_f32_32x32x16_bf16 v[32:47], v[120:123], v[52:55], v[32:47]
	v_exp_f32_e32 v198, v198
	v_exp_f32_e32 v199, v199
	v_mfma_f32_32x32x16_bf16 v[32:47], v[124:127], v[56:59], v[32:47]
	v_exp_f32_e32 v200, v200
	v_exp_f32_e32 v201, v201
	v_mfma_f32_32x32x16_bf16 v[32:47], v[128:131], v[60:63], v[32:47]
	v_exp_f32_e32 v202, v202
	v_exp_f32_e32 v203, v203
	s_add_i32 s90, s76, 544
	v_add_u32_e32 v84, s90, v107
	v_add_u32_e32 v85, 0, v84
	v_add_u32_e32 v86, 1, v84
	v_add_u32_e32 v87, 2, v84
	v_add_u32_e32 v88, 3, v84
	v_cmp_gt_u32_e64 s[30:31], s98, v85
	v_cmp_gt_u32_e64 s[36:37], s98, v86
	v_cmp_gt_u32_e64 s[78:79], s98, v87
	v_cmp_gt_u32_e64 s[50:51], s98, v88
	v_cndmask_b32_e64 v188, 0, v188, s[30:31]
	v_add_u32_e32 v85, 8, v84
	v_cmp_gt_u32_e64 s[30:31], s98, v85
	v_cndmask_b32_e64 v189, 0, v189, s[36:37]
	v_add_u32_e32 v86, 9, v84
	v_cmp_gt_u32_e64 s[36:37], s98, v86
	v_cndmask_b32_e64 v190, 0, v190, s[78:79]
	v_add_u32_e32 v87, 10, v84
	v_cmp_gt_u32_e64 s[78:79], s98, v87
	v_cndmask_b32_e64 v191, 0, v191, s[50:51]
	v_add_u32_e32 v88, 11, v84
	v_cmp_gt_u32_e64 s[50:51], s98, v88
	v_cndmask_b32_e64 v192, 0, v192, s[30:31]
	v_add_u32_e32 v85, 16, v84
	v_cmp_gt_u32_e64 s[30:31], s98, v85
	v_cndmask_b32_e64 v193, 0, v193, s[36:37]
	v_add_u32_e32 v86, 17, v84
	v_cmp_gt_u32_e64 s[36:37], s98, v86
	v_cndmask_b32_e64 v194, 0, v194, s[78:79]
	v_add_u32_e32 v87, 18, v84
	v_cmp_gt_u32_e64 s[78:79], s98, v87
	v_cndmask_b32_e64 v195, 0, v195, s[50:51]
	v_add_u32_e32 v88, 19, v84
	v_cmp_gt_u32_e64 s[50:51], s98, v88
	v_cndmask_b32_e64 v196, 0, v196, s[30:31]
	v_add_u32_e32 v85, 24, v84
	v_cmp_gt_u32_e64 s[30:31], s98, v85
	v_cndmask_b32_e64 v197, 0, v197, s[36:37]
	v_add_u32_e32 v86, 25, v84
	v_cmp_gt_u32_e64 s[36:37], s98, v86
	v_cndmask_b32_e64 v198, 0, v198, s[78:79]
	v_add_u32_e32 v87, 26, v84
	v_cmp_gt_u32_e64 s[78:79], s98, v87
	v_cndmask_b32_e64 v199, 0, v199, s[50:51]
	v_add_u32_e32 v88, 27, v84
	v_cmp_gt_u32_e64 s[50:51], s98, v88
	v_nop
	v_cndmask_b32_e64 v200, 0, v200, s[30:31]
	v_cndmask_b32_e64 v201, 0, v201, s[36:37]
	v_cndmask_b32_e64 v202, 0, v202, s[78:79]
	v_cndmask_b32_e64 v203, 0, v203, s[50:51]
	v_cvt_pk_bf16_f32 v64, v188, v189
	v_cvt_pk_bf16_f32 v65, v190, v191
	v_cvt_pk_bf16_f32 v66, v192, v193
	v_cvt_pk_bf16_f32 v67, v194, v195
	v_cvt_pk_bf16_f32 v68, v196, v197
	v_cvt_pk_bf16_f32 v69, v198, v199
	v_cvt_pk_bf16_f32 v70, v200, v201
	v_cvt_pk_bf16_f32 v71, v202, v203
	v_pk_add_f32 v[232:233], v[232:233], v[188:189]
	v_pk_add_f32 v[232:233], v[232:233], v[190:191]
	v_pk_add_f32 v[232:233], v[232:233], v[192:193]
	v_pk_add_f32 v[232:233], v[232:233], v[194:195]
	v_pk_add_f32 v[232:233], v[232:233], v[196:197]
	v_pk_add_f32 v[232:233], v[232:233], v[198:199]
	v_pk_add_f32 v[232:233], v[232:233], v[200:201]
	v_pk_add_f32 v[232:233], v[232:233], v[202:203]
	ds_read2_b32 v[188:189], v115 offset0:32 offset1:33
	ds_read2_b32 v[190:191], v115 offset0:34 offset1:35
	ds_read2_b32 v[192:193], v115 offset0:40 offset1:41
	ds_read2_b32 v[194:195], v115 offset0:42 offset1:43
	ds_read2_b32 v[196:197], v115 offset0:48 offset1:49
	ds_read2_b32 v[198:199], v115 offset0:50 offset1:51
	ds_read2_b32 v[200:201], v115 offset0:56 offset1:57
	ds_read2_b32 v[202:203], v115 offset0:58 offset1:59
	v_mfma_f32_32x32x16_bf16 v[0:15], v[64:67], v[72:75], v[0:15]
	v_mfma_f32_32x32x16_bf16 v[16:31], v[64:67], v[76:79], v[16:31]
	v_mfma_f32_32x32x16_bf16 v[0:15], v[68:71], v[220:223], v[0:15]
	v_mfma_f32_32x32x16_bf16 v[16:31], v[68:71], v[224:227], v[16:31]
	s_add_i32 s90, s76, 0
	v_add_u32_e32 v80, s90, v239
	v_add_u32_e32 v83, s90, v240
	v_add_u32_e32 v99, s90, v241
	v_add_u32_e32 v253, s90, v242
	v_add_u32_e32 v254, s90, v101
	v_add_u32_e32 v255, s90, v150
	v_med3_i32 v80, v80, 0, s99
	v_med3_i32 v83, v83, 0, s99
	v_med3_i32 v99, v99, 0, s99
	v_med3_i32 v253, v253, 0, s99
	v_med3_i32 v254, v254, 0, s99
	v_med3_i32 v255, v255, 0, s99
	v_mad_u32_u24 v80, v80, s100, v252
	v_mad_u32_u24 v83, v83, s100, v252
	v_mad_u32_u24 v99, v99, s100, v252
	v_mad_u32_u24 v253, v253, s100, v252
	v_mad_u32_u24 v254, v254, s100, v153
	v_mad_u32_u24 v255, v255, s100, v153
	global_load_dwordx4 v[116:119], v80, s[82:83]
	global_load_dwordx4 v[120:123], v83, s[82:83]
	global_load_dwordx4 v[124:127], v99, s[82:83]
	global_load_dwordx4 v[128:131], v253, s[82:83]
	global_load_dwordx4 v[132:135], v254, s[82:83] offset:768
	global_load_dwordx4 v[136:139], v255, s[82:83] offset:768
	global_load_dwordx4 v[140:143], v254, s[82:83] offset:832
	global_load_dwordx4 v[144:147], v255, s[82:83] offset:832
	ds_read_b64_tr_b16 v[72:73], v231
	ds_read_b64_tr_b16 v[74:75], v231 offset:512
	ds_read_b64_tr_b16 v[76:77], v231 offset:2048
	ds_read_b64_tr_b16 v[78:79], v231 offset:2560
	ds_read_b64_tr_b16 v[220:221], v231 offset:1024
	ds_read_b64_tr_b16 v[222:223], v231 offset:1536
	ds_read_b64_tr_b16 v[224:225], v231 offset:3072
	ds_read_b64_tr_b16 v[226:227], v231 offset:3584
	v_exp_f32_e32 v32, v32
	v_exp_f32_e32 v33, v33
	v_exp_f32_e32 v34, v34
	v_exp_f32_e32 v35, v35
	s_waitcnt vmcnt(12)
	ds_write_b128 v247, v[156:159]
	ds_write_b128 v247, v[160:163] offset:1024
	ds_write_b128 v247, v[164:167] offset:2048
	ds_write_b128 v247, v[168:171] offset:3072
	ds_read_b128 v[156:159], v248
	ds_read_b128 v[160:163], v249
	ds_read_b128 v[164:167], v250
	ds_read_b128 v[168:171], v251
	s_waitcnt vmcnt(8)
	ds_write_b128 v112, v[172:175]
	ds_write_b128 v112, v[176:179] offset:1024
	ds_write_b128 v112, v[180:183] offset:2048
	ds_write_b128 v112, v[184:187] offset:3072
	v_exp_f32_e32 v36, v36
	v_exp_f32_e32 v37, v37
	v_exp_f32_e32 v38, v38
	v_exp_f32_e32 v39, v39
	s_waitcnt lgkmcnt(4)
	v_mfma_f32_32x32x16_bf16 v[188:203], v[156:159], v[48:51], v[188:203]
	v_exp_f32_e32 v40, v40
	v_exp_f32_e32 v41, v41
	v_mfma_f32_32x32x16_bf16 v[188:203], v[160:163], v[52:55], v[188:203]
	v_exp_f32_e32 v42, v42
	v_exp_f32_e32 v43, v43
	v_mfma_f32_32x32x16_bf16 v[188:203], v[164:167], v[56:59], v[188:203]
	v_exp_f32_e32 v44, v44
	v_exp_f32_e32 v45, v45
	v_mfma_f32_32x32x16_bf16 v[188:203], v[168:171], v[60:63], v[188:203]
	v_exp_f32_e32 v46, v46
	v_exp_f32_e32 v47, v47
	s_add_i32 s90, s76, -256
	v_lshlrev_b32_e32 v84, 2, v107
	v_add_u32_e32 v84, s90, v84
	v_add_u32_e32 v85, 0, v84
	v_add_u32_e32 v86, 4, v84
	v_add_u32_e32 v87, 8, v84
	v_add_u32_e32 v88, 12, v84
	v_cmp_gt_u32_e64 s[30:31], s98, v85
	v_cmp_gt_u32_e64 s[36:37], s98, v86
	v_cmp_gt_u32_e64 s[78:79], s98, v87
	v_cmp_gt_u32_e64 s[50:51], s98, v88
	v_cndmask_b32_e64 v32, 0, v32, s[30:31]
	v_add_u32_e32 v85, 32, v84
	v_cmp_gt_u32_e64 s[30:31], s98, v85
	v_cndmask_b32_e64 v33, 0, v33, s[36:37]
	v_add_u32_e32 v86, 36, v84
	v_cmp_gt_u32_e64 s[36:37], s98, v86
	v_cndmask_b32_e64 v34, 0, v34, s[78:79]
	v_add_u32_e32 v87, 40, v84
	v_cmp_gt_u32_e64 s[78:79], s98, v87
	v_cndmask_b32_e64 v35, 0, v35, s[50:51]
	v_add_u32_e32 v88, 44, v84
	v_cmp_gt_u32_e64 s[50:51], s98, v88
	v_cndmask_b32_e64 v36, 0, v36, s[30:31]
	v_add_u32_e32 v85, 64, v84
	v_cmp_gt_u32_e64 s[30:31], s98, v85
	v_cndmask_b32_e64 v37, 0, v37, s[36:37]
	v_add_u32_e32 v86, 68, v84
	v_cmp_gt_u32_e64 s[36:37], s98, v86
	v_cndmask_b32_e64 v38, 0, v38, s[78:79]
	v_add_u32_e32 v87, 72, v84
	v_cmp_gt_u32_e64 s[78:79], s98, v87
	v_cndmask_b32_e64 v39, 0, v39, s[50:51]
	v_add_u32_e32 v88, 76, v84
	v_cmp_gt_u32_e64 s[50:51], s98, v88
	v_cndmask_b32_e64 v40, 0, v40, s[30:31]
	v_add_u32_e32 v85, 96, v84
	v_cmp_gt_u32_e64 s[30:31], s98, v85
	v_cndmask_b32_e64 v41, 0, v41, s[36:37]
	v_add_u32_e32 v86, 100, v84
	v_cmp_gt_u32_e64 s[36:37], s98, v86
	v_cndmask_b32_e64 v42, 0, v42, s[78:79]
	v_add_u32_e32 v87, 104, v84
	v_cmp_gt_u32_e64 s[78:79], s98, v87
	v_cndmask_b32_e64 v43, 0, v43, s[50:51]
	v_add_u32_e32 v88, 108, v84
	v_cmp_gt_u32_e64 s[50:51], s98, v88
	v_nop
	v_cndmask_b32_e64 v44, 0, v44, s[30:31]
	v_cndmask_b32_e64 v45, 0, v45, s[36:37]
	v_cndmask_b32_e64 v46, 0, v46, s[78:79]
	v_cndmask_b32_e64 v47, 0, v47, s[50:51]
	v_cvt_pk_bf16_f32 v64, v32, v33
	v_cvt_pk_bf16_f32 v65, v34, v35
	v_cvt_pk_bf16_f32 v66, v36, v37
	v_cvt_pk_bf16_f32 v67, v38, v39
	v_cvt_pk_bf16_f32 v68, v40, v41
	v_cvt_pk_bf16_f32 v69, v42, v43
	v_cvt_pk_bf16_f32 v70, v44, v45
	v_cvt_pk_bf16_f32 v71, v46, v47
	v_pk_add_f32 v[232:233], v[232:233], v[32:33]
	v_pk_add_f32 v[232:233], v[232:233], v[34:35]
	v_pk_add_f32 v[232:233], v[232:233], v[36:37]
	v_pk_add_f32 v[232:233], v[232:233], v[38:39]
	v_pk_add_f32 v[232:233], v[232:233], v[40:41]
	v_pk_add_f32 v[232:233], v[232:233], v[42:43]
	v_pk_add_f32 v[232:233], v[232:233], v[44:45]
	v_pk_add_f32 v[232:233], v[232:233], v[46:47]
	ds_read2_b32 v[32:33], v115 offset0:64 offset1:65
	ds_read2_b32 v[34:35], v115 offset0:66 offset1:67
	ds_read2_b32 v[36:37], v115 offset0:72 offset1:73
	ds_read2_b32 v[38:39], v115 offset0:74 offset1:75
	ds_read2_b32 v[40:41], v115 offset0:80 offset1:81
	ds_read2_b32 v[42:43], v115 offset0:82 offset1:83
	ds_read2_b32 v[44:45], v115 offset0:88 offset1:89
	ds_read2_b32 v[46:47], v115 offset0:90 offset1:91
	v_mfma_f32_32x32x16_bf16 v[0:15], v[64:67], v[72:75], v[0:15]
	v_mfma_f32_32x32x16_bf16 v[16:31], v[64:67], v[76:79], v[16:31]
	v_mfma_f32_32x32x16_bf16 v[0:15], v[68:71], v[220:223], v[0:15]
	v_mfma_f32_32x32x16_bf16 v[16:31], v[68:71], v[224:227], v[16:31]
	s_add_i32 s90, s76, 128
	v_add_u32_e32 v80, s90, v239
	v_add_u32_e32 v83, s90, v240
	v_add_u32_e32 v99, s90, v241
	v_add_u32_e32 v253, s90, v242
	v_add_u32_e32 v254, s90, v101
	v_add_u32_e32 v255, s90, v150
	v_med3_i32 v80, v80, 0, s99
	v_med3_i32 v83, v83, 0, s99
	v_med3_i32 v99, v99, 0, s99
	v_med3_i32 v253, v253, 0, s99
	v_med3_i32 v254, v254, 0, s99
	v_med3_i32 v255, v255, 0, s99
	v_mad_u32_u24 v80, v80, s100, v252
	v_mad_u32_u24 v83, v83, s100, v252
	v_mad_u32_u24 v99, v99, s100, v252
	v_mad_u32_u24 v253, v253, s100, v252
	v_mad_u32_u24 v254, v254, s100, v153
	v_mad_u32_u24 v255, v255, s100, v153
	global_load_dwordx4 v[156:159], v80, s[82:83]
	global_load_dwordx4 v[160:163], v83, s[82:83]
	global_load_dwordx4 v[164:167], v99, s[82:83]
	global_load_dwordx4 v[168:171], v253, s[82:83]
	global_load_dwordx4 v[172:175], v254, s[82:83] offset:768
	global_load_dwordx4 v[176:179], v255, s[82:83] offset:768
	global_load_dwordx4 v[180:183], v254, s[82:83] offset:832
	global_load_dwordx4 v[184:187], v255, s[82:83] offset:832
	ds_read_b64_tr_b16 v[72:73], v231
	ds_read_b64_tr_b16 v[74:75], v231 offset:512
	ds_read_b64_tr_b16 v[76:77], v231 offset:2048
	ds_read_b64_tr_b16 v[78:79], v231 offset:2560
	ds_read_b64_tr_b16 v[220:221], v231 offset:1024
	ds_read_b64_tr_b16 v[222:223], v231 offset:1536
	ds_read_b64_tr_b16 v[224:225], v231 offset:3072
	ds_read_b64_tr_b16 v[226:227], v231 offset:3584
	v_exp_f32_e32 v188, v188
	v_exp_f32_e32 v189, v189
	v_exp_f32_e32 v190, v190
	v_exp_f32_e32 v191, v191
	s_waitcnt vmcnt(12)
	ds_write_b128 v247, v[116:119]
	ds_write_b128 v247, v[120:123] offset:1024
	ds_write_b128 v247, v[124:127] offset:2048
	ds_write_b128 v247, v[128:131] offset:3072
	ds_read_b128 v[116:119], v248
	ds_read_b128 v[120:123], v249
	ds_read_b128 v[124:127], v250
	ds_read_b128 v[128:131], v251
	s_waitcnt vmcnt(8)
	ds_write_b128 v112, v[132:135]
	ds_write_b128 v112, v[136:139] offset:1024
	ds_write_b128 v112, v[140:143] offset:2048
	ds_write_b128 v112, v[144:147] offset:3072
	v_exp_f32_e32 v192, v192
	v_exp_f32_e32 v193, v193
	v_exp_f32_e32 v194, v194
	v_exp_f32_e32 v195, v195
	s_waitcnt lgkmcnt(4)
	v_mfma_f32_32x32x16_bf16 v[32:47], v[116:119], v[48:51], v[32:47]
	v_exp_f32_e32 v196, v196
	v_exp_f32_e32 v197, v197
	v_mfma_f32_32x32x16_bf16 v[32:47], v[120:123], v[52:55], v[32:47]
	v_exp_f32_e32 v198, v198
	v_exp_f32_e32 v199, v199
	v_mfma_f32_32x32x16_bf16 v[32:47], v[124:127], v[56:59], v[32:47]
	v_exp_f32_e32 v200, v200
	v_exp_f32_e32 v201, v201
	v_mfma_f32_32x32x16_bf16 v[32:47], v[128:131], v[60:63], v[32:47]
	v_exp_f32_e32 v202, v202
	v_exp_f32_e32 v203, v203
	s_add_i32 s90, s76, -128
	v_lshlrev_b32_e32 v84, 2, v107
	v_add_u32_e32 v84, s90, v84
	v_add_u32_e32 v85, 0, v84
	v_add_u32_e32 v86, 4, v84
	v_add_u32_e32 v87, 8, v84
	v_add_u32_e32 v88, 12, v84
	v_cmp_gt_u32_e64 s[30:31], s98, v85
	v_cmp_gt_u32_e64 s[36:37], s98, v86
	v_cmp_gt_u32_e64 s[78:79], s98, v87
	v_cmp_gt_u32_e64 s[50:51], s98, v88
	v_cndmask_b32_e64 v188, 0, v188, s[30:31]
	v_add_u32_e32 v85, 32, v84
	v_cmp_gt_u32_e64 s[30:31], s98, v85
	v_cndmask_b32_e64 v189, 0, v189, s[36:37]
	v_add_u32_e32 v86, 36, v84
	v_cmp_gt_u32_e64 s[36:37], s98, v86
	v_cndmask_b32_e64 v190, 0, v190, s[78:79]
	v_add_u32_e32 v87, 40, v84
	v_cmp_gt_u32_e64 s[78:79], s98, v87
	v_cndmask_b32_e64 v191, 0, v191, s[50:51]
	v_add_u32_e32 v88, 44, v84
	v_cmp_gt_u32_e64 s[50:51], s98, v88
	v_cndmask_b32_e64 v192, 0, v192, s[30:31]
	v_add_u32_e32 v85, 64, v84
	v_cmp_gt_u32_e64 s[30:31], s98, v85
	v_cndmask_b32_e64 v193, 0, v193, s[36:37]
	v_add_u32_e32 v86, 68, v84
	v_cmp_gt_u32_e64 s[36:37], s98, v86
	v_cndmask_b32_e64 v194, 0, v194, s[78:79]
	v_add_u32_e32 v87, 72, v84
	v_cmp_gt_u32_e64 s[78:79], s98, v87
	v_cndmask_b32_e64 v195, 0, v195, s[50:51]
	v_add_u32_e32 v88, 76, v84
	v_cmp_gt_u32_e64 s[50:51], s98, v88
	v_cndmask_b32_e64 v196, 0, v196, s[30:31]
	v_add_u32_e32 v85, 96, v84
	v_cmp_gt_u32_e64 s[30:31], s98, v85
	v_cndmask_b32_e64 v197, 0, v197, s[36:37]
	v_add_u32_e32 v86, 100, v84
	v_cmp_gt_u32_e64 s[36:37], s98, v86
	v_cndmask_b32_e64 v198, 0, v198, s[78:79]
	v_add_u32_e32 v87, 104, v84
	v_cmp_gt_u32_e64 s[78:79], s98, v87
	v_cndmask_b32_e64 v199, 0, v199, s[50:51]
	v_add_u32_e32 v88, 108, v84
	v_cmp_gt_u32_e64 s[50:51], s98, v88
	v_nop
	v_cndmask_b32_e64 v200, 0, v200, s[30:31]
	v_cndmask_b32_e64 v201, 0, v201, s[36:37]
	v_cndmask_b32_e64 v202, 0, v202, s[78:79]
	v_cndmask_b32_e64 v203, 0, v203, s[50:51]
	v_cvt_pk_bf16_f32 v64, v188, v189
	v_cvt_pk_bf16_f32 v65, v190, v191
	v_cvt_pk_bf16_f32 v66, v192, v193
	v_cvt_pk_bf16_f32 v67, v194, v195
	v_cvt_pk_bf16_f32 v68, v196, v197
	v_cvt_pk_bf16_f32 v69, v198, v199
	v_cvt_pk_bf16_f32 v70, v200, v201
	v_cvt_pk_bf16_f32 v71, v202, v203
	v_pk_add_f32 v[232:233], v[232:233], v[188:189]
	v_pk_add_f32 v[232:233], v[232:233], v[190:191]
	v_pk_add_f32 v[232:233], v[232:233], v[192:193]
	v_pk_add_f32 v[232:233], v[232:233], v[194:195]
	v_pk_add_f32 v[232:233], v[232:233], v[196:197]
	v_pk_add_f32 v[232:233], v[232:233], v[198:199]
	v_pk_add_f32 v[232:233], v[232:233], v[200:201]
	v_pk_add_f32 v[232:233], v[232:233], v[202:203]
	ds_read2_b32 v[188:189], v115 offset0:96 offset1:97
	ds_read2_b32 v[190:191], v115 offset0:98 offset1:99
	ds_read2_b32 v[192:193], v115 offset0:104 offset1:105
	ds_read2_b32 v[194:195], v115 offset0:106 offset1:107
	ds_read2_b32 v[196:197], v115 offset0:112 offset1:113
	ds_read2_b32 v[198:199], v115 offset0:114 offset1:115
	ds_read2_b32 v[200:201], v115 offset0:120 offset1:121
	ds_read2_b32 v[202:203], v115 offset0:122 offset1:123
	v_mfma_f32_32x32x16_bf16 v[0:15], v[64:67], v[72:75], v[0:15]
	v_mfma_f32_32x32x16_bf16 v[16:31], v[64:67], v[76:79], v[16:31]
	v_mfma_f32_32x32x16_bf16 v[0:15], v[68:71], v[220:223], v[0:15]
	v_mfma_f32_32x32x16_bf16 v[16:31], v[68:71], v[224:227], v[16:31]
	s_add_i32 s90, s76, 256
	v_add_u32_e32 v80, s90, v239
	v_add_u32_e32 v83, s90, v240
	v_add_u32_e32 v99, s90, v241
	v_add_u32_e32 v253, s90, v242
	v_add_u32_e32 v254, s90, v101
	v_add_u32_e32 v255, s90, v150
	v_med3_i32 v80, v80, 0, s99
	v_med3_i32 v83, v83, 0, s99
	v_med3_i32 v99, v99, 0, s99
	v_med3_i32 v253, v253, 0, s99
	v_med3_i32 v254, v254, 0, s99
	v_med3_i32 v255, v255, 0, s99
	v_mad_u32_u24 v80, v80, s100, v252
	v_mad_u32_u24 v83, v83, s100, v252
	v_mad_u32_u24 v99, v99, s100, v252
	v_mad_u32_u24 v253, v253, s100, v252
	v_mad_u32_u24 v254, v254, s100, v153
	v_mad_u32_u24 v255, v255, s100, v153
	global_load_dwordx4 v[116:119], v80, s[82:83]
	global_load_dwordx4 v[120:123], v83, s[82:83]
	global_load_dwordx4 v[124:127], v99, s[82:83]
	global_load_dwordx4 v[128:131], v253, s[82:83]
	global_load_dwordx4 v[132:135], v254, s[82:83] offset:768
	global_load_dwordx4 v[136:139], v255, s[82:83] offset:768
	global_load_dwordx4 v[140:143], v254, s[82:83] offset:832
	global_load_dwordx4 v[144:147], v255, s[82:83] offset:832
	ds_read_b64_tr_b16 v[72:73], v231
	ds_read_b64_tr_b16 v[74:75], v231 offset:512
	ds_read_b64_tr_b16 v[76:77], v231 offset:2048
	ds_read_b64_tr_b16 v[78:79], v231 offset:2560
	ds_read_b64_tr_b16 v[220:221], v231 offset:1024
	ds_read_b64_tr_b16 v[222:223], v231 offset:1536
	ds_read_b64_tr_b16 v[224:225], v231 offset:3072
	ds_read_b64_tr_b16 v[226:227], v231 offset:3584
	v_exp_f32_e32 v32, v32
	v_exp_f32_e32 v33, v33
	v_exp_f32_e32 v34, v34
	v_exp_f32_e32 v35, v35
	s_waitcnt vmcnt(12)
	ds_write_b128 v247, v[156:159]
	ds_write_b128 v247, v[160:163] offset:1024
	ds_write_b128 v247, v[164:167] offset:2048
	ds_write_b128 v247, v[168:171] offset:3072
	ds_read_b128 v[156:159], v248
	ds_read_b128 v[160:163], v249
	ds_read_b128 v[164:167], v250
	ds_read_b128 v[168:171], v251
	s_waitcnt vmcnt(8)
	ds_write_b128 v112, v[172:175]
	ds_write_b128 v112, v[176:179] offset:1024
	ds_write_b128 v112, v[180:183] offset:2048
	ds_write_b128 v112, v[184:187] offset:3072
	v_exp_f32_e32 v36, v36
	v_exp_f32_e32 v37, v37
	v_exp_f32_e32 v38, v38
	v_exp_f32_e32 v39, v39
	s_waitcnt lgkmcnt(4)
	v_mfma_f32_32x32x16_bf16 v[188:203], v[156:159], v[48:51], v[188:203]
	v_exp_f32_e32 v40, v40
	v_exp_f32_e32 v41, v41
	v_mfma_f32_32x32x16_bf16 v[188:203], v[160:163], v[52:55], v[188:203]
	v_exp_f32_e32 v42, v42
	v_exp_f32_e32 v43, v43
	v_mfma_f32_32x32x16_bf16 v[188:203], v[164:167], v[56:59], v[188:203]
	v_exp_f32_e32 v44, v44
	v_exp_f32_e32 v45, v45
	v_mfma_f32_32x32x16_bf16 v[188:203], v[168:171], v[60:63], v[188:203]
	v_exp_f32_e32 v46, v46
	v_exp_f32_e32 v47, v47
	s_add_i32 s90, s76, 0
	v_lshlrev_b32_e32 v84, 2, v107
	v_add_u32_e32 v84, s90, v84
	v_add_u32_e32 v85, 0, v84
	v_add_u32_e32 v86, 4, v84
	v_add_u32_e32 v87, 8, v84
	v_add_u32_e32 v88, 12, v84
	v_cmp_gt_u32_e64 s[30:31], s98, v85
	v_cmp_gt_u32_e64 s[36:37], s98, v86
	v_cmp_gt_u32_e64 s[78:79], s98, v87
	v_cmp_gt_u32_e64 s[50:51], s98, v88
	v_cndmask_b32_e64 v32, 0, v32, s[30:31]
	v_add_u32_e32 v85, 32, v84
	v_cmp_gt_u32_e64 s[30:31], s98, v85
	v_cndmask_b32_e64 v33, 0, v33, s[36:37]
	v_add_u32_e32 v86, 36, v84
	v_cmp_gt_u32_e64 s[36:37], s98, v86
	v_cndmask_b32_e64 v34, 0, v34, s[78:79]
	v_add_u32_e32 v87, 40, v84
	v_cmp_gt_u32_e64 s[78:79], s98, v87
	v_cndmask_b32_e64 v35, 0, v35, s[50:51]
	v_add_u32_e32 v88, 44, v84
	v_cmp_gt_u32_e64 s[50:51], s98, v88
	v_cndmask_b32_e64 v36, 0, v36, s[30:31]
	v_add_u32_e32 v85, 64, v84
	v_cmp_gt_u32_e64 s[30:31], s98, v85
	v_cndmask_b32_e64 v37, 0, v37, s[36:37]
	v_add_u32_e32 v86, 68, v84
	v_cmp_gt_u32_e64 s[36:37], s98, v86
	v_cndmask_b32_e64 v38, 0, v38, s[78:79]
	v_add_u32_e32 v87, 72, v84
	v_cmp_gt_u32_e64 s[78:79], s98, v87
	v_cndmask_b32_e64 v39, 0, v39, s[50:51]
	v_add_u32_e32 v88, 76, v84
	v_cmp_gt_u32_e64 s[50:51], s98, v88
	v_cndmask_b32_e64 v40, 0, v40, s[30:31]
	v_add_u32_e32 v85, 96, v84
	v_cmp_gt_u32_e64 s[30:31], s98, v85
	v_cndmask_b32_e64 v41, 0, v41, s[36:37]
	v_add_u32_e32 v86, 100, v84
	v_cmp_gt_u32_e64 s[36:37], s98, v86
	v_cndmask_b32_e64 v42, 0, v42, s[78:79]
	v_add_u32_e32 v87, 104, v84
	v_cmp_gt_u32_e64 s[78:79], s98, v87
	v_cndmask_b32_e64 v43, 0, v43, s[50:51]
	v_add_u32_e32 v88, 108, v84
	v_cmp_gt_u32_e64 s[50:51], s98, v88
	v_nop
	v_cndmask_b32_e64 v44, 0, v44, s[30:31]
	v_cndmask_b32_e64 v45, 0, v45, s[36:37]
	v_cndmask_b32_e64 v46, 0, v46, s[78:79]
	v_cndmask_b32_e64 v47, 0, v47, s[50:51]
	v_cvt_pk_bf16_f32 v64, v32, v33
	v_cvt_pk_bf16_f32 v65, v34, v35
	v_cvt_pk_bf16_f32 v66, v36, v37
	v_cvt_pk_bf16_f32 v67, v38, v39
	v_cvt_pk_bf16_f32 v68, v40, v41
	v_cvt_pk_bf16_f32 v69, v42, v43
	v_cvt_pk_bf16_f32 v70, v44, v45
	v_cvt_pk_bf16_f32 v71, v46, v47
	v_pk_add_f32 v[232:233], v[232:233], v[32:33]
	v_pk_add_f32 v[232:233], v[232:233], v[34:35]
	v_pk_add_f32 v[232:233], v[232:233], v[36:37]
	v_pk_add_f32 v[232:233], v[232:233], v[38:39]
	v_pk_add_f32 v[232:233], v[232:233], v[40:41]
	v_pk_add_f32 v[232:233], v[232:233], v[42:43]
	v_pk_add_f32 v[232:233], v[232:233], v[44:45]
	v_pk_add_f32 v[232:233], v[232:233], v[46:47]
	ds_read2_b32 v[32:33], v115 offset0:128 offset1:129
	ds_read2_b32 v[34:35], v115 offset0:130 offset1:131
	ds_read2_b32 v[36:37], v115 offset0:136 offset1:137
	ds_read2_b32 v[38:39], v115 offset0:138 offset1:139
	ds_read2_b32 v[40:41], v115 offset0:144 offset1:145
	ds_read2_b32 v[42:43], v115 offset0:146 offset1:147
	ds_read2_b32 v[44:45], v115 offset0:152 offset1:153
	ds_read2_b32 v[46:47], v115 offset0:154 offset1:155
	v_mfma_f32_32x32x16_bf16 v[0:15], v[64:67], v[72:75], v[0:15]
	v_mfma_f32_32x32x16_bf16 v[16:31], v[64:67], v[76:79], v[16:31]
	v_mfma_f32_32x32x16_bf16 v[0:15], v[68:71], v[220:223], v[0:15]
	v_mfma_f32_32x32x16_bf16 v[16:31], v[68:71], v[224:227], v[16:31]
	s_add_i32 s90, s76, 384
	v_add_u32_e32 v80, s90, v239
	v_add_u32_e32 v83, s90, v240
	v_add_u32_e32 v99, s90, v241
	v_add_u32_e32 v253, s90, v242
	v_add_u32_e32 v254, s90, v101
	v_add_u32_e32 v255, s90, v150
	v_med3_i32 v80, v80, 0, s99
	v_med3_i32 v83, v83, 0, s99
	v_med3_i32 v99, v99, 0, s99
	v_med3_i32 v253, v253, 0, s99
	v_med3_i32 v254, v254, 0, s99
	v_med3_i32 v255, v255, 0, s99
	v_mad_u32_u24 v80, v80, s100, v252
	v_mad_u32_u24 v83, v83, s100, v252
	v_mad_u32_u24 v99, v99, s100, v252
	v_mad_u32_u24 v253, v253, s100, v252
	v_mad_u32_u24 v254, v254, s100, v153
	v_mad_u32_u24 v255, v255, s100, v153
	global_load_dwordx4 v[156:159], v80, s[82:83]
	global_load_dwordx4 v[160:163], v83, s[82:83]
	global_load_dwordx4 v[164:167], v99, s[82:83]
	global_load_dwordx4 v[168:171], v253, s[82:83]
	global_load_dwordx4 v[172:175], v254, s[82:83] offset:768
	global_load_dwordx4 v[176:179], v255, s[82:83] offset:768
	global_load_dwordx4 v[180:183], v254, s[82:83] offset:832
	global_load_dwordx4 v[184:187], v255, s[82:83] offset:832
	ds_read_b64_tr_b16 v[72:73], v231
	ds_read_b64_tr_b16 v[74:75], v231 offset:512
	ds_read_b64_tr_b16 v[76:77], v231 offset:2048
	ds_read_b64_tr_b16 v[78:79], v231 offset:2560
	ds_read_b64_tr_b16 v[220:221], v231 offset:1024
	ds_read_b64_tr_b16 v[222:223], v231 offset:1536
	ds_read_b64_tr_b16 v[224:225], v231 offset:3072
	ds_read_b64_tr_b16 v[226:227], v231 offset:3584
	v_exp_f32_e32 v188, v188
	v_exp_f32_e32 v189, v189
	v_exp_f32_e32 v190, v190
	v_exp_f32_e32 v191, v191
	s_waitcnt vmcnt(12)
	ds_write_b128 v247, v[116:119]
	ds_write_b128 v247, v[120:123] offset:1024
	ds_write_b128 v247, v[124:127] offset:2048
	ds_write_b128 v247, v[128:131] offset:3072
	ds_read_b128 v[116:119], v248
	ds_read_b128 v[120:123], v249
	ds_read_b128 v[124:127], v250
	ds_read_b128 v[128:131], v251
	s_waitcnt vmcnt(8)
	ds_write_b128 v112, v[132:135]
	ds_write_b128 v112, v[136:139] offset:1024
	ds_write_b128 v112, v[140:143] offset:2048
	ds_write_b128 v112, v[144:147] offset:3072
	v_exp_f32_e32 v192, v192
	v_exp_f32_e32 v193, v193
	v_exp_f32_e32 v194, v194
	v_exp_f32_e32 v195, v195
	s_waitcnt lgkmcnt(4)
	v_mfma_f32_32x32x16_bf16 v[32:47], v[116:119], v[48:51], v[32:47]
	v_exp_f32_e32 v196, v196
	v_exp_f32_e32 v197, v197
	v_mfma_f32_32x32x16_bf16 v[32:47], v[120:123], v[52:55], v[32:47]
	v_exp_f32_e32 v198, v198
	v_exp_f32_e32 v199, v199
	v_mfma_f32_32x32x16_bf16 v[32:47], v[124:127], v[56:59], v[32:47]
	v_exp_f32_e32 v200, v200
	v_exp_f32_e32 v201, v201
	v_mfma_f32_32x32x16_bf16 v[32:47], v[128:131], v[60:63], v[32:47]
	v_exp_f32_e32 v202, v202
	v_exp_f32_e32 v203, v203
	s_add_i32 s90, s76, 128
	v_lshlrev_b32_e32 v84, 2, v107
	v_add_u32_e32 v84, s90, v84
	v_add_u32_e32 v85, 0, v84
	v_add_u32_e32 v86, 4, v84
	v_add_u32_e32 v87, 8, v84
	v_add_u32_e32 v88, 12, v84
	v_cmp_gt_u32_e64 s[30:31], s98, v85
	v_cmp_gt_u32_e64 s[36:37], s98, v86
	v_cmp_gt_u32_e64 s[78:79], s98, v87
	v_cmp_gt_u32_e64 s[50:51], s98, v88
	v_cndmask_b32_e64 v188, 0, v188, s[30:31]
	v_add_u32_e32 v85, 32, v84
	v_cmp_gt_u32_e64 s[30:31], s98, v85
	v_cndmask_b32_e64 v189, 0, v189, s[36:37]
	v_add_u32_e32 v86, 36, v84
	v_cmp_gt_u32_e64 s[36:37], s98, v86
	v_cndmask_b32_e64 v190, 0, v190, s[78:79]
	v_add_u32_e32 v87, 40, v84
	v_cmp_gt_u32_e64 s[78:79], s98, v87
	v_cndmask_b32_e64 v191, 0, v191, s[50:51]
	v_add_u32_e32 v88, 44, v84
	v_cmp_gt_u32_e64 s[50:51], s98, v88
	v_cndmask_b32_e64 v192, 0, v192, s[30:31]
	v_add_u32_e32 v85, 64, v84
	v_cmp_gt_u32_e64 s[30:31], s98, v85
	v_cndmask_b32_e64 v193, 0, v193, s[36:37]
	v_add_u32_e32 v86, 68, v84
	v_cmp_gt_u32_e64 s[36:37], s98, v86
	v_cndmask_b32_e64 v194, 0, v194, s[78:79]
	v_add_u32_e32 v87, 72, v84
	v_cmp_gt_u32_e64 s[78:79], s98, v87
	v_cndmask_b32_e64 v195, 0, v195, s[50:51]
	v_add_u32_e32 v88, 76, v84
	v_cmp_gt_u32_e64 s[50:51], s98, v88
	v_cndmask_b32_e64 v196, 0, v196, s[30:31]
	v_add_u32_e32 v85, 96, v84
	v_cmp_gt_u32_e64 s[30:31], s98, v85
	v_cndmask_b32_e64 v197, 0, v197, s[36:37]
	v_add_u32_e32 v86, 100, v84
	v_cmp_gt_u32_e64 s[36:37], s98, v86
	v_cndmask_b32_e64 v198, 0, v198, s[78:79]
	v_add_u32_e32 v87, 104, v84
	v_cmp_gt_u32_e64 s[78:79], s98, v87
	v_cndmask_b32_e64 v199, 0, v199, s[50:51]
	v_add_u32_e32 v88, 108, v84
	v_cmp_gt_u32_e64 s[50:51], s98, v88
	v_nop
	v_cndmask_b32_e64 v200, 0, v200, s[30:31]
	v_cndmask_b32_e64 v201, 0, v201, s[36:37]
	v_cndmask_b32_e64 v202, 0, v202, s[78:79]
	v_cndmask_b32_e64 v203, 0, v203, s[50:51]
	v_cvt_pk_bf16_f32 v64, v188, v189
	v_cvt_pk_bf16_f32 v65, v190, v191
	v_cvt_pk_bf16_f32 v66, v192, v193
	v_cvt_pk_bf16_f32 v67, v194, v195
	v_cvt_pk_bf16_f32 v68, v196, v197
	v_cvt_pk_bf16_f32 v69, v198, v199
	v_cvt_pk_bf16_f32 v70, v200, v201
	v_cvt_pk_bf16_f32 v71, v202, v203
	v_pk_add_f32 v[232:233], v[232:233], v[188:189]
	v_pk_add_f32 v[232:233], v[232:233], v[190:191]
	v_pk_add_f32 v[232:233], v[232:233], v[192:193]
	v_pk_add_f32 v[232:233], v[232:233], v[194:195]
	v_pk_add_f32 v[232:233], v[232:233], v[196:197]
	v_pk_add_f32 v[232:233], v[232:233], v[198:199]
	v_pk_add_f32 v[232:233], v[232:233], v[200:201]
	v_pk_add_f32 v[232:233], v[232:233], v[202:203]
	ds_read2_b32 v[188:189], v115 offset0:160 offset1:161
	ds_read2_b32 v[190:191], v115 offset0:162 offset1:163
	ds_read2_b32 v[192:193], v115 offset0:168 offset1:169
	ds_read2_b32 v[194:195], v115 offset0:170 offset1:171
	ds_read2_b32 v[196:197], v115 offset0:176 offset1:177
	ds_read2_b32 v[198:199], v115 offset0:178 offset1:179
	ds_read2_b32 v[200:201], v115 offset0:184 offset1:185
	ds_read2_b32 v[202:203], v115 offset0:186 offset1:187
	v_mfma_f32_32x32x16_bf16 v[0:15], v[64:67], v[72:75], v[0:15]
	v_mfma_f32_32x32x16_bf16 v[16:31], v[64:67], v[76:79], v[16:31]
	v_mfma_f32_32x32x16_bf16 v[0:15], v[68:71], v[220:223], v[0:15]
	v_mfma_f32_32x32x16_bf16 v[16:31], v[68:71], v[224:227], v[16:31]
	s_add_i32 s90, s76, 512
	v_add_u32_e32 v80, s90, v239
	v_add_u32_e32 v83, s90, v240
	v_add_u32_e32 v99, s90, v241
	v_add_u32_e32 v253, s90, v242
	v_add_u32_e32 v254, s90, v101
	v_add_u32_e32 v255, s90, v150
	v_med3_i32 v80, v80, 0, s99
	v_med3_i32 v83, v83, 0, s99
	v_med3_i32 v99, v99, 0, s99
	v_med3_i32 v253, v253, 0, s99
	v_med3_i32 v254, v254, 0, s99
	v_med3_i32 v255, v255, 0, s99
	v_mad_u32_u24 v80, v80, s100, v252
	v_mad_u32_u24 v83, v83, s100, v252
	v_mad_u32_u24 v99, v99, s100, v252
	v_mad_u32_u24 v253, v253, s100, v252
	v_mad_u32_u24 v254, v254, s100, v153
	v_mad_u32_u24 v255, v255, s100, v153
	global_load_dwordx4 v[116:119], v80, s[82:83]
	global_load_dwordx4 v[120:123], v83, s[82:83]
	global_load_dwordx4 v[124:127], v99, s[82:83]
	global_load_dwordx4 v[128:131], v253, s[82:83]
	global_load_dwordx4 v[132:135], v254, s[82:83] offset:768
	global_load_dwordx4 v[136:139], v255, s[82:83] offset:768
	global_load_dwordx4 v[140:143], v254, s[82:83] offset:832
	global_load_dwordx4 v[144:147], v255, s[82:83] offset:832
	ds_read_b64_tr_b16 v[72:73], v231
	ds_read_b64_tr_b16 v[74:75], v231 offset:512
	ds_read_b64_tr_b16 v[76:77], v231 offset:2048
	ds_read_b64_tr_b16 v[78:79], v231 offset:2560
	ds_read_b64_tr_b16 v[220:221], v231 offset:1024
	ds_read_b64_tr_b16 v[222:223], v231 offset:1536
	ds_read_b64_tr_b16 v[224:225], v231 offset:3072
	ds_read_b64_tr_b16 v[226:227], v231 offset:3584
	v_exp_f32_e32 v32, v32
	v_exp_f32_e32 v33, v33
	v_exp_f32_e32 v34, v34
	v_exp_f32_e32 v35, v35
	s_waitcnt vmcnt(12)
	ds_write_b128 v247, v[156:159]
	ds_write_b128 v247, v[160:163] offset:1024
	ds_write_b128 v247, v[164:167] offset:2048
	ds_write_b128 v247, v[168:171] offset:3072
	ds_read_b128 v[156:159], v248
	ds_read_b128 v[160:163], v249
	ds_read_b128 v[164:167], v250
	ds_read_b128 v[168:171], v251
	s_waitcnt vmcnt(8)
	ds_write_b128 v112, v[172:175]
	ds_write_b128 v112, v[176:179] offset:1024
	ds_write_b128 v112, v[180:183] offset:2048
	ds_write_b128 v112, v[184:187] offset:3072
	v_exp_f32_e32 v36, v36
	v_exp_f32_e32 v37, v37
	v_exp_f32_e32 v38, v38
	v_exp_f32_e32 v39, v39
	s_waitcnt lgkmcnt(4)
	v_mfma_f32_32x32x16_bf16 v[188:203], v[156:159], v[48:51], v[188:203]
	v_exp_f32_e32 v40, v40
	v_exp_f32_e32 v41, v41
	v_mfma_f32_32x32x16_bf16 v[188:203], v[160:163], v[52:55], v[188:203]
	v_exp_f32_e32 v42, v42
	v_exp_f32_e32 v43, v43
	v_mfma_f32_32x32x16_bf16 v[188:203], v[164:167], v[56:59], v[188:203]
	v_exp_f32_e32 v44, v44
	v_exp_f32_e32 v45, v45
	v_mfma_f32_32x32x16_bf16 v[188:203], v[168:171], v[60:63], v[188:203]
	v_exp_f32_e32 v46, v46
	v_exp_f32_e32 v47, v47
	s_add_i32 s90, s76, 256
	v_lshlrev_b32_e32 v84, 2, v107
	v_add_u32_e32 v84, s90, v84
	v_add_u32_e32 v85, 0, v84
	v_add_u32_e32 v86, 4, v84
	v_add_u32_e32 v87, 8, v84
	v_add_u32_e32 v88, 12, v84
	v_cmp_gt_u32_e64 s[30:31], s98, v85
	v_cmp_gt_u32_e64 s[36:37], s98, v86
	v_cmp_gt_u32_e64 s[78:79], s98, v87
	v_cmp_gt_u32_e64 s[50:51], s98, v88
	v_cndmask_b32_e64 v32, 0, v32, s[30:31]
	v_add_u32_e32 v85, 32, v84
	v_cmp_gt_u32_e64 s[30:31], s98, v85
	v_cndmask_b32_e64 v33, 0, v33, s[36:37]
	v_add_u32_e32 v86, 36, v84
	v_cmp_gt_u32_e64 s[36:37], s98, v86
	v_cndmask_b32_e64 v34, 0, v34, s[78:79]
	v_add_u32_e32 v87, 40, v84
	v_cmp_gt_u32_e64 s[78:79], s98, v87
	v_cndmask_b32_e64 v35, 0, v35, s[50:51]
	v_add_u32_e32 v88, 44, v84
	v_cmp_gt_u32_e64 s[50:51], s98, v88
	v_cndmask_b32_e64 v36, 0, v36, s[30:31]
	v_add_u32_e32 v85, 64, v84
	v_cmp_gt_u32_e64 s[30:31], s98, v85
	v_cndmask_b32_e64 v37, 0, v37, s[36:37]
	v_add_u32_e32 v86, 68, v84
	v_cmp_gt_u32_e64 s[36:37], s98, v86
	v_cndmask_b32_e64 v38, 0, v38, s[78:79]
	v_add_u32_e32 v87, 72, v84
	v_cmp_gt_u32_e64 s[78:79], s98, v87
	v_cndmask_b32_e64 v39, 0, v39, s[50:51]
	v_add_u32_e32 v88, 76, v84
	v_cmp_gt_u32_e64 s[50:51], s98, v88
	v_cndmask_b32_e64 v40, 0, v40, s[30:31]
	v_add_u32_e32 v85, 96, v84
	v_cmp_gt_u32_e64 s[30:31], s98, v85
	v_cndmask_b32_e64 v41, 0, v41, s[36:37]
	v_add_u32_e32 v86, 100, v84
	v_cmp_gt_u32_e64 s[36:37], s98, v86
	v_cndmask_b32_e64 v42, 0, v42, s[78:79]
	v_add_u32_e32 v87, 104, v84
	v_cmp_gt_u32_e64 s[78:79], s98, v87
	v_cndmask_b32_e64 v43, 0, v43, s[50:51]
	v_add_u32_e32 v88, 108, v84
	v_cmp_gt_u32_e64 s[50:51], s98, v88
	v_nop
	v_cndmask_b32_e64 v44, 0, v44, s[30:31]
	v_cndmask_b32_e64 v45, 0, v45, s[36:37]
	v_cndmask_b32_e64 v46, 0, v46, s[78:79]
	v_cndmask_b32_e64 v47, 0, v47, s[50:51]
	v_cvt_pk_bf16_f32 v64, v32, v33
	v_cvt_pk_bf16_f32 v65, v34, v35
	v_cvt_pk_bf16_f32 v66, v36, v37
	v_cvt_pk_bf16_f32 v67, v38, v39
	v_cvt_pk_bf16_f32 v68, v40, v41
	v_cvt_pk_bf16_f32 v69, v42, v43
	v_cvt_pk_bf16_f32 v70, v44, v45
	v_cvt_pk_bf16_f32 v71, v46, v47
	v_pk_add_f32 v[232:233], v[232:233], v[32:33]
	v_pk_add_f32 v[232:233], v[232:233], v[34:35]
	v_pk_add_f32 v[232:233], v[232:233], v[36:37]
	v_pk_add_f32 v[232:233], v[232:233], v[38:39]
	v_pk_add_f32 v[232:233], v[232:233], v[40:41]
	v_pk_add_f32 v[232:233], v[232:233], v[42:43]
	v_pk_add_f32 v[232:233], v[232:233], v[44:45]
	v_pk_add_f32 v[232:233], v[232:233], v[46:47]
	ds_read2_b32 v[32:33], v115 offset0:192 offset1:193
	ds_read2_b32 v[34:35], v115 offset0:194 offset1:195
	ds_read2_b32 v[36:37], v115 offset0:200 offset1:201
	ds_read2_b32 v[38:39], v115 offset0:202 offset1:203
	ds_read2_b32 v[40:41], v115 offset0:208 offset1:209
	ds_read2_b32 v[42:43], v115 offset0:210 offset1:211
	ds_read2_b32 v[44:45], v115 offset0:216 offset1:217
	ds_read2_b32 v[46:47], v115 offset0:218 offset1:219
	v_mfma_f32_32x32x16_bf16 v[0:15], v[64:67], v[72:75], v[0:15]
	v_mfma_f32_32x32x16_bf16 v[16:31], v[64:67], v[76:79], v[16:31]
	v_mfma_f32_32x32x16_bf16 v[0:15], v[68:71], v[220:223], v[0:15]
	v_mfma_f32_32x32x16_bf16 v[16:31], v[68:71], v[224:227], v[16:31]
	s_add_i32 s90, s76, 640
	v_add_u32_e32 v80, s90, v239
	v_add_u32_e32 v83, s90, v240
	v_add_u32_e32 v99, s90, v241
	v_add_u32_e32 v253, s90, v242
	v_add_u32_e32 v254, s90, v101
	v_add_u32_e32 v255, s90, v150
	v_med3_i32 v80, v80, 0, s99
	v_med3_i32 v83, v83, 0, s99
	v_med3_i32 v99, v99, 0, s99
	v_med3_i32 v253, v253, 0, s99
	v_med3_i32 v254, v254, 0, s99
	v_med3_i32 v255, v255, 0, s99
	v_mad_u32_u24 v80, v80, s100, v252
	v_mad_u32_u24 v83, v83, s100, v252
	v_mad_u32_u24 v99, v99, s100, v252
	v_mad_u32_u24 v253, v253, s100, v252
	v_mad_u32_u24 v254, v254, s100, v153
	v_mad_u32_u24 v255, v255, s100, v153
	global_load_dwordx4 v[156:159], v80, s[82:83]
	global_load_dwordx4 v[160:163], v83, s[82:83]
	global_load_dwordx4 v[164:167], v99, s[82:83]
	global_load_dwordx4 v[168:171], v253, s[82:83]
	global_load_dwordx4 v[172:175], v254, s[82:83] offset:768
	global_load_dwordx4 v[176:179], v255, s[82:83] offset:768
	global_load_dwordx4 v[180:183], v254, s[82:83] offset:832
	global_load_dwordx4 v[184:187], v255, s[82:83] offset:832
	ds_read_b64_tr_b16 v[72:73], v231
	ds_read_b64_tr_b16 v[74:75], v231 offset:512
	ds_read_b64_tr_b16 v[76:77], v231 offset:2048
	ds_read_b64_tr_b16 v[78:79], v231 offset:2560
	ds_read_b64_tr_b16 v[220:221], v231 offset:1024
	ds_read_b64_tr_b16 v[222:223], v231 offset:1536
	ds_read_b64_tr_b16 v[224:225], v231 offset:3072
	ds_read_b64_tr_b16 v[226:227], v231 offset:3584
	v_exp_f32_e32 v188, v188
	v_exp_f32_e32 v189, v189
	v_exp_f32_e32 v190, v190
	v_exp_f32_e32 v191, v191
	s_waitcnt vmcnt(12)
	ds_write_b128 v247, v[116:119]
	ds_write_b128 v247, v[120:123] offset:1024
	ds_write_b128 v247, v[124:127] offset:2048
	ds_write_b128 v247, v[128:131] offset:3072
	ds_read_b128 v[116:119], v248
	ds_read_b128 v[120:123], v249
	ds_read_b128 v[124:127], v250
	ds_read_b128 v[128:131], v251
	s_waitcnt vmcnt(8)
	ds_write_b128 v112, v[132:135]
	ds_write_b128 v112, v[136:139] offset:1024
	ds_write_b128 v112, v[140:143] offset:2048
	ds_write_b128 v112, v[144:147] offset:3072
	v_exp_f32_e32 v192, v192
	v_exp_f32_e32 v193, v193
	v_exp_f32_e32 v194, v194
	v_exp_f32_e32 v195, v195
	s_waitcnt lgkmcnt(4)
	v_mfma_f32_32x32x16_bf16 v[32:47], v[116:119], v[48:51], v[32:47]
	v_exp_f32_e32 v196, v196
	v_exp_f32_e32 v197, v197
	v_mfma_f32_32x32x16_bf16 v[32:47], v[120:123], v[52:55], v[32:47]
	v_exp_f32_e32 v198, v198
	v_exp_f32_e32 v199, v199
	v_mfma_f32_32x32x16_bf16 v[32:47], v[124:127], v[56:59], v[32:47]
	v_exp_f32_e32 v200, v200
	v_exp_f32_e32 v201, v201
	v_mfma_f32_32x32x16_bf16 v[32:47], v[128:131], v[60:63], v[32:47]
	v_exp_f32_e32 v202, v202
	v_exp_f32_e32 v203, v203
	s_add_i32 s90, s76, 384
	v_lshlrev_b32_e32 v84, 2, v107
	v_add_u32_e32 v84, s90, v84
	v_add_u32_e32 v85, 0, v84
	v_add_u32_e32 v86, 4, v84
	v_add_u32_e32 v87, 8, v84
	v_add_u32_e32 v88, 12, v84
	v_cmp_gt_u32_e64 s[30:31], s98, v85
	v_cmp_gt_u32_e64 s[36:37], s98, v86
	v_cmp_gt_u32_e64 s[78:79], s98, v87
	v_cmp_gt_u32_e64 s[50:51], s98, v88
	v_cndmask_b32_e64 v188, 0, v188, s[30:31]
	v_add_u32_e32 v85, 32, v84
	v_cmp_gt_u32_e64 s[30:31], s98, v85
	v_cndmask_b32_e64 v189, 0, v189, s[36:37]
	v_add_u32_e32 v86, 36, v84
	v_cmp_gt_u32_e64 s[36:37], s98, v86
	v_cndmask_b32_e64 v190, 0, v190, s[78:79]
	v_add_u32_e32 v87, 40, v84
	v_cmp_gt_u32_e64 s[78:79], s98, v87
	v_cndmask_b32_e64 v191, 0, v191, s[50:51]
	v_add_u32_e32 v88, 44, v84
	v_cmp_gt_u32_e64 s[50:51], s98, v88
	v_cndmask_b32_e64 v192, 0, v192, s[30:31]
	v_add_u32_e32 v85, 64, v84
	v_cmp_gt_u32_e64 s[30:31], s98, v85
	v_cndmask_b32_e64 v193, 0, v193, s[36:37]
	v_add_u32_e32 v86, 68, v84
	v_cmp_gt_u32_e64 s[36:37], s98, v86
	v_cndmask_b32_e64 v194, 0, v194, s[78:79]
	v_add_u32_e32 v87, 72, v84
	v_cmp_gt_u32_e64 s[78:79], s98, v87
	v_cndmask_b32_e64 v195, 0, v195, s[50:51]
	v_add_u32_e32 v88, 76, v84
	v_cmp_gt_u32_e64 s[50:51], s98, v88
	v_cndmask_b32_e64 v196, 0, v196, s[30:31]
	v_add_u32_e32 v85, 96, v84
	v_cmp_gt_u32_e64 s[30:31], s98, v85
	v_cndmask_b32_e64 v197, 0, v197, s[36:37]
	v_add_u32_e32 v86, 100, v84
	v_cmp_gt_u32_e64 s[36:37], s98, v86
	v_cndmask_b32_e64 v198, 0, v198, s[78:79]
	v_add_u32_e32 v87, 104, v84
	v_cmp_gt_u32_e64 s[78:79], s98, v87
	v_cndmask_b32_e64 v199, 0, v199, s[50:51]
	v_add_u32_e32 v88, 108, v84
	v_cmp_gt_u32_e64 s[50:51], s98, v88
	v_nop
	v_cndmask_b32_e64 v200, 0, v200, s[30:31]
	v_cndmask_b32_e64 v201, 0, v201, s[36:37]
	v_cndmask_b32_e64 v202, 0, v202, s[78:79]
	v_cndmask_b32_e64 v203, 0, v203, s[50:51]
	v_cvt_pk_bf16_f32 v64, v188, v189
	v_cvt_pk_bf16_f32 v65, v190, v191
	v_cvt_pk_bf16_f32 v66, v192, v193
	v_cvt_pk_bf16_f32 v67, v194, v195
	v_cvt_pk_bf16_f32 v68, v196, v197
	v_cvt_pk_bf16_f32 v69, v198, v199
	v_cvt_pk_bf16_f32 v70, v200, v201
	v_cvt_pk_bf16_f32 v71, v202, v203
	v_pk_add_f32 v[232:233], v[232:233], v[188:189]
	v_pk_add_f32 v[232:233], v[232:233], v[190:191]
	v_pk_add_f32 v[232:233], v[232:233], v[192:193]
	v_pk_add_f32 v[232:233], v[232:233], v[194:195]
	v_pk_add_f32 v[232:233], v[232:233], v[196:197]
	v_pk_add_f32 v[232:233], v[232:233], v[198:199]
	v_pk_add_f32 v[232:233], v[232:233], v[200:201]
	v_pk_add_f32 v[232:233], v[232:233], v[202:203]
	ds_read2_b32 v[188:189], v115 offset0:224 offset1:225
	ds_read2_b32 v[190:191], v115 offset0:226 offset1:227
	ds_read2_b32 v[192:193], v115 offset0:232 offset1:233
	ds_read2_b32 v[194:195], v115 offset0:234 offset1:235
	ds_read2_b32 v[196:197], v115 offset0:240 offset1:241
	ds_read2_b32 v[198:199], v115 offset0:242 offset1:243
	ds_read2_b32 v[200:201], v115 offset0:248 offset1:249
	ds_read2_b32 v[202:203], v115 offset0:250 offset1:251
	v_mfma_f32_32x32x16_bf16 v[0:15], v[64:67], v[72:75], v[0:15]
	v_mfma_f32_32x32x16_bf16 v[16:31], v[64:67], v[76:79], v[16:31]
	v_mfma_f32_32x32x16_bf16 v[0:15], v[68:71], v[220:223], v[0:15]
	v_mfma_f32_32x32x16_bf16 v[16:31], v[68:71], v[224:227], v[16:31]
	s_add_i32 s90, s76, -1024
	v_add_u32_e32 v80, s90, v243
	v_add_u32_e32 v83, s90, v244
	v_add_u32_e32 v99, s90, v245
	v_add_u32_e32 v253, s90, v246
	v_add_u32_e32 v254, s90, v148
	v_add_u32_e32 v255, s90, v151
	v_med3_i32 v80, v80, 0, s99
	v_med3_i32 v83, v83, 0, s99
	v_med3_i32 v99, v99, 0, s99
	v_med3_i32 v253, v253, 0, s99
	v_med3_i32 v254, v254, 0, s99
	v_med3_i32 v255, v255, 0, s99
	v_mad_u32_u24 v80, v80, s100, v252
	v_mad_u32_u24 v83, v83, s100, v252
	v_mad_u32_u24 v99, v99, s100, v252
	v_mad_u32_u24 v253, v253, s100, v252
	v_mad_u32_u24 v254, v254, s100, v153
	v_mad_u32_u24 v255, v255, s100, v153
	global_load_dwordx4 v[116:119], v80, s[82:83]
	global_load_dwordx4 v[120:123], v83, s[82:83]
	global_load_dwordx4 v[124:127], v99, s[82:83]
	global_load_dwordx4 v[128:131], v253, s[82:83]
	global_load_dwordx4 v[132:135], v254, s[82:83] offset:768
	global_load_dwordx4 v[136:139], v255, s[82:83] offset:768
	global_load_dwordx4 v[140:143], v254, s[82:83] offset:832
	global_load_dwordx4 v[144:147], v255, s[82:83] offset:832
	ds_read_b64_tr_b16 v[72:73], v231
	ds_read_b64_tr_b16 v[74:75], v231 offset:512
	ds_read_b64_tr_b16 v[76:77], v231 offset:2048
	ds_read_b64_tr_b16 v[78:79], v231 offset:2560
	ds_read_b64_tr_b16 v[220:221], v231 offset:1024
	ds_read_b64_tr_b16 v[222:223], v231 offset:1536
	ds_read_b64_tr_b16 v[224:225], v231 offset:3072
	ds_read_b64_tr_b16 v[226:227], v231 offset:3584
	v_exp_f32_e32 v32, v32
	v_exp_f32_e32 v33, v33
	v_exp_f32_e32 v34, v34
	v_exp_f32_e32 v35, v35
	s_waitcnt vmcnt(12)
	ds_write_b128 v247, v[156:159]
	ds_write_b128 v247, v[160:163] offset:1024
	ds_write_b128 v247, v[164:167] offset:2048
	ds_write_b128 v247, v[168:171] offset:3072
	ds_read_b128 v[156:159], v248
	ds_read_b128 v[160:163], v249
	ds_read_b128 v[164:167], v250
	ds_read_b128 v[168:171], v251
	s_waitcnt vmcnt(8)
	ds_write_b128 v112, v[172:175]
	ds_write_b128 v112, v[176:179] offset:1024
	ds_write_b128 v112, v[180:183] offset:2048
	ds_write_b128 v112, v[184:187] offset:3072
	v_exp_f32_e32 v36, v36
	v_exp_f32_e32 v37, v37
	v_exp_f32_e32 v38, v38
	v_exp_f32_e32 v39, v39
	s_waitcnt lgkmcnt(4)
	v_mfma_f32_32x32x16_bf16 v[188:203], v[156:159], v[48:51], v[188:203]
	v_exp_f32_e32 v40, v40
	v_exp_f32_e32 v41, v41
	v_mfma_f32_32x32x16_bf16 v[188:203], v[160:163], v[52:55], v[188:203]
	v_exp_f32_e32 v42, v42
	v_exp_f32_e32 v43, v43
	v_mfma_f32_32x32x16_bf16 v[188:203], v[164:167], v[56:59], v[188:203]
	v_exp_f32_e32 v44, v44
	v_exp_f32_e32 v45, v45
	v_mfma_f32_32x32x16_bf16 v[188:203], v[168:171], v[60:63], v[188:203]
	v_exp_f32_e32 v46, v46
	v_exp_f32_e32 v47, v47
	s_add_i32 s90, s76, 512
	v_lshlrev_b32_e32 v84, 2, v107
	v_add_u32_e32 v84, s90, v84
	v_add_u32_e32 v85, 0, v84
	v_add_u32_e32 v86, 4, v84
	v_add_u32_e32 v87, 8, v84
	v_add_u32_e32 v88, 12, v84
	v_cmp_gt_u32_e64 s[30:31], s98, v85
	v_cmp_gt_u32_e64 s[36:37], s98, v86
	v_cmp_gt_u32_e64 s[78:79], s98, v87
	v_cmp_gt_u32_e64 s[50:51], s98, v88
	v_cndmask_b32_e64 v32, 0, v32, s[30:31]
	v_add_u32_e32 v85, 32, v84
	v_cmp_gt_u32_e64 s[30:31], s98, v85
	v_cndmask_b32_e64 v33, 0, v33, s[36:37]
	v_add_u32_e32 v86, 36, v84
	v_cmp_gt_u32_e64 s[36:37], s98, v86
	v_cndmask_b32_e64 v34, 0, v34, s[78:79]
	v_add_u32_e32 v87, 40, v84
	v_cmp_gt_u32_e64 s[78:79], s98, v87
	v_cndmask_b32_e64 v35, 0, v35, s[50:51]
	v_add_u32_e32 v88, 44, v84
	v_cmp_gt_u32_e64 s[50:51], s98, v88
	v_cndmask_b32_e64 v36, 0, v36, s[30:31]
	v_add_u32_e32 v85, 64, v84
	v_cmp_gt_u32_e64 s[30:31], s98, v85
	v_cndmask_b32_e64 v37, 0, v37, s[36:37]
	v_add_u32_e32 v86, 68, v84
	v_cmp_gt_u32_e64 s[36:37], s98, v86
	v_cndmask_b32_e64 v38, 0, v38, s[78:79]
	v_add_u32_e32 v87, 72, v84
	v_cmp_gt_u32_e64 s[78:79], s98, v87
	v_cndmask_b32_e64 v39, 0, v39, s[50:51]
	v_add_u32_e32 v88, 76, v84
	v_cmp_gt_u32_e64 s[50:51], s98, v88
	v_cndmask_b32_e64 v40, 0, v40, s[30:31]
	v_add_u32_e32 v85, 96, v84
	v_cmp_gt_u32_e64 s[30:31], s98, v85
	v_cndmask_b32_e64 v41, 0, v41, s[36:37]
	v_add_u32_e32 v86, 100, v84
	v_cmp_gt_u32_e64 s[36:37], s98, v86
	v_cndmask_b32_e64 v42, 0, v42, s[78:79]
	v_add_u32_e32 v87, 104, v84
	v_cmp_gt_u32_e64 s[78:79], s98, v87
	v_cndmask_b32_e64 v43, 0, v43, s[50:51]
	v_add_u32_e32 v88, 108, v84
	v_cmp_gt_u32_e64 s[50:51], s98, v88
	v_nop
	v_cndmask_b32_e64 v44, 0, v44, s[30:31]
	v_cndmask_b32_e64 v45, 0, v45, s[36:37]
	v_cndmask_b32_e64 v46, 0, v46, s[78:79]
	v_cndmask_b32_e64 v47, 0, v47, s[50:51]
	v_cvt_pk_bf16_f32 v64, v32, v33
	v_cvt_pk_bf16_f32 v65, v34, v35
	v_cvt_pk_bf16_f32 v66, v36, v37
	v_cvt_pk_bf16_f32 v67, v38, v39
	v_cvt_pk_bf16_f32 v68, v40, v41
	v_cvt_pk_bf16_f32 v69, v42, v43
	v_cvt_pk_bf16_f32 v70, v44, v45
	v_cvt_pk_bf16_f32 v71, v46, v47
	v_pk_add_f32 v[232:233], v[232:233], v[32:33]
	v_pk_add_f32 v[232:233], v[232:233], v[34:35]
	v_pk_add_f32 v[232:233], v[232:233], v[36:37]
	v_pk_add_f32 v[232:233], v[232:233], v[38:39]
	v_pk_add_f32 v[232:233], v[232:233], v[40:41]
	v_pk_add_f32 v[232:233], v[232:233], v[42:43]
	v_pk_add_f32 v[232:233], v[232:233], v[44:45]
	v_pk_add_f32 v[232:233], v[232:233], v[46:47]
	v_mov_b32_e32 v115, v230
	ds_read2_b32 v[32:33], v115 offset0:0 offset1:1
	ds_read2_b32 v[34:35], v115 offset0:2 offset1:3
	ds_read2_b32 v[36:37], v115 offset0:8 offset1:9
	ds_read2_b32 v[38:39], v115 offset0:10 offset1:11
	ds_read2_b32 v[40:41], v115 offset0:16 offset1:17
	ds_read2_b32 v[42:43], v115 offset0:18 offset1:19
	ds_read2_b32 v[44:45], v115 offset0:24 offset1:25
	ds_read2_b32 v[46:47], v115 offset0:26 offset1:27
	v_mfma_f32_32x32x16_bf16 v[0:15], v[64:67], v[72:75], v[0:15]
	v_mfma_f32_32x32x16_bf16 v[16:31], v[64:67], v[76:79], v[16:31]
	v_mfma_f32_32x32x16_bf16 v[0:15], v[68:71], v[220:223], v[0:15]
	v_mfma_f32_32x32x16_bf16 v[16:31], v[68:71], v[224:227], v[16:31]
	s_add_i32 s90, s76, -512
	v_add_u32_e32 v80, s90, v243
	v_add_u32_e32 v83, s90, v244
	v_add_u32_e32 v99, s90, v245
	v_add_u32_e32 v253, s90, v246
	v_add_u32_e32 v254, s90, v148
	v_add_u32_e32 v255, s90, v151
	v_med3_i32 v80, v80, 0, s99
	v_med3_i32 v83, v83, 0, s99
	v_med3_i32 v99, v99, 0, s99
	v_med3_i32 v253, v253, 0, s99
	v_med3_i32 v254, v254, 0, s99
	v_med3_i32 v255, v255, 0, s99
	v_mad_u32_u24 v80, v80, s100, v252
	v_mad_u32_u24 v83, v83, s100, v252
	v_mad_u32_u24 v99, v99, s100, v252
	v_mad_u32_u24 v253, v253, s100, v252
	v_mad_u32_u24 v254, v254, s100, v153
	v_mad_u32_u24 v255, v255, s100, v153
	global_load_dwordx4 v[156:159], v80, s[82:83]
	global_load_dwordx4 v[160:163], v83, s[82:83]
	global_load_dwordx4 v[164:167], v99, s[82:83]
	global_load_dwordx4 v[168:171], v253, s[82:83]
	global_load_dwordx4 v[172:175], v254, s[82:83] offset:768
	global_load_dwordx4 v[176:179], v255, s[82:83] offset:768
	global_load_dwordx4 v[180:183], v254, s[82:83] offset:832
	global_load_dwordx4 v[184:187], v255, s[82:83] offset:832
	ds_read_b64_tr_b16 v[72:73], v231
	ds_read_b64_tr_b16 v[74:75], v231 offset:512
	ds_read_b64_tr_b16 v[76:77], v231 offset:2048
	ds_read_b64_tr_b16 v[78:79], v231 offset:2560
	ds_read_b64_tr_b16 v[220:221], v231 offset:1024
	ds_read_b64_tr_b16 v[222:223], v231 offset:1536
	ds_read_b64_tr_b16 v[224:225], v231 offset:3072
	ds_read_b64_tr_b16 v[226:227], v231 offset:3584
	v_exp_f32_e32 v188, v188
	v_exp_f32_e32 v189, v189
	v_exp_f32_e32 v190, v190
	v_exp_f32_e32 v191, v191
	s_waitcnt vmcnt(12)
	ds_write_b128 v247, v[116:119]
	ds_write_b128 v247, v[120:123] offset:1024
	ds_write_b128 v247, v[124:127] offset:2048
	ds_write_b128 v247, v[128:131] offset:3072
	ds_read_b128 v[116:119], v248
	ds_read_b128 v[120:123], v249
	ds_read_b128 v[124:127], v250
	ds_read_b128 v[128:131], v251
	s_waitcnt vmcnt(8)
	ds_write_b128 v112, v[132:135]
	ds_write_b128 v112, v[136:139] offset:1024
	ds_write_b128 v112, v[140:143] offset:2048
	ds_write_b128 v112, v[144:147] offset:3072
	v_exp_f32_e32 v192, v192
	v_exp_f32_e32 v193, v193
	v_exp_f32_e32 v194, v194
	v_exp_f32_e32 v195, v195
	s_waitcnt lgkmcnt(4)
	v_mfma_f32_32x32x16_bf16 v[32:47], v[116:119], v[48:51], v[32:47]
	v_exp_f32_e32 v196, v196
	v_exp_f32_e32 v197, v197
	v_mfma_f32_32x32x16_bf16 v[32:47], v[120:123], v[52:55], v[32:47]
	v_exp_f32_e32 v198, v198
	v_exp_f32_e32 v199, v199
	v_mfma_f32_32x32x16_bf16 v[32:47], v[124:127], v[56:59], v[32:47]
	v_exp_f32_e32 v200, v200
	v_exp_f32_e32 v201, v201
	v_mfma_f32_32x32x16_bf16 v[32:47], v[128:131], v[60:63], v[32:47]
	v_exp_f32_e32 v202, v202
	v_exp_f32_e32 v203, v203
	s_add_i32 s90, s76, 640
	v_lshlrev_b32_e32 v84, 2, v107
	v_add_u32_e32 v84, s90, v84
	v_add_u32_e32 v85, 0, v84
	v_add_u32_e32 v86, 4, v84
	v_add_u32_e32 v87, 8, v84
	v_add_u32_e32 v88, 12, v84
	v_cmp_gt_u32_e64 s[30:31], s98, v85
	v_cmp_gt_u32_e64 s[36:37], s98, v86
	v_cmp_gt_u32_e64 s[78:79], s98, v87
	v_cmp_gt_u32_e64 s[50:51], s98, v88
	v_cndmask_b32_e64 v188, 0, v188, s[30:31]
	v_add_u32_e32 v85, 32, v84
	v_cmp_gt_u32_e64 s[30:31], s98, v85
	v_cndmask_b32_e64 v189, 0, v189, s[36:37]
	v_add_u32_e32 v86, 36, v84
	v_cmp_gt_u32_e64 s[36:37], s98, v86
	v_cndmask_b32_e64 v190, 0, v190, s[78:79]
	v_add_u32_e32 v87, 40, v84
	v_cmp_gt_u32_e64 s[78:79], s98, v87
	v_cndmask_b32_e64 v191, 0, v191, s[50:51]
	v_add_u32_e32 v88, 44, v84
	v_cmp_gt_u32_e64 s[50:51], s98, v88
	v_cndmask_b32_e64 v192, 0, v192, s[30:31]
	v_add_u32_e32 v85, 64, v84
	v_cmp_gt_u32_e64 s[30:31], s98, v85
	v_cndmask_b32_e64 v193, 0, v193, s[36:37]
	v_add_u32_e32 v86, 68, v84
	v_cmp_gt_u32_e64 s[36:37], s98, v86
	v_cndmask_b32_e64 v194, 0, v194, s[78:79]
	v_add_u32_e32 v87, 72, v84
	v_cmp_gt_u32_e64 s[78:79], s98, v87
	v_cndmask_b32_e64 v195, 0, v195, s[50:51]
	v_add_u32_e32 v88, 76, v84
	v_cmp_gt_u32_e64 s[50:51], s98, v88
	v_cndmask_b32_e64 v196, 0, v196, s[30:31]
	v_add_u32_e32 v85, 96, v84
	v_cmp_gt_u32_e64 s[30:31], s98, v85
	v_cndmask_b32_e64 v197, 0, v197, s[36:37]
	v_add_u32_e32 v86, 100, v84
	v_cmp_gt_u32_e64 s[36:37], s98, v86
	v_cndmask_b32_e64 v198, 0, v198, s[78:79]
	v_add_u32_e32 v87, 104, v84
	v_cmp_gt_u32_e64 s[78:79], s98, v87
	v_cndmask_b32_e64 v199, 0, v199, s[50:51]
	v_add_u32_e32 v88, 108, v84
	v_cmp_gt_u32_e64 s[50:51], s98, v88
	v_nop
	v_cndmask_b32_e64 v200, 0, v200, s[30:31]
	v_cndmask_b32_e64 v201, 0, v201, s[36:37]
	v_cndmask_b32_e64 v202, 0, v202, s[78:79]
	v_cndmask_b32_e64 v203, 0, v203, s[50:51]
	v_cvt_pk_bf16_f32 v64, v188, v189
	v_cvt_pk_bf16_f32 v65, v190, v191
	v_cvt_pk_bf16_f32 v66, v192, v193
	v_cvt_pk_bf16_f32 v67, v194, v195
	v_cvt_pk_bf16_f32 v68, v196, v197
	v_cvt_pk_bf16_f32 v69, v198, v199
	v_cvt_pk_bf16_f32 v70, v200, v201
	v_cvt_pk_bf16_f32 v71, v202, v203
	v_pk_add_f32 v[232:233], v[232:233], v[188:189]
	v_pk_add_f32 v[232:233], v[232:233], v[190:191]
	v_pk_add_f32 v[232:233], v[232:233], v[192:193]
	v_pk_add_f32 v[232:233], v[232:233], v[194:195]
	v_pk_add_f32 v[232:233], v[232:233], v[196:197]
	v_pk_add_f32 v[232:233], v[232:233], v[198:199]
	v_pk_add_f32 v[232:233], v[232:233], v[200:201]
	v_pk_add_f32 v[232:233], v[232:233], v[202:203]
	ds_read2_b32 v[188:189], v115 offset0:32 offset1:33
	ds_read2_b32 v[190:191], v115 offset0:34 offset1:35
	ds_read2_b32 v[192:193], v115 offset0:40 offset1:41
	ds_read2_b32 v[194:195], v115 offset0:42 offset1:43
	ds_read2_b32 v[196:197], v115 offset0:48 offset1:49
	ds_read2_b32 v[198:199], v115 offset0:50 offset1:51
	ds_read2_b32 v[200:201], v115 offset0:56 offset1:57
	ds_read2_b32 v[202:203], v115 offset0:58 offset1:59
	v_mfma_f32_32x32x16_bf16 v[0:15], v[64:67], v[72:75], v[0:15]
	v_mfma_f32_32x32x16_bf16 v[16:31], v[64:67], v[76:79], v[16:31]
	v_mfma_f32_32x32x16_bf16 v[0:15], v[68:71], v[220:223], v[0:15]
	v_mfma_f32_32x32x16_bf16 v[16:31], v[68:71], v[224:227], v[16:31]
	s_add_i32 s90, s76, 0
	v_add_u32_e32 v80, s90, v243
	v_add_u32_e32 v83, s90, v244
	v_add_u32_e32 v99, s90, v245
	v_add_u32_e32 v253, s90, v246
	v_add_u32_e32 v254, s90, v148
	v_add_u32_e32 v255, s90, v151
	v_med3_i32 v80, v80, 0, s99
	v_med3_i32 v83, v83, 0, s99
	v_med3_i32 v99, v99, 0, s99
	v_med3_i32 v253, v253, 0, s99
	v_med3_i32 v254, v254, 0, s99
	v_med3_i32 v255, v255, 0, s99
	v_mad_u32_u24 v80, v80, s100, v252
	v_mad_u32_u24 v83, v83, s100, v252
	v_mad_u32_u24 v99, v99, s100, v252
	v_mad_u32_u24 v253, v253, s100, v252
	v_mad_u32_u24 v254, v254, s100, v153
	v_mad_u32_u24 v255, v255, s100, v153
	global_load_dwordx4 v[116:119], v80, s[82:83]
	global_load_dwordx4 v[120:123], v83, s[82:83]
	global_load_dwordx4 v[124:127], v99, s[82:83]
	global_load_dwordx4 v[128:131], v253, s[82:83]
	global_load_dwordx4 v[132:135], v254, s[82:83] offset:768
	global_load_dwordx4 v[136:139], v255, s[82:83] offset:768
	global_load_dwordx4 v[140:143], v254, s[82:83] offset:832
	global_load_dwordx4 v[144:147], v255, s[82:83] offset:832
	ds_read_b64_tr_b16 v[72:73], v231
	ds_read_b64_tr_b16 v[74:75], v231 offset:512
	ds_read_b64_tr_b16 v[76:77], v231 offset:2048
	ds_read_b64_tr_b16 v[78:79], v231 offset:2560
	ds_read_b64_tr_b16 v[220:221], v231 offset:1024
	ds_read_b64_tr_b16 v[222:223], v231 offset:1536
	ds_read_b64_tr_b16 v[224:225], v231 offset:3072
	ds_read_b64_tr_b16 v[226:227], v231 offset:3584
	v_exp_f32_e32 v32, v32
	v_exp_f32_e32 v33, v33
	v_exp_f32_e32 v34, v34
	v_exp_f32_e32 v35, v35
	s_waitcnt vmcnt(12)
	ds_write_b128 v247, v[156:159]
	ds_write_b128 v247, v[160:163] offset:1024
	ds_write_b128 v247, v[164:167] offset:2048
	ds_write_b128 v247, v[168:171] offset:3072
	ds_read_b128 v[156:159], v248
	ds_read_b128 v[160:163], v249
	ds_read_b128 v[164:167], v250
	ds_read_b128 v[168:171], v251
	s_waitcnt vmcnt(8)
	ds_write_b128 v112, v[172:175]
	ds_write_b128 v112, v[176:179] offset:1024
	ds_write_b128 v112, v[180:183] offset:2048
	ds_write_b128 v112, v[184:187] offset:3072
	v_exp_f32_e32 v36, v36
	v_exp_f32_e32 v37, v37
	v_exp_f32_e32 v38, v38
	v_exp_f32_e32 v39, v39
	s_waitcnt lgkmcnt(4)
	v_mfma_f32_32x32x16_bf16 v[188:203], v[156:159], v[48:51], v[188:203]
	v_exp_f32_e32 v40, v40
	v_exp_f32_e32 v41, v41
	v_mfma_f32_32x32x16_bf16 v[188:203], v[160:163], v[52:55], v[188:203]
	v_exp_f32_e32 v42, v42
	v_exp_f32_e32 v43, v43
	v_mfma_f32_32x32x16_bf16 v[188:203], v[164:167], v[56:59], v[188:203]
	v_exp_f32_e32 v44, v44
	v_exp_f32_e32 v45, v45
	v_mfma_f32_32x32x16_bf16 v[188:203], v[168:171], v[60:63], v[188:203]
	v_exp_f32_e32 v46, v46
	v_exp_f32_e32 v47, v47
	s_add_i32 s90, s76, -1024
	v_lshlrev_b32_e32 v84, 4, v107
	v_add_u32_e32 v84, s90, v84
	v_add_u32_e32 v85, 0, v84
	v_add_u32_e32 v86, 16, v84
	v_add_u32_e32 v87, 32, v84
	v_add_u32_e32 v88, 48, v84
	v_cmp_gt_u32_e64 s[30:31], s98, v85
	v_cmp_gt_u32_e64 s[36:37], s98, v86
	v_cmp_gt_u32_e64 s[78:79], s98, v87
	v_cmp_gt_u32_e64 s[50:51], s98, v88
	v_cndmask_b32_e64 v32, 0, v32, s[30:31]
	v_add_u32_e32 v85, 128, v84
	v_cmp_gt_u32_e64 s[30:31], s98, v85
	v_cndmask_b32_e64 v33, 0, v33, s[36:37]
	v_add_u32_e32 v86, 144, v84
	v_cmp_gt_u32_e64 s[36:37], s98, v86
	v_cndmask_b32_e64 v34, 0, v34, s[78:79]
	v_add_u32_e32 v87, 160, v84
	v_cmp_gt_u32_e64 s[78:79], s98, v87
	v_cndmask_b32_e64 v35, 0, v35, s[50:51]
	v_add_u32_e32 v88, 176, v84
	v_cmp_gt_u32_e64 s[50:51], s98, v88
	v_cndmask_b32_e64 v36, 0, v36, s[30:31]
	v_add_u32_e32 v85, 256, v84
	v_cmp_gt_u32_e64 s[30:31], s98, v85
	v_cndmask_b32_e64 v37, 0, v37, s[36:37]
	v_add_u32_e32 v86, 272, v84
	v_cmp_gt_u32_e64 s[36:37], s98, v86
	v_cndmask_b32_e64 v38, 0, v38, s[78:79]
	v_add_u32_e32 v87, 288, v84
	v_cmp_gt_u32_e64 s[78:79], s98, v87
	v_cndmask_b32_e64 v39, 0, v39, s[50:51]
	v_add_u32_e32 v88, 304, v84
	v_cmp_gt_u32_e64 s[50:51], s98, v88
	v_cndmask_b32_e64 v40, 0, v40, s[30:31]
	v_add_u32_e32 v85, 384, v84
	v_cmp_gt_u32_e64 s[30:31], s98, v85
	v_cndmask_b32_e64 v41, 0, v41, s[36:37]
	v_add_u32_e32 v86, 400, v84
	v_cmp_gt_u32_e64 s[36:37], s98, v86
	v_cndmask_b32_e64 v42, 0, v42, s[78:79]
	v_add_u32_e32 v87, 416, v84
	v_cmp_gt_u32_e64 s[78:79], s98, v87
	v_cndmask_b32_e64 v43, 0, v43, s[50:51]
	v_add_u32_e32 v88, 432, v84
	v_cmp_gt_u32_e64 s[50:51], s98, v88
	v_nop
	v_cndmask_b32_e64 v44, 0, v44, s[30:31]
	v_cndmask_b32_e64 v45, 0, v45, s[36:37]
	v_cndmask_b32_e64 v46, 0, v46, s[78:79]
	v_cndmask_b32_e64 v47, 0, v47, s[50:51]
	v_cvt_pk_bf16_f32 v64, v32, v33
	v_cvt_pk_bf16_f32 v65, v34, v35
	v_cvt_pk_bf16_f32 v66, v36, v37
	v_cvt_pk_bf16_f32 v67, v38, v39
	v_cvt_pk_bf16_f32 v68, v40, v41
	v_cvt_pk_bf16_f32 v69, v42, v43
	v_cvt_pk_bf16_f32 v70, v44, v45
	v_cvt_pk_bf16_f32 v71, v46, v47
	v_pk_add_f32 v[232:233], v[232:233], v[32:33]
	v_pk_add_f32 v[232:233], v[232:233], v[34:35]
	v_pk_add_f32 v[232:233], v[232:233], v[36:37]
	v_pk_add_f32 v[232:233], v[232:233], v[38:39]
	v_pk_add_f32 v[232:233], v[232:233], v[40:41]
	v_pk_add_f32 v[232:233], v[232:233], v[42:43]
	v_pk_add_f32 v[232:233], v[232:233], v[44:45]
	v_pk_add_f32 v[232:233], v[232:233], v[46:47]
	ds_read2_b32 v[32:33], v115 offset0:64 offset1:65
	ds_read2_b32 v[34:35], v115 offset0:66 offset1:67
	ds_read2_b32 v[36:37], v115 offset0:72 offset1:73
	ds_read2_b32 v[38:39], v115 offset0:74 offset1:75
	ds_read2_b32 v[40:41], v115 offset0:80 offset1:81
	ds_read2_b32 v[42:43], v115 offset0:82 offset1:83
	ds_read2_b32 v[44:45], v115 offset0:88 offset1:89
	ds_read2_b32 v[46:47], v115 offset0:90 offset1:91
	v_mfma_f32_32x32x16_bf16 v[0:15], v[64:67], v[72:75], v[0:15]
	v_mfma_f32_32x32x16_bf16 v[16:31], v[64:67], v[76:79], v[16:31]
	v_mfma_f32_32x32x16_bf16 v[0:15], v[68:71], v[220:223], v[0:15]
	v_mfma_f32_32x32x16_bf16 v[16:31], v[68:71], v[224:227], v[16:31]
	s_add_i32 s90, s76, 512
	v_add_u32_e32 v80, s90, v243
	v_add_u32_e32 v83, s90, v244
	v_add_u32_e32 v99, s90, v245
	v_add_u32_e32 v253, s90, v246
	v_add_u32_e32 v254, s90, v148
	v_add_u32_e32 v255, s90, v151
	v_med3_i32 v80, v80, 0, s99
	v_med3_i32 v83, v83, 0, s99
	v_med3_i32 v99, v99, 0, s99
	v_med3_i32 v253, v253, 0, s99
	v_med3_i32 v254, v254, 0, s99
	v_med3_i32 v255, v255, 0, s99
	v_mad_u32_u24 v80, v80, s100, v252
	v_mad_u32_u24 v83, v83, s100, v252
	v_mad_u32_u24 v99, v99, s100, v252
	v_mad_u32_u24 v253, v253, s100, v252
	v_mad_u32_u24 v254, v254, s100, v153
	v_mad_u32_u24 v255, v255, s100, v153
	global_load_dwordx4 v[156:159], v80, s[82:83]
	global_load_dwordx4 v[160:163], v83, s[82:83]
	global_load_dwordx4 v[164:167], v99, s[82:83]
	global_load_dwordx4 v[168:171], v253, s[82:83]
	global_load_dwordx4 v[172:175], v254, s[82:83] offset:768
	global_load_dwordx4 v[176:179], v255, s[82:83] offset:768
	global_load_dwordx4 v[180:183], v254, s[82:83] offset:832
	global_load_dwordx4 v[184:187], v255, s[82:83] offset:832
	ds_read_b64_tr_b16 v[72:73], v231
	ds_read_b64_tr_b16 v[74:75], v231 offset:512
	ds_read_b64_tr_b16 v[76:77], v231 offset:2048
	ds_read_b64_tr_b16 v[78:79], v231 offset:2560
	ds_read_b64_tr_b16 v[220:221], v231 offset:1024
	ds_read_b64_tr_b16 v[222:223], v231 offset:1536
	ds_read_b64_tr_b16 v[224:225], v231 offset:3072
	ds_read_b64_tr_b16 v[226:227], v231 offset:3584
	v_exp_f32_e32 v188, v188
	v_exp_f32_e32 v189, v189
	v_exp_f32_e32 v190, v190
	v_exp_f32_e32 v191, v191
	s_waitcnt vmcnt(12)
	ds_write_b128 v247, v[116:119]
	ds_write_b128 v247, v[120:123] offset:1024
	ds_write_b128 v247, v[124:127] offset:2048
	ds_write_b128 v247, v[128:131] offset:3072
	ds_read_b128 v[116:119], v248
	ds_read_b128 v[120:123], v249
	ds_read_b128 v[124:127], v250
	ds_read_b128 v[128:131], v251
	s_waitcnt vmcnt(8)
	ds_write_b128 v112, v[132:135]
	ds_write_b128 v112, v[136:139] offset:1024
	ds_write_b128 v112, v[140:143] offset:2048
	ds_write_b128 v112, v[144:147] offset:3072
	v_exp_f32_e32 v192, v192
	v_exp_f32_e32 v193, v193
	v_exp_f32_e32 v194, v194
	v_exp_f32_e32 v195, v195
	s_waitcnt lgkmcnt(4)
	v_mfma_f32_32x32x16_bf16 v[32:47], v[116:119], v[48:51], v[32:47]
	v_exp_f32_e32 v196, v196
	v_exp_f32_e32 v197, v197
	v_mfma_f32_32x32x16_bf16 v[32:47], v[120:123], v[52:55], v[32:47]
	v_exp_f32_e32 v198, v198
	v_exp_f32_e32 v199, v199
	v_mfma_f32_32x32x16_bf16 v[32:47], v[124:127], v[56:59], v[32:47]
	v_exp_f32_e32 v200, v200
	v_exp_f32_e32 v201, v201
	v_mfma_f32_32x32x16_bf16 v[32:47], v[128:131], v[60:63], v[32:47]
	v_exp_f32_e32 v202, v202
	v_exp_f32_e32 v203, v203
	s_add_i32 s90, s76, -512
	v_lshlrev_b32_e32 v84, 4, v107
	v_add_u32_e32 v84, s90, v84
	v_add_u32_e32 v85, 0, v84
	v_add_u32_e32 v86, 16, v84
	v_add_u32_e32 v87, 32, v84
	v_add_u32_e32 v88, 48, v84
	v_cmp_gt_u32_e64 s[30:31], s98, v85
	v_cmp_gt_u32_e64 s[36:37], s98, v86
	v_cmp_gt_u32_e64 s[78:79], s98, v87
	v_cmp_gt_u32_e64 s[50:51], s98, v88
	v_cndmask_b32_e64 v188, 0, v188, s[30:31]
	v_add_u32_e32 v85, 128, v84
	v_cmp_gt_u32_e64 s[30:31], s98, v85
	v_cndmask_b32_e64 v189, 0, v189, s[36:37]
	v_add_u32_e32 v86, 144, v84
	v_cmp_gt_u32_e64 s[36:37], s98, v86
	v_cndmask_b32_e64 v190, 0, v190, s[78:79]
	v_add_u32_e32 v87, 160, v84
	v_cmp_gt_u32_e64 s[78:79], s98, v87
	v_cndmask_b32_e64 v191, 0, v191, s[50:51]
	v_add_u32_e32 v88, 176, v84
	v_cmp_gt_u32_e64 s[50:51], s98, v88
	v_cndmask_b32_e64 v192, 0, v192, s[30:31]
	v_add_u32_e32 v85, 256, v84
	v_cmp_gt_u32_e64 s[30:31], s98, v85
	v_cndmask_b32_e64 v193, 0, v193, s[36:37]
	v_add_u32_e32 v86, 272, v84
	v_cmp_gt_u32_e64 s[36:37], s98, v86
	v_cndmask_b32_e64 v194, 0, v194, s[78:79]
	v_add_u32_e32 v87, 288, v84
	v_cmp_gt_u32_e64 s[78:79], s98, v87
	v_cndmask_b32_e64 v195, 0, v195, s[50:51]
	v_add_u32_e32 v88, 304, v84
	v_cmp_gt_u32_e64 s[50:51], s98, v88
	v_cndmask_b32_e64 v196, 0, v196, s[30:31]
	v_add_u32_e32 v85, 384, v84
	v_cmp_gt_u32_e64 s[30:31], s98, v85
	v_cndmask_b32_e64 v197, 0, v197, s[36:37]
	v_add_u32_e32 v86, 400, v84
	v_cmp_gt_u32_e64 s[36:37], s98, v86
	v_cndmask_b32_e64 v198, 0, v198, s[78:79]
	v_add_u32_e32 v87, 416, v84
	v_cmp_gt_u32_e64 s[78:79], s98, v87
	v_cndmask_b32_e64 v199, 0, v199, s[50:51]
	v_add_u32_e32 v88, 432, v84
	v_cmp_gt_u32_e64 s[50:51], s98, v88
	v_nop
	v_cndmask_b32_e64 v200, 0, v200, s[30:31]
	v_cndmask_b32_e64 v201, 0, v201, s[36:37]
	v_cndmask_b32_e64 v202, 0, v202, s[78:79]
	v_cndmask_b32_e64 v203, 0, v203, s[50:51]
	v_cvt_pk_bf16_f32 v64, v188, v189
	v_cvt_pk_bf16_f32 v65, v190, v191
	v_cvt_pk_bf16_f32 v66, v192, v193
	v_cvt_pk_bf16_f32 v67, v194, v195
	v_cvt_pk_bf16_f32 v68, v196, v197
	v_cvt_pk_bf16_f32 v69, v198, v199
	v_cvt_pk_bf16_f32 v70, v200, v201
	v_cvt_pk_bf16_f32 v71, v202, v203
	v_pk_add_f32 v[232:233], v[232:233], v[188:189]
	v_pk_add_f32 v[232:233], v[232:233], v[190:191]
	v_pk_add_f32 v[232:233], v[232:233], v[192:193]
	v_pk_add_f32 v[232:233], v[232:233], v[194:195]
	v_pk_add_f32 v[232:233], v[232:233], v[196:197]
	v_pk_add_f32 v[232:233], v[232:233], v[198:199]
	v_pk_add_f32 v[232:233], v[232:233], v[200:201]
	v_pk_add_f32 v[232:233], v[232:233], v[202:203]
	ds_read2_b32 v[188:189], v115 offset0:96 offset1:97
	ds_read2_b32 v[190:191], v115 offset0:98 offset1:99
	ds_read2_b32 v[192:193], v115 offset0:104 offset1:105
	ds_read2_b32 v[194:195], v115 offset0:106 offset1:107
	ds_read2_b32 v[196:197], v115 offset0:112 offset1:113
	ds_read2_b32 v[198:199], v115 offset0:114 offset1:115
	ds_read2_b32 v[200:201], v115 offset0:120 offset1:121
	ds_read2_b32 v[202:203], v115 offset0:122 offset1:123
	v_mfma_f32_32x32x16_bf16 v[0:15], v[64:67], v[72:75], v[0:15]
	v_mfma_f32_32x32x16_bf16 v[16:31], v[64:67], v[76:79], v[16:31]
	v_mfma_f32_32x32x16_bf16 v[0:15], v[68:71], v[220:223], v[0:15]
	v_mfma_f32_32x32x16_bf16 v[16:31], v[68:71], v[224:227], v[16:31]
	s_add_i32 s90, s76, 1024
	v_add_u32_e32 v80, s90, v243
	v_add_u32_e32 v83, s90, v244
	v_add_u32_e32 v99, s90, v245
	v_add_u32_e32 v253, s90, v246
	v_add_u32_e32 v254, s90, v148
	v_add_u32_e32 v255, s90, v151
	v_med3_i32 v80, v80, 0, s99
	v_med3_i32 v83, v83, 0, s99
	v_med3_i32 v99, v99, 0, s99
	v_med3_i32 v253, v253, 0, s99
	v_med3_i32 v254, v254, 0, s99
	v_med3_i32 v255, v255, 0, s99
	v_mad_u32_u24 v80, v80, s100, v252
	v_mad_u32_u24 v83, v83, s100, v252
	v_mad_u32_u24 v99, v99, s100, v252
	v_mad_u32_u24 v253, v253, s100, v252
	v_mad_u32_u24 v254, v254, s100, v153
	v_mad_u32_u24 v255, v255, s100, v153
	global_load_dwordx4 v[116:119], v80, s[82:83]
	global_load_dwordx4 v[120:123], v83, s[82:83]
	global_load_dwordx4 v[124:127], v99, s[82:83]
	global_load_dwordx4 v[128:131], v253, s[82:83]
	global_load_dwordx4 v[132:135], v254, s[82:83] offset:768
	global_load_dwordx4 v[136:139], v255, s[82:83] offset:768
	global_load_dwordx4 v[140:143], v254, s[82:83] offset:832
	global_load_dwordx4 v[144:147], v255, s[82:83] offset:832
	ds_read_b64_tr_b16 v[72:73], v231
	ds_read_b64_tr_b16 v[74:75], v231 offset:512
	ds_read_b64_tr_b16 v[76:77], v231 offset:2048
	ds_read_b64_tr_b16 v[78:79], v231 offset:2560
	ds_read_b64_tr_b16 v[220:221], v231 offset:1024
	ds_read_b64_tr_b16 v[222:223], v231 offset:1536
	ds_read_b64_tr_b16 v[224:225], v231 offset:3072
	ds_read_b64_tr_b16 v[226:227], v231 offset:3584
	v_exp_f32_e32 v32, v32
	v_exp_f32_e32 v33, v33
	v_exp_f32_e32 v34, v34
	v_exp_f32_e32 v35, v35
	s_waitcnt vmcnt(12)
	ds_write_b128 v247, v[156:159]
	ds_write_b128 v247, v[160:163] offset:1024
	ds_write_b128 v247, v[164:167] offset:2048
	ds_write_b128 v247, v[168:171] offset:3072
	ds_read_b128 v[156:159], v248
	ds_read_b128 v[160:163], v249
	ds_read_b128 v[164:167], v250
	ds_read_b128 v[168:171], v251
	s_waitcnt vmcnt(8)
	ds_write_b128 v112, v[172:175]
	ds_write_b128 v112, v[176:179] offset:1024
	ds_write_b128 v112, v[180:183] offset:2048
	ds_write_b128 v112, v[184:187] offset:3072
	v_exp_f32_e32 v36, v36
	v_exp_f32_e32 v37, v37
	v_exp_f32_e32 v38, v38
	v_exp_f32_e32 v39, v39
	s_waitcnt lgkmcnt(4)
	v_mfma_f32_32x32x16_bf16 v[188:203], v[156:159], v[48:51], v[188:203]
	v_exp_f32_e32 v40, v40
	v_exp_f32_e32 v41, v41
	v_mfma_f32_32x32x16_bf16 v[188:203], v[160:163], v[52:55], v[188:203]
	v_exp_f32_e32 v42, v42
	v_exp_f32_e32 v43, v43
	v_mfma_f32_32x32x16_bf16 v[188:203], v[164:167], v[56:59], v[188:203]
	v_exp_f32_e32 v44, v44
	v_exp_f32_e32 v45, v45
	v_mfma_f32_32x32x16_bf16 v[188:203], v[168:171], v[60:63], v[188:203]
	v_exp_f32_e32 v46, v46
	v_exp_f32_e32 v47, v47
	s_add_i32 s90, s76, 0
	v_lshlrev_b32_e32 v84, 4, v107
	v_add_u32_e32 v84, s90, v84
	v_add_u32_e32 v85, 0, v84
	v_add_u32_e32 v86, 16, v84
	v_add_u32_e32 v87, 32, v84
	v_add_u32_e32 v88, 48, v84
	v_cmp_gt_u32_e64 s[30:31], s98, v85
	v_cmp_gt_u32_e64 s[36:37], s98, v86
	v_cmp_gt_u32_e64 s[78:79], s98, v87
	v_cmp_gt_u32_e64 s[50:51], s98, v88
	v_cndmask_b32_e64 v32, 0, v32, s[30:31]
	v_add_u32_e32 v85, 128, v84
	v_cmp_gt_u32_e64 s[30:31], s98, v85
	v_cndmask_b32_e64 v33, 0, v33, s[36:37]
	v_add_u32_e32 v86, 144, v84
	v_cmp_gt_u32_e64 s[36:37], s98, v86
	v_cndmask_b32_e64 v34, 0, v34, s[78:79]
	v_add_u32_e32 v87, 160, v84
	v_cmp_gt_u32_e64 s[78:79], s98, v87
	v_cndmask_b32_e64 v35, 0, v35, s[50:51]
	v_add_u32_e32 v88, 176, v84
	v_cmp_gt_u32_e64 s[50:51], s98, v88
	v_cndmask_b32_e64 v36, 0, v36, s[30:31]
	v_add_u32_e32 v85, 256, v84
	v_cmp_gt_u32_e64 s[30:31], s98, v85
	v_cndmask_b32_e64 v37, 0, v37, s[36:37]
	v_add_u32_e32 v86, 272, v84
	v_cmp_gt_u32_e64 s[36:37], s98, v86
	v_cndmask_b32_e64 v38, 0, v38, s[78:79]
	v_add_u32_e32 v87, 288, v84
	v_cmp_gt_u32_e64 s[78:79], s98, v87
	v_cndmask_b32_e64 v39, 0, v39, s[50:51]
	v_add_u32_e32 v88, 304, v84
	v_cmp_gt_u32_e64 s[50:51], s98, v88
	v_cndmask_b32_e64 v40, 0, v40, s[30:31]
	v_add_u32_e32 v85, 384, v84
	v_cmp_gt_u32_e64 s[30:31], s98, v85
	v_cndmask_b32_e64 v41, 0, v41, s[36:37]
	v_add_u32_e32 v86, 400, v84
	v_cmp_gt_u32_e64 s[36:37], s98, v86
	v_cndmask_b32_e64 v42, 0, v42, s[78:79]
	v_add_u32_e32 v87, 416, v84
	v_cmp_gt_u32_e64 s[78:79], s98, v87
	v_cndmask_b32_e64 v43, 0, v43, s[50:51]
	v_add_u32_e32 v88, 432, v84
	v_cmp_gt_u32_e64 s[50:51], s98, v88
	v_nop
	v_cndmask_b32_e64 v44, 0, v44, s[30:31]
	v_cndmask_b32_e64 v45, 0, v45, s[36:37]
	v_cndmask_b32_e64 v46, 0, v46, s[78:79]
	v_cndmask_b32_e64 v47, 0, v47, s[50:51]
	v_cvt_pk_bf16_f32 v64, v32, v33
	v_cvt_pk_bf16_f32 v65, v34, v35
	v_cvt_pk_bf16_f32 v66, v36, v37
	v_cvt_pk_bf16_f32 v67, v38, v39
	v_cvt_pk_bf16_f32 v68, v40, v41
	v_cvt_pk_bf16_f32 v69, v42, v43
	v_cvt_pk_bf16_f32 v70, v44, v45
	v_cvt_pk_bf16_f32 v71, v46, v47
	v_pk_add_f32 v[232:233], v[232:233], v[32:33]
	v_pk_add_f32 v[232:233], v[232:233], v[34:35]
	v_pk_add_f32 v[232:233], v[232:233], v[36:37]
	v_pk_add_f32 v[232:233], v[232:233], v[38:39]
	v_pk_add_f32 v[232:233], v[232:233], v[40:41]
	v_pk_add_f32 v[232:233], v[232:233], v[42:43]
	v_pk_add_f32 v[232:233], v[232:233], v[44:45]
	v_pk_add_f32 v[232:233], v[232:233], v[46:47]
	ds_read2_b32 v[32:33], v115 offset0:128 offset1:129
	ds_read2_b32 v[34:35], v115 offset0:130 offset1:131
	ds_read2_b32 v[36:37], v115 offset0:136 offset1:137
	ds_read2_b32 v[38:39], v115 offset0:138 offset1:139
	ds_read2_b32 v[40:41], v115 offset0:144 offset1:145
	ds_read2_b32 v[42:43], v115 offset0:146 offset1:147
	ds_read2_b32 v[44:45], v115 offset0:152 offset1:153
	ds_read2_b32 v[46:47], v115 offset0:154 offset1:155
	v_mfma_f32_32x32x16_bf16 v[0:15], v[64:67], v[72:75], v[0:15]
	v_mfma_f32_32x32x16_bf16 v[16:31], v[64:67], v[76:79], v[16:31]
	v_mfma_f32_32x32x16_bf16 v[0:15], v[68:71], v[220:223], v[0:15]
	v_mfma_f32_32x32x16_bf16 v[16:31], v[68:71], v[224:227], v[16:31]
	ds_read_b64_tr_b16 v[72:73], v231
	ds_read_b64_tr_b16 v[74:75], v231 offset:512
	ds_read_b64_tr_b16 v[76:77], v231 offset:2048
	ds_read_b64_tr_b16 v[78:79], v231 offset:2560
	ds_read_b64_tr_b16 v[220:221], v231 offset:1024
	ds_read_b64_tr_b16 v[222:223], v231 offset:1536
	ds_read_b64_tr_b16 v[224:225], v231 offset:3072
	ds_read_b64_tr_b16 v[226:227], v231 offset:3584
	v_exp_f32_e32 v188, v188
	v_exp_f32_e32 v189, v189
	v_exp_f32_e32 v190, v190
	v_exp_f32_e32 v191, v191
	s_waitcnt vmcnt(4)
	ds_write_b128 v247, v[116:119]
	ds_write_b128 v247, v[120:123] offset:1024
	ds_write_b128 v247, v[124:127] offset:2048
	ds_write_b128 v247, v[128:131] offset:3072
	ds_read_b128 v[116:119], v248
	ds_read_b128 v[120:123], v249
	ds_read_b128 v[124:127], v250
	ds_read_b128 v[128:131], v251
	s_waitcnt vmcnt(0)
	ds_write_b128 v112, v[132:135]
	ds_write_b128 v112, v[136:139] offset:1024
	ds_write_b128 v112, v[140:143] offset:2048
	ds_write_b128 v112, v[144:147] offset:3072
	v_exp_f32_e32 v192, v192
	v_exp_f32_e32 v193, v193
	v_exp_f32_e32 v194, v194
	v_exp_f32_e32 v195, v195
	s_waitcnt lgkmcnt(4)
	v_mfma_f32_32x32x16_bf16 v[32:47], v[116:119], v[48:51], v[32:47]
	v_exp_f32_e32 v196, v196
	v_exp_f32_e32 v197, v197
	v_mfma_f32_32x32x16_bf16 v[32:47], v[120:123], v[52:55], v[32:47]
	v_exp_f32_e32 v198, v198
	v_exp_f32_e32 v199, v199
	v_mfma_f32_32x32x16_bf16 v[32:47], v[124:127], v[56:59], v[32:47]
	v_exp_f32_e32 v200, v200
	v_exp_f32_e32 v201, v201
	v_mfma_f32_32x32x16_bf16 v[32:47], v[128:131], v[60:63], v[32:47]
	v_exp_f32_e32 v202, v202
	v_exp_f32_e32 v203, v203
	s_add_i32 s90, s76, 512
	v_lshlrev_b32_e32 v84, 4, v107
	v_add_u32_e32 v84, s90, v84
	v_add_u32_e32 v85, 0, v84
	v_add_u32_e32 v86, 16, v84
	v_add_u32_e32 v87, 32, v84
	v_add_u32_e32 v88, 48, v84
	v_cmp_gt_u32_e64 s[30:31], s98, v85
	v_cmp_gt_u32_e64 s[36:37], s98, v86
	v_cmp_gt_u32_e64 s[78:79], s98, v87
	v_cmp_gt_u32_e64 s[50:51], s98, v88
	v_cndmask_b32_e64 v188, 0, v188, s[30:31]
	v_add_u32_e32 v85, 128, v84
	v_cmp_gt_u32_e64 s[30:31], s98, v85
	v_cndmask_b32_e64 v189, 0, v189, s[36:37]
	v_add_u32_e32 v86, 144, v84
	v_cmp_gt_u32_e64 s[36:37], s98, v86
	v_cndmask_b32_e64 v190, 0, v190, s[78:79]
	v_add_u32_e32 v87, 160, v84
	v_cmp_gt_u32_e64 s[78:79], s98, v87
	v_cndmask_b32_e64 v191, 0, v191, s[50:51]
	v_add_u32_e32 v88, 176, v84
	v_cmp_gt_u32_e64 s[50:51], s98, v88
	v_cndmask_b32_e64 v192, 0, v192, s[30:31]
	v_add_u32_e32 v85, 256, v84
	v_cmp_gt_u32_e64 s[30:31], s98, v85
	v_cndmask_b32_e64 v193, 0, v193, s[36:37]
	v_add_u32_e32 v86, 272, v84
	v_cmp_gt_u32_e64 s[36:37], s98, v86
	v_cndmask_b32_e64 v194, 0, v194, s[78:79]
	v_add_u32_e32 v87, 288, v84
	v_cmp_gt_u32_e64 s[78:79], s98, v87
	v_cndmask_b32_e64 v195, 0, v195, s[50:51]
	v_add_u32_e32 v88, 304, v84
	v_cmp_gt_u32_e64 s[50:51], s98, v88
	v_cndmask_b32_e64 v196, 0, v196, s[30:31]
	v_add_u32_e32 v85, 384, v84
	v_cmp_gt_u32_e64 s[30:31], s98, v85
	v_cndmask_b32_e64 v197, 0, v197, s[36:37]
	v_add_u32_e32 v86, 400, v84
	v_cmp_gt_u32_e64 s[36:37], s98, v86
	v_cndmask_b32_e64 v198, 0, v198, s[78:79]
	v_add_u32_e32 v87, 416, v84
	v_cmp_gt_u32_e64 s[78:79], s98, v87
	v_cndmask_b32_e64 v199, 0, v199, s[50:51]
	v_add_u32_e32 v88, 432, v84
	v_cmp_gt_u32_e64 s[50:51], s98, v88
	v_nop
	v_cndmask_b32_e64 v200, 0, v200, s[30:31]
	v_cndmask_b32_e64 v201, 0, v201, s[36:37]
	v_cndmask_b32_e64 v202, 0, v202, s[78:79]
	v_cndmask_b32_e64 v203, 0, v203, s[50:51]
	v_cvt_pk_bf16_f32 v64, v188, v189
	v_cvt_pk_bf16_f32 v65, v190, v191
	v_cvt_pk_bf16_f32 v66, v192, v193
	v_cvt_pk_bf16_f32 v67, v194, v195
	v_cvt_pk_bf16_f32 v68, v196, v197
	v_cvt_pk_bf16_f32 v69, v198, v199
	v_cvt_pk_bf16_f32 v70, v200, v201
	v_cvt_pk_bf16_f32 v71, v202, v203
	v_pk_add_f32 v[232:233], v[232:233], v[188:189]
	v_pk_add_f32 v[232:233], v[232:233], v[190:191]
	v_pk_add_f32 v[232:233], v[232:233], v[192:193]
	v_pk_add_f32 v[232:233], v[232:233], v[194:195]
	v_pk_add_f32 v[232:233], v[232:233], v[196:197]
	v_pk_add_f32 v[232:233], v[232:233], v[198:199]
	v_pk_add_f32 v[232:233], v[232:233], v[200:201]
	v_pk_add_f32 v[232:233], v[232:233], v[202:203]
	v_mfma_f32_32x32x16_bf16 v[0:15], v[64:67], v[72:75], v[0:15]
	v_mfma_f32_32x32x16_bf16 v[16:31], v[64:67], v[76:79], v[16:31]
	v_mfma_f32_32x32x16_bf16 v[0:15], v[68:71], v[220:223], v[0:15]
	v_mfma_f32_32x32x16_bf16 v[16:31], v[68:71], v[224:227], v[16:31]
	ds_read_b64_tr_b16 v[72:73], v231
	ds_read_b64_tr_b16 v[74:75], v231 offset:512
	ds_read_b64_tr_b16 v[76:77], v231 offset:2048
	ds_read_b64_tr_b16 v[78:79], v231 offset:2560
	ds_read_b64_tr_b16 v[220:221], v231 offset:1024
	ds_read_b64_tr_b16 v[222:223], v231 offset:1536
	ds_read_b64_tr_b16 v[224:225], v231 offset:3072
	ds_read_b64_tr_b16 v[226:227], v231 offset:3584
	s_waitcnt lgkmcnt(0)
	v_exp_f32_e32 v32, v32
	v_exp_f32_e32 v33, v33
	v_exp_f32_e32 v34, v34
	v_exp_f32_e32 v35, v35
	v_exp_f32_e32 v36, v36
	v_exp_f32_e32 v37, v37
	v_exp_f32_e32 v38, v38
	v_exp_f32_e32 v39, v39
	v_exp_f32_e32 v40, v40
	v_exp_f32_e32 v41, v41
	v_exp_f32_e32 v42, v42
	v_exp_f32_e32 v43, v43
	v_exp_f32_e32 v44, v44
	v_exp_f32_e32 v45, v45
	v_exp_f32_e32 v46, v46
	v_exp_f32_e32 v47, v47
	s_add_i32 s90, s76, 1024
	v_lshlrev_b32_e32 v84, 4, v107
	v_add_u32_e32 v84, s90, v84
	v_add_u32_e32 v85, 0, v84
	v_add_u32_e32 v86, 16, v84
	v_add_u32_e32 v87, 32, v84
	v_add_u32_e32 v88, 48, v84
	v_cmp_gt_u32_e64 s[30:31], s98, v85
	v_cmp_gt_u32_e64 s[36:37], s98, v86
	v_cmp_gt_u32_e64 s[78:79], s98, v87
	v_cmp_gt_u32_e64 s[50:51], s98, v88
	v_cndmask_b32_e64 v32, 0, v32, s[30:31]
	v_add_u32_e32 v85, 128, v84
	v_cmp_gt_u32_e64 s[30:31], s98, v85
	v_cndmask_b32_e64 v33, 0, v33, s[36:37]
	v_add_u32_e32 v86, 144, v84
	v_cmp_gt_u32_e64 s[36:37], s98, v86
	v_cndmask_b32_e64 v34, 0, v34, s[78:79]
	v_add_u32_e32 v87, 160, v84
	v_cmp_gt_u32_e64 s[78:79], s98, v87
	v_cndmask_b32_e64 v35, 0, v35, s[50:51]
	v_add_u32_e32 v88, 176, v84
	v_cmp_gt_u32_e64 s[50:51], s98, v88
	v_cndmask_b32_e64 v36, 0, v36, s[30:31]
	v_add_u32_e32 v85, 256, v84
	v_cmp_gt_u32_e64 s[30:31], s98, v85
	v_cndmask_b32_e64 v37, 0, v37, s[36:37]
	v_add_u32_e32 v86, 272, v84
	v_cmp_gt_u32_e64 s[36:37], s98, v86
	v_cndmask_b32_e64 v38, 0, v38, s[78:79]
	v_add_u32_e32 v87, 288, v84
	v_cmp_gt_u32_e64 s[78:79], s98, v87
	v_cndmask_b32_e64 v39, 0, v39, s[50:51]
	v_add_u32_e32 v88, 304, v84
	v_cmp_gt_u32_e64 s[50:51], s98, v88
	v_cndmask_b32_e64 v40, 0, v40, s[30:31]
	v_add_u32_e32 v85, 384, v84
	v_cmp_gt_u32_e64 s[30:31], s98, v85
	v_cndmask_b32_e64 v41, 0, v41, s[36:37]
	v_add_u32_e32 v86, 400, v84
	v_cmp_gt_u32_e64 s[36:37], s98, v86
	v_cndmask_b32_e64 v42, 0, v42, s[78:79]
	v_add_u32_e32 v87, 416, v84
	v_cmp_gt_u32_e64 s[78:79], s98, v87
	v_cndmask_b32_e64 v43, 0, v43, s[50:51]
	v_add_u32_e32 v88, 432, v84
	v_cmp_gt_u32_e64 s[50:51], s98, v88
	v_nop
	v_cndmask_b32_e64 v44, 0, v44, s[30:31]
	v_cndmask_b32_e64 v45, 0, v45, s[36:37]
	v_cndmask_b32_e64 v46, 0, v46, s[78:79]
	v_cndmask_b32_e64 v47, 0, v47, s[50:51]
	v_cvt_pk_bf16_f32 v64, v32, v33
	v_cvt_pk_bf16_f32 v65, v34, v35
	v_cvt_pk_bf16_f32 v66, v36, v37
	v_cvt_pk_bf16_f32 v67, v38, v39
	v_cvt_pk_bf16_f32 v68, v40, v41
	v_cvt_pk_bf16_f32 v69, v42, v43
	v_cvt_pk_bf16_f32 v70, v44, v45
	v_cvt_pk_bf16_f32 v71, v46, v47
	v_pk_add_f32 v[232:233], v[232:233], v[32:33]
	v_pk_add_f32 v[232:233], v[232:233], v[34:35]
	v_pk_add_f32 v[232:233], v[232:233], v[36:37]
	v_pk_add_f32 v[232:233], v[232:233], v[38:39]
	v_pk_add_f32 v[232:233], v[232:233], v[40:41]
	v_pk_add_f32 v[232:233], v[232:233], v[42:43]
	v_pk_add_f32 v[232:233], v[232:233], v[44:45]
	v_pk_add_f32 v[232:233], v[232:233], v[46:47]
	v_mfma_f32_32x32x16_bf16 v[0:15], v[64:67], v[72:75], v[0:15]
	v_mfma_f32_32x32x16_bf16 v[16:31], v[64:67], v[76:79], v[16:31]
	v_mfma_f32_32x32x16_bf16 v[0:15], v[68:71], v[220:223], v[0:15]
	v_mfma_f32_32x32x16_bf16 v[16:31], v[68:71], v[224:227], v[16:31]
	v_add_f32_e32 v113, v232, v233
	v_or_b32_e32 v114, 1, v107
	v_or_b32_e32 v97, 2, v107
	v_or_b32_e32 v96, 3, v107
	v_or_b32_e32 v95, 8, v107
	v_or_b32_e32 v94, 9, v107
	v_or_b32_e32 v93, 10, v107
	v_or_b32_e32 v92, 11, v107
	v_or_b32_e32 v91, 16, v107
	v_or_b32_e32 v90, 17, v107
	v_or_b32_e32 v89, 18, v107
	v_or_b32_e32 v88, 19, v107
	v_or_b32_e32 v87, 24, v107
	v_or_b32_e32 v86, 25, v107
	v_or_b32_e32 v85, 26, v107
	v_or_b32_e32 v84, 27, v107
	s_nop 11
	s_branch .LBB0_553

.LBB0_1266:
	s_lshr_b32 s82, s60, 8
	s_mul_i32 s82, s82, 13
	s_add_i32 s82, s82, s60
	s_ashr_i32 s4, s60, 6
	s_mul_hi_i32 s9, s4, 0x2aaaaaab
	s_lshl_b32 s5, s82, 8
	s_lshr_b32 s10, s9, 31
	s_and_b32 s8, s5, 0x3e00
	s_lshl_b32 s5, s82, 3
	s_add_i32 s9, s9, s10
	s_and_b32 s5, s5, 8
	s_mul_i32 s10, s9, 6
	s_add_i32 s5, s5, s61
	s_sub_i32 s10, s4, s10
	s_mul_hi_i32 s4, s9, 0x6000000
	s_mul_i32 s9, s9, 0x6000000
	v_mov_b32_e32 v2, v154
	s_add_u32 s52, s44, s9
	s_addc_u32 s53, s45, s4
	v_and_b32_e32 v105, 31, v2
	s_add_i32 s67, s5, s8
	v_lshl_add_u32 v3, v105, 4, s67
	v_mov_b64_e32 v[0:1], s[52:53]
	s_lshl_b32 s54, s10, 6
	v_bfe_u32 v106, v2, 5, 1
	v_mad_u64_u32 v[0:1], s[4:5], v3, s62, v[0:1]
	s_ashr_i32 s55, s54, 31
	v_lshl_add_u64 v[0:1], s[54:55], 1, v[0:1]
	v_lshlrev_b32_e32 v80, 4, v106
	v_lshl_add_u64 v[0:1], v[0:1], 0, v[80:81]
	global_load_dwordx4 v[48:51], v[0:1], off offset:1280
	global_load_dwordx4 v[52:55], v[0:1], off offset:1312
	global_load_dwordx4 v[56:59], v[0:1], off offset:1344
	global_load_dwordx4 v[60:63], v[0:1], off offset:1376
	v_readfirstlane_b32 s4, v2
	s_lshl_b32 s4, s4, 6
	s_and_b32 s4, s4, 0xfffff000
	v_lshlrev_b32_e32 v0, 1, v2
	v_lshlrev_b32_e32 v104, 3, v2
	v_lshlrev_b32_e32 v107, 2, v106
	v_lshrrev_b32_e32 v1, 2, v2
	v_and_b32_e32 v103, 63, v2
	v_and_b32_e32 v0, 32, v0
	v_and_b32_e32 v98, 24, v104
	v_and_or_b32 v1, v1, 3, v107
	s_add_i32 s69, s4, 0
	v_lshlrev_b32_e32 v108, 6, v1
	v_lshlrev_b32_e32 v1, 3, v106
	v_add3_u32 v109, s69, v0, v98
	s_addk_i32 s8, 0xc400
	v_lshrrev_b32_e32 v110, 2, v103
	v_lshlrev_b32_e32 v0, 4, v103
	s_mov_b64 s[4:5], -1
	s_cmp_gt_u32 s8, 0xffffc7ff
	v_lshlrev_b32_e32 v100, 1, v98
	s_mul_i32 s8, s10, 0x1c00
	v_lshlrev_b32_e32 v82, 1, v1
	v_or_b32_e32 v111, 16, v110
	v_add_u32_e32 v112, s69, v0
	s_cbranch_scc0 .LBB0_1270
	s_movk_i32 s100, 0x1800
	s_add_i32 s101, s8, 0x15c00
	s_lshl_b32 s90, s54, 1
	s_add_u32 s82, s52, s90
	s_addc_u32 s83, s53, 0
	s_add_u32 s82, s82, 0x1200
	s_addc_u32 s83, s83, 0
	s_sub_i32 s90, s67, 64
	s_mul_i32 s90, s90, 0x1800
	s_add_u32 s84, s82, s90
	s_addc_u32 s85, s83, 0
	s_sub_i32 s90, s67, 256
	s_mul_i32 s90, s90, 0x1800
	s_add_u32 s86, s82, s90
	s_addc_u32 s87, s83, 0
	s_sub_i32 s90, s67, 1024
	s_mul_i32 s90, s90, 0x1800
	s_add_u32 s88, s82, s90
	s_addc_u32 s89, s83, 0
	v_lshlrev_b32_e32 v153, 1, v98
	v_mad_u32_u24 v80, v105, s100, v82
	v_mad_u32_u24 v100, v110, s100, v153
	v_add_u32_e32 v149, 0x18000, v100
	v_lshlrev_b32_e32 v83, 2, v105
	v_mad_u32_u24 v83, v83, s100, v82
	v_lshlrev_b32_e32 v101, 2, v110
	v_mad_u32_u24 v101, v101, s100, v153
	v_add_u32_e32 v150, 0x60000, v101
	v_lshlrev_b32_e32 v99, 4, v105
	v_mad_u32_u24 v99, v99, s100, v82
	v_lshlrev_b32_e32 v148, 4, v110
	v_mad_u32_u24 v148, v148, s100, v153
	v_add_u32_e32 v151, 0x180000, v148
	v_lshrrev_b32_e32 v249, 3, v103
	v_and_b32_e32 v250, 7, v103
	v_lshlrev_b32_e32 v250, 4, v250
	v_add_u32_e32 v235, 0, v249
	v_mad_u32_u24 v235, v235, s100, v250
	v_add_u32_e32 v236, 8, v249
	v_mad_u32_u24 v236, v236, s100, v250
	v_add_u32_e32 v237, 16, v249
	v_mad_u32_u24 v237, v237, s100, v250
	v_add_u32_e32 v238, 24, v249
	v_mad_u32_u24 v238, v238, s100, v250
	v_add_u32_e32 v239, 0, v249
	v_lshlrev_b32_e32 v239, 2, v239
	v_mad_u32_u24 v239, v239, s100, v250
	v_add_u32_e32 v240, 8, v249
	v_lshlrev_b32_e32 v240, 2, v240
	v_mad_u32_u24 v240, v240, s100, v250
	v_add_u32_e32 v241, 16, v249
	v_lshlrev_b32_e32 v241, 2, v241
	v_mad_u32_u24 v241, v241, s100, v250
	v_add_u32_e32 v242, 24, v249
	v_lshlrev_b32_e32 v242, 2, v242
	v_mad_u32_u24 v242, v242, s100, v250
	v_add_u32_e32 v243, 0, v249
	v_lshlrev_b32_e32 v243, 4, v243
	v_mad_u32_u24 v243, v243, s100, v250
	v_add_u32_e32 v244, 8, v249
	v_lshlrev_b32_e32 v244, 4, v244
	v_mad_u32_u24 v244, v244, s100, v250
	v_add_u32_e32 v245, 16, v249
	v_lshlrev_b32_e32 v245, 4, v245
	v_mad_u32_u24 v245, v245, s100, v250
	v_add_u32_e32 v246, 24, v249
	v_lshlrev_b32_e32 v246, 4, v246
	v_mad_u32_u24 v246, v246, s100, v250
	v_and_b32_e32 v247, 7, v249
	v_lshlrev_b32_e32 v247, 4, v247
	v_xor_b32_e32 v247, v247, v112
	v_and_b32_e32 v153, 7, v105
	v_or_b32_e32 v248, 0, v106
	v_xor_b32_e32 v248, v248, v153
	v_lshlrev_b32_e32 v248, 4, v248
	v_lshl_add_u32 v248, v105, 7, v248
	v_add_u32_e32 v248, s69, v248
	v_or_b32_e32 v249, 2, v106
	v_xor_b32_e32 v249, v249, v153
	v_lshlrev_b32_e32 v249, 4, v249
	v_lshl_add_u32 v249, v105, 7, v249
	v_add_u32_e32 v249, s69, v249
	v_or_b32_e32 v250, 4, v106
	v_xor_b32_e32 v250, v250, v153
	v_lshlrev_b32_e32 v250, 4, v250
	v_lshl_add_u32 v250, v105, 7, v250
	v_add_u32_e32 v250, s69, v250
	v_or_b32_e32 v251, 6, v106
	v_xor_b32_e32 v251, v251, v153
	v_lshlrev_b32_e32 v251, 4, v251
	v_lshl_add_u32 v251, v105, 7, v251
	v_add_u32_e32 v251, s69, v251
	v_lshlrev_b32_e32 v153, 1, v98
	v_mul_u32_u24_e32 v228, 17, v105
	v_sub_u32_e32 v228, v107, v228
	s_mul_i32 s90, s54, 153
	s_lshr_b32 s90, s90, 1
	s_add_i32 s90, s90, 34876
	v_lshl_add_u32 v228, v228, 2, s90
	v_lshlrev_b32_e32 v229, 2, v105
	v_sub_u32_e32 v229, v107, v229
	s_add_i32 s90, s101, 5104
	v_lshl_add_u32 v229, v229, 2, s90
	v_sub_u32_e32 v230, v107, v105
	s_add_i32 s90, s101, 6364
	v_lshl_add_u32 v230, v230, 2, s90
	v_add_u32_e32 v231, v109, v108
	v_mov_b64_e32 v[232:233], 0
	v_mov_b64_e32 v[0:1], 0
	v_mov_b64_e32 v[2:3], 0
	v_mov_b64_e32 v[4:5], 0
	v_mov_b64_e32 v[6:7], 0
	v_mov_b64_e32 v[8:9], 0
	v_mov_b64_e32 v[10:11], 0
	v_mov_b64_e32 v[12:13], 0
	v_mov_b64_e32 v[14:15], 0
	v_mov_b64_e32 v[16:17], 0
	v_mov_b64_e32 v[18:19], 0
	v_mov_b64_e32 v[20:21], 0
	v_mov_b64_e32 v[22:23], 0
	v_mov_b64_e32 v[24:25], 0
	v_mov_b64_e32 v[26:27], 0
	v_mov_b64_e32 v[28:29], 0
	v_mov_b64_e32 v[30:31], 0
	global_load_dwordx4 v[116:119], v235, s[84:85]
	global_load_dwordx4 v[120:123], v236, s[84:85]
	global_load_dwordx4 v[124:127], v237, s[84:85]
	global_load_dwordx4 v[128:131], v238, s[84:85]
	global_load_dwordx4 v[132:135], v100, s[84:85] offset:768
	global_load_dwordx4 v[136:139], v149, s[84:85] offset:768
	global_load_dwordx4 v[140:143], v100, s[84:85] offset:832
	global_load_dwordx4 v[144:147], v149, s[84:85] offset:832
	s_add_u32 s84, s84, 0x30000
	s_addc_u32 s85, s85, 0
	global_load_dwordx4 v[156:159], v235, s[84:85]
	global_load_dwordx4 v[160:163], v236, s[84:85]
	global_load_dwordx4 v[164:167], v237, s[84:85]
	global_load_dwordx4 v[168:171], v238, s[84:85]
	global_load_dwordx4 v[172:175], v100, s[84:85] offset:768
	global_load_dwordx4 v[176:179], v149, s[84:85] offset:768
	global_load_dwordx4 v[180:183], v100, s[84:85] offset:832
	global_load_dwordx4 v[184:187], v149, s[84:85] offset:832
	s_add_u32 s84, s84, 0x30000
	s_addc_u32 s85, s85, 0
	v_mov_b32_e32 v115, v228
	ds_read2_b32 v[32:33], v115 offset0:0 offset1:1
	ds_read2_b32 v[34:35], v115 offset0:2 offset1:3
	ds_read2_b32 v[36:37], v115 offset0:8 offset1:9
	ds_read2_b32 v[38:39], v115 offset0:10 offset1:11
	ds_read2_b32 v[40:41], v115 offset0:17 offset1:18
	ds_read2_b32 v[42:43], v115 offset0:19 offset1:20
	ds_read2_b32 v[44:45], v115 offset0:25 offset1:26
	ds_read2_b32 v[46:47], v115 offset0:27 offset1:28
	s_waitcnt vmcnt(8)
	ds_write_b128 v247, v[116:119]
	ds_write_b128 v247, v[120:123] offset:1024
	ds_write_b128 v247, v[124:127] offset:2048
	ds_write_b128 v247, v[128:131] offset:3072
	ds_read_b128 v[116:119], v248
	ds_read_b128 v[120:123], v249
	ds_read_b128 v[124:127], v250
	ds_read_b128 v[128:131], v251
	ds_write_b128 v112, v[132:135]
	ds_write_b128 v112, v[136:139] offset:1024
	ds_write_b128 v112, v[140:143] offset:2048
	ds_write_b128 v112, v[144:147] offset:3072
	s_waitcnt lgkmcnt(4)
	v_mfma_f32_32x32x16_bf16 v[32:47], v[116:119], v[48:51], v[32:47]
	v_mfma_f32_32x32x16_bf16 v[32:47], v[120:123], v[52:55], v[32:47]
	v_mfma_f32_32x32x16_bf16 v[32:47], v[124:127], v[56:59], v[32:47]
	v_mfma_f32_32x32x16_bf16 v[32:47], v[128:131], v[60:63], v[32:47]
	ds_read2_b32 v[188:189], v115 offset0:34 offset1:35
	ds_read2_b32 v[190:191], v115 offset0:36 offset1:37
	ds_read2_b32 v[192:193], v115 offset0:42 offset1:43
	ds_read2_b32 v[194:195], v115 offset0:44 offset1:45
	ds_read2_b32 v[196:197], v115 offset0:51 offset1:52
	ds_read2_b32 v[198:199], v115 offset0:53 offset1:54
	ds_read2_b32 v[200:201], v115 offset0:59 offset1:60
	ds_read2_b32 v[202:203], v115 offset0:61 offset1:62
	global_load_dwordx4 v[116:119], v235, s[84:85]
	global_load_dwordx4 v[120:123], v236, s[84:85]
	global_load_dwordx4 v[124:127], v237, s[84:85]
	global_load_dwordx4 v[128:131], v238, s[84:85]
	global_load_dwordx4 v[132:135], v100, s[84:85] offset:768
	global_load_dwordx4 v[136:139], v149, s[84:85] offset:768
	global_load_dwordx4 v[140:143], v100, s[84:85] offset:832
	global_load_dwordx4 v[144:147], v149, s[84:85] offset:832
	s_add_u32 s84, s84, 0x30000
	s_addc_u32 s85, s85, 0
	ds_read_b64_tr_b16 v[72:73], v231
	ds_read_b64_tr_b16 v[74:75], v231 offset:512
	ds_read_b64_tr_b16 v[76:77], v231 offset:2048
	ds_read_b64_tr_b16 v[78:79], v231 offset:2560
	ds_read_b64_tr_b16 v[220:221], v231 offset:1024
	ds_read_b64_tr_b16 v[222:223], v231 offset:1536
	ds_read_b64_tr_b16 v[224:225], v231 offset:3072
	ds_read_b64_tr_b16 v[226:227], v231 offset:3584
	v_exp_f32_e32 v32, v32
	v_exp_f32_e32 v33, v33
	v_exp_f32_e32 v34, v34
	v_exp_f32_e32 v35, v35
	s_waitcnt vmcnt(12)
	ds_write_b128 v247, v[156:159]
	ds_write_b128 v247, v[160:163] offset:1024
	ds_write_b128 v247, v[164:167] offset:2048
	ds_write_b128 v247, v[168:171] offset:3072
	ds_read_b128 v[156:159], v248
	ds_read_b128 v[160:163], v249
	ds_read_b128 v[164:167], v250
	ds_read_b128 v[168:171], v251
	s_waitcnt vmcnt(8)
	ds_write_b128 v112, v[172:175]
	ds_write_b128 v112, v[176:179] offset:1024
	ds_write_b128 v112, v[180:183] offset:2048
	ds_write_b128 v112, v[184:187] offset:3072
	v_exp_f32_e32 v36, v36
	v_exp_f32_e32 v37, v37
	v_exp_f32_e32 v38, v38
	v_exp_f32_e32 v39, v39
	s_waitcnt lgkmcnt(4)
	v_mfma_f32_32x32x16_bf16 v[188:203], v[156:159], v[48:51], v[188:203]
	v_exp_f32_e32 v40, v40
	v_exp_f32_e32 v41, v41
	v_mfma_f32_32x32x16_bf16 v[188:203], v[160:163], v[52:55], v[188:203]
	v_exp_f32_e32 v42, v42
	v_exp_f32_e32 v43, v43
	v_mfma_f32_32x32x16_bf16 v[188:203], v[164:167], v[56:59], v[188:203]
	v_exp_f32_e32 v44, v44
	v_exp_f32_e32 v45, v45
	v_mfma_f32_32x32x16_bf16 v[188:203], v[168:171], v[60:63], v[188:203]
	v_exp_f32_e32 v46, v46
	v_exp_f32_e32 v47, v47
	v_cvt_pk_bf16_f32 v64, v32, v33
	v_cvt_pk_bf16_f32 v65, v34, v35
	v_cvt_pk_bf16_f32 v66, v36, v37
	v_cvt_pk_bf16_f32 v67, v38, v39
	v_cvt_pk_bf16_f32 v68, v40, v41
	v_cvt_pk_bf16_f32 v69, v42, v43
	v_cvt_pk_bf16_f32 v70, v44, v45
	v_cvt_pk_bf16_f32 v71, v46, v47
	v_pk_add_f32 v[232:233], v[232:233], v[32:33]
	v_pk_add_f32 v[232:233], v[232:233], v[34:35]
	v_pk_add_f32 v[232:233], v[232:233], v[36:37]
	v_pk_add_f32 v[232:233], v[232:233], v[38:39]
	v_pk_add_f32 v[232:233], v[232:233], v[40:41]
	v_pk_add_f32 v[232:233], v[232:233], v[42:43]
	v_pk_add_f32 v[232:233], v[232:233], v[44:45]
	v_pk_add_f32 v[232:233], v[232:233], v[46:47]
	ds_read2_b32 v[32:33], v115 offset0:68 offset1:69
	ds_read2_b32 v[34:35], v115 offset0:70 offset1:71
	ds_read2_b32 v[36:37], v115 offset0:76 offset1:77
	ds_read2_b32 v[38:39], v115 offset0:78 offset1:79
	ds_read2_b32 v[40:41], v115 offset0:85 offset1:86
	ds_read2_b32 v[42:43], v115 offset0:87 offset1:88
	ds_read2_b32 v[44:45], v115 offset0:93 offset1:94
	ds_read2_b32 v[46:47], v115 offset0:95 offset1:96
	v_mfma_f32_32x32x16_bf16 v[0:15], v[64:67], v[72:75], v[0:15]
	v_mfma_f32_32x32x16_bf16 v[16:31], v[64:67], v[76:79], v[16:31]
	v_mfma_f32_32x32x16_bf16 v[0:15], v[68:71], v[220:223], v[0:15]
	v_mfma_f32_32x32x16_bf16 v[16:31], v[68:71], v[224:227], v[16:31]
	global_load_dwordx4 v[156:159], v235, s[84:85]
	global_load_dwordx4 v[160:163], v236, s[84:85]
	global_load_dwordx4 v[164:167], v237, s[84:85]
	global_load_dwordx4 v[168:171], v238, s[84:85]
	global_load_dwordx4 v[172:175], v100, s[84:85] offset:768
	global_load_dwordx4 v[176:179], v149, s[84:85] offset:768
	global_load_dwordx4 v[180:183], v100, s[84:85] offset:832
	global_load_dwordx4 v[184:187], v149, s[84:85] offset:832
	s_add_u32 s84, s84, 0x30000
	s_addc_u32 s85, s85, 0
	ds_read_b64_tr_b16 v[72:73], v231
	ds_read_b64_tr_b16 v[74:75], v231 offset:512
	ds_read_b64_tr_b16 v[76:77], v231 offset:2048
	ds_read_b64_tr_b16 v[78:79], v231 offset:2560
	ds_read_b64_tr_b16 v[220:221], v231 offset:1024
	ds_read_b64_tr_b16 v[222:223], v231 offset:1536
	ds_read_b64_tr_b16 v[224:225], v231 offset:3072
	ds_read_b64_tr_b16 v[226:227], v231 offset:3584
	v_exp_f32_e32 v188, v188
	v_exp_f32_e32 v189, v189
	v_exp_f32_e32 v190, v190
	v_exp_f32_e32 v191, v191
	s_waitcnt vmcnt(12)
	ds_write_b128 v247, v[116:119]
	ds_write_b128 v247, v[120:123] offset:1024
	ds_write_b128 v247, v[124:127] offset:2048
	ds_write_b128 v247, v[128:131] offset:3072
	ds_read_b128 v[116:119], v248
	ds_read_b128 v[120:123], v249
	ds_read_b128 v[124:127], v250
	ds_read_b128 v[128:131], v251
	s_waitcnt vmcnt(8)
	ds_write_b128 v112, v[132:135]
	ds_write_b128 v112, v[136:139] offset:1024
	ds_write_b128 v112, v[140:143] offset:2048
	ds_write_b128 v112, v[144:147] offset:3072
	v_exp_f32_e32 v192, v192
	v_exp_f32_e32 v193, v193
	v_exp_f32_e32 v194, v194
	v_exp_f32_e32 v195, v195
	s_waitcnt lgkmcnt(4)
	v_mfma_f32_32x32x16_bf16 v[32:47], v[116:119], v[48:51], v[32:47]
	v_exp_f32_e32 v196, v196
	v_exp_f32_e32 v197, v197
	v_mfma_f32_32x32x16_bf16 v[32:47], v[120:123], v[52:55], v[32:47]
	v_exp_f32_e32 v198, v198
	v_exp_f32_e32 v199, v199
	v_mfma_f32_32x32x16_bf16 v[32:47], v[124:127], v[56:59], v[32:47]
	v_exp_f32_e32 v200, v200
	v_exp_f32_e32 v201, v201
	v_mfma_f32_32x32x16_bf16 v[32:47], v[128:131], v[60:63], v[32:47]
	v_exp_f32_e32 v202, v202
	v_exp_f32_e32 v203, v203
	v_cvt_pk_bf16_f32 v64, v188, v189
	v_cvt_pk_bf16_f32 v65, v190, v191
	v_cvt_pk_bf16_f32 v66, v192, v193
	v_cvt_pk_bf16_f32 v67, v194, v195
	v_cvt_pk_bf16_f32 v68, v196, v197
	v_cvt_pk_bf16_f32 v69, v198, v199
	v_cvt_pk_bf16_f32 v70, v200, v201
	v_cvt_pk_bf16_f32 v71, v202, v203
	v_pk_add_f32 v[232:233], v[232:233], v[188:189]
	v_pk_add_f32 v[232:233], v[232:233], v[190:191]
	v_pk_add_f32 v[232:233], v[232:233], v[192:193]
	v_pk_add_f32 v[232:233], v[232:233], v[194:195]
	v_pk_add_f32 v[232:233], v[232:233], v[196:197]
	v_pk_add_f32 v[232:233], v[232:233], v[198:199]
	v_pk_add_f32 v[232:233], v[232:233], v[200:201]
	v_pk_add_f32 v[232:233], v[232:233], v[202:203]
	ds_read2_b32 v[188:189], v115 offset0:102 offset1:103
	ds_read2_b32 v[190:191], v115 offset0:104 offset1:105
	ds_read2_b32 v[192:193], v115 offset0:110 offset1:111
	ds_read2_b32 v[194:195], v115 offset0:112 offset1:113
	ds_read2_b32 v[196:197], v115 offset0:119 offset1:120
	ds_read2_b32 v[198:199], v115 offset0:121 offset1:122
	ds_read2_b32 v[200:201], v115 offset0:127 offset1:128
	ds_read2_b32 v[202:203], v115 offset0:129 offset1:130
	v_mfma_f32_32x32x16_bf16 v[0:15], v[64:67], v[72:75], v[0:15]
	v_mfma_f32_32x32x16_bf16 v[16:31], v[64:67], v[76:79], v[16:31]
	v_mfma_f32_32x32x16_bf16 v[0:15], v[68:71], v[220:223], v[0:15]
	v_mfma_f32_32x32x16_bf16 v[16:31], v[68:71], v[224:227], v[16:31]
	global_load_dwordx4 v[116:119], v235, s[84:85]
	global_load_dwordx4 v[120:123], v236, s[84:85]
	global_load_dwordx4 v[124:127], v237, s[84:85]
	global_load_dwordx4 v[128:131], v238, s[84:85]
	global_load_dwordx4 v[132:135], v100, s[84:85] offset:768
	global_load_dwordx4 v[136:139], v149, s[84:85] offset:768
	global_load_dwordx4 v[140:143], v100, s[84:85] offset:832
	global_load_dwordx4 v[144:147], v149, s[84:85] offset:832
	s_add_u32 s84, s84, 0x30000
	s_addc_u32 s85, s85, 0
	ds_read_b64_tr_b16 v[72:73], v231
	ds_read_b64_tr_b16 v[74:75], v231 offset:512
	ds_read_b64_tr_b16 v[76:77], v231 offset:2048
	ds_read_b64_tr_b16 v[78:79], v231 offset:2560
	ds_read_b64_tr_b16 v[220:221], v231 offset:1024
	ds_read_b64_tr_b16 v[222:223], v231 offset:1536
	ds_read_b64_tr_b16 v[224:225], v231 offset:3072
	ds_read_b64_tr_b16 v[226:227], v231 offset:3584
	v_exp_f32_e32 v32, v32
	v_exp_f32_e32 v33, v33
	v_exp_f32_e32 v34, v34
	v_exp_f32_e32 v35, v35
	s_waitcnt vmcnt(12)
	ds_write_b128 v247, v[156:159]
	ds_write_b128 v247, v[160:163] offset:1024
	ds_write_b128 v247, v[164:167] offset:2048
	ds_write_b128 v247, v[168:171] offset:3072
	ds_read_b128 v[156:159], v248
	ds_read_b128 v[160:163], v249
	ds_read_b128 v[164:167], v250
	ds_read_b128 v[168:171], v251
	s_waitcnt vmcnt(8)
	ds_write_b128 v112, v[172:175]
	ds_write_b128 v112, v[176:179] offset:1024
	ds_write_b128 v112, v[180:183] offset:2048
	ds_write_b128 v112, v[184:187] offset:3072
	v_exp_f32_e32 v36, v36
	v_exp_f32_e32 v37, v37
	v_exp_f32_e32 v38, v38
	v_exp_f32_e32 v39, v39
	s_waitcnt lgkmcnt(4)
	v_mfma_f32_32x32x16_bf16 v[188:203], v[156:159], v[48:51], v[188:203]
	v_exp_f32_e32 v40, v40
	v_exp_f32_e32 v41, v41
	v_mfma_f32_32x32x16_bf16 v[188:203], v[160:163], v[52:55], v[188:203]
	v_exp_f32_e32 v42, v42
	v_exp_f32_e32 v43, v43
	v_mfma_f32_32x32x16_bf16 v[188:203], v[164:167], v[56:59], v[188:203]
	v_exp_f32_e32 v44, v44
	v_exp_f32_e32 v45, v45
	v_mfma_f32_32x32x16_bf16 v[188:203], v[168:171], v[60:63], v[188:203]
	v_exp_f32_e32 v46, v46
	v_exp_f32_e32 v47, v47
	v_cvt_pk_bf16_f32 v64, v32, v33
	v_cvt_pk_bf16_f32 v65, v34, v35
	v_cvt_pk_bf16_f32 v66, v36, v37
	v_cvt_pk_bf16_f32 v67, v38, v39
	v_cvt_pk_bf16_f32 v68, v40, v41
	v_cvt_pk_bf16_f32 v69, v42, v43
	v_cvt_pk_bf16_f32 v70, v44, v45
	v_cvt_pk_bf16_f32 v71, v46, v47
	v_pk_add_f32 v[232:233], v[232:233], v[32:33]
	v_pk_add_f32 v[232:233], v[232:233], v[34:35]
	v_pk_add_f32 v[232:233], v[232:233], v[36:37]
	v_pk_add_f32 v[232:233], v[232:233], v[38:39]
	v_pk_add_f32 v[232:233], v[232:233], v[40:41]
	v_pk_add_f32 v[232:233], v[232:233], v[42:43]
	v_pk_add_f32 v[232:233], v[232:233], v[44:45]
	v_pk_add_f32 v[232:233], v[232:233], v[46:47]
	ds_read2_b32 v[32:33], v115 offset0:136 offset1:137
	ds_read2_b32 v[34:35], v115 offset0:138 offset1:139
	ds_read2_b32 v[36:37], v115 offset0:144 offset1:145
	ds_read2_b32 v[38:39], v115 offset0:146 offset1:147
	ds_read2_b32 v[40:41], v115 offset0:153 offset1:154
	ds_read2_b32 v[42:43], v115 offset0:155 offset1:156
	ds_read2_b32 v[44:45], v115 offset0:161 offset1:162
	ds_read2_b32 v[46:47], v115 offset0:163 offset1:164
	v_mfma_f32_32x32x16_bf16 v[0:15], v[64:67], v[72:75], v[0:15]
	v_mfma_f32_32x32x16_bf16 v[16:31], v[64:67], v[76:79], v[16:31]
	v_mfma_f32_32x32x16_bf16 v[0:15], v[68:71], v[220:223], v[0:15]
	v_mfma_f32_32x32x16_bf16 v[16:31], v[68:71], v[224:227], v[16:31]
	global_load_dwordx4 v[156:159], v235, s[84:85]
	global_load_dwordx4 v[160:163], v236, s[84:85]
	global_load_dwordx4 v[164:167], v237, s[84:85]
	global_load_dwordx4 v[168:171], v238, s[84:85]
	global_load_dwordx4 v[172:175], v100, s[84:85] offset:768
	global_load_dwordx4 v[176:179], v149, s[84:85] offset:768
	global_load_dwordx4 v[180:183], v100, s[84:85] offset:832
	global_load_dwordx4 v[184:187], v149, s[84:85] offset:832
	s_add_u32 s84, s84, 0x30000
	s_addc_u32 s85, s85, 0
	ds_read_b64_tr_b16 v[72:73], v231
	ds_read_b64_tr_b16 v[74:75], v231 offset:512
	ds_read_b64_tr_b16 v[76:77], v231 offset:2048
	ds_read_b64_tr_b16 v[78:79], v231 offset:2560
	ds_read_b64_tr_b16 v[220:221], v231 offset:1024
	ds_read_b64_tr_b16 v[222:223], v231 offset:1536
	ds_read_b64_tr_b16 v[224:225], v231 offset:3072
	ds_read_b64_tr_b16 v[226:227], v231 offset:3584
	v_exp_f32_e32 v188, v188
	v_exp_f32_e32 v189, v189
	v_exp_f32_e32 v190, v190
	v_exp_f32_e32 v191, v191
	s_waitcnt vmcnt(12)
	ds_write_b128 v247, v[116:119]
	ds_write_b128 v247, v[120:123] offset:1024
	ds_write_b128 v247, v[124:127] offset:2048
	ds_write_b128 v247, v[128:131] offset:3072
	ds_read_b128 v[116:119], v248
	ds_read_b128 v[120:123], v249
	ds_read_b128 v[124:127], v250
	ds_read_b128 v[128:131], v251
	s_waitcnt vmcnt(8)
	ds_write_b128 v112, v[132:135]
	ds_write_b128 v112, v[136:139] offset:1024
	ds_write_b128 v112, v[140:143] offset:2048
	ds_write_b128 v112, v[144:147] offset:3072
	v_exp_f32_e32 v192, v192
	v_exp_f32_e32 v193, v193
	v_exp_f32_e32 v194, v194
	v_exp_f32_e32 v195, v195
	s_waitcnt lgkmcnt(4)
	v_mfma_f32_32x32x16_bf16 v[32:47], v[116:119], v[48:51], v[32:47]
	v_exp_f32_e32 v196, v196
	v_exp_f32_e32 v197, v197
	v_mfma_f32_32x32x16_bf16 v[32:47], v[120:123], v[52:55], v[32:47]
	v_exp_f32_e32 v198, v198
	v_exp_f32_e32 v199, v199
	v_mfma_f32_32x32x16_bf16 v[32:47], v[124:127], v[56:59], v[32:47]
	v_exp_f32_e32 v200, v200
	v_exp_f32_e32 v201, v201
	v_mfma_f32_32x32x16_bf16 v[32:47], v[128:131], v[60:63], v[32:47]
	v_exp_f32_e32 v202, v202
	v_exp_f32_e32 v203, v203
	v_cvt_pk_bf16_f32 v64, v188, v189
	v_cvt_pk_bf16_f32 v65, v190, v191
	v_cvt_pk_bf16_f32 v66, v192, v193
	v_cvt_pk_bf16_f32 v67, v194, v195
	v_cvt_pk_bf16_f32 v68, v196, v197
	v_cvt_pk_bf16_f32 v69, v198, v199
	v_cvt_pk_bf16_f32 v70, v200, v201
	v_cvt_pk_bf16_f32 v71, v202, v203
	v_pk_add_f32 v[232:233], v[232:233], v[188:189]
	v_pk_add_f32 v[232:233], v[232:233], v[190:191]
	v_pk_add_f32 v[232:233], v[232:233], v[192:193]
	v_pk_add_f32 v[232:233], v[232:233], v[194:195]
	v_pk_add_f32 v[232:233], v[232:233], v[196:197]
	v_pk_add_f32 v[232:233], v[232:233], v[198:199]
	v_pk_add_f32 v[232:233], v[232:233], v[200:201]
	v_pk_add_f32 v[232:233], v[232:233], v[202:203]
	ds_read2_b32 v[188:189], v115 offset0:170 offset1:171
	ds_read2_b32 v[190:191], v115 offset0:172 offset1:173
	ds_read2_b32 v[192:193], v115 offset0:178 offset1:179
	ds_read2_b32 v[194:195], v115 offset0:180 offset1:181
	ds_read2_b32 v[196:197], v115 offset0:187 offset1:188
	ds_read2_b32 v[198:199], v115 offset0:189 offset1:190
	ds_read2_b32 v[200:201], v115 offset0:195 offset1:196
	ds_read2_b32 v[202:203], v115 offset0:197 offset1:198
	v_mfma_f32_32x32x16_bf16 v[0:15], v[64:67], v[72:75], v[0:15]
	v_mfma_f32_32x32x16_bf16 v[16:31], v[64:67], v[76:79], v[16:31]
	v_mfma_f32_32x32x16_bf16 v[0:15], v[68:71], v[220:223], v[0:15]
	v_mfma_f32_32x32x16_bf16 v[16:31], v[68:71], v[224:227], v[16:31]
	global_load_dwordx4 v[116:119], v235, s[84:85]
	global_load_dwordx4 v[120:123], v236, s[84:85]
	global_load_dwordx4 v[124:127], v237, s[84:85]
	global_load_dwordx4 v[128:131], v238, s[84:85]
	global_load_dwordx4 v[132:135], v100, s[84:85] offset:768
	global_load_dwordx4 v[136:139], v149, s[84:85] offset:768
	global_load_dwordx4 v[140:143], v100, s[84:85] offset:832
	global_load_dwordx4 v[144:147], v149, s[84:85] offset:832
	s_add_u32 s84, s84, 0x30000
	s_addc_u32 s85, s85, 0
	ds_read_b64_tr_b16 v[72:73], v231
	ds_read_b64_tr_b16 v[74:75], v231 offset:512
	ds_read_b64_tr_b16 v[76:77], v231 offset:2048
	ds_read_b64_tr_b16 v[78:79], v231 offset:2560
	ds_read_b64_tr_b16 v[220:221], v231 offset:1024
	ds_read_b64_tr_b16 v[222:223], v231 offset:1536
	ds_read_b64_tr_b16 v[224:225], v231 offset:3072
	ds_read_b64_tr_b16 v[226:227], v231 offset:3584
	v_exp_f32_e32 v32, v32
	v_exp_f32_e32 v33, v33
	v_exp_f32_e32 v34, v34
	v_exp_f32_e32 v35, v35
	s_waitcnt vmcnt(12)
	ds_write_b128 v247, v[156:159]
	ds_write_b128 v247, v[160:163] offset:1024
	ds_write_b128 v247, v[164:167] offset:2048
	ds_write_b128 v247, v[168:171] offset:3072
	ds_read_b128 v[156:159], v248
	ds_read_b128 v[160:163], v249
	ds_read_b128 v[164:167], v250
	ds_read_b128 v[168:171], v251
	s_waitcnt vmcnt(8)
	ds_write_b128 v112, v[172:175]
	ds_write_b128 v112, v[176:179] offset:1024
	ds_write_b128 v112, v[180:183] offset:2048
	ds_write_b128 v112, v[184:187] offset:3072
	v_exp_f32_e32 v36, v36
	v_exp_f32_e32 v37, v37
	v_exp_f32_e32 v38, v38
	v_exp_f32_e32 v39, v39
	s_waitcnt lgkmcnt(4)
	v_mfma_f32_32x32x16_bf16 v[188:203], v[156:159], v[48:51], v[188:203]
	v_exp_f32_e32 v40, v40
	v_exp_f32_e32 v41, v41
	v_mfma_f32_32x32x16_bf16 v[188:203], v[160:163], v[52:55], v[188:203]
	v_exp_f32_e32 v42, v42
	v_exp_f32_e32 v43, v43
	v_mfma_f32_32x32x16_bf16 v[188:203], v[164:167], v[56:59], v[188:203]
	v_exp_f32_e32 v44, v44
	v_exp_f32_e32 v45, v45
	v_mfma_f32_32x32x16_bf16 v[188:203], v[168:171], v[60:63], v[188:203]
	v_exp_f32_e32 v46, v46
	v_exp_f32_e32 v47, v47
	v_cvt_pk_bf16_f32 v64, v32, v33
	v_cvt_pk_bf16_f32 v65, v34, v35
	v_cvt_pk_bf16_f32 v66, v36, v37
	v_cvt_pk_bf16_f32 v67, v38, v39
	v_cvt_pk_bf16_f32 v68, v40, v41
	v_cvt_pk_bf16_f32 v69, v42, v43
	v_cvt_pk_bf16_f32 v70, v44, v45
	v_cvt_pk_bf16_f32 v71, v46, v47
	v_pk_add_f32 v[232:233], v[232:233], v[32:33]
	v_pk_add_f32 v[232:233], v[232:233], v[34:35]
	v_pk_add_f32 v[232:233], v[232:233], v[36:37]
	v_pk_add_f32 v[232:233], v[232:233], v[38:39]
	v_pk_add_f32 v[232:233], v[232:233], v[40:41]
	v_pk_add_f32 v[232:233], v[232:233], v[42:43]
	v_pk_add_f32 v[232:233], v[232:233], v[44:45]
	v_pk_add_f32 v[232:233], v[232:233], v[46:47]
	ds_read2_b32 v[32:33], v115 offset0:204 offset1:205
	ds_read2_b32 v[34:35], v115 offset0:206 offset1:207
	ds_read2_b32 v[36:37], v115 offset0:212 offset1:213
	ds_read2_b32 v[38:39], v115 offset0:214 offset1:215
	ds_read2_b32 v[40:41], v115 offset0:221 offset1:222
	ds_read2_b32 v[42:43], v115 offset0:223 offset1:224
	ds_read2_b32 v[44:45], v115 offset0:229 offset1:230
	ds_read2_b32 v[46:47], v115 offset0:231 offset1:232
	v_mfma_f32_32x32x16_bf16 v[0:15], v[64:67], v[72:75], v[0:15]
	v_mfma_f32_32x32x16_bf16 v[16:31], v[64:67], v[76:79], v[16:31]
	v_mfma_f32_32x32x16_bf16 v[0:15], v[68:71], v[220:223], v[0:15]
	v_mfma_f32_32x32x16_bf16 v[16:31], v[68:71], v[224:227], v[16:31]
	global_load_dwordx4 v[156:159], v235, s[84:85]
	global_load_dwordx4 v[160:163], v236, s[84:85]
	global_load_dwordx4 v[164:167], v237, s[84:85]
	global_load_dwordx4 v[168:171], v238, s[84:85]
	global_load_dwordx4 v[172:175], v100, s[84:85] offset:768
	global_load_dwordx4 v[176:179], v149, s[84:85] offset:768
	global_load_dwordx4 v[180:183], v100, s[84:85] offset:832
	global_load_dwordx4 v[184:187], v149, s[84:85] offset:832
	s_add_u32 s84, s84, 0x30000
	s_addc_u32 s85, s85, 0
	ds_read_b64_tr_b16 v[72:73], v231
	ds_read_b64_tr_b16 v[74:75], v231 offset:512
	ds_read_b64_tr_b16 v[76:77], v231 offset:2048
	ds_read_b64_tr_b16 v[78:79], v231 offset:2560
	ds_read_b64_tr_b16 v[220:221], v231 offset:1024
	ds_read_b64_tr_b16 v[222:223], v231 offset:1536
	ds_read_b64_tr_b16 v[224:225], v231 offset:3072
	ds_read_b64_tr_b16 v[226:227], v231 offset:3584
	v_exp_f32_e32 v188, v188
	v_exp_f32_e32 v189, v189
	v_exp_f32_e32 v190, v190
	v_exp_f32_e32 v191, v191
	s_waitcnt vmcnt(12)
	ds_write_b128 v247, v[116:119]
	ds_write_b128 v247, v[120:123] offset:1024
	ds_write_b128 v247, v[124:127] offset:2048
	ds_write_b128 v247, v[128:131] offset:3072
	ds_read_b128 v[116:119], v248
	ds_read_b128 v[120:123], v249
	ds_read_b128 v[124:127], v250
	ds_read_b128 v[128:131], v251
	s_waitcnt vmcnt(8)
	ds_write_b128 v112, v[132:135]
	ds_write_b128 v112, v[136:139] offset:1024
	ds_write_b128 v112, v[140:143] offset:2048
	ds_write_b128 v112, v[144:147] offset:3072
	v_exp_f32_e32 v192, v192
	v_exp_f32_e32 v193, v193
	v_exp_f32_e32 v194, v194
	v_exp_f32_e32 v195, v195
	s_waitcnt lgkmcnt(4)
	v_mfma_f32_32x32x16_bf16 v[32:47], v[116:119], v[48:51], v[32:47]
	v_exp_f32_e32 v196, v196
	v_exp_f32_e32 v197, v197
	v_mfma_f32_32x32x16_bf16 v[32:47], v[120:123], v[52:55], v[32:47]
	v_exp_f32_e32 v198, v198
	v_exp_f32_e32 v199, v199
	v_mfma_f32_32x32x16_bf16 v[32:47], v[124:127], v[56:59], v[32:47]
	v_exp_f32_e32 v200, v200
	v_exp_f32_e32 v201, v201
	v_mfma_f32_32x32x16_bf16 v[32:47], v[128:131], v[60:63], v[32:47]
	v_exp_f32_e32 v202, v202
	v_exp_f32_e32 v203, v203
	v_cvt_pk_bf16_f32 v64, v188, v189
	v_cvt_pk_bf16_f32 v65, v190, v191
	v_cvt_pk_bf16_f32 v66, v192, v193
	v_cvt_pk_bf16_f32 v67, v194, v195
	v_cvt_pk_bf16_f32 v68, v196, v197
	v_cvt_pk_bf16_f32 v69, v198, v199
	v_cvt_pk_bf16_f32 v70, v200, v201
	v_cvt_pk_bf16_f32 v71, v202, v203
	v_pk_add_f32 v[232:233], v[232:233], v[188:189]
	v_pk_add_f32 v[232:233], v[232:233], v[190:191]
	v_pk_add_f32 v[232:233], v[232:233], v[192:193]
	v_pk_add_f32 v[232:233], v[232:233], v[194:195]
	v_pk_add_f32 v[232:233], v[232:233], v[196:197]
	v_pk_add_f32 v[232:233], v[232:233], v[198:199]
	v_pk_add_f32 v[232:233], v[232:233], v[200:201]
	v_pk_add_f32 v[232:233], v[232:233], v[202:203]
	v_add_u32_e32 v115, 952, v115
	ds_read2_b32 v[188:189], v115 offset0:0 offset1:1
	ds_read2_b32 v[190:191], v115 offset0:2 offset1:3
	ds_read2_b32 v[192:193], v115 offset0:8 offset1:9
	ds_read2_b32 v[194:195], v115 offset0:10 offset1:11
	ds_read2_b32 v[196:197], v115 offset0:17 offset1:18
	ds_read2_b32 v[198:199], v115 offset0:19 offset1:20
	ds_read2_b32 v[200:201], v115 offset0:25 offset1:26
	ds_read2_b32 v[202:203], v115 offset0:27 offset1:28
	v_mfma_f32_32x32x16_bf16 v[0:15], v[64:67], v[72:75], v[0:15]
	v_mfma_f32_32x32x16_bf16 v[16:31], v[64:67], v[76:79], v[16:31]
	v_mfma_f32_32x32x16_bf16 v[0:15], v[68:71], v[220:223], v[0:15]
	v_mfma_f32_32x32x16_bf16 v[16:31], v[68:71], v[224:227], v[16:31]
	global_load_dwordx4 v[116:119], v235, s[84:85]
	global_load_dwordx4 v[120:123], v236, s[84:85]
	global_load_dwordx4 v[124:127], v237, s[84:85]
	global_load_dwordx4 v[128:131], v238, s[84:85]
	global_load_dwordx4 v[132:135], v100, s[84:85] offset:768
	global_load_dwordx4 v[136:139], v149, s[84:85] offset:768
	global_load_dwordx4 v[140:143], v100, s[84:85] offset:832
	global_load_dwordx4 v[144:147], v149, s[84:85] offset:832
	s_add_u32 s84, s84, 0x30000
	s_addc_u32 s85, s85, 0
	ds_read_b64_tr_b16 v[72:73], v231
	ds_read_b64_tr_b16 v[74:75], v231 offset:512
	ds_read_b64_tr_b16 v[76:77], v231 offset:2048
	ds_read_b64_tr_b16 v[78:79], v231 offset:2560
	ds_read_b64_tr_b16 v[220:221], v231 offset:1024
	ds_read_b64_tr_b16 v[222:223], v231 offset:1536
	ds_read_b64_tr_b16 v[224:225], v231 offset:3072
	ds_read_b64_tr_b16 v[226:227], v231 offset:3584
	v_exp_f32_e32 v32, v32
	v_exp_f32_e32 v33, v33
	v_exp_f32_e32 v34, v34
	v_exp_f32_e32 v35, v35
	s_waitcnt vmcnt(12)
	ds_write_b128 v247, v[156:159]
	ds_write_b128 v247, v[160:163] offset:1024
	ds_write_b128 v247, v[164:167] offset:2048
	ds_write_b128 v247, v[168:171] offset:3072
	ds_read_b128 v[156:159], v248
	ds_read_b128 v[160:163], v249
	ds_read_b128 v[164:167], v250
	ds_read_b128 v[168:171], v251
	s_waitcnt vmcnt(8)
	ds_write_b128 v112, v[172:175]
	ds_write_b128 v112, v[176:179] offset:1024
	ds_write_b128 v112, v[180:183] offset:2048
	ds_write_b128 v112, v[184:187] offset:3072
	v_exp_f32_e32 v36, v36
	v_exp_f32_e32 v37, v37
	v_exp_f32_e32 v38, v38
	v_exp_f32_e32 v39, v39
	s_waitcnt lgkmcnt(4)
	v_mfma_f32_32x32x16_bf16 v[188:203], v[156:159], v[48:51], v[188:203]
	v_exp_f32_e32 v40, v40
	v_exp_f32_e32 v41, v41
	v_mfma_f32_32x32x16_bf16 v[188:203], v[160:163], v[52:55], v[188:203]
	v_exp_f32_e32 v42, v42
	v_exp_f32_e32 v43, v43
	v_mfma_f32_32x32x16_bf16 v[188:203], v[164:167], v[56:59], v[188:203]
	v_exp_f32_e32 v44, v44
	v_exp_f32_e32 v45, v45
	v_mfma_f32_32x32x16_bf16 v[188:203], v[168:171], v[60:63], v[188:203]
	v_exp_f32_e32 v46, v46
	v_exp_f32_e32 v47, v47
	v_cvt_pk_bf16_f32 v64, v32, v33
	v_cvt_pk_bf16_f32 v65, v34, v35
	v_cvt_pk_bf16_f32 v66, v36, v37
	v_cvt_pk_bf16_f32 v67, v38, v39
	v_cvt_pk_bf16_f32 v68, v40, v41
	v_cvt_pk_bf16_f32 v69, v42, v43
	v_cvt_pk_bf16_f32 v70, v44, v45
	v_cvt_pk_bf16_f32 v71, v46, v47
	v_pk_add_f32 v[232:233], v[232:233], v[32:33]
	v_pk_add_f32 v[232:233], v[232:233], v[34:35]
	v_pk_add_f32 v[232:233], v[232:233], v[36:37]
	v_pk_add_f32 v[232:233], v[232:233], v[38:39]
	v_pk_add_f32 v[232:233], v[232:233], v[40:41]
	v_pk_add_f32 v[232:233], v[232:233], v[42:43]
	v_pk_add_f32 v[232:233], v[232:233], v[44:45]
	v_pk_add_f32 v[232:233], v[232:233], v[46:47]
	ds_read2_b32 v[32:33], v115 offset0:34 offset1:35
	ds_read2_b32 v[34:35], v115 offset0:36 offset1:37
	ds_read2_b32 v[36:37], v115 offset0:42 offset1:43
	ds_read2_b32 v[38:39], v115 offset0:44 offset1:45
	ds_read2_b32 v[40:41], v115 offset0:51 offset1:52
	ds_read2_b32 v[42:43], v115 offset0:53 offset1:54
	ds_read2_b32 v[44:45], v115 offset0:59 offset1:60
	ds_read2_b32 v[46:47], v115 offset0:61 offset1:62
	v_mfma_f32_32x32x16_bf16 v[0:15], v[64:67], v[72:75], v[0:15]
	v_mfma_f32_32x32x16_bf16 v[16:31], v[64:67], v[76:79], v[16:31]
	v_mfma_f32_32x32x16_bf16 v[0:15], v[68:71], v[220:223], v[0:15]
	v_mfma_f32_32x32x16_bf16 v[16:31], v[68:71], v[224:227], v[16:31]
	global_load_dwordx4 v[156:159], v235, s[84:85]
	global_load_dwordx4 v[160:163], v236, s[84:85]
	global_load_dwordx4 v[164:167], v237, s[84:85]
	global_load_dwordx4 v[168:171], v238, s[84:85]
	global_load_dwordx4 v[172:175], v100, s[84:85] offset:768
	global_load_dwordx4 v[176:179], v149, s[84:85] offset:768
	global_load_dwordx4 v[180:183], v100, s[84:85] offset:832
	global_load_dwordx4 v[184:187], v149, s[84:85] offset:832
	s_add_u32 s84, s84, 0x30000
	s_addc_u32 s85, s85, 0
	ds_read_b64_tr_b16 v[72:73], v231
	ds_read_b64_tr_b16 v[74:75], v231 offset:512
	ds_read_b64_tr_b16 v[76:77], v231 offset:2048
	ds_read_b64_tr_b16 v[78:79], v231 offset:2560
	ds_read_b64_tr_b16 v[220:221], v231 offset:1024
	ds_read_b64_tr_b16 v[222:223], v231 offset:1536
	ds_read_b64_tr_b16 v[224:225], v231 offset:3072
	ds_read_b64_tr_b16 v[226:227], v231 offset:3584
	v_exp_f32_e32 v188, v188
	v_exp_f32_e32 v189, v189
	v_exp_f32_e32 v190, v190
	v_exp_f32_e32 v191, v191
	s_waitcnt vmcnt(12)
	ds_write_b128 v247, v[116:119]
	ds_write_b128 v247, v[120:123] offset:1024
	ds_write_b128 v247, v[124:127] offset:2048
	ds_write_b128 v247, v[128:131] offset:3072
	ds_read_b128 v[116:119], v248
	ds_read_b128 v[120:123], v249
	ds_read_b128 v[124:127], v250
	ds_read_b128 v[128:131], v251
	s_waitcnt vmcnt(8)
	ds_write_b128 v112, v[132:135]
	ds_write_b128 v112, v[136:139] offset:1024
	ds_write_b128 v112, v[140:143] offset:2048
	ds_write_b128 v112, v[144:147] offset:3072
	v_exp_f32_e32 v192, v192
	v_exp_f32_e32 v193, v193
	v_exp_f32_e32 v194, v194
	v_exp_f32_e32 v195, v195
	s_waitcnt lgkmcnt(4)
	v_mfma_f32_32x32x16_bf16 v[32:47], v[116:119], v[48:51], v[32:47]
	v_exp_f32_e32 v196, v196
	v_exp_f32_e32 v197, v197
	v_mfma_f32_32x32x16_bf16 v[32:47], v[120:123], v[52:55], v[32:47]
	v_exp_f32_e32 v198, v198
	v_exp_f32_e32 v199, v199
	v_mfma_f32_32x32x16_bf16 v[32:47], v[124:127], v[56:59], v[32:47]
	v_exp_f32_e32 v200, v200
	v_exp_f32_e32 v201, v201
	v_mfma_f32_32x32x16_bf16 v[32:47], v[128:131], v[60:63], v[32:47]
	v_exp_f32_e32 v202, v202
	v_exp_f32_e32 v203, v203
	v_cvt_pk_bf16_f32 v64, v188, v189
	v_cvt_pk_bf16_f32 v65, v190, v191
	v_cvt_pk_bf16_f32 v66, v192, v193
	v_cvt_pk_bf16_f32 v67, v194, v195
	v_cvt_pk_bf16_f32 v68, v196, v197
	v_cvt_pk_bf16_f32 v69, v198, v199
	v_cvt_pk_bf16_f32 v70, v200, v201
	v_cvt_pk_bf16_f32 v71, v202, v203
	v_pk_add_f32 v[232:233], v[232:233], v[188:189]
	v_pk_add_f32 v[232:233], v[232:233], v[190:191]
	v_pk_add_f32 v[232:233], v[232:233], v[192:193]
	v_pk_add_f32 v[232:233], v[232:233], v[194:195]
	v_pk_add_f32 v[232:233], v[232:233], v[196:197]
	v_pk_add_f32 v[232:233], v[232:233], v[198:199]
	v_pk_add_f32 v[232:233], v[232:233], v[200:201]
	v_pk_add_f32 v[232:233], v[232:233], v[202:203]
	ds_read2_b32 v[188:189], v115 offset0:68 offset1:69
	ds_read2_b32 v[190:191], v115 offset0:70 offset1:71
	ds_read2_b32 v[192:193], v115 offset0:76 offset1:77
	ds_read2_b32 v[194:195], v115 offset0:78 offset1:79
	ds_read2_b32 v[196:197], v115 offset0:85 offset1:86
	ds_read2_b32 v[198:199], v115 offset0:87 offset1:88
	ds_read2_b32 v[200:201], v115 offset0:93 offset1:94
	ds_read2_b32 v[202:203], v115 offset0:95 offset1:96
	v_mfma_f32_32x32x16_bf16 v[0:15], v[64:67], v[72:75], v[0:15]
	v_mfma_f32_32x32x16_bf16 v[16:31], v[64:67], v[76:79], v[16:31]
	v_mfma_f32_32x32x16_bf16 v[0:15], v[68:71], v[220:223], v[0:15]
	v_mfma_f32_32x32x16_bf16 v[16:31], v[68:71], v[224:227], v[16:31]
	global_load_dwordx4 v[116:119], v235, s[84:85]
	global_load_dwordx4 v[120:123], v236, s[84:85]
	global_load_dwordx4 v[124:127], v237, s[84:85]
	global_load_dwordx4 v[128:131], v238, s[84:85]
	global_load_dwordx4 v[132:135], v100, s[84:85] offset:768
	global_load_dwordx4 v[136:139], v149, s[84:85] offset:768
	global_load_dwordx4 v[140:143], v100, s[84:85] offset:832
	global_load_dwordx4 v[144:147], v149, s[84:85] offset:832
	s_add_u32 s84, s84, 0x30000
	s_addc_u32 s85, s85, 0
	ds_read_b64_tr_b16 v[72:73], v231
	ds_read_b64_tr_b16 v[74:75], v231 offset:512
	ds_read_b64_tr_b16 v[76:77], v231 offset:2048
	ds_read_b64_tr_b16 v[78:79], v231 offset:2560
	ds_read_b64_tr_b16 v[220:221], v231 offset:1024
	ds_read_b64_tr_b16 v[222:223], v231 offset:1536
	ds_read_b64_tr_b16 v[224:225], v231 offset:3072
	ds_read_b64_tr_b16 v[226:227], v231 offset:3584
	v_exp_f32_e32 v32, v32
	v_exp_f32_e32 v33, v33
	v_exp_f32_e32 v34, v34
	v_exp_f32_e32 v35, v35
	s_waitcnt vmcnt(12)
	ds_write_b128 v247, v[156:159]
	ds_write_b128 v247, v[160:163] offset:1024
	ds_write_b128 v247, v[164:167] offset:2048
	ds_write_b128 v247, v[168:171] offset:3072
	ds_read_b128 v[156:159], v248
	ds_read_b128 v[160:163], v249
	ds_read_b128 v[164:167], v250
	ds_read_b128 v[168:171], v251
	s_waitcnt vmcnt(8)
	ds_write_b128 v112, v[172:175]
	ds_write_b128 v112, v[176:179] offset:1024
	ds_write_b128 v112, v[180:183] offset:2048
	ds_write_b128 v112, v[184:187] offset:3072
	v_exp_f32_e32 v36, v36
	v_exp_f32_e32 v37, v37
	v_exp_f32_e32 v38, v38
	v_exp_f32_e32 v39, v39
	s_waitcnt lgkmcnt(4)
	v_mfma_f32_32x32x16_bf16 v[188:203], v[156:159], v[48:51], v[188:203]
	v_exp_f32_e32 v40, v40
	v_exp_f32_e32 v41, v41
	v_mfma_f32_32x32x16_bf16 v[188:203], v[160:163], v[52:55], v[188:203]
	v_exp_f32_e32 v42, v42
	v_exp_f32_e32 v43, v43
	v_mfma_f32_32x32x16_bf16 v[188:203], v[164:167], v[56:59], v[188:203]
	v_exp_f32_e32 v44, v44
	v_exp_f32_e32 v45, v45
	v_mfma_f32_32x32x16_bf16 v[188:203], v[168:171], v[60:63], v[188:203]
	v_exp_f32_e32 v46, v46
	v_exp_f32_e32 v47, v47
	v_cvt_pk_bf16_f32 v64, v32, v33
	v_cvt_pk_bf16_f32 v65, v34, v35
	v_cvt_pk_bf16_f32 v66, v36, v37
	v_cvt_pk_bf16_f32 v67, v38, v39
	v_cvt_pk_bf16_f32 v68, v40, v41
	v_cvt_pk_bf16_f32 v69, v42, v43
	v_cvt_pk_bf16_f32 v70, v44, v45
	v_cvt_pk_bf16_f32 v71, v46, v47
	v_pk_add_f32 v[232:233], v[232:233], v[32:33]
	v_pk_add_f32 v[232:233], v[232:233], v[34:35]
	v_pk_add_f32 v[232:233], v[232:233], v[36:37]
	v_pk_add_f32 v[232:233], v[232:233], v[38:39]
	v_pk_add_f32 v[232:233], v[232:233], v[40:41]
	v_pk_add_f32 v[232:233], v[232:233], v[42:43]
	v_pk_add_f32 v[232:233], v[232:233], v[44:45]
	v_pk_add_f32 v[232:233], v[232:233], v[46:47]
	ds_read2_b32 v[32:33], v115 offset0:102 offset1:103
	ds_read2_b32 v[34:35], v115 offset0:104 offset1:105
	ds_read2_b32 v[36:37], v115 offset0:110 offset1:111
	ds_read2_b32 v[38:39], v115 offset0:112 offset1:113
	ds_read2_b32 v[40:41], v115 offset0:119 offset1:120
	ds_read2_b32 v[42:43], v115 offset0:121 offset1:122
	ds_read2_b32 v[44:45], v115 offset0:127 offset1:128
	ds_read2_b32 v[46:47], v115 offset0:129 offset1:130
	v_mfma_f32_32x32x16_bf16 v[0:15], v[64:67], v[72:75], v[0:15]
	v_mfma_f32_32x32x16_bf16 v[16:31], v[64:67], v[76:79], v[16:31]
	v_mfma_f32_32x32x16_bf16 v[0:15], v[68:71], v[220:223], v[0:15]
	v_mfma_f32_32x32x16_bf16 v[16:31], v[68:71], v[224:227], v[16:31]
	global_load_dwordx4 v[156:159], v235, s[84:85]
	global_load_dwordx4 v[160:163], v236, s[84:85]
	global_load_dwordx4 v[164:167], v237, s[84:85]
	global_load_dwordx4 v[168:171], v238, s[84:85]
	global_load_dwordx4 v[172:175], v100, s[84:85] offset:768
	global_load_dwordx4 v[176:179], v149, s[84:85] offset:768
	global_load_dwordx4 v[180:183], v100, s[84:85] offset:832
	global_load_dwordx4 v[184:187], v149, s[84:85] offset:832
	s_add_u32 s84, s84, 0x30000
	s_addc_u32 s85, s85, 0
	ds_read_b64_tr_b16 v[72:73], v231
	ds_read_b64_tr_b16 v[74:75], v231 offset:512
	ds_read_b64_tr_b16 v[76:77], v231 offset:2048
	ds_read_b64_tr_b16 v[78:79], v231 offset:2560
	ds_read_b64_tr_b16 v[220:221], v231 offset:1024
	ds_read_b64_tr_b16 v[222:223], v231 offset:1536
	ds_read_b64_tr_b16 v[224:225], v231 offset:3072
	ds_read_b64_tr_b16 v[226:227], v231 offset:3584
	v_exp_f32_e32 v188, v188
	v_exp_f32_e32 v189, v189
	v_exp_f32_e32 v190, v190
	v_exp_f32_e32 v191, v191
	s_waitcnt vmcnt(12)
	ds_write_b128 v247, v[116:119]
	ds_write_b128 v247, v[120:123] offset:1024
	ds_write_b128 v247, v[124:127] offset:2048
	ds_write_b128 v247, v[128:131] offset:3072
	ds_read_b128 v[116:119], v248
	ds_read_b128 v[120:123], v249
	ds_read_b128 v[124:127], v250
	ds_read_b128 v[128:131], v251
	s_waitcnt vmcnt(8)
	ds_write_b128 v112, v[132:135]
	ds_write_b128 v112, v[136:139] offset:1024
	ds_write_b128 v112, v[140:143] offset:2048
	ds_write_b128 v112, v[144:147] offset:3072
	v_exp_f32_e32 v192, v192
	v_exp_f32_e32 v193, v193
	v_exp_f32_e32 v194, v194
	v_exp_f32_e32 v195, v195
	s_waitcnt lgkmcnt(4)
	v_mfma_f32_32x32x16_bf16 v[32:47], v[116:119], v[48:51], v[32:47]
	v_exp_f32_e32 v196, v196
	v_exp_f32_e32 v197, v197
	v_mfma_f32_32x32x16_bf16 v[32:47], v[120:123], v[52:55], v[32:47]
	v_exp_f32_e32 v198, v198
	v_exp_f32_e32 v199, v199
	v_mfma_f32_32x32x16_bf16 v[32:47], v[124:127], v[56:59], v[32:47]
	v_exp_f32_e32 v200, v200
	v_exp_f32_e32 v201, v201
	v_mfma_f32_32x32x16_bf16 v[32:47], v[128:131], v[60:63], v[32:47]
	v_exp_f32_e32 v202, v202
	v_exp_f32_e32 v203, v203
	v_cvt_pk_bf16_f32 v64, v188, v189
	v_cvt_pk_bf16_f32 v65, v190, v191
	v_cvt_pk_bf16_f32 v66, v192, v193
	v_cvt_pk_bf16_f32 v67, v194, v195
	v_cvt_pk_bf16_f32 v68, v196, v197
	v_cvt_pk_bf16_f32 v69, v198, v199
	v_cvt_pk_bf16_f32 v70, v200, v201
	v_cvt_pk_bf16_f32 v71, v202, v203
	v_pk_add_f32 v[232:233], v[232:233], v[188:189]
	v_pk_add_f32 v[232:233], v[232:233], v[190:191]
	v_pk_add_f32 v[232:233], v[232:233], v[192:193]
	v_pk_add_f32 v[232:233], v[232:233], v[194:195]
	v_pk_add_f32 v[232:233], v[232:233], v[196:197]
	v_pk_add_f32 v[232:233], v[232:233], v[198:199]
	v_pk_add_f32 v[232:233], v[232:233], v[200:201]
	v_pk_add_f32 v[232:233], v[232:233], v[202:203]
	ds_read2_b32 v[188:189], v115 offset0:136 offset1:137
	ds_read2_b32 v[190:191], v115 offset0:138 offset1:139
	ds_read2_b32 v[192:193], v115 offset0:144 offset1:145
	ds_read2_b32 v[194:195], v115 offset0:146 offset1:147
	ds_read2_b32 v[196:197], v115 offset0:153 offset1:154
	ds_read2_b32 v[198:199], v115 offset0:155 offset1:156
	ds_read2_b32 v[200:201], v115 offset0:161 offset1:162
	ds_read2_b32 v[202:203], v115 offset0:163 offset1:164
	v_mfma_f32_32x32x16_bf16 v[0:15], v[64:67], v[72:75], v[0:15]
	v_mfma_f32_32x32x16_bf16 v[16:31], v[64:67], v[76:79], v[16:31]
	v_mfma_f32_32x32x16_bf16 v[0:15], v[68:71], v[220:223], v[0:15]
	v_mfma_f32_32x32x16_bf16 v[16:31], v[68:71], v[224:227], v[16:31]
	global_load_dwordx4 v[116:119], v235, s[84:85]
	global_load_dwordx4 v[120:123], v236, s[84:85]
	global_load_dwordx4 v[124:127], v237, s[84:85]
	global_load_dwordx4 v[128:131], v238, s[84:85]
	global_load_dwordx4 v[132:135], v100, s[84:85] offset:768
	global_load_dwordx4 v[136:139], v149, s[84:85] offset:768
	global_load_dwordx4 v[140:143], v100, s[84:85] offset:832
	global_load_dwordx4 v[144:147], v149, s[84:85] offset:832
	s_add_u32 s84, s84, 0x30000
	s_addc_u32 s85, s85, 0
	ds_read_b64_tr_b16 v[72:73], v231
	ds_read_b64_tr_b16 v[74:75], v231 offset:512
	ds_read_b64_tr_b16 v[76:77], v231 offset:2048
	ds_read_b64_tr_b16 v[78:79], v231 offset:2560
	ds_read_b64_tr_b16 v[220:221], v231 offset:1024
	ds_read_b64_tr_b16 v[222:223], v231 offset:1536
	ds_read_b64_tr_b16 v[224:225], v231 offset:3072
	ds_read_b64_tr_b16 v[226:227], v231 offset:3584
	v_exp_f32_e32 v32, v32
	v_exp_f32_e32 v33, v33
	v_exp_f32_e32 v34, v34
	v_exp_f32_e32 v35, v35
	s_waitcnt vmcnt(12)
	ds_write_b128 v247, v[156:159]
	ds_write_b128 v247, v[160:163] offset:1024
	ds_write_b128 v247, v[164:167] offset:2048
	ds_write_b128 v247, v[168:171] offset:3072
	ds_read_b128 v[156:159], v248
	ds_read_b128 v[160:163], v249
	ds_read_b128 v[164:167], v250
	ds_read_b128 v[168:171], v251
	s_waitcnt vmcnt(8)
	ds_write_b128 v112, v[172:175]
	ds_write_b128 v112, v[176:179] offset:1024
	ds_write_b128 v112, v[180:183] offset:2048
	ds_write_b128 v112, v[184:187] offset:3072
	v_exp_f32_e32 v36, v36
	v_exp_f32_e32 v37, v37
	v_exp_f32_e32 v38, v38
	v_exp_f32_e32 v39, v39
	s_waitcnt lgkmcnt(4)
	v_mfma_f32_32x32x16_bf16 v[188:203], v[156:159], v[48:51], v[188:203]
	v_exp_f32_e32 v40, v40
	v_exp_f32_e32 v41, v41
	v_mfma_f32_32x32x16_bf16 v[188:203], v[160:163], v[52:55], v[188:203]
	v_exp_f32_e32 v42, v42
	v_exp_f32_e32 v43, v43
	v_mfma_f32_32x32x16_bf16 v[188:203], v[164:167], v[56:59], v[188:203]
	v_exp_f32_e32 v44, v44
	v_exp_f32_e32 v45, v45
	v_mfma_f32_32x32x16_bf16 v[188:203], v[168:171], v[60:63], v[188:203]
	v_exp_f32_e32 v46, v46
	v_exp_f32_e32 v47, v47
	v_cvt_pk_bf16_f32 v64, v32, v33
	v_cvt_pk_bf16_f32 v65, v34, v35
	v_cvt_pk_bf16_f32 v66, v36, v37
	v_cvt_pk_bf16_f32 v67, v38, v39
	v_cvt_pk_bf16_f32 v68, v40, v41
	v_cvt_pk_bf16_f32 v69, v42, v43
	v_cvt_pk_bf16_f32 v70, v44, v45
	v_cvt_pk_bf16_f32 v71, v46, v47
	v_pk_add_f32 v[232:233], v[232:233], v[32:33]
	v_pk_add_f32 v[232:233], v[232:233], v[34:35]
	v_pk_add_f32 v[232:233], v[232:233], v[36:37]
	v_pk_add_f32 v[232:233], v[232:233], v[38:39]
	v_pk_add_f32 v[232:233], v[232:233], v[40:41]
	v_pk_add_f32 v[232:233], v[232:233], v[42:43]
	v_pk_add_f32 v[232:233], v[232:233], v[44:45]
	v_pk_add_f32 v[232:233], v[232:233], v[46:47]
	ds_read2_b32 v[32:33], v115 offset0:170 offset1:171
	ds_read2_b32 v[34:35], v115 offset0:172 offset1:173
	ds_read2_b32 v[36:37], v115 offset0:178 offset1:179
	ds_read2_b32 v[38:39], v115 offset0:180 offset1:181
	ds_read2_b32 v[40:41], v115 offset0:187 offset1:188
	ds_read2_b32 v[42:43], v115 offset0:189 offset1:190
	ds_read2_b32 v[44:45], v115 offset0:195 offset1:196
	ds_read2_b32 v[46:47], v115 offset0:197 offset1:198
	v_mfma_f32_32x32x16_bf16 v[0:15], v[64:67], v[72:75], v[0:15]
	v_mfma_f32_32x32x16_bf16 v[16:31], v[64:67], v[76:79], v[16:31]
	v_mfma_f32_32x32x16_bf16 v[0:15], v[68:71], v[220:223], v[0:15]
	v_mfma_f32_32x32x16_bf16 v[16:31], v[68:71], v[224:227], v[16:31]
	global_load_dwordx4 v[156:159], v235, s[84:85]
	global_load_dwordx4 v[160:163], v236, s[84:85]
	global_load_dwordx4 v[164:167], v237, s[84:85]
	global_load_dwordx4 v[168:171], v238, s[84:85]
	global_load_dwordx4 v[172:175], v100, s[84:85] offset:768
	global_load_dwordx4 v[176:179], v149, s[84:85] offset:768
	global_load_dwordx4 v[180:183], v100, s[84:85] offset:832
	global_load_dwordx4 v[184:187], v149, s[84:85] offset:832
	s_add_u32 s84, s84, 0x30000
	s_addc_u32 s85, s85, 0
	ds_read_b64_tr_b16 v[72:73], v231
	ds_read_b64_tr_b16 v[74:75], v231 offset:512
	ds_read_b64_tr_b16 v[76:77], v231 offset:2048
	ds_read_b64_tr_b16 v[78:79], v231 offset:2560
	ds_read_b64_tr_b16 v[220:221], v231 offset:1024
	ds_read_b64_tr_b16 v[222:223], v231 offset:1536
	ds_read_b64_tr_b16 v[224:225], v231 offset:3072
	ds_read_b64_tr_b16 v[226:227], v231 offset:3584
	v_exp_f32_e32 v188, v188
	v_exp_f32_e32 v189, v189
	v_exp_f32_e32 v190, v190
	v_exp_f32_e32 v191, v191
	s_waitcnt vmcnt(12)
	ds_write_b128 v247, v[116:119]
	ds_write_b128 v247, v[120:123] offset:1024
	ds_write_b128 v247, v[124:127] offset:2048
	ds_write_b128 v247, v[128:131] offset:3072
	ds_read_b128 v[116:119], v248
	ds_read_b128 v[120:123], v249
	ds_read_b128 v[124:127], v250
	ds_read_b128 v[128:131], v251
	s_waitcnt vmcnt(8)
	ds_write_b128 v112, v[132:135]
	ds_write_b128 v112, v[136:139] offset:1024
	ds_write_b128 v112, v[140:143] offset:2048
	ds_write_b128 v112, v[144:147] offset:3072
	v_exp_f32_e32 v192, v192
	v_exp_f32_e32 v193, v193
	v_exp_f32_e32 v194, v194
	v_exp_f32_e32 v195, v195
	s_waitcnt lgkmcnt(4)
	v_mfma_f32_32x32x16_bf16 v[32:47], v[116:119], v[48:51], v[32:47]
	v_exp_f32_e32 v196, v196
	v_exp_f32_e32 v197, v197
	v_mfma_f32_32x32x16_bf16 v[32:47], v[120:123], v[52:55], v[32:47]
	v_exp_f32_e32 v198, v198
	v_exp_f32_e32 v199, v199
	v_mfma_f32_32x32x16_bf16 v[32:47], v[124:127], v[56:59], v[32:47]
	v_exp_f32_e32 v200, v200
	v_exp_f32_e32 v201, v201
	v_mfma_f32_32x32x16_bf16 v[32:47], v[128:131], v[60:63], v[32:47]
	v_exp_f32_e32 v202, v202
	v_exp_f32_e32 v203, v203
	v_cvt_pk_bf16_f32 v64, v188, v189
	v_cvt_pk_bf16_f32 v65, v190, v191
	v_cvt_pk_bf16_f32 v66, v192, v193
	v_cvt_pk_bf16_f32 v67, v194, v195
	v_cvt_pk_bf16_f32 v68, v196, v197
	v_cvt_pk_bf16_f32 v69, v198, v199
	v_cvt_pk_bf16_f32 v70, v200, v201
	v_cvt_pk_bf16_f32 v71, v202, v203
	v_pk_add_f32 v[232:233], v[232:233], v[188:189]
	v_pk_add_f32 v[232:233], v[232:233], v[190:191]
	v_pk_add_f32 v[232:233], v[232:233], v[192:193]
	v_pk_add_f32 v[232:233], v[232:233], v[194:195]
	v_pk_add_f32 v[232:233], v[232:233], v[196:197]
	v_pk_add_f32 v[232:233], v[232:233], v[198:199]
	v_pk_add_f32 v[232:233], v[232:233], v[200:201]
	v_pk_add_f32 v[232:233], v[232:233], v[202:203]
	ds_read2_b32 v[188:189], v115 offset0:204 offset1:205
	ds_read2_b32 v[190:191], v115 offset0:206 offset1:207
	ds_read2_b32 v[192:193], v115 offset0:212 offset1:213
	ds_read2_b32 v[194:195], v115 offset0:214 offset1:215
	ds_read2_b32 v[196:197], v115 offset0:221 offset1:222
	ds_read2_b32 v[198:199], v115 offset0:223 offset1:224
	ds_read2_b32 v[200:201], v115 offset0:229 offset1:230
	ds_read2_b32 v[202:203], v115 offset0:231 offset1:232
	v_mfma_f32_32x32x16_bf16 v[0:15], v[64:67], v[72:75], v[0:15]
	v_mfma_f32_32x32x16_bf16 v[16:31], v[64:67], v[76:79], v[16:31]
	v_mfma_f32_32x32x16_bf16 v[0:15], v[68:71], v[220:223], v[0:15]
	v_mfma_f32_32x32x16_bf16 v[16:31], v[68:71], v[224:227], v[16:31]
	global_load_dwordx4 v[116:119], v235, s[84:85]
	global_load_dwordx4 v[120:123], v236, s[84:85]
	global_load_dwordx4 v[124:127], v237, s[84:85]
	global_load_dwordx4 v[128:131], v238, s[84:85]
	global_load_dwordx4 v[132:135], v100, s[84:85] offset:768
	global_load_dwordx4 v[136:139], v149, s[84:85] offset:768
	global_load_dwordx4 v[140:143], v100, s[84:85] offset:832
	global_load_dwordx4 v[144:147], v149, s[84:85] offset:832
	s_add_u32 s84, s84, 0x30000
	s_addc_u32 s85, s85, 0
	ds_read_b64_tr_b16 v[72:73], v231
	ds_read_b64_tr_b16 v[74:75], v231 offset:512
	ds_read_b64_tr_b16 v[76:77], v231 offset:2048
	ds_read_b64_tr_b16 v[78:79], v231 offset:2560
	ds_read_b64_tr_b16 v[220:221], v231 offset:1024
	ds_read_b64_tr_b16 v[222:223], v231 offset:1536
	ds_read_b64_tr_b16 v[224:225], v231 offset:3072
	ds_read_b64_tr_b16 v[226:227], v231 offset:3584
	v_exp_f32_e32 v32, v32
	v_exp_f32_e32 v33, v33
	v_exp_f32_e32 v34, v34
	v_exp_f32_e32 v35, v35
	s_waitcnt vmcnt(12)
	ds_write_b128 v247, v[156:159]
	ds_write_b128 v247, v[160:163] offset:1024
	ds_write_b128 v247, v[164:167] offset:2048
	ds_write_b128 v247, v[168:171] offset:3072
	ds_read_b128 v[156:159], v248
	ds_read_b128 v[160:163], v249
	ds_read_b128 v[164:167], v250
	ds_read_b128 v[168:171], v251
	s_waitcnt vmcnt(8)
	ds_write_b128 v112, v[172:175]
	ds_write_b128 v112, v[176:179] offset:1024
	ds_write_b128 v112, v[180:183] offset:2048
	ds_write_b128 v112, v[184:187] offset:3072
	v_exp_f32_e32 v36, v36
	v_exp_f32_e32 v37, v37
	v_exp_f32_e32 v38, v38
	v_exp_f32_e32 v39, v39
	s_waitcnt lgkmcnt(4)
	v_mfma_f32_32x32x16_bf16 v[188:203], v[156:159], v[48:51], v[188:203]
	v_exp_f32_e32 v40, v40
	v_exp_f32_e32 v41, v41
	v_mfma_f32_32x32x16_bf16 v[188:203], v[160:163], v[52:55], v[188:203]
	v_exp_f32_e32 v42, v42
	v_exp_f32_e32 v43, v43
	v_mfma_f32_32x32x16_bf16 v[188:203], v[164:167], v[56:59], v[188:203]
	v_exp_f32_e32 v44, v44
	v_exp_f32_e32 v45, v45
	v_mfma_f32_32x32x16_bf16 v[188:203], v[168:171], v[60:63], v[188:203]
	v_exp_f32_e32 v46, v46
	v_exp_f32_e32 v47, v47
	v_cvt_pk_bf16_f32 v64, v32, v33
	v_cvt_pk_bf16_f32 v65, v34, v35
	v_cvt_pk_bf16_f32 v66, v36, v37
	v_cvt_pk_bf16_f32 v67, v38, v39
	v_cvt_pk_bf16_f32 v68, v40, v41
	v_cvt_pk_bf16_f32 v69, v42, v43
	v_cvt_pk_bf16_f32 v70, v44, v45
	v_cvt_pk_bf16_f32 v71, v46, v47
	v_pk_add_f32 v[232:233], v[232:233], v[32:33]
	v_pk_add_f32 v[232:233], v[232:233], v[34:35]
	v_pk_add_f32 v[232:233], v[232:233], v[36:37]
	v_pk_add_f32 v[232:233], v[232:233], v[38:39]
	v_pk_add_f32 v[232:233], v[232:233], v[40:41]
	v_pk_add_f32 v[232:233], v[232:233], v[42:43]
	v_pk_add_f32 v[232:233], v[232:233], v[44:45]
	v_pk_add_f32 v[232:233], v[232:233], v[46:47]
	v_add_u32_e32 v115, 952, v115
	ds_read2_b32 v[32:33], v115 offset0:0 offset1:1
	ds_read2_b32 v[34:35], v115 offset0:2 offset1:3
	ds_read2_b32 v[36:37], v115 offset0:8 offset1:9
	ds_read2_b32 v[38:39], v115 offset0:10 offset1:11
	ds_read2_b32 v[40:41], v115 offset0:17 offset1:18
	ds_read2_b32 v[42:43], v115 offset0:19 offset1:20
	ds_read2_b32 v[44:45], v115 offset0:25 offset1:26
	ds_read2_b32 v[46:47], v115 offset0:27 offset1:28
	v_mfma_f32_32x32x16_bf16 v[0:15], v[64:67], v[72:75], v[0:15]
	v_mfma_f32_32x32x16_bf16 v[16:31], v[64:67], v[76:79], v[16:31]
	v_mfma_f32_32x32x16_bf16 v[0:15], v[68:71], v[220:223], v[0:15]
	v_mfma_f32_32x32x16_bf16 v[16:31], v[68:71], v[224:227], v[16:31]
	global_load_dwordx4 v[156:159], v235, s[84:85]
	global_load_dwordx4 v[160:163], v236, s[84:85]
	global_load_dwordx4 v[164:167], v237, s[84:85]
	global_load_dwordx4 v[168:171], v238, s[84:85]
	global_load_dwordx4 v[172:175], v100, s[84:85] offset:768
	global_load_dwordx4 v[176:179], v149, s[84:85] offset:768
	global_load_dwordx4 v[180:183], v100, s[84:85] offset:832
	global_load_dwordx4 v[184:187], v149, s[84:85] offset:832
	s_add_u32 s84, s84, 0x30000
	s_addc_u32 s85, s85, 0
	ds_read_b64_tr_b16 v[72:73], v231
	ds_read_b64_tr_b16 v[74:75], v231 offset:512
	ds_read_b64_tr_b16 v[76:77], v231 offset:2048
	ds_read_b64_tr_b16 v[78:79], v231 offset:2560
	ds_read_b64_tr_b16 v[220:221], v231 offset:1024
	ds_read_b64_tr_b16 v[222:223], v231 offset:1536
	ds_read_b64_tr_b16 v[224:225], v231 offset:3072
	ds_read_b64_tr_b16 v[226:227], v231 offset:3584
	v_exp_f32_e32 v188, v188
	v_exp_f32_e32 v189, v189
	v_exp_f32_e32 v190, v190
	v_exp_f32_e32 v191, v191
	s_waitcnt vmcnt(12)
	ds_write_b128 v247, v[116:119]
	ds_write_b128 v247, v[120:123] offset:1024
	ds_write_b128 v247, v[124:127] offset:2048
	ds_write_b128 v247, v[128:131] offset:3072
	ds_read_b128 v[116:119], v248
	ds_read_b128 v[120:123], v249
	ds_read_b128 v[124:127], v250
	ds_read_b128 v[128:131], v251
	s_waitcnt vmcnt(8)
	ds_write_b128 v112, v[132:135]
	ds_write_b128 v112, v[136:139] offset:1024
	ds_write_b128 v112, v[140:143] offset:2048
	ds_write_b128 v112, v[144:147] offset:3072
	v_exp_f32_e32 v192, v192
	v_exp_f32_e32 v193, v193
	v_exp_f32_e32 v194, v194
	v_exp_f32_e32 v195, v195
	s_waitcnt lgkmcnt(4)
	v_mfma_f32_32x32x16_bf16 v[32:47], v[116:119], v[48:51], v[32:47]
	v_exp_f32_e32 v196, v196
	v_exp_f32_e32 v197, v197
	v_mfma_f32_32x32x16_bf16 v[32:47], v[120:123], v[52:55], v[32:47]
	v_exp_f32_e32 v198, v198
	v_exp_f32_e32 v199, v199
	v_mfma_f32_32x32x16_bf16 v[32:47], v[124:127], v[56:59], v[32:47]
	v_exp_f32_e32 v200, v200
	v_exp_f32_e32 v201, v201
	v_mfma_f32_32x32x16_bf16 v[32:47], v[128:131], v[60:63], v[32:47]
	v_exp_f32_e32 v202, v202
	v_exp_f32_e32 v203, v203
	v_cvt_pk_bf16_f32 v64, v188, v189
	v_cvt_pk_bf16_f32 v65, v190, v191
	v_cvt_pk_bf16_f32 v66, v192, v193
	v_cvt_pk_bf16_f32 v67, v194, v195
	v_cvt_pk_bf16_f32 v68, v196, v197
	v_cvt_pk_bf16_f32 v69, v198, v199
	v_cvt_pk_bf16_f32 v70, v200, v201
	v_cvt_pk_bf16_f32 v71, v202, v203
	v_pk_add_f32 v[232:233], v[232:233], v[188:189]
	v_pk_add_f32 v[232:233], v[232:233], v[190:191]
	v_pk_add_f32 v[232:233], v[232:233], v[192:193]
	v_pk_add_f32 v[232:233], v[232:233], v[194:195]
	v_pk_add_f32 v[232:233], v[232:233], v[196:197]
	v_pk_add_f32 v[232:233], v[232:233], v[198:199]
	v_pk_add_f32 v[232:233], v[232:233], v[200:201]
	v_pk_add_f32 v[232:233], v[232:233], v[202:203]
	ds_read2_b32 v[188:189], v115 offset0:34 offset1:35
	ds_read2_b32 v[190:191], v115 offset0:36 offset1:37
	ds_read2_b32 v[192:193], v115 offset0:42 offset1:43
	ds_read2_b32 v[194:195], v115 offset0:44 offset1:45
	ds_read2_b32 v[196:197], v115 offset0:51 offset1:52
	ds_read2_b32 v[198:199], v115 offset0:53 offset1:54
	ds_read2_b32 v[200:201], v115 offset0:59 offset1:60
	ds_read2_b32 v[202:203], v115 offset0:61 offset1:62
	v_mfma_f32_32x32x16_bf16 v[0:15], v[64:67], v[72:75], v[0:15]
	v_mfma_f32_32x32x16_bf16 v[16:31], v[64:67], v[76:79], v[16:31]
	v_mfma_f32_32x32x16_bf16 v[0:15], v[68:71], v[220:223], v[0:15]
	v_mfma_f32_32x32x16_bf16 v[16:31], v[68:71], v[224:227], v[16:31]
	global_load_dwordx4 v[116:119], v235, s[84:85]
	global_load_dwordx4 v[120:123], v236, s[84:85]
	global_load_dwordx4 v[124:127], v237, s[84:85]
	global_load_dwordx4 v[128:131], v238, s[84:85]
	global_load_dwordx4 v[132:135], v100, s[84:85] offset:768
	global_load_dwordx4 v[136:139], v149, s[84:85] offset:768
	global_load_dwordx4 v[140:143], v100, s[84:85] offset:832
	global_load_dwordx4 v[144:147], v149, s[84:85] offset:832
	s_add_u32 s84, s84, 0x30000
	s_addc_u32 s85, s85, 0
	ds_read_b64_tr_b16 v[72:73], v231
	ds_read_b64_tr_b16 v[74:75], v231 offset:512
	ds_read_b64_tr_b16 v[76:77], v231 offset:2048
	ds_read_b64_tr_b16 v[78:79], v231 offset:2560
	ds_read_b64_tr_b16 v[220:221], v231 offset:1024
	ds_read_b64_tr_b16 v[222:223], v231 offset:1536
	ds_read_b64_tr_b16 v[224:225], v231 offset:3072
	ds_read_b64_tr_b16 v[226:227], v231 offset:3584
	v_exp_f32_e32 v32, v32
	v_exp_f32_e32 v33, v33
	v_exp_f32_e32 v34, v34
	v_exp_f32_e32 v35, v35
	s_waitcnt vmcnt(12)
	ds_write_b128 v247, v[156:159]
	ds_write_b128 v247, v[160:163] offset:1024
	ds_write_b128 v247, v[164:167] offset:2048
	ds_write_b128 v247, v[168:171] offset:3072
	ds_read_b128 v[156:159], v248
	ds_read_b128 v[160:163], v249
	ds_read_b128 v[164:167], v250
	ds_read_b128 v[168:171], v251
	s_waitcnt vmcnt(8)
	ds_write_b128 v112, v[172:175]
	ds_write_b128 v112, v[176:179] offset:1024
	ds_write_b128 v112, v[180:183] offset:2048
	ds_write_b128 v112, v[184:187] offset:3072
	v_exp_f32_e32 v36, v36
	v_exp_f32_e32 v37, v37
	v_exp_f32_e32 v38, v38
	v_exp_f32_e32 v39, v39
	s_waitcnt lgkmcnt(4)
	v_mfma_f32_32x32x16_bf16 v[188:203], v[156:159], v[48:51], v[188:203]
	v_exp_f32_e32 v40, v40
	v_exp_f32_e32 v41, v41
	v_mfma_f32_32x32x16_bf16 v[188:203], v[160:163], v[52:55], v[188:203]
	v_exp_f32_e32 v42, v42
	v_exp_f32_e32 v43, v43
	v_mfma_f32_32x32x16_bf16 v[188:203], v[164:167], v[56:59], v[188:203]
	v_exp_f32_e32 v44, v44
	v_exp_f32_e32 v45, v45
	v_mfma_f32_32x32x16_bf16 v[188:203], v[168:171], v[60:63], v[188:203]
	v_exp_f32_e32 v46, v46
	v_exp_f32_e32 v47, v47
	v_cvt_pk_bf16_f32 v64, v32, v33
	v_cvt_pk_bf16_f32 v65, v34, v35
	v_cvt_pk_bf16_f32 v66, v36, v37
	v_cvt_pk_bf16_f32 v67, v38, v39
	v_cvt_pk_bf16_f32 v68, v40, v41
	v_cvt_pk_bf16_f32 v69, v42, v43
	v_cvt_pk_bf16_f32 v70, v44, v45
	v_cvt_pk_bf16_f32 v71, v46, v47
	v_pk_add_f32 v[232:233], v[232:233], v[32:33]
	v_pk_add_f32 v[232:233], v[232:233], v[34:35]
	v_pk_add_f32 v[232:233], v[232:233], v[36:37]
	v_pk_add_f32 v[232:233], v[232:233], v[38:39]
	v_pk_add_f32 v[232:233], v[232:233], v[40:41]
	v_pk_add_f32 v[232:233], v[232:233], v[42:43]
	v_pk_add_f32 v[232:233], v[232:233], v[44:45]
	v_pk_add_f32 v[232:233], v[232:233], v[46:47]
	ds_read2_b32 v[32:33], v115 offset0:68 offset1:69
	ds_read2_b32 v[34:35], v115 offset0:70 offset1:71
	ds_read2_b32 v[36:37], v115 offset0:76 offset1:77
	ds_read2_b32 v[38:39], v115 offset0:78 offset1:79
	ds_read2_b32 v[40:41], v115 offset0:85 offset1:86
	ds_read2_b32 v[42:43], v115 offset0:87 offset1:88
	ds_read2_b32 v[44:45], v115 offset0:93 offset1:94
	ds_read2_b32 v[46:47], v115 offset0:95 offset1:96
	v_mfma_f32_32x32x16_bf16 v[0:15], v[64:67], v[72:75], v[0:15]
	v_mfma_f32_32x32x16_bf16 v[16:31], v[64:67], v[76:79], v[16:31]
	v_mfma_f32_32x32x16_bf16 v[0:15], v[68:71], v[220:223], v[0:15]
	v_mfma_f32_32x32x16_bf16 v[16:31], v[68:71], v[224:227], v[16:31]
	global_load_dwordx4 v[156:159], v235, s[84:85]
	global_load_dwordx4 v[160:163], v236, s[84:85]
	global_load_dwordx4 v[164:167], v237, s[84:85]
	global_load_dwordx4 v[168:171], v238, s[84:85]
	global_load_dwordx4 v[172:175], v100, s[84:85] offset:768
	global_load_dwordx4 v[176:179], v149, s[84:85] offset:768
	global_load_dwordx4 v[180:183], v100, s[84:85] offset:832
	global_load_dwordx4 v[184:187], v149, s[84:85] offset:832
	s_add_u32 s84, s84, 0x30000
	s_addc_u32 s85, s85, 0
	ds_read_b64_tr_b16 v[72:73], v231
	ds_read_b64_tr_b16 v[74:75], v231 offset:512
	ds_read_b64_tr_b16 v[76:77], v231 offset:2048
	ds_read_b64_tr_b16 v[78:79], v231 offset:2560
	ds_read_b64_tr_b16 v[220:221], v231 offset:1024
	ds_read_b64_tr_b16 v[222:223], v231 offset:1536
	ds_read_b64_tr_b16 v[224:225], v231 offset:3072
	ds_read_b64_tr_b16 v[226:227], v231 offset:3584
	v_exp_f32_e32 v188, v188
	v_exp_f32_e32 v189, v189
	v_exp_f32_e32 v190, v190
	v_exp_f32_e32 v191, v191
	s_waitcnt vmcnt(12)
	ds_write_b128 v247, v[116:119]
	ds_write_b128 v247, v[120:123] offset:1024
	ds_write_b128 v247, v[124:127] offset:2048
	ds_write_b128 v247, v[128:131] offset:3072
	ds_read_b128 v[116:119], v248
	ds_read_b128 v[120:123], v249
	ds_read_b128 v[124:127], v250
	ds_read_b128 v[128:131], v251
	s_waitcnt vmcnt(8)
	ds_write_b128 v112, v[132:135]
	ds_write_b128 v112, v[136:139] offset:1024
	ds_write_b128 v112, v[140:143] offset:2048
	ds_write_b128 v112, v[144:147] offset:3072
	v_exp_f32_e32 v192, v192
	v_exp_f32_e32 v193, v193
	v_exp_f32_e32 v194, v194
	v_exp_f32_e32 v195, v195
	s_waitcnt lgkmcnt(4)
	v_mfma_f32_32x32x16_bf16 v[32:47], v[116:119], v[48:51], v[32:47]
	v_exp_f32_e32 v196, v196
	v_exp_f32_e32 v197, v197
	v_mfma_f32_32x32x16_bf16 v[32:47], v[120:123], v[52:55], v[32:47]
	v_exp_f32_e32 v198, v198
	v_exp_f32_e32 v199, v199
	v_mfma_f32_32x32x16_bf16 v[32:47], v[124:127], v[56:59], v[32:47]
	v_exp_f32_e32 v200, v200
	v_exp_f32_e32 v201, v201
	v_mfma_f32_32x32x16_bf16 v[32:47], v[128:131], v[60:63], v[32:47]
	v_exp_f32_e32 v202, v202
	v_exp_f32_e32 v203, v203
	v_cvt_pk_bf16_f32 v64, v188, v189
	v_cvt_pk_bf16_f32 v65, v190, v191
	v_cvt_pk_bf16_f32 v66, v192, v193
	v_cvt_pk_bf16_f32 v67, v194, v195
	v_cvt_pk_bf16_f32 v68, v196, v197
	v_cvt_pk_bf16_f32 v69, v198, v199
	v_cvt_pk_bf16_f32 v70, v200, v201
	v_cvt_pk_bf16_f32 v71, v202, v203
	v_pk_add_f32 v[232:233], v[232:233], v[188:189]
	v_pk_add_f32 v[232:233], v[232:233], v[190:191]
	v_pk_add_f32 v[232:233], v[232:233], v[192:193]
	v_pk_add_f32 v[232:233], v[232:233], v[194:195]
	v_pk_add_f32 v[232:233], v[232:233], v[196:197]
	v_pk_add_f32 v[232:233], v[232:233], v[198:199]
	v_pk_add_f32 v[232:233], v[232:233], v[200:201]
	v_pk_add_f32 v[232:233], v[232:233], v[202:203]
	ds_read2_b32 v[188:189], v115 offset0:102 offset1:103
	ds_read2_b32 v[190:191], v115 offset0:104 offset1:105
	ds_read2_b32 v[192:193], v115 offset0:110 offset1:111
	ds_read2_b32 v[194:195], v115 offset0:112 offset1:113
	ds_read2_b32 v[196:197], v115 offset0:119 offset1:120
	ds_read2_b32 v[198:199], v115 offset0:121 offset1:122
	ds_read2_b32 v[200:201], v115 offset0:127 offset1:128
	ds_read2_b32 v[202:203], v115 offset0:129 offset1:130
	v_mfma_f32_32x32x16_bf16 v[0:15], v[64:67], v[72:75], v[0:15]
	v_mfma_f32_32x32x16_bf16 v[16:31], v[64:67], v[76:79], v[16:31]
	v_mfma_f32_32x32x16_bf16 v[0:15], v[68:71], v[220:223], v[0:15]
	v_mfma_f32_32x32x16_bf16 v[16:31], v[68:71], v[224:227], v[16:31]
	global_load_dwordx4 v[116:119], v235, s[84:85]
	global_load_dwordx4 v[120:123], v236, s[84:85]
	global_load_dwordx4 v[124:127], v237, s[84:85]
	global_load_dwordx4 v[128:131], v238, s[84:85]
	global_load_dwordx4 v[132:135], v100, s[84:85] offset:768
	global_load_dwordx4 v[136:139], v149, s[84:85] offset:768
	global_load_dwordx4 v[140:143], v100, s[84:85] offset:832
	global_load_dwordx4 v[144:147], v149, s[84:85] offset:832
	s_add_u32 s84, s84, 0x30000
	s_addc_u32 s85, s85, 0
	ds_read_b64_tr_b16 v[72:73], v231
	ds_read_b64_tr_b16 v[74:75], v231 offset:512
	ds_read_b64_tr_b16 v[76:77], v231 offset:2048
	ds_read_b64_tr_b16 v[78:79], v231 offset:2560
	ds_read_b64_tr_b16 v[220:221], v231 offset:1024
	ds_read_b64_tr_b16 v[222:223], v231 offset:1536
	ds_read_b64_tr_b16 v[224:225], v231 offset:3072
	ds_read_b64_tr_b16 v[226:227], v231 offset:3584
	v_exp_f32_e32 v32, v32
	v_exp_f32_e32 v33, v33
	v_exp_f32_e32 v34, v34
	v_exp_f32_e32 v35, v35
	s_waitcnt vmcnt(12)
	ds_write_b128 v247, v[156:159]
	ds_write_b128 v247, v[160:163] offset:1024
	ds_write_b128 v247, v[164:167] offset:2048
	ds_write_b128 v247, v[168:171] offset:3072
	ds_read_b128 v[156:159], v248
	ds_read_b128 v[160:163], v249
	ds_read_b128 v[164:167], v250
	ds_read_b128 v[168:171], v251
	s_waitcnt vmcnt(8)
	ds_write_b128 v112, v[172:175]
	ds_write_b128 v112, v[176:179] offset:1024
	ds_write_b128 v112, v[180:183] offset:2048
	ds_write_b128 v112, v[184:187] offset:3072
	v_exp_f32_e32 v36, v36
	v_exp_f32_e32 v37, v37
	v_exp_f32_e32 v38, v38
	v_exp_f32_e32 v39, v39
	s_waitcnt lgkmcnt(4)
	v_mfma_f32_32x32x16_bf16 v[188:203], v[156:159], v[48:51], v[188:203]
	v_exp_f32_e32 v40, v40
	v_exp_f32_e32 v41, v41
	v_mfma_f32_32x32x16_bf16 v[188:203], v[160:163], v[52:55], v[188:203]
	v_exp_f32_e32 v42, v42
	v_exp_f32_e32 v43, v43
	v_mfma_f32_32x32x16_bf16 v[188:203], v[164:167], v[56:59], v[188:203]
	v_exp_f32_e32 v44, v44
	v_exp_f32_e32 v45, v45
	v_mfma_f32_32x32x16_bf16 v[188:203], v[168:171], v[60:63], v[188:203]
	v_exp_f32_e32 v46, v46
	v_exp_f32_e32 v47, v47
	v_cvt_pk_bf16_f32 v64, v32, v33
	v_cvt_pk_bf16_f32 v65, v34, v35
	v_cvt_pk_bf16_f32 v66, v36, v37
	v_cvt_pk_bf16_f32 v67, v38, v39
	v_cvt_pk_bf16_f32 v68, v40, v41
	v_cvt_pk_bf16_f32 v69, v42, v43
	v_cvt_pk_bf16_f32 v70, v44, v45
	v_cvt_pk_bf16_f32 v71, v46, v47
	v_pk_add_f32 v[232:233], v[232:233], v[32:33]
	v_pk_add_f32 v[232:233], v[232:233], v[34:35]
	v_pk_add_f32 v[232:233], v[232:233], v[36:37]
	v_pk_add_f32 v[232:233], v[232:233], v[38:39]
	v_pk_add_f32 v[232:233], v[232:233], v[40:41]
	v_pk_add_f32 v[232:233], v[232:233], v[42:43]
	v_pk_add_f32 v[232:233], v[232:233], v[44:45]
	v_pk_add_f32 v[232:233], v[232:233], v[46:47]
	ds_read2_b32 v[32:33], v115 offset0:136 offset1:137
	ds_read2_b32 v[34:35], v115 offset0:138 offset1:139
	ds_read2_b32 v[36:37], v115 offset0:144 offset1:145
	ds_read2_b32 v[38:39], v115 offset0:146 offset1:147
	ds_read2_b32 v[40:41], v115 offset0:153 offset1:154
	ds_read2_b32 v[42:43], v115 offset0:155 offset1:156
	ds_read2_b32 v[44:45], v115 offset0:161 offset1:162
	ds_read2_b32 v[46:47], v115 offset0:163 offset1:164
	v_mfma_f32_32x32x16_bf16 v[0:15], v[64:67], v[72:75], v[0:15]
	v_mfma_f32_32x32x16_bf16 v[16:31], v[64:67], v[76:79], v[16:31]
	v_mfma_f32_32x32x16_bf16 v[0:15], v[68:71], v[220:223], v[0:15]
	v_mfma_f32_32x32x16_bf16 v[16:31], v[68:71], v[224:227], v[16:31]
	global_load_dwordx4 v[156:159], v235, s[84:85]
	global_load_dwordx4 v[160:163], v236, s[84:85]
	global_load_dwordx4 v[164:167], v237, s[84:85]
	global_load_dwordx4 v[168:171], v238, s[84:85]
	global_load_dwordx4 v[172:175], v100, s[84:85] offset:768
	global_load_dwordx4 v[176:179], v149, s[84:85] offset:768
	global_load_dwordx4 v[180:183], v100, s[84:85] offset:832
	global_load_dwordx4 v[184:187], v149, s[84:85] offset:832
	ds_read_b64_tr_b16 v[72:73], v231
	ds_read_b64_tr_b16 v[74:75], v231 offset:512
	ds_read_b64_tr_b16 v[76:77], v231 offset:2048
	ds_read_b64_tr_b16 v[78:79], v231 offset:2560
	ds_read_b64_tr_b16 v[220:221], v231 offset:1024
	ds_read_b64_tr_b16 v[222:223], v231 offset:1536
	ds_read_b64_tr_b16 v[224:225], v231 offset:3072
	ds_read_b64_tr_b16 v[226:227], v231 offset:3584
	v_exp_f32_e32 v188, v188
	v_exp_f32_e32 v189, v189
	v_exp_f32_e32 v190, v190
	v_exp_f32_e32 v191, v191
	s_waitcnt vmcnt(12)
	ds_write_b128 v247, v[116:119]
	ds_write_b128 v247, v[120:123] offset:1024
	ds_write_b128 v247, v[124:127] offset:2048
	ds_write_b128 v247, v[128:131] offset:3072
	ds_read_b128 v[116:119], v248
	ds_read_b128 v[120:123], v249
	ds_read_b128 v[124:127], v250
	ds_read_b128 v[128:131], v251
	s_waitcnt vmcnt(8)
	ds_write_b128 v112, v[132:135]
	ds_write_b128 v112, v[136:139] offset:1024
	ds_write_b128 v112, v[140:143] offset:2048
	ds_write_b128 v112, v[144:147] offset:3072
	v_exp_f32_e32 v192, v192
	v_exp_f32_e32 v193, v193
	v_exp_f32_e32 v194, v194
	v_exp_f32_e32 v195, v195
	s_waitcnt lgkmcnt(4)
	v_mfma_f32_32x32x16_bf16 v[32:47], v[116:119], v[48:51], v[32:47]
	v_exp_f32_e32 v196, v196
	v_exp_f32_e32 v197, v197
	v_mfma_f32_32x32x16_bf16 v[32:47], v[120:123], v[52:55], v[32:47]
	v_exp_f32_e32 v198, v198
	v_exp_f32_e32 v199, v199
	v_mfma_f32_32x32x16_bf16 v[32:47], v[124:127], v[56:59], v[32:47]
	v_exp_f32_e32 v200, v200
	v_exp_f32_e32 v201, v201
	v_mfma_f32_32x32x16_bf16 v[32:47], v[128:131], v[60:63], v[32:47]
	v_exp_f32_e32 v202, v202
	v_exp_f32_e32 v203, v203
	v_cvt_pk_bf16_f32 v64, v188, v189
	v_cvt_pk_bf16_f32 v65, v190, v191
	v_cvt_pk_bf16_f32 v66, v192, v193
	v_cvt_pk_bf16_f32 v67, v194, v195
	v_cvt_pk_bf16_f32 v68, v196, v197
	v_cvt_pk_bf16_f32 v69, v198, v199
	v_cvt_pk_bf16_f32 v70, v200, v201
	v_cvt_pk_bf16_f32 v71, v202, v203
	v_pk_add_f32 v[232:233], v[232:233], v[188:189]
	v_pk_add_f32 v[232:233], v[232:233], v[190:191]
	v_pk_add_f32 v[232:233], v[232:233], v[192:193]
	v_pk_add_f32 v[232:233], v[232:233], v[194:195]
	v_pk_add_f32 v[232:233], v[232:233], v[196:197]
	v_pk_add_f32 v[232:233], v[232:233], v[198:199]
	v_pk_add_f32 v[232:233], v[232:233], v[200:201]
	v_pk_add_f32 v[232:233], v[232:233], v[202:203]
	ds_read2_b32 v[188:189], v115 offset0:170 offset1:171
	ds_read2_b32 v[190:191], v115 offset0:172 offset1:173
	ds_read2_b32 v[192:193], v115 offset0:178 offset1:179
	ds_read2_b32 v[194:195], v115 offset0:180 offset1:181
	ds_read2_b32 v[196:197], v115 offset0:187 offset1:188
	ds_read2_b32 v[198:199], v115 offset0:189 offset1:190
	ds_read2_b32 v[200:201], v115 offset0:195 offset1:196
	ds_read2_b32 v[202:203], v115 offset0:197 offset1:198
	v_mfma_f32_32x32x16_bf16 v[0:15], v[64:67], v[72:75], v[0:15]
	v_mfma_f32_32x32x16_bf16 v[16:31], v[64:67], v[76:79], v[16:31]
	v_mfma_f32_32x32x16_bf16 v[0:15], v[68:71], v[220:223], v[0:15]
	v_mfma_f32_32x32x16_bf16 v[16:31], v[68:71], v[224:227], v[16:31]
	global_load_dwordx4 v[116:119], v239, s[86:87]
	global_load_dwordx4 v[120:123], v240, s[86:87]
	global_load_dwordx4 v[124:127], v241, s[86:87]
	global_load_dwordx4 v[128:131], v242, s[86:87]
	global_load_dwordx4 v[132:135], v101, s[86:87] offset:768
	global_load_dwordx4 v[136:139], v150, s[86:87] offset:768
	global_load_dwordx4 v[140:143], v101, s[86:87] offset:832
	global_load_dwordx4 v[144:147], v150, s[86:87] offset:832
	s_add_u32 s86, s86, 0xc0000
	s_addc_u32 s87, s87, 0
	ds_read_b64_tr_b16 v[72:73], v231
	ds_read_b64_tr_b16 v[74:75], v231 offset:512
	ds_read_b64_tr_b16 v[76:77], v231 offset:2048
	ds_read_b64_tr_b16 v[78:79], v231 offset:2560
	ds_read_b64_tr_b16 v[220:221], v231 offset:1024
	ds_read_b64_tr_b16 v[222:223], v231 offset:1536
	ds_read_b64_tr_b16 v[224:225], v231 offset:3072
	ds_read_b64_tr_b16 v[226:227], v231 offset:3584
	v_exp_f32_e32 v32, v32
	v_exp_f32_e32 v33, v33
	v_exp_f32_e32 v34, v34
	v_exp_f32_e32 v35, v35
	s_waitcnt vmcnt(12)
	ds_write_b128 v247, v[156:159]
	ds_write_b128 v247, v[160:163] offset:1024
	ds_write_b128 v247, v[164:167] offset:2048
	ds_write_b128 v247, v[168:171] offset:3072
	ds_read_b128 v[156:159], v248
	ds_read_b128 v[160:163], v249
	ds_read_b128 v[164:167], v250
	ds_read_b128 v[168:171], v251
	s_waitcnt vmcnt(8)
	ds_write_b128 v112, v[172:175]
	ds_write_b128 v112, v[176:179] offset:1024
	ds_write_b128 v112, v[180:183] offset:2048
	ds_write_b128 v112, v[184:187] offset:3072
	v_exp_f32_e32 v36, v36
	v_exp_f32_e32 v37, v37
	v_exp_f32_e32 v38, v38
	v_exp_f32_e32 v39, v39
	s_waitcnt lgkmcnt(4)
	v_mfma_f32_32x32x16_bf16 v[188:203], v[156:159], v[48:51], v[188:203]
	v_exp_f32_e32 v40, v40
	v_exp_f32_e32 v41, v41
	v_mfma_f32_32x32x16_bf16 v[188:203], v[160:163], v[52:55], v[188:203]
	v_exp_f32_e32 v42, v42
	v_exp_f32_e32 v43, v43
	v_mfma_f32_32x32x16_bf16 v[188:203], v[164:167], v[56:59], v[188:203]
	v_exp_f32_e32 v44, v44
	v_exp_f32_e32 v45, v45
	v_mfma_f32_32x32x16_bf16 v[188:203], v[168:171], v[60:63], v[188:203]
	v_exp_f32_e32 v46, v46
	v_exp_f32_e32 v47, v47
	v_cvt_pk_bf16_f32 v64, v32, v33
	v_cvt_pk_bf16_f32 v65, v34, v35
	v_cvt_pk_bf16_f32 v66, v36, v37
	v_cvt_pk_bf16_f32 v67, v38, v39
	v_cvt_pk_bf16_f32 v68, v40, v41
	v_cvt_pk_bf16_f32 v69, v42, v43
	v_cvt_pk_bf16_f32 v70, v44, v45
	v_cvt_pk_bf16_f32 v71, v46, v47
	v_pk_add_f32 v[232:233], v[232:233], v[32:33]
	v_pk_add_f32 v[232:233], v[232:233], v[34:35]
	v_pk_add_f32 v[232:233], v[232:233], v[36:37]
	v_pk_add_f32 v[232:233], v[232:233], v[38:39]
	v_pk_add_f32 v[232:233], v[232:233], v[40:41]
	v_pk_add_f32 v[232:233], v[232:233], v[42:43]
	v_pk_add_f32 v[232:233], v[232:233], v[44:45]
	v_pk_add_f32 v[232:233], v[232:233], v[46:47]
	v_mov_b32_e32 v115, v229
	ds_read2_b32 v[32:33], v115 offset0:0 offset1:1
	ds_read2_b32 v[34:35], v115 offset0:2 offset1:3
	ds_read2_b32 v[36:37], v115 offset0:8 offset1:9
	ds_read2_b32 v[38:39], v115 offset0:10 offset1:11
	ds_read2_b32 v[40:41], v115 offset0:16 offset1:17
	ds_read2_b32 v[42:43], v115 offset0:18 offset1:19
	ds_read2_b32 v[44:45], v115 offset0:24 offset1:25
	ds_read2_b32 v[46:47], v115 offset0:26 offset1:27
	v_mfma_f32_32x32x16_bf16 v[0:15], v[64:67], v[72:75], v[0:15]
	v_mfma_f32_32x32x16_bf16 v[16:31], v[64:67], v[76:79], v[16:31]
	v_mfma_f32_32x32x16_bf16 v[0:15], v[68:71], v[220:223], v[0:15]
	v_mfma_f32_32x32x16_bf16 v[16:31], v[68:71], v[224:227], v[16:31]
	global_load_dwordx4 v[156:159], v239, s[86:87]
	global_load_dwordx4 v[160:163], v240, s[86:87]
	global_load_dwordx4 v[164:167], v241, s[86:87]
	global_load_dwordx4 v[168:171], v242, s[86:87]
	global_load_dwordx4 v[172:175], v101, s[86:87] offset:768
	global_load_dwordx4 v[176:179], v150, s[86:87] offset:768
	global_load_dwordx4 v[180:183], v101, s[86:87] offset:832
	global_load_dwordx4 v[184:187], v150, s[86:87] offset:832
	s_add_u32 s86, s86, 0xc0000
	s_addc_u32 s87, s87, 0
	ds_read_b64_tr_b16 v[72:73], v231
	ds_read_b64_tr_b16 v[74:75], v231 offset:512
	ds_read_b64_tr_b16 v[76:77], v231 offset:2048
	ds_read_b64_tr_b16 v[78:79], v231 offset:2560
	ds_read_b64_tr_b16 v[220:221], v231 offset:1024
	ds_read_b64_tr_b16 v[222:223], v231 offset:1536
	ds_read_b64_tr_b16 v[224:225], v231 offset:3072
	ds_read_b64_tr_b16 v[226:227], v231 offset:3584
	v_exp_f32_e32 v188, v188
	v_exp_f32_e32 v189, v189
	v_exp_f32_e32 v190, v190
	v_exp_f32_e32 v191, v191
	s_waitcnt vmcnt(12)
	ds_write_b128 v247, v[116:119]
	ds_write_b128 v247, v[120:123] offset:1024
	ds_write_b128 v247, v[124:127] offset:2048
	ds_write_b128 v247, v[128:131] offset:3072
	ds_read_b128 v[116:119], v248
	ds_read_b128 v[120:123], v249
	ds_read_b128 v[124:127], v250
	ds_read_b128 v[128:131], v251
	s_waitcnt vmcnt(8)
	ds_write_b128 v112, v[132:135]
	ds_write_b128 v112, v[136:139] offset:1024
	ds_write_b128 v112, v[140:143] offset:2048
	ds_write_b128 v112, v[144:147] offset:3072
	v_exp_f32_e32 v192, v192
	v_exp_f32_e32 v193, v193
	v_exp_f32_e32 v194, v194
	v_exp_f32_e32 v195, v195
	s_waitcnt lgkmcnt(4)
	v_mfma_f32_32x32x16_bf16 v[32:47], v[116:119], v[48:51], v[32:47]
	v_exp_f32_e32 v196, v196
	v_exp_f32_e32 v197, v197
	v_mfma_f32_32x32x16_bf16 v[32:47], v[120:123], v[52:55], v[32:47]
	v_exp_f32_e32 v198, v198
	v_exp_f32_e32 v199, v199
	v_mfma_f32_32x32x16_bf16 v[32:47], v[124:127], v[56:59], v[32:47]
	v_exp_f32_e32 v200, v200
	v_exp_f32_e32 v201, v201
	v_mfma_f32_32x32x16_bf16 v[32:47], v[128:131], v[60:63], v[32:47]
	v_exp_f32_e32 v202, v202
	v_exp_f32_e32 v203, v203
	v_cvt_pk_bf16_f32 v64, v188, v189
	v_cvt_pk_bf16_f32 v65, v190, v191
	v_cvt_pk_bf16_f32 v66, v192, v193
	v_cvt_pk_bf16_f32 v67, v194, v195
	v_cvt_pk_bf16_f32 v68, v196, v197
	v_cvt_pk_bf16_f32 v69, v198, v199
	v_cvt_pk_bf16_f32 v70, v200, v201
	v_cvt_pk_bf16_f32 v71, v202, v203
	v_pk_add_f32 v[232:233], v[232:233], v[188:189]
	v_pk_add_f32 v[232:233], v[232:233], v[190:191]
	v_pk_add_f32 v[232:233], v[232:233], v[192:193]
	v_pk_add_f32 v[232:233], v[232:233], v[194:195]
	v_pk_add_f32 v[232:233], v[232:233], v[196:197]
	v_pk_add_f32 v[232:233], v[232:233], v[198:199]
	v_pk_add_f32 v[232:233], v[232:233], v[200:201]
	v_pk_add_f32 v[232:233], v[232:233], v[202:203]
	ds_read2_b32 v[188:189], v115 offset0:32 offset1:33
	ds_read2_b32 v[190:191], v115 offset0:34 offset1:35
	ds_read2_b32 v[192:193], v115 offset0:40 offset1:41
	ds_read2_b32 v[194:195], v115 offset0:42 offset1:43
	ds_read2_b32 v[196:197], v115 offset0:48 offset1:49
	ds_read2_b32 v[198:199], v115 offset0:50 offset1:51
	ds_read2_b32 v[200:201], v115 offset0:56 offset1:57
	ds_read2_b32 v[202:203], v115 offset0:58 offset1:59
	v_mfma_f32_32x32x16_bf16 v[0:15], v[64:67], v[72:75], v[0:15]
	v_mfma_f32_32x32x16_bf16 v[16:31], v[64:67], v[76:79], v[16:31]
	v_mfma_f32_32x32x16_bf16 v[0:15], v[68:71], v[220:223], v[0:15]
	v_mfma_f32_32x32x16_bf16 v[16:31], v[68:71], v[224:227], v[16:31]
	global_load_dwordx4 v[116:119], v239, s[86:87]
	global_load_dwordx4 v[120:123], v240, s[86:87]
	global_load_dwordx4 v[124:127], v241, s[86:87]
	global_load_dwordx4 v[128:131], v242, s[86:87]
	global_load_dwordx4 v[132:135], v101, s[86:87] offset:768
	global_load_dwordx4 v[136:139], v150, s[86:87] offset:768
	global_load_dwordx4 v[140:143], v101, s[86:87] offset:832
	global_load_dwordx4 v[144:147], v150, s[86:87] offset:832
	s_add_u32 s86, s86, 0xc0000
	s_addc_u32 s87, s87, 0
	ds_read_b64_tr_b16 v[72:73], v231
	ds_read_b64_tr_b16 v[74:75], v231 offset:512
	ds_read_b64_tr_b16 v[76:77], v231 offset:2048
	ds_read_b64_tr_b16 v[78:79], v231 offset:2560
	ds_read_b64_tr_b16 v[220:221], v231 offset:1024
	ds_read_b64_tr_b16 v[222:223], v231 offset:1536
	ds_read_b64_tr_b16 v[224:225], v231 offset:3072
	ds_read_b64_tr_b16 v[226:227], v231 offset:3584
	v_exp_f32_e32 v32, v32
	v_exp_f32_e32 v33, v33
	v_exp_f32_e32 v34, v34
	v_exp_f32_e32 v35, v35
	s_waitcnt vmcnt(12)
	ds_write_b128 v247, v[156:159]
	ds_write_b128 v247, v[160:163] offset:1024
	ds_write_b128 v247, v[164:167] offset:2048
	ds_write_b128 v247, v[168:171] offset:3072
	ds_read_b128 v[156:159], v248
	ds_read_b128 v[160:163], v249
	ds_read_b128 v[164:167], v250
	ds_read_b128 v[168:171], v251
	s_waitcnt vmcnt(8)
	ds_write_b128 v112, v[172:175]
	ds_write_b128 v112, v[176:179] offset:1024
	ds_write_b128 v112, v[180:183] offset:2048
	ds_write_b128 v112, v[184:187] offset:3072
	v_exp_f32_e32 v36, v36
	v_exp_f32_e32 v37, v37
	v_exp_f32_e32 v38, v38
	v_exp_f32_e32 v39, v39
	s_waitcnt lgkmcnt(4)
	v_mfma_f32_32x32x16_bf16 v[188:203], v[156:159], v[48:51], v[188:203]
	v_exp_f32_e32 v40, v40
	v_exp_f32_e32 v41, v41
	v_mfma_f32_32x32x16_bf16 v[188:203], v[160:163], v[52:55], v[188:203]
	v_exp_f32_e32 v42, v42
	v_exp_f32_e32 v43, v43
	v_mfma_f32_32x32x16_bf16 v[188:203], v[164:167], v[56:59], v[188:203]
	v_exp_f32_e32 v44, v44
	v_exp_f32_e32 v45, v45
	v_mfma_f32_32x32x16_bf16 v[188:203], v[168:171], v[60:63], v[188:203]
	v_exp_f32_e32 v46, v46
	v_exp_f32_e32 v47, v47
	v_cvt_pk_bf16_f32 v64, v32, v33
	v_cvt_pk_bf16_f32 v65, v34, v35
	v_cvt_pk_bf16_f32 v66, v36, v37
	v_cvt_pk_bf16_f32 v67, v38, v39
	v_cvt_pk_bf16_f32 v68, v40, v41
	v_cvt_pk_bf16_f32 v69, v42, v43
	v_cvt_pk_bf16_f32 v70, v44, v45
	v_cvt_pk_bf16_f32 v71, v46, v47
	v_pk_add_f32 v[232:233], v[232:233], v[32:33]
	v_pk_add_f32 v[232:233], v[232:233], v[34:35]
	v_pk_add_f32 v[232:233], v[232:233], v[36:37]
	v_pk_add_f32 v[232:233], v[232:233], v[38:39]
	v_pk_add_f32 v[232:233], v[232:233], v[40:41]
	v_pk_add_f32 v[232:233], v[232:233], v[42:43]
	v_pk_add_f32 v[232:233], v[232:233], v[44:45]
	v_pk_add_f32 v[232:233], v[232:233], v[46:47]
	ds_read2_b32 v[32:33], v115 offset0:64 offset1:65
	ds_read2_b32 v[34:35], v115 offset0:66 offset1:67
	ds_read2_b32 v[36:37], v115 offset0:72 offset1:73
	ds_read2_b32 v[38:39], v115 offset0:74 offset1:75
	ds_read2_b32 v[40:41], v115 offset0:80 offset1:81
	ds_read2_b32 v[42:43], v115 offset0:82 offset1:83
	ds_read2_b32 v[44:45], v115 offset0:88 offset1:89
	ds_read2_b32 v[46:47], v115 offset0:90 offset1:91
	v_mfma_f32_32x32x16_bf16 v[0:15], v[64:67], v[72:75], v[0:15]
	v_mfma_f32_32x32x16_bf16 v[16:31], v[64:67], v[76:79], v[16:31]
	v_mfma_f32_32x32x16_bf16 v[0:15], v[68:71], v[220:223], v[0:15]
	v_mfma_f32_32x32x16_bf16 v[16:31], v[68:71], v[224:227], v[16:31]
	global_load_dwordx4 v[156:159], v239, s[86:87]
	global_load_dwordx4 v[160:163], v240, s[86:87]
	global_load_dwordx4 v[164:167], v241, s[86:87]
	global_load_dwordx4 v[168:171], v242, s[86:87]
	global_load_dwordx4 v[172:175], v101, s[86:87] offset:768
	global_load_dwordx4 v[176:179], v150, s[86:87] offset:768
	global_load_dwordx4 v[180:183], v101, s[86:87] offset:832
	global_load_dwordx4 v[184:187], v150, s[86:87] offset:832
	s_add_u32 s86, s86, 0xc0000
	s_addc_u32 s87, s87, 0
	ds_read_b64_tr_b16 v[72:73], v231
	ds_read_b64_tr_b16 v[74:75], v231 offset:512
	ds_read_b64_tr_b16 v[76:77], v231 offset:2048
	ds_read_b64_tr_b16 v[78:79], v231 offset:2560
	ds_read_b64_tr_b16 v[220:221], v231 offset:1024
	ds_read_b64_tr_b16 v[222:223], v231 offset:1536
	ds_read_b64_tr_b16 v[224:225], v231 offset:3072
	ds_read_b64_tr_b16 v[226:227], v231 offset:3584
	v_exp_f32_e32 v188, v188
	v_exp_f32_e32 v189, v189
	v_exp_f32_e32 v190, v190
	v_exp_f32_e32 v191, v191
	s_waitcnt vmcnt(12)
	ds_write_b128 v247, v[116:119]
	ds_write_b128 v247, v[120:123] offset:1024
	ds_write_b128 v247, v[124:127] offset:2048
	ds_write_b128 v247, v[128:131] offset:3072
	ds_read_b128 v[116:119], v248
	ds_read_b128 v[120:123], v249
	ds_read_b128 v[124:127], v250
	ds_read_b128 v[128:131], v251
	s_waitcnt vmcnt(8)
	ds_write_b128 v112, v[132:135]
	ds_write_b128 v112, v[136:139] offset:1024
	ds_write_b128 v112, v[140:143] offset:2048
	ds_write_b128 v112, v[144:147] offset:3072
	v_exp_f32_e32 v192, v192
	v_exp_f32_e32 v193, v193
	v_exp_f32_e32 v194, v194
	v_exp_f32_e32 v195, v195
	s_waitcnt lgkmcnt(4)
	v_mfma_f32_32x32x16_bf16 v[32:47], v[116:119], v[48:51], v[32:47]
	v_exp_f32_e32 v196, v196
	v_exp_f32_e32 v197, v197
	v_mfma_f32_32x32x16_bf16 v[32:47], v[120:123], v[52:55], v[32:47]
	v_exp_f32_e32 v198, v198
	v_exp_f32_e32 v199, v199
	v_mfma_f32_32x32x16_bf16 v[32:47], v[124:127], v[56:59], v[32:47]
	v_exp_f32_e32 v200, v200
	v_exp_f32_e32 v201, v201
	v_mfma_f32_32x32x16_bf16 v[32:47], v[128:131], v[60:63], v[32:47]
	v_exp_f32_e32 v202, v202
	v_exp_f32_e32 v203, v203
	v_cvt_pk_bf16_f32 v64, v188, v189
	v_cvt_pk_bf16_f32 v65, v190, v191
	v_cvt_pk_bf16_f32 v66, v192, v193
	v_cvt_pk_bf16_f32 v67, v194, v195
	v_cvt_pk_bf16_f32 v68, v196, v197
	v_cvt_pk_bf16_f32 v69, v198, v199
	v_cvt_pk_bf16_f32 v70, v200, v201
	v_cvt_pk_bf16_f32 v71, v202, v203
	v_pk_add_f32 v[232:233], v[232:233], v[188:189]
	v_pk_add_f32 v[232:233], v[232:233], v[190:191]
	v_pk_add_f32 v[232:233], v[232:233], v[192:193]
	v_pk_add_f32 v[232:233], v[232:233], v[194:195]
	v_pk_add_f32 v[232:233], v[232:233], v[196:197]
	v_pk_add_f32 v[232:233], v[232:233], v[198:199]
	v_pk_add_f32 v[232:233], v[232:233], v[200:201]
	v_pk_add_f32 v[232:233], v[232:233], v[202:203]
	ds_read2_b32 v[188:189], v115 offset0:96 offset1:97
	ds_read2_b32 v[190:191], v115 offset0:98 offset1:99
	ds_read2_b32 v[192:193], v115 offset0:104 offset1:105
	ds_read2_b32 v[194:195], v115 offset0:106 offset1:107
	ds_read2_b32 v[196:197], v115 offset0:112 offset1:113
	ds_read2_b32 v[198:199], v115 offset0:114 offset1:115
	ds_read2_b32 v[200:201], v115 offset0:120 offset1:121
	ds_read2_b32 v[202:203], v115 offset0:122 offset1:123
	v_mfma_f32_32x32x16_bf16 v[0:15], v[64:67], v[72:75], v[0:15]
	v_mfma_f32_32x32x16_bf16 v[16:31], v[64:67], v[76:79], v[16:31]
	v_mfma_f32_32x32x16_bf16 v[0:15], v[68:71], v[220:223], v[0:15]
	v_mfma_f32_32x32x16_bf16 v[16:31], v[68:71], v[224:227], v[16:31]
	global_load_dwordx4 v[116:119], v239, s[86:87]
	global_load_dwordx4 v[120:123], v240, s[86:87]
	global_load_dwordx4 v[124:127], v241, s[86:87]
	global_load_dwordx4 v[128:131], v242, s[86:87]
	global_load_dwordx4 v[132:135], v101, s[86:87] offset:768
	global_load_dwordx4 v[136:139], v150, s[86:87] offset:768
	global_load_dwordx4 v[140:143], v101, s[86:87] offset:832
	global_load_dwordx4 v[144:147], v150, s[86:87] offset:832
	s_add_u32 s86, s86, 0xc0000
	s_addc_u32 s87, s87, 0
	ds_read_b64_tr_b16 v[72:73], v231
	ds_read_b64_tr_b16 v[74:75], v231 offset:512
	ds_read_b64_tr_b16 v[76:77], v231 offset:2048
	ds_read_b64_tr_b16 v[78:79], v231 offset:2560
	ds_read_b64_tr_b16 v[220:221], v231 offset:1024
	ds_read_b64_tr_b16 v[222:223], v231 offset:1536
	ds_read_b64_tr_b16 v[224:225], v231 offset:3072
	ds_read_b64_tr_b16 v[226:227], v231 offset:3584
	v_exp_f32_e32 v32, v32
	v_exp_f32_e32 v33, v33
	v_exp_f32_e32 v34, v34
	v_exp_f32_e32 v35, v35
	s_waitcnt vmcnt(12)
	ds_write_b128 v247, v[156:159]
	ds_write_b128 v247, v[160:163] offset:1024
	ds_write_b128 v247, v[164:167] offset:2048
	ds_write_b128 v247, v[168:171] offset:3072
	ds_read_b128 v[156:159], v248
	ds_read_b128 v[160:163], v249
	ds_read_b128 v[164:167], v250
	ds_read_b128 v[168:171], v251
	s_waitcnt vmcnt(8)
	ds_write_b128 v112, v[172:175]
	ds_write_b128 v112, v[176:179] offset:1024
	ds_write_b128 v112, v[180:183] offset:2048
	ds_write_b128 v112, v[184:187] offset:3072
	v_exp_f32_e32 v36, v36
	v_exp_f32_e32 v37, v37
	v_exp_f32_e32 v38, v38
	v_exp_f32_e32 v39, v39
	s_waitcnt lgkmcnt(4)
	v_mfma_f32_32x32x16_bf16 v[188:203], v[156:159], v[48:51], v[188:203]
	v_exp_f32_e32 v40, v40
	v_exp_f32_e32 v41, v41
	v_mfma_f32_32x32x16_bf16 v[188:203], v[160:163], v[52:55], v[188:203]
	v_exp_f32_e32 v42, v42
	v_exp_f32_e32 v43, v43
	v_mfma_f32_32x32x16_bf16 v[188:203], v[164:167], v[56:59], v[188:203]
	v_exp_f32_e32 v44, v44
	v_exp_f32_e32 v45, v45
	v_mfma_f32_32x32x16_bf16 v[188:203], v[168:171], v[60:63], v[188:203]
	v_exp_f32_e32 v46, v46
	v_exp_f32_e32 v47, v47
	v_cvt_pk_bf16_f32 v64, v32, v33
	v_cvt_pk_bf16_f32 v65, v34, v35
	v_cvt_pk_bf16_f32 v66, v36, v37
	v_cvt_pk_bf16_f32 v67, v38, v39
	v_cvt_pk_bf16_f32 v68, v40, v41
	v_cvt_pk_bf16_f32 v69, v42, v43
	v_cvt_pk_bf16_f32 v70, v44, v45
	v_cvt_pk_bf16_f32 v71, v46, v47
	v_pk_add_f32 v[232:233], v[232:233], v[32:33]
	v_pk_add_f32 v[232:233], v[232:233], v[34:35]
	v_pk_add_f32 v[232:233], v[232:233], v[36:37]
	v_pk_add_f32 v[232:233], v[232:233], v[38:39]
	v_pk_add_f32 v[232:233], v[232:233], v[40:41]
	v_pk_add_f32 v[232:233], v[232:233], v[42:43]
	v_pk_add_f32 v[232:233], v[232:233], v[44:45]
	v_pk_add_f32 v[232:233], v[232:233], v[46:47]
	ds_read2_b32 v[32:33], v115 offset0:128 offset1:129
	ds_read2_b32 v[34:35], v115 offset0:130 offset1:131
	ds_read2_b32 v[36:37], v115 offset0:136 offset1:137
	ds_read2_b32 v[38:39], v115 offset0:138 offset1:139
	ds_read2_b32 v[40:41], v115 offset0:144 offset1:145
	ds_read2_b32 v[42:43], v115 offset0:146 offset1:147
	ds_read2_b32 v[44:45], v115 offset0:152 offset1:153
	ds_read2_b32 v[46:47], v115 offset0:154 offset1:155
	v_mfma_f32_32x32x16_bf16 v[0:15], v[64:67], v[72:75], v[0:15]
	v_mfma_f32_32x32x16_bf16 v[16:31], v[64:67], v[76:79], v[16:31]
	v_mfma_f32_32x32x16_bf16 v[0:15], v[68:71], v[220:223], v[0:15]
	v_mfma_f32_32x32x16_bf16 v[16:31], v[68:71], v[224:227], v[16:31]
	global_load_dwordx4 v[156:159], v239, s[86:87]
	global_load_dwordx4 v[160:163], v240, s[86:87]
	global_load_dwordx4 v[164:167], v241, s[86:87]
	global_load_dwordx4 v[168:171], v242, s[86:87]
	global_load_dwordx4 v[172:175], v101, s[86:87] offset:768
	global_load_dwordx4 v[176:179], v150, s[86:87] offset:768
	global_load_dwordx4 v[180:183], v101, s[86:87] offset:832
	global_load_dwordx4 v[184:187], v150, s[86:87] offset:832
	s_add_u32 s86, s86, 0xc0000
	s_addc_u32 s87, s87, 0
	ds_read_b64_tr_b16 v[72:73], v231
	ds_read_b64_tr_b16 v[74:75], v231 offset:512
	ds_read_b64_tr_b16 v[76:77], v231 offset:2048
	ds_read_b64_tr_b16 v[78:79], v231 offset:2560
	ds_read_b64_tr_b16 v[220:221], v231 offset:1024
	ds_read_b64_tr_b16 v[222:223], v231 offset:1536
	ds_read_b64_tr_b16 v[224:225], v231 offset:3072
	ds_read_b64_tr_b16 v[226:227], v231 offset:3584
	v_exp_f32_e32 v188, v188
	v_exp_f32_e32 v189, v189
	v_exp_f32_e32 v190, v190
	v_exp_f32_e32 v191, v191
	s_waitcnt vmcnt(12)
	ds_write_b128 v247, v[116:119]
	ds_write_b128 v247, v[120:123] offset:1024
	ds_write_b128 v247, v[124:127] offset:2048
	ds_write_b128 v247, v[128:131] offset:3072
	ds_read_b128 v[116:119], v248
	ds_read_b128 v[120:123], v249
	ds_read_b128 v[124:127], v250
	ds_read_b128 v[128:131], v251
	s_waitcnt vmcnt(8)
	ds_write_b128 v112, v[132:135]
	ds_write_b128 v112, v[136:139] offset:1024
	ds_write_b128 v112, v[140:143] offset:2048
	ds_write_b128 v112, v[144:147] offset:3072
	v_exp_f32_e32 v192, v192
	v_exp_f32_e32 v193, v193
	v_exp_f32_e32 v194, v194
	v_exp_f32_e32 v195, v195
	s_waitcnt lgkmcnt(4)
	v_mfma_f32_32x32x16_bf16 v[32:47], v[116:119], v[48:51], v[32:47]
	v_exp_f32_e32 v196, v196
	v_exp_f32_e32 v197, v197
	v_mfma_f32_32x32x16_bf16 v[32:47], v[120:123], v[52:55], v[32:47]
	v_exp_f32_e32 v198, v198
	v_exp_f32_e32 v199, v199
	v_mfma_f32_32x32x16_bf16 v[32:47], v[124:127], v[56:59], v[32:47]
	v_exp_f32_e32 v200, v200
	v_exp_f32_e32 v201, v201
	v_mfma_f32_32x32x16_bf16 v[32:47], v[128:131], v[60:63], v[32:47]
	v_exp_f32_e32 v202, v202
	v_exp_f32_e32 v203, v203
	v_cvt_pk_bf16_f32 v64, v188, v189
	v_cvt_pk_bf16_f32 v65, v190, v191
	v_cvt_pk_bf16_f32 v66, v192, v193
	v_cvt_pk_bf16_f32 v67, v194, v195
	v_cvt_pk_bf16_f32 v68, v196, v197
	v_cvt_pk_bf16_f32 v69, v198, v199
	v_cvt_pk_bf16_f32 v70, v200, v201
	v_cvt_pk_bf16_f32 v71, v202, v203
	v_pk_add_f32 v[232:233], v[232:233], v[188:189]
	v_pk_add_f32 v[232:233], v[232:233], v[190:191]
	v_pk_add_f32 v[232:233], v[232:233], v[192:193]
	v_pk_add_f32 v[232:233], v[232:233], v[194:195]
	v_pk_add_f32 v[232:233], v[232:233], v[196:197]
	v_pk_add_f32 v[232:233], v[232:233], v[198:199]
	v_pk_add_f32 v[232:233], v[232:233], v[200:201]
	v_pk_add_f32 v[232:233], v[232:233], v[202:203]
	ds_read2_b32 v[188:189], v115 offset0:160 offset1:161
	ds_read2_b32 v[190:191], v115 offset0:162 offset1:163
	ds_read2_b32 v[192:193], v115 offset0:168 offset1:169
	ds_read2_b32 v[194:195], v115 offset0:170 offset1:171
	ds_read2_b32 v[196:197], v115 offset0:176 offset1:177
	ds_read2_b32 v[198:199], v115 offset0:178 offset1:179
	ds_read2_b32 v[200:201], v115 offset0:184 offset1:185
	ds_read2_b32 v[202:203], v115 offset0:186 offset1:187
	v_mfma_f32_32x32x16_bf16 v[0:15], v[64:67], v[72:75], v[0:15]
	v_mfma_f32_32x32x16_bf16 v[16:31], v[64:67], v[76:79], v[16:31]
	v_mfma_f32_32x32x16_bf16 v[0:15], v[68:71], v[220:223], v[0:15]
	v_mfma_f32_32x32x16_bf16 v[16:31], v[68:71], v[224:227], v[16:31]
	global_load_dwordx4 v[116:119], v239, s[86:87]
	global_load_dwordx4 v[120:123], v240, s[86:87]
	global_load_dwordx4 v[124:127], v241, s[86:87]
	global_load_dwordx4 v[128:131], v242, s[86:87]
	global_load_dwordx4 v[132:135], v101, s[86:87] offset:768
	global_load_dwordx4 v[136:139], v150, s[86:87] offset:768
	global_load_dwordx4 v[140:143], v101, s[86:87] offset:832
	global_load_dwordx4 v[144:147], v150, s[86:87] offset:832
	s_add_u32 s86, s86, 0xc0000
	s_addc_u32 s87, s87, 0
	ds_read_b64_tr_b16 v[72:73], v231
	ds_read_b64_tr_b16 v[74:75], v231 offset:512
	ds_read_b64_tr_b16 v[76:77], v231 offset:2048
	ds_read_b64_tr_b16 v[78:79], v231 offset:2560
	ds_read_b64_tr_b16 v[220:221], v231 offset:1024
	ds_read_b64_tr_b16 v[222:223], v231 offset:1536
	ds_read_b64_tr_b16 v[224:225], v231 offset:3072
	ds_read_b64_tr_b16 v[226:227], v231 offset:3584
	v_exp_f32_e32 v32, v32
	v_exp_f32_e32 v33, v33
	v_exp_f32_e32 v34, v34
	v_exp_f32_e32 v35, v35
	s_waitcnt vmcnt(12)
	ds_write_b128 v247, v[156:159]
	ds_write_b128 v247, v[160:163] offset:1024
	ds_write_b128 v247, v[164:167] offset:2048
	ds_write_b128 v247, v[168:171] offset:3072
	ds_read_b128 v[156:159], v248
	ds_read_b128 v[160:163], v249
	ds_read_b128 v[164:167], v250
	ds_read_b128 v[168:171], v251
	s_waitcnt vmcnt(8)
	ds_write_b128 v112, v[172:175]
	ds_write_b128 v112, v[176:179] offset:1024
	ds_write_b128 v112, v[180:183] offset:2048
	ds_write_b128 v112, v[184:187] offset:3072
	v_exp_f32_e32 v36, v36
	v_exp_f32_e32 v37, v37
	v_exp_f32_e32 v38, v38
	v_exp_f32_e32 v39, v39
	s_waitcnt lgkmcnt(4)
	v_mfma_f32_32x32x16_bf16 v[188:203], v[156:159], v[48:51], v[188:203]
	v_exp_f32_e32 v40, v40
	v_exp_f32_e32 v41, v41
	v_mfma_f32_32x32x16_bf16 v[188:203], v[160:163], v[52:55], v[188:203]
	v_exp_f32_e32 v42, v42
	v_exp_f32_e32 v43, v43
	v_mfma_f32_32x32x16_bf16 v[188:203], v[164:167], v[56:59], v[188:203]
	v_exp_f32_e32 v44, v44
	v_exp_f32_e32 v45, v45
	v_mfma_f32_32x32x16_bf16 v[188:203], v[168:171], v[60:63], v[188:203]
	v_exp_f32_e32 v46, v46
	v_exp_f32_e32 v47, v47
	v_cvt_pk_bf16_f32 v64, v32, v33
	v_cvt_pk_bf16_f32 v65, v34, v35
	v_cvt_pk_bf16_f32 v66, v36, v37
	v_cvt_pk_bf16_f32 v67, v38, v39
	v_cvt_pk_bf16_f32 v68, v40, v41
	v_cvt_pk_bf16_f32 v69, v42, v43
	v_cvt_pk_bf16_f32 v70, v44, v45
	v_cvt_pk_bf16_f32 v71, v46, v47
	v_pk_add_f32 v[232:233], v[232:233], v[32:33]
	v_pk_add_f32 v[232:233], v[232:233], v[34:35]
	v_pk_add_f32 v[232:233], v[232:233], v[36:37]
	v_pk_add_f32 v[232:233], v[232:233], v[38:39]
	v_pk_add_f32 v[232:233], v[232:233], v[40:41]
	v_pk_add_f32 v[232:233], v[232:233], v[42:43]
	v_pk_add_f32 v[232:233], v[232:233], v[44:45]
	v_pk_add_f32 v[232:233], v[232:233], v[46:47]
	ds_read2_b32 v[32:33], v115 offset0:192 offset1:193
	ds_read2_b32 v[34:35], v115 offset0:194 offset1:195
	ds_read2_b32 v[36:37], v115 offset0:200 offset1:201
	ds_read2_b32 v[38:39], v115 offset0:202 offset1:203
	ds_read2_b32 v[40:41], v115 offset0:208 offset1:209
	ds_read2_b32 v[42:43], v115 offset0:210 offset1:211
	ds_read2_b32 v[44:45], v115 offset0:216 offset1:217
	ds_read2_b32 v[46:47], v115 offset0:218 offset1:219
	v_mfma_f32_32x32x16_bf16 v[0:15], v[64:67], v[72:75], v[0:15]
	v_mfma_f32_32x32x16_bf16 v[16:31], v[64:67], v[76:79], v[16:31]
	v_mfma_f32_32x32x16_bf16 v[0:15], v[68:71], v[220:223], v[0:15]
	v_mfma_f32_32x32x16_bf16 v[16:31], v[68:71], v[224:227], v[16:31]
	global_load_dwordx4 v[156:159], v239, s[86:87]
	global_load_dwordx4 v[160:163], v240, s[86:87]
	global_load_dwordx4 v[164:167], v241, s[86:87]
	global_load_dwordx4 v[168:171], v242, s[86:87]
	global_load_dwordx4 v[172:175], v101, s[86:87] offset:768
	global_load_dwordx4 v[176:179], v150, s[86:87] offset:768
	global_load_dwordx4 v[180:183], v101, s[86:87] offset:832
	global_load_dwordx4 v[184:187], v150, s[86:87] offset:832
	ds_read_b64_tr_b16 v[72:73], v231
	ds_read_b64_tr_b16 v[74:75], v231 offset:512
	ds_read_b64_tr_b16 v[76:77], v231 offset:2048
	ds_read_b64_tr_b16 v[78:79], v231 offset:2560
	ds_read_b64_tr_b16 v[220:221], v231 offset:1024
	ds_read_b64_tr_b16 v[222:223], v231 offset:1536
	ds_read_b64_tr_b16 v[224:225], v231 offset:3072
	ds_read_b64_tr_b16 v[226:227], v231 offset:3584
	v_exp_f32_e32 v188, v188
	v_exp_f32_e32 v189, v189
	v_exp_f32_e32 v190, v190
	v_exp_f32_e32 v191, v191
	s_waitcnt vmcnt(12)
	ds_write_b128 v247, v[116:119]
	ds_write_b128 v247, v[120:123] offset:1024
	ds_write_b128 v247, v[124:127] offset:2048
	ds_write_b128 v247, v[128:131] offset:3072
	ds_read_b128 v[116:119], v248
	ds_read_b128 v[120:123], v249
	ds_read_b128 v[124:127], v250
	ds_read_b128 v[128:131], v251
	s_waitcnt vmcnt(8)
	ds_write_b128 v112, v[132:135]
	ds_write_b128 v112, v[136:139] offset:1024
	ds_write_b128 v112, v[140:143] offset:2048
	ds_write_b128 v112, v[144:147] offset:3072
	v_exp_f32_e32 v192, v192
	v_exp_f32_e32 v193, v193
	v_exp_f32_e32 v194, v194
	v_exp_f32_e32 v195, v195
	s_waitcnt lgkmcnt(4)
	v_mfma_f32_32x32x16_bf16 v[32:47], v[116:119], v[48:51], v[32:47]
	v_exp_f32_e32 v196, v196
	v_exp_f32_e32 v197, v197
	v_mfma_f32_32x32x16_bf16 v[32:47], v[120:123], v[52:55], v[32:47]
	v_exp_f32_e32 v198, v198
	v_exp_f32_e32 v199, v199
	v_mfma_f32_32x32x16_bf16 v[32:47], v[124:127], v[56:59], v[32:47]
	v_exp_f32_e32 v200, v200
	v_exp_f32_e32 v201, v201
	v_mfma_f32_32x32x16_bf16 v[32:47], v[128:131], v[60:63], v[32:47]
	v_exp_f32_e32 v202, v202
	v_exp_f32_e32 v203, v203
	v_cvt_pk_bf16_f32 v64, v188, v189
	v_cvt_pk_bf16_f32 v65, v190, v191
	v_cvt_pk_bf16_f32 v66, v192, v193
	v_cvt_pk_bf16_f32 v67, v194, v195
	v_cvt_pk_bf16_f32 v68, v196, v197
	v_cvt_pk_bf16_f32 v69, v198, v199
	v_cvt_pk_bf16_f32 v70, v200, v201
	v_cvt_pk_bf16_f32 v71, v202, v203
	v_pk_add_f32 v[232:233], v[232:233], v[188:189]
	v_pk_add_f32 v[232:233], v[232:233], v[190:191]
	v_pk_add_f32 v[232:233], v[232:233], v[192:193]
	v_pk_add_f32 v[232:233], v[232:233], v[194:195]
	v_pk_add_f32 v[232:233], v[232:233], v[196:197]
	v_pk_add_f32 v[232:233], v[232:233], v[198:199]
	v_pk_add_f32 v[232:233], v[232:233], v[200:201]
	v_pk_add_f32 v[232:233], v[232:233], v[202:203]
	ds_read2_b32 v[188:189], v115 offset0:224 offset1:225
	ds_read2_b32 v[190:191], v115 offset0:226 offset1:227
	ds_read2_b32 v[192:193], v115 offset0:232 offset1:233
	ds_read2_b32 v[194:195], v115 offset0:234 offset1:235
	ds_read2_b32 v[196:197], v115 offset0:240 offset1:241
	ds_read2_b32 v[198:199], v115 offset0:242 offset1:243
	ds_read2_b32 v[200:201], v115 offset0:248 offset1:249
	ds_read2_b32 v[202:203], v115 offset0:250 offset1:251
	v_mfma_f32_32x32x16_bf16 v[0:15], v[64:67], v[72:75], v[0:15]
	v_mfma_f32_32x32x16_bf16 v[16:31], v[64:67], v[76:79], v[16:31]
	v_mfma_f32_32x32x16_bf16 v[0:15], v[68:71], v[220:223], v[0:15]
	v_mfma_f32_32x32x16_bf16 v[16:31], v[68:71], v[224:227], v[16:31]
	global_load_dwordx4 v[116:119], v243, s[88:89]
	global_load_dwordx4 v[120:123], v244, s[88:89]
	global_load_dwordx4 v[124:127], v245, s[88:89]
	global_load_dwordx4 v[128:131], v246, s[88:89]
	global_load_dwordx4 v[132:135], v148, s[88:89] offset:768
	global_load_dwordx4 v[136:139], v151, s[88:89] offset:768
	global_load_dwordx4 v[140:143], v148, s[88:89] offset:832
	global_load_dwordx4 v[144:147], v151, s[88:89] offset:832
	s_add_u32 s88, s88, 0x300000
	s_addc_u32 s89, s89, 0
	ds_read_b64_tr_b16 v[72:73], v231
	ds_read_b64_tr_b16 v[74:75], v231 offset:512
	ds_read_b64_tr_b16 v[76:77], v231 offset:2048
	ds_read_b64_tr_b16 v[78:79], v231 offset:2560
	ds_read_b64_tr_b16 v[220:221], v231 offset:1024
	ds_read_b64_tr_b16 v[222:223], v231 offset:1536
	ds_read_b64_tr_b16 v[224:225], v231 offset:3072
	ds_read_b64_tr_b16 v[226:227], v231 offset:3584
	v_exp_f32_e32 v32, v32
	v_exp_f32_e32 v33, v33
	v_exp_f32_e32 v34, v34
	v_exp_f32_e32 v35, v35
	s_waitcnt vmcnt(12)
	ds_write_b128 v247, v[156:159]
	ds_write_b128 v247, v[160:163] offset:1024
	ds_write_b128 v247, v[164:167] offset:2048
	ds_write_b128 v247, v[168:171] offset:3072
	ds_read_b128 v[156:159], v248
	ds_read_b128 v[160:163], v249
	ds_read_b128 v[164:167], v250
	ds_read_b128 v[168:171], v251
	s_waitcnt vmcnt(8)
	ds_write_b128 v112, v[172:175]
	ds_write_b128 v112, v[176:179] offset:1024
	ds_write_b128 v112, v[180:183] offset:2048
	ds_write_b128 v112, v[184:187] offset:3072
	v_exp_f32_e32 v36, v36
	v_exp_f32_e32 v37, v37
	v_exp_f32_e32 v38, v38
	v_exp_f32_e32 v39, v39
	s_waitcnt lgkmcnt(4)
	v_mfma_f32_32x32x16_bf16 v[188:203], v[156:159], v[48:51], v[188:203]
	v_exp_f32_e32 v40, v40
	v_exp_f32_e32 v41, v41
	v_mfma_f32_32x32x16_bf16 v[188:203], v[160:163], v[52:55], v[188:203]
	v_exp_f32_e32 v42, v42
	v_exp_f32_e32 v43, v43
	v_mfma_f32_32x32x16_bf16 v[188:203], v[164:167], v[56:59], v[188:203]
	v_exp_f32_e32 v44, v44
	v_exp_f32_e32 v45, v45
	v_mfma_f32_32x32x16_bf16 v[188:203], v[168:171], v[60:63], v[188:203]
	v_exp_f32_e32 v46, v46
	v_exp_f32_e32 v47, v47
	v_cvt_pk_bf16_f32 v64, v32, v33
	v_cvt_pk_bf16_f32 v65, v34, v35
	v_cvt_pk_bf16_f32 v66, v36, v37
	v_cvt_pk_bf16_f32 v67, v38, v39
	v_cvt_pk_bf16_f32 v68, v40, v41
	v_cvt_pk_bf16_f32 v69, v42, v43
	v_cvt_pk_bf16_f32 v70, v44, v45
	v_cvt_pk_bf16_f32 v71, v46, v47
	v_pk_add_f32 v[232:233], v[232:233], v[32:33]
	v_pk_add_f32 v[232:233], v[232:233], v[34:35]
	v_pk_add_f32 v[232:233], v[232:233], v[36:37]
	v_pk_add_f32 v[232:233], v[232:233], v[38:39]
	v_pk_add_f32 v[232:233], v[232:233], v[40:41]
	v_pk_add_f32 v[232:233], v[232:233], v[42:43]
	v_pk_add_f32 v[232:233], v[232:233], v[44:45]
	v_pk_add_f32 v[232:233], v[232:233], v[46:47]
	v_mov_b32_e32 v115, v230
	ds_read2_b32 v[32:33], v115 offset0:0 offset1:1
	ds_read2_b32 v[34:35], v115 offset0:2 offset1:3
	ds_read2_b32 v[36:37], v115 offset0:8 offset1:9
	ds_read2_b32 v[38:39], v115 offset0:10 offset1:11
	ds_read2_b32 v[40:41], v115 offset0:16 offset1:17
	ds_read2_b32 v[42:43], v115 offset0:18 offset1:19
	ds_read2_b32 v[44:45], v115 offset0:24 offset1:25
	ds_read2_b32 v[46:47], v115 offset0:26 offset1:27
	v_mfma_f32_32x32x16_bf16 v[0:15], v[64:67], v[72:75], v[0:15]
	v_mfma_f32_32x32x16_bf16 v[16:31], v[64:67], v[76:79], v[16:31]
	v_mfma_f32_32x32x16_bf16 v[0:15], v[68:71], v[220:223], v[0:15]
	v_mfma_f32_32x32x16_bf16 v[16:31], v[68:71], v[224:227], v[16:31]
	global_load_dwordx4 v[156:159], v243, s[88:89]
	global_load_dwordx4 v[160:163], v244, s[88:89]
	global_load_dwordx4 v[164:167], v245, s[88:89]
	global_load_dwordx4 v[168:171], v246, s[88:89]
	global_load_dwordx4 v[172:175], v148, s[88:89] offset:768
	global_load_dwordx4 v[176:179], v151, s[88:89] offset:768
	global_load_dwordx4 v[180:183], v148, s[88:89] offset:832
	global_load_dwordx4 v[184:187], v151, s[88:89] offset:832
	s_add_u32 s88, s88, 0x300000
	s_addc_u32 s89, s89, 0
	ds_read_b64_tr_b16 v[72:73], v231
	ds_read_b64_tr_b16 v[74:75], v231 offset:512
	ds_read_b64_tr_b16 v[76:77], v231 offset:2048
	ds_read_b64_tr_b16 v[78:79], v231 offset:2560
	ds_read_b64_tr_b16 v[220:221], v231 offset:1024
	ds_read_b64_tr_b16 v[222:223], v231 offset:1536
	ds_read_b64_tr_b16 v[224:225], v231 offset:3072
	ds_read_b64_tr_b16 v[226:227], v231 offset:3584
	v_exp_f32_e32 v188, v188
	v_exp_f32_e32 v189, v189
	v_exp_f32_e32 v190, v190
	v_exp_f32_e32 v191, v191
	s_waitcnt vmcnt(12)
	ds_write_b128 v247, v[116:119]
	ds_write_b128 v247, v[120:123] offset:1024
	ds_write_b128 v247, v[124:127] offset:2048
	ds_write_b128 v247, v[128:131] offset:3072
	ds_read_b128 v[116:119], v248
	ds_read_b128 v[120:123], v249
	ds_read_b128 v[124:127], v250
	ds_read_b128 v[128:131], v251
	s_waitcnt vmcnt(8)
	ds_write_b128 v112, v[132:135]
	ds_write_b128 v112, v[136:139] offset:1024
	ds_write_b128 v112, v[140:143] offset:2048
	ds_write_b128 v112, v[144:147] offset:3072
	v_exp_f32_e32 v192, v192
	v_exp_f32_e32 v193, v193
	v_exp_f32_e32 v194, v194
	v_exp_f32_e32 v195, v195
	s_waitcnt lgkmcnt(4)
	v_mfma_f32_32x32x16_bf16 v[32:47], v[116:119], v[48:51], v[32:47]
	v_exp_f32_e32 v196, v196
	v_exp_f32_e32 v197, v197
	v_mfma_f32_32x32x16_bf16 v[32:47], v[120:123], v[52:55], v[32:47]
	v_exp_f32_e32 v198, v198
	v_exp_f32_e32 v199, v199
	v_mfma_f32_32x32x16_bf16 v[32:47], v[124:127], v[56:59], v[32:47]
	v_exp_f32_e32 v200, v200
	v_exp_f32_e32 v201, v201
	v_mfma_f32_32x32x16_bf16 v[32:47], v[128:131], v[60:63], v[32:47]
	v_exp_f32_e32 v202, v202
	v_exp_f32_e32 v203, v203
	v_cvt_pk_bf16_f32 v64, v188, v189
	v_cvt_pk_bf16_f32 v65, v190, v191
	v_cvt_pk_bf16_f32 v66, v192, v193
	v_cvt_pk_bf16_f32 v67, v194, v195
	v_cvt_pk_bf16_f32 v68, v196, v197
	v_cvt_pk_bf16_f32 v69, v198, v199
	v_cvt_pk_bf16_f32 v70, v200, v201
	v_cvt_pk_bf16_f32 v71, v202, v203
	v_pk_add_f32 v[232:233], v[232:233], v[188:189]
	v_pk_add_f32 v[232:233], v[232:233], v[190:191]
	v_pk_add_f32 v[232:233], v[232:233], v[192:193]
	v_pk_add_f32 v[232:233], v[232:233], v[194:195]
	v_pk_add_f32 v[232:233], v[232:233], v[196:197]
	v_pk_add_f32 v[232:233], v[232:233], v[198:199]
	v_pk_add_f32 v[232:233], v[232:233], v[200:201]
	v_pk_add_f32 v[232:233], v[232:233], v[202:203]
	ds_read2_b32 v[188:189], v115 offset0:32 offset1:33
	ds_read2_b32 v[190:191], v115 offset0:34 offset1:35
	ds_read2_b32 v[192:193], v115 offset0:40 offset1:41
	ds_read2_b32 v[194:195], v115 offset0:42 offset1:43
	ds_read2_b32 v[196:197], v115 offset0:48 offset1:49
	ds_read2_b32 v[198:199], v115 offset0:50 offset1:51
	ds_read2_b32 v[200:201], v115 offset0:56 offset1:57
	ds_read2_b32 v[202:203], v115 offset0:58 offset1:59
	v_mfma_f32_32x32x16_bf16 v[0:15], v[64:67], v[72:75], v[0:15]
	v_mfma_f32_32x32x16_bf16 v[16:31], v[64:67], v[76:79], v[16:31]
	v_mfma_f32_32x32x16_bf16 v[0:15], v[68:71], v[220:223], v[0:15]
	v_mfma_f32_32x32x16_bf16 v[16:31], v[68:71], v[224:227], v[16:31]
	global_load_dwordx4 v[116:119], v243, s[88:89]
	global_load_dwordx4 v[120:123], v244, s[88:89]
	global_load_dwordx4 v[124:127], v245, s[88:89]
	global_load_dwordx4 v[128:131], v246, s[88:89]
	global_load_dwordx4 v[132:135], v148, s[88:89] offset:768
	global_load_dwordx4 v[136:139], v151, s[88:89] offset:768
	global_load_dwordx4 v[140:143], v148, s[88:89] offset:832
	global_load_dwordx4 v[144:147], v151, s[88:89] offset:832
	s_add_u32 s88, s88, 0x300000
	s_addc_u32 s89, s89, 0
	ds_read_b64_tr_b16 v[72:73], v231
	ds_read_b64_tr_b16 v[74:75], v231 offset:512
	ds_read_b64_tr_b16 v[76:77], v231 offset:2048
	ds_read_b64_tr_b16 v[78:79], v231 offset:2560
	ds_read_b64_tr_b16 v[220:221], v231 offset:1024
	ds_read_b64_tr_b16 v[222:223], v231 offset:1536
	ds_read_b64_tr_b16 v[224:225], v231 offset:3072
	ds_read_b64_tr_b16 v[226:227], v231 offset:3584
	v_exp_f32_e32 v32, v32
	v_exp_f32_e32 v33, v33
	v_exp_f32_e32 v34, v34
	v_exp_f32_e32 v35, v35
	s_waitcnt vmcnt(12)
	ds_write_b128 v247, v[156:159]
	ds_write_b128 v247, v[160:163] offset:1024
	ds_write_b128 v247, v[164:167] offset:2048
	ds_write_b128 v247, v[168:171] offset:3072
	ds_read_b128 v[156:159], v248
	ds_read_b128 v[160:163], v249
	ds_read_b128 v[164:167], v250
	ds_read_b128 v[168:171], v251
	s_waitcnt vmcnt(8)
	ds_write_b128 v112, v[172:175]
	ds_write_b128 v112, v[176:179] offset:1024
	ds_write_b128 v112, v[180:183] offset:2048
	ds_write_b128 v112, v[184:187] offset:3072
	v_exp_f32_e32 v36, v36
	v_exp_f32_e32 v37, v37
	v_exp_f32_e32 v38, v38
	v_exp_f32_e32 v39, v39
	s_waitcnt lgkmcnt(4)
	v_mfma_f32_32x32x16_bf16 v[188:203], v[156:159], v[48:51], v[188:203]
	v_exp_f32_e32 v40, v40
	v_exp_f32_e32 v41, v41
	v_mfma_f32_32x32x16_bf16 v[188:203], v[160:163], v[52:55], v[188:203]
	v_exp_f32_e32 v42, v42
	v_exp_f32_e32 v43, v43
	v_mfma_f32_32x32x16_bf16 v[188:203], v[164:167], v[56:59], v[188:203]
	v_exp_f32_e32 v44, v44
	v_exp_f32_e32 v45, v45
	v_mfma_f32_32x32x16_bf16 v[188:203], v[168:171], v[60:63], v[188:203]
	v_exp_f32_e32 v46, v46
	v_exp_f32_e32 v47, v47
	v_cvt_pk_bf16_f32 v64, v32, v33
	v_cvt_pk_bf16_f32 v65, v34, v35
	v_cvt_pk_bf16_f32 v66, v36, v37
	v_cvt_pk_bf16_f32 v67, v38, v39
	v_cvt_pk_bf16_f32 v68, v40, v41
	v_cvt_pk_bf16_f32 v69, v42, v43
	v_cvt_pk_bf16_f32 v70, v44, v45
	v_cvt_pk_bf16_f32 v71, v46, v47
	v_pk_add_f32 v[232:233], v[232:233], v[32:33]
	v_pk_add_f32 v[232:233], v[232:233], v[34:35]
	v_pk_add_f32 v[232:233], v[232:233], v[36:37]
	v_pk_add_f32 v[232:233], v[232:233], v[38:39]
	v_pk_add_f32 v[232:233], v[232:233], v[40:41]
	v_pk_add_f32 v[232:233], v[232:233], v[42:43]
	v_pk_add_f32 v[232:233], v[232:233], v[44:45]
	v_pk_add_f32 v[232:233], v[232:233], v[46:47]
	ds_read2_b32 v[32:33], v115 offset0:64 offset1:65
	ds_read2_b32 v[34:35], v115 offset0:66 offset1:67
	ds_read2_b32 v[36:37], v115 offset0:72 offset1:73
	ds_read2_b32 v[38:39], v115 offset0:74 offset1:75
	ds_read2_b32 v[40:41], v115 offset0:80 offset1:81
	ds_read2_b32 v[42:43], v115 offset0:82 offset1:83
	ds_read2_b32 v[44:45], v115 offset0:88 offset1:89
	ds_read2_b32 v[46:47], v115 offset0:90 offset1:91
	v_mfma_f32_32x32x16_bf16 v[0:15], v[64:67], v[72:75], v[0:15]
	v_mfma_f32_32x32x16_bf16 v[16:31], v[64:67], v[76:79], v[16:31]
	v_mfma_f32_32x32x16_bf16 v[0:15], v[68:71], v[220:223], v[0:15]
	v_mfma_f32_32x32x16_bf16 v[16:31], v[68:71], v[224:227], v[16:31]
	global_load_dwordx4 v[156:159], v243, s[88:89]
	global_load_dwordx4 v[160:163], v244, s[88:89]
	global_load_dwordx4 v[164:167], v245, s[88:89]
	global_load_dwordx4 v[168:171], v246, s[88:89]
	global_load_dwordx4 v[172:175], v148, s[88:89] offset:768
	global_load_dwordx4 v[176:179], v151, s[88:89] offset:768
	global_load_dwordx4 v[180:183], v148, s[88:89] offset:832
	global_load_dwordx4 v[184:187], v151, s[88:89] offset:832
	s_add_u32 s88, s88, 0x300000
	s_addc_u32 s89, s89, 0
	ds_read_b64_tr_b16 v[72:73], v231
	ds_read_b64_tr_b16 v[74:75], v231 offset:512
	ds_read_b64_tr_b16 v[76:77], v231 offset:2048
	ds_read_b64_tr_b16 v[78:79], v231 offset:2560
	ds_read_b64_tr_b16 v[220:221], v231 offset:1024
	ds_read_b64_tr_b16 v[222:223], v231 offset:1536
	ds_read_b64_tr_b16 v[224:225], v231 offset:3072
	ds_read_b64_tr_b16 v[226:227], v231 offset:3584
	v_exp_f32_e32 v188, v188
	v_exp_f32_e32 v189, v189
	v_exp_f32_e32 v190, v190
	v_exp_f32_e32 v191, v191
	s_waitcnt vmcnt(12)
	ds_write_b128 v247, v[116:119]
	ds_write_b128 v247, v[120:123] offset:1024
	ds_write_b128 v247, v[124:127] offset:2048
	ds_write_b128 v247, v[128:131] offset:3072
	ds_read_b128 v[116:119], v248
	ds_read_b128 v[120:123], v249
	ds_read_b128 v[124:127], v250
	ds_read_b128 v[128:131], v251
	s_waitcnt vmcnt(8)
	ds_write_b128 v112, v[132:135]
	ds_write_b128 v112, v[136:139] offset:1024
	ds_write_b128 v112, v[140:143] offset:2048
	ds_write_b128 v112, v[144:147] offset:3072
	v_exp_f32_e32 v192, v192
	v_exp_f32_e32 v193, v193
	v_exp_f32_e32 v194, v194
	v_exp_f32_e32 v195, v195
	s_waitcnt lgkmcnt(4)
	v_mfma_f32_32x32x16_bf16 v[32:47], v[116:119], v[48:51], v[32:47]
	v_exp_f32_e32 v196, v196
	v_exp_f32_e32 v197, v197
	v_mfma_f32_32x32x16_bf16 v[32:47], v[120:123], v[52:55], v[32:47]
	v_exp_f32_e32 v198, v198
	v_exp_f32_e32 v199, v199
	v_mfma_f32_32x32x16_bf16 v[32:47], v[124:127], v[56:59], v[32:47]
	v_exp_f32_e32 v200, v200
	v_exp_f32_e32 v201, v201
	v_mfma_f32_32x32x16_bf16 v[32:47], v[128:131], v[60:63], v[32:47]
	v_exp_f32_e32 v202, v202
	v_exp_f32_e32 v203, v203
	v_cvt_pk_bf16_f32 v64, v188, v189
	v_cvt_pk_bf16_f32 v65, v190, v191
	v_cvt_pk_bf16_f32 v66, v192, v193
	v_cvt_pk_bf16_f32 v67, v194, v195
	v_cvt_pk_bf16_f32 v68, v196, v197
	v_cvt_pk_bf16_f32 v69, v198, v199
	v_cvt_pk_bf16_f32 v70, v200, v201
	v_cvt_pk_bf16_f32 v71, v202, v203
	v_pk_add_f32 v[232:233], v[232:233], v[188:189]
	v_pk_add_f32 v[232:233], v[232:233], v[190:191]
	v_pk_add_f32 v[232:233], v[232:233], v[192:193]
	v_pk_add_f32 v[232:233], v[232:233], v[194:195]
	v_pk_add_f32 v[232:233], v[232:233], v[196:197]
	v_pk_add_f32 v[232:233], v[232:233], v[198:199]
	v_pk_add_f32 v[232:233], v[232:233], v[200:201]
	v_pk_add_f32 v[232:233], v[232:233], v[202:203]
	ds_read2_b32 v[188:189], v115 offset0:96 offset1:97
	ds_read2_b32 v[190:191], v115 offset0:98 offset1:99
	ds_read2_b32 v[192:193], v115 offset0:104 offset1:105
	ds_read2_b32 v[194:195], v115 offset0:106 offset1:107
	ds_read2_b32 v[196:197], v115 offset0:112 offset1:113
	ds_read2_b32 v[198:199], v115 offset0:114 offset1:115
	ds_read2_b32 v[200:201], v115 offset0:120 offset1:121
	ds_read2_b32 v[202:203], v115 offset0:122 offset1:123
	v_mfma_f32_32x32x16_bf16 v[0:15], v[64:67], v[72:75], v[0:15]
	v_mfma_f32_32x32x16_bf16 v[16:31], v[64:67], v[76:79], v[16:31]
	v_mfma_f32_32x32x16_bf16 v[0:15], v[68:71], v[220:223], v[0:15]
	v_mfma_f32_32x32x16_bf16 v[16:31], v[68:71], v[224:227], v[16:31]
	global_load_dwordx4 v[116:119], v243, s[88:89]
	global_load_dwordx4 v[120:123], v244, s[88:89]
	global_load_dwordx4 v[124:127], v245, s[88:89]
	global_load_dwordx4 v[128:131], v246, s[88:89]
	global_load_dwordx4 v[132:135], v148, s[88:89] offset:768
	global_load_dwordx4 v[136:139], v151, s[88:89] offset:768
	global_load_dwordx4 v[140:143], v148, s[88:89] offset:832
	global_load_dwordx4 v[144:147], v151, s[88:89] offset:832
	ds_read_b64_tr_b16 v[72:73], v231
	ds_read_b64_tr_b16 v[74:75], v231 offset:512
	ds_read_b64_tr_b16 v[76:77], v231 offset:2048
	ds_read_b64_tr_b16 v[78:79], v231 offset:2560
	ds_read_b64_tr_b16 v[220:221], v231 offset:1024
	ds_read_b64_tr_b16 v[222:223], v231 offset:1536
	ds_read_b64_tr_b16 v[224:225], v231 offset:3072
	ds_read_b64_tr_b16 v[226:227], v231 offset:3584
	v_exp_f32_e32 v32, v32
	v_exp_f32_e32 v33, v33
	v_exp_f32_e32 v34, v34
	v_exp_f32_e32 v35, v35
	s_waitcnt vmcnt(12)
	ds_write_b128 v247, v[156:159]
	ds_write_b128 v247, v[160:163] offset:1024
	ds_write_b128 v247, v[164:167] offset:2048
	ds_write_b128 v247, v[168:171] offset:3072
	ds_read_b128 v[156:159], v248
	ds_read_b128 v[160:163], v249
	ds_read_b128 v[164:167], v250
	ds_read_b128 v[168:171], v251
	s_waitcnt vmcnt(8)
	ds_write_b128 v112, v[172:175]
	ds_write_b128 v112, v[176:179] offset:1024
	ds_write_b128 v112, v[180:183] offset:2048
	ds_write_b128 v112, v[184:187] offset:3072
	v_exp_f32_e32 v36, v36
	v_exp_f32_e32 v37, v37
	v_exp_f32_e32 v38, v38
	v_exp_f32_e32 v39, v39
	s_waitcnt lgkmcnt(4)
	v_mfma_f32_32x32x16_bf16 v[188:203], v[156:159], v[48:51], v[188:203]
	v_exp_f32_e32 v40, v40
	v_exp_f32_e32 v41, v41
	v_mfma_f32_32x32x16_bf16 v[188:203], v[160:163], v[52:55], v[188:203]
	v_exp_f32_e32 v42, v42
	v_exp_f32_e32 v43, v43
	v_mfma_f32_32x32x16_bf16 v[188:203], v[164:167], v[56:59], v[188:203]
	v_exp_f32_e32 v44, v44
	v_exp_f32_e32 v45, v45
	v_mfma_f32_32x32x16_bf16 v[188:203], v[168:171], v[60:63], v[188:203]
	v_exp_f32_e32 v46, v46
	v_exp_f32_e32 v47, v47
	v_cvt_pk_bf16_f32 v64, v32, v33
	v_cvt_pk_bf16_f32 v65, v34, v35
	v_cvt_pk_bf16_f32 v66, v36, v37
	v_cvt_pk_bf16_f32 v67, v38, v39
	v_cvt_pk_bf16_f32 v68, v40, v41
	v_cvt_pk_bf16_f32 v69, v42, v43
	v_cvt_pk_bf16_f32 v70, v44, v45
	v_cvt_pk_bf16_f32 v71, v46, v47
	v_pk_add_f32 v[232:233], v[232:233], v[32:33]
	v_pk_add_f32 v[232:233], v[232:233], v[34:35]
	v_pk_add_f32 v[232:233], v[232:233], v[36:37]
	v_pk_add_f32 v[232:233], v[232:233], v[38:39]
	v_pk_add_f32 v[232:233], v[232:233], v[40:41]
	v_pk_add_f32 v[232:233], v[232:233], v[42:43]
	v_pk_add_f32 v[232:233], v[232:233], v[44:45]
	v_pk_add_f32 v[232:233], v[232:233], v[46:47]
	ds_read2_b32 v[32:33], v115 offset0:128 offset1:129
	ds_read2_b32 v[34:35], v115 offset0:130 offset1:131
	ds_read2_b32 v[36:37], v115 offset0:136 offset1:137
	ds_read2_b32 v[38:39], v115 offset0:138 offset1:139
	ds_read2_b32 v[40:41], v115 offset0:144 offset1:145
	ds_read2_b32 v[42:43], v115 offset0:146 offset1:147
	ds_read2_b32 v[44:45], v115 offset0:152 offset1:153
	ds_read2_b32 v[46:47], v115 offset0:154 offset1:155
	v_mfma_f32_32x32x16_bf16 v[0:15], v[64:67], v[72:75], v[0:15]
	v_mfma_f32_32x32x16_bf16 v[16:31], v[64:67], v[76:79], v[16:31]
	v_mfma_f32_32x32x16_bf16 v[0:15], v[68:71], v[220:223], v[0:15]
	v_mfma_f32_32x32x16_bf16 v[16:31], v[68:71], v[224:227], v[16:31]
	ds_read_b64_tr_b16 v[72:73], v231
	ds_read_b64_tr_b16 v[74:75], v231 offset:512
	ds_read_b64_tr_b16 v[76:77], v231 offset:2048
	ds_read_b64_tr_b16 v[78:79], v231 offset:2560
	ds_read_b64_tr_b16 v[220:221], v231 offset:1024
	ds_read_b64_tr_b16 v[222:223], v231 offset:1536
	ds_read_b64_tr_b16 v[224:225], v231 offset:3072
	ds_read_b64_tr_b16 v[226:227], v231 offset:3584
	v_exp_f32_e32 v188, v188
	v_exp_f32_e32 v189, v189
	v_exp_f32_e32 v190, v190
	v_exp_f32_e32 v191, v191
	s_waitcnt vmcnt(4)
; #define LAS __attribute__((address_space(3)))
; __device__ __forceinline__ int crow(int r, int hi) { return (r & 3) + 8 * (r >> 2) + 4 * hi; }
; __device__ __forceinline__ void dil_unit(LAS unsigned char* lds, bf16_t* proj, int seq, int hd, int T0, int rho) {
;     ...
;     if (bound) DIL_LOOP(true); else DIL_LOOP(false);
;     ...
;     LAS bf16_t* stg = (LAS bf16_t*)wbuf;
;     l += __shfl_xor(l, 32);
; #pragma unroll
;     for (int rr = 0; rr < 16; ++rr) {
;         const int j = crow(rr, hi);
;         const float il = __builtin_amdgcn_rcpf(__shfl(l, j));
	ds_write_b128 v247, v[116:119]
	ds_write_b128 v247, v[120:123] offset:1024
	ds_write_b128 v247, v[124:127] offset:2048
	ds_write_b128 v247, v[128:131] offset:3072
	ds_read_b128 v[116:119], v248
	ds_read_b128 v[120:123], v249
	ds_read_b128 v[124:127], v250
	ds_read_b128 v[128:131], v251
	s_waitcnt vmcnt(0)
	ds_write_b128 v112, v[132:135]
	ds_write_b128 v112, v[136:139] offset:1024
	ds_write_b128 v112, v[140:143] offset:2048
	ds_write_b128 v112, v[144:147] offset:3072
	v_exp_f32_e32 v192, v192
	v_exp_f32_e32 v193, v193
	v_exp_f32_e32 v194, v194
	v_exp_f32_e32 v195, v195
	s_waitcnt lgkmcnt(4)
	v_mfma_f32_32x32x16_bf16 v[32:47], v[116:119], v[48:51], v[32:47]
	v_exp_f32_e32 v196, v196
	v_exp_f32_e32 v197, v197
	v_mfma_f32_32x32x16_bf16 v[32:47], v[120:123], v[52:55], v[32:47]
	v_exp_f32_e32 v198, v198
	v_exp_f32_e32 v199, v199
	v_mfma_f32_32x32x16_bf16 v[32:47], v[124:127], v[56:59], v[32:47]
	v_exp_f32_e32 v200, v200
	v_exp_f32_e32 v201, v201
	v_mfma_f32_32x32x16_bf16 v[32:47], v[128:131], v[60:63], v[32:47]
	v_exp_f32_e32 v202, v202
	v_exp_f32_e32 v203, v203
	v_cvt_pk_bf16_f32 v64, v188, v189
	v_cvt_pk_bf16_f32 v65, v190, v191
	v_cvt_pk_bf16_f32 v66, v192, v193
	v_cvt_pk_bf16_f32 v67, v194, v195
	v_cvt_pk_bf16_f32 v68, v196, v197
	v_cvt_pk_bf16_f32 v69, v198, v199
	v_cvt_pk_bf16_f32 v70, v200, v201
	v_cvt_pk_bf16_f32 v71, v202, v203
	v_pk_add_f32 v[232:233], v[232:233], v[188:189]
	v_pk_add_f32 v[232:233], v[232:233], v[190:191]
	v_pk_add_f32 v[232:233], v[232:233], v[192:193]
	v_pk_add_f32 v[232:233], v[232:233], v[194:195]
	v_pk_add_f32 v[232:233], v[232:233], v[196:197]
	v_pk_add_f32 v[232:233], v[232:233], v[198:199]
	v_pk_add_f32 v[232:233], v[232:233], v[200:201]
	v_pk_add_f32 v[232:233], v[232:233], v[202:203]
	v_mfma_f32_32x32x16_bf16 v[0:15], v[64:67], v[72:75], v[0:15]
	v_mfma_f32_32x32x16_bf16 v[16:31], v[64:67], v[76:79], v[16:31]
	v_mfma_f32_32x32x16_bf16 v[0:15], v[68:71], v[220:223], v[0:15]
	v_mfma_f32_32x32x16_bf16 v[16:31], v[68:71], v[224:227], v[16:31]
	ds_read_b64_tr_b16 v[72:73], v231
	ds_read_b64_tr_b16 v[74:75], v231 offset:512
	ds_read_b64_tr_b16 v[76:77], v231 offset:2048
	ds_read_b64_tr_b16 v[78:79], v231 offset:2560
	ds_read_b64_tr_b16 v[220:221], v231 offset:1024
	ds_read_b64_tr_b16 v[222:223], v231 offset:1536
	ds_read_b64_tr_b16 v[224:225], v231 offset:3072
	ds_read_b64_tr_b16 v[226:227], v231 offset:3584
	s_waitcnt lgkmcnt(0)
	v_exp_f32_e32 v32, v32
	v_exp_f32_e32 v33, v33
	v_exp_f32_e32 v34, v34
	v_exp_f32_e32 v35, v35
	v_exp_f32_e32 v36, v36
	v_exp_f32_e32 v37, v37
	v_exp_f32_e32 v38, v38
	v_exp_f32_e32 v39, v39
	v_exp_f32_e32 v40, v40
	v_exp_f32_e32 v41, v41
	v_exp_f32_e32 v42, v42
	v_exp_f32_e32 v43, v43
	v_exp_f32_e32 v44, v44
	v_exp_f32_e32 v45, v45
	v_exp_f32_e32 v46, v46
	v_exp_f32_e32 v47, v47
	v_cvt_pk_bf16_f32 v64, v32, v33
	v_cvt_pk_bf16_f32 v65, v34, v35
	v_cvt_pk_bf16_f32 v66, v36, v37
	v_cvt_pk_bf16_f32 v67, v38, v39
	v_cvt_pk_bf16_f32 v68, v40, v41
	v_cvt_pk_bf16_f32 v69, v42, v43
	v_cvt_pk_bf16_f32 v70, v44, v45
	v_cvt_pk_bf16_f32 v71, v46, v47
	v_pk_add_f32 v[232:233], v[232:233], v[32:33]
	v_pk_add_f32 v[232:233], v[232:233], v[34:35]
	v_pk_add_f32 v[232:233], v[232:233], v[36:37]
	v_pk_add_f32 v[232:233], v[232:233], v[38:39]
	v_pk_add_f32 v[232:233], v[232:233], v[40:41]
	v_pk_add_f32 v[232:233], v[232:233], v[42:43]
	v_pk_add_f32 v[232:233], v[232:233], v[44:45]
	v_pk_add_f32 v[232:233], v[232:233], v[46:47]
	v_mfma_f32_32x32x16_bf16 v[0:15], v[64:67], v[72:75], v[0:15]
	v_mfma_f32_32x32x16_bf16 v[16:31], v[64:67], v[76:79], v[16:31]
	v_mfma_f32_32x32x16_bf16 v[0:15], v[68:71], v[220:223], v[0:15]
	v_mfma_f32_32x32x16_bf16 v[16:31], v[68:71], v[224:227], v[16:31]
	v_add_f32_e32 v113, v232, v233
	v_or_b32_e32 v114, 1, v107
	v_or_b32_e32 v97, 2, v107
	v_or_b32_e32 v96, 3, v107
	v_or_b32_e32 v95, 8, v107
	v_or_b32_e32 v94, 9, v107
	v_or_b32_e32 v93, 10, v107
	v_or_b32_e32 v92, 11, v107
	v_or_b32_e32 v91, 16, v107
	v_or_b32_e32 v90, 17, v107
	v_or_b32_e32 v89, 18, v107
	v_or_b32_e32 v88, 19, v107
	v_or_b32_e32 v87, 24, v107
	v_or_b32_e32 v86, 25, v107
	v_or_b32_e32 v85, 26, v107
	v_or_b32_e32 v84, 27, v107
	s_nop 11
	s_branch .LBB0_1265
.LBB0_1270:
	s_movk_i32 s100, 0x1800
	s_add_i32 s101, s8, 0x15c00
	s_lshl_b32 s90, s54, 1
	s_add_u32 s82, s52, s90
	s_addc_u32 s83, s53, 0
	s_add_u32 s82, s82, 0x1200
	s_addc_u32 s83, s83, 0
	s_sub_i32 s90, s67, 64
	s_mul_i32 s90, s90, 0x1800
	s_add_u32 s84, s82, s90
	s_addc_u32 s85, s83, 0
	s_sub_i32 s90, s67, 256
	s_mul_i32 s90, s90, 0x1800
	s_add_u32 s86, s82, s90
	s_addc_u32 s87, s83, 0
	s_sub_i32 s90, s67, 1024
	s_mul_i32 s90, s90, 0x1800
	s_add_u32 s88, s82, s90
	s_addc_u32 s89, s83, 0
	v_lshlrev_b32_e32 v153, 1, v98
	v_mad_u32_u24 v80, v105, s100, v82
	v_mad_u32_u24 v100, v110, s100, v153
	v_add_u32_e32 v149, 0x18000, v100
	v_lshlrev_b32_e32 v83, 2, v105
	v_mad_u32_u24 v83, v83, s100, v82
	v_lshlrev_b32_e32 v101, 2, v110
	v_mad_u32_u24 v101, v101, s100, v153
	v_add_u32_e32 v150, 0x60000, v101
	v_lshlrev_b32_e32 v99, 4, v105
	v_mad_u32_u24 v99, v99, s100, v82
	v_lshlrev_b32_e32 v148, 4, v110
	v_mad_u32_u24 v148, v148, s100, v153
	v_add_u32_e32 v151, 0x180000, v148
	v_lshrrev_b32_e32 v249, 3, v103
	v_and_b32_e32 v250, 7, v103
	v_lshlrev_b32_e32 v250, 4, v250
	v_add_u32_e32 v235, 0, v249
	v_add_u32_e32 v236, 8, v249
	v_add_u32_e32 v237, 16, v249
	v_add_u32_e32 v238, 24, v249
	v_add_u32_e32 v239, 0, v249
	v_lshlrev_b32_e32 v239, 2, v239
	v_add_u32_e32 v240, 8, v249
	v_lshlrev_b32_e32 v240, 2, v240
	v_add_u32_e32 v241, 16, v249
	v_lshlrev_b32_e32 v241, 2, v241
	v_add_u32_e32 v242, 24, v249
	v_lshlrev_b32_e32 v242, 2, v242
	v_add_u32_e32 v243, 0, v249
; #define LAS __attribute__((address_space(3)))
; #define GAS __attribute__((address_space(1)))
; __device__ __forceinline__ void dil_unit(LAS unsigned char* lds, bf16_t* proj, int seq, int hd, int T0, int rho) {
;     ...
;     const int tid = tid_, lane = tid & 63, r32 = lane & 31, hi = lane >> 5, wid = __builtin_amdgcn_readfirstlane(tid >> 6);
;     bf16_t* base = proj + (size_t)seq * SEQ * NIN;
;     LAS unsigned char* wbuf = lds + wid * 4096;
;     const LAS unsigned char* vp = wbuf + ((lane >> 4) & 1) * 32 + (lane & 3) * 8 + (4 * hi + ((lane & 15) >> 2)) * 64;
;     const int P0 = T0 + rho;
;     bf16x8 qr[4];
; #pragma unroll
;     for (int ks = 0; ks < 4; ++ks) qr[ks] = *(const GAS bf16x8*)(base + (size_t)(P0 + 16 * r32) * NIN + PC_LQ + hd * 64 + 16 * ks + 8 * hi);
;     f32x16 o0 = {}, o1 = {}; float l = 0.f;
;     const bool bound = (T0 < 1024) || (T0 >= 15360);
	v_lshlrev_b32_e32 v243, 4, v243
	v_add_u32_e32 v244, 8, v249
	v_lshlrev_b32_e32 v244, 4, v244
	v_add_u32_e32 v245, 16, v249
	v_lshlrev_b32_e32 v245, 4, v245
	v_add_u32_e32 v246, 24, v249
	v_lshlrev_b32_e32 v246, 4, v246
	v_mov_b32_e32 v252, v250
	v_mov_b32_e32 v100, v110
	v_add_u32_e32 v149, 16, v100
	v_lshlrev_b32_e32 v101, 2, v110
	v_add_u32_e32 v150, 64, v101
	v_lshlrev_b32_e32 v148, 4, v110
	v_add_u32_e32 v151, 256, v148
	s_mov_b32 s98, 0x4000
	s_mov_b32 s99, 0x3fff
	v_and_b32_e32 v247, 7, v249
	v_lshlrev_b32_e32 v247, 4, v247
	v_xor_b32_e32 v247, v247, v112
	v_and_b32_e32 v153, 7, v105
	v_or_b32_e32 v248, 0, v106
	v_xor_b32_e32 v248, v248, v153
	v_lshlrev_b32_e32 v248, 4, v248
	v_lshl_add_u32 v248, v105, 7, v248
	v_add_u32_e32 v248, s69, v248
	v_or_b32_e32 v249, 2, v106
	v_xor_b32_e32 v249, v249, v153
	v_lshlrev_b32_e32 v249, 4, v249
	v_lshl_add_u32 v249, v105, 7, v249
	v_add_u32_e32 v249, s69, v249
	v_or_b32_e32 v250, 4, v106
	v_xor_b32_e32 v250, v250, v153
	v_lshlrev_b32_e32 v250, 4, v250
	v_lshl_add_u32 v250, v105, 7, v250
	v_add_u32_e32 v250, s69, v250
	v_or_b32_e32 v251, 6, v106
	v_xor_b32_e32 v251, v251, v153
	v_lshlrev_b32_e32 v251, 4, v251
	v_lshl_add_u32 v251, v105, 7, v251
	v_add_u32_e32 v251, s69, v251
	v_lshlrev_b32_e32 v153, 1, v98
	v_mul_u32_u24_e32 v228, 17, v105
	v_sub_u32_e32 v228, v107, v228
	s_mul_i32 s90, s54, 153
	s_lshr_b32 s90, s90, 1
	s_add_i32 s90, s90, 34876
	v_lshl_add_u32 v228, v228, 2, s90
	v_lshlrev_b32_e32 v229, 2, v105
	v_sub_u32_e32 v229, v107, v229
	s_add_i32 s90, s101, 5104
	v_lshl_add_u32 v229, v229, 2, s90
	v_sub_u32_e32 v230, v107, v105
	s_add_i32 s90, s101, 6364
	v_lshl_add_u32 v230, v230, 2, s90
	v_add_u32_e32 v231, v109, v108
	v_mov_b64_e32 v[232:233], 0
	v_mov_b64_e32 v[0:1], 0
	v_mov_b64_e32 v[2:3], 0
	v_mov_b64_e32 v[4:5], 0
	v_mov_b64_e32 v[6:7], 0
	v_mov_b64_e32 v[8:9], 0
	v_mov_b64_e32 v[10:11], 0
	v_mov_b64_e32 v[12:13], 0
	v_mov_b64_e32 v[14:15], 0
	v_mov_b64_e32 v[16:17], 0
	v_mov_b64_e32 v[18:19], 0
	v_mov_b64_e32 v[20:21], 0
	v_mov_b64_e32 v[22:23], 0
	v_mov_b64_e32 v[24:25], 0
	v_mov_b64_e32 v[26:27], 0
	v_mov_b64_e32 v[28:29], 0
	v_mov_b64_e32 v[30:31], 0
	s_add_i32 s90, s67, -64
	v_add_u32_e32 v80, s90, v235
	v_add_u32_e32 v83, s90, v236
	v_add_u32_e32 v99, s90, v237
	v_add_u32_e32 v253, s90, v238
	v_add_u32_e32 v254, s90, v100
	v_add_u32_e32 v255, s90, v149
	v_med3_i32 v80, v80, 0, s99
	v_med3_i32 v83, v83, 0, s99
	v_med3_i32 v99, v99, 0, s99
	v_med3_i32 v253, v253, 0, s99
	v_med3_i32 v254, v254, 0, s99
	v_med3_i32 v255, v255, 0, s99
	v_mad_u32_u24 v80, v80, s100, v252
	v_mad_u32_u24 v83, v83, s100, v252
	v_mad_u32_u24 v99, v99, s100, v252
	v_mad_u32_u24 v253, v253, s100, v252
	v_mad_u32_u24 v254, v254, s100, v153
	v_mad_u32_u24 v255, v255, s100, v153
	global_load_dwordx4 v[116:119], v80, s[82:83]
	global_load_dwordx4 v[120:123], v83, s[82:83]
	global_load_dwordx4 v[124:127], v99, s[82:83]
	global_load_dwordx4 v[128:131], v253, s[82:83]
	global_load_dwordx4 v[132:135], v254, s[82:83] offset:768
	global_load_dwordx4 v[136:139], v255, s[82:83] offset:768
	global_load_dwordx4 v[140:143], v254, s[82:83] offset:832
	global_load_dwordx4 v[144:147], v255, s[82:83] offset:832
	s_add_i32 s90, s67, -32
	v_add_u32_e32 v80, s90, v235
	v_add_u32_e32 v83, s90, v236
	v_add_u32_e32 v99, s90, v237
	v_add_u32_e32 v253, s90, v238
	v_add_u32_e32 v254, s90, v100
	v_add_u32_e32 v255, s90, v149
	v_med3_i32 v80, v80, 0, s99
	v_med3_i32 v83, v83, 0, s99
	v_med3_i32 v99, v99, 0, s99
	v_med3_i32 v253, v253, 0, s99
	v_med3_i32 v254, v254, 0, s99
	v_med3_i32 v255, v255, 0, s99
	v_mad_u32_u24 v80, v80, s100, v252
	v_mad_u32_u24 v83, v83, s100, v252
	v_mad_u32_u24 v99, v99, s100, v252
	v_mad_u32_u24 v253, v253, s100, v252
	v_mad_u32_u24 v254, v254, s100, v153
	v_mad_u32_u24 v255, v255, s100, v153
	global_load_dwordx4 v[156:159], v80, s[82:83]
	global_load_dwordx4 v[160:163], v83, s[82:83]
	global_load_dwordx4 v[164:167], v99, s[82:83]
	global_load_dwordx4 v[168:171], v253, s[82:83]
	global_load_dwordx4 v[172:175], v254, s[82:83] offset:768
	global_load_dwordx4 v[176:179], v255, s[82:83] offset:768
	global_load_dwordx4 v[180:183], v254, s[82:83] offset:832
	global_load_dwordx4 v[184:187], v255, s[82:83] offset:832
	v_mov_b32_e32 v115, v228
	ds_read2_b32 v[32:33], v115 offset0:0 offset1:1
	ds_read2_b32 v[34:35], v115 offset0:2 offset1:3
	ds_read2_b32 v[36:37], v115 offset0:8 offset1:9
	ds_read2_b32 v[38:39], v115 offset0:10 offset1:11
	ds_read2_b32 v[40:41], v115 offset0:17 offset1:18
	ds_read2_b32 v[42:43], v115 offset0:19 offset1:20
	ds_read2_b32 v[44:45], v115 offset0:25 offset1:26
	ds_read2_b32 v[46:47], v115 offset0:27 offset1:28
	s_waitcnt vmcnt(8)
	ds_write_b128 v247, v[116:119]
	ds_write_b128 v247, v[120:123] offset:1024
	ds_write_b128 v247, v[124:127] offset:2048
	ds_write_b128 v247, v[128:131] offset:3072
	ds_read_b128 v[116:119], v248
	ds_read_b128 v[120:123], v249
	ds_read_b128 v[124:127], v250
	ds_read_b128 v[128:131], v251
	ds_write_b128 v112, v[132:135]
	ds_write_b128 v112, v[136:139] offset:1024
	ds_write_b128 v112, v[140:143] offset:2048
	ds_write_b128 v112, v[144:147] offset:3072
	s_waitcnt lgkmcnt(4)
	v_mfma_f32_32x32x16_bf16 v[32:47], v[116:119], v[48:51], v[32:47]
	v_mfma_f32_32x32x16_bf16 v[32:47], v[120:123], v[52:55], v[32:47]
	v_mfma_f32_32x32x16_bf16 v[32:47], v[124:127], v[56:59], v[32:47]
	v_mfma_f32_32x32x16_bf16 v[32:47], v[128:131], v[60:63], v[32:47]
	ds_read2_b32 v[188:189], v115 offset0:34 offset1:35
	ds_read2_b32 v[190:191], v115 offset0:36 offset1:37
	ds_read2_b32 v[192:193], v115 offset0:42 offset1:43
	ds_read2_b32 v[194:195], v115 offset0:44 offset1:45
	ds_read2_b32 v[196:197], v115 offset0:51 offset1:52
	ds_read2_b32 v[198:199], v115 offset0:53 offset1:54
	ds_read2_b32 v[200:201], v115 offset0:59 offset1:60
	ds_read2_b32 v[202:203], v115 offset0:61 offset1:62
	s_add_i32 s90, s67, 0
	v_add_u32_e32 v80, s90, v235
	v_add_u32_e32 v83, s90, v236
	v_add_u32_e32 v99, s90, v237
	v_add_u32_e32 v253, s90, v238
	v_add_u32_e32 v254, s90, v100
	v_add_u32_e32 v255, s90, v149
	v_med3_i32 v80, v80, 0, s99
	v_med3_i32 v83, v83, 0, s99
	v_med3_i32 v99, v99, 0, s99
	v_med3_i32 v253, v253, 0, s99
	v_med3_i32 v254, v254, 0, s99
	v_med3_i32 v255, v255, 0, s99
	v_mad_u32_u24 v80, v80, s100, v252
	v_mad_u32_u24 v83, v83, s100, v252
	v_mad_u32_u24 v99, v99, s100, v252
	v_mad_u32_u24 v253, v253, s100, v252
	v_mad_u32_u24 v254, v254, s100, v153
	v_mad_u32_u24 v255, v255, s100, v153
	global_load_dwordx4 v[116:119], v80, s[82:83]
	global_load_dwordx4 v[120:123], v83, s[82:83]
	global_load_dwordx4 v[124:127], v99, s[82:83]
	global_load_dwordx4 v[128:131], v253, s[82:83]
	global_load_dwordx4 v[132:135], v254, s[82:83] offset:768
	global_load_dwordx4 v[136:139], v255, s[82:83] offset:768
	global_load_dwordx4 v[140:143], v254, s[82:83] offset:832
	global_load_dwordx4 v[144:147], v255, s[82:83] offset:832
	ds_read_b64_tr_b16 v[72:73], v231
	ds_read_b64_tr_b16 v[74:75], v231 offset:512
	ds_read_b64_tr_b16 v[76:77], v231 offset:2048
	ds_read_b64_tr_b16 v[78:79], v231 offset:2560
	ds_read_b64_tr_b16 v[220:221], v231 offset:1024
	ds_read_b64_tr_b16 v[222:223], v231 offset:1536
	ds_read_b64_tr_b16 v[224:225], v231 offset:3072
	ds_read_b64_tr_b16 v[226:227], v231 offset:3584
	v_exp_f32_e32 v32, v32
	v_exp_f32_e32 v33, v33
	v_exp_f32_e32 v34, v34
	v_exp_f32_e32 v35, v35
	s_waitcnt vmcnt(12)
	ds_write_b128 v247, v[156:159]
	ds_write_b128 v247, v[160:163] offset:1024
	ds_write_b128 v247, v[164:167] offset:2048
	ds_write_b128 v247, v[168:171] offset:3072
	ds_read_b128 v[156:159], v248
	ds_read_b128 v[160:163], v249
	ds_read_b128 v[164:167], v250
	ds_read_b128 v[168:171], v251
	s_waitcnt vmcnt(8)
	ds_write_b128 v112, v[172:175]
	ds_write_b128 v112, v[176:179] offset:1024
	ds_write_b128 v112, v[180:183] offset:2048
	ds_write_b128 v112, v[184:187] offset:3072
	v_exp_f32_e32 v36, v36
	v_exp_f32_e32 v37, v37
	v_exp_f32_e32 v38, v38
	v_exp_f32_e32 v39, v39
	s_waitcnt lgkmcnt(4)
	v_mfma_f32_32x32x16_bf16 v[188:203], v[156:159], v[48:51], v[188:203]
	v_exp_f32_e32 v40, v40
	v_exp_f32_e32 v41, v41
	v_mfma_f32_32x32x16_bf16 v[188:203], v[160:163], v[52:55], v[188:203]
	v_exp_f32_e32 v42, v42
	v_exp_f32_e32 v43, v43
	v_mfma_f32_32x32x16_bf16 v[188:203], v[164:167], v[56:59], v[188:203]
	v_exp_f32_e32 v44, v44
	v_exp_f32_e32 v45, v45
	v_mfma_f32_32x32x16_bf16 v[188:203], v[168:171], v[60:63], v[188:203]
	v_exp_f32_e32 v46, v46
	v_exp_f32_e32 v47, v47
	s_add_i32 s90, s67, -64
	v_add_u32_e32 v84, s90, v107
	v_add_u32_e32 v85, 0, v84
	v_add_u32_e32 v86, 1, v84
	v_add_u32_e32 v87, 2, v84
	v_add_u32_e32 v88, 3, v84
	v_cmp_gt_u32_e64 s[30:31], s98, v85
	v_cmp_gt_u32_e64 s[36:37], s98, v86
	v_cmp_gt_u32_e64 s[78:79], s98, v87
	v_cmp_gt_u32_e64 s[50:51], s98, v88
	v_cndmask_b32_e64 v32, 0, v32, s[30:31]
	v_add_u32_e32 v85, 8, v84
	v_cmp_gt_u32_e64 s[30:31], s98, v85
	v_cndmask_b32_e64 v33, 0, v33, s[36:37]
	v_add_u32_e32 v86, 9, v84
	v_cmp_gt_u32_e64 s[36:37], s98, v86
	v_cndmask_b32_e64 v34, 0, v34, s[78:79]
	v_add_u32_e32 v87, 10, v84
	v_cmp_gt_u32_e64 s[78:79], s98, v87
	v_cndmask_b32_e64 v35, 0, v35, s[50:51]
	v_add_u32_e32 v88, 11, v84
	v_cmp_gt_u32_e64 s[50:51], s98, v88
	v_cndmask_b32_e64 v36, 0, v36, s[30:31]
	v_add_u32_e32 v85, 16, v84
	v_cmp_gt_u32_e64 s[30:31], s98, v85
	v_cndmask_b32_e64 v37, 0, v37, s[36:37]
	v_add_u32_e32 v86, 17, v84
	v_cmp_gt_u32_e64 s[36:37], s98, v86
	v_cndmask_b32_e64 v38, 0, v38, s[78:79]
	v_add_u32_e32 v87, 18, v84
	v_cmp_gt_u32_e64 s[78:79], s98, v87
	v_cndmask_b32_e64 v39, 0, v39, s[50:51]
	v_add_u32_e32 v88, 19, v84
	v_cmp_gt_u32_e64 s[50:51], s98, v88
	v_cndmask_b32_e64 v40, 0, v40, s[30:31]
	v_add_u32_e32 v85, 24, v84
	v_cmp_gt_u32_e64 s[30:31], s98, v85
	v_cndmask_b32_e64 v41, 0, v41, s[36:37]
	v_add_u32_e32 v86, 25, v84
	v_cmp_gt_u32_e64 s[36:37], s98, v86
	v_cndmask_b32_e64 v42, 0, v42, s[78:79]
	v_add_u32_e32 v87, 26, v84
	v_cmp_gt_u32_e64 s[78:79], s98, v87
	v_cndmask_b32_e64 v43, 0, v43, s[50:51]
	v_add_u32_e32 v88, 27, v84
	v_cmp_gt_u32_e64 s[50:51], s98, v88
	v_nop
	v_cndmask_b32_e64 v44, 0, v44, s[30:31]
	v_cndmask_b32_e64 v45, 0, v45, s[36:37]
	v_cndmask_b32_e64 v46, 0, v46, s[78:79]
	v_cndmask_b32_e64 v47, 0, v47, s[50:51]
	v_cvt_pk_bf16_f32 v64, v32, v33
	v_cvt_pk_bf16_f32 v65, v34, v35
	v_cvt_pk_bf16_f32 v66, v36, v37
	v_cvt_pk_bf16_f32 v67, v38, v39
	v_cvt_pk_bf16_f32 v68, v40, v41
	v_cvt_pk_bf16_f32 v69, v42, v43
	v_cvt_pk_bf16_f32 v70, v44, v45
	v_cvt_pk_bf16_f32 v71, v46, v47
	v_pk_add_f32 v[232:233], v[232:233], v[32:33]
	v_pk_add_f32 v[232:233], v[232:233], v[34:35]
	v_pk_add_f32 v[232:233], v[232:233], v[36:37]
	v_pk_add_f32 v[232:233], v[232:233], v[38:39]
	v_pk_add_f32 v[232:233], v[232:233], v[40:41]
	v_pk_add_f32 v[232:233], v[232:233], v[42:43]
	v_pk_add_f32 v[232:233], v[232:233], v[44:45]
	v_pk_add_f32 v[232:233], v[232:233], v[46:47]
	ds_read2_b32 v[32:33], v115 offset0:68 offset1:69
	ds_read2_b32 v[34:35], v115 offset0:70 offset1:71
	ds_read2_b32 v[36:37], v115 offset0:76 offset1:77
	ds_read2_b32 v[38:39], v115 offset0:78 offset1:79
	ds_read2_b32 v[40:41], v115 offset0:85 offset1:86
	ds_read2_b32 v[42:43], v115 offset0:87 offset1:88
	ds_read2_b32 v[44:45], v115 offset0:93 offset1:94
	ds_read2_b32 v[46:47], v115 offset0:95 offset1:96
	v_mfma_f32_32x32x16_bf16 v[0:15], v[64:67], v[72:75], v[0:15]
	v_mfma_f32_32x32x16_bf16 v[16:31], v[64:67], v[76:79], v[16:31]
	v_mfma_f32_32x32x16_bf16 v[0:15], v[68:71], v[220:223], v[0:15]
	v_mfma_f32_32x32x16_bf16 v[16:31], v[68:71], v[224:227], v[16:31]
	s_add_i32 s90, s67, 32
	v_add_u32_e32 v80, s90, v235
	v_add_u32_e32 v83, s90, v236
	v_add_u32_e32 v99, s90, v237
	v_add_u32_e32 v253, s90, v238
	v_add_u32_e32 v254, s90, v100
	v_add_u32_e32 v255, s90, v149
	v_med3_i32 v80, v80, 0, s99
	v_med3_i32 v83, v83, 0, s99
	v_med3_i32 v99, v99, 0, s99
	v_med3_i32 v253, v253, 0, s99
	v_med3_i32 v254, v254, 0, s99
	v_med3_i32 v255, v255, 0, s99
	v_mad_u32_u24 v80, v80, s100, v252
	v_mad_u32_u24 v83, v83, s100, v252
	v_mad_u32_u24 v99, v99, s100, v252
	v_mad_u32_u24 v253, v253, s100, v252
	v_mad_u32_u24 v254, v254, s100, v153
	v_mad_u32_u24 v255, v255, s100, v153
	global_load_dwordx4 v[156:159], v80, s[82:83]
	global_load_dwordx4 v[160:163], v83, s[82:83]
	global_load_dwordx4 v[164:167], v99, s[82:83]
	global_load_dwordx4 v[168:171], v253, s[82:83]
	global_load_dwordx4 v[172:175], v254, s[82:83] offset:768
	global_load_dwordx4 v[176:179], v255, s[82:83] offset:768
	global_load_dwordx4 v[180:183], v254, s[82:83] offset:832
	global_load_dwordx4 v[184:187], v255, s[82:83] offset:832
	ds_read_b64_tr_b16 v[72:73], v231
	ds_read_b64_tr_b16 v[74:75], v231 offset:512
	ds_read_b64_tr_b16 v[76:77], v231 offset:2048
	ds_read_b64_tr_b16 v[78:79], v231 offset:2560
	ds_read_b64_tr_b16 v[220:221], v231 offset:1024
	ds_read_b64_tr_b16 v[222:223], v231 offset:1536
	ds_read_b64_tr_b16 v[224:225], v231 offset:3072
	ds_read_b64_tr_b16 v[226:227], v231 offset:3584
	v_exp_f32_e32 v188, v188
	v_exp_f32_e32 v189, v189
	v_exp_f32_e32 v190, v190
	v_exp_f32_e32 v191, v191
	s_waitcnt vmcnt(12)
	ds_write_b128 v247, v[116:119]
	ds_write_b128 v247, v[120:123] offset:1024
	ds_write_b128 v247, v[124:127] offset:2048
	ds_write_b128 v247, v[128:131] offset:3072
	ds_read_b128 v[116:119], v248
	ds_read_b128 v[120:123], v249
	ds_read_b128 v[124:127], v250
	ds_read_b128 v[128:131], v251
	s_waitcnt vmcnt(8)
	ds_write_b128 v112, v[132:135]
	ds_write_b128 v112, v[136:139] offset:1024
	ds_write_b128 v112, v[140:143] offset:2048
	ds_write_b128 v112, v[144:147] offset:3072
	v_exp_f32_e32 v192, v192
	v_exp_f32_e32 v193, v193
	v_exp_f32_e32 v194, v194
	v_exp_f32_e32 v195, v195
	s_waitcnt lgkmcnt(4)
	v_mfma_f32_32x32x16_bf16 v[32:47], v[116:119], v[48:51], v[32:47]
	v_exp_f32_e32 v196, v196
	v_exp_f32_e32 v197, v197
	v_mfma_f32_32x32x16_bf16 v[32:47], v[120:123], v[52:55], v[32:47]
	v_exp_f32_e32 v198, v198
	v_exp_f32_e32 v199, v199
	v_mfma_f32_32x32x16_bf16 v[32:47], v[124:127], v[56:59], v[32:47]
	v_exp_f32_e32 v200, v200
	v_exp_f32_e32 v201, v201
	v_mfma_f32_32x32x16_bf16 v[32:47], v[128:131], v[60:63], v[32:47]
	v_exp_f32_e32 v202, v202
	v_exp_f32_e32 v203, v203
	s_add_i32 s90, s67, -32
	v_add_u32_e32 v84, s90, v107
	v_add_u32_e32 v85, 0, v84
	v_add_u32_e32 v86, 1, v84
	v_add_u32_e32 v87, 2, v84
	v_add_u32_e32 v88, 3, v84
	v_cmp_gt_u32_e64 s[30:31], s98, v85
	v_cmp_gt_u32_e64 s[36:37], s98, v86
	v_cmp_gt_u32_e64 s[78:79], s98, v87
	v_cmp_gt_u32_e64 s[50:51], s98, v88
	v_cndmask_b32_e64 v188, 0, v188, s[30:31]
	v_add_u32_e32 v85, 8, v84
	v_cmp_gt_u32_e64 s[30:31], s98, v85
	v_cndmask_b32_e64 v189, 0, v189, s[36:37]
	v_add_u32_e32 v86, 9, v84
	v_cmp_gt_u32_e64 s[36:37], s98, v86
	v_cndmask_b32_e64 v190, 0, v190, s[78:79]
	v_add_u32_e32 v87, 10, v84
	v_cmp_gt_u32_e64 s[78:79], s98, v87
	v_cndmask_b32_e64 v191, 0, v191, s[50:51]
	v_add_u32_e32 v88, 11, v84
	v_cmp_gt_u32_e64 s[50:51], s98, v88
	v_cndmask_b32_e64 v192, 0, v192, s[30:31]
	v_add_u32_e32 v85, 16, v84
	v_cmp_gt_u32_e64 s[30:31], s98, v85
	v_cndmask_b32_e64 v193, 0, v193, s[36:37]
	v_add_u32_e32 v86, 17, v84
	v_cmp_gt_u32_e64 s[36:37], s98, v86
	v_cndmask_b32_e64 v194, 0, v194, s[78:79]
	v_add_u32_e32 v87, 18, v84
	v_cmp_gt_u32_e64 s[78:79], s98, v87
	v_cndmask_b32_e64 v195, 0, v195, s[50:51]
	v_add_u32_e32 v88, 19, v84
	v_cmp_gt_u32_e64 s[50:51], s98, v88
	v_cndmask_b32_e64 v196, 0, v196, s[30:31]
	v_add_u32_e32 v85, 24, v84
	v_cmp_gt_u32_e64 s[30:31], s98, v85
	v_cndmask_b32_e64 v197, 0, v197, s[36:37]
	v_add_u32_e32 v86, 25, v84
	v_cmp_gt_u32_e64 s[36:37], s98, v86
	v_cndmask_b32_e64 v198, 0, v198, s[78:79]
	v_add_u32_e32 v87, 26, v84
	v_cmp_gt_u32_e64 s[78:79], s98, v87
	v_cndmask_b32_e64 v199, 0, v199, s[50:51]
	v_add_u32_e32 v88, 27, v84
	v_cmp_gt_u32_e64 s[50:51], s98, v88
	v_nop
	v_cndmask_b32_e64 v200, 0, v200, s[30:31]
	v_cndmask_b32_e64 v201, 0, v201, s[36:37]
	v_cndmask_b32_e64 v202, 0, v202, s[78:79]
	v_cndmask_b32_e64 v203, 0, v203, s[50:51]
	v_cvt_pk_bf16_f32 v64, v188, v189
	v_cvt_pk_bf16_f32 v65, v190, v191
	v_cvt_pk_bf16_f32 v66, v192, v193
	v_cvt_pk_bf16_f32 v67, v194, v195
	v_cvt_pk_bf16_f32 v68, v196, v197
	v_cvt_pk_bf16_f32 v69, v198, v199
	v_cvt_pk_bf16_f32 v70, v200, v201
	v_cvt_pk_bf16_f32 v71, v202, v203
	v_pk_add_f32 v[232:233], v[232:233], v[188:189]
	v_pk_add_f32 v[232:233], v[232:233], v[190:191]
	v_pk_add_f32 v[232:233], v[232:233], v[192:193]
	v_pk_add_f32 v[232:233], v[232:233], v[194:195]
	v_pk_add_f32 v[232:233], v[232:233], v[196:197]
	v_pk_add_f32 v[232:233], v[232:233], v[198:199]
	v_pk_add_f32 v[232:233], v[232:233], v[200:201]
	v_pk_add_f32 v[232:233], v[232:233], v[202:203]
	ds_read2_b32 v[188:189], v115 offset0:102 offset1:103
	ds_read2_b32 v[190:191], v115 offset0:104 offset1:105
	ds_read2_b32 v[192:193], v115 offset0:110 offset1:111
	ds_read2_b32 v[194:195], v115 offset0:112 offset1:113
	ds_read2_b32 v[196:197], v115 offset0:119 offset1:120
	ds_read2_b32 v[198:199], v115 offset0:121 offset1:122
	ds_read2_b32 v[200:201], v115 offset0:127 offset1:128
	ds_read2_b32 v[202:203], v115 offset0:129 offset1:130
	v_mfma_f32_32x32x16_bf16 v[0:15], v[64:67], v[72:75], v[0:15]
	v_mfma_f32_32x32x16_bf16 v[16:31], v[64:67], v[76:79], v[16:31]
	v_mfma_f32_32x32x16_bf16 v[0:15], v[68:71], v[220:223], v[0:15]
	v_mfma_f32_32x32x16_bf16 v[16:31], v[68:71], v[224:227], v[16:31]
	s_add_i32 s90, s67, 64
	v_add_u32_e32 v80, s90, v235
	v_add_u32_e32 v83, s90, v236
	v_add_u32_e32 v99, s90, v237
	v_add_u32_e32 v253, s90, v238
	v_add_u32_e32 v254, s90, v100
	v_add_u32_e32 v255, s90, v149
	v_med3_i32 v80, v80, 0, s99
	v_med3_i32 v83, v83, 0, s99
	v_med3_i32 v99, v99, 0, s99
	v_med3_i32 v253, v253, 0, s99
	v_med3_i32 v254, v254, 0, s99
	v_med3_i32 v255, v255, 0, s99
	v_mad_u32_u24 v80, v80, s100, v252
	v_mad_u32_u24 v83, v83, s100, v252
	v_mad_u32_u24 v99, v99, s100, v252
	v_mad_u32_u24 v253, v253, s100, v252
	v_mad_u32_u24 v254, v254, s100, v153
	v_mad_u32_u24 v255, v255, s100, v153
	global_load_dwordx4 v[116:119], v80, s[82:83]
	global_load_dwordx4 v[120:123], v83, s[82:83]
	global_load_dwordx4 v[124:127], v99, s[82:83]
	global_load_dwordx4 v[128:131], v253, s[82:83]
	global_load_dwordx4 v[132:135], v254, s[82:83] offset:768
	global_load_dwordx4 v[136:139], v255, s[82:83] offset:768
	global_load_dwordx4 v[140:143], v254, s[82:83] offset:832
	global_load_dwordx4 v[144:147], v255, s[82:83] offset:832
	ds_read_b64_tr_b16 v[72:73], v231
	ds_read_b64_tr_b16 v[74:75], v231 offset:512
	ds_read_b64_tr_b16 v[76:77], v231 offset:2048
	ds_read_b64_tr_b16 v[78:79], v231 offset:2560
	ds_read_b64_tr_b16 v[220:221], v231 offset:1024
	ds_read_b64_tr_b16 v[222:223], v231 offset:1536
	ds_read_b64_tr_b16 v[224:225], v231 offset:3072
	ds_read_b64_tr_b16 v[226:227], v231 offset:3584
	v_exp_f32_e32 v32, v32
	v_exp_f32_e32 v33, v33
	v_exp_f32_e32 v34, v34
	v_exp_f32_e32 v35, v35
	s_waitcnt vmcnt(12)
	ds_write_b128 v247, v[156:159]
	ds_write_b128 v247, v[160:163] offset:1024
	ds_write_b128 v247, v[164:167] offset:2048
	ds_write_b128 v247, v[168:171] offset:3072
	ds_read_b128 v[156:159], v248
	ds_read_b128 v[160:163], v249
	ds_read_b128 v[164:167], v250
	ds_read_b128 v[168:171], v251
	s_waitcnt vmcnt(8)
	ds_write_b128 v112, v[172:175]
	ds_write_b128 v112, v[176:179] offset:1024
	ds_write_b128 v112, v[180:183] offset:2048
	ds_write_b128 v112, v[184:187] offset:3072
	v_exp_f32_e32 v36, v36
	v_exp_f32_e32 v37, v37
	v_exp_f32_e32 v38, v38
	v_exp_f32_e32 v39, v39
	s_waitcnt lgkmcnt(4)
	v_mfma_f32_32x32x16_bf16 v[188:203], v[156:159], v[48:51], v[188:203]
	v_exp_f32_e32 v40, v40
	v_exp_f32_e32 v41, v41
	v_mfma_f32_32x32x16_bf16 v[188:203], v[160:163], v[52:55], v[188:203]
	v_exp_f32_e32 v42, v42
	v_exp_f32_e32 v43, v43
	v_mfma_f32_32x32x16_bf16 v[188:203], v[164:167], v[56:59], v[188:203]
	v_exp_f32_e32 v44, v44
	v_exp_f32_e32 v45, v45
	v_mfma_f32_32x32x16_bf16 v[188:203], v[168:171], v[60:63], v[188:203]
	v_exp_f32_e32 v46, v46
	v_exp_f32_e32 v47, v47
	s_add_i32 s90, s67, 0
	v_add_u32_e32 v84, s90, v107
	v_add_u32_e32 v85, 0, v84
	v_add_u32_e32 v86, 1, v84
	v_add_u32_e32 v87, 2, v84
	v_add_u32_e32 v88, 3, v84
	v_cmp_gt_u32_e64 s[30:31], s98, v85
	v_cmp_gt_u32_e64 s[36:37], s98, v86
	v_cmp_gt_u32_e64 s[78:79], s98, v87
	v_cmp_gt_u32_e64 s[50:51], s98, v88
	v_cndmask_b32_e64 v32, 0, v32, s[30:31]
	v_add_u32_e32 v85, 8, v84
	v_cmp_gt_u32_e64 s[30:31], s98, v85
	v_cndmask_b32_e64 v33, 0, v33, s[36:37]
	v_add_u32_e32 v86, 9, v84
	v_cmp_gt_u32_e64 s[36:37], s98, v86
	v_cndmask_b32_e64 v34, 0, v34, s[78:79]
	v_add_u32_e32 v87, 10, v84
	v_cmp_gt_u32_e64 s[78:79], s98, v87
	v_cndmask_b32_e64 v35, 0, v35, s[50:51]
	v_add_u32_e32 v88, 11, v84
	v_cmp_gt_u32_e64 s[50:51], s98, v88
	v_cndmask_b32_e64 v36, 0, v36, s[30:31]
	v_add_u32_e32 v85, 16, v84
	v_cmp_gt_u32_e64 s[30:31], s98, v85
	v_cndmask_b32_e64 v37, 0, v37, s[36:37]
	v_add_u32_e32 v86, 17, v84
	v_cmp_gt_u32_e64 s[36:37], s98, v86
	v_cndmask_b32_e64 v38, 0, v38, s[78:79]
	v_add_u32_e32 v87, 18, v84
	v_cmp_gt_u32_e64 s[78:79], s98, v87
	v_cndmask_b32_e64 v39, 0, v39, s[50:51]
	v_add_u32_e32 v88, 19, v84
	v_cmp_gt_u32_e64 s[50:51], s98, v88
	v_cndmask_b32_e64 v40, 0, v40, s[30:31]
	v_add_u32_e32 v85, 24, v84
	v_cmp_gt_u32_e64 s[30:31], s98, v85
	v_cndmask_b32_e64 v41, 0, v41, s[36:37]
	v_add_u32_e32 v86, 25, v84
	v_cmp_gt_u32_e64 s[36:37], s98, v86
	v_cndmask_b32_e64 v42, 0, v42, s[78:79]
	v_add_u32_e32 v87, 26, v84
	v_cmp_gt_u32_e64 s[78:79], s98, v87
	v_cndmask_b32_e64 v43, 0, v43, s[50:51]
	v_add_u32_e32 v88, 27, v84
	v_cmp_gt_u32_e64 s[50:51], s98, v88
	v_nop
	v_cndmask_b32_e64 v44, 0, v44, s[30:31]
	v_cndmask_b32_e64 v45, 0, v45, s[36:37]
	v_cndmask_b32_e64 v46, 0, v46, s[78:79]
	v_cndmask_b32_e64 v47, 0, v47, s[50:51]
	v_cvt_pk_bf16_f32 v64, v32, v33
	v_cvt_pk_bf16_f32 v65, v34, v35
	v_cvt_pk_bf16_f32 v66, v36, v37
	v_cvt_pk_bf16_f32 v67, v38, v39
	v_cvt_pk_bf16_f32 v68, v40, v41
	v_cvt_pk_bf16_f32 v69, v42, v43
	v_cvt_pk_bf16_f32 v70, v44, v45
	v_cvt_pk_bf16_f32 v71, v46, v47
	v_pk_add_f32 v[232:233], v[232:233], v[32:33]
	v_pk_add_f32 v[232:233], v[232:233], v[34:35]
	v_pk_add_f32 v[232:233], v[232:233], v[36:37]
	v_pk_add_f32 v[232:233], v[232:233], v[38:39]
	v_pk_add_f32 v[232:233], v[232:233], v[40:41]
	v_pk_add_f32 v[232:233], v[232:233], v[42:43]
	v_pk_add_f32 v[232:233], v[232:233], v[44:45]
	v_pk_add_f32 v[232:233], v[232:233], v[46:47]
	ds_read2_b32 v[32:33], v115 offset0:136 offset1:137
	ds_read2_b32 v[34:35], v115 offset0:138 offset1:139
	ds_read2_b32 v[36:37], v115 offset0:144 offset1:145
	ds_read2_b32 v[38:39], v115 offset0:146 offset1:147
	ds_read2_b32 v[40:41], v115 offset0:153 offset1:154
	ds_read2_b32 v[42:43], v115 offset0:155 offset1:156
	ds_read2_b32 v[44:45], v115 offset0:161 offset1:162
	ds_read2_b32 v[46:47], v115 offset0:163 offset1:164
	v_mfma_f32_32x32x16_bf16 v[0:15], v[64:67], v[72:75], v[0:15]
	v_mfma_f32_32x32x16_bf16 v[16:31], v[64:67], v[76:79], v[16:31]
	v_mfma_f32_32x32x16_bf16 v[0:15], v[68:71], v[220:223], v[0:15]
	v_mfma_f32_32x32x16_bf16 v[16:31], v[68:71], v[224:227], v[16:31]
	s_add_i32 s90, s67, 96
	v_add_u32_e32 v80, s90, v235
	v_add_u32_e32 v83, s90, v236
	v_add_u32_e32 v99, s90, v237
	v_add_u32_e32 v253, s90, v238
	v_add_u32_e32 v254, s90, v100
	v_add_u32_e32 v255, s90, v149
	v_med3_i32 v80, v80, 0, s99
	v_med3_i32 v83, v83, 0, s99
	v_med3_i32 v99, v99, 0, s99
	v_med3_i32 v253, v253, 0, s99
	v_med3_i32 v254, v254, 0, s99
	v_med3_i32 v255, v255, 0, s99
	v_mad_u32_u24 v80, v80, s100, v252
	v_mad_u32_u24 v83, v83, s100, v252
	v_mad_u32_u24 v99, v99, s100, v252
	v_mad_u32_u24 v253, v253, s100, v252
	v_mad_u32_u24 v254, v254, s100, v153
	v_mad_u32_u24 v255, v255, s100, v153
	global_load_dwordx4 v[156:159], v80, s[82:83]
	global_load_dwordx4 v[160:163], v83, s[82:83]
	global_load_dwordx4 v[164:167], v99, s[82:83]
	global_load_dwordx4 v[168:171], v253, s[82:83]
	global_load_dwordx4 v[172:175], v254, s[82:83] offset:768
	global_load_dwordx4 v[176:179], v255, s[82:83] offset:768
	global_load_dwordx4 v[180:183], v254, s[82:83] offset:832
	global_load_dwordx4 v[184:187], v255, s[82:83] offset:832
	ds_read_b64_tr_b16 v[72:73], v231
	ds_read_b64_tr_b16 v[74:75], v231 offset:512
	ds_read_b64_tr_b16 v[76:77], v231 offset:2048
	ds_read_b64_tr_b16 v[78:79], v231 offset:2560
	ds_read_b64_tr_b16 v[220:221], v231 offset:1024
	ds_read_b64_tr_b16 v[222:223], v231 offset:1536
	ds_read_b64_tr_b16 v[224:225], v231 offset:3072
	ds_read_b64_tr_b16 v[226:227], v231 offset:3584
	v_exp_f32_e32 v188, v188
	v_exp_f32_e32 v189, v189
	v_exp_f32_e32 v190, v190
	v_exp_f32_e32 v191, v191
	s_waitcnt vmcnt(12)
	ds_write_b128 v247, v[116:119]
	ds_write_b128 v247, v[120:123] offset:1024
	ds_write_b128 v247, v[124:127] offset:2048
	ds_write_b128 v247, v[128:131] offset:3072
	ds_read_b128 v[116:119], v248
	ds_read_b128 v[120:123], v249
	ds_read_b128 v[124:127], v250
	ds_read_b128 v[128:131], v251
	s_waitcnt vmcnt(8)
	ds_write_b128 v112, v[132:135]
	ds_write_b128 v112, v[136:139] offset:1024
	ds_write_b128 v112, v[140:143] offset:2048
	ds_write_b128 v112, v[144:147] offset:3072
	v_exp_f32_e32 v192, v192
	v_exp_f32_e32 v193, v193
	v_exp_f32_e32 v194, v194
	v_exp_f32_e32 v195, v195
	s_waitcnt lgkmcnt(4)
	v_mfma_f32_32x32x16_bf16 v[32:47], v[116:119], v[48:51], v[32:47]
	v_exp_f32_e32 v196, v196
	v_exp_f32_e32 v197, v197
	v_mfma_f32_32x32x16_bf16 v[32:47], v[120:123], v[52:55], v[32:47]
	v_exp_f32_e32 v198, v198
	v_exp_f32_e32 v199, v199
	v_mfma_f32_32x32x16_bf16 v[32:47], v[124:127], v[56:59], v[32:47]
	v_exp_f32_e32 v200, v200
	v_exp_f32_e32 v201, v201
	v_mfma_f32_32x32x16_bf16 v[32:47], v[128:131], v[60:63], v[32:47]
	v_exp_f32_e32 v202, v202
	v_exp_f32_e32 v203, v203
	s_add_i32 s90, s67, 32
	v_add_u32_e32 v84, s90, v107
	v_add_u32_e32 v85, 0, v84
	v_add_u32_e32 v86, 1, v84
	v_add_u32_e32 v87, 2, v84
	v_add_u32_e32 v88, 3, v84
	v_cmp_gt_u32_e64 s[30:31], s98, v85
	v_cmp_gt_u32_e64 s[36:37], s98, v86
	v_cmp_gt_u32_e64 s[78:79], s98, v87
	v_cmp_gt_u32_e64 s[50:51], s98, v88
	v_cndmask_b32_e64 v188, 0, v188, s[30:31]
	v_add_u32_e32 v85, 8, v84
	v_cmp_gt_u32_e64 s[30:31], s98, v85
	v_cndmask_b32_e64 v189, 0, v189, s[36:37]
	v_add_u32_e32 v86, 9, v84
	v_cmp_gt_u32_e64 s[36:37], s98, v86
	v_cndmask_b32_e64 v190, 0, v190, s[78:79]
	v_add_u32_e32 v87, 10, v84
	v_cmp_gt_u32_e64 s[78:79], s98, v87
	v_cndmask_b32_e64 v191, 0, v191, s[50:51]
	v_add_u32_e32 v88, 11, v84
	v_cmp_gt_u32_e64 s[50:51], s98, v88
	v_cndmask_b32_e64 v192, 0, v192, s[30:31]
	v_add_u32_e32 v85, 16, v84
	v_cmp_gt_u32_e64 s[30:31], s98, v85
	v_cndmask_b32_e64 v193, 0, v193, s[36:37]
	v_add_u32_e32 v86, 17, v84
	v_cmp_gt_u32_e64 s[36:37], s98, v86
	v_cndmask_b32_e64 v194, 0, v194, s[78:79]
	v_add_u32_e32 v87, 18, v84
	v_cmp_gt_u32_e64 s[78:79], s98, v87
	v_cndmask_b32_e64 v195, 0, v195, s[50:51]
	v_add_u32_e32 v88, 19, v84
	v_cmp_gt_u32_e64 s[50:51], s98, v88
	v_cndmask_b32_e64 v196, 0, v196, s[30:31]
	v_add_u32_e32 v85, 24, v84
	v_cmp_gt_u32_e64 s[30:31], s98, v85
	v_cndmask_b32_e64 v197, 0, v197, s[36:37]
	v_add_u32_e32 v86, 25, v84
	v_cmp_gt_u32_e64 s[36:37], s98, v86
	v_cndmask_b32_e64 v198, 0, v198, s[78:79]
	v_add_u32_e32 v87, 26, v84
	v_cmp_gt_u32_e64 s[78:79], s98, v87
	v_cndmask_b32_e64 v199, 0, v199, s[50:51]
	v_add_u32_e32 v88, 27, v84
	v_cmp_gt_u32_e64 s[50:51], s98, v88
	v_nop
	v_cndmask_b32_e64 v200, 0, v200, s[30:31]
	v_cndmask_b32_e64 v201, 0, v201, s[36:37]
	v_cndmask_b32_e64 v202, 0, v202, s[78:79]
	v_cndmask_b32_e64 v203, 0, v203, s[50:51]
	v_cvt_pk_bf16_f32 v64, v188, v189
	v_cvt_pk_bf16_f32 v65, v190, v191
	v_cvt_pk_bf16_f32 v66, v192, v193
	v_cvt_pk_bf16_f32 v67, v194, v195
	v_cvt_pk_bf16_f32 v68, v196, v197
	v_cvt_pk_bf16_f32 v69, v198, v199
	v_cvt_pk_bf16_f32 v70, v200, v201
	v_cvt_pk_bf16_f32 v71, v202, v203
	v_pk_add_f32 v[232:233], v[232:233], v[188:189]
	v_pk_add_f32 v[232:233], v[232:233], v[190:191]
	v_pk_add_f32 v[232:233], v[232:233], v[192:193]
	v_pk_add_f32 v[232:233], v[232:233], v[194:195]
	v_pk_add_f32 v[232:233], v[232:233], v[196:197]
	v_pk_add_f32 v[232:233], v[232:233], v[198:199]
	v_pk_add_f32 v[232:233], v[232:233], v[200:201]
	v_pk_add_f32 v[232:233], v[232:233], v[202:203]
	ds_read2_b32 v[188:189], v115 offset0:170 offset1:171
	ds_read2_b32 v[190:191], v115 offset0:172 offset1:173
	ds_read2_b32 v[192:193], v115 offset0:178 offset1:179
	ds_read2_b32 v[194:195], v115 offset0:180 offset1:181
	ds_read2_b32 v[196:197], v115 offset0:187 offset1:188
	ds_read2_b32 v[198:199], v115 offset0:189 offset1:190
	ds_read2_b32 v[200:201], v115 offset0:195 offset1:196
	ds_read2_b32 v[202:203], v115 offset0:197 offset1:198
	v_mfma_f32_32x32x16_bf16 v[0:15], v[64:67], v[72:75], v[0:15]
	v_mfma_f32_32x32x16_bf16 v[16:31], v[64:67], v[76:79], v[16:31]
	v_mfma_f32_32x32x16_bf16 v[0:15], v[68:71], v[220:223], v[0:15]
	v_mfma_f32_32x32x16_bf16 v[16:31], v[68:71], v[224:227], v[16:31]
	s_add_i32 s90, s67, 128
	v_add_u32_e32 v80, s90, v235
	v_add_u32_e32 v83, s90, v236
	v_add_u32_e32 v99, s90, v237
	v_add_u32_e32 v253, s90, v238
	v_add_u32_e32 v254, s90, v100
	v_add_u32_e32 v255, s90, v149
	v_med3_i32 v80, v80, 0, s99
	v_med3_i32 v83, v83, 0, s99
	v_med3_i32 v99, v99, 0, s99
	v_med3_i32 v253, v253, 0, s99
	v_med3_i32 v254, v254, 0, s99
	v_med3_i32 v255, v255, 0, s99
	v_mad_u32_u24 v80, v80, s100, v252
	v_mad_u32_u24 v83, v83, s100, v252
	v_mad_u32_u24 v99, v99, s100, v252
	v_mad_u32_u24 v253, v253, s100, v252
	v_mad_u32_u24 v254, v254, s100, v153
	v_mad_u32_u24 v255, v255, s100, v153
	global_load_dwordx4 v[116:119], v80, s[82:83]
	global_load_dwordx4 v[120:123], v83, s[82:83]
	global_load_dwordx4 v[124:127], v99, s[82:83]
	global_load_dwordx4 v[128:131], v253, s[82:83]
	global_load_dwordx4 v[132:135], v254, s[82:83] offset:768
	global_load_dwordx4 v[136:139], v255, s[82:83] offset:768
	global_load_dwordx4 v[140:143], v254, s[82:83] offset:832
	global_load_dwordx4 v[144:147], v255, s[82:83] offset:832
	ds_read_b64_tr_b16 v[72:73], v231
	ds_read_b64_tr_b16 v[74:75], v231 offset:512
	ds_read_b64_tr_b16 v[76:77], v231 offset:2048
	ds_read_b64_tr_b16 v[78:79], v231 offset:2560
	ds_read_b64_tr_b16 v[220:221], v231 offset:1024
	ds_read_b64_tr_b16 v[222:223], v231 offset:1536
	ds_read_b64_tr_b16 v[224:225], v231 offset:3072
	ds_read_b64_tr_b16 v[226:227], v231 offset:3584
	v_exp_f32_e32 v32, v32
	v_exp_f32_e32 v33, v33
	v_exp_f32_e32 v34, v34
	v_exp_f32_e32 v35, v35
	s_waitcnt vmcnt(12)
	ds_write_b128 v247, v[156:159]
	ds_write_b128 v247, v[160:163] offset:1024
	ds_write_b128 v247, v[164:167] offset:2048
	ds_write_b128 v247, v[168:171] offset:3072
	ds_read_b128 v[156:159], v248
	ds_read_b128 v[160:163], v249
	ds_read_b128 v[164:167], v250
	ds_read_b128 v[168:171], v251
	s_waitcnt vmcnt(8)
	ds_write_b128 v112, v[172:175]
	ds_write_b128 v112, v[176:179] offset:1024
	ds_write_b128 v112, v[180:183] offset:2048
	ds_write_b128 v112, v[184:187] offset:3072
	v_exp_f32_e32 v36, v36
	v_exp_f32_e32 v37, v37
	v_exp_f32_e32 v38, v38
	v_exp_f32_e32 v39, v39
	s_waitcnt lgkmcnt(4)
	v_mfma_f32_32x32x16_bf16 v[188:203], v[156:159], v[48:51], v[188:203]
	v_exp_f32_e32 v40, v40
	v_exp_f32_e32 v41, v41
	v_mfma_f32_32x32x16_bf16 v[188:203], v[160:163], v[52:55], v[188:203]
	v_exp_f32_e32 v42, v42
	v_exp_f32_e32 v43, v43
	v_mfma_f32_32x32x16_bf16 v[188:203], v[164:167], v[56:59], v[188:203]
	v_exp_f32_e32 v44, v44
	v_exp_f32_e32 v45, v45
	v_mfma_f32_32x32x16_bf16 v[188:203], v[168:171], v[60:63], v[188:203]
	v_exp_f32_e32 v46, v46
	v_exp_f32_e32 v47, v47
	s_add_i32 s90, s67, 64
	v_add_u32_e32 v84, s90, v107
	v_add_u32_e32 v85, 0, v84
	v_add_u32_e32 v86, 1, v84
	v_add_u32_e32 v87, 2, v84
	v_add_u32_e32 v88, 3, v84
	v_cmp_gt_u32_e64 s[30:31], s98, v85
	v_cmp_gt_u32_e64 s[36:37], s98, v86
	v_cmp_gt_u32_e64 s[78:79], s98, v87
	v_cmp_gt_u32_e64 s[50:51], s98, v88
	v_cndmask_b32_e64 v32, 0, v32, s[30:31]
	v_add_u32_e32 v85, 8, v84
	v_cmp_gt_u32_e64 s[30:31], s98, v85
	v_cndmask_b32_e64 v33, 0, v33, s[36:37]
	v_add_u32_e32 v86, 9, v84
	v_cmp_gt_u32_e64 s[36:37], s98, v86
	v_cndmask_b32_e64 v34, 0, v34, s[78:79]
	v_add_u32_e32 v87, 10, v84
	v_cmp_gt_u32_e64 s[78:79], s98, v87
	v_cndmask_b32_e64 v35, 0, v35, s[50:51]
	v_add_u32_e32 v88, 11, v84
	v_cmp_gt_u32_e64 s[50:51], s98, v88
	v_cndmask_b32_e64 v36, 0, v36, s[30:31]
	v_add_u32_e32 v85, 16, v84
	v_cmp_gt_u32_e64 s[30:31], s98, v85
	v_cndmask_b32_e64 v37, 0, v37, s[36:37]
	v_add_u32_e32 v86, 17, v84
	v_cmp_gt_u32_e64 s[36:37], s98, v86
	v_cndmask_b32_e64 v38, 0, v38, s[78:79]
	v_add_u32_e32 v87, 18, v84
	v_cmp_gt_u32_e64 s[78:79], s98, v87
	v_cndmask_b32_e64 v39, 0, v39, s[50:51]
	v_add_u32_e32 v88, 19, v84
	v_cmp_gt_u32_e64 s[50:51], s98, v88
	v_cndmask_b32_e64 v40, 0, v40, s[30:31]
	v_add_u32_e32 v85, 24, v84
	v_cmp_gt_u32_e64 s[30:31], s98, v85
	v_cndmask_b32_e64 v41, 0, v41, s[36:37]
	v_add_u32_e32 v86, 25, v84
	v_cmp_gt_u32_e64 s[36:37], s98, v86
	v_cndmask_b32_e64 v42, 0, v42, s[78:79]
	v_add_u32_e32 v87, 26, v84
	v_cmp_gt_u32_e64 s[78:79], s98, v87
	v_cndmask_b32_e64 v43, 0, v43, s[50:51]
	v_add_u32_e32 v88, 27, v84
	v_cmp_gt_u32_e64 s[50:51], s98, v88
	v_nop
	v_cndmask_b32_e64 v44, 0, v44, s[30:31]
	v_cndmask_b32_e64 v45, 0, v45, s[36:37]
	v_cndmask_b32_e64 v46, 0, v46, s[78:79]
	v_cndmask_b32_e64 v47, 0, v47, s[50:51]
	v_cvt_pk_bf16_f32 v64, v32, v33
	v_cvt_pk_bf16_f32 v65, v34, v35
	v_cvt_pk_bf16_f32 v66, v36, v37
	v_cvt_pk_bf16_f32 v67, v38, v39
	v_cvt_pk_bf16_f32 v68, v40, v41
	v_cvt_pk_bf16_f32 v69, v42, v43
	v_cvt_pk_bf16_f32 v70, v44, v45
	v_cvt_pk_bf16_f32 v71, v46, v47
	v_pk_add_f32 v[232:233], v[232:233], v[32:33]
	v_pk_add_f32 v[232:233], v[232:233], v[34:35]
	v_pk_add_f32 v[232:233], v[232:233], v[36:37]
	v_pk_add_f32 v[232:233], v[232:233], v[38:39]
	v_pk_add_f32 v[232:233], v[232:233], v[40:41]
	v_pk_add_f32 v[232:233], v[232:233], v[42:43]
	v_pk_add_f32 v[232:233], v[232:233], v[44:45]
	v_pk_add_f32 v[232:233], v[232:233], v[46:47]
	ds_read2_b32 v[32:33], v115 offset0:204 offset1:205
	ds_read2_b32 v[34:35], v115 offset0:206 offset1:207
	ds_read2_b32 v[36:37], v115 offset0:212 offset1:213
	ds_read2_b32 v[38:39], v115 offset0:214 offset1:215
	ds_read2_b32 v[40:41], v115 offset0:221 offset1:222
	ds_read2_b32 v[42:43], v115 offset0:223 offset1:224
	ds_read2_b32 v[44:45], v115 offset0:229 offset1:230
	ds_read2_b32 v[46:47], v115 offset0:231 offset1:232
	v_mfma_f32_32x32x16_bf16 v[0:15], v[64:67], v[72:75], v[0:15]
	v_mfma_f32_32x32x16_bf16 v[16:31], v[64:67], v[76:79], v[16:31]
	v_mfma_f32_32x32x16_bf16 v[0:15], v[68:71], v[220:223], v[0:15]
	v_mfma_f32_32x32x16_bf16 v[16:31], v[68:71], v[224:227], v[16:31]
	s_add_i32 s90, s67, 160
	v_add_u32_e32 v80, s90, v235
	v_add_u32_e32 v83, s90, v236
	v_add_u32_e32 v99, s90, v237
	v_add_u32_e32 v253, s90, v238
	v_add_u32_e32 v254, s90, v100
	v_add_u32_e32 v255, s90, v149
	v_med3_i32 v80, v80, 0, s99
	v_med3_i32 v83, v83, 0, s99
	v_med3_i32 v99, v99, 0, s99
	v_med3_i32 v253, v253, 0, s99
	v_med3_i32 v254, v254, 0, s99
	v_med3_i32 v255, v255, 0, s99
	v_mad_u32_u24 v80, v80, s100, v252
	v_mad_u32_u24 v83, v83, s100, v252
	v_mad_u32_u24 v99, v99, s100, v252
	v_mad_u32_u24 v253, v253, s100, v252
	v_mad_u32_u24 v254, v254, s100, v153
	v_mad_u32_u24 v255, v255, s100, v153
	global_load_dwordx4 v[156:159], v80, s[82:83]
	global_load_dwordx4 v[160:163], v83, s[82:83]
	global_load_dwordx4 v[164:167], v99, s[82:83]
	global_load_dwordx4 v[168:171], v253, s[82:83]
	global_load_dwordx4 v[172:175], v254, s[82:83] offset:768
	global_load_dwordx4 v[176:179], v255, s[82:83] offset:768
	global_load_dwordx4 v[180:183], v254, s[82:83] offset:832
	global_load_dwordx4 v[184:187], v255, s[82:83] offset:832
	ds_read_b64_tr_b16 v[72:73], v231
	ds_read_b64_tr_b16 v[74:75], v231 offset:512
	ds_read_b64_tr_b16 v[76:77], v231 offset:2048
	ds_read_b64_tr_b16 v[78:79], v231 offset:2560
	ds_read_b64_tr_b16 v[220:221], v231 offset:1024
	ds_read_b64_tr_b16 v[222:223], v231 offset:1536
	ds_read_b64_tr_b16 v[224:225], v231 offset:3072
	ds_read_b64_tr_b16 v[226:227], v231 offset:3584
	v_exp_f32_e32 v188, v188
	v_exp_f32_e32 v189, v189
	v_exp_f32_e32 v190, v190
	v_exp_f32_e32 v191, v191
	s_waitcnt vmcnt(12)
	ds_write_b128 v247, v[116:119]
	ds_write_b128 v247, v[120:123] offset:1024
	ds_write_b128 v247, v[124:127] offset:2048
	ds_write_b128 v247, v[128:131] offset:3072
	ds_read_b128 v[116:119], v248
	ds_read_b128 v[120:123], v249
	ds_read_b128 v[124:127], v250
	ds_read_b128 v[128:131], v251
	s_waitcnt vmcnt(8)
	ds_write_b128 v112, v[132:135]
	ds_write_b128 v112, v[136:139] offset:1024
	ds_write_b128 v112, v[140:143] offset:2048
	ds_write_b128 v112, v[144:147] offset:3072
	v_exp_f32_e32 v192, v192
	v_exp_f32_e32 v193, v193
	v_exp_f32_e32 v194, v194
	v_exp_f32_e32 v195, v195
	s_waitcnt lgkmcnt(4)
	v_mfma_f32_32x32x16_bf16 v[32:47], v[116:119], v[48:51], v[32:47]
	v_exp_f32_e32 v196, v196
	v_exp_f32_e32 v197, v197
	v_mfma_f32_32x32x16_bf16 v[32:47], v[120:123], v[52:55], v[32:47]
	v_exp_f32_e32 v198, v198
	v_exp_f32_e32 v199, v199
	v_mfma_f32_32x32x16_bf16 v[32:47], v[124:127], v[56:59], v[32:47]
	v_exp_f32_e32 v200, v200
	v_exp_f32_e32 v201, v201
	v_mfma_f32_32x32x16_bf16 v[32:47], v[128:131], v[60:63], v[32:47]
	v_exp_f32_e32 v202, v202
	v_exp_f32_e32 v203, v203
	s_add_i32 s90, s67, 96
	v_add_u32_e32 v84, s90, v107
	v_add_u32_e32 v85, 0, v84
	v_add_u32_e32 v86, 1, v84
	v_add_u32_e32 v87, 2, v84
	v_add_u32_e32 v88, 3, v84
	v_cmp_gt_u32_e64 s[30:31], s98, v85
	v_cmp_gt_u32_e64 s[36:37], s98, v86
	v_cmp_gt_u32_e64 s[78:79], s98, v87
	v_cmp_gt_u32_e64 s[50:51], s98, v88
	v_cndmask_b32_e64 v188, 0, v188, s[30:31]
	v_add_u32_e32 v85, 8, v84
	v_cmp_gt_u32_e64 s[30:31], s98, v85
	v_cndmask_b32_e64 v189, 0, v189, s[36:37]
	v_add_u32_e32 v86, 9, v84
	v_cmp_gt_u32_e64 s[36:37], s98, v86
	v_cndmask_b32_e64 v190, 0, v190, s[78:79]
	v_add_u32_e32 v87, 10, v84
	v_cmp_gt_u32_e64 s[78:79], s98, v87
	v_cndmask_b32_e64 v191, 0, v191, s[50:51]
	v_add_u32_e32 v88, 11, v84
	v_cmp_gt_u32_e64 s[50:51], s98, v88
	v_cndmask_b32_e64 v192, 0, v192, s[30:31]
	v_add_u32_e32 v85, 16, v84
	v_cmp_gt_u32_e64 s[30:31], s98, v85
	v_cndmask_b32_e64 v193, 0, v193, s[36:37]
	v_add_u32_e32 v86, 17, v84
	v_cmp_gt_u32_e64 s[36:37], s98, v86
	v_cndmask_b32_e64 v194, 0, v194, s[78:79]
	v_add_u32_e32 v87, 18, v84
	v_cmp_gt_u32_e64 s[78:79], s98, v87
	v_cndmask_b32_e64 v195, 0, v195, s[50:51]
	v_add_u32_e32 v88, 19, v84
	v_cmp_gt_u32_e64 s[50:51], s98, v88
	v_cndmask_b32_e64 v196, 0, v196, s[30:31]
	v_add_u32_e32 v85, 24, v84
	v_cmp_gt_u32_e64 s[30:31], s98, v85
	v_cndmask_b32_e64 v197, 0, v197, s[36:37]
	v_add_u32_e32 v86, 25, v84
	v_cmp_gt_u32_e64 s[36:37], s98, v86
	v_cndmask_b32_e64 v198, 0, v198, s[78:79]
	v_add_u32_e32 v87, 26, v84
	v_cmp_gt_u32_e64 s[78:79], s98, v87
	v_cndmask_b32_e64 v199, 0, v199, s[50:51]
	v_add_u32_e32 v88, 27, v84
	v_cmp_gt_u32_e64 s[50:51], s98, v88
	v_nop
	v_cndmask_b32_e64 v200, 0, v200, s[30:31]
	v_cndmask_b32_e64 v201, 0, v201, s[36:37]
	v_cndmask_b32_e64 v202, 0, v202, s[78:79]
	v_cndmask_b32_e64 v203, 0, v203, s[50:51]
	v_cvt_pk_bf16_f32 v64, v188, v189
	v_cvt_pk_bf16_f32 v65, v190, v191
	v_cvt_pk_bf16_f32 v66, v192, v193
	v_cvt_pk_bf16_f32 v67, v194, v195
	v_cvt_pk_bf16_f32 v68, v196, v197
	v_cvt_pk_bf16_f32 v69, v198, v199
	v_cvt_pk_bf16_f32 v70, v200, v201
	v_cvt_pk_bf16_f32 v71, v202, v203
	v_pk_add_f32 v[232:233], v[232:233], v[188:189]
	v_pk_add_f32 v[232:233], v[232:233], v[190:191]
	v_pk_add_f32 v[232:233], v[232:233], v[192:193]
	v_pk_add_f32 v[232:233], v[232:233], v[194:195]
	v_pk_add_f32 v[232:233], v[232:233], v[196:197]
	v_pk_add_f32 v[232:233], v[232:233], v[198:199]
	v_pk_add_f32 v[232:233], v[232:233], v[200:201]
	v_pk_add_f32 v[232:233], v[232:233], v[202:203]
	v_add_u32_e32 v115, 952, v115
	ds_read2_b32 v[188:189], v115 offset0:0 offset1:1
	ds_read2_b32 v[190:191], v115 offset0:2 offset1:3
	ds_read2_b32 v[192:193], v115 offset0:8 offset1:9
	ds_read2_b32 v[194:195], v115 offset0:10 offset1:11
	ds_read2_b32 v[196:197], v115 offset0:17 offset1:18
	ds_read2_b32 v[198:199], v115 offset0:19 offset1:20
	ds_read2_b32 v[200:201], v115 offset0:25 offset1:26
	ds_read2_b32 v[202:203], v115 offset0:27 offset1:28
	v_mfma_f32_32x32x16_bf16 v[0:15], v[64:67], v[72:75], v[0:15]
	v_mfma_f32_32x32x16_bf16 v[16:31], v[64:67], v[76:79], v[16:31]
	v_mfma_f32_32x32x16_bf16 v[0:15], v[68:71], v[220:223], v[0:15]
	v_mfma_f32_32x32x16_bf16 v[16:31], v[68:71], v[224:227], v[16:31]
	s_add_i32 s90, s67, 192
	v_add_u32_e32 v80, s90, v235
	v_add_u32_e32 v83, s90, v236
	v_add_u32_e32 v99, s90, v237
	v_add_u32_e32 v253, s90, v238
	v_add_u32_e32 v254, s90, v100
	v_add_u32_e32 v255, s90, v149
	v_med3_i32 v80, v80, 0, s99
	v_med3_i32 v83, v83, 0, s99
	v_med3_i32 v99, v99, 0, s99
	v_med3_i32 v253, v253, 0, s99
	v_med3_i32 v254, v254, 0, s99
	v_med3_i32 v255, v255, 0, s99
	v_mad_u32_u24 v80, v80, s100, v252
	v_mad_u32_u24 v83, v83, s100, v252
	v_mad_u32_u24 v99, v99, s100, v252
	v_mad_u32_u24 v253, v253, s100, v252
	v_mad_u32_u24 v254, v254, s100, v153
	v_mad_u32_u24 v255, v255, s100, v153
	global_load_dwordx4 v[116:119], v80, s[82:83]
	global_load_dwordx4 v[120:123], v83, s[82:83]
	global_load_dwordx4 v[124:127], v99, s[82:83]
	global_load_dwordx4 v[128:131], v253, s[82:83]
	global_load_dwordx4 v[132:135], v254, s[82:83] offset:768
	global_load_dwordx4 v[136:139], v255, s[82:83] offset:768
	global_load_dwordx4 v[140:143], v254, s[82:83] offset:832
	global_load_dwordx4 v[144:147], v255, s[82:83] offset:832
	ds_read_b64_tr_b16 v[72:73], v231
	ds_read_b64_tr_b16 v[74:75], v231 offset:512
	ds_read_b64_tr_b16 v[76:77], v231 offset:2048
	ds_read_b64_tr_b16 v[78:79], v231 offset:2560
	ds_read_b64_tr_b16 v[220:221], v231 offset:1024
	ds_read_b64_tr_b16 v[222:223], v231 offset:1536
	ds_read_b64_tr_b16 v[224:225], v231 offset:3072
	ds_read_b64_tr_b16 v[226:227], v231 offset:3584
	v_exp_f32_e32 v32, v32
	v_exp_f32_e32 v33, v33
	v_exp_f32_e32 v34, v34
	v_exp_f32_e32 v35, v35
	s_waitcnt vmcnt(12)
	ds_write_b128 v247, v[156:159]
	ds_write_b128 v247, v[160:163] offset:1024
	ds_write_b128 v247, v[164:167] offset:2048
	ds_write_b128 v247, v[168:171] offset:3072
	ds_read_b128 v[156:159], v248
	ds_read_b128 v[160:163], v249
	ds_read_b128 v[164:167], v250
	ds_read_b128 v[168:171], v251
	s_waitcnt vmcnt(8)
	ds_write_b128 v112, v[172:175]
	ds_write_b128 v112, v[176:179] offset:1024
	ds_write_b128 v112, v[180:183] offset:2048
	ds_write_b128 v112, v[184:187] offset:3072
	v_exp_f32_e32 v36, v36
	v_exp_f32_e32 v37, v37
	v_exp_f32_e32 v38, v38
	v_exp_f32_e32 v39, v39
	s_waitcnt lgkmcnt(4)
	v_mfma_f32_32x32x16_bf16 v[188:203], v[156:159], v[48:51], v[188:203]
	v_exp_f32_e32 v40, v40
	v_exp_f32_e32 v41, v41
	v_mfma_f32_32x32x16_bf16 v[188:203], v[160:163], v[52:55], v[188:203]
	v_exp_f32_e32 v42, v42
	v_exp_f32_e32 v43, v43
	v_mfma_f32_32x32x16_bf16 v[188:203], v[164:167], v[56:59], v[188:203]
	v_exp_f32_e32 v44, v44
	v_exp_f32_e32 v45, v45
	v_mfma_f32_32x32x16_bf16 v[188:203], v[168:171], v[60:63], v[188:203]
	v_exp_f32_e32 v46, v46
	v_exp_f32_e32 v47, v47
	s_add_i32 s90, s67, 128
	v_add_u32_e32 v84, s90, v107
	v_add_u32_e32 v85, 0, v84
	v_add_u32_e32 v86, 1, v84
	v_add_u32_e32 v87, 2, v84
	v_add_u32_e32 v88, 3, v84
	v_cmp_gt_u32_e64 s[30:31], s98, v85
	v_cmp_gt_u32_e64 s[36:37], s98, v86
	v_cmp_gt_u32_e64 s[78:79], s98, v87
	v_cmp_gt_u32_e64 s[50:51], s98, v88
	v_cndmask_b32_e64 v32, 0, v32, s[30:31]
	v_add_u32_e32 v85, 8, v84
	v_cmp_gt_u32_e64 s[30:31], s98, v85
	v_cndmask_b32_e64 v33, 0, v33, s[36:37]
	v_add_u32_e32 v86, 9, v84
	v_cmp_gt_u32_e64 s[36:37], s98, v86
	v_cndmask_b32_e64 v34, 0, v34, s[78:79]
	v_add_u32_e32 v87, 10, v84
	v_cmp_gt_u32_e64 s[78:79], s98, v87
	v_cndmask_b32_e64 v35, 0, v35, s[50:51]
	v_add_u32_e32 v88, 11, v84
	v_cmp_gt_u32_e64 s[50:51], s98, v88
	v_cndmask_b32_e64 v36, 0, v36, s[30:31]
	v_add_u32_e32 v85, 16, v84
	v_cmp_gt_u32_e64 s[30:31], s98, v85
	v_cndmask_b32_e64 v37, 0, v37, s[36:37]
	v_add_u32_e32 v86, 17, v84
	v_cmp_gt_u32_e64 s[36:37], s98, v86
	v_cndmask_b32_e64 v38, 0, v38, s[78:79]
	v_add_u32_e32 v87, 18, v84
	v_cmp_gt_u32_e64 s[78:79], s98, v87
	v_cndmask_b32_e64 v39, 0, v39, s[50:51]
	v_add_u32_e32 v88, 19, v84
	v_cmp_gt_u32_e64 s[50:51], s98, v88
	v_cndmask_b32_e64 v40, 0, v40, s[30:31]
	v_add_u32_e32 v85, 24, v84
	v_cmp_gt_u32_e64 s[30:31], s98, v85
	v_cndmask_b32_e64 v41, 0, v41, s[36:37]
	v_add_u32_e32 v86, 25, v84
	v_cmp_gt_u32_e64 s[36:37], s98, v86
	v_cndmask_b32_e64 v42, 0, v42, s[78:79]
	v_add_u32_e32 v87, 26, v84
	v_cmp_gt_u32_e64 s[78:79], s98, v87
	v_cndmask_b32_e64 v43, 0, v43, s[50:51]
	v_add_u32_e32 v88, 27, v84
	v_cmp_gt_u32_e64 s[50:51], s98, v88
	v_nop
	v_cndmask_b32_e64 v44, 0, v44, s[30:31]
	v_cndmask_b32_e64 v45, 0, v45, s[36:37]
	v_cndmask_b32_e64 v46, 0, v46, s[78:79]
	v_cndmask_b32_e64 v47, 0, v47, s[50:51]
	v_cvt_pk_bf16_f32 v64, v32, v33
	v_cvt_pk_bf16_f32 v65, v34, v35
	v_cvt_pk_bf16_f32 v66, v36, v37
	v_cvt_pk_bf16_f32 v67, v38, v39
	v_cvt_pk_bf16_f32 v68, v40, v41
	v_cvt_pk_bf16_f32 v69, v42, v43
	v_cvt_pk_bf16_f32 v70, v44, v45
	v_cvt_pk_bf16_f32 v71, v46, v47
	v_pk_add_f32 v[232:233], v[232:233], v[32:33]
	v_pk_add_f32 v[232:233], v[232:233], v[34:35]
	v_pk_add_f32 v[232:233], v[232:233], v[36:37]
	v_pk_add_f32 v[232:233], v[232:233], v[38:39]
	v_pk_add_f32 v[232:233], v[232:233], v[40:41]
	v_pk_add_f32 v[232:233], v[232:233], v[42:43]
	v_pk_add_f32 v[232:233], v[232:233], v[44:45]
	v_pk_add_f32 v[232:233], v[232:233], v[46:47]
	ds_read2_b32 v[32:33], v115 offset0:34 offset1:35
	ds_read2_b32 v[34:35], v115 offset0:36 offset1:37
	ds_read2_b32 v[36:37], v115 offset0:42 offset1:43
	ds_read2_b32 v[38:39], v115 offset0:44 offset1:45
	ds_read2_b32 v[40:41], v115 offset0:51 offset1:52
	ds_read2_b32 v[42:43], v115 offset0:53 offset1:54
	ds_read2_b32 v[44:45], v115 offset0:59 offset1:60
	ds_read2_b32 v[46:47], v115 offset0:61 offset1:62
	v_mfma_f32_32x32x16_bf16 v[0:15], v[64:67], v[72:75], v[0:15]
	v_mfma_f32_32x32x16_bf16 v[16:31], v[64:67], v[76:79], v[16:31]
	v_mfma_f32_32x32x16_bf16 v[0:15], v[68:71], v[220:223], v[0:15]
	v_mfma_f32_32x32x16_bf16 v[16:31], v[68:71], v[224:227], v[16:31]
	s_add_i32 s90, s67, 224
	v_add_u32_e32 v80, s90, v235
	v_add_u32_e32 v83, s90, v236
	v_add_u32_e32 v99, s90, v237
	v_add_u32_e32 v253, s90, v238
	v_add_u32_e32 v254, s90, v100
	v_add_u32_e32 v255, s90, v149
	v_med3_i32 v80, v80, 0, s99
	v_med3_i32 v83, v83, 0, s99
	v_med3_i32 v99, v99, 0, s99
	v_med3_i32 v253, v253, 0, s99
	v_med3_i32 v254, v254, 0, s99
	v_med3_i32 v255, v255, 0, s99
	v_mad_u32_u24 v80, v80, s100, v252
	v_mad_u32_u24 v83, v83, s100, v252
	v_mad_u32_u24 v99, v99, s100, v252
	v_mad_u32_u24 v253, v253, s100, v252
	v_mad_u32_u24 v254, v254, s100, v153
	v_mad_u32_u24 v255, v255, s100, v153
	global_load_dwordx4 v[156:159], v80, s[82:83]
	global_load_dwordx4 v[160:163], v83, s[82:83]
	global_load_dwordx4 v[164:167], v99, s[82:83]
	global_load_dwordx4 v[168:171], v253, s[82:83]
	global_load_dwordx4 v[172:175], v254, s[82:83] offset:768
	global_load_dwordx4 v[176:179], v255, s[82:83] offset:768
	global_load_dwordx4 v[180:183], v254, s[82:83] offset:832
	global_load_dwordx4 v[184:187], v255, s[82:83] offset:832
	ds_read_b64_tr_b16 v[72:73], v231
	ds_read_b64_tr_b16 v[74:75], v231 offset:512
	ds_read_b64_tr_b16 v[76:77], v231 offset:2048
	ds_read_b64_tr_b16 v[78:79], v231 offset:2560
	ds_read_b64_tr_b16 v[220:221], v231 offset:1024
	ds_read_b64_tr_b16 v[222:223], v231 offset:1536
	ds_read_b64_tr_b16 v[224:225], v231 offset:3072
	ds_read_b64_tr_b16 v[226:227], v231 offset:3584
	v_exp_f32_e32 v188, v188
	v_exp_f32_e32 v189, v189
	v_exp_f32_e32 v190, v190
	v_exp_f32_e32 v191, v191
	s_waitcnt vmcnt(12)
	ds_write_b128 v247, v[116:119]
	ds_write_b128 v247, v[120:123] offset:1024
	ds_write_b128 v247, v[124:127] offset:2048
	ds_write_b128 v247, v[128:131] offset:3072
	ds_read_b128 v[116:119], v248
	ds_read_b128 v[120:123], v249
	ds_read_b128 v[124:127], v250
	ds_read_b128 v[128:131], v251
	s_waitcnt vmcnt(8)
	ds_write_b128 v112, v[132:135]
	ds_write_b128 v112, v[136:139] offset:1024
	ds_write_b128 v112, v[140:143] offset:2048
	ds_write_b128 v112, v[144:147] offset:3072
	v_exp_f32_e32 v192, v192
	v_exp_f32_e32 v193, v193
	v_exp_f32_e32 v194, v194
	v_exp_f32_e32 v195, v195
	s_waitcnt lgkmcnt(4)
	v_mfma_f32_32x32x16_bf16 v[32:47], v[116:119], v[48:51], v[32:47]
	v_exp_f32_e32 v196, v196
	v_exp_f32_e32 v197, v197
	v_mfma_f32_32x32x16_bf16 v[32:47], v[120:123], v[52:55], v[32:47]
	v_exp_f32_e32 v198, v198
	v_exp_f32_e32 v199, v199
	v_mfma_f32_32x32x16_bf16 v[32:47], v[124:127], v[56:59], v[32:47]
	v_exp_f32_e32 v200, v200
	v_exp_f32_e32 v201, v201
	v_mfma_f32_32x32x16_bf16 v[32:47], v[128:131], v[60:63], v[32:47]
	v_exp_f32_e32 v202, v202
	v_exp_f32_e32 v203, v203
	s_add_i32 s90, s67, 160
	v_add_u32_e32 v84, s90, v107
	v_add_u32_e32 v85, 0, v84
	v_add_u32_e32 v86, 1, v84
	v_add_u32_e32 v87, 2, v84
	v_add_u32_e32 v88, 3, v84
	v_cmp_gt_u32_e64 s[30:31], s98, v85
	v_cmp_gt_u32_e64 s[36:37], s98, v86
	v_cmp_gt_u32_e64 s[78:79], s98, v87
	v_cmp_gt_u32_e64 s[50:51], s98, v88
	v_cndmask_b32_e64 v188, 0, v188, s[30:31]
	v_add_u32_e32 v85, 8, v84
	v_cmp_gt_u32_e64 s[30:31], s98, v85
	v_cndmask_b32_e64 v189, 0, v189, s[36:37]
	v_add_u32_e32 v86, 9, v84
	v_cmp_gt_u32_e64 s[36:37], s98, v86
	v_cndmask_b32_e64 v190, 0, v190, s[78:79]
	v_add_u32_e32 v87, 10, v84
	v_cmp_gt_u32_e64 s[78:79], s98, v87
	v_cndmask_b32_e64 v191, 0, v191, s[50:51]
	v_add_u32_e32 v88, 11, v84
	v_cmp_gt_u32_e64 s[50:51], s98, v88
	v_cndmask_b32_e64 v192, 0, v192, s[30:31]
	v_add_u32_e32 v85, 16, v84
	v_cmp_gt_u32_e64 s[30:31], s98, v85
	v_cndmask_b32_e64 v193, 0, v193, s[36:37]
	v_add_u32_e32 v86, 17, v84
	v_cmp_gt_u32_e64 s[36:37], s98, v86
	v_cndmask_b32_e64 v194, 0, v194, s[78:79]
	v_add_u32_e32 v87, 18, v84
	v_cmp_gt_u32_e64 s[78:79], s98, v87
	v_cndmask_b32_e64 v195, 0, v195, s[50:51]
	v_add_u32_e32 v88, 19, v84
	v_cmp_gt_u32_e64 s[50:51], s98, v88
	v_cndmask_b32_e64 v196, 0, v196, s[30:31]
	v_add_u32_e32 v85, 24, v84
	v_cmp_gt_u32_e64 s[30:31], s98, v85
	v_cndmask_b32_e64 v197, 0, v197, s[36:37]
	v_add_u32_e32 v86, 25, v84
	v_cmp_gt_u32_e64 s[36:37], s98, v86
	v_cndmask_b32_e64 v198, 0, v198, s[78:79]
	v_add_u32_e32 v87, 26, v84
	v_cmp_gt_u32_e64 s[78:79], s98, v87
	v_cndmask_b32_e64 v199, 0, v199, s[50:51]
	v_add_u32_e32 v88, 27, v84
	v_cmp_gt_u32_e64 s[50:51], s98, v88
	v_nop
	v_cndmask_b32_e64 v200, 0, v200, s[30:31]
	v_cndmask_b32_e64 v201, 0, v201, s[36:37]
	v_cndmask_b32_e64 v202, 0, v202, s[78:79]
	v_cndmask_b32_e64 v203, 0, v203, s[50:51]
	v_cvt_pk_bf16_f32 v64, v188, v189
	v_cvt_pk_bf16_f32 v65, v190, v191
	v_cvt_pk_bf16_f32 v66, v192, v193
	v_cvt_pk_bf16_f32 v67, v194, v195
	v_cvt_pk_bf16_f32 v68, v196, v197
	v_cvt_pk_bf16_f32 v69, v198, v199
	v_cvt_pk_bf16_f32 v70, v200, v201
	v_cvt_pk_bf16_f32 v71, v202, v203
	v_pk_add_f32 v[232:233], v[232:233], v[188:189]
	v_pk_add_f32 v[232:233], v[232:233], v[190:191]
	v_pk_add_f32 v[232:233], v[232:233], v[192:193]
	v_pk_add_f32 v[232:233], v[232:233], v[194:195]
	v_pk_add_f32 v[232:233], v[232:233], v[196:197]
	v_pk_add_f32 v[232:233], v[232:233], v[198:199]
	v_pk_add_f32 v[232:233], v[232:233], v[200:201]
	v_pk_add_f32 v[232:233], v[232:233], v[202:203]
	ds_read2_b32 v[188:189], v115 offset0:68 offset1:69
	ds_read2_b32 v[190:191], v115 offset0:70 offset1:71
	ds_read2_b32 v[192:193], v115 offset0:76 offset1:77
	ds_read2_b32 v[194:195], v115 offset0:78 offset1:79
	ds_read2_b32 v[196:197], v115 offset0:85 offset1:86
	ds_read2_b32 v[198:199], v115 offset0:87 offset1:88
	ds_read2_b32 v[200:201], v115 offset0:93 offset1:94
	ds_read2_b32 v[202:203], v115 offset0:95 offset1:96
	v_mfma_f32_32x32x16_bf16 v[0:15], v[64:67], v[72:75], v[0:15]
	v_mfma_f32_32x32x16_bf16 v[16:31], v[64:67], v[76:79], v[16:31]
	v_mfma_f32_32x32x16_bf16 v[0:15], v[68:71], v[220:223], v[0:15]
	v_mfma_f32_32x32x16_bf16 v[16:31], v[68:71], v[224:227], v[16:31]
	s_add_i32 s90, s67, 256
	v_add_u32_e32 v80, s90, v235
	v_add_u32_e32 v83, s90, v236
	v_add_u32_e32 v99, s90, v237
	v_add_u32_e32 v253, s90, v238
	v_add_u32_e32 v254, s90, v100
	v_add_u32_e32 v255, s90, v149
	v_med3_i32 v80, v80, 0, s99
	v_med3_i32 v83, v83, 0, s99
	v_med3_i32 v99, v99, 0, s99
	v_med3_i32 v253, v253, 0, s99
	v_med3_i32 v254, v254, 0, s99
	v_med3_i32 v255, v255, 0, s99
	v_mad_u32_u24 v80, v80, s100, v252
	v_mad_u32_u24 v83, v83, s100, v252
	v_mad_u32_u24 v99, v99, s100, v252
	v_mad_u32_u24 v253, v253, s100, v252
	v_mad_u32_u24 v254, v254, s100, v153
	v_mad_u32_u24 v255, v255, s100, v153
	global_load_dwordx4 v[116:119], v80, s[82:83]
	global_load_dwordx4 v[120:123], v83, s[82:83]
	global_load_dwordx4 v[124:127], v99, s[82:83]
	global_load_dwordx4 v[128:131], v253, s[82:83]
	global_load_dwordx4 v[132:135], v254, s[82:83] offset:768
	global_load_dwordx4 v[136:139], v255, s[82:83] offset:768
	global_load_dwordx4 v[140:143], v254, s[82:83] offset:832
	global_load_dwordx4 v[144:147], v255, s[82:83] offset:832
	ds_read_b64_tr_b16 v[72:73], v231
	ds_read_b64_tr_b16 v[74:75], v231 offset:512
	ds_read_b64_tr_b16 v[76:77], v231 offset:2048
	ds_read_b64_tr_b16 v[78:79], v231 offset:2560
	ds_read_b64_tr_b16 v[220:221], v231 offset:1024
	ds_read_b64_tr_b16 v[222:223], v231 offset:1536
	ds_read_b64_tr_b16 v[224:225], v231 offset:3072
	ds_read_b64_tr_b16 v[226:227], v231 offset:3584
	v_exp_f32_e32 v32, v32
	v_exp_f32_e32 v33, v33
	v_exp_f32_e32 v34, v34
	v_exp_f32_e32 v35, v35
	s_waitcnt vmcnt(12)
	ds_write_b128 v247, v[156:159]
	ds_write_b128 v247, v[160:163] offset:1024
	ds_write_b128 v247, v[164:167] offset:2048
	ds_write_b128 v247, v[168:171] offset:3072
	ds_read_b128 v[156:159], v248
	ds_read_b128 v[160:163], v249
	ds_read_b128 v[164:167], v250
	ds_read_b128 v[168:171], v251
	s_waitcnt vmcnt(8)
	ds_write_b128 v112, v[172:175]
	ds_write_b128 v112, v[176:179] offset:1024
	ds_write_b128 v112, v[180:183] offset:2048
	ds_write_b128 v112, v[184:187] offset:3072
	v_exp_f32_e32 v36, v36
	v_exp_f32_e32 v37, v37
	v_exp_f32_e32 v38, v38
	v_exp_f32_e32 v39, v39
	s_waitcnt lgkmcnt(4)
	v_mfma_f32_32x32x16_bf16 v[188:203], v[156:159], v[48:51], v[188:203]
	v_exp_f32_e32 v40, v40
	v_exp_f32_e32 v41, v41
	v_mfma_f32_32x32x16_bf16 v[188:203], v[160:163], v[52:55], v[188:203]
	v_exp_f32_e32 v42, v42
	v_exp_f32_e32 v43, v43
	v_mfma_f32_32x32x16_bf16 v[188:203], v[164:167], v[56:59], v[188:203]
	v_exp_f32_e32 v44, v44
	v_exp_f32_e32 v45, v45
	v_mfma_f32_32x32x16_bf16 v[188:203], v[168:171], v[60:63], v[188:203]
	v_exp_f32_e32 v46, v46
	v_exp_f32_e32 v47, v47
	s_add_i32 s90, s67, 192
	v_add_u32_e32 v84, s90, v107
	v_add_u32_e32 v85, 0, v84
	v_add_u32_e32 v86, 1, v84
	v_add_u32_e32 v87, 2, v84
	v_add_u32_e32 v88, 3, v84
	v_cmp_gt_u32_e64 s[30:31], s98, v85
	v_cmp_gt_u32_e64 s[36:37], s98, v86
	v_cmp_gt_u32_e64 s[78:79], s98, v87
	v_cmp_gt_u32_e64 s[50:51], s98, v88
	v_cndmask_b32_e64 v32, 0, v32, s[30:31]
	v_add_u32_e32 v85, 8, v84
	v_cmp_gt_u32_e64 s[30:31], s98, v85
	v_cndmask_b32_e64 v33, 0, v33, s[36:37]
	v_add_u32_e32 v86, 9, v84
	v_cmp_gt_u32_e64 s[36:37], s98, v86
	v_cndmask_b32_e64 v34, 0, v34, s[78:79]
	v_add_u32_e32 v87, 10, v84
	v_cmp_gt_u32_e64 s[78:79], s98, v87
	v_cndmask_b32_e64 v35, 0, v35, s[50:51]
	v_add_u32_e32 v88, 11, v84
	v_cmp_gt_u32_e64 s[50:51], s98, v88
	v_cndmask_b32_e64 v36, 0, v36, s[30:31]
	v_add_u32_e32 v85, 16, v84
	v_cmp_gt_u32_e64 s[30:31], s98, v85
	v_cndmask_b32_e64 v37, 0, v37, s[36:37]
	v_add_u32_e32 v86, 17, v84
	v_cmp_gt_u32_e64 s[36:37], s98, v86
	v_cndmask_b32_e64 v38, 0, v38, s[78:79]
	v_add_u32_e32 v87, 18, v84
	v_cmp_gt_u32_e64 s[78:79], s98, v87
	v_cndmask_b32_e64 v39, 0, v39, s[50:51]
	v_add_u32_e32 v88, 19, v84
	v_cmp_gt_u32_e64 s[50:51], s98, v88
	v_cndmask_b32_e64 v40, 0, v40, s[30:31]
	v_add_u32_e32 v85, 24, v84
	v_cmp_gt_u32_e64 s[30:31], s98, v85
	v_cndmask_b32_e64 v41, 0, v41, s[36:37]
	v_add_u32_e32 v86, 25, v84
	v_cmp_gt_u32_e64 s[36:37], s98, v86
	v_cndmask_b32_e64 v42, 0, v42, s[78:79]
	v_add_u32_e32 v87, 26, v84
	v_cmp_gt_u32_e64 s[78:79], s98, v87
	v_cndmask_b32_e64 v43, 0, v43, s[50:51]
	v_add_u32_e32 v88, 27, v84
	v_cmp_gt_u32_e64 s[50:51], s98, v88
	v_nop
	v_cndmask_b32_e64 v44, 0, v44, s[30:31]
	v_cndmask_b32_e64 v45, 0, v45, s[36:37]
	v_cndmask_b32_e64 v46, 0, v46, s[78:79]
	v_cndmask_b32_e64 v47, 0, v47, s[50:51]
	v_cvt_pk_bf16_f32 v64, v32, v33
	v_cvt_pk_bf16_f32 v65, v34, v35
	v_cvt_pk_bf16_f32 v66, v36, v37
	v_cvt_pk_bf16_f32 v67, v38, v39
	v_cvt_pk_bf16_f32 v68, v40, v41
	v_cvt_pk_bf16_f32 v69, v42, v43
	v_cvt_pk_bf16_f32 v70, v44, v45
	v_cvt_pk_bf16_f32 v71, v46, v47
	v_pk_add_f32 v[232:233], v[232:233], v[32:33]
	v_pk_add_f32 v[232:233], v[232:233], v[34:35]
	v_pk_add_f32 v[232:233], v[232:233], v[36:37]
	v_pk_add_f32 v[232:233], v[232:233], v[38:39]
	v_pk_add_f32 v[232:233], v[232:233], v[40:41]
	v_pk_add_f32 v[232:233], v[232:233], v[42:43]
	v_pk_add_f32 v[232:233], v[232:233], v[44:45]
	v_pk_add_f32 v[232:233], v[232:233], v[46:47]
	ds_read2_b32 v[32:33], v115 offset0:102 offset1:103
	ds_read2_b32 v[34:35], v115 offset0:104 offset1:105
	ds_read2_b32 v[36:37], v115 offset0:110 offset1:111
	ds_read2_b32 v[38:39], v115 offset0:112 offset1:113
	ds_read2_b32 v[40:41], v115 offset0:119 offset1:120
	ds_read2_b32 v[42:43], v115 offset0:121 offset1:122
	ds_read2_b32 v[44:45], v115 offset0:127 offset1:128
	ds_read2_b32 v[46:47], v115 offset0:129 offset1:130
	v_mfma_f32_32x32x16_bf16 v[0:15], v[64:67], v[72:75], v[0:15]
	v_mfma_f32_32x32x16_bf16 v[16:31], v[64:67], v[76:79], v[16:31]
	v_mfma_f32_32x32x16_bf16 v[0:15], v[68:71], v[220:223], v[0:15]
	v_mfma_f32_32x32x16_bf16 v[16:31], v[68:71], v[224:227], v[16:31]
	s_add_i32 s90, s67, 288
	v_add_u32_e32 v80, s90, v235
	v_add_u32_e32 v83, s90, v236
	v_add_u32_e32 v99, s90, v237
	v_add_u32_e32 v253, s90, v238
	v_add_u32_e32 v254, s90, v100
	v_add_u32_e32 v255, s90, v149
	v_med3_i32 v80, v80, 0, s99
	v_med3_i32 v83, v83, 0, s99
	v_med3_i32 v99, v99, 0, s99
	v_med3_i32 v253, v253, 0, s99
	v_med3_i32 v254, v254, 0, s99
	v_med3_i32 v255, v255, 0, s99
	v_mad_u32_u24 v80, v80, s100, v252
	v_mad_u32_u24 v83, v83, s100, v252
	v_mad_u32_u24 v99, v99, s100, v252
	v_mad_u32_u24 v253, v253, s100, v252
	v_mad_u32_u24 v254, v254, s100, v153
	v_mad_u32_u24 v255, v255, s100, v153
	global_load_dwordx4 v[156:159], v80, s[82:83]
	global_load_dwordx4 v[160:163], v83, s[82:83]
	global_load_dwordx4 v[164:167], v99, s[82:83]
	global_load_dwordx4 v[168:171], v253, s[82:83]
	global_load_dwordx4 v[172:175], v254, s[82:83] offset:768
	global_load_dwordx4 v[176:179], v255, s[82:83] offset:768
	global_load_dwordx4 v[180:183], v254, s[82:83] offset:832
	global_load_dwordx4 v[184:187], v255, s[82:83] offset:832
	ds_read_b64_tr_b16 v[72:73], v231
	ds_read_b64_tr_b16 v[74:75], v231 offset:512
	ds_read_b64_tr_b16 v[76:77], v231 offset:2048
	ds_read_b64_tr_b16 v[78:79], v231 offset:2560
	ds_read_b64_tr_b16 v[220:221], v231 offset:1024
	ds_read_b64_tr_b16 v[222:223], v231 offset:1536
	ds_read_b64_tr_b16 v[224:225], v231 offset:3072
	ds_read_b64_tr_b16 v[226:227], v231 offset:3584
	v_exp_f32_e32 v188, v188
	v_exp_f32_e32 v189, v189
	v_exp_f32_e32 v190, v190
	v_exp_f32_e32 v191, v191
	s_waitcnt vmcnt(12)
	ds_write_b128 v247, v[116:119]
	ds_write_b128 v247, v[120:123] offset:1024
	ds_write_b128 v247, v[124:127] offset:2048
	ds_write_b128 v247, v[128:131] offset:3072
	ds_read_b128 v[116:119], v248
	ds_read_b128 v[120:123], v249
	ds_read_b128 v[124:127], v250
	ds_read_b128 v[128:131], v251
	s_waitcnt vmcnt(8)
	ds_write_b128 v112, v[132:135]
	ds_write_b128 v112, v[136:139] offset:1024
	ds_write_b128 v112, v[140:143] offset:2048
	ds_write_b128 v112, v[144:147] offset:3072
	v_exp_f32_e32 v192, v192
	v_exp_f32_e32 v193, v193
	v_exp_f32_e32 v194, v194
	v_exp_f32_e32 v195, v195
	s_waitcnt lgkmcnt(4)
	v_mfma_f32_32x32x16_bf16 v[32:47], v[116:119], v[48:51], v[32:47]
	v_exp_f32_e32 v196, v196
	v_exp_f32_e32 v197, v197
	v_mfma_f32_32x32x16_bf16 v[32:47], v[120:123], v[52:55], v[32:47]
	v_exp_f32_e32 v198, v198
	v_exp_f32_e32 v199, v199
	v_mfma_f32_32x32x16_bf16 v[32:47], v[124:127], v[56:59], v[32:47]
	v_exp_f32_e32 v200, v200
	v_exp_f32_e32 v201, v201
	v_mfma_f32_32x32x16_bf16 v[32:47], v[128:131], v[60:63], v[32:47]
	v_exp_f32_e32 v202, v202
	v_exp_f32_e32 v203, v203
	s_add_i32 s90, s67, 224
	v_add_u32_e32 v84, s90, v107
	v_add_u32_e32 v85, 0, v84
	v_add_u32_e32 v86, 1, v84
	v_add_u32_e32 v87, 2, v84
	v_add_u32_e32 v88, 3, v84
	v_cmp_gt_u32_e64 s[30:31], s98, v85
	v_cmp_gt_u32_e64 s[36:37], s98, v86
	v_cmp_gt_u32_e64 s[78:79], s98, v87
	v_cmp_gt_u32_e64 s[50:51], s98, v88
	v_cndmask_b32_e64 v188, 0, v188, s[30:31]
	v_add_u32_e32 v85, 8, v84
	v_cmp_gt_u32_e64 s[30:31], s98, v85
	v_cndmask_b32_e64 v189, 0, v189, s[36:37]
	v_add_u32_e32 v86, 9, v84
	v_cmp_gt_u32_e64 s[36:37], s98, v86
	v_cndmask_b32_e64 v190, 0, v190, s[78:79]
	v_add_u32_e32 v87, 10, v84
	v_cmp_gt_u32_e64 s[78:79], s98, v87
	v_cndmask_b32_e64 v191, 0, v191, s[50:51]
	v_add_u32_e32 v88, 11, v84
	v_cmp_gt_u32_e64 s[50:51], s98, v88
	v_cndmask_b32_e64 v192, 0, v192, s[30:31]
	v_add_u32_e32 v85, 16, v84
	v_cmp_gt_u32_e64 s[30:31], s98, v85
	v_cndmask_b32_e64 v193, 0, v193, s[36:37]
	v_add_u32_e32 v86, 17, v84
	v_cmp_gt_u32_e64 s[36:37], s98, v86
	v_cndmask_b32_e64 v194, 0, v194, s[78:79]
	v_add_u32_e32 v87, 18, v84
	v_cmp_gt_u32_e64 s[78:79], s98, v87
	v_cndmask_b32_e64 v195, 0, v195, s[50:51]
	v_add_u32_e32 v88, 19, v84
	v_cmp_gt_u32_e64 s[50:51], s98, v88
	v_cndmask_b32_e64 v196, 0, v196, s[30:31]
	v_add_u32_e32 v85, 24, v84
	v_cmp_gt_u32_e64 s[30:31], s98, v85
	v_cndmask_b32_e64 v197, 0, v197, s[36:37]
	v_add_u32_e32 v86, 25, v84
	v_cmp_gt_u32_e64 s[36:37], s98, v86
	v_cndmask_b32_e64 v198, 0, v198, s[78:79]
	v_add_u32_e32 v87, 26, v84
	v_cmp_gt_u32_e64 s[78:79], s98, v87
	v_cndmask_b32_e64 v199, 0, v199, s[50:51]
	v_add_u32_e32 v88, 27, v84
	v_cmp_gt_u32_e64 s[50:51], s98, v88
	v_nop
	v_cndmask_b32_e64 v200, 0, v200, s[30:31]
	v_cndmask_b32_e64 v201, 0, v201, s[36:37]
	v_cndmask_b32_e64 v202, 0, v202, s[78:79]
	v_cndmask_b32_e64 v203, 0, v203, s[50:51]
	v_cvt_pk_bf16_f32 v64, v188, v189
	v_cvt_pk_bf16_f32 v65, v190, v191
	v_cvt_pk_bf16_f32 v66, v192, v193
	v_cvt_pk_bf16_f32 v67, v194, v195
	v_cvt_pk_bf16_f32 v68, v196, v197
	v_cvt_pk_bf16_f32 v69, v198, v199
	v_cvt_pk_bf16_f32 v70, v200, v201
	v_cvt_pk_bf16_f32 v71, v202, v203
	v_pk_add_f32 v[232:233], v[232:233], v[188:189]
	v_pk_add_f32 v[232:233], v[232:233], v[190:191]
	v_pk_add_f32 v[232:233], v[232:233], v[192:193]
	v_pk_add_f32 v[232:233], v[232:233], v[194:195]
	v_pk_add_f32 v[232:233], v[232:233], v[196:197]
	v_pk_add_f32 v[232:233], v[232:233], v[198:199]
	v_pk_add_f32 v[232:233], v[232:233], v[200:201]
	v_pk_add_f32 v[232:233], v[232:233], v[202:203]
	ds_read2_b32 v[188:189], v115 offset0:136 offset1:137
	ds_read2_b32 v[190:191], v115 offset0:138 offset1:139
	ds_read2_b32 v[192:193], v115 offset0:144 offset1:145
	ds_read2_b32 v[194:195], v115 offset0:146 offset1:147
	ds_read2_b32 v[196:197], v115 offset0:153 offset1:154
	ds_read2_b32 v[198:199], v115 offset0:155 offset1:156
	ds_read2_b32 v[200:201], v115 offset0:161 offset1:162
	ds_read2_b32 v[202:203], v115 offset0:163 offset1:164
	v_mfma_f32_32x32x16_bf16 v[0:15], v[64:67], v[72:75], v[0:15]
	v_mfma_f32_32x32x16_bf16 v[16:31], v[64:67], v[76:79], v[16:31]
	v_mfma_f32_32x32x16_bf16 v[0:15], v[68:71], v[220:223], v[0:15]
	v_mfma_f32_32x32x16_bf16 v[16:31], v[68:71], v[224:227], v[16:31]
	s_add_i32 s90, s67, 320
	v_add_u32_e32 v80, s90, v235
	v_add_u32_e32 v83, s90, v236
	v_add_u32_e32 v99, s90, v237
	v_add_u32_e32 v253, s90, v238
	v_add_u32_e32 v254, s90, v100
	v_add_u32_e32 v255, s90, v149
	v_med3_i32 v80, v80, 0, s99
	v_med3_i32 v83, v83, 0, s99
	v_med3_i32 v99, v99, 0, s99
	v_med3_i32 v253, v253, 0, s99
	v_med3_i32 v254, v254, 0, s99
	v_med3_i32 v255, v255, 0, s99
	v_mad_u32_u24 v80, v80, s100, v252
	v_mad_u32_u24 v83, v83, s100, v252
	v_mad_u32_u24 v99, v99, s100, v252
	v_mad_u32_u24 v253, v253, s100, v252
	v_mad_u32_u24 v254, v254, s100, v153
	v_mad_u32_u24 v255, v255, s100, v153
	global_load_dwordx4 v[116:119], v80, s[82:83]
	global_load_dwordx4 v[120:123], v83, s[82:83]
	global_load_dwordx4 v[124:127], v99, s[82:83]
	global_load_dwordx4 v[128:131], v253, s[82:83]
	global_load_dwordx4 v[132:135], v254, s[82:83] offset:768
	global_load_dwordx4 v[136:139], v255, s[82:83] offset:768
	global_load_dwordx4 v[140:143], v254, s[82:83] offset:832
	global_load_dwordx4 v[144:147], v255, s[82:83] offset:832
	ds_read_b64_tr_b16 v[72:73], v231
	ds_read_b64_tr_b16 v[74:75], v231 offset:512
	ds_read_b64_tr_b16 v[76:77], v231 offset:2048
	ds_read_b64_tr_b16 v[78:79], v231 offset:2560
	ds_read_b64_tr_b16 v[220:221], v231 offset:1024
	ds_read_b64_tr_b16 v[222:223], v231 offset:1536
	ds_read_b64_tr_b16 v[224:225], v231 offset:3072
	ds_read_b64_tr_b16 v[226:227], v231 offset:3584
	v_exp_f32_e32 v32, v32
	v_exp_f32_e32 v33, v33
	v_exp_f32_e32 v34, v34
	v_exp_f32_e32 v35, v35
	s_waitcnt vmcnt(12)
	ds_write_b128 v247, v[156:159]
	ds_write_b128 v247, v[160:163] offset:1024
	ds_write_b128 v247, v[164:167] offset:2048
	ds_write_b128 v247, v[168:171] offset:3072
	ds_read_b128 v[156:159], v248
	ds_read_b128 v[160:163], v249
	ds_read_b128 v[164:167], v250
	ds_read_b128 v[168:171], v251
	s_waitcnt vmcnt(8)
	ds_write_b128 v112, v[172:175]
	ds_write_b128 v112, v[176:179] offset:1024
	ds_write_b128 v112, v[180:183] offset:2048
	ds_write_b128 v112, v[184:187] offset:3072
	v_exp_f32_e32 v36, v36
	v_exp_f32_e32 v37, v37
	v_exp_f32_e32 v38, v38
	v_exp_f32_e32 v39, v39
	s_waitcnt lgkmcnt(4)
	v_mfma_f32_32x32x16_bf16 v[188:203], v[156:159], v[48:51], v[188:203]
	v_exp_f32_e32 v40, v40
	v_exp_f32_e32 v41, v41
	v_mfma_f32_32x32x16_bf16 v[188:203], v[160:163], v[52:55], v[188:203]
	v_exp_f32_e32 v42, v42
	v_exp_f32_e32 v43, v43
	v_mfma_f32_32x32x16_bf16 v[188:203], v[164:167], v[56:59], v[188:203]
	v_exp_f32_e32 v44, v44
	v_exp_f32_e32 v45, v45
	v_mfma_f32_32x32x16_bf16 v[188:203], v[168:171], v[60:63], v[188:203]
	v_exp_f32_e32 v46, v46
	v_exp_f32_e32 v47, v47
	s_add_i32 s90, s67, 256
	v_add_u32_e32 v84, s90, v107
	v_add_u32_e32 v85, 0, v84
	v_add_u32_e32 v86, 1, v84
	v_add_u32_e32 v87, 2, v84
	v_add_u32_e32 v88, 3, v84
	v_cmp_gt_u32_e64 s[30:31], s98, v85
	v_cmp_gt_u32_e64 s[36:37], s98, v86
	v_cmp_gt_u32_e64 s[78:79], s98, v87
	v_cmp_gt_u32_e64 s[50:51], s98, v88
	v_cndmask_b32_e64 v32, 0, v32, s[30:31]
	v_add_u32_e32 v85, 8, v84
	v_cmp_gt_u32_e64 s[30:31], s98, v85
	v_cndmask_b32_e64 v33, 0, v33, s[36:37]
	v_add_u32_e32 v86, 9, v84
	v_cmp_gt_u32_e64 s[36:37], s98, v86
	v_cndmask_b32_e64 v34, 0, v34, s[78:79]
	v_add_u32_e32 v87, 10, v84
	v_cmp_gt_u32_e64 s[78:79], s98, v87
	v_cndmask_b32_e64 v35, 0, v35, s[50:51]
	v_add_u32_e32 v88, 11, v84
	v_cmp_gt_u32_e64 s[50:51], s98, v88
	v_cndmask_b32_e64 v36, 0, v36, s[30:31]
	v_add_u32_e32 v85, 16, v84
	v_cmp_gt_u32_e64 s[30:31], s98, v85
	v_cndmask_b32_e64 v37, 0, v37, s[36:37]
	v_add_u32_e32 v86, 17, v84
	v_cmp_gt_u32_e64 s[36:37], s98, v86
	v_cndmask_b32_e64 v38, 0, v38, s[78:79]
	v_add_u32_e32 v87, 18, v84
	v_cmp_gt_u32_e64 s[78:79], s98, v87
	v_cndmask_b32_e64 v39, 0, v39, s[50:51]
	v_add_u32_e32 v88, 19, v84
	v_cmp_gt_u32_e64 s[50:51], s98, v88
	v_cndmask_b32_e64 v40, 0, v40, s[30:31]
	v_add_u32_e32 v85, 24, v84
	v_cmp_gt_u32_e64 s[30:31], s98, v85
	v_cndmask_b32_e64 v41, 0, v41, s[36:37]
	v_add_u32_e32 v86, 25, v84
	v_cmp_gt_u32_e64 s[36:37], s98, v86
	v_cndmask_b32_e64 v42, 0, v42, s[78:79]
	v_add_u32_e32 v87, 26, v84
	v_cmp_gt_u32_e64 s[78:79], s98, v87
	v_cndmask_b32_e64 v43, 0, v43, s[50:51]
	v_add_u32_e32 v88, 27, v84
	v_cmp_gt_u32_e64 s[50:51], s98, v88
	v_nop
	v_cndmask_b32_e64 v44, 0, v44, s[30:31]
	v_cndmask_b32_e64 v45, 0, v45, s[36:37]
	v_cndmask_b32_e64 v46, 0, v46, s[78:79]
	v_cndmask_b32_e64 v47, 0, v47, s[50:51]
	v_cvt_pk_bf16_f32 v64, v32, v33
	v_cvt_pk_bf16_f32 v65, v34, v35
	v_cvt_pk_bf16_f32 v66, v36, v37
	v_cvt_pk_bf16_f32 v67, v38, v39
	v_cvt_pk_bf16_f32 v68, v40, v41
	v_cvt_pk_bf16_f32 v69, v42, v43
	v_cvt_pk_bf16_f32 v70, v44, v45
	v_cvt_pk_bf16_f32 v71, v46, v47
	v_pk_add_f32 v[232:233], v[232:233], v[32:33]
	v_pk_add_f32 v[232:233], v[232:233], v[34:35]
	v_pk_add_f32 v[232:233], v[232:233], v[36:37]
	v_pk_add_f32 v[232:233], v[232:233], v[38:39]
	v_pk_add_f32 v[232:233], v[232:233], v[40:41]
	v_pk_add_f32 v[232:233], v[232:233], v[42:43]
	v_pk_add_f32 v[232:233], v[232:233], v[44:45]
	v_pk_add_f32 v[232:233], v[232:233], v[46:47]
	ds_read2_b32 v[32:33], v115 offset0:170 offset1:171
	ds_read2_b32 v[34:35], v115 offset0:172 offset1:173
	ds_read2_b32 v[36:37], v115 offset0:178 offset1:179
	ds_read2_b32 v[38:39], v115 offset0:180 offset1:181
	ds_read2_b32 v[40:41], v115 offset0:187 offset1:188
	ds_read2_b32 v[42:43], v115 offset0:189 offset1:190
	ds_read2_b32 v[44:45], v115 offset0:195 offset1:196
	ds_read2_b32 v[46:47], v115 offset0:197 offset1:198
	v_mfma_f32_32x32x16_bf16 v[0:15], v[64:67], v[72:75], v[0:15]
	v_mfma_f32_32x32x16_bf16 v[16:31], v[64:67], v[76:79], v[16:31]
	v_mfma_f32_32x32x16_bf16 v[0:15], v[68:71], v[220:223], v[0:15]
	v_mfma_f32_32x32x16_bf16 v[16:31], v[68:71], v[224:227], v[16:31]
	s_add_i32 s90, s67, 352
	v_add_u32_e32 v80, s90, v235
	v_add_u32_e32 v83, s90, v236
	v_add_u32_e32 v99, s90, v237
	v_add_u32_e32 v253, s90, v238
	v_add_u32_e32 v254, s90, v100
	v_add_u32_e32 v255, s90, v149
	v_med3_i32 v80, v80, 0, s99
	v_med3_i32 v83, v83, 0, s99
	v_med3_i32 v99, v99, 0, s99
	v_med3_i32 v253, v253, 0, s99
	v_med3_i32 v254, v254, 0, s99
	v_med3_i32 v255, v255, 0, s99
	v_mad_u32_u24 v80, v80, s100, v252
	v_mad_u32_u24 v83, v83, s100, v252
	v_mad_u32_u24 v99, v99, s100, v252
	v_mad_u32_u24 v253, v253, s100, v252
	v_mad_u32_u24 v254, v254, s100, v153
	v_mad_u32_u24 v255, v255, s100, v153
	global_load_dwordx4 v[156:159], v80, s[82:83]
	global_load_dwordx4 v[160:163], v83, s[82:83]
	global_load_dwordx4 v[164:167], v99, s[82:83]
	global_load_dwordx4 v[168:171], v253, s[82:83]
	global_load_dwordx4 v[172:175], v254, s[82:83] offset:768
	global_load_dwordx4 v[176:179], v255, s[82:83] offset:768
	global_load_dwordx4 v[180:183], v254, s[82:83] offset:832
	global_load_dwordx4 v[184:187], v255, s[82:83] offset:832
	ds_read_b64_tr_b16 v[72:73], v231
	ds_read_b64_tr_b16 v[74:75], v231 offset:512
	ds_read_b64_tr_b16 v[76:77], v231 offset:2048
	ds_read_b64_tr_b16 v[78:79], v231 offset:2560
	ds_read_b64_tr_b16 v[220:221], v231 offset:1024
	ds_read_b64_tr_b16 v[222:223], v231 offset:1536
	ds_read_b64_tr_b16 v[224:225], v231 offset:3072
	ds_read_b64_tr_b16 v[226:227], v231 offset:3584
	v_exp_f32_e32 v188, v188
	v_exp_f32_e32 v189, v189
	v_exp_f32_e32 v190, v190
	v_exp_f32_e32 v191, v191
	s_waitcnt vmcnt(12)
	ds_write_b128 v247, v[116:119]
	ds_write_b128 v247, v[120:123] offset:1024
	ds_write_b128 v247, v[124:127] offset:2048
	ds_write_b128 v247, v[128:131] offset:3072
	ds_read_b128 v[116:119], v248
	ds_read_b128 v[120:123], v249
	ds_read_b128 v[124:127], v250
	ds_read_b128 v[128:131], v251
	s_waitcnt vmcnt(8)
	ds_write_b128 v112, v[132:135]
	ds_write_b128 v112, v[136:139] offset:1024
	ds_write_b128 v112, v[140:143] offset:2048
	ds_write_b128 v112, v[144:147] offset:3072
	v_exp_f32_e32 v192, v192
	v_exp_f32_e32 v193, v193
	v_exp_f32_e32 v194, v194
	v_exp_f32_e32 v195, v195
	s_waitcnt lgkmcnt(4)
	v_mfma_f32_32x32x16_bf16 v[32:47], v[116:119], v[48:51], v[32:47]
	v_exp_f32_e32 v196, v196
	v_exp_f32_e32 v197, v197
	v_mfma_f32_32x32x16_bf16 v[32:47], v[120:123], v[52:55], v[32:47]
	v_exp_f32_e32 v198, v198
	v_exp_f32_e32 v199, v199
	v_mfma_f32_32x32x16_bf16 v[32:47], v[124:127], v[56:59], v[32:47]
	v_exp_f32_e32 v200, v200
	v_exp_f32_e32 v201, v201
	v_mfma_f32_32x32x16_bf16 v[32:47], v[128:131], v[60:63], v[32:47]
	v_exp_f32_e32 v202, v202
	v_exp_f32_e32 v203, v203
	s_add_i32 s90, s67, 288
	v_add_u32_e32 v84, s90, v107
	v_add_u32_e32 v85, 0, v84
	v_add_u32_e32 v86, 1, v84
	v_add_u32_e32 v87, 2, v84
	v_add_u32_e32 v88, 3, v84
	v_cmp_gt_u32_e64 s[30:31], s98, v85
	v_cmp_gt_u32_e64 s[36:37], s98, v86
	v_cmp_gt_u32_e64 s[78:79], s98, v87
	v_cmp_gt_u32_e64 s[50:51], s98, v88
	v_cndmask_b32_e64 v188, 0, v188, s[30:31]
	v_add_u32_e32 v85, 8, v84
	v_cmp_gt_u32_e64 s[30:31], s98, v85
	v_cndmask_b32_e64 v189, 0, v189, s[36:37]
	v_add_u32_e32 v86, 9, v84
	v_cmp_gt_u32_e64 s[36:37], s98, v86
	v_cndmask_b32_e64 v190, 0, v190, s[78:79]
	v_add_u32_e32 v87, 10, v84
	v_cmp_gt_u32_e64 s[78:79], s98, v87
	v_cndmask_b32_e64 v191, 0, v191, s[50:51]
	v_add_u32_e32 v88, 11, v84
	v_cmp_gt_u32_e64 s[50:51], s98, v88
	v_cndmask_b32_e64 v192, 0, v192, s[30:31]
	v_add_u32_e32 v85, 16, v84
	v_cmp_gt_u32_e64 s[30:31], s98, v85
	v_cndmask_b32_e64 v193, 0, v193, s[36:37]
	v_add_u32_e32 v86, 17, v84
	v_cmp_gt_u32_e64 s[36:37], s98, v86
	v_cndmask_b32_e64 v194, 0, v194, s[78:79]
	v_add_u32_e32 v87, 18, v84
	v_cmp_gt_u32_e64 s[78:79], s98, v87
	v_cndmask_b32_e64 v195, 0, v195, s[50:51]
	v_add_u32_e32 v88, 19, v84
	v_cmp_gt_u32_e64 s[50:51], s98, v88
	v_cndmask_b32_e64 v196, 0, v196, s[30:31]
	v_add_u32_e32 v85, 24, v84
	v_cmp_gt_u32_e64 s[30:31], s98, v85
	v_cndmask_b32_e64 v197, 0, v197, s[36:37]
	v_add_u32_e32 v86, 25, v84
	v_cmp_gt_u32_e64 s[36:37], s98, v86
	v_cndmask_b32_e64 v198, 0, v198, s[78:79]
	v_add_u32_e32 v87, 26, v84
	v_cmp_gt_u32_e64 s[78:79], s98, v87
	v_cndmask_b32_e64 v199, 0, v199, s[50:51]
	v_add_u32_e32 v88, 27, v84
	v_cmp_gt_u32_e64 s[50:51], s98, v88
	v_nop
	v_cndmask_b32_e64 v200, 0, v200, s[30:31]
	v_cndmask_b32_e64 v201, 0, v201, s[36:37]
	v_cndmask_b32_e64 v202, 0, v202, s[78:79]
	v_cndmask_b32_e64 v203, 0, v203, s[50:51]
	v_cvt_pk_bf16_f32 v64, v188, v189
	v_cvt_pk_bf16_f32 v65, v190, v191
	v_cvt_pk_bf16_f32 v66, v192, v193
	v_cvt_pk_bf16_f32 v67, v194, v195
	v_cvt_pk_bf16_f32 v68, v196, v197
	v_cvt_pk_bf16_f32 v69, v198, v199
	v_cvt_pk_bf16_f32 v70, v200, v201
	v_cvt_pk_bf16_f32 v71, v202, v203
	v_pk_add_f32 v[232:233], v[232:233], v[188:189]
	v_pk_add_f32 v[232:233], v[232:233], v[190:191]
	v_pk_add_f32 v[232:233], v[232:233], v[192:193]
	v_pk_add_f32 v[232:233], v[232:233], v[194:195]
	v_pk_add_f32 v[232:233], v[232:233], v[196:197]
	v_pk_add_f32 v[232:233], v[232:233], v[198:199]
	v_pk_add_f32 v[232:233], v[232:233], v[200:201]
	v_pk_add_f32 v[232:233], v[232:233], v[202:203]
	ds_read2_b32 v[188:189], v115 offset0:204 offset1:205
	ds_read2_b32 v[190:191], v115 offset0:206 offset1:207
	ds_read2_b32 v[192:193], v115 offset0:212 offset1:213
	ds_read2_b32 v[194:195], v115 offset0:214 offset1:215
	ds_read2_b32 v[196:197], v115 offset0:221 offset1:222
	ds_read2_b32 v[198:199], v115 offset0:223 offset1:224
	ds_read2_b32 v[200:201], v115 offset0:229 offset1:230
	ds_read2_b32 v[202:203], v115 offset0:231 offset1:232
	v_mfma_f32_32x32x16_bf16 v[0:15], v[64:67], v[72:75], v[0:15]
	v_mfma_f32_32x32x16_bf16 v[16:31], v[64:67], v[76:79], v[16:31]
	v_mfma_f32_32x32x16_bf16 v[0:15], v[68:71], v[220:223], v[0:15]
	v_mfma_f32_32x32x16_bf16 v[16:31], v[68:71], v[224:227], v[16:31]
	s_add_i32 s90, s67, 384
	v_add_u32_e32 v80, s90, v235
	v_add_u32_e32 v83, s90, v236
	v_add_u32_e32 v99, s90, v237
	v_add_u32_e32 v253, s90, v238
	v_add_u32_e32 v254, s90, v100
	v_add_u32_e32 v255, s90, v149
	v_med3_i32 v80, v80, 0, s99
	v_med3_i32 v83, v83, 0, s99
	v_med3_i32 v99, v99, 0, s99
	v_med3_i32 v253, v253, 0, s99
	v_med3_i32 v254, v254, 0, s99
	v_med3_i32 v255, v255, 0, s99
	v_mad_u32_u24 v80, v80, s100, v252
	v_mad_u32_u24 v83, v83, s100, v252
	v_mad_u32_u24 v99, v99, s100, v252
	v_mad_u32_u24 v253, v253, s100, v252
	v_mad_u32_u24 v254, v254, s100, v153
	v_mad_u32_u24 v255, v255, s100, v153
	global_load_dwordx4 v[116:119], v80, s[82:83]
	global_load_dwordx4 v[120:123], v83, s[82:83]
	global_load_dwordx4 v[124:127], v99, s[82:83]
	global_load_dwordx4 v[128:131], v253, s[82:83]
	global_load_dwordx4 v[132:135], v254, s[82:83] offset:768
	global_load_dwordx4 v[136:139], v255, s[82:83] offset:768
	global_load_dwordx4 v[140:143], v254, s[82:83] offset:832
	global_load_dwordx4 v[144:147], v255, s[82:83] offset:832
	ds_read_b64_tr_b16 v[72:73], v231
	ds_read_b64_tr_b16 v[74:75], v231 offset:512
	ds_read_b64_tr_b16 v[76:77], v231 offset:2048
	ds_read_b64_tr_b16 v[78:79], v231 offset:2560
	ds_read_b64_tr_b16 v[220:221], v231 offset:1024
	ds_read_b64_tr_b16 v[222:223], v231 offset:1536
	ds_read_b64_tr_b16 v[224:225], v231 offset:3072
	ds_read_b64_tr_b16 v[226:227], v231 offset:3584
	v_exp_f32_e32 v32, v32
	v_exp_f32_e32 v33, v33
	v_exp_f32_e32 v34, v34
	v_exp_f32_e32 v35, v35
	s_waitcnt vmcnt(12)
	ds_write_b128 v247, v[156:159]
	ds_write_b128 v247, v[160:163] offset:1024
	ds_write_b128 v247, v[164:167] offset:2048
	ds_write_b128 v247, v[168:171] offset:3072
	ds_read_b128 v[156:159], v248
	ds_read_b128 v[160:163], v249
	ds_read_b128 v[164:167], v250
	ds_read_b128 v[168:171], v251
	s_waitcnt vmcnt(8)
	ds_write_b128 v112, v[172:175]
	ds_write_b128 v112, v[176:179] offset:1024
	ds_write_b128 v112, v[180:183] offset:2048
	ds_write_b128 v112, v[184:187] offset:3072
	v_exp_f32_e32 v36, v36
	v_exp_f32_e32 v37, v37
	v_exp_f32_e32 v38, v38
	v_exp_f32_e32 v39, v39
	s_waitcnt lgkmcnt(4)
	v_mfma_f32_32x32x16_bf16 v[188:203], v[156:159], v[48:51], v[188:203]
	v_exp_f32_e32 v40, v40
	v_exp_f32_e32 v41, v41
	v_mfma_f32_32x32x16_bf16 v[188:203], v[160:163], v[52:55], v[188:203]
	v_exp_f32_e32 v42, v42
	v_exp_f32_e32 v43, v43
	v_mfma_f32_32x32x16_bf16 v[188:203], v[164:167], v[56:59], v[188:203]
	v_exp_f32_e32 v44, v44
	v_exp_f32_e32 v45, v45
	v_mfma_f32_32x32x16_bf16 v[188:203], v[168:171], v[60:63], v[188:203]
	v_exp_f32_e32 v46, v46
	v_exp_f32_e32 v47, v47
	s_add_i32 s90, s67, 320
	v_add_u32_e32 v84, s90, v107
	v_add_u32_e32 v85, 0, v84
	v_add_u32_e32 v86, 1, v84
	v_add_u32_e32 v87, 2, v84
	v_add_u32_e32 v88, 3, v84
	v_cmp_gt_u32_e64 s[30:31], s98, v85
	v_cmp_gt_u32_e64 s[36:37], s98, v86
	v_cmp_gt_u32_e64 s[78:79], s98, v87
	v_cmp_gt_u32_e64 s[50:51], s98, v88
	v_cndmask_b32_e64 v32, 0, v32, s[30:31]
	v_add_u32_e32 v85, 8, v84
	v_cmp_gt_u32_e64 s[30:31], s98, v85
	v_cndmask_b32_e64 v33, 0, v33, s[36:37]
	v_add_u32_e32 v86, 9, v84
	v_cmp_gt_u32_e64 s[36:37], s98, v86
	v_cndmask_b32_e64 v34, 0, v34, s[78:79]
	v_add_u32_e32 v87, 10, v84
	v_cmp_gt_u32_e64 s[78:79], s98, v87
	v_cndmask_b32_e64 v35, 0, v35, s[50:51]
	v_add_u32_e32 v88, 11, v84
	v_cmp_gt_u32_e64 s[50:51], s98, v88
	v_cndmask_b32_e64 v36, 0, v36, s[30:31]
	v_add_u32_e32 v85, 16, v84
	v_cmp_gt_u32_e64 s[30:31], s98, v85
	v_cndmask_b32_e64 v37, 0, v37, s[36:37]
	v_add_u32_e32 v86, 17, v84
	v_cmp_gt_u32_e64 s[36:37], s98, v86
	v_cndmask_b32_e64 v38, 0, v38, s[78:79]
	v_add_u32_e32 v87, 18, v84
	v_cmp_gt_u32_e64 s[78:79], s98, v87
	v_cndmask_b32_e64 v39, 0, v39, s[50:51]
	v_add_u32_e32 v88, 19, v84
	v_cmp_gt_u32_e64 s[50:51], s98, v88
	v_cndmask_b32_e64 v40, 0, v40, s[30:31]
	v_add_u32_e32 v85, 24, v84
	v_cmp_gt_u32_e64 s[30:31], s98, v85
	v_cndmask_b32_e64 v41, 0, v41, s[36:37]
	v_add_u32_e32 v86, 25, v84
	v_cmp_gt_u32_e64 s[36:37], s98, v86
	v_cndmask_b32_e64 v42, 0, v42, s[78:79]
	v_add_u32_e32 v87, 26, v84
	v_cmp_gt_u32_e64 s[78:79], s98, v87
	v_cndmask_b32_e64 v43, 0, v43, s[50:51]
	v_add_u32_e32 v88, 27, v84
	v_cmp_gt_u32_e64 s[50:51], s98, v88
	v_nop
	v_cndmask_b32_e64 v44, 0, v44, s[30:31]
	v_cndmask_b32_e64 v45, 0, v45, s[36:37]
	v_cndmask_b32_e64 v46, 0, v46, s[78:79]
	v_cndmask_b32_e64 v47, 0, v47, s[50:51]
	v_cvt_pk_bf16_f32 v64, v32, v33
	v_cvt_pk_bf16_f32 v65, v34, v35
	v_cvt_pk_bf16_f32 v66, v36, v37
	v_cvt_pk_bf16_f32 v67, v38, v39
	v_cvt_pk_bf16_f32 v68, v40, v41
	v_cvt_pk_bf16_f32 v69, v42, v43
	v_cvt_pk_bf16_f32 v70, v44, v45
	v_cvt_pk_bf16_f32 v71, v46, v47
	v_pk_add_f32 v[232:233], v[232:233], v[32:33]
	v_pk_add_f32 v[232:233], v[232:233], v[34:35]
	v_pk_add_f32 v[232:233], v[232:233], v[36:37]
	v_pk_add_f32 v[232:233], v[232:233], v[38:39]
	v_pk_add_f32 v[232:233], v[232:233], v[40:41]
	v_pk_add_f32 v[232:233], v[232:233], v[42:43]
	v_pk_add_f32 v[232:233], v[232:233], v[44:45]
	v_pk_add_f32 v[232:233], v[232:233], v[46:47]
	v_add_u32_e32 v115, 952, v115
	ds_read2_b32 v[32:33], v115 offset0:0 offset1:1
	ds_read2_b32 v[34:35], v115 offset0:2 offset1:3
	ds_read2_b32 v[36:37], v115 offset0:8 offset1:9
	ds_read2_b32 v[38:39], v115 offset0:10 offset1:11
	ds_read2_b32 v[40:41], v115 offset0:17 offset1:18
	ds_read2_b32 v[42:43], v115 offset0:19 offset1:20
	ds_read2_b32 v[44:45], v115 offset0:25 offset1:26
	ds_read2_b32 v[46:47], v115 offset0:27 offset1:28
	v_mfma_f32_32x32x16_bf16 v[0:15], v[64:67], v[72:75], v[0:15]
	v_mfma_f32_32x32x16_bf16 v[16:31], v[64:67], v[76:79], v[16:31]
	v_mfma_f32_32x32x16_bf16 v[0:15], v[68:71], v[220:223], v[0:15]
	v_mfma_f32_32x32x16_bf16 v[16:31], v[68:71], v[224:227], v[16:31]
	s_add_i32 s90, s67, 416
	v_add_u32_e32 v80, s90, v235
	v_add_u32_e32 v83, s90, v236
	v_add_u32_e32 v99, s90, v237
	v_add_u32_e32 v253, s90, v238
	v_add_u32_e32 v254, s90, v100
	v_add_u32_e32 v255, s90, v149
	v_med3_i32 v80, v80, 0, s99
	v_med3_i32 v83, v83, 0, s99
	v_med3_i32 v99, v99, 0, s99
	v_med3_i32 v253, v253, 0, s99
	v_med3_i32 v254, v254, 0, s99
	v_med3_i32 v255, v255, 0, s99
	v_mad_u32_u24 v80, v80, s100, v252
	v_mad_u32_u24 v83, v83, s100, v252
	v_mad_u32_u24 v99, v99, s100, v252
	v_mad_u32_u24 v253, v253, s100, v252
	v_mad_u32_u24 v254, v254, s100, v153
	v_mad_u32_u24 v255, v255, s100, v153
	global_load_dwordx4 v[156:159], v80, s[82:83]
	global_load_dwordx4 v[160:163], v83, s[82:83]
	global_load_dwordx4 v[164:167], v99, s[82:83]
	global_load_dwordx4 v[168:171], v253, s[82:83]
	global_load_dwordx4 v[172:175], v254, s[82:83] offset:768
	global_load_dwordx4 v[176:179], v255, s[82:83] offset:768
	global_load_dwordx4 v[180:183], v254, s[82:83] offset:832
	global_load_dwordx4 v[184:187], v255, s[82:83] offset:832
	ds_read_b64_tr_b16 v[72:73], v231
	ds_read_b64_tr_b16 v[74:75], v231 offset:512
	ds_read_b64_tr_b16 v[76:77], v231 offset:2048
	ds_read_b64_tr_b16 v[78:79], v231 offset:2560
	ds_read_b64_tr_b16 v[220:221], v231 offset:1024
	ds_read_b64_tr_b16 v[222:223], v231 offset:1536
	ds_read_b64_tr_b16 v[224:225], v231 offset:3072
	ds_read_b64_tr_b16 v[226:227], v231 offset:3584
	v_exp_f32_e32 v188, v188
	v_exp_f32_e32 v189, v189
	v_exp_f32_e32 v190, v190
	v_exp_f32_e32 v191, v191
	s_waitcnt vmcnt(12)
	ds_write_b128 v247, v[116:119]
	ds_write_b128 v247, v[120:123] offset:1024
	ds_write_b128 v247, v[124:127] offset:2048
	ds_write_b128 v247, v[128:131] offset:3072
	ds_read_b128 v[116:119], v248
	ds_read_b128 v[120:123], v249
	ds_read_b128 v[124:127], v250
	ds_read_b128 v[128:131], v251
	s_waitcnt vmcnt(8)
	ds_write_b128 v112, v[132:135]
	ds_write_b128 v112, v[136:139] offset:1024
	ds_write_b128 v112, v[140:143] offset:2048
	ds_write_b128 v112, v[144:147] offset:3072
	v_exp_f32_e32 v192, v192
	v_exp_f32_e32 v193, v193
	v_exp_f32_e32 v194, v194
	v_exp_f32_e32 v195, v195
	s_waitcnt lgkmcnt(4)
	v_mfma_f32_32x32x16_bf16 v[32:47], v[116:119], v[48:51], v[32:47]
	v_exp_f32_e32 v196, v196
	v_exp_f32_e32 v197, v197
	v_mfma_f32_32x32x16_bf16 v[32:47], v[120:123], v[52:55], v[32:47]
	v_exp_f32_e32 v198, v198
	v_exp_f32_e32 v199, v199
	v_mfma_f32_32x32x16_bf16 v[32:47], v[124:127], v[56:59], v[32:47]
	v_exp_f32_e32 v200, v200
	v_exp_f32_e32 v201, v201
	v_mfma_f32_32x32x16_bf16 v[32:47], v[128:131], v[60:63], v[32:47]
	v_exp_f32_e32 v202, v202
	v_exp_f32_e32 v203, v203
	s_add_i32 s90, s67, 352
	v_add_u32_e32 v84, s90, v107
	v_add_u32_e32 v85, 0, v84
	v_add_u32_e32 v86, 1, v84
	v_add_u32_e32 v87, 2, v84
	v_add_u32_e32 v88, 3, v84
	v_cmp_gt_u32_e64 s[30:31], s98, v85
	v_cmp_gt_u32_e64 s[36:37], s98, v86
	v_cmp_gt_u32_e64 s[78:79], s98, v87
	v_cmp_gt_u32_e64 s[50:51], s98, v88
	v_cndmask_b32_e64 v188, 0, v188, s[30:31]
	v_add_u32_e32 v85, 8, v84
	v_cmp_gt_u32_e64 s[30:31], s98, v85
	v_cndmask_b32_e64 v189, 0, v189, s[36:37]
	v_add_u32_e32 v86, 9, v84
	v_cmp_gt_u32_e64 s[36:37], s98, v86
	v_cndmask_b32_e64 v190, 0, v190, s[78:79]
	v_add_u32_e32 v87, 10, v84
	v_cmp_gt_u32_e64 s[78:79], s98, v87
	v_cndmask_b32_e64 v191, 0, v191, s[50:51]
	v_add_u32_e32 v88, 11, v84
	v_cmp_gt_u32_e64 s[50:51], s98, v88
	v_cndmask_b32_e64 v192, 0, v192, s[30:31]
	v_add_u32_e32 v85, 16, v84
	v_cmp_gt_u32_e64 s[30:31], s98, v85
	v_cndmask_b32_e64 v193, 0, v193, s[36:37]
	v_add_u32_e32 v86, 17, v84
	v_cmp_gt_u32_e64 s[36:37], s98, v86
	v_cndmask_b32_e64 v194, 0, v194, s[78:79]
	v_add_u32_e32 v87, 18, v84
	v_cmp_gt_u32_e64 s[78:79], s98, v87
	v_cndmask_b32_e64 v195, 0, v195, s[50:51]
	v_add_u32_e32 v88, 19, v84
	v_cmp_gt_u32_e64 s[50:51], s98, v88
	v_cndmask_b32_e64 v196, 0, v196, s[30:31]
	v_add_u32_e32 v85, 24, v84
	v_cmp_gt_u32_e64 s[30:31], s98, v85
	v_cndmask_b32_e64 v197, 0, v197, s[36:37]
	v_add_u32_e32 v86, 25, v84
	v_cmp_gt_u32_e64 s[36:37], s98, v86
	v_cndmask_b32_e64 v198, 0, v198, s[78:79]
	v_add_u32_e32 v87, 26, v84
	v_cmp_gt_u32_e64 s[78:79], s98, v87
	v_cndmask_b32_e64 v199, 0, v199, s[50:51]
	v_add_u32_e32 v88, 27, v84
	v_cmp_gt_u32_e64 s[50:51], s98, v88
	v_nop
	v_cndmask_b32_e64 v200, 0, v200, s[30:31]
	v_cndmask_b32_e64 v201, 0, v201, s[36:37]
	v_cndmask_b32_e64 v202, 0, v202, s[78:79]
	v_cndmask_b32_e64 v203, 0, v203, s[50:51]
	v_cvt_pk_bf16_f32 v64, v188, v189
	v_cvt_pk_bf16_f32 v65, v190, v191
	v_cvt_pk_bf16_f32 v66, v192, v193
	v_cvt_pk_bf16_f32 v67, v194, v195
	v_cvt_pk_bf16_f32 v68, v196, v197
	v_cvt_pk_bf16_f32 v69, v198, v199
	v_cvt_pk_bf16_f32 v70, v200, v201
	v_cvt_pk_bf16_f32 v71, v202, v203
	v_pk_add_f32 v[232:233], v[232:233], v[188:189]
	v_pk_add_f32 v[232:233], v[232:233], v[190:191]
	v_pk_add_f32 v[232:233], v[232:233], v[192:193]
	v_pk_add_f32 v[232:233], v[232:233], v[194:195]
	v_pk_add_f32 v[232:233], v[232:233], v[196:197]
	v_pk_add_f32 v[232:233], v[232:233], v[198:199]
	v_pk_add_f32 v[232:233], v[232:233], v[200:201]
	v_pk_add_f32 v[232:233], v[232:233], v[202:203]
	ds_read2_b32 v[188:189], v115 offset0:34 offset1:35
	ds_read2_b32 v[190:191], v115 offset0:36 offset1:37
	ds_read2_b32 v[192:193], v115 offset0:42 offset1:43
	ds_read2_b32 v[194:195], v115 offset0:44 offset1:45
	ds_read2_b32 v[196:197], v115 offset0:51 offset1:52
	ds_read2_b32 v[198:199], v115 offset0:53 offset1:54
	ds_read2_b32 v[200:201], v115 offset0:59 offset1:60
	ds_read2_b32 v[202:203], v115 offset0:61 offset1:62
	v_mfma_f32_32x32x16_bf16 v[0:15], v[64:67], v[72:75], v[0:15]
	v_mfma_f32_32x32x16_bf16 v[16:31], v[64:67], v[76:79], v[16:31]
	v_mfma_f32_32x32x16_bf16 v[0:15], v[68:71], v[220:223], v[0:15]
	v_mfma_f32_32x32x16_bf16 v[16:31], v[68:71], v[224:227], v[16:31]
	s_add_i32 s90, s67, 448
	v_add_u32_e32 v80, s90, v235
	v_add_u32_e32 v83, s90, v236
	v_add_u32_e32 v99, s90, v237
	v_add_u32_e32 v253, s90, v238
	v_add_u32_e32 v254, s90, v100
	v_add_u32_e32 v255, s90, v149
	v_med3_i32 v80, v80, 0, s99
	v_med3_i32 v83, v83, 0, s99
	v_med3_i32 v99, v99, 0, s99
	v_med3_i32 v253, v253, 0, s99
	v_med3_i32 v254, v254, 0, s99
	v_med3_i32 v255, v255, 0, s99
	v_mad_u32_u24 v80, v80, s100, v252
	v_mad_u32_u24 v83, v83, s100, v252
	v_mad_u32_u24 v99, v99, s100, v252
	v_mad_u32_u24 v253, v253, s100, v252
	v_mad_u32_u24 v254, v254, s100, v153
	v_mad_u32_u24 v255, v255, s100, v153
	global_load_dwordx4 v[116:119], v80, s[82:83]
	global_load_dwordx4 v[120:123], v83, s[82:83]
	global_load_dwordx4 v[124:127], v99, s[82:83]
	global_load_dwordx4 v[128:131], v253, s[82:83]
	global_load_dwordx4 v[132:135], v254, s[82:83] offset:768
	global_load_dwordx4 v[136:139], v255, s[82:83] offset:768
	global_load_dwordx4 v[140:143], v254, s[82:83] offset:832
	global_load_dwordx4 v[144:147], v255, s[82:83] offset:832
	ds_read_b64_tr_b16 v[72:73], v231
	ds_read_b64_tr_b16 v[74:75], v231 offset:512
	ds_read_b64_tr_b16 v[76:77], v231 offset:2048
	ds_read_b64_tr_b16 v[78:79], v231 offset:2560
	ds_read_b64_tr_b16 v[220:221], v231 offset:1024
	ds_read_b64_tr_b16 v[222:223], v231 offset:1536
	ds_read_b64_tr_b16 v[224:225], v231 offset:3072
	ds_read_b64_tr_b16 v[226:227], v231 offset:3584
	v_exp_f32_e32 v32, v32
	v_exp_f32_e32 v33, v33
	v_exp_f32_e32 v34, v34
	v_exp_f32_e32 v35, v35
	s_waitcnt vmcnt(12)
	ds_write_b128 v247, v[156:159]
	ds_write_b128 v247, v[160:163] offset:1024
	ds_write_b128 v247, v[164:167] offset:2048
	ds_write_b128 v247, v[168:171] offset:3072
	ds_read_b128 v[156:159], v248
	ds_read_b128 v[160:163], v249
	ds_read_b128 v[164:167], v250
	ds_read_b128 v[168:171], v251
	s_waitcnt vmcnt(8)
	ds_write_b128 v112, v[172:175]
	ds_write_b128 v112, v[176:179] offset:1024
	ds_write_b128 v112, v[180:183] offset:2048
	ds_write_b128 v112, v[184:187] offset:3072
	v_exp_f32_e32 v36, v36
	v_exp_f32_e32 v37, v37
	v_exp_f32_e32 v38, v38
	v_exp_f32_e32 v39, v39
	s_waitcnt lgkmcnt(4)
	v_mfma_f32_32x32x16_bf16 v[188:203], v[156:159], v[48:51], v[188:203]
	v_exp_f32_e32 v40, v40
	v_exp_f32_e32 v41, v41
	v_mfma_f32_32x32x16_bf16 v[188:203], v[160:163], v[52:55], v[188:203]
	v_exp_f32_e32 v42, v42
	v_exp_f32_e32 v43, v43
	v_mfma_f32_32x32x16_bf16 v[188:203], v[164:167], v[56:59], v[188:203]
	v_exp_f32_e32 v44, v44
	v_exp_f32_e32 v45, v45
	v_mfma_f32_32x32x16_bf16 v[188:203], v[168:171], v[60:63], v[188:203]
	v_exp_f32_e32 v46, v46
	v_exp_f32_e32 v47, v47
	s_add_i32 s90, s67, 384
	v_add_u32_e32 v84, s90, v107
	v_add_u32_e32 v85, 0, v84
	v_add_u32_e32 v86, 1, v84
	v_add_u32_e32 v87, 2, v84
	v_add_u32_e32 v88, 3, v84
	v_cmp_gt_u32_e64 s[30:31], s98, v85
	v_cmp_gt_u32_e64 s[36:37], s98, v86
	v_cmp_gt_u32_e64 s[78:79], s98, v87
	v_cmp_gt_u32_e64 s[50:51], s98, v88
	v_cndmask_b32_e64 v32, 0, v32, s[30:31]
	v_add_u32_e32 v85, 8, v84
	v_cmp_gt_u32_e64 s[30:31], s98, v85
	v_cndmask_b32_e64 v33, 0, v33, s[36:37]
	v_add_u32_e32 v86, 9, v84
	v_cmp_gt_u32_e64 s[36:37], s98, v86
	v_cndmask_b32_e64 v34, 0, v34, s[78:79]
	v_add_u32_e32 v87, 10, v84
	v_cmp_gt_u32_e64 s[78:79], s98, v87
	v_cndmask_b32_e64 v35, 0, v35, s[50:51]
	v_add_u32_e32 v88, 11, v84
	v_cmp_gt_u32_e64 s[50:51], s98, v88
	v_cndmask_b32_e64 v36, 0, v36, s[30:31]
	v_add_u32_e32 v85, 16, v84
	v_cmp_gt_u32_e64 s[30:31], s98, v85
	v_cndmask_b32_e64 v37, 0, v37, s[36:37]
	v_add_u32_e32 v86, 17, v84
	v_cmp_gt_u32_e64 s[36:37], s98, v86
	v_cndmask_b32_e64 v38, 0, v38, s[78:79]
	v_add_u32_e32 v87, 18, v84
	v_cmp_gt_u32_e64 s[78:79], s98, v87
	v_cndmask_b32_e64 v39, 0, v39, s[50:51]
	v_add_u32_e32 v88, 19, v84
	v_cmp_gt_u32_e64 s[50:51], s98, v88
	v_cndmask_b32_e64 v40, 0, v40, s[30:31]
	v_add_u32_e32 v85, 24, v84
	v_cmp_gt_u32_e64 s[30:31], s98, v85
	v_cndmask_b32_e64 v41, 0, v41, s[36:37]
	v_add_u32_e32 v86, 25, v84
	v_cmp_gt_u32_e64 s[36:37], s98, v86
	v_cndmask_b32_e64 v42, 0, v42, s[78:79]
	v_add_u32_e32 v87, 26, v84
	v_cmp_gt_u32_e64 s[78:79], s98, v87
	v_cndmask_b32_e64 v43, 0, v43, s[50:51]
	v_add_u32_e32 v88, 27, v84
	v_cmp_gt_u32_e64 s[50:51], s98, v88
	v_nop
	v_cndmask_b32_e64 v44, 0, v44, s[30:31]
	v_cndmask_b32_e64 v45, 0, v45, s[36:37]
	v_cndmask_b32_e64 v46, 0, v46, s[78:79]
	v_cndmask_b32_e64 v47, 0, v47, s[50:51]
	v_cvt_pk_bf16_f32 v64, v32, v33
	v_cvt_pk_bf16_f32 v65, v34, v35
	v_cvt_pk_bf16_f32 v66, v36, v37
	v_cvt_pk_bf16_f32 v67, v38, v39
	v_cvt_pk_bf16_f32 v68, v40, v41
	v_cvt_pk_bf16_f32 v69, v42, v43
	v_cvt_pk_bf16_f32 v70, v44, v45
	v_cvt_pk_bf16_f32 v71, v46, v47
	v_pk_add_f32 v[232:233], v[232:233], v[32:33]
	v_pk_add_f32 v[232:233], v[232:233], v[34:35]
	v_pk_add_f32 v[232:233], v[232:233], v[36:37]
	v_pk_add_f32 v[232:233], v[232:233], v[38:39]
	v_pk_add_f32 v[232:233], v[232:233], v[40:41]
	v_pk_add_f32 v[232:233], v[232:233], v[42:43]
	v_pk_add_f32 v[232:233], v[232:233], v[44:45]
	v_pk_add_f32 v[232:233], v[232:233], v[46:47]
	ds_read2_b32 v[32:33], v115 offset0:68 offset1:69
	ds_read2_b32 v[34:35], v115 offset0:70 offset1:71
	ds_read2_b32 v[36:37], v115 offset0:76 offset1:77
	ds_read2_b32 v[38:39], v115 offset0:78 offset1:79
	ds_read2_b32 v[40:41], v115 offset0:85 offset1:86
	ds_read2_b32 v[42:43], v115 offset0:87 offset1:88
	ds_read2_b32 v[44:45], v115 offset0:93 offset1:94
	ds_read2_b32 v[46:47], v115 offset0:95 offset1:96
	v_mfma_f32_32x32x16_bf16 v[0:15], v[64:67], v[72:75], v[0:15]
	v_mfma_f32_32x32x16_bf16 v[16:31], v[64:67], v[76:79], v[16:31]
	v_mfma_f32_32x32x16_bf16 v[0:15], v[68:71], v[220:223], v[0:15]
	v_mfma_f32_32x32x16_bf16 v[16:31], v[68:71], v[224:227], v[16:31]
	s_add_i32 s90, s67, 480
	v_add_u32_e32 v80, s90, v235
	v_add_u32_e32 v83, s90, v236
	v_add_u32_e32 v99, s90, v237
	v_add_u32_e32 v253, s90, v238
	v_add_u32_e32 v254, s90, v100
	v_add_u32_e32 v255, s90, v149
	v_med3_i32 v80, v80, 0, s99
	v_med3_i32 v83, v83, 0, s99
	v_med3_i32 v99, v99, 0, s99
	v_med3_i32 v253, v253, 0, s99
	v_med3_i32 v254, v254, 0, s99
	v_med3_i32 v255, v255, 0, s99
	v_mad_u32_u24 v80, v80, s100, v252
	v_mad_u32_u24 v83, v83, s100, v252
	v_mad_u32_u24 v99, v99, s100, v252
	v_mad_u32_u24 v253, v253, s100, v252
	v_mad_u32_u24 v254, v254, s100, v153
	v_mad_u32_u24 v255, v255, s100, v153
	global_load_dwordx4 v[156:159], v80, s[82:83]
	global_load_dwordx4 v[160:163], v83, s[82:83]
	global_load_dwordx4 v[164:167], v99, s[82:83]
	global_load_dwordx4 v[168:171], v253, s[82:83]
	global_load_dwordx4 v[172:175], v254, s[82:83] offset:768
	global_load_dwordx4 v[176:179], v255, s[82:83] offset:768
	global_load_dwordx4 v[180:183], v254, s[82:83] offset:832
	global_load_dwordx4 v[184:187], v255, s[82:83] offset:832
	ds_read_b64_tr_b16 v[72:73], v231
	ds_read_b64_tr_b16 v[74:75], v231 offset:512
	ds_read_b64_tr_b16 v[76:77], v231 offset:2048
	ds_read_b64_tr_b16 v[78:79], v231 offset:2560
	ds_read_b64_tr_b16 v[220:221], v231 offset:1024
	ds_read_b64_tr_b16 v[222:223], v231 offset:1536
	ds_read_b64_tr_b16 v[224:225], v231 offset:3072
	ds_read_b64_tr_b16 v[226:227], v231 offset:3584
	v_exp_f32_e32 v188, v188
	v_exp_f32_e32 v189, v189
	v_exp_f32_e32 v190, v190
	v_exp_f32_e32 v191, v191
	s_waitcnt vmcnt(12)
	ds_write_b128 v247, v[116:119]
	ds_write_b128 v247, v[120:123] offset:1024
	ds_write_b128 v247, v[124:127] offset:2048
	ds_write_b128 v247, v[128:131] offset:3072
	ds_read_b128 v[116:119], v248
	ds_read_b128 v[120:123], v249
	ds_read_b128 v[124:127], v250
	ds_read_b128 v[128:131], v251
	s_waitcnt vmcnt(8)
	ds_write_b128 v112, v[132:135]
	ds_write_b128 v112, v[136:139] offset:1024
	ds_write_b128 v112, v[140:143] offset:2048
	ds_write_b128 v112, v[144:147] offset:3072
	v_exp_f32_e32 v192, v192
	v_exp_f32_e32 v193, v193
	v_exp_f32_e32 v194, v194
	v_exp_f32_e32 v195, v195
	s_waitcnt lgkmcnt(4)
	v_mfma_f32_32x32x16_bf16 v[32:47], v[116:119], v[48:51], v[32:47]
	v_exp_f32_e32 v196, v196
	v_exp_f32_e32 v197, v197
	v_mfma_f32_32x32x16_bf16 v[32:47], v[120:123], v[52:55], v[32:47]
	v_exp_f32_e32 v198, v198
	v_exp_f32_e32 v199, v199
	v_mfma_f32_32x32x16_bf16 v[32:47], v[124:127], v[56:59], v[32:47]
	v_exp_f32_e32 v200, v200
	v_exp_f32_e32 v201, v201
	v_mfma_f32_32x32x16_bf16 v[32:47], v[128:131], v[60:63], v[32:47]
	v_exp_f32_e32 v202, v202
	v_exp_f32_e32 v203, v203
	s_add_i32 s90, s67, 416
	v_add_u32_e32 v84, s90, v107
	v_add_u32_e32 v85, 0, v84
	v_add_u32_e32 v86, 1, v84
	v_add_u32_e32 v87, 2, v84
	v_add_u32_e32 v88, 3, v84
	v_cmp_gt_u32_e64 s[30:31], s98, v85
	v_cmp_gt_u32_e64 s[36:37], s98, v86
	v_cmp_gt_u32_e64 s[78:79], s98, v87
	v_cmp_gt_u32_e64 s[50:51], s98, v88
	v_cndmask_b32_e64 v188, 0, v188, s[30:31]
	v_add_u32_e32 v85, 8, v84
	v_cmp_gt_u32_e64 s[30:31], s98, v85
	v_cndmask_b32_e64 v189, 0, v189, s[36:37]
	v_add_u32_e32 v86, 9, v84
	v_cmp_gt_u32_e64 s[36:37], s98, v86
	v_cndmask_b32_e64 v190, 0, v190, s[78:79]
	v_add_u32_e32 v87, 10, v84
	v_cmp_gt_u32_e64 s[78:79], s98, v87
	v_cndmask_b32_e64 v191, 0, v191, s[50:51]
	v_add_u32_e32 v88, 11, v84
	v_cmp_gt_u32_e64 s[50:51], s98, v88
	v_cndmask_b32_e64 v192, 0, v192, s[30:31]
	v_add_u32_e32 v85, 16, v84
	v_cmp_gt_u32_e64 s[30:31], s98, v85
	v_cndmask_b32_e64 v193, 0, v193, s[36:37]
	v_add_u32_e32 v86, 17, v84
	v_cmp_gt_u32_e64 s[36:37], s98, v86
	v_cndmask_b32_e64 v194, 0, v194, s[78:79]
	v_add_u32_e32 v87, 18, v84
	v_cmp_gt_u32_e64 s[78:79], s98, v87
	v_cndmask_b32_e64 v195, 0, v195, s[50:51]
	v_add_u32_e32 v88, 19, v84
	v_cmp_gt_u32_e64 s[50:51], s98, v88
	v_cndmask_b32_e64 v196, 0, v196, s[30:31]
	v_add_u32_e32 v85, 24, v84
	v_cmp_gt_u32_e64 s[30:31], s98, v85
	v_cndmask_b32_e64 v197, 0, v197, s[36:37]
	v_add_u32_e32 v86, 25, v84
	v_cmp_gt_u32_e64 s[36:37], s98, v86
	v_cndmask_b32_e64 v198, 0, v198, s[78:79]
	v_add_u32_e32 v87, 26, v84
	v_cmp_gt_u32_e64 s[78:79], s98, v87
	v_cndmask_b32_e64 v199, 0, v199, s[50:51]
	v_add_u32_e32 v88, 27, v84
	v_cmp_gt_u32_e64 s[50:51], s98, v88
	v_nop
	v_cndmask_b32_e64 v200, 0, v200, s[30:31]
	v_cndmask_b32_e64 v201, 0, v201, s[36:37]
	v_cndmask_b32_e64 v202, 0, v202, s[78:79]
	v_cndmask_b32_e64 v203, 0, v203, s[50:51]
	v_cvt_pk_bf16_f32 v64, v188, v189
	v_cvt_pk_bf16_f32 v65, v190, v191
	v_cvt_pk_bf16_f32 v66, v192, v193
	v_cvt_pk_bf16_f32 v67, v194, v195
	v_cvt_pk_bf16_f32 v68, v196, v197
	v_cvt_pk_bf16_f32 v69, v198, v199
	v_cvt_pk_bf16_f32 v70, v200, v201
	v_cvt_pk_bf16_f32 v71, v202, v203
	v_pk_add_f32 v[232:233], v[232:233], v[188:189]
	v_pk_add_f32 v[232:233], v[232:233], v[190:191]
	v_pk_add_f32 v[232:233], v[232:233], v[192:193]
	v_pk_add_f32 v[232:233], v[232:233], v[194:195]
	v_pk_add_f32 v[232:233], v[232:233], v[196:197]
	v_pk_add_f32 v[232:233], v[232:233], v[198:199]
	v_pk_add_f32 v[232:233], v[232:233], v[200:201]
	v_pk_add_f32 v[232:233], v[232:233], v[202:203]
	ds_read2_b32 v[188:189], v115 offset0:102 offset1:103
	ds_read2_b32 v[190:191], v115 offset0:104 offset1:105
	ds_read2_b32 v[192:193], v115 offset0:110 offset1:111
	ds_read2_b32 v[194:195], v115 offset0:112 offset1:113
	ds_read2_b32 v[196:197], v115 offset0:119 offset1:120
	ds_read2_b32 v[198:199], v115 offset0:121 offset1:122
	ds_read2_b32 v[200:201], v115 offset0:127 offset1:128
	ds_read2_b32 v[202:203], v115 offset0:129 offset1:130
	v_mfma_f32_32x32x16_bf16 v[0:15], v[64:67], v[72:75], v[0:15]
	v_mfma_f32_32x32x16_bf16 v[16:31], v[64:67], v[76:79], v[16:31]
	v_mfma_f32_32x32x16_bf16 v[0:15], v[68:71], v[220:223], v[0:15]
	v_mfma_f32_32x32x16_bf16 v[16:31], v[68:71], v[224:227], v[16:31]
	s_add_i32 s90, s67, 512
	v_add_u32_e32 v80, s90, v235
	v_add_u32_e32 v83, s90, v236
	v_add_u32_e32 v99, s90, v237
	v_add_u32_e32 v253, s90, v238
	v_add_u32_e32 v254, s90, v100
	v_add_u32_e32 v255, s90, v149
	v_med3_i32 v80, v80, 0, s99
	v_med3_i32 v83, v83, 0, s99
	v_med3_i32 v99, v99, 0, s99
	v_med3_i32 v253, v253, 0, s99
	v_med3_i32 v254, v254, 0, s99
	v_med3_i32 v255, v255, 0, s99
	v_mad_u32_u24 v80, v80, s100, v252
	v_mad_u32_u24 v83, v83, s100, v252
	v_mad_u32_u24 v99, v99, s100, v252
	v_mad_u32_u24 v253, v253, s100, v252
	v_mad_u32_u24 v254, v254, s100, v153
	v_mad_u32_u24 v255, v255, s100, v153
	global_load_dwordx4 v[116:119], v80, s[82:83]
	global_load_dwordx4 v[120:123], v83, s[82:83]
	global_load_dwordx4 v[124:127], v99, s[82:83]
	global_load_dwordx4 v[128:131], v253, s[82:83]
	global_load_dwordx4 v[132:135], v254, s[82:83] offset:768
	global_load_dwordx4 v[136:139], v255, s[82:83] offset:768
	global_load_dwordx4 v[140:143], v254, s[82:83] offset:832
	global_load_dwordx4 v[144:147], v255, s[82:83] offset:832
	ds_read_b64_tr_b16 v[72:73], v231
	ds_read_b64_tr_b16 v[74:75], v231 offset:512
	ds_read_b64_tr_b16 v[76:77], v231 offset:2048
	ds_read_b64_tr_b16 v[78:79], v231 offset:2560
	ds_read_b64_tr_b16 v[220:221], v231 offset:1024
	ds_read_b64_tr_b16 v[222:223], v231 offset:1536
	ds_read_b64_tr_b16 v[224:225], v231 offset:3072
	ds_read_b64_tr_b16 v[226:227], v231 offset:3584
	v_exp_f32_e32 v32, v32
	v_exp_f32_e32 v33, v33
	v_exp_f32_e32 v34, v34
	v_exp_f32_e32 v35, v35
	s_waitcnt vmcnt(12)
	ds_write_b128 v247, v[156:159]
	ds_write_b128 v247, v[160:163] offset:1024
	ds_write_b128 v247, v[164:167] offset:2048
	ds_write_b128 v247, v[168:171] offset:3072
	ds_read_b128 v[156:159], v248
	ds_read_b128 v[160:163], v249
	ds_read_b128 v[164:167], v250
	ds_read_b128 v[168:171], v251
	s_waitcnt vmcnt(8)
	ds_write_b128 v112, v[172:175]
	ds_write_b128 v112, v[176:179] offset:1024
	ds_write_b128 v112, v[180:183] offset:2048
	ds_write_b128 v112, v[184:187] offset:3072
	v_exp_f32_e32 v36, v36
	v_exp_f32_e32 v37, v37
	v_exp_f32_e32 v38, v38
	v_exp_f32_e32 v39, v39
	s_waitcnt lgkmcnt(4)
	v_mfma_f32_32x32x16_bf16 v[188:203], v[156:159], v[48:51], v[188:203]
	v_exp_f32_e32 v40, v40
	v_exp_f32_e32 v41, v41
	v_mfma_f32_32x32x16_bf16 v[188:203], v[160:163], v[52:55], v[188:203]
	v_exp_f32_e32 v42, v42
	v_exp_f32_e32 v43, v43
	v_mfma_f32_32x32x16_bf16 v[188:203], v[164:167], v[56:59], v[188:203]
	v_exp_f32_e32 v44, v44
	v_exp_f32_e32 v45, v45
	v_mfma_f32_32x32x16_bf16 v[188:203], v[168:171], v[60:63], v[188:203]
	v_exp_f32_e32 v46, v46
	v_exp_f32_e32 v47, v47
	s_add_i32 s90, s67, 448
	v_add_u32_e32 v84, s90, v107
	v_add_u32_e32 v85, 0, v84
	v_add_u32_e32 v86, 1, v84
	v_add_u32_e32 v87, 2, v84
	v_add_u32_e32 v88, 3, v84
	v_cmp_gt_u32_e64 s[30:31], s98, v85
	v_cmp_gt_u32_e64 s[36:37], s98, v86
	v_cmp_gt_u32_e64 s[78:79], s98, v87
	v_cmp_gt_u32_e64 s[50:51], s98, v88
	v_cndmask_b32_e64 v32, 0, v32, s[30:31]
	v_add_u32_e32 v85, 8, v84
	v_cmp_gt_u32_e64 s[30:31], s98, v85
	v_cndmask_b32_e64 v33, 0, v33, s[36:37]
	v_add_u32_e32 v86, 9, v84
	v_cmp_gt_u32_e64 s[36:37], s98, v86
	v_cndmask_b32_e64 v34, 0, v34, s[78:79]
	v_add_u32_e32 v87, 10, v84
	v_cmp_gt_u32_e64 s[78:79], s98, v87
	v_cndmask_b32_e64 v35, 0, v35, s[50:51]
	v_add_u32_e32 v88, 11, v84
	v_cmp_gt_u32_e64 s[50:51], s98, v88
	v_cndmask_b32_e64 v36, 0, v36, s[30:31]
	v_add_u32_e32 v85, 16, v84
	v_cmp_gt_u32_e64 s[30:31], s98, v85
	v_cndmask_b32_e64 v37, 0, v37, s[36:37]
	v_add_u32_e32 v86, 17, v84
	v_cmp_gt_u32_e64 s[36:37], s98, v86
	v_cndmask_b32_e64 v38, 0, v38, s[78:79]
	v_add_u32_e32 v87, 18, v84
	v_cmp_gt_u32_e64 s[78:79], s98, v87
	v_cndmask_b32_e64 v39, 0, v39, s[50:51]
	v_add_u32_e32 v88, 19, v84
	v_cmp_gt_u32_e64 s[50:51], s98, v88
	v_cndmask_b32_e64 v40, 0, v40, s[30:31]
	v_add_u32_e32 v85, 24, v84
	v_cmp_gt_u32_e64 s[30:31], s98, v85
	v_cndmask_b32_e64 v41, 0, v41, s[36:37]
	v_add_u32_e32 v86, 25, v84
	v_cmp_gt_u32_e64 s[36:37], s98, v86
	v_cndmask_b32_e64 v42, 0, v42, s[78:79]
	v_add_u32_e32 v87, 26, v84
	v_cmp_gt_u32_e64 s[78:79], s98, v87
	v_cndmask_b32_e64 v43, 0, v43, s[50:51]
	v_add_u32_e32 v88, 27, v84
	v_cmp_gt_u32_e64 s[50:51], s98, v88
	v_nop
	v_cndmask_b32_e64 v44, 0, v44, s[30:31]
	v_cndmask_b32_e64 v45, 0, v45, s[36:37]
	v_cndmask_b32_e64 v46, 0, v46, s[78:79]
	v_cndmask_b32_e64 v47, 0, v47, s[50:51]
	v_cvt_pk_bf16_f32 v64, v32, v33
	v_cvt_pk_bf16_f32 v65, v34, v35
	v_cvt_pk_bf16_f32 v66, v36, v37
	v_cvt_pk_bf16_f32 v67, v38, v39
	v_cvt_pk_bf16_f32 v68, v40, v41
	v_cvt_pk_bf16_f32 v69, v42, v43
	v_cvt_pk_bf16_f32 v70, v44, v45
	v_cvt_pk_bf16_f32 v71, v46, v47
	v_pk_add_f32 v[232:233], v[232:233], v[32:33]
	v_pk_add_f32 v[232:233], v[232:233], v[34:35]
	v_pk_add_f32 v[232:233], v[232:233], v[36:37]
	v_pk_add_f32 v[232:233], v[232:233], v[38:39]
	v_pk_add_f32 v[232:233], v[232:233], v[40:41]
	v_pk_add_f32 v[232:233], v[232:233], v[42:43]
	v_pk_add_f32 v[232:233], v[232:233], v[44:45]
	v_pk_add_f32 v[232:233], v[232:233], v[46:47]
	ds_read2_b32 v[32:33], v115 offset0:136 offset1:137
	ds_read2_b32 v[34:35], v115 offset0:138 offset1:139
	ds_read2_b32 v[36:37], v115 offset0:144 offset1:145
	ds_read2_b32 v[38:39], v115 offset0:146 offset1:147
	ds_read2_b32 v[40:41], v115 offset0:153 offset1:154
	ds_read2_b32 v[42:43], v115 offset0:155 offset1:156
	ds_read2_b32 v[44:45], v115 offset0:161 offset1:162
	ds_read2_b32 v[46:47], v115 offset0:163 offset1:164
	v_mfma_f32_32x32x16_bf16 v[0:15], v[64:67], v[72:75], v[0:15]
	v_mfma_f32_32x32x16_bf16 v[16:31], v[64:67], v[76:79], v[16:31]
	v_mfma_f32_32x32x16_bf16 v[0:15], v[68:71], v[220:223], v[0:15]
	v_mfma_f32_32x32x16_bf16 v[16:31], v[68:71], v[224:227], v[16:31]
	s_add_i32 s90, s67, 544
	v_add_u32_e32 v80, s90, v235
	v_add_u32_e32 v83, s90, v236
	v_add_u32_e32 v99, s90, v237
	v_add_u32_e32 v253, s90, v238
	v_add_u32_e32 v254, s90, v100
	v_add_u32_e32 v255, s90, v149
	v_med3_i32 v80, v80, 0, s99
	v_med3_i32 v83, v83, 0, s99
	v_med3_i32 v99, v99, 0, s99
	v_med3_i32 v253, v253, 0, s99
	v_med3_i32 v254, v254, 0, s99
	v_med3_i32 v255, v255, 0, s99
	v_mad_u32_u24 v80, v80, s100, v252
	v_mad_u32_u24 v83, v83, s100, v252
	v_mad_u32_u24 v99, v99, s100, v252
	v_mad_u32_u24 v253, v253, s100, v252
	v_mad_u32_u24 v254, v254, s100, v153
	v_mad_u32_u24 v255, v255, s100, v153
	global_load_dwordx4 v[156:159], v80, s[82:83]
	global_load_dwordx4 v[160:163], v83, s[82:83]
	global_load_dwordx4 v[164:167], v99, s[82:83]
	global_load_dwordx4 v[168:171], v253, s[82:83]
	global_load_dwordx4 v[172:175], v254, s[82:83] offset:768
	global_load_dwordx4 v[176:179], v255, s[82:83] offset:768
	global_load_dwordx4 v[180:183], v254, s[82:83] offset:832
	global_load_dwordx4 v[184:187], v255, s[82:83] offset:832
	ds_read_b64_tr_b16 v[72:73], v231
	ds_read_b64_tr_b16 v[74:75], v231 offset:512
	ds_read_b64_tr_b16 v[76:77], v231 offset:2048
	ds_read_b64_tr_b16 v[78:79], v231 offset:2560
	ds_read_b64_tr_b16 v[220:221], v231 offset:1024
	ds_read_b64_tr_b16 v[222:223], v231 offset:1536
	ds_read_b64_tr_b16 v[224:225], v231 offset:3072
	ds_read_b64_tr_b16 v[226:227], v231 offset:3584
	v_exp_f32_e32 v188, v188
	v_exp_f32_e32 v189, v189
	v_exp_f32_e32 v190, v190
	v_exp_f32_e32 v191, v191
	s_waitcnt vmcnt(12)
	ds_write_b128 v247, v[116:119]
	ds_write_b128 v247, v[120:123] offset:1024
	ds_write_b128 v247, v[124:127] offset:2048
	ds_write_b128 v247, v[128:131] offset:3072
	ds_read_b128 v[116:119], v248
	ds_read_b128 v[120:123], v249
	ds_read_b128 v[124:127], v250
	ds_read_b128 v[128:131], v251
	s_waitcnt vmcnt(8)
	ds_write_b128 v112, v[132:135]
	ds_write_b128 v112, v[136:139] offset:1024
	ds_write_b128 v112, v[140:143] offset:2048
	ds_write_b128 v112, v[144:147] offset:3072
	v_exp_f32_e32 v192, v192
	v_exp_f32_e32 v193, v193
	v_exp_f32_e32 v194, v194
	v_exp_f32_e32 v195, v195
	s_waitcnt lgkmcnt(4)
	v_mfma_f32_32x32x16_bf16 v[32:47], v[116:119], v[48:51], v[32:47]
	v_exp_f32_e32 v196, v196
	v_exp_f32_e32 v197, v197
	v_mfma_f32_32x32x16_bf16 v[32:47], v[120:123], v[52:55], v[32:47]
	v_exp_f32_e32 v198, v198
	v_exp_f32_e32 v199, v199
	v_mfma_f32_32x32x16_bf16 v[32:47], v[124:127], v[56:59], v[32:47]
	v_exp_f32_e32 v200, v200
	v_exp_f32_e32 v201, v201
	v_mfma_f32_32x32x16_bf16 v[32:47], v[128:131], v[60:63], v[32:47]
	v_exp_f32_e32 v202, v202
	v_exp_f32_e32 v203, v203
	s_add_i32 s90, s67, 480
	v_add_u32_e32 v84, s90, v107
	v_add_u32_e32 v85, 0, v84
	v_add_u32_e32 v86, 1, v84
	v_add_u32_e32 v87, 2, v84
	v_add_u32_e32 v88, 3, v84
	v_cmp_gt_u32_e64 s[30:31], s98, v85
	v_cmp_gt_u32_e64 s[36:37], s98, v86
	v_cmp_gt_u32_e64 s[78:79], s98, v87
	v_cmp_gt_u32_e64 s[50:51], s98, v88
	v_cndmask_b32_e64 v188, 0, v188, s[30:31]
	v_add_u32_e32 v85, 8, v84
	v_cmp_gt_u32_e64 s[30:31], s98, v85
	v_cndmask_b32_e64 v189, 0, v189, s[36:37]
	v_add_u32_e32 v86, 9, v84
	v_cmp_gt_u32_e64 s[36:37], s98, v86
	v_cndmask_b32_e64 v190, 0, v190, s[78:79]
	v_add_u32_e32 v87, 10, v84
	v_cmp_gt_u32_e64 s[78:79], s98, v87
	v_cndmask_b32_e64 v191, 0, v191, s[50:51]
	v_add_u32_e32 v88, 11, v84
	v_cmp_gt_u32_e64 s[50:51], s98, v88
	v_cndmask_b32_e64 v192, 0, v192, s[30:31]
	v_add_u32_e32 v85, 16, v84
	v_cmp_gt_u32_e64 s[30:31], s98, v85
	v_cndmask_b32_e64 v193, 0, v193, s[36:37]
	v_add_u32_e32 v86, 17, v84
	v_cmp_gt_u32_e64 s[36:37], s98, v86
	v_cndmask_b32_e64 v194, 0, v194, s[78:79]
	v_add_u32_e32 v87, 18, v84
	v_cmp_gt_u32_e64 s[78:79], s98, v87
	v_cndmask_b32_e64 v195, 0, v195, s[50:51]
	v_add_u32_e32 v88, 19, v84
	v_cmp_gt_u32_e64 s[50:51], s98, v88
	v_cndmask_b32_e64 v196, 0, v196, s[30:31]
	v_add_u32_e32 v85, 24, v84
	v_cmp_gt_u32_e64 s[30:31], s98, v85
	v_cndmask_b32_e64 v197, 0, v197, s[36:37]
	v_add_u32_e32 v86, 25, v84
	v_cmp_gt_u32_e64 s[36:37], s98, v86
	v_cndmask_b32_e64 v198, 0, v198, s[78:79]
	v_add_u32_e32 v87, 26, v84
	v_cmp_gt_u32_e64 s[78:79], s98, v87
	v_cndmask_b32_e64 v199, 0, v199, s[50:51]
	v_add_u32_e32 v88, 27, v84
	v_cmp_gt_u32_e64 s[50:51], s98, v88
	v_nop
	v_cndmask_b32_e64 v200, 0, v200, s[30:31]
	v_cndmask_b32_e64 v201, 0, v201, s[36:37]
	v_cndmask_b32_e64 v202, 0, v202, s[78:79]
	v_cndmask_b32_e64 v203, 0, v203, s[50:51]
	v_cvt_pk_bf16_f32 v64, v188, v189
	v_cvt_pk_bf16_f32 v65, v190, v191
	v_cvt_pk_bf16_f32 v66, v192, v193
	v_cvt_pk_bf16_f32 v67, v194, v195
	v_cvt_pk_bf16_f32 v68, v196, v197
	v_cvt_pk_bf16_f32 v69, v198, v199
	v_cvt_pk_bf16_f32 v70, v200, v201
	v_cvt_pk_bf16_f32 v71, v202, v203
	v_pk_add_f32 v[232:233], v[232:233], v[188:189]
	v_pk_add_f32 v[232:233], v[232:233], v[190:191]
	v_pk_add_f32 v[232:233], v[232:233], v[192:193]
	v_pk_add_f32 v[232:233], v[232:233], v[194:195]
	v_pk_add_f32 v[232:233], v[232:233], v[196:197]
	v_pk_add_f32 v[232:233], v[232:233], v[198:199]
	v_pk_add_f32 v[232:233], v[232:233], v[200:201]
	v_pk_add_f32 v[232:233], v[232:233], v[202:203]
	ds_read2_b32 v[188:189], v115 offset0:170 offset1:171
	ds_read2_b32 v[190:191], v115 offset0:172 offset1:173
	ds_read2_b32 v[192:193], v115 offset0:178 offset1:179
	ds_read2_b32 v[194:195], v115 offset0:180 offset1:181
	ds_read2_b32 v[196:197], v115 offset0:187 offset1:188
	ds_read2_b32 v[198:199], v115 offset0:189 offset1:190
	ds_read2_b32 v[200:201], v115 offset0:195 offset1:196
	ds_read2_b32 v[202:203], v115 offset0:197 offset1:198
	v_mfma_f32_32x32x16_bf16 v[0:15], v[64:67], v[72:75], v[0:15]
	v_mfma_f32_32x32x16_bf16 v[16:31], v[64:67], v[76:79], v[16:31]
	v_mfma_f32_32x32x16_bf16 v[0:15], v[68:71], v[220:223], v[0:15]
	v_mfma_f32_32x32x16_bf16 v[16:31], v[68:71], v[224:227], v[16:31]
	s_add_i32 s90, s67, -256
	v_add_u32_e32 v80, s90, v239
	v_add_u32_e32 v83, s90, v240
	v_add_u32_e32 v99, s90, v241
	v_add_u32_e32 v253, s90, v242
	v_add_u32_e32 v254, s90, v101
	v_add_u32_e32 v255, s90, v150
	v_med3_i32 v80, v80, 0, s99
	v_med3_i32 v83, v83, 0, s99
	v_med3_i32 v99, v99, 0, s99
	v_med3_i32 v253, v253, 0, s99
	v_med3_i32 v254, v254, 0, s99
	v_med3_i32 v255, v255, 0, s99
	v_mad_u32_u24 v80, v80, s100, v252
	v_mad_u32_u24 v83, v83, s100, v252
	v_mad_u32_u24 v99, v99, s100, v252
	v_mad_u32_u24 v253, v253, s100, v252
	v_mad_u32_u24 v254, v254, s100, v153
	v_mad_u32_u24 v255, v255, s100, v153
	global_load_dwordx4 v[116:119], v80, s[82:83]
	global_load_dwordx4 v[120:123], v83, s[82:83]
	global_load_dwordx4 v[124:127], v99, s[82:83]
	global_load_dwordx4 v[128:131], v253, s[82:83]
	global_load_dwordx4 v[132:135], v254, s[82:83] offset:768
	global_load_dwordx4 v[136:139], v255, s[82:83] offset:768
	global_load_dwordx4 v[140:143], v254, s[82:83] offset:832
	global_load_dwordx4 v[144:147], v255, s[82:83] offset:832
	ds_read_b64_tr_b16 v[72:73], v231
	ds_read_b64_tr_b16 v[74:75], v231 offset:512
	ds_read_b64_tr_b16 v[76:77], v231 offset:2048
	ds_read_b64_tr_b16 v[78:79], v231 offset:2560
	ds_read_b64_tr_b16 v[220:221], v231 offset:1024
	ds_read_b64_tr_b16 v[222:223], v231 offset:1536
	ds_read_b64_tr_b16 v[224:225], v231 offset:3072
	ds_read_b64_tr_b16 v[226:227], v231 offset:3584
	v_exp_f32_e32 v32, v32
	v_exp_f32_e32 v33, v33
	v_exp_f32_e32 v34, v34
	v_exp_f32_e32 v35, v35
	s_waitcnt vmcnt(12)
	ds_write_b128 v247, v[156:159]
	ds_write_b128 v247, v[160:163] offset:1024
	ds_write_b128 v247, v[164:167] offset:2048
	ds_write_b128 v247, v[168:171] offset:3072
	ds_read_b128 v[156:159], v248
	ds_read_b128 v[160:163], v249
	ds_read_b128 v[164:167], v250
	ds_read_b128 v[168:171], v251
	s_waitcnt vmcnt(8)
	ds_write_b128 v112, v[172:175]
	ds_write_b128 v112, v[176:179] offset:1024
	ds_write_b128 v112, v[180:183] offset:2048
	ds_write_b128 v112, v[184:187] offset:3072
	v_exp_f32_e32 v36, v36
	v_exp_f32_e32 v37, v37
	v_exp_f32_e32 v38, v38
	v_exp_f32_e32 v39, v39
	s_waitcnt lgkmcnt(4)
	v_mfma_f32_32x32x16_bf16 v[188:203], v[156:159], v[48:51], v[188:203]
	v_exp_f32_e32 v40, v40
	v_exp_f32_e32 v41, v41
	v_mfma_f32_32x32x16_bf16 v[188:203], v[160:163], v[52:55], v[188:203]
	v_exp_f32_e32 v42, v42
	v_exp_f32_e32 v43, v43
	v_mfma_f32_32x32x16_bf16 v[188:203], v[164:167], v[56:59], v[188:203]
	v_exp_f32_e32 v44, v44
	v_exp_f32_e32 v45, v45
	v_mfma_f32_32x32x16_bf16 v[188:203], v[168:171], v[60:63], v[188:203]
	v_exp_f32_e32 v46, v46
	v_exp_f32_e32 v47, v47
	s_add_i32 s90, s67, 512
	v_add_u32_e32 v84, s90, v107
	v_add_u32_e32 v85, 0, v84
	v_add_u32_e32 v86, 1, v84
	v_add_u32_e32 v87, 2, v84
	v_add_u32_e32 v88, 3, v84
	v_cmp_gt_u32_e64 s[30:31], s98, v85
	v_cmp_gt_u32_e64 s[36:37], s98, v86
	v_cmp_gt_u32_e64 s[78:79], s98, v87
	v_cmp_gt_u32_e64 s[50:51], s98, v88
	v_cndmask_b32_e64 v32, 0, v32, s[30:31]
	v_add_u32_e32 v85, 8, v84
	v_cmp_gt_u32_e64 s[30:31], s98, v85
	v_cndmask_b32_e64 v33, 0, v33, s[36:37]
	v_add_u32_e32 v86, 9, v84
	v_cmp_gt_u32_e64 s[36:37], s98, v86
	v_cndmask_b32_e64 v34, 0, v34, s[78:79]
	v_add_u32_e32 v87, 10, v84
	v_cmp_gt_u32_e64 s[78:79], s98, v87
	v_cndmask_b32_e64 v35, 0, v35, s[50:51]
	v_add_u32_e32 v88, 11, v84
	v_cmp_gt_u32_e64 s[50:51], s98, v88
	v_cndmask_b32_e64 v36, 0, v36, s[30:31]
	v_add_u32_e32 v85, 16, v84
	v_cmp_gt_u32_e64 s[30:31], s98, v85
	v_cndmask_b32_e64 v37, 0, v37, s[36:37]
	v_add_u32_e32 v86, 17, v84
	v_cmp_gt_u32_e64 s[36:37], s98, v86
	v_cndmask_b32_e64 v38, 0, v38, s[78:79]
	v_add_u32_e32 v87, 18, v84
	v_cmp_gt_u32_e64 s[78:79], s98, v87
	v_cndmask_b32_e64 v39, 0, v39, s[50:51]
	v_add_u32_e32 v88, 19, v84
	v_cmp_gt_u32_e64 s[50:51], s98, v88
	v_cndmask_b32_e64 v40, 0, v40, s[30:31]
	v_add_u32_e32 v85, 24, v84
	v_cmp_gt_u32_e64 s[30:31], s98, v85
	v_cndmask_b32_e64 v41, 0, v41, s[36:37]
	v_add_u32_e32 v86, 25, v84
	v_cmp_gt_u32_e64 s[36:37], s98, v86
	v_cndmask_b32_e64 v42, 0, v42, s[78:79]
	v_add_u32_e32 v87, 26, v84
	v_cmp_gt_u32_e64 s[78:79], s98, v87
	v_cndmask_b32_e64 v43, 0, v43, s[50:51]
	v_add_u32_e32 v88, 27, v84
	v_cmp_gt_u32_e64 s[50:51], s98, v88
	v_nop
	v_cndmask_b32_e64 v44, 0, v44, s[30:31]
	v_cndmask_b32_e64 v45, 0, v45, s[36:37]
	v_cndmask_b32_e64 v46, 0, v46, s[78:79]
	v_cndmask_b32_e64 v47, 0, v47, s[50:51]
	v_cvt_pk_bf16_f32 v64, v32, v33
	v_cvt_pk_bf16_f32 v65, v34, v35
	v_cvt_pk_bf16_f32 v66, v36, v37
	v_cvt_pk_bf16_f32 v67, v38, v39
	v_cvt_pk_bf16_f32 v68, v40, v41
	v_cvt_pk_bf16_f32 v69, v42, v43
	v_cvt_pk_bf16_f32 v70, v44, v45
	v_cvt_pk_bf16_f32 v71, v46, v47
	v_pk_add_f32 v[232:233], v[232:233], v[32:33]
	v_pk_add_f32 v[232:233], v[232:233], v[34:35]
	v_pk_add_f32 v[232:233], v[232:233], v[36:37]
	v_pk_add_f32 v[232:233], v[232:233], v[38:39]
	v_pk_add_f32 v[232:233], v[232:233], v[40:41]
	v_pk_add_f32 v[232:233], v[232:233], v[42:43]
	v_pk_add_f32 v[232:233], v[232:233], v[44:45]
	v_pk_add_f32 v[232:233], v[232:233], v[46:47]
	v_mov_b32_e32 v115, v229
	ds_read2_b32 v[32:33], v115 offset0:0 offset1:1
	ds_read2_b32 v[34:35], v115 offset0:2 offset1:3
	ds_read2_b32 v[36:37], v115 offset0:8 offset1:9
	ds_read2_b32 v[38:39], v115 offset0:10 offset1:11
	ds_read2_b32 v[40:41], v115 offset0:16 offset1:17
	ds_read2_b32 v[42:43], v115 offset0:18 offset1:19
	ds_read2_b32 v[44:45], v115 offset0:24 offset1:25
	ds_read2_b32 v[46:47], v115 offset0:26 offset1:27
	v_mfma_f32_32x32x16_bf16 v[0:15], v[64:67], v[72:75], v[0:15]
	v_mfma_f32_32x32x16_bf16 v[16:31], v[64:67], v[76:79], v[16:31]
	v_mfma_f32_32x32x16_bf16 v[0:15], v[68:71], v[220:223], v[0:15]
	v_mfma_f32_32x32x16_bf16 v[16:31], v[68:71], v[224:227], v[16:31]
	s_add_i32 s90, s67, -128
	v_add_u32_e32 v80, s90, v239
	v_add_u32_e32 v83, s90, v240
	v_add_u32_e32 v99, s90, v241
	v_add_u32_e32 v253, s90, v242
	v_add_u32_e32 v254, s90, v101
	v_add_u32_e32 v255, s90, v150
	v_med3_i32 v80, v80, 0, s99
	v_med3_i32 v83, v83, 0, s99
	v_med3_i32 v99, v99, 0, s99
	v_med3_i32 v253, v253, 0, s99
	v_med3_i32 v254, v254, 0, s99
	v_med3_i32 v255, v255, 0, s99
	v_mad_u32_u24 v80, v80, s100, v252
	v_mad_u32_u24 v83, v83, s100, v252
	v_mad_u32_u24 v99, v99, s100, v252
	v_mad_u32_u24 v253, v253, s100, v252
	v_mad_u32_u24 v254, v254, s100, v153
	v_mad_u32_u24 v255, v255, s100, v153
	global_load_dwordx4 v[156:159], v80, s[82:83]
	global_load_dwordx4 v[160:163], v83, s[82:83]
	global_load_dwordx4 v[164:167], v99, s[82:83]
	global_load_dwordx4 v[168:171], v253, s[82:83]
	global_load_dwordx4 v[172:175], v254, s[82:83] offset:768
	global_load_dwordx4 v[176:179], v255, s[82:83] offset:768
	global_load_dwordx4 v[180:183], v254, s[82:83] offset:832
	global_load_dwordx4 v[184:187], v255, s[82:83] offset:832
	ds_read_b64_tr_b16 v[72:73], v231
	ds_read_b64_tr_b16 v[74:75], v231 offset:512
	ds_read_b64_tr_b16 v[76:77], v231 offset:2048
	ds_read_b64_tr_b16 v[78:79], v231 offset:2560
	ds_read_b64_tr_b16 v[220:221], v231 offset:1024
	ds_read_b64_tr_b16 v[222:223], v231 offset:1536
	ds_read_b64_tr_b16 v[224:225], v231 offset:3072
	ds_read_b64_tr_b16 v[226:227], v231 offset:3584
	v_exp_f32_e32 v188, v188
	v_exp_f32_e32 v189, v189
	v_exp_f32_e32 v190, v190
	v_exp_f32_e32 v191, v191
	s_waitcnt vmcnt(12)
	ds_write_b128 v247, v[116:119]
	ds_write_b128 v247, v[120:123] offset:1024
	ds_write_b128 v247, v[124:127] offset:2048
	ds_write_b128 v247, v[128:131] offset:3072
	ds_read_b128 v[116:119], v248
	ds_read_b128 v[120:123], v249
	ds_read_b128 v[124:127], v250
	ds_read_b128 v[128:131], v251
	s_waitcnt vmcnt(8)
	ds_write_b128 v112, v[132:135]
	ds_write_b128 v112, v[136:139] offset:1024
	ds_write_b128 v112, v[140:143] offset:2048
	ds_write_b128 v112, v[144:147] offset:3072
	v_exp_f32_e32 v192, v192
	v_exp_f32_e32 v193, v193
	v_exp_f32_e32 v194, v194
	v_exp_f32_e32 v195, v195
	s_waitcnt lgkmcnt(4)
	v_mfma_f32_32x32x16_bf16 v[32:47], v[116:119], v[48:51], v[32:47]
	v_exp_f32_e32 v196, v196
	v_exp_f32_e32 v197, v197
	v_mfma_f32_32x32x16_bf16 v[32:47], v[120:123], v[52:55], v[32:47]
	v_exp_f32_e32 v198, v198
	v_exp_f32_e32 v199, v199
	v_mfma_f32_32x32x16_bf16 v[32:47], v[124:127], v[56:59], v[32:47]
	v_exp_f32_e32 v200, v200
	v_exp_f32_e32 v201, v201
	v_mfma_f32_32x32x16_bf16 v[32:47], v[128:131], v[60:63], v[32:47]
	v_exp_f32_e32 v202, v202
	v_exp_f32_e32 v203, v203
	s_add_i32 s90, s67, 544
	v_add_u32_e32 v84, s90, v107
	v_add_u32_e32 v85, 0, v84
	v_add_u32_e32 v86, 1, v84
	v_add_u32_e32 v87, 2, v84
	v_add_u32_e32 v88, 3, v84
	v_cmp_gt_u32_e64 s[30:31], s98, v85
	v_cmp_gt_u32_e64 s[36:37], s98, v86
	v_cmp_gt_u32_e64 s[78:79], s98, v87
	v_cmp_gt_u32_e64 s[50:51], s98, v88
	v_cndmask_b32_e64 v188, 0, v188, s[30:31]
	v_add_u32_e32 v85, 8, v84
	v_cmp_gt_u32_e64 s[30:31], s98, v85
	v_cndmask_b32_e64 v189, 0, v189, s[36:37]
	v_add_u32_e32 v86, 9, v84
	v_cmp_gt_u32_e64 s[36:37], s98, v86
	v_cndmask_b32_e64 v190, 0, v190, s[78:79]
	v_add_u32_e32 v87, 10, v84
	v_cmp_gt_u32_e64 s[78:79], s98, v87
	v_cndmask_b32_e64 v191, 0, v191, s[50:51]
	v_add_u32_e32 v88, 11, v84
	v_cmp_gt_u32_e64 s[50:51], s98, v88
	v_cndmask_b32_e64 v192, 0, v192, s[30:31]
	v_add_u32_e32 v85, 16, v84
	v_cmp_gt_u32_e64 s[30:31], s98, v85
	v_cndmask_b32_e64 v193, 0, v193, s[36:37]
	v_add_u32_e32 v86, 17, v84
	v_cmp_gt_u32_e64 s[36:37], s98, v86
	v_cndmask_b32_e64 v194, 0, v194, s[78:79]
	v_add_u32_e32 v87, 18, v84
	v_cmp_gt_u32_e64 s[78:79], s98, v87
	v_cndmask_b32_e64 v195, 0, v195, s[50:51]
	v_add_u32_e32 v88, 19, v84
	v_cmp_gt_u32_e64 s[50:51], s98, v88
	v_cndmask_b32_e64 v196, 0, v196, s[30:31]
	v_add_u32_e32 v85, 24, v84
	v_cmp_gt_u32_e64 s[30:31], s98, v85
	v_cndmask_b32_e64 v197, 0, v197, s[36:37]
	v_add_u32_e32 v86, 25, v84
	v_cmp_gt_u32_e64 s[36:37], s98, v86
	v_cndmask_b32_e64 v198, 0, v198, s[78:79]
	v_add_u32_e32 v87, 26, v84
	v_cmp_gt_u32_e64 s[78:79], s98, v87
	v_cndmask_b32_e64 v199, 0, v199, s[50:51]
	v_add_u32_e32 v88, 27, v84
	v_cmp_gt_u32_e64 s[50:51], s98, v88
	v_nop
	v_cndmask_b32_e64 v200, 0, v200, s[30:31]
	v_cndmask_b32_e64 v201, 0, v201, s[36:37]
	v_cndmask_b32_e64 v202, 0, v202, s[78:79]
	v_cndmask_b32_e64 v203, 0, v203, s[50:51]
	v_cvt_pk_bf16_f32 v64, v188, v189
	v_cvt_pk_bf16_f32 v65, v190, v191
	v_cvt_pk_bf16_f32 v66, v192, v193
	v_cvt_pk_bf16_f32 v67, v194, v195
	v_cvt_pk_bf16_f32 v68, v196, v197
	v_cvt_pk_bf16_f32 v69, v198, v199
	v_cvt_pk_bf16_f32 v70, v200, v201
	v_cvt_pk_bf16_f32 v71, v202, v203
	v_pk_add_f32 v[232:233], v[232:233], v[188:189]
	v_pk_add_f32 v[232:233], v[232:233], v[190:191]
	v_pk_add_f32 v[232:233], v[232:233], v[192:193]
	v_pk_add_f32 v[232:233], v[232:233], v[194:195]
	v_pk_add_f32 v[232:233], v[232:233], v[196:197]
	v_pk_add_f32 v[232:233], v[232:233], v[198:199]
	v_pk_add_f32 v[232:233], v[232:233], v[200:201]
	v_pk_add_f32 v[232:233], v[232:233], v[202:203]
	ds_read2_b32 v[188:189], v115 offset0:32 offset1:33
	ds_read2_b32 v[190:191], v115 offset0:34 offset1:35
	ds_read2_b32 v[192:193], v115 offset0:40 offset1:41
	ds_read2_b32 v[194:195], v115 offset0:42 offset1:43
	ds_read2_b32 v[196:197], v115 offset0:48 offset1:49
	ds_read2_b32 v[198:199], v115 offset0:50 offset1:51
	ds_read2_b32 v[200:201], v115 offset0:56 offset1:57
	ds_read2_b32 v[202:203], v115 offset0:58 offset1:59
	v_mfma_f32_32x32x16_bf16 v[0:15], v[64:67], v[72:75], v[0:15]
	v_mfma_f32_32x32x16_bf16 v[16:31], v[64:67], v[76:79], v[16:31]
	v_mfma_f32_32x32x16_bf16 v[0:15], v[68:71], v[220:223], v[0:15]
	v_mfma_f32_32x32x16_bf16 v[16:31], v[68:71], v[224:227], v[16:31]
	s_add_i32 s90, s67, 0
	v_add_u32_e32 v80, s90, v239
	v_add_u32_e32 v83, s90, v240
	v_add_u32_e32 v99, s90, v241
	v_add_u32_e32 v253, s90, v242
	v_add_u32_e32 v254, s90, v101
	v_add_u32_e32 v255, s90, v150
	v_med3_i32 v80, v80, 0, s99
	v_med3_i32 v83, v83, 0, s99
	v_med3_i32 v99, v99, 0, s99
	v_med3_i32 v253, v253, 0, s99
	v_med3_i32 v254, v254, 0, s99
	v_med3_i32 v255, v255, 0, s99
	v_mad_u32_u24 v80, v80, s100, v252
	v_mad_u32_u24 v83, v83, s100, v252
	v_mad_u32_u24 v99, v99, s100, v252
	v_mad_u32_u24 v253, v253, s100, v252
	v_mad_u32_u24 v254, v254, s100, v153
	v_mad_u32_u24 v255, v255, s100, v153
	global_load_dwordx4 v[116:119], v80, s[82:83]
	global_load_dwordx4 v[120:123], v83, s[82:83]
	global_load_dwordx4 v[124:127], v99, s[82:83]
	global_load_dwordx4 v[128:131], v253, s[82:83]
	global_load_dwordx4 v[132:135], v254, s[82:83] offset:768
	global_load_dwordx4 v[136:139], v255, s[82:83] offset:768
	global_load_dwordx4 v[140:143], v254, s[82:83] offset:832
	global_load_dwordx4 v[144:147], v255, s[82:83] offset:832
	ds_read_b64_tr_b16 v[72:73], v231
	ds_read_b64_tr_b16 v[74:75], v231 offset:512
	ds_read_b64_tr_b16 v[76:77], v231 offset:2048
	ds_read_b64_tr_b16 v[78:79], v231 offset:2560
	ds_read_b64_tr_b16 v[220:221], v231 offset:1024
	ds_read_b64_tr_b16 v[222:223], v231 offset:1536
	ds_read_b64_tr_b16 v[224:225], v231 offset:3072
	ds_read_b64_tr_b16 v[226:227], v231 offset:3584
	v_exp_f32_e32 v32, v32
	v_exp_f32_e32 v33, v33
	v_exp_f32_e32 v34, v34
	v_exp_f32_e32 v35, v35
	s_waitcnt vmcnt(12)
	ds_write_b128 v247, v[156:159]
	ds_write_b128 v247, v[160:163] offset:1024
	ds_write_b128 v247, v[164:167] offset:2048
	ds_write_b128 v247, v[168:171] offset:3072
	ds_read_b128 v[156:159], v248
	ds_read_b128 v[160:163], v249
	ds_read_b128 v[164:167], v250
	ds_read_b128 v[168:171], v251
	s_waitcnt vmcnt(8)
	ds_write_b128 v112, v[172:175]
	ds_write_b128 v112, v[176:179] offset:1024
	ds_write_b128 v112, v[180:183] offset:2048
	ds_write_b128 v112, v[184:187] offset:3072
	v_exp_f32_e32 v36, v36
	v_exp_f32_e32 v37, v37
	v_exp_f32_e32 v38, v38
	v_exp_f32_e32 v39, v39
	s_waitcnt lgkmcnt(4)
	v_mfma_f32_32x32x16_bf16 v[188:203], v[156:159], v[48:51], v[188:203]
	v_exp_f32_e32 v40, v40
	v_exp_f32_e32 v41, v41
	v_mfma_f32_32x32x16_bf16 v[188:203], v[160:163], v[52:55], v[188:203]
	v_exp_f32_e32 v42, v42
	v_exp_f32_e32 v43, v43
	v_mfma_f32_32x32x16_bf16 v[188:203], v[164:167], v[56:59], v[188:203]
	v_exp_f32_e32 v44, v44
	v_exp_f32_e32 v45, v45
	v_mfma_f32_32x32x16_bf16 v[188:203], v[168:171], v[60:63], v[188:203]
	v_exp_f32_e32 v46, v46
	v_exp_f32_e32 v47, v47
	s_add_i32 s90, s67, -256
	v_lshlrev_b32_e32 v84, 2, v107
	v_add_u32_e32 v84, s90, v84
	v_add_u32_e32 v85, 0, v84
	v_add_u32_e32 v86, 4, v84
	v_add_u32_e32 v87, 8, v84
	v_add_u32_e32 v88, 12, v84
	v_cmp_gt_u32_e64 s[30:31], s98, v85
	v_cmp_gt_u32_e64 s[36:37], s98, v86
	v_cmp_gt_u32_e64 s[78:79], s98, v87
	v_cmp_gt_u32_e64 s[50:51], s98, v88
	v_cndmask_b32_e64 v32, 0, v32, s[30:31]
	v_add_u32_e32 v85, 32, v84
	v_cmp_gt_u32_e64 s[30:31], s98, v85
	v_cndmask_b32_e64 v33, 0, v33, s[36:37]
	v_add_u32_e32 v86, 36, v84
	v_cmp_gt_u32_e64 s[36:37], s98, v86
	v_cndmask_b32_e64 v34, 0, v34, s[78:79]
	v_add_u32_e32 v87, 40, v84
	v_cmp_gt_u32_e64 s[78:79], s98, v87
	v_cndmask_b32_e64 v35, 0, v35, s[50:51]
	v_add_u32_e32 v88, 44, v84
	v_cmp_gt_u32_e64 s[50:51], s98, v88
	v_cndmask_b32_e64 v36, 0, v36, s[30:31]
	v_add_u32_e32 v85, 64, v84
	v_cmp_gt_u32_e64 s[30:31], s98, v85
	v_cndmask_b32_e64 v37, 0, v37, s[36:37]
	v_add_u32_e32 v86, 68, v84
	v_cmp_gt_u32_e64 s[36:37], s98, v86
	v_cndmask_b32_e64 v38, 0, v38, s[78:79]
	v_add_u32_e32 v87, 72, v84
	v_cmp_gt_u32_e64 s[78:79], s98, v87
	v_cndmask_b32_e64 v39, 0, v39, s[50:51]
	v_add_u32_e32 v88, 76, v84
	v_cmp_gt_u32_e64 s[50:51], s98, v88
	v_cndmask_b32_e64 v40, 0, v40, s[30:31]
	v_add_u32_e32 v85, 96, v84
	v_cmp_gt_u32_e64 s[30:31], s98, v85
	v_cndmask_b32_e64 v41, 0, v41, s[36:37]
	v_add_u32_e32 v86, 100, v84
	v_cmp_gt_u32_e64 s[36:37], s98, v86
	v_cndmask_b32_e64 v42, 0, v42, s[78:79]
	v_add_u32_e32 v87, 104, v84
	v_cmp_gt_u32_e64 s[78:79], s98, v87
	v_cndmask_b32_e64 v43, 0, v43, s[50:51]
	v_add_u32_e32 v88, 108, v84
	v_cmp_gt_u32_e64 s[50:51], s98, v88
	v_nop
	v_cndmask_b32_e64 v44, 0, v44, s[30:31]
	v_cndmask_b32_e64 v45, 0, v45, s[36:37]
	v_cndmask_b32_e64 v46, 0, v46, s[78:79]
	v_cndmask_b32_e64 v47, 0, v47, s[50:51]
	v_cvt_pk_bf16_f32 v64, v32, v33
	v_cvt_pk_bf16_f32 v65, v34, v35
	v_cvt_pk_bf16_f32 v66, v36, v37
	v_cvt_pk_bf16_f32 v67, v38, v39
	v_cvt_pk_bf16_f32 v68, v40, v41
	v_cvt_pk_bf16_f32 v69, v42, v43
	v_cvt_pk_bf16_f32 v70, v44, v45
	v_cvt_pk_bf16_f32 v71, v46, v47
	v_pk_add_f32 v[232:233], v[232:233], v[32:33]
	v_pk_add_f32 v[232:233], v[232:233], v[34:35]
	v_pk_add_f32 v[232:233], v[232:233], v[36:37]
	v_pk_add_f32 v[232:233], v[232:233], v[38:39]
	v_pk_add_f32 v[232:233], v[232:233], v[40:41]
	v_pk_add_f32 v[232:233], v[232:233], v[42:43]
	v_pk_add_f32 v[232:233], v[232:233], v[44:45]
	v_pk_add_f32 v[232:233], v[232:233], v[46:47]
	ds_read2_b32 v[32:33], v115 offset0:64 offset1:65
	ds_read2_b32 v[34:35], v115 offset0:66 offset1:67
	ds_read2_b32 v[36:37], v115 offset0:72 offset1:73
	ds_read2_b32 v[38:39], v115 offset0:74 offset1:75
	ds_read2_b32 v[40:41], v115 offset0:80 offset1:81
	ds_read2_b32 v[42:43], v115 offset0:82 offset1:83
	ds_read2_b32 v[44:45], v115 offset0:88 offset1:89
	ds_read2_b32 v[46:47], v115 offset0:90 offset1:91
	v_mfma_f32_32x32x16_bf16 v[0:15], v[64:67], v[72:75], v[0:15]
	v_mfma_f32_32x32x16_bf16 v[16:31], v[64:67], v[76:79], v[16:31]
	v_mfma_f32_32x32x16_bf16 v[0:15], v[68:71], v[220:223], v[0:15]
	v_mfma_f32_32x32x16_bf16 v[16:31], v[68:71], v[224:227], v[16:31]
	s_add_i32 s90, s67, 128
	v_add_u32_e32 v80, s90, v239
	v_add_u32_e32 v83, s90, v240
	v_add_u32_e32 v99, s90, v241
	v_add_u32_e32 v253, s90, v242
	v_add_u32_e32 v254, s90, v101
	v_add_u32_e32 v255, s90, v150
	v_med3_i32 v80, v80, 0, s99
	v_med3_i32 v83, v83, 0, s99
	v_med3_i32 v99, v99, 0, s99
	v_med3_i32 v253, v253, 0, s99
	v_med3_i32 v254, v254, 0, s99
	v_med3_i32 v255, v255, 0, s99
	v_mad_u32_u24 v80, v80, s100, v252
	v_mad_u32_u24 v83, v83, s100, v252
	v_mad_u32_u24 v99, v99, s100, v252
	v_mad_u32_u24 v253, v253, s100, v252
	v_mad_u32_u24 v254, v254, s100, v153
	v_mad_u32_u24 v255, v255, s100, v153
	global_load_dwordx4 v[156:159], v80, s[82:83]
	global_load_dwordx4 v[160:163], v83, s[82:83]
	global_load_dwordx4 v[164:167], v99, s[82:83]
	global_load_dwordx4 v[168:171], v253, s[82:83]
	global_load_dwordx4 v[172:175], v254, s[82:83] offset:768
	global_load_dwordx4 v[176:179], v255, s[82:83] offset:768
	global_load_dwordx4 v[180:183], v254, s[82:83] offset:832
	global_load_dwordx4 v[184:187], v255, s[82:83] offset:832
	ds_read_b64_tr_b16 v[72:73], v231
	ds_read_b64_tr_b16 v[74:75], v231 offset:512
	ds_read_b64_tr_b16 v[76:77], v231 offset:2048
	ds_read_b64_tr_b16 v[78:79], v231 offset:2560
	ds_read_b64_tr_b16 v[220:221], v231 offset:1024
	ds_read_b64_tr_b16 v[222:223], v231 offset:1536
	ds_read_b64_tr_b16 v[224:225], v231 offset:3072
	ds_read_b64_tr_b16 v[226:227], v231 offset:3584
	v_exp_f32_e32 v188, v188
	v_exp_f32_e32 v189, v189
	v_exp_f32_e32 v190, v190
	v_exp_f32_e32 v191, v191
	s_waitcnt vmcnt(12)
	ds_write_b128 v247, v[116:119]
	ds_write_b128 v247, v[120:123] offset:1024
	ds_write_b128 v247, v[124:127] offset:2048
	ds_write_b128 v247, v[128:131] offset:3072
	ds_read_b128 v[116:119], v248
	ds_read_b128 v[120:123], v249
	ds_read_b128 v[124:127], v250
	ds_read_b128 v[128:131], v251
	s_waitcnt vmcnt(8)
	ds_write_b128 v112, v[132:135]
	ds_write_b128 v112, v[136:139] offset:1024
	ds_write_b128 v112, v[140:143] offset:2048
	ds_write_b128 v112, v[144:147] offset:3072
	v_exp_f32_e32 v192, v192
	v_exp_f32_e32 v193, v193
	v_exp_f32_e32 v194, v194
	v_exp_f32_e32 v195, v195
	s_waitcnt lgkmcnt(4)
	v_mfma_f32_32x32x16_bf16 v[32:47], v[116:119], v[48:51], v[32:47]
	v_exp_f32_e32 v196, v196
	v_exp_f32_e32 v197, v197
	v_mfma_f32_32x32x16_bf16 v[32:47], v[120:123], v[52:55], v[32:47]
	v_exp_f32_e32 v198, v198
	v_exp_f32_e32 v199, v199
	v_mfma_f32_32x32x16_bf16 v[32:47], v[124:127], v[56:59], v[32:47]
	v_exp_f32_e32 v200, v200
	v_exp_f32_e32 v201, v201
	v_mfma_f32_32x32x16_bf16 v[32:47], v[128:131], v[60:63], v[32:47]
	v_exp_f32_e32 v202, v202
	v_exp_f32_e32 v203, v203
	s_add_i32 s90, s67, -128
	v_lshlrev_b32_e32 v84, 2, v107
	v_add_u32_e32 v84, s90, v84
	v_add_u32_e32 v85, 0, v84
	v_add_u32_e32 v86, 4, v84
	v_add_u32_e32 v87, 8, v84
	v_add_u32_e32 v88, 12, v84
	v_cmp_gt_u32_e64 s[30:31], s98, v85
	v_cmp_gt_u32_e64 s[36:37], s98, v86
	v_cmp_gt_u32_e64 s[78:79], s98, v87
	v_cmp_gt_u32_e64 s[50:51], s98, v88
	v_cndmask_b32_e64 v188, 0, v188, s[30:31]
	v_add_u32_e32 v85, 32, v84
	v_cmp_gt_u32_e64 s[30:31], s98, v85
	v_cndmask_b32_e64 v189, 0, v189, s[36:37]
	v_add_u32_e32 v86, 36, v84
	v_cmp_gt_u32_e64 s[36:37], s98, v86
	v_cndmask_b32_e64 v190, 0, v190, s[78:79]
	v_add_u32_e32 v87, 40, v84
	v_cmp_gt_u32_e64 s[78:79], s98, v87
	v_cndmask_b32_e64 v191, 0, v191, s[50:51]
	v_add_u32_e32 v88, 44, v84
	v_cmp_gt_u32_e64 s[50:51], s98, v88
	v_cndmask_b32_e64 v192, 0, v192, s[30:31]
	v_add_u32_e32 v85, 64, v84
	v_cmp_gt_u32_e64 s[30:31], s98, v85
	v_cndmask_b32_e64 v193, 0, v193, s[36:37]
	v_add_u32_e32 v86, 68, v84
	v_cmp_gt_u32_e64 s[36:37], s98, v86
	v_cndmask_b32_e64 v194, 0, v194, s[78:79]
	v_add_u32_e32 v87, 72, v84
	v_cmp_gt_u32_e64 s[78:79], s98, v87
	v_cndmask_b32_e64 v195, 0, v195, s[50:51]
	v_add_u32_e32 v88, 76, v84
	v_cmp_gt_u32_e64 s[50:51], s98, v88
	v_cndmask_b32_e64 v196, 0, v196, s[30:31]
	v_add_u32_e32 v85, 96, v84
	v_cmp_gt_u32_e64 s[30:31], s98, v85
	v_cndmask_b32_e64 v197, 0, v197, s[36:37]
	v_add_u32_e32 v86, 100, v84
	v_cmp_gt_u32_e64 s[36:37], s98, v86
	v_cndmask_b32_e64 v198, 0, v198, s[78:79]
	v_add_u32_e32 v87, 104, v84
	v_cmp_gt_u32_e64 s[78:79], s98, v87
	v_cndmask_b32_e64 v199, 0, v199, s[50:51]
	v_add_u32_e32 v88, 108, v84
	v_cmp_gt_u32_e64 s[50:51], s98, v88
	v_nop
	v_cndmask_b32_e64 v200, 0, v200, s[30:31]
	v_cndmask_b32_e64 v201, 0, v201, s[36:37]
	v_cndmask_b32_e64 v202, 0, v202, s[78:79]
	v_cndmask_b32_e64 v203, 0, v203, s[50:51]
	v_cvt_pk_bf16_f32 v64, v188, v189
	v_cvt_pk_bf16_f32 v65, v190, v191
	v_cvt_pk_bf16_f32 v66, v192, v193
	v_cvt_pk_bf16_f32 v67, v194, v195
	v_cvt_pk_bf16_f32 v68, v196, v197
	v_cvt_pk_bf16_f32 v69, v198, v199
	v_cvt_pk_bf16_f32 v70, v200, v201
	v_cvt_pk_bf16_f32 v71, v202, v203
	v_pk_add_f32 v[232:233], v[232:233], v[188:189]
	v_pk_add_f32 v[232:233], v[232:233], v[190:191]
	v_pk_add_f32 v[232:233], v[232:233], v[192:193]
	v_pk_add_f32 v[232:233], v[232:233], v[194:195]
	v_pk_add_f32 v[232:233], v[232:233], v[196:197]
	v_pk_add_f32 v[232:233], v[232:233], v[198:199]
	v_pk_add_f32 v[232:233], v[232:233], v[200:201]
	v_pk_add_f32 v[232:233], v[232:233], v[202:203]
	ds_read2_b32 v[188:189], v115 offset0:96 offset1:97
	ds_read2_b32 v[190:191], v115 offset0:98 offset1:99
	ds_read2_b32 v[192:193], v115 offset0:104 offset1:105
	ds_read2_b32 v[194:195], v115 offset0:106 offset1:107
	ds_read2_b32 v[196:197], v115 offset0:112 offset1:113
	ds_read2_b32 v[198:199], v115 offset0:114 offset1:115
	ds_read2_b32 v[200:201], v115 offset0:120 offset1:121
	ds_read2_b32 v[202:203], v115 offset0:122 offset1:123
	v_mfma_f32_32x32x16_bf16 v[0:15], v[64:67], v[72:75], v[0:15]
	v_mfma_f32_32x32x16_bf16 v[16:31], v[64:67], v[76:79], v[16:31]
	v_mfma_f32_32x32x16_bf16 v[0:15], v[68:71], v[220:223], v[0:15]
	v_mfma_f32_32x32x16_bf16 v[16:31], v[68:71], v[224:227], v[16:31]
	s_add_i32 s90, s67, 256
	v_add_u32_e32 v80, s90, v239
	v_add_u32_e32 v83, s90, v240
	v_add_u32_e32 v99, s90, v241
	v_add_u32_e32 v253, s90, v242
	v_add_u32_e32 v254, s90, v101
	v_add_u32_e32 v255, s90, v150
	v_med3_i32 v80, v80, 0, s99
	v_med3_i32 v83, v83, 0, s99
	v_med3_i32 v99, v99, 0, s99
	v_med3_i32 v253, v253, 0, s99
	v_med3_i32 v254, v254, 0, s99
	v_med3_i32 v255, v255, 0, s99
	v_mad_u32_u24 v80, v80, s100, v252
	v_mad_u32_u24 v83, v83, s100, v252
	v_mad_u32_u24 v99, v99, s100, v252
	v_mad_u32_u24 v253, v253, s100, v252
	v_mad_u32_u24 v254, v254, s100, v153
	v_mad_u32_u24 v255, v255, s100, v153
	global_load_dwordx4 v[116:119], v80, s[82:83]
	global_load_dwordx4 v[120:123], v83, s[82:83]
	global_load_dwordx4 v[124:127], v99, s[82:83]
	global_load_dwordx4 v[128:131], v253, s[82:83]
	global_load_dwordx4 v[132:135], v254, s[82:83] offset:768
	global_load_dwordx4 v[136:139], v255, s[82:83] offset:768
	global_load_dwordx4 v[140:143], v254, s[82:83] offset:832
	global_load_dwordx4 v[144:147], v255, s[82:83] offset:832
	ds_read_b64_tr_b16 v[72:73], v231
	ds_read_b64_tr_b16 v[74:75], v231 offset:512
	ds_read_b64_tr_b16 v[76:77], v231 offset:2048
	ds_read_b64_tr_b16 v[78:79], v231 offset:2560
	ds_read_b64_tr_b16 v[220:221], v231 offset:1024
	ds_read_b64_tr_b16 v[222:223], v231 offset:1536
	ds_read_b64_tr_b16 v[224:225], v231 offset:3072
	ds_read_b64_tr_b16 v[226:227], v231 offset:3584
	v_exp_f32_e32 v32, v32
	v_exp_f32_e32 v33, v33
	v_exp_f32_e32 v34, v34
	v_exp_f32_e32 v35, v35
	s_waitcnt vmcnt(12)
	ds_write_b128 v247, v[156:159]
	ds_write_b128 v247, v[160:163] offset:1024
	ds_write_b128 v247, v[164:167] offset:2048
	ds_write_b128 v247, v[168:171] offset:3072
	ds_read_b128 v[156:159], v248
	ds_read_b128 v[160:163], v249
	ds_read_b128 v[164:167], v250
	ds_read_b128 v[168:171], v251
	s_waitcnt vmcnt(8)
	ds_write_b128 v112, v[172:175]
	ds_write_b128 v112, v[176:179] offset:1024
	ds_write_b128 v112, v[180:183] offset:2048
	ds_write_b128 v112, v[184:187] offset:3072
	v_exp_f32_e32 v36, v36
	v_exp_f32_e32 v37, v37
	v_exp_f32_e32 v38, v38
	v_exp_f32_e32 v39, v39
	s_waitcnt lgkmcnt(4)
	v_mfma_f32_32x32x16_bf16 v[188:203], v[156:159], v[48:51], v[188:203]
	v_exp_f32_e32 v40, v40
	v_exp_f32_e32 v41, v41
	v_mfma_f32_32x32x16_bf16 v[188:203], v[160:163], v[52:55], v[188:203]
	v_exp_f32_e32 v42, v42
	v_exp_f32_e32 v43, v43
	v_mfma_f32_32x32x16_bf16 v[188:203], v[164:167], v[56:59], v[188:203]
	v_exp_f32_e32 v44, v44
	v_exp_f32_e32 v45, v45
	v_mfma_f32_32x32x16_bf16 v[188:203], v[168:171], v[60:63], v[188:203]
	v_exp_f32_e32 v46, v46
	v_exp_f32_e32 v47, v47
	s_add_i32 s90, s67, 0
	v_lshlrev_b32_e32 v84, 2, v107
	v_add_u32_e32 v84, s90, v84
	v_add_u32_e32 v85, 0, v84
	v_add_u32_e32 v86, 4, v84
	v_add_u32_e32 v87, 8, v84
	v_add_u32_e32 v88, 12, v84
	v_cmp_gt_u32_e64 s[30:31], s98, v85
	v_cmp_gt_u32_e64 s[36:37], s98, v86
	v_cmp_gt_u32_e64 s[78:79], s98, v87
	v_cmp_gt_u32_e64 s[50:51], s98, v88
	v_cndmask_b32_e64 v32, 0, v32, s[30:31]
	v_add_u32_e32 v85, 32, v84
	v_cmp_gt_u32_e64 s[30:31], s98, v85
	v_cndmask_b32_e64 v33, 0, v33, s[36:37]
	v_add_u32_e32 v86, 36, v84
	v_cmp_gt_u32_e64 s[36:37], s98, v86
	v_cndmask_b32_e64 v34, 0, v34, s[78:79]
	v_add_u32_e32 v87, 40, v84
	v_cmp_gt_u32_e64 s[78:79], s98, v87
	v_cndmask_b32_e64 v35, 0, v35, s[50:51]
	v_add_u32_e32 v88, 44, v84
	v_cmp_gt_u32_e64 s[50:51], s98, v88
	v_cndmask_b32_e64 v36, 0, v36, s[30:31]
	v_add_u32_e32 v85, 64, v84
	v_cmp_gt_u32_e64 s[30:31], s98, v85
	v_cndmask_b32_e64 v37, 0, v37, s[36:37]
	v_add_u32_e32 v86, 68, v84
	v_cmp_gt_u32_e64 s[36:37], s98, v86
	v_cndmask_b32_e64 v38, 0, v38, s[78:79]
	v_add_u32_e32 v87, 72, v84
	v_cmp_gt_u32_e64 s[78:79], s98, v87
	v_cndmask_b32_e64 v39, 0, v39, s[50:51]
	v_add_u32_e32 v88, 76, v84
	v_cmp_gt_u32_e64 s[50:51], s98, v88
	v_cndmask_b32_e64 v40, 0, v40, s[30:31]
	v_add_u32_e32 v85, 96, v84
	v_cmp_gt_u32_e64 s[30:31], s98, v85
	v_cndmask_b32_e64 v41, 0, v41, s[36:37]
	v_add_u32_e32 v86, 100, v84
	v_cmp_gt_u32_e64 s[36:37], s98, v86
	v_cndmask_b32_e64 v42, 0, v42, s[78:79]
	v_add_u32_e32 v87, 104, v84
	v_cmp_gt_u32_e64 s[78:79], s98, v87
	v_cndmask_b32_e64 v43, 0, v43, s[50:51]
	v_add_u32_e32 v88, 108, v84
	v_cmp_gt_u32_e64 s[50:51], s98, v88
	v_nop
	v_cndmask_b32_e64 v44, 0, v44, s[30:31]
	v_cndmask_b32_e64 v45, 0, v45, s[36:37]
	v_cndmask_b32_e64 v46, 0, v46, s[78:79]
	v_cndmask_b32_e64 v47, 0, v47, s[50:51]
	v_cvt_pk_bf16_f32 v64, v32, v33
	v_cvt_pk_bf16_f32 v65, v34, v35
	v_cvt_pk_bf16_f32 v66, v36, v37
	v_cvt_pk_bf16_f32 v67, v38, v39
	v_cvt_pk_bf16_f32 v68, v40, v41
	v_cvt_pk_bf16_f32 v69, v42, v43
	v_cvt_pk_bf16_f32 v70, v44, v45
	v_cvt_pk_bf16_f32 v71, v46, v47
	v_pk_add_f32 v[232:233], v[232:233], v[32:33]
	v_pk_add_f32 v[232:233], v[232:233], v[34:35]
	v_pk_add_f32 v[232:233], v[232:233], v[36:37]
	v_pk_add_f32 v[232:233], v[232:233], v[38:39]
	v_pk_add_f32 v[232:233], v[232:233], v[40:41]
	v_pk_add_f32 v[232:233], v[232:233], v[42:43]
	v_pk_add_f32 v[232:233], v[232:233], v[44:45]
	v_pk_add_f32 v[232:233], v[232:233], v[46:47]
	ds_read2_b32 v[32:33], v115 offset0:128 offset1:129
	ds_read2_b32 v[34:35], v115 offset0:130 offset1:131
	ds_read2_b32 v[36:37], v115 offset0:136 offset1:137
	ds_read2_b32 v[38:39], v115 offset0:138 offset1:139
	ds_read2_b32 v[40:41], v115 offset0:144 offset1:145
	ds_read2_b32 v[42:43], v115 offset0:146 offset1:147
	ds_read2_b32 v[44:45], v115 offset0:152 offset1:153
	ds_read2_b32 v[46:47], v115 offset0:154 offset1:155
	v_mfma_f32_32x32x16_bf16 v[0:15], v[64:67], v[72:75], v[0:15]
	v_mfma_f32_32x32x16_bf16 v[16:31], v[64:67], v[76:79], v[16:31]
	v_mfma_f32_32x32x16_bf16 v[0:15], v[68:71], v[220:223], v[0:15]
	v_mfma_f32_32x32x16_bf16 v[16:31], v[68:71], v[224:227], v[16:31]
	s_add_i32 s90, s67, 384
	v_add_u32_e32 v80, s90, v239
	v_add_u32_e32 v83, s90, v240
	v_add_u32_e32 v99, s90, v241
	v_add_u32_e32 v253, s90, v242
	v_add_u32_e32 v254, s90, v101
	v_add_u32_e32 v255, s90, v150
	v_med3_i32 v80, v80, 0, s99
	v_med3_i32 v83, v83, 0, s99
	v_med3_i32 v99, v99, 0, s99
	v_med3_i32 v253, v253, 0, s99
	v_med3_i32 v254, v254, 0, s99
	v_med3_i32 v255, v255, 0, s99
	v_mad_u32_u24 v80, v80, s100, v252
	v_mad_u32_u24 v83, v83, s100, v252
	v_mad_u32_u24 v99, v99, s100, v252
	v_mad_u32_u24 v253, v253, s100, v252
	v_mad_u32_u24 v254, v254, s100, v153
	v_mad_u32_u24 v255, v255, s100, v153
	global_load_dwordx4 v[156:159], v80, s[82:83]
	global_load_dwordx4 v[160:163], v83, s[82:83]
	global_load_dwordx4 v[164:167], v99, s[82:83]
	global_load_dwordx4 v[168:171], v253, s[82:83]
	global_load_dwordx4 v[172:175], v254, s[82:83] offset:768
	global_load_dwordx4 v[176:179], v255, s[82:83] offset:768
	global_load_dwordx4 v[180:183], v254, s[82:83] offset:832
	global_load_dwordx4 v[184:187], v255, s[82:83] offset:832
	ds_read_b64_tr_b16 v[72:73], v231
	ds_read_b64_tr_b16 v[74:75], v231 offset:512
	ds_read_b64_tr_b16 v[76:77], v231 offset:2048
	ds_read_b64_tr_b16 v[78:79], v231 offset:2560
	ds_read_b64_tr_b16 v[220:221], v231 offset:1024
	ds_read_b64_tr_b16 v[222:223], v231 offset:1536
	ds_read_b64_tr_b16 v[224:225], v231 offset:3072
	ds_read_b64_tr_b16 v[226:227], v231 offset:3584
	v_exp_f32_e32 v188, v188
	v_exp_f32_e32 v189, v189
	v_exp_f32_e32 v190, v190
	v_exp_f32_e32 v191, v191
	s_waitcnt vmcnt(12)
	ds_write_b128 v247, v[116:119]
	ds_write_b128 v247, v[120:123] offset:1024
	ds_write_b128 v247, v[124:127] offset:2048
	ds_write_b128 v247, v[128:131] offset:3072
	ds_read_b128 v[116:119], v248
	ds_read_b128 v[120:123], v249
	ds_read_b128 v[124:127], v250
	ds_read_b128 v[128:131], v251
	s_waitcnt vmcnt(8)
	ds_write_b128 v112, v[132:135]
	ds_write_b128 v112, v[136:139] offset:1024
	ds_write_b128 v112, v[140:143] offset:2048
	ds_write_b128 v112, v[144:147] offset:3072
	v_exp_f32_e32 v192, v192
	v_exp_f32_e32 v193, v193
	v_exp_f32_e32 v194, v194
	v_exp_f32_e32 v195, v195
	s_waitcnt lgkmcnt(4)
	v_mfma_f32_32x32x16_bf16 v[32:47], v[116:119], v[48:51], v[32:47]
	v_exp_f32_e32 v196, v196
	v_exp_f32_e32 v197, v197
	v_mfma_f32_32x32x16_bf16 v[32:47], v[120:123], v[52:55], v[32:47]
	v_exp_f32_e32 v198, v198
	v_exp_f32_e32 v199, v199
	v_mfma_f32_32x32x16_bf16 v[32:47], v[124:127], v[56:59], v[32:47]
	v_exp_f32_e32 v200, v200
	v_exp_f32_e32 v201, v201
	v_mfma_f32_32x32x16_bf16 v[32:47], v[128:131], v[60:63], v[32:47]
	v_exp_f32_e32 v202, v202
	v_exp_f32_e32 v203, v203
	s_add_i32 s90, s67, 128
	v_lshlrev_b32_e32 v84, 2, v107
	v_add_u32_e32 v84, s90, v84
	v_add_u32_e32 v85, 0, v84
	v_add_u32_e32 v86, 4, v84
	v_add_u32_e32 v87, 8, v84
	v_add_u32_e32 v88, 12, v84
	v_cmp_gt_u32_e64 s[30:31], s98, v85
	v_cmp_gt_u32_e64 s[36:37], s98, v86
	v_cmp_gt_u32_e64 s[78:79], s98, v87
	v_cmp_gt_u32_e64 s[50:51], s98, v88
	v_cndmask_b32_e64 v188, 0, v188, s[30:31]
	v_add_u32_e32 v85, 32, v84
	v_cmp_gt_u32_e64 s[30:31], s98, v85
	v_cndmask_b32_e64 v189, 0, v189, s[36:37]
	v_add_u32_e32 v86, 36, v84
	v_cmp_gt_u32_e64 s[36:37], s98, v86
	v_cndmask_b32_e64 v190, 0, v190, s[78:79]
	v_add_u32_e32 v87, 40, v84
	v_cmp_gt_u32_e64 s[78:79], s98, v87
	v_cndmask_b32_e64 v191, 0, v191, s[50:51]
	v_add_u32_e32 v88, 44, v84
	v_cmp_gt_u32_e64 s[50:51], s98, v88
	v_cndmask_b32_e64 v192, 0, v192, s[30:31]
	v_add_u32_e32 v85, 64, v84
	v_cmp_gt_u32_e64 s[30:31], s98, v85
	v_cndmask_b32_e64 v193, 0, v193, s[36:37]
	v_add_u32_e32 v86, 68, v84
	v_cmp_gt_u32_e64 s[36:37], s98, v86
	v_cndmask_b32_e64 v194, 0, v194, s[78:79]
	v_add_u32_e32 v87, 72, v84
	v_cmp_gt_u32_e64 s[78:79], s98, v87
	v_cndmask_b32_e64 v195, 0, v195, s[50:51]
	v_add_u32_e32 v88, 76, v84
	v_cmp_gt_u32_e64 s[50:51], s98, v88
	v_cndmask_b32_e64 v196, 0, v196, s[30:31]
	v_add_u32_e32 v85, 96, v84
	v_cmp_gt_u32_e64 s[30:31], s98, v85
	v_cndmask_b32_e64 v197, 0, v197, s[36:37]
	v_add_u32_e32 v86, 100, v84
	v_cmp_gt_u32_e64 s[36:37], s98, v86
	v_cndmask_b32_e64 v198, 0, v198, s[78:79]
	v_add_u32_e32 v87, 104, v84
	v_cmp_gt_u32_e64 s[78:79], s98, v87
	v_cndmask_b32_e64 v199, 0, v199, s[50:51]
	v_add_u32_e32 v88, 108, v84
	v_cmp_gt_u32_e64 s[50:51], s98, v88
	v_nop
	v_cndmask_b32_e64 v200, 0, v200, s[30:31]
	v_cndmask_b32_e64 v201, 0, v201, s[36:37]
	v_cndmask_b32_e64 v202, 0, v202, s[78:79]
	v_cndmask_b32_e64 v203, 0, v203, s[50:51]
	v_cvt_pk_bf16_f32 v64, v188, v189
	v_cvt_pk_bf16_f32 v65, v190, v191
	v_cvt_pk_bf16_f32 v66, v192, v193
	v_cvt_pk_bf16_f32 v67, v194, v195
	v_cvt_pk_bf16_f32 v68, v196, v197
	v_cvt_pk_bf16_f32 v69, v198, v199
	v_cvt_pk_bf16_f32 v70, v200, v201
	v_cvt_pk_bf16_f32 v71, v202, v203
	v_pk_add_f32 v[232:233], v[232:233], v[188:189]
	v_pk_add_f32 v[232:233], v[232:233], v[190:191]
	v_pk_add_f32 v[232:233], v[232:233], v[192:193]
	v_pk_add_f32 v[232:233], v[232:233], v[194:195]
	v_pk_add_f32 v[232:233], v[232:233], v[196:197]
	v_pk_add_f32 v[232:233], v[232:233], v[198:199]
	v_pk_add_f32 v[232:233], v[232:233], v[200:201]
	v_pk_add_f32 v[232:233], v[232:233], v[202:203]
	ds_read2_b32 v[188:189], v115 offset0:160 offset1:161
	ds_read2_b32 v[190:191], v115 offset0:162 offset1:163
	ds_read2_b32 v[192:193], v115 offset0:168 offset1:169
	ds_read2_b32 v[194:195], v115 offset0:170 offset1:171
	ds_read2_b32 v[196:197], v115 offset0:176 offset1:177
	ds_read2_b32 v[198:199], v115 offset0:178 offset1:179
	ds_read2_b32 v[200:201], v115 offset0:184 offset1:185
	ds_read2_b32 v[202:203], v115 offset0:186 offset1:187
	v_mfma_f32_32x32x16_bf16 v[0:15], v[64:67], v[72:75], v[0:15]
	v_mfma_f32_32x32x16_bf16 v[16:31], v[64:67], v[76:79], v[16:31]
	v_mfma_f32_32x32x16_bf16 v[0:15], v[68:71], v[220:223], v[0:15]
	v_mfma_f32_32x32x16_bf16 v[16:31], v[68:71], v[224:227], v[16:31]
	s_add_i32 s90, s67, 512
	v_add_u32_e32 v80, s90, v239
	v_add_u32_e32 v83, s90, v240
	v_add_u32_e32 v99, s90, v241
	v_add_u32_e32 v253, s90, v242
	v_add_u32_e32 v254, s90, v101
	v_add_u32_e32 v255, s90, v150
	v_med3_i32 v80, v80, 0, s99
	v_med3_i32 v83, v83, 0, s99
	v_med3_i32 v99, v99, 0, s99
	v_med3_i32 v253, v253, 0, s99
	v_med3_i32 v254, v254, 0, s99
	v_med3_i32 v255, v255, 0, s99
	v_mad_u32_u24 v80, v80, s100, v252
	v_mad_u32_u24 v83, v83, s100, v252
	v_mad_u32_u24 v99, v99, s100, v252
	v_mad_u32_u24 v253, v253, s100, v252
	v_mad_u32_u24 v254, v254, s100, v153
	v_mad_u32_u24 v255, v255, s100, v153
	global_load_dwordx4 v[116:119], v80, s[82:83]
	global_load_dwordx4 v[120:123], v83, s[82:83]
	global_load_dwordx4 v[124:127], v99, s[82:83]
	global_load_dwordx4 v[128:131], v253, s[82:83]
	global_load_dwordx4 v[132:135], v254, s[82:83] offset:768
	global_load_dwordx4 v[136:139], v255, s[82:83] offset:768
	global_load_dwordx4 v[140:143], v254, s[82:83] offset:832
	global_load_dwordx4 v[144:147], v255, s[82:83] offset:832
	ds_read_b64_tr_b16 v[72:73], v231
	ds_read_b64_tr_b16 v[74:75], v231 offset:512
	ds_read_b64_tr_b16 v[76:77], v231 offset:2048
	ds_read_b64_tr_b16 v[78:79], v231 offset:2560
	ds_read_b64_tr_b16 v[220:221], v231 offset:1024
	ds_read_b64_tr_b16 v[222:223], v231 offset:1536
	ds_read_b64_tr_b16 v[224:225], v231 offset:3072
	ds_read_b64_tr_b16 v[226:227], v231 offset:3584
	v_exp_f32_e32 v32, v32
	v_exp_f32_e32 v33, v33
	v_exp_f32_e32 v34, v34
	v_exp_f32_e32 v35, v35
	s_waitcnt vmcnt(12)
	ds_write_b128 v247, v[156:159]
	ds_write_b128 v247, v[160:163] offset:1024
	ds_write_b128 v247, v[164:167] offset:2048
	ds_write_b128 v247, v[168:171] offset:3072
	ds_read_b128 v[156:159], v248
	ds_read_b128 v[160:163], v249
	ds_read_b128 v[164:167], v250
	ds_read_b128 v[168:171], v251
	s_waitcnt vmcnt(8)
	ds_write_b128 v112, v[172:175]
	ds_write_b128 v112, v[176:179] offset:1024
	ds_write_b128 v112, v[180:183] offset:2048
	ds_write_b128 v112, v[184:187] offset:3072
	v_exp_f32_e32 v36, v36
	v_exp_f32_e32 v37, v37
	v_exp_f32_e32 v38, v38
	v_exp_f32_e32 v39, v39
	s_waitcnt lgkmcnt(4)
	v_mfma_f32_32x32x16_bf16 v[188:203], v[156:159], v[48:51], v[188:203]
	v_exp_f32_e32 v40, v40
	v_exp_f32_e32 v41, v41
	v_mfma_f32_32x32x16_bf16 v[188:203], v[160:163], v[52:55], v[188:203]
	v_exp_f32_e32 v42, v42
	v_exp_f32_e32 v43, v43
	v_mfma_f32_32x32x16_bf16 v[188:203], v[164:167], v[56:59], v[188:203]
	v_exp_f32_e32 v44, v44
	v_exp_f32_e32 v45, v45
	v_mfma_f32_32x32x16_bf16 v[188:203], v[168:171], v[60:63], v[188:203]
	v_exp_f32_e32 v46, v46
	v_exp_f32_e32 v47, v47
	s_add_i32 s90, s67, 256
	v_lshlrev_b32_e32 v84, 2, v107
	v_add_u32_e32 v84, s90, v84
	v_add_u32_e32 v85, 0, v84
	v_add_u32_e32 v86, 4, v84
	v_add_u32_e32 v87, 8, v84
	v_add_u32_e32 v88, 12, v84
	v_cmp_gt_u32_e64 s[30:31], s98, v85
	v_cmp_gt_u32_e64 s[36:37], s98, v86
	v_cmp_gt_u32_e64 s[78:79], s98, v87
	v_cmp_gt_u32_e64 s[50:51], s98, v88
	v_cndmask_b32_e64 v32, 0, v32, s[30:31]
	v_add_u32_e32 v85, 32, v84
	v_cmp_gt_u32_e64 s[30:31], s98, v85
	v_cndmask_b32_e64 v33, 0, v33, s[36:37]
	v_add_u32_e32 v86, 36, v84
	v_cmp_gt_u32_e64 s[36:37], s98, v86
	v_cndmask_b32_e64 v34, 0, v34, s[78:79]
	v_add_u32_e32 v87, 40, v84
	v_cmp_gt_u32_e64 s[78:79], s98, v87
	v_cndmask_b32_e64 v35, 0, v35, s[50:51]
	v_add_u32_e32 v88, 44, v84
	v_cmp_gt_u32_e64 s[50:51], s98, v88
	v_cndmask_b32_e64 v36, 0, v36, s[30:31]
	v_add_u32_e32 v85, 64, v84
	v_cmp_gt_u32_e64 s[30:31], s98, v85
	v_cndmask_b32_e64 v37, 0, v37, s[36:37]
	v_add_u32_e32 v86, 68, v84
	v_cmp_gt_u32_e64 s[36:37], s98, v86
	v_cndmask_b32_e64 v38, 0, v38, s[78:79]
	v_add_u32_e32 v87, 72, v84
	v_cmp_gt_u32_e64 s[78:79], s98, v87
	v_cndmask_b32_e64 v39, 0, v39, s[50:51]
	v_add_u32_e32 v88, 76, v84
	v_cmp_gt_u32_e64 s[50:51], s98, v88
	v_cndmask_b32_e64 v40, 0, v40, s[30:31]
	v_add_u32_e32 v85, 96, v84
	v_cmp_gt_u32_e64 s[30:31], s98, v85
	v_cndmask_b32_e64 v41, 0, v41, s[36:37]
	v_add_u32_e32 v86, 100, v84
	v_cmp_gt_u32_e64 s[36:37], s98, v86
	v_cndmask_b32_e64 v42, 0, v42, s[78:79]
	v_add_u32_e32 v87, 104, v84
	v_cmp_gt_u32_e64 s[78:79], s98, v87
	v_cndmask_b32_e64 v43, 0, v43, s[50:51]
	v_add_u32_e32 v88, 108, v84
	v_cmp_gt_u32_e64 s[50:51], s98, v88
	v_nop
	v_cndmask_b32_e64 v44, 0, v44, s[30:31]
	v_cndmask_b32_e64 v45, 0, v45, s[36:37]
	v_cndmask_b32_e64 v46, 0, v46, s[78:79]
	v_cndmask_b32_e64 v47, 0, v47, s[50:51]
	v_cvt_pk_bf16_f32 v64, v32, v33
	v_cvt_pk_bf16_f32 v65, v34, v35
	v_cvt_pk_bf16_f32 v66, v36, v37
	v_cvt_pk_bf16_f32 v67, v38, v39
	v_cvt_pk_bf16_f32 v68, v40, v41
	v_cvt_pk_bf16_f32 v69, v42, v43
	v_cvt_pk_bf16_f32 v70, v44, v45
	v_cvt_pk_bf16_f32 v71, v46, v47
	v_pk_add_f32 v[232:233], v[232:233], v[32:33]
	v_pk_add_f32 v[232:233], v[232:233], v[34:35]
	v_pk_add_f32 v[232:233], v[232:233], v[36:37]
	v_pk_add_f32 v[232:233], v[232:233], v[38:39]
	v_pk_add_f32 v[232:233], v[232:233], v[40:41]
	v_pk_add_f32 v[232:233], v[232:233], v[42:43]
	v_pk_add_f32 v[232:233], v[232:233], v[44:45]
	v_pk_add_f32 v[232:233], v[232:233], v[46:47]
	ds_read2_b32 v[32:33], v115 offset0:192 offset1:193
	ds_read2_b32 v[34:35], v115 offset0:194 offset1:195
	ds_read2_b32 v[36:37], v115 offset0:200 offset1:201
	ds_read2_b32 v[38:39], v115 offset0:202 offset1:203
	ds_read2_b32 v[40:41], v115 offset0:208 offset1:209
	ds_read2_b32 v[42:43], v115 offset0:210 offset1:211
	ds_read2_b32 v[44:45], v115 offset0:216 offset1:217
	ds_read2_b32 v[46:47], v115 offset0:218 offset1:219
	v_mfma_f32_32x32x16_bf16 v[0:15], v[64:67], v[72:75], v[0:15]
	v_mfma_f32_32x32x16_bf16 v[16:31], v[64:67], v[76:79], v[16:31]
	v_mfma_f32_32x32x16_bf16 v[0:15], v[68:71], v[220:223], v[0:15]
	v_mfma_f32_32x32x16_bf16 v[16:31], v[68:71], v[224:227], v[16:31]
	s_add_i32 s90, s67, 640
	v_add_u32_e32 v80, s90, v239
	v_add_u32_e32 v83, s90, v240
	v_add_u32_e32 v99, s90, v241
	v_add_u32_e32 v253, s90, v242
	v_add_u32_e32 v254, s90, v101
	v_add_u32_e32 v255, s90, v150
	v_med3_i32 v80, v80, 0, s99
	v_med3_i32 v83, v83, 0, s99
	v_med3_i32 v99, v99, 0, s99
	v_med3_i32 v253, v253, 0, s99
	v_med3_i32 v254, v254, 0, s99
	v_med3_i32 v255, v255, 0, s99
	v_mad_u32_u24 v80, v80, s100, v252
	v_mad_u32_u24 v83, v83, s100, v252
	v_mad_u32_u24 v99, v99, s100, v252
	v_mad_u32_u24 v253, v253, s100, v252
	v_mad_u32_u24 v254, v254, s100, v153
	v_mad_u32_u24 v255, v255, s100, v153
	global_load_dwordx4 v[156:159], v80, s[82:83]
	global_load_dwordx4 v[160:163], v83, s[82:83]
	global_load_dwordx4 v[164:167], v99, s[82:83]
	global_load_dwordx4 v[168:171], v253, s[82:83]
	global_load_dwordx4 v[172:175], v254, s[82:83] offset:768
	global_load_dwordx4 v[176:179], v255, s[82:83] offset:768
	global_load_dwordx4 v[180:183], v254, s[82:83] offset:832
	global_load_dwordx4 v[184:187], v255, s[82:83] offset:832
	ds_read_b64_tr_b16 v[72:73], v231
	ds_read_b64_tr_b16 v[74:75], v231 offset:512
	ds_read_b64_tr_b16 v[76:77], v231 offset:2048
	ds_read_b64_tr_b16 v[78:79], v231 offset:2560
	ds_read_b64_tr_b16 v[220:221], v231 offset:1024
	ds_read_b64_tr_b16 v[222:223], v231 offset:1536
	ds_read_b64_tr_b16 v[224:225], v231 offset:3072
	ds_read_b64_tr_b16 v[226:227], v231 offset:3584
	v_exp_f32_e32 v188, v188
	v_exp_f32_e32 v189, v189
	v_exp_f32_e32 v190, v190
	v_exp_f32_e32 v191, v191
	s_waitcnt vmcnt(12)
	ds_write_b128 v247, v[116:119]
	ds_write_b128 v247, v[120:123] offset:1024
	ds_write_b128 v247, v[124:127] offset:2048
	ds_write_b128 v247, v[128:131] offset:3072
	ds_read_b128 v[116:119], v248
	ds_read_b128 v[120:123], v249
	ds_read_b128 v[124:127], v250
	ds_read_b128 v[128:131], v251
	s_waitcnt vmcnt(8)
	ds_write_b128 v112, v[132:135]
	ds_write_b128 v112, v[136:139] offset:1024
	ds_write_b128 v112, v[140:143] offset:2048
	ds_write_b128 v112, v[144:147] offset:3072
	v_exp_f32_e32 v192, v192
	v_exp_f32_e32 v193, v193
	v_exp_f32_e32 v194, v194
	v_exp_f32_e32 v195, v195
	s_waitcnt lgkmcnt(4)
	v_mfma_f32_32x32x16_bf16 v[32:47], v[116:119], v[48:51], v[32:47]
	v_exp_f32_e32 v196, v196
	v_exp_f32_e32 v197, v197
	v_mfma_f32_32x32x16_bf16 v[32:47], v[120:123], v[52:55], v[32:47]
	v_exp_f32_e32 v198, v198
	v_exp_f32_e32 v199, v199
	v_mfma_f32_32x32x16_bf16 v[32:47], v[124:127], v[56:59], v[32:47]
	v_exp_f32_e32 v200, v200
	v_exp_f32_e32 v201, v201
	v_mfma_f32_32x32x16_bf16 v[32:47], v[128:131], v[60:63], v[32:47]
	v_exp_f32_e32 v202, v202
	v_exp_f32_e32 v203, v203
	s_add_i32 s90, s67, 384
	v_lshlrev_b32_e32 v84, 2, v107
	v_add_u32_e32 v84, s90, v84
	v_add_u32_e32 v85, 0, v84
	v_add_u32_e32 v86, 4, v84
	v_add_u32_e32 v87, 8, v84
	v_add_u32_e32 v88, 12, v84
	v_cmp_gt_u32_e64 s[30:31], s98, v85
	v_cmp_gt_u32_e64 s[36:37], s98, v86
	v_cmp_gt_u32_e64 s[78:79], s98, v87
	v_cmp_gt_u32_e64 s[50:51], s98, v88
	v_cndmask_b32_e64 v188, 0, v188, s[30:31]
	v_add_u32_e32 v85, 32, v84
	v_cmp_gt_u32_e64 s[30:31], s98, v85
	v_cndmask_b32_e64 v189, 0, v189, s[36:37]
	v_add_u32_e32 v86, 36, v84
	v_cmp_gt_u32_e64 s[36:37], s98, v86
	v_cndmask_b32_e64 v190, 0, v190, s[78:79]
	v_add_u32_e32 v87, 40, v84
	v_cmp_gt_u32_e64 s[78:79], s98, v87
	v_cndmask_b32_e64 v191, 0, v191, s[50:51]
	v_add_u32_e32 v88, 44, v84
	v_cmp_gt_u32_e64 s[50:51], s98, v88
	v_cndmask_b32_e64 v192, 0, v192, s[30:31]
	v_add_u32_e32 v85, 64, v84
	v_cmp_gt_u32_e64 s[30:31], s98, v85
	v_cndmask_b32_e64 v193, 0, v193, s[36:37]
	v_add_u32_e32 v86, 68, v84
	v_cmp_gt_u32_e64 s[36:37], s98, v86
	v_cndmask_b32_e64 v194, 0, v194, s[78:79]
	v_add_u32_e32 v87, 72, v84
	v_cmp_gt_u32_e64 s[78:79], s98, v87
	v_cndmask_b32_e64 v195, 0, v195, s[50:51]
	v_add_u32_e32 v88, 76, v84
	v_cmp_gt_u32_e64 s[50:51], s98, v88
	v_cndmask_b32_e64 v196, 0, v196, s[30:31]
	v_add_u32_e32 v85, 96, v84
	v_cmp_gt_u32_e64 s[30:31], s98, v85
	v_cndmask_b32_e64 v197, 0, v197, s[36:37]
	v_add_u32_e32 v86, 100, v84
	v_cmp_gt_u32_e64 s[36:37], s98, v86
	v_cndmask_b32_e64 v198, 0, v198, s[78:79]
	v_add_u32_e32 v87, 104, v84
	v_cmp_gt_u32_e64 s[78:79], s98, v87
	v_cndmask_b32_e64 v199, 0, v199, s[50:51]
	v_add_u32_e32 v88, 108, v84
	v_cmp_gt_u32_e64 s[50:51], s98, v88
	v_nop
	v_cndmask_b32_e64 v200, 0, v200, s[30:31]
	v_cndmask_b32_e64 v201, 0, v201, s[36:37]
	v_cndmask_b32_e64 v202, 0, v202, s[78:79]
	v_cndmask_b32_e64 v203, 0, v203, s[50:51]
	v_cvt_pk_bf16_f32 v64, v188, v189
	v_cvt_pk_bf16_f32 v65, v190, v191
	v_cvt_pk_bf16_f32 v66, v192, v193
	v_cvt_pk_bf16_f32 v67, v194, v195
	v_cvt_pk_bf16_f32 v68, v196, v197
	v_cvt_pk_bf16_f32 v69, v198, v199
	v_cvt_pk_bf16_f32 v70, v200, v201
	v_cvt_pk_bf16_f32 v71, v202, v203
	v_pk_add_f32 v[232:233], v[232:233], v[188:189]
	v_pk_add_f32 v[232:233], v[232:233], v[190:191]
	v_pk_add_f32 v[232:233], v[232:233], v[192:193]
	v_pk_add_f32 v[232:233], v[232:233], v[194:195]
	v_pk_add_f32 v[232:233], v[232:233], v[196:197]
	v_pk_add_f32 v[232:233], v[232:233], v[198:199]
	v_pk_add_f32 v[232:233], v[232:233], v[200:201]
	v_pk_add_f32 v[232:233], v[232:233], v[202:203]
	ds_read2_b32 v[188:189], v115 offset0:224 offset1:225
	ds_read2_b32 v[190:191], v115 offset0:226 offset1:227
	ds_read2_b32 v[192:193], v115 offset0:232 offset1:233
	ds_read2_b32 v[194:195], v115 offset0:234 offset1:235
	ds_read2_b32 v[196:197], v115 offset0:240 offset1:241
	ds_read2_b32 v[198:199], v115 offset0:242 offset1:243
	ds_read2_b32 v[200:201], v115 offset0:248 offset1:249
	ds_read2_b32 v[202:203], v115 offset0:250 offset1:251
	v_mfma_f32_32x32x16_bf16 v[0:15], v[64:67], v[72:75], v[0:15]
	v_mfma_f32_32x32x16_bf16 v[16:31], v[64:67], v[76:79], v[16:31]
	v_mfma_f32_32x32x16_bf16 v[0:15], v[68:71], v[220:223], v[0:15]
	v_mfma_f32_32x32x16_bf16 v[16:31], v[68:71], v[224:227], v[16:31]
	s_add_i32 s90, s67, -1024
	v_add_u32_e32 v80, s90, v243
	v_add_u32_e32 v83, s90, v244
	v_add_u32_e32 v99, s90, v245
	v_add_u32_e32 v253, s90, v246
	v_add_u32_e32 v254, s90, v148
	v_add_u32_e32 v255, s90, v151
	v_med3_i32 v80, v80, 0, s99
	v_med3_i32 v83, v83, 0, s99
	v_med3_i32 v99, v99, 0, s99
	v_med3_i32 v253, v253, 0, s99
	v_med3_i32 v254, v254, 0, s99
	v_med3_i32 v255, v255, 0, s99
	v_mad_u32_u24 v80, v80, s100, v252
	v_mad_u32_u24 v83, v83, s100, v252
	v_mad_u32_u24 v99, v99, s100, v252
	v_mad_u32_u24 v253, v253, s100, v252
	v_mad_u32_u24 v254, v254, s100, v153
	v_mad_u32_u24 v255, v255, s100, v153
	global_load_dwordx4 v[116:119], v80, s[82:83]
	global_load_dwordx4 v[120:123], v83, s[82:83]
	global_load_dwordx4 v[124:127], v99, s[82:83]
	global_load_dwordx4 v[128:131], v253, s[82:83]
	global_load_dwordx4 v[132:135], v254, s[82:83] offset:768
	global_load_dwordx4 v[136:139], v255, s[82:83] offset:768
	global_load_dwordx4 v[140:143], v254, s[82:83] offset:832
	global_load_dwordx4 v[144:147], v255, s[82:83] offset:832
	ds_read_b64_tr_b16 v[72:73], v231
	ds_read_b64_tr_b16 v[74:75], v231 offset:512
	ds_read_b64_tr_b16 v[76:77], v231 offset:2048
	ds_read_b64_tr_b16 v[78:79], v231 offset:2560
	ds_read_b64_tr_b16 v[220:221], v231 offset:1024
	ds_read_b64_tr_b16 v[222:223], v231 offset:1536
	ds_read_b64_tr_b16 v[224:225], v231 offset:3072
	ds_read_b64_tr_b16 v[226:227], v231 offset:3584
	v_exp_f32_e32 v32, v32
	v_exp_f32_e32 v33, v33
	v_exp_f32_e32 v34, v34
	v_exp_f32_e32 v35, v35
	s_waitcnt vmcnt(12)
	ds_write_b128 v247, v[156:159]
	ds_write_b128 v247, v[160:163] offset:1024
	ds_write_b128 v247, v[164:167] offset:2048
	ds_write_b128 v247, v[168:171] offset:3072
	ds_read_b128 v[156:159], v248
	ds_read_b128 v[160:163], v249
	ds_read_b128 v[164:167], v250
	ds_read_b128 v[168:171], v251
	s_waitcnt vmcnt(8)
	ds_write_b128 v112, v[172:175]
	ds_write_b128 v112, v[176:179] offset:1024
	ds_write_b128 v112, v[180:183] offset:2048
	ds_write_b128 v112, v[184:187] offset:3072
	v_exp_f32_e32 v36, v36
	v_exp_f32_e32 v37, v37
	v_exp_f32_e32 v38, v38
	v_exp_f32_e32 v39, v39
	s_waitcnt lgkmcnt(4)
	v_mfma_f32_32x32x16_bf16 v[188:203], v[156:159], v[48:51], v[188:203]
	v_exp_f32_e32 v40, v40
	v_exp_f32_e32 v41, v41
	v_mfma_f32_32x32x16_bf16 v[188:203], v[160:163], v[52:55], v[188:203]
	v_exp_f32_e32 v42, v42
	v_exp_f32_e32 v43, v43
	v_mfma_f32_32x32x16_bf16 v[188:203], v[164:167], v[56:59], v[188:203]
	v_exp_f32_e32 v44, v44
	v_exp_f32_e32 v45, v45
	v_mfma_f32_32x32x16_bf16 v[188:203], v[168:171], v[60:63], v[188:203]
	v_exp_f32_e32 v46, v46
	v_exp_f32_e32 v47, v47
	s_add_i32 s90, s67, 512
	v_lshlrev_b32_e32 v84, 2, v107
	v_add_u32_e32 v84, s90, v84
	v_add_u32_e32 v85, 0, v84
	v_add_u32_e32 v86, 4, v84
	v_add_u32_e32 v87, 8, v84
	v_add_u32_e32 v88, 12, v84
	v_cmp_gt_u32_e64 s[30:31], s98, v85
	v_cmp_gt_u32_e64 s[36:37], s98, v86
	v_cmp_gt_u32_e64 s[78:79], s98, v87
	v_cmp_gt_u32_e64 s[50:51], s98, v88
	v_cndmask_b32_e64 v32, 0, v32, s[30:31]
	v_add_u32_e32 v85, 32, v84
	v_cmp_gt_u32_e64 s[30:31], s98, v85
	v_cndmask_b32_e64 v33, 0, v33, s[36:37]
	v_add_u32_e32 v86, 36, v84
	v_cmp_gt_u32_e64 s[36:37], s98, v86
	v_cndmask_b32_e64 v34, 0, v34, s[78:79]
	v_add_u32_e32 v87, 40, v84
	v_cmp_gt_u32_e64 s[78:79], s98, v87
	v_cndmask_b32_e64 v35, 0, v35, s[50:51]
	v_add_u32_e32 v88, 44, v84
	v_cmp_gt_u32_e64 s[50:51], s98, v88
	v_cndmask_b32_e64 v36, 0, v36, s[30:31]
	v_add_u32_e32 v85, 64, v84
	v_cmp_gt_u32_e64 s[30:31], s98, v85
	v_cndmask_b32_e64 v37, 0, v37, s[36:37]
	v_add_u32_e32 v86, 68, v84
	v_cmp_gt_u32_e64 s[36:37], s98, v86
	v_cndmask_b32_e64 v38, 0, v38, s[78:79]
	v_add_u32_e32 v87, 72, v84
	v_cmp_gt_u32_e64 s[78:79], s98, v87
	v_cndmask_b32_e64 v39, 0, v39, s[50:51]
	v_add_u32_e32 v88, 76, v84
	v_cmp_gt_u32_e64 s[50:51], s98, v88
	v_cndmask_b32_e64 v40, 0, v40, s[30:31]
	v_add_u32_e32 v85, 96, v84
	v_cmp_gt_u32_e64 s[30:31], s98, v85
	v_cndmask_b32_e64 v41, 0, v41, s[36:37]
	v_add_u32_e32 v86, 100, v84
	v_cmp_gt_u32_e64 s[36:37], s98, v86
	v_cndmask_b32_e64 v42, 0, v42, s[78:79]
	v_add_u32_e32 v87, 104, v84
	v_cmp_gt_u32_e64 s[78:79], s98, v87
	v_cndmask_b32_e64 v43, 0, v43, s[50:51]
	v_add_u32_e32 v88, 108, v84
	v_cmp_gt_u32_e64 s[50:51], s98, v88
	v_nop
	v_cndmask_b32_e64 v44, 0, v44, s[30:31]
	v_cndmask_b32_e64 v45, 0, v45, s[36:37]
	v_cndmask_b32_e64 v46, 0, v46, s[78:79]
	v_cndmask_b32_e64 v47, 0, v47, s[50:51]
	v_cvt_pk_bf16_f32 v64, v32, v33
	v_cvt_pk_bf16_f32 v65, v34, v35
	v_cvt_pk_bf16_f32 v66, v36, v37
	v_cvt_pk_bf16_f32 v67, v38, v39
	v_cvt_pk_bf16_f32 v68, v40, v41
	v_cvt_pk_bf16_f32 v69, v42, v43
	v_cvt_pk_bf16_f32 v70, v44, v45
	v_cvt_pk_bf16_f32 v71, v46, v47
	v_pk_add_f32 v[232:233], v[232:233], v[32:33]
	v_pk_add_f32 v[232:233], v[232:233], v[34:35]
	v_pk_add_f32 v[232:233], v[232:233], v[36:37]
	v_pk_add_f32 v[232:233], v[232:233], v[38:39]
	v_pk_add_f32 v[232:233], v[232:233], v[40:41]
	v_pk_add_f32 v[232:233], v[232:233], v[42:43]
	v_pk_add_f32 v[232:233], v[232:233], v[44:45]
	v_pk_add_f32 v[232:233], v[232:233], v[46:47]
	v_mov_b32_e32 v115, v230
	ds_read2_b32 v[32:33], v115 offset0:0 offset1:1
	ds_read2_b32 v[34:35], v115 offset0:2 offset1:3
	ds_read2_b32 v[36:37], v115 offset0:8 offset1:9
	ds_read2_b32 v[38:39], v115 offset0:10 offset1:11
	ds_read2_b32 v[40:41], v115 offset0:16 offset1:17
	ds_read2_b32 v[42:43], v115 offset0:18 offset1:19
	ds_read2_b32 v[44:45], v115 offset0:24 offset1:25
	ds_read2_b32 v[46:47], v115 offset0:26 offset1:27
	v_mfma_f32_32x32x16_bf16 v[0:15], v[64:67], v[72:75], v[0:15]
	v_mfma_f32_32x32x16_bf16 v[16:31], v[64:67], v[76:79], v[16:31]
	v_mfma_f32_32x32x16_bf16 v[0:15], v[68:71], v[220:223], v[0:15]
	v_mfma_f32_32x32x16_bf16 v[16:31], v[68:71], v[224:227], v[16:31]
	s_add_i32 s90, s67, -512
	v_add_u32_e32 v80, s90, v243
	v_add_u32_e32 v83, s90, v244
	v_add_u32_e32 v99, s90, v245
	v_add_u32_e32 v253, s90, v246
	v_add_u32_e32 v254, s90, v148
	v_add_u32_e32 v255, s90, v151
	v_med3_i32 v80, v80, 0, s99
	v_med3_i32 v83, v83, 0, s99
	v_med3_i32 v99, v99, 0, s99
	v_med3_i32 v253, v253, 0, s99
	v_med3_i32 v254, v254, 0, s99
	v_med3_i32 v255, v255, 0, s99
	v_mad_u32_u24 v80, v80, s100, v252
	v_mad_u32_u24 v83, v83, s100, v252
	v_mad_u32_u24 v99, v99, s100, v252
	v_mad_u32_u24 v253, v253, s100, v252
	v_mad_u32_u24 v254, v254, s100, v153
	v_mad_u32_u24 v255, v255, s100, v153
	global_load_dwordx4 v[156:159], v80, s[82:83]
	global_load_dwordx4 v[160:163], v83, s[82:83]
	global_load_dwordx4 v[164:167], v99, s[82:83]
	global_load_dwordx4 v[168:171], v253, s[82:83]
	global_load_dwordx4 v[172:175], v254, s[82:83] offset:768
	global_load_dwordx4 v[176:179], v255, s[82:83] offset:768
	global_load_dwordx4 v[180:183], v254, s[82:83] offset:832
	global_load_dwordx4 v[184:187], v255, s[82:83] offset:832
	ds_read_b64_tr_b16 v[72:73], v231
	ds_read_b64_tr_b16 v[74:75], v231 offset:512
	ds_read_b64_tr_b16 v[76:77], v231 offset:2048
	ds_read_b64_tr_b16 v[78:79], v231 offset:2560
	ds_read_b64_tr_b16 v[220:221], v231 offset:1024
	ds_read_b64_tr_b16 v[222:223], v231 offset:1536
	ds_read_b64_tr_b16 v[224:225], v231 offset:3072
	ds_read_b64_tr_b16 v[226:227], v231 offset:3584
	v_exp_f32_e32 v188, v188
	v_exp_f32_e32 v189, v189
	v_exp_f32_e32 v190, v190
	v_exp_f32_e32 v191, v191
	s_waitcnt vmcnt(12)
	ds_write_b128 v247, v[116:119]
	ds_write_b128 v247, v[120:123] offset:1024
	ds_write_b128 v247, v[124:127] offset:2048
	ds_write_b128 v247, v[128:131] offset:3072
	ds_read_b128 v[116:119], v248
	ds_read_b128 v[120:123], v249
	ds_read_b128 v[124:127], v250
	ds_read_b128 v[128:131], v251
	s_waitcnt vmcnt(8)
	ds_write_b128 v112, v[132:135]
	ds_write_b128 v112, v[136:139] offset:1024
	ds_write_b128 v112, v[140:143] offset:2048
	ds_write_b128 v112, v[144:147] offset:3072
	v_exp_f32_e32 v192, v192
	v_exp_f32_e32 v193, v193
	v_exp_f32_e32 v194, v194
	v_exp_f32_e32 v195, v195
	s_waitcnt lgkmcnt(4)
	v_mfma_f32_32x32x16_bf16 v[32:47], v[116:119], v[48:51], v[32:47]
	v_exp_f32_e32 v196, v196
	v_exp_f32_e32 v197, v197
	v_mfma_f32_32x32x16_bf16 v[32:47], v[120:123], v[52:55], v[32:47]
	v_exp_f32_e32 v198, v198
	v_exp_f32_e32 v199, v199
	v_mfma_f32_32x32x16_bf16 v[32:47], v[124:127], v[56:59], v[32:47]
	v_exp_f32_e32 v200, v200
	v_exp_f32_e32 v201, v201
	v_mfma_f32_32x32x16_bf16 v[32:47], v[128:131], v[60:63], v[32:47]
	v_exp_f32_e32 v202, v202
	v_exp_f32_e32 v203, v203
	s_add_i32 s90, s67, 640
	v_lshlrev_b32_e32 v84, 2, v107
	v_add_u32_e32 v84, s90, v84
	v_add_u32_e32 v85, 0, v84
	v_add_u32_e32 v86, 4, v84
	v_add_u32_e32 v87, 8, v84
	v_add_u32_e32 v88, 12, v84
	v_cmp_gt_u32_e64 s[30:31], s98, v85
	v_cmp_gt_u32_e64 s[36:37], s98, v86
	v_cmp_gt_u32_e64 s[78:79], s98, v87
	v_cmp_gt_u32_e64 s[50:51], s98, v88
	v_cndmask_b32_e64 v188, 0, v188, s[30:31]
	v_add_u32_e32 v85, 32, v84
	v_cmp_gt_u32_e64 s[30:31], s98, v85
	v_cndmask_b32_e64 v189, 0, v189, s[36:37]
	v_add_u32_e32 v86, 36, v84
	v_cmp_gt_u32_e64 s[36:37], s98, v86
	v_cndmask_b32_e64 v190, 0, v190, s[78:79]
	v_add_u32_e32 v87, 40, v84
	v_cmp_gt_u32_e64 s[78:79], s98, v87
	v_cndmask_b32_e64 v191, 0, v191, s[50:51]
	v_add_u32_e32 v88, 44, v84
	v_cmp_gt_u32_e64 s[50:51], s98, v88
	v_cndmask_b32_e64 v192, 0, v192, s[30:31]
	v_add_u32_e32 v85, 64, v84
	v_cmp_gt_u32_e64 s[30:31], s98, v85
	v_cndmask_b32_e64 v193, 0, v193, s[36:37]
	v_add_u32_e32 v86, 68, v84
	v_cmp_gt_u32_e64 s[36:37], s98, v86
	v_cndmask_b32_e64 v194, 0, v194, s[78:79]
	v_add_u32_e32 v87, 72, v84
	v_cmp_gt_u32_e64 s[78:79], s98, v87
	v_cndmask_b32_e64 v195, 0, v195, s[50:51]
	v_add_u32_e32 v88, 76, v84
	v_cmp_gt_u32_e64 s[50:51], s98, v88
	v_cndmask_b32_e64 v196, 0, v196, s[30:31]
	v_add_u32_e32 v85, 96, v84
	v_cmp_gt_u32_e64 s[30:31], s98, v85
	v_cndmask_b32_e64 v197, 0, v197, s[36:37]
	v_add_u32_e32 v86, 100, v84
	v_cmp_gt_u32_e64 s[36:37], s98, v86
	v_cndmask_b32_e64 v198, 0, v198, s[78:79]
	v_add_u32_e32 v87, 104, v84
	v_cmp_gt_u32_e64 s[78:79], s98, v87
	v_cndmask_b32_e64 v199, 0, v199, s[50:51]
	v_add_u32_e32 v88, 108, v84
	v_cmp_gt_u32_e64 s[50:51], s98, v88
	v_nop
	v_cndmask_b32_e64 v200, 0, v200, s[30:31]
	v_cndmask_b32_e64 v201, 0, v201, s[36:37]
	v_cndmask_b32_e64 v202, 0, v202, s[78:79]
	v_cndmask_b32_e64 v203, 0, v203, s[50:51]
	v_cvt_pk_bf16_f32 v64, v188, v189
	v_cvt_pk_bf16_f32 v65, v190, v191
	v_cvt_pk_bf16_f32 v66, v192, v193
	v_cvt_pk_bf16_f32 v67, v194, v195
	v_cvt_pk_bf16_f32 v68, v196, v197
	v_cvt_pk_bf16_f32 v69, v198, v199
	v_cvt_pk_bf16_f32 v70, v200, v201
	v_cvt_pk_bf16_f32 v71, v202, v203
	v_pk_add_f32 v[232:233], v[232:233], v[188:189]
	v_pk_add_f32 v[232:233], v[232:233], v[190:191]
	v_pk_add_f32 v[232:233], v[232:233], v[192:193]
	v_pk_add_f32 v[232:233], v[232:233], v[194:195]
	v_pk_add_f32 v[232:233], v[232:233], v[196:197]
	v_pk_add_f32 v[232:233], v[232:233], v[198:199]
	v_pk_add_f32 v[232:233], v[232:233], v[200:201]
	v_pk_add_f32 v[232:233], v[232:233], v[202:203]
	ds_read2_b32 v[188:189], v115 offset0:32 offset1:33
	ds_read2_b32 v[190:191], v115 offset0:34 offset1:35
	ds_read2_b32 v[192:193], v115 offset0:40 offset1:41
	ds_read2_b32 v[194:195], v115 offset0:42 offset1:43
	ds_read2_b32 v[196:197], v115 offset0:48 offset1:49
	ds_read2_b32 v[198:199], v115 offset0:50 offset1:51
	ds_read2_b32 v[200:201], v115 offset0:56 offset1:57
	ds_read2_b32 v[202:203], v115 offset0:58 offset1:59
	v_mfma_f32_32x32x16_bf16 v[0:15], v[64:67], v[72:75], v[0:15]
	v_mfma_f32_32x32x16_bf16 v[16:31], v[64:67], v[76:79], v[16:31]
	v_mfma_f32_32x32x16_bf16 v[0:15], v[68:71], v[220:223], v[0:15]
	v_mfma_f32_32x32x16_bf16 v[16:31], v[68:71], v[224:227], v[16:31]
	s_add_i32 s90, s67, 0
	v_add_u32_e32 v80, s90, v243
	v_add_u32_e32 v83, s90, v244
	v_add_u32_e32 v99, s90, v245
	v_add_u32_e32 v253, s90, v246
	v_add_u32_e32 v254, s90, v148
	v_add_u32_e32 v255, s90, v151
	v_med3_i32 v80, v80, 0, s99
	v_med3_i32 v83, v83, 0, s99
	v_med3_i32 v99, v99, 0, s99
	v_med3_i32 v253, v253, 0, s99
	v_med3_i32 v254, v254, 0, s99
	v_med3_i32 v255, v255, 0, s99
	v_mad_u32_u24 v80, v80, s100, v252
	v_mad_u32_u24 v83, v83, s100, v252
	v_mad_u32_u24 v99, v99, s100, v252
	v_mad_u32_u24 v253, v253, s100, v252
	v_mad_u32_u24 v254, v254, s100, v153
	v_mad_u32_u24 v255, v255, s100, v153
	global_load_dwordx4 v[116:119], v80, s[82:83]
	global_load_dwordx4 v[120:123], v83, s[82:83]
	global_load_dwordx4 v[124:127], v99, s[82:83]
	global_load_dwordx4 v[128:131], v253, s[82:83]
	global_load_dwordx4 v[132:135], v254, s[82:83] offset:768
	global_load_dwordx4 v[136:139], v255, s[82:83] offset:768
	global_load_dwordx4 v[140:143], v254, s[82:83] offset:832
	global_load_dwordx4 v[144:147], v255, s[82:83] offset:832
	ds_read_b64_tr_b16 v[72:73], v231
	ds_read_b64_tr_b16 v[74:75], v231 offset:512
	ds_read_b64_tr_b16 v[76:77], v231 offset:2048
	ds_read_b64_tr_b16 v[78:79], v231 offset:2560
	ds_read_b64_tr_b16 v[220:221], v231 offset:1024
	ds_read_b64_tr_b16 v[222:223], v231 offset:1536
	ds_read_b64_tr_b16 v[224:225], v231 offset:3072
	ds_read_b64_tr_b16 v[226:227], v231 offset:3584
	v_exp_f32_e32 v32, v32
	v_exp_f32_e32 v33, v33
	v_exp_f32_e32 v34, v34
	v_exp_f32_e32 v35, v35
	s_waitcnt vmcnt(12)
	ds_write_b128 v247, v[156:159]
	ds_write_b128 v247, v[160:163] offset:1024
	ds_write_b128 v247, v[164:167] offset:2048
	ds_write_b128 v247, v[168:171] offset:3072
	ds_read_b128 v[156:159], v248
	ds_read_b128 v[160:163], v249
	ds_read_b128 v[164:167], v250
	ds_read_b128 v[168:171], v251
	s_waitcnt vmcnt(8)
	ds_write_b128 v112, v[172:175]
	ds_write_b128 v112, v[176:179] offset:1024
	ds_write_b128 v112, v[180:183] offset:2048
	ds_write_b128 v112, v[184:187] offset:3072
	v_exp_f32_e32 v36, v36
	v_exp_f32_e32 v37, v37
	v_exp_f32_e32 v38, v38
	v_exp_f32_e32 v39, v39
	s_waitcnt lgkmcnt(4)
	v_mfma_f32_32x32x16_bf16 v[188:203], v[156:159], v[48:51], v[188:203]
	v_exp_f32_e32 v40, v40
	v_exp_f32_e32 v41, v41
	v_mfma_f32_32x32x16_bf16 v[188:203], v[160:163], v[52:55], v[188:203]
	v_exp_f32_e32 v42, v42
	v_exp_f32_e32 v43, v43
	v_mfma_f32_32x32x16_bf16 v[188:203], v[164:167], v[56:59], v[188:203]
	v_exp_f32_e32 v44, v44
	v_exp_f32_e32 v45, v45
	v_mfma_f32_32x32x16_bf16 v[188:203], v[168:171], v[60:63], v[188:203]
	v_exp_f32_e32 v46, v46
	v_exp_f32_e32 v47, v47
	s_add_i32 s90, s67, -1024
	v_lshlrev_b32_e32 v84, 4, v107
	v_add_u32_e32 v84, s90, v84
	v_add_u32_e32 v85, 0, v84
	v_add_u32_e32 v86, 16, v84
	v_add_u32_e32 v87, 32, v84
	v_add_u32_e32 v88, 48, v84
	v_cmp_gt_u32_e64 s[30:31], s98, v85
	v_cmp_gt_u32_e64 s[36:37], s98, v86
	v_cmp_gt_u32_e64 s[78:79], s98, v87
	v_cmp_gt_u32_e64 s[50:51], s98, v88
	v_cndmask_b32_e64 v32, 0, v32, s[30:31]
	v_add_u32_e32 v85, 128, v84
	v_cmp_gt_u32_e64 s[30:31], s98, v85
	v_cndmask_b32_e64 v33, 0, v33, s[36:37]
	v_add_u32_e32 v86, 144, v84
	v_cmp_gt_u32_e64 s[36:37], s98, v86
	v_cndmask_b32_e64 v34, 0, v34, s[78:79]
	v_add_u32_e32 v87, 160, v84
	v_cmp_gt_u32_e64 s[78:79], s98, v87
	v_cndmask_b32_e64 v35, 0, v35, s[50:51]
	v_add_u32_e32 v88, 176, v84
	v_cmp_gt_u32_e64 s[50:51], s98, v88
	v_cndmask_b32_e64 v36, 0, v36, s[30:31]
	v_add_u32_e32 v85, 256, v84
	v_cmp_gt_u32_e64 s[30:31], s98, v85
	v_cndmask_b32_e64 v37, 0, v37, s[36:37]
	v_add_u32_e32 v86, 272, v84
	v_cmp_gt_u32_e64 s[36:37], s98, v86
	v_cndmask_b32_e64 v38, 0, v38, s[78:79]
	v_add_u32_e32 v87, 288, v84
	v_cmp_gt_u32_e64 s[78:79], s98, v87
	v_cndmask_b32_e64 v39, 0, v39, s[50:51]
	v_add_u32_e32 v88, 304, v84
	v_cmp_gt_u32_e64 s[50:51], s98, v88
	v_cndmask_b32_e64 v40, 0, v40, s[30:31]
	v_add_u32_e32 v85, 384, v84
	v_cmp_gt_u32_e64 s[30:31], s98, v85
	v_cndmask_b32_e64 v41, 0, v41, s[36:37]
	v_add_u32_e32 v86, 400, v84
	v_cmp_gt_u32_e64 s[36:37], s98, v86
	v_cndmask_b32_e64 v42, 0, v42, s[78:79]
	v_add_u32_e32 v87, 416, v84
	v_cmp_gt_u32_e64 s[78:79], s98, v87
	v_cndmask_b32_e64 v43, 0, v43, s[50:51]
	v_add_u32_e32 v88, 432, v84
	v_cmp_gt_u32_e64 s[50:51], s98, v88
	v_nop
	v_cndmask_b32_e64 v44, 0, v44, s[30:31]
	v_cndmask_b32_e64 v45, 0, v45, s[36:37]
	v_cndmask_b32_e64 v46, 0, v46, s[78:79]
	v_cndmask_b32_e64 v47, 0, v47, s[50:51]
	v_cvt_pk_bf16_f32 v64, v32, v33
	v_cvt_pk_bf16_f32 v65, v34, v35
	v_cvt_pk_bf16_f32 v66, v36, v37
	v_cvt_pk_bf16_f32 v67, v38, v39
	v_cvt_pk_bf16_f32 v68, v40, v41
	v_cvt_pk_bf16_f32 v69, v42, v43
	v_cvt_pk_bf16_f32 v70, v44, v45
	v_cvt_pk_bf16_f32 v71, v46, v47
	v_pk_add_f32 v[232:233], v[232:233], v[32:33]
	v_pk_add_f32 v[232:233], v[232:233], v[34:35]
	v_pk_add_f32 v[232:233], v[232:233], v[36:37]
	v_pk_add_f32 v[232:233], v[232:233], v[38:39]
	v_pk_add_f32 v[232:233], v[232:233], v[40:41]
	v_pk_add_f32 v[232:233], v[232:233], v[42:43]
	v_pk_add_f32 v[232:233], v[232:233], v[44:45]
	v_pk_add_f32 v[232:233], v[232:233], v[46:47]
	ds_read2_b32 v[32:33], v115 offset0:64 offset1:65
	ds_read2_b32 v[34:35], v115 offset0:66 offset1:67
	ds_read2_b32 v[36:37], v115 offset0:72 offset1:73
	ds_read2_b32 v[38:39], v115 offset0:74 offset1:75
	ds_read2_b32 v[40:41], v115 offset0:80 offset1:81
	ds_read2_b32 v[42:43], v115 offset0:82 offset1:83
	ds_read2_b32 v[44:45], v115 offset0:88 offset1:89
	ds_read2_b32 v[46:47], v115 offset0:90 offset1:91
	v_mfma_f32_32x32x16_bf16 v[0:15], v[64:67], v[72:75], v[0:15]
	v_mfma_f32_32x32x16_bf16 v[16:31], v[64:67], v[76:79], v[16:31]
	v_mfma_f32_32x32x16_bf16 v[0:15], v[68:71], v[220:223], v[0:15]
	v_mfma_f32_32x32x16_bf16 v[16:31], v[68:71], v[224:227], v[16:31]
	s_add_i32 s90, s67, 512
	v_add_u32_e32 v80, s90, v243
	v_add_u32_e32 v83, s90, v244
	v_add_u32_e32 v99, s90, v245
	v_add_u32_e32 v253, s90, v246
	v_add_u32_e32 v254, s90, v148
	v_add_u32_e32 v255, s90, v151
	v_med3_i32 v80, v80, 0, s99
	v_med3_i32 v83, v83, 0, s99
	v_med3_i32 v99, v99, 0, s99
	v_med3_i32 v253, v253, 0, s99
	v_med3_i32 v254, v254, 0, s99
	v_med3_i32 v255, v255, 0, s99
	v_mad_u32_u24 v80, v80, s100, v252
	v_mad_u32_u24 v83, v83, s100, v252
	v_mad_u32_u24 v99, v99, s100, v252
	v_mad_u32_u24 v253, v253, s100, v252
	v_mad_u32_u24 v254, v254, s100, v153
	v_mad_u32_u24 v255, v255, s100, v153
	global_load_dwordx4 v[156:159], v80, s[82:83]
	global_load_dwordx4 v[160:163], v83, s[82:83]
	global_load_dwordx4 v[164:167], v99, s[82:83]
	global_load_dwordx4 v[168:171], v253, s[82:83]
	global_load_dwordx4 v[172:175], v254, s[82:83] offset:768
	global_load_dwordx4 v[176:179], v255, s[82:83] offset:768
	global_load_dwordx4 v[180:183], v254, s[82:83] offset:832
	global_load_dwordx4 v[184:187], v255, s[82:83] offset:832
	ds_read_b64_tr_b16 v[72:73], v231
	ds_read_b64_tr_b16 v[74:75], v231 offset:512
	ds_read_b64_tr_b16 v[76:77], v231 offset:2048
	ds_read_b64_tr_b16 v[78:79], v231 offset:2560
	ds_read_b64_tr_b16 v[220:221], v231 offset:1024
	ds_read_b64_tr_b16 v[222:223], v231 offset:1536
	ds_read_b64_tr_b16 v[224:225], v231 offset:3072
	ds_read_b64_tr_b16 v[226:227], v231 offset:3584
	v_exp_f32_e32 v188, v188
	v_exp_f32_e32 v189, v189
	v_exp_f32_e32 v190, v190
	v_exp_f32_e32 v191, v191
	s_waitcnt vmcnt(12)
	ds_write_b128 v247, v[116:119]
	ds_write_b128 v247, v[120:123] offset:1024
	ds_write_b128 v247, v[124:127] offset:2048
	ds_write_b128 v247, v[128:131] offset:3072
	ds_read_b128 v[116:119], v248
	ds_read_b128 v[120:123], v249
	ds_read_b128 v[124:127], v250
	ds_read_b128 v[128:131], v251
	s_waitcnt vmcnt(8)
	ds_write_b128 v112, v[132:135]
	ds_write_b128 v112, v[136:139] offset:1024
	ds_write_b128 v112, v[140:143] offset:2048
	ds_write_b128 v112, v[144:147] offset:3072
	v_exp_f32_e32 v192, v192
	v_exp_f32_e32 v193, v193
	v_exp_f32_e32 v194, v194
	v_exp_f32_e32 v195, v195
	s_waitcnt lgkmcnt(4)
	v_mfma_f32_32x32x16_bf16 v[32:47], v[116:119], v[48:51], v[32:47]
	v_exp_f32_e32 v196, v196
	v_exp_f32_e32 v197, v197
	v_mfma_f32_32x32x16_bf16 v[32:47], v[120:123], v[52:55], v[32:47]
	v_exp_f32_e32 v198, v198
	v_exp_f32_e32 v199, v199
	v_mfma_f32_32x32x16_bf16 v[32:47], v[124:127], v[56:59], v[32:47]
	v_exp_f32_e32 v200, v200
	v_exp_f32_e32 v201, v201
	v_mfma_f32_32x32x16_bf16 v[32:47], v[128:131], v[60:63], v[32:47]
	v_exp_f32_e32 v202, v202
	v_exp_f32_e32 v203, v203
	s_add_i32 s90, s67, -512
	v_lshlrev_b32_e32 v84, 4, v107
	v_add_u32_e32 v84, s90, v84
	v_add_u32_e32 v85, 0, v84
	v_add_u32_e32 v86, 16, v84
	v_add_u32_e32 v87, 32, v84
	v_add_u32_e32 v88, 48, v84
	v_cmp_gt_u32_e64 s[30:31], s98, v85
	v_cmp_gt_u32_e64 s[36:37], s98, v86
	v_cmp_gt_u32_e64 s[78:79], s98, v87
	v_cmp_gt_u32_e64 s[50:51], s98, v88
	v_cndmask_b32_e64 v188, 0, v188, s[30:31]
	v_add_u32_e32 v85, 128, v84
	v_cmp_gt_u32_e64 s[30:31], s98, v85
	v_cndmask_b32_e64 v189, 0, v189, s[36:37]
	v_add_u32_e32 v86, 144, v84
	v_cmp_gt_u32_e64 s[36:37], s98, v86
	v_cndmask_b32_e64 v190, 0, v190, s[78:79]
	v_add_u32_e32 v87, 160, v84
	v_cmp_gt_u32_e64 s[78:79], s98, v87
	v_cndmask_b32_e64 v191, 0, v191, s[50:51]
	v_add_u32_e32 v88, 176, v84
	v_cmp_gt_u32_e64 s[50:51], s98, v88
	v_cndmask_b32_e64 v192, 0, v192, s[30:31]
	v_add_u32_e32 v85, 256, v84
	v_cmp_gt_u32_e64 s[30:31], s98, v85
	v_cndmask_b32_e64 v193, 0, v193, s[36:37]
	v_add_u32_e32 v86, 272, v84
	v_cmp_gt_u32_e64 s[36:37], s98, v86
	v_cndmask_b32_e64 v194, 0, v194, s[78:79]
	v_add_u32_e32 v87, 288, v84
	v_cmp_gt_u32_e64 s[78:79], s98, v87
	v_cndmask_b32_e64 v195, 0, v195, s[50:51]
	v_add_u32_e32 v88, 304, v84
	v_cmp_gt_u32_e64 s[50:51], s98, v88
	v_cndmask_b32_e64 v196, 0, v196, s[30:31]
	v_add_u32_e32 v85, 384, v84
	v_cmp_gt_u32_e64 s[30:31], s98, v85
	v_cndmask_b32_e64 v197, 0, v197, s[36:37]
	v_add_u32_e32 v86, 400, v84
	v_cmp_gt_u32_e64 s[36:37], s98, v86
	v_cndmask_b32_e64 v198, 0, v198, s[78:79]
	v_add_u32_e32 v87, 416, v84
	v_cmp_gt_u32_e64 s[78:79], s98, v87
	v_cndmask_b32_e64 v199, 0, v199, s[50:51]
	v_add_u32_e32 v88, 432, v84
	v_cmp_gt_u32_e64 s[50:51], s98, v88
	v_nop
	v_cndmask_b32_e64 v200, 0, v200, s[30:31]
	v_cndmask_b32_e64 v201, 0, v201, s[36:37]
	v_cndmask_b32_e64 v202, 0, v202, s[78:79]
	v_cndmask_b32_e64 v203, 0, v203, s[50:51]
	v_cvt_pk_bf16_f32 v64, v188, v189
	v_cvt_pk_bf16_f32 v65, v190, v191
	v_cvt_pk_bf16_f32 v66, v192, v193
	v_cvt_pk_bf16_f32 v67, v194, v195
	v_cvt_pk_bf16_f32 v68, v196, v197
	v_cvt_pk_bf16_f32 v69, v198, v199
	v_cvt_pk_bf16_f32 v70, v200, v201
	v_cvt_pk_bf16_f32 v71, v202, v203
	v_pk_add_f32 v[232:233], v[232:233], v[188:189]
	v_pk_add_f32 v[232:233], v[232:233], v[190:191]
	v_pk_add_f32 v[232:233], v[232:233], v[192:193]
	v_pk_add_f32 v[232:233], v[232:233], v[194:195]
	v_pk_add_f32 v[232:233], v[232:233], v[196:197]
	v_pk_add_f32 v[232:233], v[232:233], v[198:199]
	v_pk_add_f32 v[232:233], v[232:233], v[200:201]
	v_pk_add_f32 v[232:233], v[232:233], v[202:203]
	ds_read2_b32 v[188:189], v115 offset0:96 offset1:97
	ds_read2_b32 v[190:191], v115 offset0:98 offset1:99
	ds_read2_b32 v[192:193], v115 offset0:104 offset1:105
	ds_read2_b32 v[194:195], v115 offset0:106 offset1:107
	ds_read2_b32 v[196:197], v115 offset0:112 offset1:113
	ds_read2_b32 v[198:199], v115 offset0:114 offset1:115
	ds_read2_b32 v[200:201], v115 offset0:120 offset1:121
	ds_read2_b32 v[202:203], v115 offset0:122 offset1:123
	v_mfma_f32_32x32x16_bf16 v[0:15], v[64:67], v[72:75], v[0:15]
	v_mfma_f32_32x32x16_bf16 v[16:31], v[64:67], v[76:79], v[16:31]
	v_mfma_f32_32x32x16_bf16 v[0:15], v[68:71], v[220:223], v[0:15]
	v_mfma_f32_32x32x16_bf16 v[16:31], v[68:71], v[224:227], v[16:31]
	s_add_i32 s90, s67, 1024
	v_add_u32_e32 v80, s90, v243
	v_add_u32_e32 v83, s90, v244
	v_add_u32_e32 v99, s90, v245
	v_add_u32_e32 v253, s90, v246
	v_add_u32_e32 v254, s90, v148
	v_add_u32_e32 v255, s90, v151
	v_med3_i32 v80, v80, 0, s99
	v_med3_i32 v83, v83, 0, s99
	v_med3_i32 v99, v99, 0, s99
	v_med3_i32 v253, v253, 0, s99
	v_med3_i32 v254, v254, 0, s99
	v_med3_i32 v255, v255, 0, s99
	v_mad_u32_u24 v80, v80, s100, v252
	v_mad_u32_u24 v83, v83, s100, v252
	v_mad_u32_u24 v99, v99, s100, v252
	v_mad_u32_u24 v253, v253, s100, v252
	v_mad_u32_u24 v254, v254, s100, v153
	v_mad_u32_u24 v255, v255, s100, v153
	global_load_dwordx4 v[116:119], v80, s[82:83]
	global_load_dwordx4 v[120:123], v83, s[82:83]
	global_load_dwordx4 v[124:127], v99, s[82:83]
	global_load_dwordx4 v[128:131], v253, s[82:83]
	global_load_dwordx4 v[132:135], v254, s[82:83] offset:768
	global_load_dwordx4 v[136:139], v255, s[82:83] offset:768
	global_load_dwordx4 v[140:143], v254, s[82:83] offset:832
	global_load_dwordx4 v[144:147], v255, s[82:83] offset:832
	ds_read_b64_tr_b16 v[72:73], v231
	ds_read_b64_tr_b16 v[74:75], v231 offset:512
	ds_read_b64_tr_b16 v[76:77], v231 offset:2048
	ds_read_b64_tr_b16 v[78:79], v231 offset:2560
	ds_read_b64_tr_b16 v[220:221], v231 offset:1024
	ds_read_b64_tr_b16 v[222:223], v231 offset:1536
	ds_read_b64_tr_b16 v[224:225], v231 offset:3072
	ds_read_b64_tr_b16 v[226:227], v231 offset:3584
	v_exp_f32_e32 v32, v32
	v_exp_f32_e32 v33, v33
	v_exp_f32_e32 v34, v34
	v_exp_f32_e32 v35, v35
	s_waitcnt vmcnt(12)
	ds_write_b128 v247, v[156:159]
	ds_write_b128 v247, v[160:163] offset:1024
	ds_write_b128 v247, v[164:167] offset:2048
	ds_write_b128 v247, v[168:171] offset:3072
	ds_read_b128 v[156:159], v248
	ds_read_b128 v[160:163], v249
	ds_read_b128 v[164:167], v250
	ds_read_b128 v[168:171], v251
	s_waitcnt vmcnt(8)
	ds_write_b128 v112, v[172:175]
	ds_write_b128 v112, v[176:179] offset:1024
	ds_write_b128 v112, v[180:183] offset:2048
	ds_write_b128 v112, v[184:187] offset:3072
	v_exp_f32_e32 v36, v36
	v_exp_f32_e32 v37, v37
	v_exp_f32_e32 v38, v38
	v_exp_f32_e32 v39, v39
	s_waitcnt lgkmcnt(4)
	v_mfma_f32_32x32x16_bf16 v[188:203], v[156:159], v[48:51], v[188:203]
	v_exp_f32_e32 v40, v40
	v_exp_f32_e32 v41, v41
	v_mfma_f32_32x32x16_bf16 v[188:203], v[160:163], v[52:55], v[188:203]
	v_exp_f32_e32 v42, v42
	v_exp_f32_e32 v43, v43
	v_mfma_f32_32x32x16_bf16 v[188:203], v[164:167], v[56:59], v[188:203]
	v_exp_f32_e32 v44, v44
	v_exp_f32_e32 v45, v45
	v_mfma_f32_32x32x16_bf16 v[188:203], v[168:171], v[60:63], v[188:203]
	v_exp_f32_e32 v46, v46
	v_exp_f32_e32 v47, v47
	s_add_i32 s90, s67, 0
	v_lshlrev_b32_e32 v84, 4, v107
	v_add_u32_e32 v84, s90, v84
	v_add_u32_e32 v85, 0, v84
	v_add_u32_e32 v86, 16, v84
	v_add_u32_e32 v87, 32, v84
	v_add_u32_e32 v88, 48, v84
	v_cmp_gt_u32_e64 s[30:31], s98, v85
	v_cmp_gt_u32_e64 s[36:37], s98, v86
	v_cmp_gt_u32_e64 s[78:79], s98, v87
	v_cmp_gt_u32_e64 s[50:51], s98, v88
	v_cndmask_b32_e64 v32, 0, v32, s[30:31]
	v_add_u32_e32 v85, 128, v84
	v_cmp_gt_u32_e64 s[30:31], s98, v85
	v_cndmask_b32_e64 v33, 0, v33, s[36:37]
	v_add_u32_e32 v86, 144, v84
	v_cmp_gt_u32_e64 s[36:37], s98, v86
	v_cndmask_b32_e64 v34, 0, v34, s[78:79]
	v_add_u32_e32 v87, 160, v84
	v_cmp_gt_u32_e64 s[78:79], s98, v87
	v_cndmask_b32_e64 v35, 0, v35, s[50:51]
	v_add_u32_e32 v88, 176, v84
	v_cmp_gt_u32_e64 s[50:51], s98, v88
	v_cndmask_b32_e64 v36, 0, v36, s[30:31]
	v_add_u32_e32 v85, 256, v84
	v_cmp_gt_u32_e64 s[30:31], s98, v85
	v_cndmask_b32_e64 v37, 0, v37, s[36:37]
	v_add_u32_e32 v86, 272, v84
	v_cmp_gt_u32_e64 s[36:37], s98, v86
	v_cndmask_b32_e64 v38, 0, v38, s[78:79]
	v_add_u32_e32 v87, 288, v84
	v_cmp_gt_u32_e64 s[78:79], s98, v87
	v_cndmask_b32_e64 v39, 0, v39, s[50:51]
	v_add_u32_e32 v88, 304, v84
	v_cmp_gt_u32_e64 s[50:51], s98, v88
	v_cndmask_b32_e64 v40, 0, v40, s[30:31]
	v_add_u32_e32 v85, 384, v84
	v_cmp_gt_u32_e64 s[30:31], s98, v85
	v_cndmask_b32_e64 v41, 0, v41, s[36:37]
	v_add_u32_e32 v86, 400, v84
	v_cmp_gt_u32_e64 s[36:37], s98, v86
	v_cndmask_b32_e64 v42, 0, v42, s[78:79]
	v_add_u32_e32 v87, 416, v84
	v_cmp_gt_u32_e64 s[78:79], s98, v87
	v_cndmask_b32_e64 v43, 0, v43, s[50:51]
	v_add_u32_e32 v88, 432, v84
	v_cmp_gt_u32_e64 s[50:51], s98, v88
	v_nop
	v_cndmask_b32_e64 v44, 0, v44, s[30:31]
	v_cndmask_b32_e64 v45, 0, v45, s[36:37]
	v_cndmask_b32_e64 v46, 0, v46, s[78:79]
	v_cndmask_b32_e64 v47, 0, v47, s[50:51]
	v_cvt_pk_bf16_f32 v64, v32, v33
	v_cvt_pk_bf16_f32 v65, v34, v35
	v_cvt_pk_bf16_f32 v66, v36, v37
	v_cvt_pk_bf16_f32 v67, v38, v39
	v_cvt_pk_bf16_f32 v68, v40, v41
	v_cvt_pk_bf16_f32 v69, v42, v43
	v_cvt_pk_bf16_f32 v70, v44, v45
	v_cvt_pk_bf16_f32 v71, v46, v47
	v_pk_add_f32 v[232:233], v[232:233], v[32:33]
	v_pk_add_f32 v[232:233], v[232:233], v[34:35]
	v_pk_add_f32 v[232:233], v[232:233], v[36:37]
	v_pk_add_f32 v[232:233], v[232:233], v[38:39]
	v_pk_add_f32 v[232:233], v[232:233], v[40:41]
	v_pk_add_f32 v[232:233], v[232:233], v[42:43]
	v_pk_add_f32 v[232:233], v[232:233], v[44:45]
	v_pk_add_f32 v[232:233], v[232:233], v[46:47]
	ds_read2_b32 v[32:33], v115 offset0:128 offset1:129
	ds_read2_b32 v[34:35], v115 offset0:130 offset1:131
	ds_read2_b32 v[36:37], v115 offset0:136 offset1:137
	ds_read2_b32 v[38:39], v115 offset0:138 offset1:139
	ds_read2_b32 v[40:41], v115 offset0:144 offset1:145
	ds_read2_b32 v[42:43], v115 offset0:146 offset1:147
	ds_read2_b32 v[44:45], v115 offset0:152 offset1:153
	ds_read2_b32 v[46:47], v115 offset0:154 offset1:155
	v_mfma_f32_32x32x16_bf16 v[0:15], v[64:67], v[72:75], v[0:15]
	v_mfma_f32_32x32x16_bf16 v[16:31], v[64:67], v[76:79], v[16:31]
	v_mfma_f32_32x32x16_bf16 v[0:15], v[68:71], v[220:223], v[0:15]
	v_mfma_f32_32x32x16_bf16 v[16:31], v[68:71], v[224:227], v[16:31]
	ds_read_b64_tr_b16 v[72:73], v231
	ds_read_b64_tr_b16 v[74:75], v231 offset:512
	ds_read_b64_tr_b16 v[76:77], v231 offset:2048
	ds_read_b64_tr_b16 v[78:79], v231 offset:2560
	ds_read_b64_tr_b16 v[220:221], v231 offset:1024
	ds_read_b64_tr_b16 v[222:223], v231 offset:1536
	ds_read_b64_tr_b16 v[224:225], v231 offset:3072
	ds_read_b64_tr_b16 v[226:227], v231 offset:3584
	v_exp_f32_e32 v188, v188
	v_exp_f32_e32 v189, v189
	v_exp_f32_e32 v190, v190
	v_exp_f32_e32 v191, v191
	s_waitcnt vmcnt(4)
	ds_write_b128 v247, v[116:119]
	ds_write_b128 v247, v[120:123] offset:1024
	ds_write_b128 v247, v[124:127] offset:2048
	ds_write_b128 v247, v[128:131] offset:3072
	ds_read_b128 v[116:119], v248
	ds_read_b128 v[120:123], v249
	ds_read_b128 v[124:127], v250
	ds_read_b128 v[128:131], v251
	s_waitcnt vmcnt(0)
	ds_write_b128 v112, v[132:135]
	ds_write_b128 v112, v[136:139] offset:1024
	ds_write_b128 v112, v[140:143] offset:2048
	ds_write_b128 v112, v[144:147] offset:3072
	v_exp_f32_e32 v192, v192
	v_exp_f32_e32 v193, v193
	v_exp_f32_e32 v194, v194
	v_exp_f32_e32 v195, v195
	s_waitcnt lgkmcnt(4)
	v_mfma_f32_32x32x16_bf16 v[32:47], v[116:119], v[48:51], v[32:47]
	v_exp_f32_e32 v196, v196
	v_exp_f32_e32 v197, v197
	v_mfma_f32_32x32x16_bf16 v[32:47], v[120:123], v[52:55], v[32:47]
	v_exp_f32_e32 v198, v198
	v_exp_f32_e32 v199, v199
	v_mfma_f32_32x32x16_bf16 v[32:47], v[124:127], v[56:59], v[32:47]
	v_exp_f32_e32 v200, v200
	v_exp_f32_e32 v201, v201
	v_mfma_f32_32x32x16_bf16 v[32:47], v[128:131], v[60:63], v[32:47]
	v_exp_f32_e32 v202, v202
	v_exp_f32_e32 v203, v203
	s_add_i32 s90, s67, 512
	v_lshlrev_b32_e32 v84, 4, v107
	v_add_u32_e32 v84, s90, v84
	v_add_u32_e32 v85, 0, v84
	v_add_u32_e32 v86, 16, v84
	v_add_u32_e32 v87, 32, v84
	v_add_u32_e32 v88, 48, v84
	v_cmp_gt_u32_e64 s[30:31], s98, v85
	v_cmp_gt_u32_e64 s[36:37], s98, v86
	v_cmp_gt_u32_e64 s[78:79], s98, v87
	v_cmp_gt_u32_e64 s[50:51], s98, v88
	v_cndmask_b32_e64 v188, 0, v188, s[30:31]
	v_add_u32_e32 v85, 128, v84
	v_cmp_gt_u32_e64 s[30:31], s98, v85
	v_cndmask_b32_e64 v189, 0, v189, s[36:37]
	v_add_u32_e32 v86, 144, v84
	v_cmp_gt_u32_e64 s[36:37], s98, v86
	v_cndmask_b32_e64 v190, 0, v190, s[78:79]
	v_add_u32_e32 v87, 160, v84
	v_cmp_gt_u32_e64 s[78:79], s98, v87
	v_cndmask_b32_e64 v191, 0, v191, s[50:51]
	v_add_u32_e32 v88, 176, v84
	v_cmp_gt_u32_e64 s[50:51], s98, v88
	v_cndmask_b32_e64 v192, 0, v192, s[30:31]
	v_add_u32_e32 v85, 256, v84
	v_cmp_gt_u32_e64 s[30:31], s98, v85
	v_cndmask_b32_e64 v193, 0, v193, s[36:37]
	v_add_u32_e32 v86, 272, v84
	v_cmp_gt_u32_e64 s[36:37], s98, v86
	v_cndmask_b32_e64 v194, 0, v194, s[78:79]
	v_add_u32_e32 v87, 288, v84
	v_cmp_gt_u32_e64 s[78:79], s98, v87
	v_cndmask_b32_e64 v195, 0, v195, s[50:51]
	v_add_u32_e32 v88, 304, v84
	v_cmp_gt_u32_e64 s[50:51], s98, v88
	v_cndmask_b32_e64 v196, 0, v196, s[30:31]
	v_add_u32_e32 v85, 384, v84
	v_cmp_gt_u32_e64 s[30:31], s98, v85
	v_cndmask_b32_e64 v197, 0, v197, s[36:37]
	v_add_u32_e32 v86, 400, v84
	v_cmp_gt_u32_e64 s[36:37], s98, v86
	v_cndmask_b32_e64 v198, 0, v198, s[78:79]
	v_add_u32_e32 v87, 416, v84
	v_cmp_gt_u32_e64 s[78:79], s98, v87
	v_cndmask_b32_e64 v199, 0, v199, s[50:51]
	v_add_u32_e32 v88, 432, v84
	v_cmp_gt_u32_e64 s[50:51], s98, v88
	v_nop
	v_cndmask_b32_e64 v200, 0, v200, s[30:31]
	v_cndmask_b32_e64 v201, 0, v201, s[36:37]
	v_cndmask_b32_e64 v202, 0, v202, s[78:79]
	v_cndmask_b32_e64 v203, 0, v203, s[50:51]
	v_cvt_pk_bf16_f32 v64, v188, v189
	v_cvt_pk_bf16_f32 v65, v190, v191
	v_cvt_pk_bf16_f32 v66, v192, v193
	v_cvt_pk_bf16_f32 v67, v194, v195
	v_cvt_pk_bf16_f32 v68, v196, v197
	v_cvt_pk_bf16_f32 v69, v198, v199
	v_cvt_pk_bf16_f32 v70, v200, v201
	v_cvt_pk_bf16_f32 v71, v202, v203
	v_pk_add_f32 v[232:233], v[232:233], v[188:189]
	v_pk_add_f32 v[232:233], v[232:233], v[190:191]
	v_pk_add_f32 v[232:233], v[232:233], v[192:193]
	v_pk_add_f32 v[232:233], v[232:233], v[194:195]
	v_pk_add_f32 v[232:233], v[232:233], v[196:197]
	v_pk_add_f32 v[232:233], v[232:233], v[198:199]
	v_pk_add_f32 v[232:233], v[232:233], v[200:201]
	v_pk_add_f32 v[232:233], v[232:233], v[202:203]
	v_mfma_f32_32x32x16_bf16 v[0:15], v[64:67], v[72:75], v[0:15]
	v_mfma_f32_32x32x16_bf16 v[16:31], v[64:67], v[76:79], v[16:31]
	v_mfma_f32_32x32x16_bf16 v[0:15], v[68:71], v[220:223], v[0:15]
	v_mfma_f32_32x32x16_bf16 v[16:31], v[68:71], v[224:227], v[16:31]
	ds_read_b64_tr_b16 v[72:73], v231
	ds_read_b64_tr_b16 v[74:75], v231 offset:512
	ds_read_b64_tr_b16 v[76:77], v231 offset:2048
	ds_read_b64_tr_b16 v[78:79], v231 offset:2560
	ds_read_b64_tr_b16 v[220:221], v231 offset:1024
	ds_read_b64_tr_b16 v[222:223], v231 offset:1536
	ds_read_b64_tr_b16 v[224:225], v231 offset:3072
	ds_read_b64_tr_b16 v[226:227], v231 offset:3584
	s_waitcnt lgkmcnt(0)
	v_exp_f32_e32 v32, v32
	v_exp_f32_e32 v33, v33
	v_exp_f32_e32 v34, v34
	v_exp_f32_e32 v35, v35
	v_exp_f32_e32 v36, v36
	v_exp_f32_e32 v37, v37
	v_exp_f32_e32 v38, v38
	v_exp_f32_e32 v39, v39
	v_exp_f32_e32 v40, v40
	v_exp_f32_e32 v41, v41
	v_exp_f32_e32 v42, v42
	v_exp_f32_e32 v43, v43
	v_exp_f32_e32 v44, v44
	v_exp_f32_e32 v45, v45
	v_exp_f32_e32 v46, v46
	v_exp_f32_e32 v47, v47
	s_add_i32 s90, s67, 1024
	v_lshlrev_b32_e32 v84, 4, v107
	v_add_u32_e32 v84, s90, v84
	v_add_u32_e32 v85, 0, v84
	v_add_u32_e32 v86, 16, v84
	v_add_u32_e32 v87, 32, v84
	v_add_u32_e32 v88, 48, v84
	v_cmp_gt_u32_e64 s[30:31], s98, v85
	v_cmp_gt_u32_e64 s[36:37], s98, v86
	v_cmp_gt_u32_e64 s[78:79], s98, v87
	v_cmp_gt_u32_e64 s[50:51], s98, v88
	v_cndmask_b32_e64 v32, 0, v32, s[30:31]
	v_add_u32_e32 v85, 128, v84
	v_cmp_gt_u32_e64 s[30:31], s98, v85
	v_cndmask_b32_e64 v33, 0, v33, s[36:37]
	v_add_u32_e32 v86, 144, v84
	v_cmp_gt_u32_e64 s[36:37], s98, v86
	v_cndmask_b32_e64 v34, 0, v34, s[78:79]
	v_add_u32_e32 v87, 160, v84
	v_cmp_gt_u32_e64 s[78:79], s98, v87
	v_cndmask_b32_e64 v35, 0, v35, s[50:51]
	v_add_u32_e32 v88, 176, v84
	v_cmp_gt_u32_e64 s[50:51], s98, v88
	v_cndmask_b32_e64 v36, 0, v36, s[30:31]
	v_add_u32_e32 v85, 256, v84
	v_cmp_gt_u32_e64 s[30:31], s98, v85
	v_cndmask_b32_e64 v37, 0, v37, s[36:37]
	v_add_u32_e32 v86, 272, v84
	v_cmp_gt_u32_e64 s[36:37], s98, v86
	v_cndmask_b32_e64 v38, 0, v38, s[78:79]
	v_add_u32_e32 v87, 288, v84
	v_cmp_gt_u32_e64 s[78:79], s98, v87
	v_cndmask_b32_e64 v39, 0, v39, s[50:51]
	v_add_u32_e32 v88, 304, v84
	v_cmp_gt_u32_e64 s[50:51], s98, v88
	v_cndmask_b32_e64 v40, 0, v40, s[30:31]
	v_add_u32_e32 v85, 384, v84
	v_cmp_gt_u32_e64 s[30:31], s98, v85
	v_cndmask_b32_e64 v41, 0, v41, s[36:37]
	v_add_u32_e32 v86, 400, v84
	v_cmp_gt_u32_e64 s[36:37], s98, v86
	v_cndmask_b32_e64 v42, 0, v42, s[78:79]
	v_add_u32_e32 v87, 416, v84
	v_cmp_gt_u32_e64 s[78:79], s98, v87
	v_cndmask_b32_e64 v43, 0, v43, s[50:51]
	v_add_u32_e32 v88, 432, v84
	v_cmp_gt_u32_e64 s[50:51], s98, v88
	v_nop
	v_cndmask_b32_e64 v44, 0, v44, s[30:31]
	v_cndmask_b32_e64 v45, 0, v45, s[36:37]
	v_cndmask_b32_e64 v46, 0, v46, s[78:79]
	v_cndmask_b32_e64 v47, 0, v47, s[50:51]
	v_cvt_pk_bf16_f32 v64, v32, v33
	v_cvt_pk_bf16_f32 v65, v34, v35
	v_cvt_pk_bf16_f32 v66, v36, v37
	v_cvt_pk_bf16_f32 v67, v38, v39
	v_cvt_pk_bf16_f32 v68, v40, v41
	v_cvt_pk_bf16_f32 v69, v42, v43
	v_cvt_pk_bf16_f32 v70, v44, v45
	v_cvt_pk_bf16_f32 v71, v46, v47
	v_pk_add_f32 v[232:233], v[232:233], v[32:33]
	v_pk_add_f32 v[232:233], v[232:233], v[34:35]
	v_pk_add_f32 v[232:233], v[232:233], v[36:37]
	v_pk_add_f32 v[232:233], v[232:233], v[38:39]
	v_pk_add_f32 v[232:233], v[232:233], v[40:41]
	v_pk_add_f32 v[232:233], v[232:233], v[42:43]
	v_pk_add_f32 v[232:233], v[232:233], v[44:45]
	v_pk_add_f32 v[232:233], v[232:233], v[46:47]
	v_mfma_f32_32x32x16_bf16 v[0:15], v[64:67], v[72:75], v[0:15]
	v_mfma_f32_32x32x16_bf16 v[16:31], v[64:67], v[76:79], v[16:31]
	v_mfma_f32_32x32x16_bf16 v[0:15], v[68:71], v[220:223], v[0:15]
	v_mfma_f32_32x32x16_bf16 v[16:31], v[68:71], v[224:227], v[16:31]
	v_add_f32_e32 v113, v232, v233
	v_or_b32_e32 v114, 1, v107
	v_or_b32_e32 v97, 2, v107
	v_or_b32_e32 v96, 3, v107
	v_or_b32_e32 v95, 8, v107
	v_or_b32_e32 v94, 9, v107
	v_or_b32_e32 v93, 10, v107
	v_or_b32_e32 v92, 11, v107
	v_or_b32_e32 v91, 16, v107
	v_or_b32_e32 v90, 17, v107
	v_or_b32_e32 v89, 18, v107
	v_or_b32_e32 v88, 19, v107
	v_or_b32_e32 v87, 24, v107
	v_or_b32_e32 v86, 25, v107
	v_or_b32_e32 v85, 26, v107
	v_or_b32_e32 v84, 27, v107
	s_nop 11
	s_branch .LBB0_1265
